# dil loop: static s_setprio 1 for waves 4-7 (second wave of each SIMD) for the duration of the loop
# baseline (speedup 1.0000x reference)
; #define LAS __attribute__((address_space(3)))
; #define GAS __attribute__((address_space(1)))
; __device__ __forceinline__ void dil_unit(LAS unsigned char* lds, bf16_t* proj, int seq, int hd, int T0, int rho) {
;     ...
;     const int tid = tid_, lane = tid & 63, r32 = lane & 31, hi = lane >> 5, wid = __builtin_amdgcn_readfirstlane(tid >> 6);
;     bf16_t* base = proj + (size_t)seq * SEQ * NIN;
;     LAS unsigned char* wbuf = lds + wid * 4096;
;     const LAS unsigned char* vp = wbuf + ((lane >> 4) & 1) * 32 + (lane & 3) * 8 + (4 * hi + ((lane & 15) >> 2)) * 64;
;     const int P0 = T0 + rho;
;     bf16x8 qr[4];
; #pragma unroll
;     for (int ks = 0; ks < 4; ++ks) qr[ks] = *(const GAS bf16x8*)(base + (size_t)(P0 + 16 * r32) * NIN + PC_LQ + hd * 64 + 16 * ks + 8 * hi);
;     f32x16 o0 = {}, o1 = {}; float l = 0.f;
;     const bool bound = (T0 < 1024) || (T0 >= 15360);
.LBB0_554:
	s_lshr_b32 s82, s33, 8
	s_mul_i32 s82, s82, 13
	s_add_i32 s82, s82, s33
	s_ashr_i32 s2, s33, 6
	s_mul_hi_i32 s7, s2, 0x2aaaaaab
	s_lshl_b32 s3, s82, 8
	s_lshr_b32 s8, s7, 31
	s_and_b32 s6, s3, 0x3e00
	s_lshl_b32 s3, s82, 3
	s_add_i32 s7, s7, s8
	s_and_b32 s3, s3, 8
	s_mul_i32 s8, s7, 6
	s_add_i32 s3, s3, s64
	s_sub_i32 s8, s2, s8
	s_mul_hi_i32 s2, s7, 0x6000000
	s_mul_i32 s7, s7, 0x6000000
	v_mov_b32_e32 v2, v154
	s_add_u32 s56, s48, s7
	s_addc_u32 s57, s49, s2
	v_and_b32_e32 v105, 31, v2
	s_add_i32 s76, s3, s6
	v_lshl_add_u32 v3, v105, 4, s76
	v_mov_b64_e32 v[0:1], s[56:57]
	s_lshl_b32 s58, s8, 6
	v_bfe_u32 v106, v2, 5, 1
	v_mad_u64_u32 v[0:1], s[2:3], v3, s65, v[0:1]
	s_ashr_i32 s59, s58, 31
	v_lshl_add_u64 v[0:1], s[58:59], 1, v[0:1]
	v_lshlrev_b32_e32 v80, 4, v106
	v_lshl_add_u64 v[0:1], v[0:1], 0, v[80:81]
	global_load_dwordx4 v[48:51], v[0:1], off offset:1280
	global_load_dwordx4 v[52:55], v[0:1], off offset:1312
	global_load_dwordx4 v[56:59], v[0:1], off offset:1344
	global_load_dwordx4 v[60:63], v[0:1], off offset:1376
	v_readfirstlane_b32 s2, v2
	s_lshl_b32 s2, s2, 6
	s_and_b32 s2, s2, 0xfffff000
	v_lshlrev_b32_e32 v0, 1, v2
	v_lshlrev_b32_e32 v104, 3, v2
	v_lshlrev_b32_e32 v107, 2, v106
	v_lshrrev_b32_e32 v1, 2, v2
	v_and_b32_e32 v103, 63, v2
	v_and_b32_e32 v0, 32, v0
	v_and_b32_e32 v98, 24, v104
	v_and_or_b32 v1, v1, 3, v107
	s_add_i32 s77, s2, 0
	v_lshlrev_b32_e32 v108, 6, v1
	v_lshlrev_b32_e32 v1, 3, v106
	v_add3_u32 v109, s77, v0, v98
	s_addk_i32 s6, 0xc400
	v_lshrrev_b32_e32 v110, 2, v103
	v_lshlrev_b32_e32 v0, 4, v103
	s_mov_b64 s[2:3], -1
	s_cmp_gt_u32 s6, 0xffffc7ff
	v_lshlrev_b32_e32 v100, 1, v98
	s_mul_i32 s6, s8, 0x1c00
	v_lshlrev_b32_e32 v82, 1, v1
	v_or_b32_e32 v111, 16, v110
	v_add_u32_e32 v112, s77, v0
	s_cbranch_scc0 .LBB0_558
	v_readfirstlane_b32 s91, v154
	s_nop 3
	s_bitcmp1_b32 s91, 8
	s_cbranch_scc0 .Ldn0_noprio
	s_setprio 1
.Ldn0_noprio:
	s_movk_i32 s100, 0x1800
	s_add_i32 s101, s6, 0x15c00
	s_lshl_b32 s90, s58, 1
	s_add_u32 s82, s56, s90
	s_addc_u32 s83, s57, 0
	s_add_u32 s82, s82, 0x1200
	s_addc_u32 s83, s83, 0
	s_sub_i32 s90, s76, 64
	s_mul_i32 s90, s90, 0x1800
	s_add_u32 s84, s82, s90
	s_addc_u32 s85, s83, 0
	s_sub_i32 s90, s76, 256
	s_mul_i32 s90, s90, 0x1800
	s_add_u32 s86, s82, s90
	s_addc_u32 s87, s83, 0
	s_sub_i32 s90, s76, 1024
	s_mul_i32 s90, s90, 0x1800
	s_add_u32 s88, s82, s90
	s_addc_u32 s89, s83, 0
	v_lshlrev_b32_e32 v153, 1, v98
	v_mad_u32_u24 v80, v105, s100, v82
	v_mad_u32_u24 v100, v110, s100, v153
	v_add_u32_e32 v149, 0x18000, v100
	v_lshlrev_b32_e32 v83, 2, v105
	v_mad_u32_u24 v83, v83, s100, v82
	v_lshlrev_b32_e32 v101, 2, v110
	v_mad_u32_u24 v101, v101, s100, v153
	v_add_u32_e32 v150, 0x60000, v101
	v_lshlrev_b32_e32 v99, 4, v105
	v_mad_u32_u24 v99, v99, s100, v82
	v_lshlrev_b32_e32 v148, 4, v110
	v_mad_u32_u24 v148, v148, s100, v153
	v_add_u32_e32 v151, 0x180000, v148
	v_lshrrev_b32_e32 v249, 3, v103
	v_and_b32_e32 v250, 7, v103
	v_lshlrev_b32_e32 v250, 4, v250
	v_add_u32_e32 v235, 0, v249
	v_mad_u32_u24 v235, v235, s100, v250
	v_add_u32_e32 v236, 8, v249
	v_mad_u32_u24 v236, v236, s100, v250
	v_add_u32_e32 v237, 16, v249
	v_mad_u32_u24 v237, v237, s100, v250
	v_add_u32_e32 v238, 24, v249
	v_mad_u32_u24 v238, v238, s100, v250
	v_add_u32_e32 v239, 0, v249
	v_lshlrev_b32_e32 v239, 2, v239
	v_mad_u32_u24 v239, v239, s100, v250
	v_add_u32_e32 v240, 8, v249
	v_lshlrev_b32_e32 v240, 2, v240
	v_mad_u32_u24 v240, v240, s100, v250
	v_add_u32_e32 v241, 16, v249
	v_lshlrev_b32_e32 v241, 2, v241
	v_mad_u32_u24 v241, v241, s100, v250
	v_add_u32_e32 v242, 24, v249
	v_lshlrev_b32_e32 v242, 2, v242
	v_mad_u32_u24 v242, v242, s100, v250
	v_add_u32_e32 v243, 0, v249
	v_lshlrev_b32_e32 v243, 4, v243
	v_mad_u32_u24 v243, v243, s100, v250
	v_add_u32_e32 v244, 8, v249
	v_lshlrev_b32_e32 v244, 4, v244
	v_mad_u32_u24 v244, v244, s100, v250
	v_add_u32_e32 v245, 16, v249
	v_lshlrev_b32_e32 v245, 4, v245
	v_mad_u32_u24 v245, v245, s100, v250
	v_add_u32_e32 v246, 24, v249
	v_lshlrev_b32_e32 v246, 4, v246
	v_mad_u32_u24 v246, v246, s100, v250
	v_and_b32_e32 v247, 7, v249
	v_lshlrev_b32_e32 v247, 4, v247
	v_xor_b32_e32 v247, v247, v112
	v_and_b32_e32 v153, 7, v105
	v_or_b32_e32 v248, 0, v106
	v_xor_b32_e32 v248, v248, v153
	v_lshlrev_b32_e32 v248, 4, v248
	v_lshl_add_u32 v248, v105, 7, v248
	v_add_u32_e32 v248, s77, v248
	v_or_b32_e32 v249, 2, v106
	v_xor_b32_e32 v249, v249, v153
	v_lshlrev_b32_e32 v249, 4, v249
	v_lshl_add_u32 v249, v105, 7, v249
	v_add_u32_e32 v249, s77, v249
	v_or_b32_e32 v250, 4, v106
	v_xor_b32_e32 v250, v250, v153
	v_lshlrev_b32_e32 v250, 4, v250
	v_lshl_add_u32 v250, v105, 7, v250
	v_add_u32_e32 v250, s77, v250
	v_or_b32_e32 v251, 6, v106
	v_xor_b32_e32 v251, v251, v153
	v_lshlrev_b32_e32 v251, 4, v251
	v_lshl_add_u32 v251, v105, 7, v251
	v_add_u32_e32 v251, s77, v251
	v_lshlrev_b32_e32 v153, 1, v98
	v_mul_u32_u24_e32 v228, 17, v105
	v_sub_u32_e32 v228, v107, v228
	s_mul_i32 s90, s58, 153
	s_lshr_b32 s90, s90, 1
	s_add_i32 s90, s90, 34876
	v_lshl_add_u32 v228, v228, 2, s90
	v_lshlrev_b32_e32 v229, 2, v105
	v_sub_u32_e32 v229, v107, v229
	s_add_i32 s90, s101, 5104
	v_lshl_add_u32 v229, v229, 2, s90
	v_sub_u32_e32 v230, v107, v105
	s_add_i32 s90, s101, 6364
	v_lshl_add_u32 v230, v230, 2, s90
	v_add_u32_e32 v231, v109, v108
	v_mov_b64_e32 v[232:233], 0
	v_mov_b64_e32 v[0:1], 0
	v_mov_b64_e32 v[2:3], 0
	v_mov_b64_e32 v[4:5], 0
	v_mov_b64_e32 v[6:7], 0
	v_mov_b64_e32 v[8:9], 0
	v_mov_b64_e32 v[10:11], 0
	v_mov_b64_e32 v[12:13], 0
	v_mov_b64_e32 v[14:15], 0
	v_mov_b64_e32 v[16:17], 0
	v_mov_b64_e32 v[18:19], 0
	v_mov_b64_e32 v[20:21], 0
	v_mov_b64_e32 v[22:23], 0
	v_mov_b64_e32 v[24:25], 0
; __device__ __forceinline__ void dil_unit(LAS unsigned char* lds, bf16_t* proj, int seq, int hd, int T0, int rho) {
;     ...
;     f32x16 o0 = {}, o1 = {}; float l = 0.f;
;     const bool bound = (T0 < 1024) || (T0 >= 15360);
	v_mov_b64_e32 v[26:27], 0
	v_mov_b64_e32 v[28:29], 0
	v_mov_b64_e32 v[30:31], 0
	global_load_dwordx4 v[116:119], v235, s[84:85]
	global_load_dwordx4 v[120:123], v236, s[84:85]
	global_load_dwordx4 v[124:127], v237, s[84:85]
	global_load_dwordx4 v[128:131], v238, s[84:85]
	global_load_dwordx4 v[132:135], v100, s[84:85] offset:768
	global_load_dwordx4 v[136:139], v149, s[84:85] offset:768
	global_load_dwordx4 v[140:143], v100, s[84:85] offset:832
	global_load_dwordx4 v[144:147], v149, s[84:85] offset:832
	s_add_u32 s84, s84, 0x30000
	s_addc_u32 s85, s85, 0
	global_load_dwordx4 v[156:159], v235, s[84:85]
	global_load_dwordx4 v[160:163], v236, s[84:85]
	global_load_dwordx4 v[164:167], v237, s[84:85]
	global_load_dwordx4 v[168:171], v238, s[84:85]
	global_load_dwordx4 v[172:175], v100, s[84:85] offset:768
	global_load_dwordx4 v[176:179], v149, s[84:85] offset:768
	global_load_dwordx4 v[180:183], v100, s[84:85] offset:832
	global_load_dwordx4 v[184:187], v149, s[84:85] offset:832
	s_add_u32 s84, s84, 0x30000
	s_addc_u32 s85, s85, 0
	v_mov_b32_e32 v115, v228
	ds_read2_b32 v[32:33], v115 offset0:0 offset1:1
	ds_read2_b32 v[34:35], v115 offset0:2 offset1:3
	ds_read2_b32 v[36:37], v115 offset0:8 offset1:9
	ds_read2_b32 v[38:39], v115 offset0:10 offset1:11
	ds_read2_b32 v[40:41], v115 offset0:17 offset1:18
	ds_read2_b32 v[42:43], v115 offset0:19 offset1:20
	ds_read2_b32 v[44:45], v115 offset0:25 offset1:26
	ds_read2_b32 v[46:47], v115 offset0:27 offset1:28
	s_waitcnt vmcnt(8)
	ds_write_b128 v247, v[116:119]
	ds_write_b128 v247, v[120:123] offset:1024
	ds_write_b128 v247, v[124:127] offset:2048
	ds_write_b128 v247, v[128:131] offset:3072
	ds_read_b128 v[116:119], v248
	ds_read_b128 v[120:123], v249
	ds_read_b128 v[124:127], v250
	ds_read_b128 v[128:131], v251
	ds_write_b128 v112, v[132:135]
	ds_write_b128 v112, v[136:139] offset:1024
	ds_write_b128 v112, v[140:143] offset:2048
	ds_write_b128 v112, v[144:147] offset:3072
	s_waitcnt lgkmcnt(4)
	v_mfma_f32_32x32x16_bf16 v[32:47], v[116:119], v[48:51], v[32:47]
	v_mfma_f32_32x32x16_bf16 v[32:47], v[120:123], v[52:55], v[32:47]
	v_mfma_f32_32x32x16_bf16 v[32:47], v[124:127], v[56:59], v[32:47]
	v_mfma_f32_32x32x16_bf16 v[32:47], v[128:131], v[60:63], v[32:47]
	ds_read2_b32 v[188:189], v115 offset0:34 offset1:35
	ds_read2_b32 v[190:191], v115 offset0:36 offset1:37
	ds_read2_b32 v[192:193], v115 offset0:42 offset1:43
	ds_read2_b32 v[194:195], v115 offset0:44 offset1:45
	ds_read2_b32 v[196:197], v115 offset0:51 offset1:52
	ds_read2_b32 v[198:199], v115 offset0:53 offset1:54
	ds_read2_b32 v[200:201], v115 offset0:59 offset1:60
	ds_read2_b32 v[202:203], v115 offset0:61 offset1:62
	global_load_dwordx4 v[116:119], v235, s[84:85]
	global_load_dwordx4 v[120:123], v236, s[84:85]
	global_load_dwordx4 v[124:127], v237, s[84:85]
	global_load_dwordx4 v[128:131], v238, s[84:85]
	global_load_dwordx4 v[132:135], v100, s[84:85] offset:768
	global_load_dwordx4 v[136:139], v149, s[84:85] offset:768
	global_load_dwordx4 v[140:143], v100, s[84:85] offset:832
	global_load_dwordx4 v[144:147], v149, s[84:85] offset:832
	s_add_u32 s84, s84, 0x30000
	s_addc_u32 s85, s85, 0
	ds_read_b64_tr_b16 v[72:73], v231
	ds_read_b64_tr_b16 v[74:75], v231 offset:512
	ds_read_b64_tr_b16 v[76:77], v231 offset:2048
	ds_read_b64_tr_b16 v[78:79], v231 offset:2560
	ds_read_b64_tr_b16 v[220:221], v231 offset:1024
	ds_read_b64_tr_b16 v[222:223], v231 offset:1536
	ds_read_b64_tr_b16 v[224:225], v231 offset:3072
	ds_read_b64_tr_b16 v[226:227], v231 offset:3584
	v_exp_f32_e32 v32, v32
	v_exp_f32_e32 v33, v33
	v_exp_f32_e32 v34, v34
	v_exp_f32_e32 v35, v35
	s_waitcnt vmcnt(8)
	ds_write_b128 v247, v[156:159]
	ds_write_b128 v247, v[160:163] offset:1024
	ds_write_b128 v247, v[164:167] offset:2048
	ds_write_b128 v247, v[168:171] offset:3072
	ds_read_b128 v[156:159], v248
	ds_read_b128 v[160:163], v249
	ds_read_b128 v[164:167], v250
	ds_read_b128 v[168:171], v251
	ds_write_b128 v112, v[172:175]
	ds_write_b128 v112, v[176:179] offset:1024
	ds_write_b128 v112, v[180:183] offset:2048
	ds_write_b128 v112, v[184:187] offset:3072
	v_exp_f32_e32 v36, v36
	v_exp_f32_e32 v37, v37
	v_exp_f32_e32 v38, v38
	v_exp_f32_e32 v39, v39
	s_waitcnt lgkmcnt(4)
	v_mfma_f32_32x32x16_bf16 v[188:203], v[156:159], v[48:51], v[188:203]
	v_exp_f32_e32 v40, v40
	v_exp_f32_e32 v41, v41
	v_mfma_f32_32x32x16_bf16 v[188:203], v[160:163], v[52:55], v[188:203]
	v_exp_f32_e32 v42, v42
	v_exp_f32_e32 v43, v43
	v_mfma_f32_32x32x16_bf16 v[188:203], v[164:167], v[56:59], v[188:203]
	v_exp_f32_e32 v44, v44
	v_exp_f32_e32 v45, v45
	v_mfma_f32_32x32x16_bf16 v[188:203], v[168:171], v[60:63], v[188:203]
	v_exp_f32_e32 v46, v46
	v_exp_f32_e32 v47, v47
	v_cvt_pk_bf16_f32 v64, v32, v33
	v_cvt_pk_bf16_f32 v65, v34, v35
	v_cvt_pk_bf16_f32 v66, v36, v37
	v_cvt_pk_bf16_f32 v67, v38, v39
	v_cvt_pk_bf16_f32 v68, v40, v41
	v_cvt_pk_bf16_f32 v69, v42, v43
	v_cvt_pk_bf16_f32 v70, v44, v45
	v_cvt_pk_bf16_f32 v71, v46, v47
	v_pk_add_f32 v[232:233], v[232:233], v[32:33]
	v_pk_add_f32 v[232:233], v[232:233], v[34:35]
	v_pk_add_f32 v[232:233], v[232:233], v[36:37]
	v_pk_add_f32 v[232:233], v[232:233], v[38:39]
	v_pk_add_f32 v[232:233], v[232:233], v[40:41]
	v_pk_add_f32 v[232:233], v[232:233], v[42:43]
	v_pk_add_f32 v[232:233], v[232:233], v[44:45]
	v_pk_add_f32 v[232:233], v[232:233], v[46:47]
	ds_read2_b32 v[32:33], v115 offset0:68 offset1:69
	ds_read2_b32 v[34:35], v115 offset0:70 offset1:71
	ds_read2_b32 v[36:37], v115 offset0:76 offset1:77
	ds_read2_b32 v[38:39], v115 offset0:78 offset1:79
	ds_read2_b32 v[40:41], v115 offset0:85 offset1:86
	ds_read2_b32 v[42:43], v115 offset0:87 offset1:88
	ds_read2_b32 v[44:45], v115 offset0:93 offset1:94
	ds_read2_b32 v[46:47], v115 offset0:95 offset1:96
	v_mfma_f32_32x32x16_bf16 v[0:15], v[64:67], v[72:75], v[0:15]
	v_mfma_f32_32x32x16_bf16 v[16:31], v[64:67], v[76:79], v[16:31]
	v_mfma_f32_32x32x16_bf16 v[0:15], v[68:71], v[220:223], v[0:15]
	v_mfma_f32_32x32x16_bf16 v[16:31], v[68:71], v[224:227], v[16:31]
	global_load_dwordx4 v[156:159], v235, s[84:85]
	global_load_dwordx4 v[160:163], v236, s[84:85]
	global_load_dwordx4 v[164:167], v237, s[84:85]
	global_load_dwordx4 v[168:171], v238, s[84:85]
	global_load_dwordx4 v[172:175], v100, s[84:85] offset:768
	global_load_dwordx4 v[176:179], v149, s[84:85] offset:768
	global_load_dwordx4 v[180:183], v100, s[84:85] offset:832
	global_load_dwordx4 v[184:187], v149, s[84:85] offset:832
	s_add_u32 s84, s84, 0x30000
	s_addc_u32 s85, s85, 0
	ds_read_b64_tr_b16 v[72:73], v231
	ds_read_b64_tr_b16 v[74:75], v231 offset:512
	ds_read_b64_tr_b16 v[76:77], v231 offset:2048
	ds_read_b64_tr_b16 v[78:79], v231 offset:2560
	ds_read_b64_tr_b16 v[220:221], v231 offset:1024
	ds_read_b64_tr_b16 v[222:223], v231 offset:1536
	ds_read_b64_tr_b16 v[224:225], v231 offset:3072
	ds_read_b64_tr_b16 v[226:227], v231 offset:3584
	v_exp_f32_e32 v188, v188
	v_exp_f32_e32 v189, v189
	v_exp_f32_e32 v190, v190
	v_exp_f32_e32 v191, v191
	s_waitcnt vmcnt(8)
	ds_write_b128 v247, v[116:119]
	ds_write_b128 v247, v[120:123] offset:1024
	ds_write_b128 v247, v[124:127] offset:2048
	ds_write_b128 v247, v[128:131] offset:3072
	ds_read_b128 v[116:119], v248
	ds_read_b128 v[120:123], v249
	ds_read_b128 v[124:127], v250
	ds_read_b128 v[128:131], v251
	ds_write_b128 v112, v[132:135]
	ds_write_b128 v112, v[136:139] offset:1024
	ds_write_b128 v112, v[140:143] offset:2048
	ds_write_b128 v112, v[144:147] offset:3072
	v_exp_f32_e32 v192, v192
	v_exp_f32_e32 v193, v193
	v_exp_f32_e32 v194, v194
	v_exp_f32_e32 v195, v195
	s_waitcnt lgkmcnt(4)
	v_mfma_f32_32x32x16_bf16 v[32:47], v[116:119], v[48:51], v[32:47]
	v_exp_f32_e32 v196, v196
	v_exp_f32_e32 v197, v197
	v_mfma_f32_32x32x16_bf16 v[32:47], v[120:123], v[52:55], v[32:47]
	v_exp_f32_e32 v198, v198
	v_exp_f32_e32 v199, v199
	v_mfma_f32_32x32x16_bf16 v[32:47], v[124:127], v[56:59], v[32:47]
	v_exp_f32_e32 v200, v200
	v_exp_f32_e32 v201, v201
	v_mfma_f32_32x32x16_bf16 v[32:47], v[128:131], v[60:63], v[32:47]
	v_exp_f32_e32 v202, v202
	v_exp_f32_e32 v203, v203
	v_cvt_pk_bf16_f32 v64, v188, v189
	v_cvt_pk_bf16_f32 v65, v190, v191
	v_cvt_pk_bf16_f32 v66, v192, v193
	v_cvt_pk_bf16_f32 v67, v194, v195
	v_cvt_pk_bf16_f32 v68, v196, v197
	v_cvt_pk_bf16_f32 v69, v198, v199
	v_cvt_pk_bf16_f32 v70, v200, v201
	v_cvt_pk_bf16_f32 v71, v202, v203
	v_pk_add_f32 v[232:233], v[232:233], v[188:189]
	v_pk_add_f32 v[232:233], v[232:233], v[190:191]
	v_pk_add_f32 v[232:233], v[232:233], v[192:193]
	v_pk_add_f32 v[232:233], v[232:233], v[194:195]
	v_pk_add_f32 v[232:233], v[232:233], v[196:197]
	v_pk_add_f32 v[232:233], v[232:233], v[198:199]
	v_pk_add_f32 v[232:233], v[232:233], v[200:201]
	v_pk_add_f32 v[232:233], v[232:233], v[202:203]
	ds_read2_b32 v[188:189], v115 offset0:102 offset1:103
	ds_read2_b32 v[190:191], v115 offset0:104 offset1:105
	ds_read2_b32 v[192:193], v115 offset0:110 offset1:111
	ds_read2_b32 v[194:195], v115 offset0:112 offset1:113
	ds_read2_b32 v[196:197], v115 offset0:119 offset1:120
	ds_read2_b32 v[198:199], v115 offset0:121 offset1:122
	ds_read2_b32 v[200:201], v115 offset0:127 offset1:128
	ds_read2_b32 v[202:203], v115 offset0:129 offset1:130
	v_mfma_f32_32x32x16_bf16 v[0:15], v[64:67], v[72:75], v[0:15]
	v_mfma_f32_32x32x16_bf16 v[16:31], v[64:67], v[76:79], v[16:31]
	v_mfma_f32_32x32x16_bf16 v[0:15], v[68:71], v[220:223], v[0:15]
	v_mfma_f32_32x32x16_bf16 v[16:31], v[68:71], v[224:227], v[16:31]
	global_load_dwordx4 v[116:119], v235, s[84:85]
	global_load_dwordx4 v[120:123], v236, s[84:85]
	global_load_dwordx4 v[124:127], v237, s[84:85]
	global_load_dwordx4 v[128:131], v238, s[84:85]
	global_load_dwordx4 v[132:135], v100, s[84:85] offset:768
	global_load_dwordx4 v[136:139], v149, s[84:85] offset:768
	global_load_dwordx4 v[140:143], v100, s[84:85] offset:832
	global_load_dwordx4 v[144:147], v149, s[84:85] offset:832
	s_add_u32 s84, s84, 0x30000
	s_addc_u32 s85, s85, 0
	ds_read_b64_tr_b16 v[72:73], v231
	ds_read_b64_tr_b16 v[74:75], v231 offset:512
	ds_read_b64_tr_b16 v[76:77], v231 offset:2048
	ds_read_b64_tr_b16 v[78:79], v231 offset:2560
	ds_read_b64_tr_b16 v[220:221], v231 offset:1024
	ds_read_b64_tr_b16 v[222:223], v231 offset:1536
	ds_read_b64_tr_b16 v[224:225], v231 offset:3072
	ds_read_b64_tr_b16 v[226:227], v231 offset:3584
	v_exp_f32_e32 v32, v32
	v_exp_f32_e32 v33, v33
	v_exp_f32_e32 v34, v34
	v_exp_f32_e32 v35, v35
	s_waitcnt vmcnt(8)
	ds_write_b128 v247, v[156:159]
	ds_write_b128 v247, v[160:163] offset:1024
	ds_write_b128 v247, v[164:167] offset:2048
	ds_write_b128 v247, v[168:171] offset:3072
	ds_read_b128 v[156:159], v248
	ds_read_b128 v[160:163], v249
	ds_read_b128 v[164:167], v250
	ds_read_b128 v[168:171], v251
	ds_write_b128 v112, v[172:175]
	ds_write_b128 v112, v[176:179] offset:1024
	ds_write_b128 v112, v[180:183] offset:2048
	ds_write_b128 v112, v[184:187] offset:3072
	v_exp_f32_e32 v36, v36
	v_exp_f32_e32 v37, v37
	v_exp_f32_e32 v38, v38
	v_exp_f32_e32 v39, v39
	s_waitcnt lgkmcnt(4)
	v_mfma_f32_32x32x16_bf16 v[188:203], v[156:159], v[48:51], v[188:203]
	v_exp_f32_e32 v40, v40
	v_exp_f32_e32 v41, v41
	v_mfma_f32_32x32x16_bf16 v[188:203], v[160:163], v[52:55], v[188:203]
	v_exp_f32_e32 v42, v42
	v_exp_f32_e32 v43, v43
	v_mfma_f32_32x32x16_bf16 v[188:203], v[164:167], v[56:59], v[188:203]
	v_exp_f32_e32 v44, v44
	v_exp_f32_e32 v45, v45
	v_mfma_f32_32x32x16_bf16 v[188:203], v[168:171], v[60:63], v[188:203]
	v_exp_f32_e32 v46, v46
	v_exp_f32_e32 v47, v47
	v_cvt_pk_bf16_f32 v64, v32, v33
	v_cvt_pk_bf16_f32 v65, v34, v35
	v_cvt_pk_bf16_f32 v66, v36, v37
	v_cvt_pk_bf16_f32 v67, v38, v39
	v_cvt_pk_bf16_f32 v68, v40, v41
	v_cvt_pk_bf16_f32 v69, v42, v43
	v_cvt_pk_bf16_f32 v70, v44, v45
	v_cvt_pk_bf16_f32 v71, v46, v47
	v_pk_add_f32 v[232:233], v[232:233], v[32:33]
	v_pk_add_f32 v[232:233], v[232:233], v[34:35]
	v_pk_add_f32 v[232:233], v[232:233], v[36:37]
	v_pk_add_f32 v[232:233], v[232:233], v[38:39]
	v_pk_add_f32 v[232:233], v[232:233], v[40:41]
	v_pk_add_f32 v[232:233], v[232:233], v[42:43]
	v_pk_add_f32 v[232:233], v[232:233], v[44:45]
	v_pk_add_f32 v[232:233], v[232:233], v[46:47]
	ds_read2_b32 v[32:33], v115 offset0:136 offset1:137
	ds_read2_b32 v[34:35], v115 offset0:138 offset1:139
	ds_read2_b32 v[36:37], v115 offset0:144 offset1:145
	ds_read2_b32 v[38:39], v115 offset0:146 offset1:147
	ds_read2_b32 v[40:41], v115 offset0:153 offset1:154
	ds_read2_b32 v[42:43], v115 offset0:155 offset1:156
	ds_read2_b32 v[44:45], v115 offset0:161 offset1:162
	ds_read2_b32 v[46:47], v115 offset0:163 offset1:164
	v_mfma_f32_32x32x16_bf16 v[0:15], v[64:67], v[72:75], v[0:15]
	v_mfma_f32_32x32x16_bf16 v[16:31], v[64:67], v[76:79], v[16:31]
	v_mfma_f32_32x32x16_bf16 v[0:15], v[68:71], v[220:223], v[0:15]
	v_mfma_f32_32x32x16_bf16 v[16:31], v[68:71], v[224:227], v[16:31]
	global_load_dwordx4 v[156:159], v235, s[84:85]
	global_load_dwordx4 v[160:163], v236, s[84:85]
	global_load_dwordx4 v[164:167], v237, s[84:85]
	global_load_dwordx4 v[168:171], v238, s[84:85]
	global_load_dwordx4 v[172:175], v100, s[84:85] offset:768
	global_load_dwordx4 v[176:179], v149, s[84:85] offset:768
	global_load_dwordx4 v[180:183], v100, s[84:85] offset:832
	global_load_dwordx4 v[184:187], v149, s[84:85] offset:832
	s_add_u32 s84, s84, 0x30000
	s_addc_u32 s85, s85, 0
	ds_read_b64_tr_b16 v[72:73], v231
	ds_read_b64_tr_b16 v[74:75], v231 offset:512
	ds_read_b64_tr_b16 v[76:77], v231 offset:2048
	ds_read_b64_tr_b16 v[78:79], v231 offset:2560
	ds_read_b64_tr_b16 v[220:221], v231 offset:1024
	ds_read_b64_tr_b16 v[222:223], v231 offset:1536
	ds_read_b64_tr_b16 v[224:225], v231 offset:3072
	ds_read_b64_tr_b16 v[226:227], v231 offset:3584
	v_exp_f32_e32 v188, v188
	v_exp_f32_e32 v189, v189
	v_exp_f32_e32 v190, v190
	v_exp_f32_e32 v191, v191
	s_waitcnt vmcnt(8)
	ds_write_b128 v247, v[116:119]
	ds_write_b128 v247, v[120:123] offset:1024
	ds_write_b128 v247, v[124:127] offset:2048
	ds_write_b128 v247, v[128:131] offset:3072
	ds_read_b128 v[116:119], v248
	ds_read_b128 v[120:123], v249
	ds_read_b128 v[124:127], v250
	ds_read_b128 v[128:131], v251
	ds_write_b128 v112, v[132:135]
	ds_write_b128 v112, v[136:139] offset:1024
	ds_write_b128 v112, v[140:143] offset:2048
	ds_write_b128 v112, v[144:147] offset:3072
	v_exp_f32_e32 v192, v192
	v_exp_f32_e32 v193, v193
	v_exp_f32_e32 v194, v194
	v_exp_f32_e32 v195, v195
	s_waitcnt lgkmcnt(4)
	v_mfma_f32_32x32x16_bf16 v[32:47], v[116:119], v[48:51], v[32:47]
	v_exp_f32_e32 v196, v196
	v_exp_f32_e32 v197, v197
	v_mfma_f32_32x32x16_bf16 v[32:47], v[120:123], v[52:55], v[32:47]
	v_exp_f32_e32 v198, v198
	v_exp_f32_e32 v199, v199
	v_mfma_f32_32x32x16_bf16 v[32:47], v[124:127], v[56:59], v[32:47]
	v_exp_f32_e32 v200, v200
	v_exp_f32_e32 v201, v201
	v_mfma_f32_32x32x16_bf16 v[32:47], v[128:131], v[60:63], v[32:47]
	v_exp_f32_e32 v202, v202
	v_exp_f32_e32 v203, v203
	v_cvt_pk_bf16_f32 v64, v188, v189
	v_cvt_pk_bf16_f32 v65, v190, v191
	v_cvt_pk_bf16_f32 v66, v192, v193
	v_cvt_pk_bf16_f32 v67, v194, v195
	v_cvt_pk_bf16_f32 v68, v196, v197
	v_cvt_pk_bf16_f32 v69, v198, v199
	v_cvt_pk_bf16_f32 v70, v200, v201
	v_cvt_pk_bf16_f32 v71, v202, v203
	v_pk_add_f32 v[232:233], v[232:233], v[188:189]
	v_pk_add_f32 v[232:233], v[232:233], v[190:191]
	v_pk_add_f32 v[232:233], v[232:233], v[192:193]
	v_pk_add_f32 v[232:233], v[232:233], v[194:195]
	v_pk_add_f32 v[232:233], v[232:233], v[196:197]
	v_pk_add_f32 v[232:233], v[232:233], v[198:199]
	v_pk_add_f32 v[232:233], v[232:233], v[200:201]
	v_pk_add_f32 v[232:233], v[232:233], v[202:203]
	ds_read2_b32 v[188:189], v115 offset0:170 offset1:171
	ds_read2_b32 v[190:191], v115 offset0:172 offset1:173
	ds_read2_b32 v[192:193], v115 offset0:178 offset1:179
	ds_read2_b32 v[194:195], v115 offset0:180 offset1:181
	ds_read2_b32 v[196:197], v115 offset0:187 offset1:188
	ds_read2_b32 v[198:199], v115 offset0:189 offset1:190
	ds_read2_b32 v[200:201], v115 offset0:195 offset1:196
	ds_read2_b32 v[202:203], v115 offset0:197 offset1:198
	v_mfma_f32_32x32x16_bf16 v[0:15], v[64:67], v[72:75], v[0:15]
	v_mfma_f32_32x32x16_bf16 v[16:31], v[64:67], v[76:79], v[16:31]
	v_mfma_f32_32x32x16_bf16 v[0:15], v[68:71], v[220:223], v[0:15]
	v_mfma_f32_32x32x16_bf16 v[16:31], v[68:71], v[224:227], v[16:31]
	global_load_dwordx4 v[116:119], v235, s[84:85]
	global_load_dwordx4 v[120:123], v236, s[84:85]
	global_load_dwordx4 v[124:127], v237, s[84:85]
	global_load_dwordx4 v[128:131], v238, s[84:85]
	global_load_dwordx4 v[132:135], v100, s[84:85] offset:768
	global_load_dwordx4 v[136:139], v149, s[84:85] offset:768
	global_load_dwordx4 v[140:143], v100, s[84:85] offset:832
	global_load_dwordx4 v[144:147], v149, s[84:85] offset:832
	s_add_u32 s84, s84, 0x30000
	s_addc_u32 s85, s85, 0
	ds_read_b64_tr_b16 v[72:73], v231
	ds_read_b64_tr_b16 v[74:75], v231 offset:512
	ds_read_b64_tr_b16 v[76:77], v231 offset:2048
	ds_read_b64_tr_b16 v[78:79], v231 offset:2560
	ds_read_b64_tr_b16 v[220:221], v231 offset:1024
	ds_read_b64_tr_b16 v[222:223], v231 offset:1536
	ds_read_b64_tr_b16 v[224:225], v231 offset:3072
	ds_read_b64_tr_b16 v[226:227], v231 offset:3584
	v_exp_f32_e32 v32, v32
	v_exp_f32_e32 v33, v33
	v_exp_f32_e32 v34, v34
	v_exp_f32_e32 v35, v35
	s_waitcnt vmcnt(8)
	ds_write_b128 v247, v[156:159]
	ds_write_b128 v247, v[160:163] offset:1024
	ds_write_b128 v247, v[164:167] offset:2048
	ds_write_b128 v247, v[168:171] offset:3072
	ds_read_b128 v[156:159], v248
	ds_read_b128 v[160:163], v249
	ds_read_b128 v[164:167], v250
	ds_read_b128 v[168:171], v251
	ds_write_b128 v112, v[172:175]
	ds_write_b128 v112, v[176:179] offset:1024
	ds_write_b128 v112, v[180:183] offset:2048
	ds_write_b128 v112, v[184:187] offset:3072
	v_exp_f32_e32 v36, v36
	v_exp_f32_e32 v37, v37
	v_exp_f32_e32 v38, v38
	v_exp_f32_e32 v39, v39
	s_waitcnt lgkmcnt(4)
	v_mfma_f32_32x32x16_bf16 v[188:203], v[156:159], v[48:51], v[188:203]
	v_exp_f32_e32 v40, v40
	v_exp_f32_e32 v41, v41
	v_mfma_f32_32x32x16_bf16 v[188:203], v[160:163], v[52:55], v[188:203]
	v_exp_f32_e32 v42, v42
	v_exp_f32_e32 v43, v43
	v_mfma_f32_32x32x16_bf16 v[188:203], v[164:167], v[56:59], v[188:203]
	v_exp_f32_e32 v44, v44
	v_exp_f32_e32 v45, v45
	v_mfma_f32_32x32x16_bf16 v[188:203], v[168:171], v[60:63], v[188:203]
	v_exp_f32_e32 v46, v46
	v_exp_f32_e32 v47, v47
	v_cvt_pk_bf16_f32 v64, v32, v33
	v_cvt_pk_bf16_f32 v65, v34, v35
	v_cvt_pk_bf16_f32 v66, v36, v37
	v_cvt_pk_bf16_f32 v67, v38, v39
	v_cvt_pk_bf16_f32 v68, v40, v41
	v_cvt_pk_bf16_f32 v69, v42, v43
	v_cvt_pk_bf16_f32 v70, v44, v45
	v_cvt_pk_bf16_f32 v71, v46, v47
	v_pk_add_f32 v[232:233], v[232:233], v[32:33]
	v_pk_add_f32 v[232:233], v[232:233], v[34:35]
	v_pk_add_f32 v[232:233], v[232:233], v[36:37]
	v_pk_add_f32 v[232:233], v[232:233], v[38:39]
	v_pk_add_f32 v[232:233], v[232:233], v[40:41]
	v_pk_add_f32 v[232:233], v[232:233], v[42:43]
	v_pk_add_f32 v[232:233], v[232:233], v[44:45]
	v_pk_add_f32 v[232:233], v[232:233], v[46:47]
	ds_read2_b32 v[32:33], v115 offset0:204 offset1:205
	ds_read2_b32 v[34:35], v115 offset0:206 offset1:207
	ds_read2_b32 v[36:37], v115 offset0:212 offset1:213
	ds_read2_b32 v[38:39], v115 offset0:214 offset1:215
	ds_read2_b32 v[40:41], v115 offset0:221 offset1:222
	ds_read2_b32 v[42:43], v115 offset0:223 offset1:224
	ds_read2_b32 v[44:45], v115 offset0:229 offset1:230
	ds_read2_b32 v[46:47], v115 offset0:231 offset1:232
	v_mfma_f32_32x32x16_bf16 v[0:15], v[64:67], v[72:75], v[0:15]
	v_mfma_f32_32x32x16_bf16 v[16:31], v[64:67], v[76:79], v[16:31]
	v_mfma_f32_32x32x16_bf16 v[0:15], v[68:71], v[220:223], v[0:15]
	v_mfma_f32_32x32x16_bf16 v[16:31], v[68:71], v[224:227], v[16:31]
	global_load_dwordx4 v[156:159], v235, s[84:85]
	global_load_dwordx4 v[160:163], v236, s[84:85]
	global_load_dwordx4 v[164:167], v237, s[84:85]
	global_load_dwordx4 v[168:171], v238, s[84:85]
	global_load_dwordx4 v[172:175], v100, s[84:85] offset:768
	global_load_dwordx4 v[176:179], v149, s[84:85] offset:768
	global_load_dwordx4 v[180:183], v100, s[84:85] offset:832
	global_load_dwordx4 v[184:187], v149, s[84:85] offset:832
	s_add_u32 s84, s84, 0x30000
	s_addc_u32 s85, s85, 0
	ds_read_b64_tr_b16 v[72:73], v231
	ds_read_b64_tr_b16 v[74:75], v231 offset:512
	ds_read_b64_tr_b16 v[76:77], v231 offset:2048
	ds_read_b64_tr_b16 v[78:79], v231 offset:2560
	ds_read_b64_tr_b16 v[220:221], v231 offset:1024
	ds_read_b64_tr_b16 v[222:223], v231 offset:1536
	ds_read_b64_tr_b16 v[224:225], v231 offset:3072
	ds_read_b64_tr_b16 v[226:227], v231 offset:3584
	v_exp_f32_e32 v188, v188
	v_exp_f32_e32 v189, v189
	v_exp_f32_e32 v190, v190
	v_exp_f32_e32 v191, v191
	s_waitcnt vmcnt(8)
	ds_write_b128 v247, v[116:119]
	ds_write_b128 v247, v[120:123] offset:1024
	ds_write_b128 v247, v[124:127] offset:2048
	ds_write_b128 v247, v[128:131] offset:3072
	ds_read_b128 v[116:119], v248
	ds_read_b128 v[120:123], v249
	ds_read_b128 v[124:127], v250
	ds_read_b128 v[128:131], v251
	ds_write_b128 v112, v[132:135]
	ds_write_b128 v112, v[136:139] offset:1024
	ds_write_b128 v112, v[140:143] offset:2048
	ds_write_b128 v112, v[144:147] offset:3072
	v_exp_f32_e32 v192, v192
	v_exp_f32_e32 v193, v193
	v_exp_f32_e32 v194, v194
	v_exp_f32_e32 v195, v195
	s_waitcnt lgkmcnt(4)
	v_mfma_f32_32x32x16_bf16 v[32:47], v[116:119], v[48:51], v[32:47]
	v_exp_f32_e32 v196, v196
	v_exp_f32_e32 v197, v197
	v_mfma_f32_32x32x16_bf16 v[32:47], v[120:123], v[52:55], v[32:47]
	v_exp_f32_e32 v198, v198
	v_exp_f32_e32 v199, v199
	v_mfma_f32_32x32x16_bf16 v[32:47], v[124:127], v[56:59], v[32:47]
	v_exp_f32_e32 v200, v200
	v_exp_f32_e32 v201, v201
	v_mfma_f32_32x32x16_bf16 v[32:47], v[128:131], v[60:63], v[32:47]
	v_exp_f32_e32 v202, v202
	v_exp_f32_e32 v203, v203
	v_cvt_pk_bf16_f32 v64, v188, v189
	v_cvt_pk_bf16_f32 v65, v190, v191
	v_cvt_pk_bf16_f32 v66, v192, v193
	v_cvt_pk_bf16_f32 v67, v194, v195
	v_cvt_pk_bf16_f32 v68, v196, v197
	v_cvt_pk_bf16_f32 v69, v198, v199
	v_cvt_pk_bf16_f32 v70, v200, v201
	v_cvt_pk_bf16_f32 v71, v202, v203
	v_pk_add_f32 v[232:233], v[232:233], v[188:189]
	v_pk_add_f32 v[232:233], v[232:233], v[190:191]
	v_pk_add_f32 v[232:233], v[232:233], v[192:193]
	v_pk_add_f32 v[232:233], v[232:233], v[194:195]
	v_pk_add_f32 v[232:233], v[232:233], v[196:197]
	v_pk_add_f32 v[232:233], v[232:233], v[198:199]
	v_pk_add_f32 v[232:233], v[232:233], v[200:201]
	v_pk_add_f32 v[232:233], v[232:233], v[202:203]
	v_add_u32_e32 v115, 952, v115
	ds_read2_b32 v[188:189], v115 offset0:0 offset1:1
	ds_read2_b32 v[190:191], v115 offset0:2 offset1:3
	ds_read2_b32 v[192:193], v115 offset0:8 offset1:9
	ds_read2_b32 v[194:195], v115 offset0:10 offset1:11
	ds_read2_b32 v[196:197], v115 offset0:17 offset1:18
	ds_read2_b32 v[198:199], v115 offset0:19 offset1:20
	ds_read2_b32 v[200:201], v115 offset0:25 offset1:26
	ds_read2_b32 v[202:203], v115 offset0:27 offset1:28
	v_mfma_f32_32x32x16_bf16 v[0:15], v[64:67], v[72:75], v[0:15]
	v_mfma_f32_32x32x16_bf16 v[16:31], v[64:67], v[76:79], v[16:31]
	v_mfma_f32_32x32x16_bf16 v[0:15], v[68:71], v[220:223], v[0:15]
	v_mfma_f32_32x32x16_bf16 v[16:31], v[68:71], v[224:227], v[16:31]
	global_load_dwordx4 v[116:119], v235, s[84:85]
	global_load_dwordx4 v[120:123], v236, s[84:85]
	global_load_dwordx4 v[124:127], v237, s[84:85]
	global_load_dwordx4 v[128:131], v238, s[84:85]
	global_load_dwordx4 v[132:135], v100, s[84:85] offset:768
	global_load_dwordx4 v[136:139], v149, s[84:85] offset:768
	global_load_dwordx4 v[140:143], v100, s[84:85] offset:832
	global_load_dwordx4 v[144:147], v149, s[84:85] offset:832
	s_add_u32 s84, s84, 0x30000
	s_addc_u32 s85, s85, 0
	ds_read_b64_tr_b16 v[72:73], v231
	ds_read_b64_tr_b16 v[74:75], v231 offset:512
	ds_read_b64_tr_b16 v[76:77], v231 offset:2048
	ds_read_b64_tr_b16 v[78:79], v231 offset:2560
	ds_read_b64_tr_b16 v[220:221], v231 offset:1024
	ds_read_b64_tr_b16 v[222:223], v231 offset:1536
	ds_read_b64_tr_b16 v[224:225], v231 offset:3072
	ds_read_b64_tr_b16 v[226:227], v231 offset:3584
	v_exp_f32_e32 v32, v32
	v_exp_f32_e32 v33, v33
	v_exp_f32_e32 v34, v34
	v_exp_f32_e32 v35, v35
	s_waitcnt vmcnt(8)
	ds_write_b128 v247, v[156:159]
	ds_write_b128 v247, v[160:163] offset:1024
	ds_write_b128 v247, v[164:167] offset:2048
	ds_write_b128 v247, v[168:171] offset:3072
	ds_read_b128 v[156:159], v248
	ds_read_b128 v[160:163], v249
	ds_read_b128 v[164:167], v250
	ds_read_b128 v[168:171], v251
	ds_write_b128 v112, v[172:175]
	ds_write_b128 v112, v[176:179] offset:1024
	ds_write_b128 v112, v[180:183] offset:2048
	ds_write_b128 v112, v[184:187] offset:3072
	v_exp_f32_e32 v36, v36
	v_exp_f32_e32 v37, v37
	v_exp_f32_e32 v38, v38
	v_exp_f32_e32 v39, v39
	s_waitcnt lgkmcnt(4)
	v_mfma_f32_32x32x16_bf16 v[188:203], v[156:159], v[48:51], v[188:203]
	v_exp_f32_e32 v40, v40
	v_exp_f32_e32 v41, v41
	v_mfma_f32_32x32x16_bf16 v[188:203], v[160:163], v[52:55], v[188:203]
	v_exp_f32_e32 v42, v42
	v_exp_f32_e32 v43, v43
	v_mfma_f32_32x32x16_bf16 v[188:203], v[164:167], v[56:59], v[188:203]
	v_exp_f32_e32 v44, v44
	v_exp_f32_e32 v45, v45
	v_mfma_f32_32x32x16_bf16 v[188:203], v[168:171], v[60:63], v[188:203]
	v_exp_f32_e32 v46, v46
	v_exp_f32_e32 v47, v47
	v_cvt_pk_bf16_f32 v64, v32, v33
	v_cvt_pk_bf16_f32 v65, v34, v35
	v_cvt_pk_bf16_f32 v66, v36, v37
	v_cvt_pk_bf16_f32 v67, v38, v39
	v_cvt_pk_bf16_f32 v68, v40, v41
	v_cvt_pk_bf16_f32 v69, v42, v43
	v_cvt_pk_bf16_f32 v70, v44, v45
	v_cvt_pk_bf16_f32 v71, v46, v47
	v_pk_add_f32 v[232:233], v[232:233], v[32:33]
	v_pk_add_f32 v[232:233], v[232:233], v[34:35]
	v_pk_add_f32 v[232:233], v[232:233], v[36:37]
	v_pk_add_f32 v[232:233], v[232:233], v[38:39]
	v_pk_add_f32 v[232:233], v[232:233], v[40:41]
	v_pk_add_f32 v[232:233], v[232:233], v[42:43]
	v_pk_add_f32 v[232:233], v[232:233], v[44:45]
	v_pk_add_f32 v[232:233], v[232:233], v[46:47]
	ds_read2_b32 v[32:33], v115 offset0:34 offset1:35
	ds_read2_b32 v[34:35], v115 offset0:36 offset1:37
	ds_read2_b32 v[36:37], v115 offset0:42 offset1:43
	ds_read2_b32 v[38:39], v115 offset0:44 offset1:45
	ds_read2_b32 v[40:41], v115 offset0:51 offset1:52
	ds_read2_b32 v[42:43], v115 offset0:53 offset1:54
	ds_read2_b32 v[44:45], v115 offset0:59 offset1:60
	ds_read2_b32 v[46:47], v115 offset0:61 offset1:62
	v_mfma_f32_32x32x16_bf16 v[0:15], v[64:67], v[72:75], v[0:15]
	v_mfma_f32_32x32x16_bf16 v[16:31], v[64:67], v[76:79], v[16:31]
	v_mfma_f32_32x32x16_bf16 v[0:15], v[68:71], v[220:223], v[0:15]
	v_mfma_f32_32x32x16_bf16 v[16:31], v[68:71], v[224:227], v[16:31]
	global_load_dwordx4 v[156:159], v235, s[84:85]
	global_load_dwordx4 v[160:163], v236, s[84:85]
	global_load_dwordx4 v[164:167], v237, s[84:85]
	global_load_dwordx4 v[168:171], v238, s[84:85]
	global_load_dwordx4 v[172:175], v100, s[84:85] offset:768
	global_load_dwordx4 v[176:179], v149, s[84:85] offset:768
	global_load_dwordx4 v[180:183], v100, s[84:85] offset:832
	global_load_dwordx4 v[184:187], v149, s[84:85] offset:832
	s_add_u32 s84, s84, 0x30000
	s_addc_u32 s85, s85, 0
	ds_read_b64_tr_b16 v[72:73], v231
	ds_read_b64_tr_b16 v[74:75], v231 offset:512
	ds_read_b64_tr_b16 v[76:77], v231 offset:2048
	ds_read_b64_tr_b16 v[78:79], v231 offset:2560
	ds_read_b64_tr_b16 v[220:221], v231 offset:1024
	ds_read_b64_tr_b16 v[222:223], v231 offset:1536
	ds_read_b64_tr_b16 v[224:225], v231 offset:3072
	ds_read_b64_tr_b16 v[226:227], v231 offset:3584
	v_exp_f32_e32 v188, v188
	v_exp_f32_e32 v189, v189
	v_exp_f32_e32 v190, v190
	v_exp_f32_e32 v191, v191
	s_waitcnt vmcnt(8)
	ds_write_b128 v247, v[116:119]
	ds_write_b128 v247, v[120:123] offset:1024
	ds_write_b128 v247, v[124:127] offset:2048
	ds_write_b128 v247, v[128:131] offset:3072
	ds_read_b128 v[116:119], v248
	ds_read_b128 v[120:123], v249
	ds_read_b128 v[124:127], v250
	ds_read_b128 v[128:131], v251
	ds_write_b128 v112, v[132:135]
	ds_write_b128 v112, v[136:139] offset:1024
	ds_write_b128 v112, v[140:143] offset:2048
	ds_write_b128 v112, v[144:147] offset:3072
	v_exp_f32_e32 v192, v192
	v_exp_f32_e32 v193, v193
	v_exp_f32_e32 v194, v194
	v_exp_f32_e32 v195, v195
	s_waitcnt lgkmcnt(4)
	v_mfma_f32_32x32x16_bf16 v[32:47], v[116:119], v[48:51], v[32:47]
	v_exp_f32_e32 v196, v196
	v_exp_f32_e32 v197, v197
	v_mfma_f32_32x32x16_bf16 v[32:47], v[120:123], v[52:55], v[32:47]
	v_exp_f32_e32 v198, v198
	v_exp_f32_e32 v199, v199
	v_mfma_f32_32x32x16_bf16 v[32:47], v[124:127], v[56:59], v[32:47]
	v_exp_f32_e32 v200, v200
	v_exp_f32_e32 v201, v201
	v_mfma_f32_32x32x16_bf16 v[32:47], v[128:131], v[60:63], v[32:47]
	v_exp_f32_e32 v202, v202
	v_exp_f32_e32 v203, v203
	v_cvt_pk_bf16_f32 v64, v188, v189
	v_cvt_pk_bf16_f32 v65, v190, v191
	v_cvt_pk_bf16_f32 v66, v192, v193
	v_cvt_pk_bf16_f32 v67, v194, v195
	v_cvt_pk_bf16_f32 v68, v196, v197
	v_cvt_pk_bf16_f32 v69, v198, v199
	v_cvt_pk_bf16_f32 v70, v200, v201
	v_cvt_pk_bf16_f32 v71, v202, v203
	v_pk_add_f32 v[232:233], v[232:233], v[188:189]
	v_pk_add_f32 v[232:233], v[232:233], v[190:191]
	v_pk_add_f32 v[232:233], v[232:233], v[192:193]
	v_pk_add_f32 v[232:233], v[232:233], v[194:195]
	v_pk_add_f32 v[232:233], v[232:233], v[196:197]
	v_pk_add_f32 v[232:233], v[232:233], v[198:199]
	v_pk_add_f32 v[232:233], v[232:233], v[200:201]
	v_pk_add_f32 v[232:233], v[232:233], v[202:203]
	ds_read2_b32 v[188:189], v115 offset0:68 offset1:69
	ds_read2_b32 v[190:191], v115 offset0:70 offset1:71
	ds_read2_b32 v[192:193], v115 offset0:76 offset1:77
	ds_read2_b32 v[194:195], v115 offset0:78 offset1:79
	ds_read2_b32 v[196:197], v115 offset0:85 offset1:86
	ds_read2_b32 v[198:199], v115 offset0:87 offset1:88
	ds_read2_b32 v[200:201], v115 offset0:93 offset1:94
	ds_read2_b32 v[202:203], v115 offset0:95 offset1:96
	v_mfma_f32_32x32x16_bf16 v[0:15], v[64:67], v[72:75], v[0:15]
	v_mfma_f32_32x32x16_bf16 v[16:31], v[64:67], v[76:79], v[16:31]
	v_mfma_f32_32x32x16_bf16 v[0:15], v[68:71], v[220:223], v[0:15]
	v_mfma_f32_32x32x16_bf16 v[16:31], v[68:71], v[224:227], v[16:31]
	global_load_dwordx4 v[116:119], v235, s[84:85]
	global_load_dwordx4 v[120:123], v236, s[84:85]
	global_load_dwordx4 v[124:127], v237, s[84:85]
	global_load_dwordx4 v[128:131], v238, s[84:85]
	global_load_dwordx4 v[132:135], v100, s[84:85] offset:768
	global_load_dwordx4 v[136:139], v149, s[84:85] offset:768
	global_load_dwordx4 v[140:143], v100, s[84:85] offset:832
	global_load_dwordx4 v[144:147], v149, s[84:85] offset:832
	s_add_u32 s84, s84, 0x30000
	s_addc_u32 s85, s85, 0
	ds_read_b64_tr_b16 v[72:73], v231
	ds_read_b64_tr_b16 v[74:75], v231 offset:512
	ds_read_b64_tr_b16 v[76:77], v231 offset:2048
	ds_read_b64_tr_b16 v[78:79], v231 offset:2560
	ds_read_b64_tr_b16 v[220:221], v231 offset:1024
	ds_read_b64_tr_b16 v[222:223], v231 offset:1536
	ds_read_b64_tr_b16 v[224:225], v231 offset:3072
	ds_read_b64_tr_b16 v[226:227], v231 offset:3584
	v_exp_f32_e32 v32, v32
	v_exp_f32_e32 v33, v33
	v_exp_f32_e32 v34, v34
	v_exp_f32_e32 v35, v35
	s_waitcnt vmcnt(8)
	ds_write_b128 v247, v[156:159]
	ds_write_b128 v247, v[160:163] offset:1024
	ds_write_b128 v247, v[164:167] offset:2048
	ds_write_b128 v247, v[168:171] offset:3072
	ds_read_b128 v[156:159], v248
	ds_read_b128 v[160:163], v249
	ds_read_b128 v[164:167], v250
	ds_read_b128 v[168:171], v251
	ds_write_b128 v112, v[172:175]
	ds_write_b128 v112, v[176:179] offset:1024
	ds_write_b128 v112, v[180:183] offset:2048
	ds_write_b128 v112, v[184:187] offset:3072
	v_exp_f32_e32 v36, v36
	v_exp_f32_e32 v37, v37
	v_exp_f32_e32 v38, v38
	v_exp_f32_e32 v39, v39
	s_waitcnt lgkmcnt(4)
	v_mfma_f32_32x32x16_bf16 v[188:203], v[156:159], v[48:51], v[188:203]
	v_exp_f32_e32 v40, v40
	v_exp_f32_e32 v41, v41
	v_mfma_f32_32x32x16_bf16 v[188:203], v[160:163], v[52:55], v[188:203]
	v_exp_f32_e32 v42, v42
	v_exp_f32_e32 v43, v43
	v_mfma_f32_32x32x16_bf16 v[188:203], v[164:167], v[56:59], v[188:203]
	v_exp_f32_e32 v44, v44
	v_exp_f32_e32 v45, v45
	v_mfma_f32_32x32x16_bf16 v[188:203], v[168:171], v[60:63], v[188:203]
	v_exp_f32_e32 v46, v46
	v_exp_f32_e32 v47, v47
	v_cvt_pk_bf16_f32 v64, v32, v33
	v_cvt_pk_bf16_f32 v65, v34, v35
	v_cvt_pk_bf16_f32 v66, v36, v37
	v_cvt_pk_bf16_f32 v67, v38, v39
	v_cvt_pk_bf16_f32 v68, v40, v41
	v_cvt_pk_bf16_f32 v69, v42, v43
	v_cvt_pk_bf16_f32 v70, v44, v45
	v_cvt_pk_bf16_f32 v71, v46, v47
	v_pk_add_f32 v[232:233], v[232:233], v[32:33]
	v_pk_add_f32 v[232:233], v[232:233], v[34:35]
	v_pk_add_f32 v[232:233], v[232:233], v[36:37]
	v_pk_add_f32 v[232:233], v[232:233], v[38:39]
	v_pk_add_f32 v[232:233], v[232:233], v[40:41]
	v_pk_add_f32 v[232:233], v[232:233], v[42:43]
	v_pk_add_f32 v[232:233], v[232:233], v[44:45]
	v_pk_add_f32 v[232:233], v[232:233], v[46:47]
	ds_read2_b32 v[32:33], v115 offset0:102 offset1:103
	ds_read2_b32 v[34:35], v115 offset0:104 offset1:105
	ds_read2_b32 v[36:37], v115 offset0:110 offset1:111
	ds_read2_b32 v[38:39], v115 offset0:112 offset1:113
	ds_read2_b32 v[40:41], v115 offset0:119 offset1:120
	ds_read2_b32 v[42:43], v115 offset0:121 offset1:122
	ds_read2_b32 v[44:45], v115 offset0:127 offset1:128
	ds_read2_b32 v[46:47], v115 offset0:129 offset1:130
	v_mfma_f32_32x32x16_bf16 v[0:15], v[64:67], v[72:75], v[0:15]
	v_mfma_f32_32x32x16_bf16 v[16:31], v[64:67], v[76:79], v[16:31]
	v_mfma_f32_32x32x16_bf16 v[0:15], v[68:71], v[220:223], v[0:15]
	v_mfma_f32_32x32x16_bf16 v[16:31], v[68:71], v[224:227], v[16:31]
	global_load_dwordx4 v[156:159], v235, s[84:85]
	global_load_dwordx4 v[160:163], v236, s[84:85]
	global_load_dwordx4 v[164:167], v237, s[84:85]
	global_load_dwordx4 v[168:171], v238, s[84:85]
	global_load_dwordx4 v[172:175], v100, s[84:85] offset:768
	global_load_dwordx4 v[176:179], v149, s[84:85] offset:768
	global_load_dwordx4 v[180:183], v100, s[84:85] offset:832
	global_load_dwordx4 v[184:187], v149, s[84:85] offset:832
	s_add_u32 s84, s84, 0x30000
	s_addc_u32 s85, s85, 0
	ds_read_b64_tr_b16 v[72:73], v231
	ds_read_b64_tr_b16 v[74:75], v231 offset:512
	ds_read_b64_tr_b16 v[76:77], v231 offset:2048
	ds_read_b64_tr_b16 v[78:79], v231 offset:2560
	ds_read_b64_tr_b16 v[220:221], v231 offset:1024
	ds_read_b64_tr_b16 v[222:223], v231 offset:1536
	ds_read_b64_tr_b16 v[224:225], v231 offset:3072
	ds_read_b64_tr_b16 v[226:227], v231 offset:3584
	v_exp_f32_e32 v188, v188
	v_exp_f32_e32 v189, v189
	v_exp_f32_e32 v190, v190
	v_exp_f32_e32 v191, v191
	s_waitcnt vmcnt(8)
	ds_write_b128 v247, v[116:119]
	ds_write_b128 v247, v[120:123] offset:1024
	ds_write_b128 v247, v[124:127] offset:2048
	ds_write_b128 v247, v[128:131] offset:3072
	ds_read_b128 v[116:119], v248
	ds_read_b128 v[120:123], v249
	ds_read_b128 v[124:127], v250
	ds_read_b128 v[128:131], v251
	ds_write_b128 v112, v[132:135]
	ds_write_b128 v112, v[136:139] offset:1024
	ds_write_b128 v112, v[140:143] offset:2048
	ds_write_b128 v112, v[144:147] offset:3072
	v_exp_f32_e32 v192, v192
	v_exp_f32_e32 v193, v193
	v_exp_f32_e32 v194, v194
	v_exp_f32_e32 v195, v195
	s_waitcnt lgkmcnt(4)
	v_mfma_f32_32x32x16_bf16 v[32:47], v[116:119], v[48:51], v[32:47]
	v_exp_f32_e32 v196, v196
	v_exp_f32_e32 v197, v197
	v_mfma_f32_32x32x16_bf16 v[32:47], v[120:123], v[52:55], v[32:47]
	v_exp_f32_e32 v198, v198
	v_exp_f32_e32 v199, v199
	v_mfma_f32_32x32x16_bf16 v[32:47], v[124:127], v[56:59], v[32:47]
	v_exp_f32_e32 v200, v200
	v_exp_f32_e32 v201, v201
	v_mfma_f32_32x32x16_bf16 v[32:47], v[128:131], v[60:63], v[32:47]
	v_exp_f32_e32 v202, v202
	v_exp_f32_e32 v203, v203
	v_cvt_pk_bf16_f32 v64, v188, v189
	v_cvt_pk_bf16_f32 v65, v190, v191
	v_cvt_pk_bf16_f32 v66, v192, v193
	v_cvt_pk_bf16_f32 v67, v194, v195
	v_cvt_pk_bf16_f32 v68, v196, v197
	v_cvt_pk_bf16_f32 v69, v198, v199
	v_cvt_pk_bf16_f32 v70, v200, v201
	v_cvt_pk_bf16_f32 v71, v202, v203
	v_pk_add_f32 v[232:233], v[232:233], v[188:189]
	v_pk_add_f32 v[232:233], v[232:233], v[190:191]
	v_pk_add_f32 v[232:233], v[232:233], v[192:193]
	v_pk_add_f32 v[232:233], v[232:233], v[194:195]
	v_pk_add_f32 v[232:233], v[232:233], v[196:197]
	v_pk_add_f32 v[232:233], v[232:233], v[198:199]
	v_pk_add_f32 v[232:233], v[232:233], v[200:201]
	v_pk_add_f32 v[232:233], v[232:233], v[202:203]
	ds_read2_b32 v[188:189], v115 offset0:136 offset1:137
	ds_read2_b32 v[190:191], v115 offset0:138 offset1:139
	ds_read2_b32 v[192:193], v115 offset0:144 offset1:145
	ds_read2_b32 v[194:195], v115 offset0:146 offset1:147
	ds_read2_b32 v[196:197], v115 offset0:153 offset1:154
	ds_read2_b32 v[198:199], v115 offset0:155 offset1:156
	ds_read2_b32 v[200:201], v115 offset0:161 offset1:162
	ds_read2_b32 v[202:203], v115 offset0:163 offset1:164
	v_mfma_f32_32x32x16_bf16 v[0:15], v[64:67], v[72:75], v[0:15]
	v_mfma_f32_32x32x16_bf16 v[16:31], v[64:67], v[76:79], v[16:31]
	v_mfma_f32_32x32x16_bf16 v[0:15], v[68:71], v[220:223], v[0:15]
	v_mfma_f32_32x32x16_bf16 v[16:31], v[68:71], v[224:227], v[16:31]
	global_load_dwordx4 v[116:119], v235, s[84:85]
	global_load_dwordx4 v[120:123], v236, s[84:85]
	global_load_dwordx4 v[124:127], v237, s[84:85]
	global_load_dwordx4 v[128:131], v238, s[84:85]
	global_load_dwordx4 v[132:135], v100, s[84:85] offset:768
	global_load_dwordx4 v[136:139], v149, s[84:85] offset:768
	global_load_dwordx4 v[140:143], v100, s[84:85] offset:832
	global_load_dwordx4 v[144:147], v149, s[84:85] offset:832
	s_add_u32 s84, s84, 0x30000
	s_addc_u32 s85, s85, 0
	ds_read_b64_tr_b16 v[72:73], v231
	ds_read_b64_tr_b16 v[74:75], v231 offset:512
	ds_read_b64_tr_b16 v[76:77], v231 offset:2048
	ds_read_b64_tr_b16 v[78:79], v231 offset:2560
	ds_read_b64_tr_b16 v[220:221], v231 offset:1024
	ds_read_b64_tr_b16 v[222:223], v231 offset:1536
	ds_read_b64_tr_b16 v[224:225], v231 offset:3072
	ds_read_b64_tr_b16 v[226:227], v231 offset:3584
	v_exp_f32_e32 v32, v32
	v_exp_f32_e32 v33, v33
	v_exp_f32_e32 v34, v34
	v_exp_f32_e32 v35, v35
	s_waitcnt vmcnt(8)
	ds_write_b128 v247, v[156:159]
	ds_write_b128 v247, v[160:163] offset:1024
	ds_write_b128 v247, v[164:167] offset:2048
	ds_write_b128 v247, v[168:171] offset:3072
	ds_read_b128 v[156:159], v248
	ds_read_b128 v[160:163], v249
	ds_read_b128 v[164:167], v250
	ds_read_b128 v[168:171], v251
	ds_write_b128 v112, v[172:175]
	ds_write_b128 v112, v[176:179] offset:1024
	ds_write_b128 v112, v[180:183] offset:2048
	ds_write_b128 v112, v[184:187] offset:3072
	v_exp_f32_e32 v36, v36
	v_exp_f32_e32 v37, v37
	v_exp_f32_e32 v38, v38
	v_exp_f32_e32 v39, v39
	s_waitcnt lgkmcnt(4)
	v_mfma_f32_32x32x16_bf16 v[188:203], v[156:159], v[48:51], v[188:203]
	v_exp_f32_e32 v40, v40
	v_exp_f32_e32 v41, v41
	v_mfma_f32_32x32x16_bf16 v[188:203], v[160:163], v[52:55], v[188:203]
	v_exp_f32_e32 v42, v42
	v_exp_f32_e32 v43, v43
	v_mfma_f32_32x32x16_bf16 v[188:203], v[164:167], v[56:59], v[188:203]
	v_exp_f32_e32 v44, v44
	v_exp_f32_e32 v45, v45
	v_mfma_f32_32x32x16_bf16 v[188:203], v[168:171], v[60:63], v[188:203]
	v_exp_f32_e32 v46, v46
	v_exp_f32_e32 v47, v47
	v_cvt_pk_bf16_f32 v64, v32, v33
	v_cvt_pk_bf16_f32 v65, v34, v35
	v_cvt_pk_bf16_f32 v66, v36, v37
	v_cvt_pk_bf16_f32 v67, v38, v39
	v_cvt_pk_bf16_f32 v68, v40, v41
	v_cvt_pk_bf16_f32 v69, v42, v43
	v_cvt_pk_bf16_f32 v70, v44, v45
	v_cvt_pk_bf16_f32 v71, v46, v47
	v_pk_add_f32 v[232:233], v[232:233], v[32:33]
	v_pk_add_f32 v[232:233], v[232:233], v[34:35]
	v_pk_add_f32 v[232:233], v[232:233], v[36:37]
	v_pk_add_f32 v[232:233], v[232:233], v[38:39]
	v_pk_add_f32 v[232:233], v[232:233], v[40:41]
	v_pk_add_f32 v[232:233], v[232:233], v[42:43]
	v_pk_add_f32 v[232:233], v[232:233], v[44:45]
	v_pk_add_f32 v[232:233], v[232:233], v[46:47]
	ds_read2_b32 v[32:33], v115 offset0:170 offset1:171
	ds_read2_b32 v[34:35], v115 offset0:172 offset1:173
	ds_read2_b32 v[36:37], v115 offset0:178 offset1:179
	ds_read2_b32 v[38:39], v115 offset0:180 offset1:181
	ds_read2_b32 v[40:41], v115 offset0:187 offset1:188
	ds_read2_b32 v[42:43], v115 offset0:189 offset1:190
	ds_read2_b32 v[44:45], v115 offset0:195 offset1:196
	ds_read2_b32 v[46:47], v115 offset0:197 offset1:198
	v_mfma_f32_32x32x16_bf16 v[0:15], v[64:67], v[72:75], v[0:15]
	v_mfma_f32_32x32x16_bf16 v[16:31], v[64:67], v[76:79], v[16:31]
	v_mfma_f32_32x32x16_bf16 v[0:15], v[68:71], v[220:223], v[0:15]
	v_mfma_f32_32x32x16_bf16 v[16:31], v[68:71], v[224:227], v[16:31]
	global_load_dwordx4 v[156:159], v235, s[84:85]
	global_load_dwordx4 v[160:163], v236, s[84:85]
	global_load_dwordx4 v[164:167], v237, s[84:85]
	global_load_dwordx4 v[168:171], v238, s[84:85]
	global_load_dwordx4 v[172:175], v100, s[84:85] offset:768
	global_load_dwordx4 v[176:179], v149, s[84:85] offset:768
	global_load_dwordx4 v[180:183], v100, s[84:85] offset:832
	global_load_dwordx4 v[184:187], v149, s[84:85] offset:832
	s_add_u32 s84, s84, 0x30000
	s_addc_u32 s85, s85, 0
	ds_read_b64_tr_b16 v[72:73], v231
	ds_read_b64_tr_b16 v[74:75], v231 offset:512
	ds_read_b64_tr_b16 v[76:77], v231 offset:2048
	ds_read_b64_tr_b16 v[78:79], v231 offset:2560
	ds_read_b64_tr_b16 v[220:221], v231 offset:1024
	ds_read_b64_tr_b16 v[222:223], v231 offset:1536
	ds_read_b64_tr_b16 v[224:225], v231 offset:3072
	ds_read_b64_tr_b16 v[226:227], v231 offset:3584
	v_exp_f32_e32 v188, v188
	v_exp_f32_e32 v189, v189
	v_exp_f32_e32 v190, v190
	v_exp_f32_e32 v191, v191
	s_waitcnt vmcnt(8)
	ds_write_b128 v247, v[116:119]
	ds_write_b128 v247, v[120:123] offset:1024
	ds_write_b128 v247, v[124:127] offset:2048
	ds_write_b128 v247, v[128:131] offset:3072
	ds_read_b128 v[116:119], v248
	ds_read_b128 v[120:123], v249
	ds_read_b128 v[124:127], v250
	ds_read_b128 v[128:131], v251
	ds_write_b128 v112, v[132:135]
	ds_write_b128 v112, v[136:139] offset:1024
	ds_write_b128 v112, v[140:143] offset:2048
	ds_write_b128 v112, v[144:147] offset:3072
	v_exp_f32_e32 v192, v192
	v_exp_f32_e32 v193, v193
	v_exp_f32_e32 v194, v194
	v_exp_f32_e32 v195, v195
	s_waitcnt lgkmcnt(4)
	v_mfma_f32_32x32x16_bf16 v[32:47], v[116:119], v[48:51], v[32:47]
	v_exp_f32_e32 v196, v196
	v_exp_f32_e32 v197, v197
	v_mfma_f32_32x32x16_bf16 v[32:47], v[120:123], v[52:55], v[32:47]
	v_exp_f32_e32 v198, v198
	v_exp_f32_e32 v199, v199
	v_mfma_f32_32x32x16_bf16 v[32:47], v[124:127], v[56:59], v[32:47]
	v_exp_f32_e32 v200, v200
	v_exp_f32_e32 v201, v201
	v_mfma_f32_32x32x16_bf16 v[32:47], v[128:131], v[60:63], v[32:47]
	v_exp_f32_e32 v202, v202
	v_exp_f32_e32 v203, v203
	v_cvt_pk_bf16_f32 v64, v188, v189
	v_cvt_pk_bf16_f32 v65, v190, v191
	v_cvt_pk_bf16_f32 v66, v192, v193
	v_cvt_pk_bf16_f32 v67, v194, v195
	v_cvt_pk_bf16_f32 v68, v196, v197
	v_cvt_pk_bf16_f32 v69, v198, v199
	v_cvt_pk_bf16_f32 v70, v200, v201
	v_cvt_pk_bf16_f32 v71, v202, v203
	v_pk_add_f32 v[232:233], v[232:233], v[188:189]
	v_pk_add_f32 v[232:233], v[232:233], v[190:191]
	v_pk_add_f32 v[232:233], v[232:233], v[192:193]
	v_pk_add_f32 v[232:233], v[232:233], v[194:195]
	v_pk_add_f32 v[232:233], v[232:233], v[196:197]
	v_pk_add_f32 v[232:233], v[232:233], v[198:199]
	v_pk_add_f32 v[232:233], v[232:233], v[200:201]
	v_pk_add_f32 v[232:233], v[232:233], v[202:203]
	ds_read2_b32 v[188:189], v115 offset0:204 offset1:205
	ds_read2_b32 v[190:191], v115 offset0:206 offset1:207
	ds_read2_b32 v[192:193], v115 offset0:212 offset1:213
	ds_read2_b32 v[194:195], v115 offset0:214 offset1:215
	ds_read2_b32 v[196:197], v115 offset0:221 offset1:222
	ds_read2_b32 v[198:199], v115 offset0:223 offset1:224
	ds_read2_b32 v[200:201], v115 offset0:229 offset1:230
	ds_read2_b32 v[202:203], v115 offset0:231 offset1:232
	v_mfma_f32_32x32x16_bf16 v[0:15], v[64:67], v[72:75], v[0:15]
	v_mfma_f32_32x32x16_bf16 v[16:31], v[64:67], v[76:79], v[16:31]
	v_mfma_f32_32x32x16_bf16 v[0:15], v[68:71], v[220:223], v[0:15]
	v_mfma_f32_32x32x16_bf16 v[16:31], v[68:71], v[224:227], v[16:31]
	global_load_dwordx4 v[116:119], v235, s[84:85]
	global_load_dwordx4 v[120:123], v236, s[84:85]
	global_load_dwordx4 v[124:127], v237, s[84:85]
	global_load_dwordx4 v[128:131], v238, s[84:85]
	global_load_dwordx4 v[132:135], v100, s[84:85] offset:768
	global_load_dwordx4 v[136:139], v149, s[84:85] offset:768
	global_load_dwordx4 v[140:143], v100, s[84:85] offset:832
	global_load_dwordx4 v[144:147], v149, s[84:85] offset:832
	s_add_u32 s84, s84, 0x30000
	s_addc_u32 s85, s85, 0
	ds_read_b64_tr_b16 v[72:73], v231
	ds_read_b64_tr_b16 v[74:75], v231 offset:512
	ds_read_b64_tr_b16 v[76:77], v231 offset:2048
	ds_read_b64_tr_b16 v[78:79], v231 offset:2560
	ds_read_b64_tr_b16 v[220:221], v231 offset:1024
	ds_read_b64_tr_b16 v[222:223], v231 offset:1536
	ds_read_b64_tr_b16 v[224:225], v231 offset:3072
	ds_read_b64_tr_b16 v[226:227], v231 offset:3584
	v_exp_f32_e32 v32, v32
	v_exp_f32_e32 v33, v33
	v_exp_f32_e32 v34, v34
	v_exp_f32_e32 v35, v35
	s_waitcnt vmcnt(8)
	ds_write_b128 v247, v[156:159]
	ds_write_b128 v247, v[160:163] offset:1024
	ds_write_b128 v247, v[164:167] offset:2048
	ds_write_b128 v247, v[168:171] offset:3072
	ds_read_b128 v[156:159], v248
	ds_read_b128 v[160:163], v249
	ds_read_b128 v[164:167], v250
	ds_read_b128 v[168:171], v251
	ds_write_b128 v112, v[172:175]
	ds_write_b128 v112, v[176:179] offset:1024
	ds_write_b128 v112, v[180:183] offset:2048
	ds_write_b128 v112, v[184:187] offset:3072
	v_exp_f32_e32 v36, v36
	v_exp_f32_e32 v37, v37
	v_exp_f32_e32 v38, v38
	v_exp_f32_e32 v39, v39
	s_waitcnt lgkmcnt(4)
	v_mfma_f32_32x32x16_bf16 v[188:203], v[156:159], v[48:51], v[188:203]
	v_exp_f32_e32 v40, v40
	v_exp_f32_e32 v41, v41
	v_mfma_f32_32x32x16_bf16 v[188:203], v[160:163], v[52:55], v[188:203]
	v_exp_f32_e32 v42, v42
	v_exp_f32_e32 v43, v43
	v_mfma_f32_32x32x16_bf16 v[188:203], v[164:167], v[56:59], v[188:203]
	v_exp_f32_e32 v44, v44
	v_exp_f32_e32 v45, v45
	v_mfma_f32_32x32x16_bf16 v[188:203], v[168:171], v[60:63], v[188:203]
	v_exp_f32_e32 v46, v46
	v_exp_f32_e32 v47, v47
	v_cvt_pk_bf16_f32 v64, v32, v33
	v_cvt_pk_bf16_f32 v65, v34, v35
	v_cvt_pk_bf16_f32 v66, v36, v37
	v_cvt_pk_bf16_f32 v67, v38, v39
	v_cvt_pk_bf16_f32 v68, v40, v41
	v_cvt_pk_bf16_f32 v69, v42, v43
	v_cvt_pk_bf16_f32 v70, v44, v45
	v_cvt_pk_bf16_f32 v71, v46, v47
	v_pk_add_f32 v[232:233], v[232:233], v[32:33]
	v_pk_add_f32 v[232:233], v[232:233], v[34:35]
	v_pk_add_f32 v[232:233], v[232:233], v[36:37]
	v_pk_add_f32 v[232:233], v[232:233], v[38:39]
	v_pk_add_f32 v[232:233], v[232:233], v[40:41]
	v_pk_add_f32 v[232:233], v[232:233], v[42:43]
	v_pk_add_f32 v[232:233], v[232:233], v[44:45]
	v_pk_add_f32 v[232:233], v[232:233], v[46:47]
	v_add_u32_e32 v115, 952, v115
	ds_read2_b32 v[32:33], v115 offset0:0 offset1:1
	ds_read2_b32 v[34:35], v115 offset0:2 offset1:3
	ds_read2_b32 v[36:37], v115 offset0:8 offset1:9
	ds_read2_b32 v[38:39], v115 offset0:10 offset1:11
	ds_read2_b32 v[40:41], v115 offset0:17 offset1:18
	ds_read2_b32 v[42:43], v115 offset0:19 offset1:20
	ds_read2_b32 v[44:45], v115 offset0:25 offset1:26
	ds_read2_b32 v[46:47], v115 offset0:27 offset1:28
	v_mfma_f32_32x32x16_bf16 v[0:15], v[64:67], v[72:75], v[0:15]
	v_mfma_f32_32x32x16_bf16 v[16:31], v[64:67], v[76:79], v[16:31]
	v_mfma_f32_32x32x16_bf16 v[0:15], v[68:71], v[220:223], v[0:15]
	v_mfma_f32_32x32x16_bf16 v[16:31], v[68:71], v[224:227], v[16:31]
	global_load_dwordx4 v[156:159], v235, s[84:85]
	global_load_dwordx4 v[160:163], v236, s[84:85]
	global_load_dwordx4 v[164:167], v237, s[84:85]
	global_load_dwordx4 v[168:171], v238, s[84:85]
	global_load_dwordx4 v[172:175], v100, s[84:85] offset:768
	global_load_dwordx4 v[176:179], v149, s[84:85] offset:768
	global_load_dwordx4 v[180:183], v100, s[84:85] offset:832
	global_load_dwordx4 v[184:187], v149, s[84:85] offset:832
	s_add_u32 s84, s84, 0x30000
	s_addc_u32 s85, s85, 0
	ds_read_b64_tr_b16 v[72:73], v231
	ds_read_b64_tr_b16 v[74:75], v231 offset:512
	ds_read_b64_tr_b16 v[76:77], v231 offset:2048
	ds_read_b64_tr_b16 v[78:79], v231 offset:2560
	ds_read_b64_tr_b16 v[220:221], v231 offset:1024
	ds_read_b64_tr_b16 v[222:223], v231 offset:1536
	ds_read_b64_tr_b16 v[224:225], v231 offset:3072
	ds_read_b64_tr_b16 v[226:227], v231 offset:3584
	v_exp_f32_e32 v188, v188
	v_exp_f32_e32 v189, v189
	v_exp_f32_e32 v190, v190
	v_exp_f32_e32 v191, v191
	s_waitcnt vmcnt(8)
	ds_write_b128 v247, v[116:119]
	ds_write_b128 v247, v[120:123] offset:1024
	ds_write_b128 v247, v[124:127] offset:2048
	ds_write_b128 v247, v[128:131] offset:3072
	ds_read_b128 v[116:119], v248
	ds_read_b128 v[120:123], v249
	ds_read_b128 v[124:127], v250
	ds_read_b128 v[128:131], v251
	ds_write_b128 v112, v[132:135]
	ds_write_b128 v112, v[136:139] offset:1024
	ds_write_b128 v112, v[140:143] offset:2048
	ds_write_b128 v112, v[144:147] offset:3072
	v_exp_f32_e32 v192, v192
	v_exp_f32_e32 v193, v193
	v_exp_f32_e32 v194, v194
	v_exp_f32_e32 v195, v195
	s_waitcnt lgkmcnt(4)
	v_mfma_f32_32x32x16_bf16 v[32:47], v[116:119], v[48:51], v[32:47]
	v_exp_f32_e32 v196, v196
	v_exp_f32_e32 v197, v197
	v_mfma_f32_32x32x16_bf16 v[32:47], v[120:123], v[52:55], v[32:47]
	v_exp_f32_e32 v198, v198
	v_exp_f32_e32 v199, v199
	v_mfma_f32_32x32x16_bf16 v[32:47], v[124:127], v[56:59], v[32:47]
	v_exp_f32_e32 v200, v200
	v_exp_f32_e32 v201, v201
	v_mfma_f32_32x32x16_bf16 v[32:47], v[128:131], v[60:63], v[32:47]
	v_exp_f32_e32 v202, v202
	v_exp_f32_e32 v203, v203
	v_cvt_pk_bf16_f32 v64, v188, v189
	v_cvt_pk_bf16_f32 v65, v190, v191
	v_cvt_pk_bf16_f32 v66, v192, v193
	v_cvt_pk_bf16_f32 v67, v194, v195
	v_cvt_pk_bf16_f32 v68, v196, v197
	v_cvt_pk_bf16_f32 v69, v198, v199
	v_cvt_pk_bf16_f32 v70, v200, v201
	v_cvt_pk_bf16_f32 v71, v202, v203
	v_pk_add_f32 v[232:233], v[232:233], v[188:189]
	v_pk_add_f32 v[232:233], v[232:233], v[190:191]
	v_pk_add_f32 v[232:233], v[232:233], v[192:193]
	v_pk_add_f32 v[232:233], v[232:233], v[194:195]
	v_pk_add_f32 v[232:233], v[232:233], v[196:197]
	v_pk_add_f32 v[232:233], v[232:233], v[198:199]
	v_pk_add_f32 v[232:233], v[232:233], v[200:201]
	v_pk_add_f32 v[232:233], v[232:233], v[202:203]
	ds_read2_b32 v[188:189], v115 offset0:34 offset1:35
	ds_read2_b32 v[190:191], v115 offset0:36 offset1:37
	ds_read2_b32 v[192:193], v115 offset0:42 offset1:43
	ds_read2_b32 v[194:195], v115 offset0:44 offset1:45
	ds_read2_b32 v[196:197], v115 offset0:51 offset1:52
	ds_read2_b32 v[198:199], v115 offset0:53 offset1:54
	ds_read2_b32 v[200:201], v115 offset0:59 offset1:60
	ds_read2_b32 v[202:203], v115 offset0:61 offset1:62
	v_mfma_f32_32x32x16_bf16 v[0:15], v[64:67], v[72:75], v[0:15]
	v_mfma_f32_32x32x16_bf16 v[16:31], v[64:67], v[76:79], v[16:31]
	v_mfma_f32_32x32x16_bf16 v[0:15], v[68:71], v[220:223], v[0:15]
	v_mfma_f32_32x32x16_bf16 v[16:31], v[68:71], v[224:227], v[16:31]
	global_load_dwordx4 v[116:119], v235, s[84:85]
	global_load_dwordx4 v[120:123], v236, s[84:85]
	global_load_dwordx4 v[124:127], v237, s[84:85]
	global_load_dwordx4 v[128:131], v238, s[84:85]
	global_load_dwordx4 v[132:135], v100, s[84:85] offset:768
	global_load_dwordx4 v[136:139], v149, s[84:85] offset:768
	global_load_dwordx4 v[140:143], v100, s[84:85] offset:832
	global_load_dwordx4 v[144:147], v149, s[84:85] offset:832
	s_add_u32 s84, s84, 0x30000
	s_addc_u32 s85, s85, 0
	ds_read_b64_tr_b16 v[72:73], v231
	ds_read_b64_tr_b16 v[74:75], v231 offset:512
	ds_read_b64_tr_b16 v[76:77], v231 offset:2048
	ds_read_b64_tr_b16 v[78:79], v231 offset:2560
	ds_read_b64_tr_b16 v[220:221], v231 offset:1024
	ds_read_b64_tr_b16 v[222:223], v231 offset:1536
	ds_read_b64_tr_b16 v[224:225], v231 offset:3072
	ds_read_b64_tr_b16 v[226:227], v231 offset:3584
	v_exp_f32_e32 v32, v32
	v_exp_f32_e32 v33, v33
	v_exp_f32_e32 v34, v34
	v_exp_f32_e32 v35, v35
	s_waitcnt vmcnt(8)
	ds_write_b128 v247, v[156:159]
	ds_write_b128 v247, v[160:163] offset:1024
	ds_write_b128 v247, v[164:167] offset:2048
	ds_write_b128 v247, v[168:171] offset:3072
	ds_read_b128 v[156:159], v248
	ds_read_b128 v[160:163], v249
	ds_read_b128 v[164:167], v250
	ds_read_b128 v[168:171], v251
	ds_write_b128 v112, v[172:175]
	ds_write_b128 v112, v[176:179] offset:1024
	ds_write_b128 v112, v[180:183] offset:2048
	ds_write_b128 v112, v[184:187] offset:3072
	v_exp_f32_e32 v36, v36
	v_exp_f32_e32 v37, v37
	v_exp_f32_e32 v38, v38
	v_exp_f32_e32 v39, v39
	s_waitcnt lgkmcnt(4)
	v_mfma_f32_32x32x16_bf16 v[188:203], v[156:159], v[48:51], v[188:203]
	v_exp_f32_e32 v40, v40
	v_exp_f32_e32 v41, v41
	v_mfma_f32_32x32x16_bf16 v[188:203], v[160:163], v[52:55], v[188:203]
	v_exp_f32_e32 v42, v42
	v_exp_f32_e32 v43, v43
	v_mfma_f32_32x32x16_bf16 v[188:203], v[164:167], v[56:59], v[188:203]
	v_exp_f32_e32 v44, v44
	v_exp_f32_e32 v45, v45
	v_mfma_f32_32x32x16_bf16 v[188:203], v[168:171], v[60:63], v[188:203]
	v_exp_f32_e32 v46, v46
	v_exp_f32_e32 v47, v47
	v_cvt_pk_bf16_f32 v64, v32, v33
	v_cvt_pk_bf16_f32 v65, v34, v35
	v_cvt_pk_bf16_f32 v66, v36, v37
	v_cvt_pk_bf16_f32 v67, v38, v39
	v_cvt_pk_bf16_f32 v68, v40, v41
	v_cvt_pk_bf16_f32 v69, v42, v43
	v_cvt_pk_bf16_f32 v70, v44, v45
	v_cvt_pk_bf16_f32 v71, v46, v47
	v_pk_add_f32 v[232:233], v[232:233], v[32:33]
	v_pk_add_f32 v[232:233], v[232:233], v[34:35]
	v_pk_add_f32 v[232:233], v[232:233], v[36:37]
	v_pk_add_f32 v[232:233], v[232:233], v[38:39]
	v_pk_add_f32 v[232:233], v[232:233], v[40:41]
	v_pk_add_f32 v[232:233], v[232:233], v[42:43]
	v_pk_add_f32 v[232:233], v[232:233], v[44:45]
	v_pk_add_f32 v[232:233], v[232:233], v[46:47]
	ds_read2_b32 v[32:33], v115 offset0:68 offset1:69
	ds_read2_b32 v[34:35], v115 offset0:70 offset1:71
	ds_read2_b32 v[36:37], v115 offset0:76 offset1:77
	ds_read2_b32 v[38:39], v115 offset0:78 offset1:79
	ds_read2_b32 v[40:41], v115 offset0:85 offset1:86
	ds_read2_b32 v[42:43], v115 offset0:87 offset1:88
	ds_read2_b32 v[44:45], v115 offset0:93 offset1:94
	ds_read2_b32 v[46:47], v115 offset0:95 offset1:96
	v_mfma_f32_32x32x16_bf16 v[0:15], v[64:67], v[72:75], v[0:15]
	v_mfma_f32_32x32x16_bf16 v[16:31], v[64:67], v[76:79], v[16:31]
	v_mfma_f32_32x32x16_bf16 v[0:15], v[68:71], v[220:223], v[0:15]
	v_mfma_f32_32x32x16_bf16 v[16:31], v[68:71], v[224:227], v[16:31]
	global_load_dwordx4 v[156:159], v235, s[84:85]
	global_load_dwordx4 v[160:163], v236, s[84:85]
	global_load_dwordx4 v[164:167], v237, s[84:85]
	global_load_dwordx4 v[168:171], v238, s[84:85]
	global_load_dwordx4 v[172:175], v100, s[84:85] offset:768
	global_load_dwordx4 v[176:179], v149, s[84:85] offset:768
	global_load_dwordx4 v[180:183], v100, s[84:85] offset:832
	global_load_dwordx4 v[184:187], v149, s[84:85] offset:832
	s_add_u32 s84, s84, 0x30000
	s_addc_u32 s85, s85, 0
	ds_read_b64_tr_b16 v[72:73], v231
	ds_read_b64_tr_b16 v[74:75], v231 offset:512
	ds_read_b64_tr_b16 v[76:77], v231 offset:2048
	ds_read_b64_tr_b16 v[78:79], v231 offset:2560
	ds_read_b64_tr_b16 v[220:221], v231 offset:1024
	ds_read_b64_tr_b16 v[222:223], v231 offset:1536
	ds_read_b64_tr_b16 v[224:225], v231 offset:3072
	ds_read_b64_tr_b16 v[226:227], v231 offset:3584
	v_exp_f32_e32 v188, v188
	v_exp_f32_e32 v189, v189
	v_exp_f32_e32 v190, v190
	v_exp_f32_e32 v191, v191
	s_waitcnt vmcnt(8)
	ds_write_b128 v247, v[116:119]
	ds_write_b128 v247, v[120:123] offset:1024
	ds_write_b128 v247, v[124:127] offset:2048
	ds_write_b128 v247, v[128:131] offset:3072
	ds_read_b128 v[116:119], v248
	ds_read_b128 v[120:123], v249
	ds_read_b128 v[124:127], v250
	ds_read_b128 v[128:131], v251
	ds_write_b128 v112, v[132:135]
	ds_write_b128 v112, v[136:139] offset:1024
	ds_write_b128 v112, v[140:143] offset:2048
	ds_write_b128 v112, v[144:147] offset:3072
	v_exp_f32_e32 v192, v192
	v_exp_f32_e32 v193, v193
	v_exp_f32_e32 v194, v194
	v_exp_f32_e32 v195, v195
	s_waitcnt lgkmcnt(4)
	v_mfma_f32_32x32x16_bf16 v[32:47], v[116:119], v[48:51], v[32:47]
	v_exp_f32_e32 v196, v196
	v_exp_f32_e32 v197, v197
	v_mfma_f32_32x32x16_bf16 v[32:47], v[120:123], v[52:55], v[32:47]
	v_exp_f32_e32 v198, v198
	v_exp_f32_e32 v199, v199
	v_mfma_f32_32x32x16_bf16 v[32:47], v[124:127], v[56:59], v[32:47]
	v_exp_f32_e32 v200, v200
	v_exp_f32_e32 v201, v201
	v_mfma_f32_32x32x16_bf16 v[32:47], v[128:131], v[60:63], v[32:47]
	v_exp_f32_e32 v202, v202
	v_exp_f32_e32 v203, v203
	v_cvt_pk_bf16_f32 v64, v188, v189
	v_cvt_pk_bf16_f32 v65, v190, v191
	v_cvt_pk_bf16_f32 v66, v192, v193
	v_cvt_pk_bf16_f32 v67, v194, v195
	v_cvt_pk_bf16_f32 v68, v196, v197
	v_cvt_pk_bf16_f32 v69, v198, v199
	v_cvt_pk_bf16_f32 v70, v200, v201
	v_cvt_pk_bf16_f32 v71, v202, v203
	v_pk_add_f32 v[232:233], v[232:233], v[188:189]
	v_pk_add_f32 v[232:233], v[232:233], v[190:191]
	v_pk_add_f32 v[232:233], v[232:233], v[192:193]
	v_pk_add_f32 v[232:233], v[232:233], v[194:195]
	v_pk_add_f32 v[232:233], v[232:233], v[196:197]
	v_pk_add_f32 v[232:233], v[232:233], v[198:199]
	v_pk_add_f32 v[232:233], v[232:233], v[200:201]
	v_pk_add_f32 v[232:233], v[232:233], v[202:203]
	ds_read2_b32 v[188:189], v115 offset0:102 offset1:103
	ds_read2_b32 v[190:191], v115 offset0:104 offset1:105
	ds_read2_b32 v[192:193], v115 offset0:110 offset1:111
	ds_read2_b32 v[194:195], v115 offset0:112 offset1:113
	ds_read2_b32 v[196:197], v115 offset0:119 offset1:120
	ds_read2_b32 v[198:199], v115 offset0:121 offset1:122
	ds_read2_b32 v[200:201], v115 offset0:127 offset1:128
	ds_read2_b32 v[202:203], v115 offset0:129 offset1:130
	v_mfma_f32_32x32x16_bf16 v[0:15], v[64:67], v[72:75], v[0:15]
	v_mfma_f32_32x32x16_bf16 v[16:31], v[64:67], v[76:79], v[16:31]
	v_mfma_f32_32x32x16_bf16 v[0:15], v[68:71], v[220:223], v[0:15]
	v_mfma_f32_32x32x16_bf16 v[16:31], v[68:71], v[224:227], v[16:31]
	global_load_dwordx4 v[116:119], v235, s[84:85]
	global_load_dwordx4 v[120:123], v236, s[84:85]
	global_load_dwordx4 v[124:127], v237, s[84:85]
	global_load_dwordx4 v[128:131], v238, s[84:85]
	global_load_dwordx4 v[132:135], v100, s[84:85] offset:768
	global_load_dwordx4 v[136:139], v149, s[84:85] offset:768
	global_load_dwordx4 v[140:143], v100, s[84:85] offset:832
	global_load_dwordx4 v[144:147], v149, s[84:85] offset:832
	s_add_u32 s84, s84, 0x30000
	s_addc_u32 s85, s85, 0
	ds_read_b64_tr_b16 v[72:73], v231
	ds_read_b64_tr_b16 v[74:75], v231 offset:512
	ds_read_b64_tr_b16 v[76:77], v231 offset:2048
	ds_read_b64_tr_b16 v[78:79], v231 offset:2560
	ds_read_b64_tr_b16 v[220:221], v231 offset:1024
	ds_read_b64_tr_b16 v[222:223], v231 offset:1536
	ds_read_b64_tr_b16 v[224:225], v231 offset:3072
	ds_read_b64_tr_b16 v[226:227], v231 offset:3584
	v_exp_f32_e32 v32, v32
	v_exp_f32_e32 v33, v33
	v_exp_f32_e32 v34, v34
	v_exp_f32_e32 v35, v35
	s_waitcnt vmcnt(8)
	ds_write_b128 v247, v[156:159]
	ds_write_b128 v247, v[160:163] offset:1024
	ds_write_b128 v247, v[164:167] offset:2048
	ds_write_b128 v247, v[168:171] offset:3072
	ds_read_b128 v[156:159], v248
	ds_read_b128 v[160:163], v249
	ds_read_b128 v[164:167], v250
	ds_read_b128 v[168:171], v251
	ds_write_b128 v112, v[172:175]
	ds_write_b128 v112, v[176:179] offset:1024
	ds_write_b128 v112, v[180:183] offset:2048
	ds_write_b128 v112, v[184:187] offset:3072
	v_exp_f32_e32 v36, v36
	v_exp_f32_e32 v37, v37
	v_exp_f32_e32 v38, v38
	v_exp_f32_e32 v39, v39
	s_waitcnt lgkmcnt(4)
	v_mfma_f32_32x32x16_bf16 v[188:203], v[156:159], v[48:51], v[188:203]
	v_exp_f32_e32 v40, v40
	v_exp_f32_e32 v41, v41
	v_mfma_f32_32x32x16_bf16 v[188:203], v[160:163], v[52:55], v[188:203]
	v_exp_f32_e32 v42, v42
	v_exp_f32_e32 v43, v43
	v_mfma_f32_32x32x16_bf16 v[188:203], v[164:167], v[56:59], v[188:203]
	v_exp_f32_e32 v44, v44
	v_exp_f32_e32 v45, v45
	v_mfma_f32_32x32x16_bf16 v[188:203], v[168:171], v[60:63], v[188:203]
	v_exp_f32_e32 v46, v46
	v_exp_f32_e32 v47, v47
	v_cvt_pk_bf16_f32 v64, v32, v33
	v_cvt_pk_bf16_f32 v65, v34, v35
	v_cvt_pk_bf16_f32 v66, v36, v37
	v_cvt_pk_bf16_f32 v67, v38, v39
	v_cvt_pk_bf16_f32 v68, v40, v41
	v_cvt_pk_bf16_f32 v69, v42, v43
	v_cvt_pk_bf16_f32 v70, v44, v45
	v_cvt_pk_bf16_f32 v71, v46, v47
	v_pk_add_f32 v[232:233], v[232:233], v[32:33]
	v_pk_add_f32 v[232:233], v[232:233], v[34:35]
	v_pk_add_f32 v[232:233], v[232:233], v[36:37]
	v_pk_add_f32 v[232:233], v[232:233], v[38:39]
	v_pk_add_f32 v[232:233], v[232:233], v[40:41]
	v_pk_add_f32 v[232:233], v[232:233], v[42:43]
	v_pk_add_f32 v[232:233], v[232:233], v[44:45]
	v_pk_add_f32 v[232:233], v[232:233], v[46:47]
	ds_read2_b32 v[32:33], v115 offset0:136 offset1:137
	ds_read2_b32 v[34:35], v115 offset0:138 offset1:139
	ds_read2_b32 v[36:37], v115 offset0:144 offset1:145
	ds_read2_b32 v[38:39], v115 offset0:146 offset1:147
	ds_read2_b32 v[40:41], v115 offset0:153 offset1:154
	ds_read2_b32 v[42:43], v115 offset0:155 offset1:156
	ds_read2_b32 v[44:45], v115 offset0:161 offset1:162
	ds_read2_b32 v[46:47], v115 offset0:163 offset1:164
	v_mfma_f32_32x32x16_bf16 v[0:15], v[64:67], v[72:75], v[0:15]
	v_mfma_f32_32x32x16_bf16 v[16:31], v[64:67], v[76:79], v[16:31]
	v_mfma_f32_32x32x16_bf16 v[0:15], v[68:71], v[220:223], v[0:15]
	v_mfma_f32_32x32x16_bf16 v[16:31], v[68:71], v[224:227], v[16:31]
	global_load_dwordx4 v[156:159], v235, s[84:85]
	global_load_dwordx4 v[160:163], v236, s[84:85]
	global_load_dwordx4 v[164:167], v237, s[84:85]
	global_load_dwordx4 v[168:171], v238, s[84:85]
	global_load_dwordx4 v[172:175], v100, s[84:85] offset:768
	global_load_dwordx4 v[176:179], v149, s[84:85] offset:768
	global_load_dwordx4 v[180:183], v100, s[84:85] offset:832
	global_load_dwordx4 v[184:187], v149, s[84:85] offset:832
	ds_read_b64_tr_b16 v[72:73], v231
	ds_read_b64_tr_b16 v[74:75], v231 offset:512
	ds_read_b64_tr_b16 v[76:77], v231 offset:2048
	ds_read_b64_tr_b16 v[78:79], v231 offset:2560
	ds_read_b64_tr_b16 v[220:221], v231 offset:1024
	ds_read_b64_tr_b16 v[222:223], v231 offset:1536
	ds_read_b64_tr_b16 v[224:225], v231 offset:3072
	ds_read_b64_tr_b16 v[226:227], v231 offset:3584
	v_exp_f32_e32 v188, v188
	v_exp_f32_e32 v189, v189
	v_exp_f32_e32 v190, v190
	v_exp_f32_e32 v191, v191
	s_waitcnt vmcnt(8)
	ds_write_b128 v247, v[116:119]
	ds_write_b128 v247, v[120:123] offset:1024
	ds_write_b128 v247, v[124:127] offset:2048
	ds_write_b128 v247, v[128:131] offset:3072
	ds_read_b128 v[116:119], v248
	ds_read_b128 v[120:123], v249
	ds_read_b128 v[124:127], v250
	ds_read_b128 v[128:131], v251
	ds_write_b128 v112, v[132:135]
	ds_write_b128 v112, v[136:139] offset:1024
	ds_write_b128 v112, v[140:143] offset:2048
	ds_write_b128 v112, v[144:147] offset:3072
	v_exp_f32_e32 v192, v192
	v_exp_f32_e32 v193, v193
	v_exp_f32_e32 v194, v194
	v_exp_f32_e32 v195, v195
	s_waitcnt lgkmcnt(4)
	v_mfma_f32_32x32x16_bf16 v[32:47], v[116:119], v[48:51], v[32:47]
	v_exp_f32_e32 v196, v196
	v_exp_f32_e32 v197, v197
	v_mfma_f32_32x32x16_bf16 v[32:47], v[120:123], v[52:55], v[32:47]
	v_exp_f32_e32 v198, v198
	v_exp_f32_e32 v199, v199
	v_mfma_f32_32x32x16_bf16 v[32:47], v[124:127], v[56:59], v[32:47]
	v_exp_f32_e32 v200, v200
	v_exp_f32_e32 v201, v201
	v_mfma_f32_32x32x16_bf16 v[32:47], v[128:131], v[60:63], v[32:47]
	v_exp_f32_e32 v202, v202
	v_exp_f32_e32 v203, v203
	v_cvt_pk_bf16_f32 v64, v188, v189
	v_cvt_pk_bf16_f32 v65, v190, v191
	v_cvt_pk_bf16_f32 v66, v192, v193
	v_cvt_pk_bf16_f32 v67, v194, v195
	v_cvt_pk_bf16_f32 v68, v196, v197
	v_cvt_pk_bf16_f32 v69, v198, v199
	v_cvt_pk_bf16_f32 v70, v200, v201
	v_cvt_pk_bf16_f32 v71, v202, v203
	v_pk_add_f32 v[232:233], v[232:233], v[188:189]
	v_pk_add_f32 v[232:233], v[232:233], v[190:191]
	v_pk_add_f32 v[232:233], v[232:233], v[192:193]
	v_pk_add_f32 v[232:233], v[232:233], v[194:195]
	v_pk_add_f32 v[232:233], v[232:233], v[196:197]
	v_pk_add_f32 v[232:233], v[232:233], v[198:199]
	v_pk_add_f32 v[232:233], v[232:233], v[200:201]
	v_pk_add_f32 v[232:233], v[232:233], v[202:203]
	ds_read2_b32 v[188:189], v115 offset0:170 offset1:171
	ds_read2_b32 v[190:191], v115 offset0:172 offset1:173
	ds_read2_b32 v[192:193], v115 offset0:178 offset1:179
	ds_read2_b32 v[194:195], v115 offset0:180 offset1:181
	ds_read2_b32 v[196:197], v115 offset0:187 offset1:188
	ds_read2_b32 v[198:199], v115 offset0:189 offset1:190
	ds_read2_b32 v[200:201], v115 offset0:195 offset1:196
	ds_read2_b32 v[202:203], v115 offset0:197 offset1:198
	v_mfma_f32_32x32x16_bf16 v[0:15], v[64:67], v[72:75], v[0:15]
	v_mfma_f32_32x32x16_bf16 v[16:31], v[64:67], v[76:79], v[16:31]
	v_mfma_f32_32x32x16_bf16 v[0:15], v[68:71], v[220:223], v[0:15]
	v_mfma_f32_32x32x16_bf16 v[16:31], v[68:71], v[224:227], v[16:31]
	global_load_dwordx4 v[116:119], v239, s[86:87]
	global_load_dwordx4 v[120:123], v240, s[86:87]
	global_load_dwordx4 v[124:127], v241, s[86:87]
	global_load_dwordx4 v[128:131], v242, s[86:87]
	global_load_dwordx4 v[132:135], v101, s[86:87] offset:768
	global_load_dwordx4 v[136:139], v150, s[86:87] offset:768
	global_load_dwordx4 v[140:143], v101, s[86:87] offset:832
	global_load_dwordx4 v[144:147], v150, s[86:87] offset:832
	s_add_u32 s86, s86, 0xc0000
	s_addc_u32 s87, s87, 0
	ds_read_b64_tr_b16 v[72:73], v231
	ds_read_b64_tr_b16 v[74:75], v231 offset:512
	ds_read_b64_tr_b16 v[76:77], v231 offset:2048
	ds_read_b64_tr_b16 v[78:79], v231 offset:2560
	ds_read_b64_tr_b16 v[220:221], v231 offset:1024
	ds_read_b64_tr_b16 v[222:223], v231 offset:1536
	ds_read_b64_tr_b16 v[224:225], v231 offset:3072
	ds_read_b64_tr_b16 v[226:227], v231 offset:3584
	v_exp_f32_e32 v32, v32
	v_exp_f32_e32 v33, v33
	v_exp_f32_e32 v34, v34
	v_exp_f32_e32 v35, v35
	s_waitcnt vmcnt(8)
	ds_write_b128 v247, v[156:159]
	ds_write_b128 v247, v[160:163] offset:1024
	ds_write_b128 v247, v[164:167] offset:2048
	ds_write_b128 v247, v[168:171] offset:3072
	ds_read_b128 v[156:159], v248
	ds_read_b128 v[160:163], v249
	ds_read_b128 v[164:167], v250
	ds_read_b128 v[168:171], v251
	ds_write_b128 v112, v[172:175]
	ds_write_b128 v112, v[176:179] offset:1024
	ds_write_b128 v112, v[180:183] offset:2048
	ds_write_b128 v112, v[184:187] offset:3072
	v_exp_f32_e32 v36, v36
	v_exp_f32_e32 v37, v37
	v_exp_f32_e32 v38, v38
	v_exp_f32_e32 v39, v39
	s_waitcnt lgkmcnt(4)
	v_mfma_f32_32x32x16_bf16 v[188:203], v[156:159], v[48:51], v[188:203]
	v_exp_f32_e32 v40, v40
	v_exp_f32_e32 v41, v41
	v_mfma_f32_32x32x16_bf16 v[188:203], v[160:163], v[52:55], v[188:203]
	v_exp_f32_e32 v42, v42
	v_exp_f32_e32 v43, v43
	v_mfma_f32_32x32x16_bf16 v[188:203], v[164:167], v[56:59], v[188:203]
	v_exp_f32_e32 v44, v44
	v_exp_f32_e32 v45, v45
	v_mfma_f32_32x32x16_bf16 v[188:203], v[168:171], v[60:63], v[188:203]
	v_exp_f32_e32 v46, v46
	v_exp_f32_e32 v47, v47
	v_cvt_pk_bf16_f32 v64, v32, v33
	v_cvt_pk_bf16_f32 v65, v34, v35
	v_cvt_pk_bf16_f32 v66, v36, v37
	v_cvt_pk_bf16_f32 v67, v38, v39
	v_cvt_pk_bf16_f32 v68, v40, v41
	v_cvt_pk_bf16_f32 v69, v42, v43
	v_cvt_pk_bf16_f32 v70, v44, v45
	v_cvt_pk_bf16_f32 v71, v46, v47
	v_pk_add_f32 v[232:233], v[232:233], v[32:33]
	v_pk_add_f32 v[232:233], v[232:233], v[34:35]
	v_pk_add_f32 v[232:233], v[232:233], v[36:37]
	v_pk_add_f32 v[232:233], v[232:233], v[38:39]
	v_pk_add_f32 v[232:233], v[232:233], v[40:41]
	v_pk_add_f32 v[232:233], v[232:233], v[42:43]
	v_pk_add_f32 v[232:233], v[232:233], v[44:45]
	v_pk_add_f32 v[232:233], v[232:233], v[46:47]
	v_mov_b32_e32 v115, v229
	ds_read2_b32 v[32:33], v115 offset0:0 offset1:1
	ds_read2_b32 v[34:35], v115 offset0:2 offset1:3
	ds_read2_b32 v[36:37], v115 offset0:8 offset1:9
	ds_read2_b32 v[38:39], v115 offset0:10 offset1:11
	ds_read2_b32 v[40:41], v115 offset0:16 offset1:17
	ds_read2_b32 v[42:43], v115 offset0:18 offset1:19
	ds_read2_b32 v[44:45], v115 offset0:24 offset1:25
	ds_read2_b32 v[46:47], v115 offset0:26 offset1:27
	v_mfma_f32_32x32x16_bf16 v[0:15], v[64:67], v[72:75], v[0:15]
	v_mfma_f32_32x32x16_bf16 v[16:31], v[64:67], v[76:79], v[16:31]
	v_mfma_f32_32x32x16_bf16 v[0:15], v[68:71], v[220:223], v[0:15]
	v_mfma_f32_32x32x16_bf16 v[16:31], v[68:71], v[224:227], v[16:31]
	global_load_dwordx4 v[156:159], v239, s[86:87]
	global_load_dwordx4 v[160:163], v240, s[86:87]
	global_load_dwordx4 v[164:167], v241, s[86:87]
	global_load_dwordx4 v[168:171], v242, s[86:87]
	global_load_dwordx4 v[172:175], v101, s[86:87] offset:768
	global_load_dwordx4 v[176:179], v150, s[86:87] offset:768
	global_load_dwordx4 v[180:183], v101, s[86:87] offset:832
	global_load_dwordx4 v[184:187], v150, s[86:87] offset:832
	s_add_u32 s86, s86, 0xc0000
	s_addc_u32 s87, s87, 0
	ds_read_b64_tr_b16 v[72:73], v231
	ds_read_b64_tr_b16 v[74:75], v231 offset:512
	ds_read_b64_tr_b16 v[76:77], v231 offset:2048
	ds_read_b64_tr_b16 v[78:79], v231 offset:2560
	ds_read_b64_tr_b16 v[220:221], v231 offset:1024
	ds_read_b64_tr_b16 v[222:223], v231 offset:1536
	ds_read_b64_tr_b16 v[224:225], v231 offset:3072
	ds_read_b64_tr_b16 v[226:227], v231 offset:3584
	v_exp_f32_e32 v188, v188
	v_exp_f32_e32 v189, v189
	v_exp_f32_e32 v190, v190
	v_exp_f32_e32 v191, v191
	s_waitcnt vmcnt(8)
	ds_write_b128 v247, v[116:119]
	ds_write_b128 v247, v[120:123] offset:1024
	ds_write_b128 v247, v[124:127] offset:2048
	ds_write_b128 v247, v[128:131] offset:3072
	ds_read_b128 v[116:119], v248
	ds_read_b128 v[120:123], v249
	ds_read_b128 v[124:127], v250
	ds_read_b128 v[128:131], v251
	ds_write_b128 v112, v[132:135]
	ds_write_b128 v112, v[136:139] offset:1024
	ds_write_b128 v112, v[140:143] offset:2048
	ds_write_b128 v112, v[144:147] offset:3072
	v_exp_f32_e32 v192, v192
	v_exp_f32_e32 v193, v193
	v_exp_f32_e32 v194, v194
	v_exp_f32_e32 v195, v195
	s_waitcnt lgkmcnt(4)
	v_mfma_f32_32x32x16_bf16 v[32:47], v[116:119], v[48:51], v[32:47]
	v_exp_f32_e32 v196, v196
	v_exp_f32_e32 v197, v197
	v_mfma_f32_32x32x16_bf16 v[32:47], v[120:123], v[52:55], v[32:47]
	v_exp_f32_e32 v198, v198
	v_exp_f32_e32 v199, v199
	v_mfma_f32_32x32x16_bf16 v[32:47], v[124:127], v[56:59], v[32:47]
	v_exp_f32_e32 v200, v200
	v_exp_f32_e32 v201, v201
	v_mfma_f32_32x32x16_bf16 v[32:47], v[128:131], v[60:63], v[32:47]
	v_exp_f32_e32 v202, v202
	v_exp_f32_e32 v203, v203
	v_cvt_pk_bf16_f32 v64, v188, v189
	v_cvt_pk_bf16_f32 v65, v190, v191
	v_cvt_pk_bf16_f32 v66, v192, v193
	v_cvt_pk_bf16_f32 v67, v194, v195
	v_cvt_pk_bf16_f32 v68, v196, v197
	v_cvt_pk_bf16_f32 v69, v198, v199
	v_cvt_pk_bf16_f32 v70, v200, v201
	v_cvt_pk_bf16_f32 v71, v202, v203
	v_pk_add_f32 v[232:233], v[232:233], v[188:189]
	v_pk_add_f32 v[232:233], v[232:233], v[190:191]
	v_pk_add_f32 v[232:233], v[232:233], v[192:193]
	v_pk_add_f32 v[232:233], v[232:233], v[194:195]
	v_pk_add_f32 v[232:233], v[232:233], v[196:197]
	v_pk_add_f32 v[232:233], v[232:233], v[198:199]
	v_pk_add_f32 v[232:233], v[232:233], v[200:201]
	v_pk_add_f32 v[232:233], v[232:233], v[202:203]
	ds_read2_b32 v[188:189], v115 offset0:32 offset1:33
	ds_read2_b32 v[190:191], v115 offset0:34 offset1:35
	ds_read2_b32 v[192:193], v115 offset0:40 offset1:41
	ds_read2_b32 v[194:195], v115 offset0:42 offset1:43
	ds_read2_b32 v[196:197], v115 offset0:48 offset1:49
	ds_read2_b32 v[198:199], v115 offset0:50 offset1:51
	ds_read2_b32 v[200:201], v115 offset0:56 offset1:57
	ds_read2_b32 v[202:203], v115 offset0:58 offset1:59
	v_mfma_f32_32x32x16_bf16 v[0:15], v[64:67], v[72:75], v[0:15]
	v_mfma_f32_32x32x16_bf16 v[16:31], v[64:67], v[76:79], v[16:31]
	v_mfma_f32_32x32x16_bf16 v[0:15], v[68:71], v[220:223], v[0:15]
	v_mfma_f32_32x32x16_bf16 v[16:31], v[68:71], v[224:227], v[16:31]
	global_load_dwordx4 v[116:119], v239, s[86:87]
	global_load_dwordx4 v[120:123], v240, s[86:87]
	global_load_dwordx4 v[124:127], v241, s[86:87]
	global_load_dwordx4 v[128:131], v242, s[86:87]
	global_load_dwordx4 v[132:135], v101, s[86:87] offset:768
	global_load_dwordx4 v[136:139], v150, s[86:87] offset:768
	global_load_dwordx4 v[140:143], v101, s[86:87] offset:832
	global_load_dwordx4 v[144:147], v150, s[86:87] offset:832
	s_add_u32 s86, s86, 0xc0000
	s_addc_u32 s87, s87, 0
	ds_read_b64_tr_b16 v[72:73], v231
	ds_read_b64_tr_b16 v[74:75], v231 offset:512
	ds_read_b64_tr_b16 v[76:77], v231 offset:2048
	ds_read_b64_tr_b16 v[78:79], v231 offset:2560
	ds_read_b64_tr_b16 v[220:221], v231 offset:1024
	ds_read_b64_tr_b16 v[222:223], v231 offset:1536
	ds_read_b64_tr_b16 v[224:225], v231 offset:3072
	ds_read_b64_tr_b16 v[226:227], v231 offset:3584
	v_exp_f32_e32 v32, v32
	v_exp_f32_e32 v33, v33
	v_exp_f32_e32 v34, v34
	v_exp_f32_e32 v35, v35
	s_waitcnt vmcnt(8)
	ds_write_b128 v247, v[156:159]
	ds_write_b128 v247, v[160:163] offset:1024
	ds_write_b128 v247, v[164:167] offset:2048
	ds_write_b128 v247, v[168:171] offset:3072
	ds_read_b128 v[156:159], v248
	ds_read_b128 v[160:163], v249
	ds_read_b128 v[164:167], v250
	ds_read_b128 v[168:171], v251
	ds_write_b128 v112, v[172:175]
	ds_write_b128 v112, v[176:179] offset:1024
	ds_write_b128 v112, v[180:183] offset:2048
	ds_write_b128 v112, v[184:187] offset:3072
	v_exp_f32_e32 v36, v36
	v_exp_f32_e32 v37, v37
	v_exp_f32_e32 v38, v38
	v_exp_f32_e32 v39, v39
	s_waitcnt lgkmcnt(4)
	v_mfma_f32_32x32x16_bf16 v[188:203], v[156:159], v[48:51], v[188:203]
	v_exp_f32_e32 v40, v40
	v_exp_f32_e32 v41, v41
	v_mfma_f32_32x32x16_bf16 v[188:203], v[160:163], v[52:55], v[188:203]
	v_exp_f32_e32 v42, v42
	v_exp_f32_e32 v43, v43
	v_mfma_f32_32x32x16_bf16 v[188:203], v[164:167], v[56:59], v[188:203]
	v_exp_f32_e32 v44, v44
	v_exp_f32_e32 v45, v45
	v_mfma_f32_32x32x16_bf16 v[188:203], v[168:171], v[60:63], v[188:203]
	v_exp_f32_e32 v46, v46
	v_exp_f32_e32 v47, v47
	v_cvt_pk_bf16_f32 v64, v32, v33
	v_cvt_pk_bf16_f32 v65, v34, v35
	v_cvt_pk_bf16_f32 v66, v36, v37
	v_cvt_pk_bf16_f32 v67, v38, v39
	v_cvt_pk_bf16_f32 v68, v40, v41
	v_cvt_pk_bf16_f32 v69, v42, v43
	v_cvt_pk_bf16_f32 v70, v44, v45
	v_cvt_pk_bf16_f32 v71, v46, v47
	v_pk_add_f32 v[232:233], v[232:233], v[32:33]
	v_pk_add_f32 v[232:233], v[232:233], v[34:35]
	v_pk_add_f32 v[232:233], v[232:233], v[36:37]
	v_pk_add_f32 v[232:233], v[232:233], v[38:39]
	v_pk_add_f32 v[232:233], v[232:233], v[40:41]
	v_pk_add_f32 v[232:233], v[232:233], v[42:43]
	v_pk_add_f32 v[232:233], v[232:233], v[44:45]
	v_pk_add_f32 v[232:233], v[232:233], v[46:47]
	ds_read2_b32 v[32:33], v115 offset0:64 offset1:65
	ds_read2_b32 v[34:35], v115 offset0:66 offset1:67
	ds_read2_b32 v[36:37], v115 offset0:72 offset1:73
	ds_read2_b32 v[38:39], v115 offset0:74 offset1:75
	ds_read2_b32 v[40:41], v115 offset0:80 offset1:81
	ds_read2_b32 v[42:43], v115 offset0:82 offset1:83
	ds_read2_b32 v[44:45], v115 offset0:88 offset1:89
	ds_read2_b32 v[46:47], v115 offset0:90 offset1:91
	v_mfma_f32_32x32x16_bf16 v[0:15], v[64:67], v[72:75], v[0:15]
	v_mfma_f32_32x32x16_bf16 v[16:31], v[64:67], v[76:79], v[16:31]
	v_mfma_f32_32x32x16_bf16 v[0:15], v[68:71], v[220:223], v[0:15]
	v_mfma_f32_32x32x16_bf16 v[16:31], v[68:71], v[224:227], v[16:31]
	global_load_dwordx4 v[156:159], v239, s[86:87]
	global_load_dwordx4 v[160:163], v240, s[86:87]
	global_load_dwordx4 v[164:167], v241, s[86:87]
	global_load_dwordx4 v[168:171], v242, s[86:87]
	global_load_dwordx4 v[172:175], v101, s[86:87] offset:768
	global_load_dwordx4 v[176:179], v150, s[86:87] offset:768
	global_load_dwordx4 v[180:183], v101, s[86:87] offset:832
	global_load_dwordx4 v[184:187], v150, s[86:87] offset:832
	s_add_u32 s86, s86, 0xc0000
	s_addc_u32 s87, s87, 0
	ds_read_b64_tr_b16 v[72:73], v231
	ds_read_b64_tr_b16 v[74:75], v231 offset:512
	ds_read_b64_tr_b16 v[76:77], v231 offset:2048
	ds_read_b64_tr_b16 v[78:79], v231 offset:2560
	ds_read_b64_tr_b16 v[220:221], v231 offset:1024
	ds_read_b64_tr_b16 v[222:223], v231 offset:1536
	ds_read_b64_tr_b16 v[224:225], v231 offset:3072
	ds_read_b64_tr_b16 v[226:227], v231 offset:3584
	v_exp_f32_e32 v188, v188
	v_exp_f32_e32 v189, v189
	v_exp_f32_e32 v190, v190
	v_exp_f32_e32 v191, v191
	s_waitcnt vmcnt(8)
	ds_write_b128 v247, v[116:119]
	ds_write_b128 v247, v[120:123] offset:1024
	ds_write_b128 v247, v[124:127] offset:2048
	ds_write_b128 v247, v[128:131] offset:3072
	ds_read_b128 v[116:119], v248
	ds_read_b128 v[120:123], v249
	ds_read_b128 v[124:127], v250
	ds_read_b128 v[128:131], v251
	ds_write_b128 v112, v[132:135]
	ds_write_b128 v112, v[136:139] offset:1024
	ds_write_b128 v112, v[140:143] offset:2048
	ds_write_b128 v112, v[144:147] offset:3072
	v_exp_f32_e32 v192, v192
	v_exp_f32_e32 v193, v193
	v_exp_f32_e32 v194, v194
	v_exp_f32_e32 v195, v195
	s_waitcnt lgkmcnt(4)
	v_mfma_f32_32x32x16_bf16 v[32:47], v[116:119], v[48:51], v[32:47]
	v_exp_f32_e32 v196, v196
	v_exp_f32_e32 v197, v197
	v_mfma_f32_32x32x16_bf16 v[32:47], v[120:123], v[52:55], v[32:47]
	v_exp_f32_e32 v198, v198
	v_exp_f32_e32 v199, v199
	v_mfma_f32_32x32x16_bf16 v[32:47], v[124:127], v[56:59], v[32:47]
	v_exp_f32_e32 v200, v200
	v_exp_f32_e32 v201, v201
	v_mfma_f32_32x32x16_bf16 v[32:47], v[128:131], v[60:63], v[32:47]
	v_exp_f32_e32 v202, v202
	v_exp_f32_e32 v203, v203
	v_cvt_pk_bf16_f32 v64, v188, v189
	v_cvt_pk_bf16_f32 v65, v190, v191
	v_cvt_pk_bf16_f32 v66, v192, v193
	v_cvt_pk_bf16_f32 v67, v194, v195
	v_cvt_pk_bf16_f32 v68, v196, v197
	v_cvt_pk_bf16_f32 v69, v198, v199
	v_cvt_pk_bf16_f32 v70, v200, v201
	v_cvt_pk_bf16_f32 v71, v202, v203
	v_pk_add_f32 v[232:233], v[232:233], v[188:189]
	v_pk_add_f32 v[232:233], v[232:233], v[190:191]
	v_pk_add_f32 v[232:233], v[232:233], v[192:193]
	v_pk_add_f32 v[232:233], v[232:233], v[194:195]
	v_pk_add_f32 v[232:233], v[232:233], v[196:197]
	v_pk_add_f32 v[232:233], v[232:233], v[198:199]
	v_pk_add_f32 v[232:233], v[232:233], v[200:201]
	v_pk_add_f32 v[232:233], v[232:233], v[202:203]
	ds_read2_b32 v[188:189], v115 offset0:96 offset1:97
	ds_read2_b32 v[190:191], v115 offset0:98 offset1:99
	ds_read2_b32 v[192:193], v115 offset0:104 offset1:105
	ds_read2_b32 v[194:195], v115 offset0:106 offset1:107
	ds_read2_b32 v[196:197], v115 offset0:112 offset1:113
	ds_read2_b32 v[198:199], v115 offset0:114 offset1:115
	ds_read2_b32 v[200:201], v115 offset0:120 offset1:121
	ds_read2_b32 v[202:203], v115 offset0:122 offset1:123
	v_mfma_f32_32x32x16_bf16 v[0:15], v[64:67], v[72:75], v[0:15]
	v_mfma_f32_32x32x16_bf16 v[16:31], v[64:67], v[76:79], v[16:31]
	v_mfma_f32_32x32x16_bf16 v[0:15], v[68:71], v[220:223], v[0:15]
	v_mfma_f32_32x32x16_bf16 v[16:31], v[68:71], v[224:227], v[16:31]
	global_load_dwordx4 v[116:119], v239, s[86:87]
	global_load_dwordx4 v[120:123], v240, s[86:87]
	global_load_dwordx4 v[124:127], v241, s[86:87]
	global_load_dwordx4 v[128:131], v242, s[86:87]
	global_load_dwordx4 v[132:135], v101, s[86:87] offset:768
	global_load_dwordx4 v[136:139], v150, s[86:87] offset:768
	global_load_dwordx4 v[140:143], v101, s[86:87] offset:832
	global_load_dwordx4 v[144:147], v150, s[86:87] offset:832
	s_add_u32 s86, s86, 0xc0000
	s_addc_u32 s87, s87, 0
	ds_read_b64_tr_b16 v[72:73], v231
	ds_read_b64_tr_b16 v[74:75], v231 offset:512
	ds_read_b64_tr_b16 v[76:77], v231 offset:2048
	ds_read_b64_tr_b16 v[78:79], v231 offset:2560
	ds_read_b64_tr_b16 v[220:221], v231 offset:1024
	ds_read_b64_tr_b16 v[222:223], v231 offset:1536
	ds_read_b64_tr_b16 v[224:225], v231 offset:3072
	ds_read_b64_tr_b16 v[226:227], v231 offset:3584
	v_exp_f32_e32 v32, v32
	v_exp_f32_e32 v33, v33
	v_exp_f32_e32 v34, v34
	v_exp_f32_e32 v35, v35
	s_waitcnt vmcnt(8)
	ds_write_b128 v247, v[156:159]
	ds_write_b128 v247, v[160:163] offset:1024
	ds_write_b128 v247, v[164:167] offset:2048
	ds_write_b128 v247, v[168:171] offset:3072
	ds_read_b128 v[156:159], v248
	ds_read_b128 v[160:163], v249
	ds_read_b128 v[164:167], v250
	ds_read_b128 v[168:171], v251
	ds_write_b128 v112, v[172:175]
	ds_write_b128 v112, v[176:179] offset:1024
	ds_write_b128 v112, v[180:183] offset:2048
	ds_write_b128 v112, v[184:187] offset:3072
	v_exp_f32_e32 v36, v36
	v_exp_f32_e32 v37, v37
	v_exp_f32_e32 v38, v38
	v_exp_f32_e32 v39, v39
	s_waitcnt lgkmcnt(4)
	v_mfma_f32_32x32x16_bf16 v[188:203], v[156:159], v[48:51], v[188:203]
	v_exp_f32_e32 v40, v40
	v_exp_f32_e32 v41, v41
	v_mfma_f32_32x32x16_bf16 v[188:203], v[160:163], v[52:55], v[188:203]
	v_exp_f32_e32 v42, v42
	v_exp_f32_e32 v43, v43
	v_mfma_f32_32x32x16_bf16 v[188:203], v[164:167], v[56:59], v[188:203]
	v_exp_f32_e32 v44, v44
	v_exp_f32_e32 v45, v45
	v_mfma_f32_32x32x16_bf16 v[188:203], v[168:171], v[60:63], v[188:203]
	v_exp_f32_e32 v46, v46
	v_exp_f32_e32 v47, v47
	v_cvt_pk_bf16_f32 v64, v32, v33
	v_cvt_pk_bf16_f32 v65, v34, v35
	v_cvt_pk_bf16_f32 v66, v36, v37
	v_cvt_pk_bf16_f32 v67, v38, v39
	v_cvt_pk_bf16_f32 v68, v40, v41
	v_cvt_pk_bf16_f32 v69, v42, v43
	v_cvt_pk_bf16_f32 v70, v44, v45
	v_cvt_pk_bf16_f32 v71, v46, v47
	v_pk_add_f32 v[232:233], v[232:233], v[32:33]
	v_pk_add_f32 v[232:233], v[232:233], v[34:35]
	v_pk_add_f32 v[232:233], v[232:233], v[36:37]
	v_pk_add_f32 v[232:233], v[232:233], v[38:39]
	v_pk_add_f32 v[232:233], v[232:233], v[40:41]
	v_pk_add_f32 v[232:233], v[232:233], v[42:43]
	v_pk_add_f32 v[232:233], v[232:233], v[44:45]
	v_pk_add_f32 v[232:233], v[232:233], v[46:47]
	ds_read2_b32 v[32:33], v115 offset0:128 offset1:129
	ds_read2_b32 v[34:35], v115 offset0:130 offset1:131
	ds_read2_b32 v[36:37], v115 offset0:136 offset1:137
	ds_read2_b32 v[38:39], v115 offset0:138 offset1:139
	ds_read2_b32 v[40:41], v115 offset0:144 offset1:145
	ds_read2_b32 v[42:43], v115 offset0:146 offset1:147
	ds_read2_b32 v[44:45], v115 offset0:152 offset1:153
	ds_read2_b32 v[46:47], v115 offset0:154 offset1:155
	v_mfma_f32_32x32x16_bf16 v[0:15], v[64:67], v[72:75], v[0:15]
	v_mfma_f32_32x32x16_bf16 v[16:31], v[64:67], v[76:79], v[16:31]
	v_mfma_f32_32x32x16_bf16 v[0:15], v[68:71], v[220:223], v[0:15]
	v_mfma_f32_32x32x16_bf16 v[16:31], v[68:71], v[224:227], v[16:31]
	global_load_dwordx4 v[156:159], v239, s[86:87]
	global_load_dwordx4 v[160:163], v240, s[86:87]
	global_load_dwordx4 v[164:167], v241, s[86:87]
	global_load_dwordx4 v[168:171], v242, s[86:87]
	global_load_dwordx4 v[172:175], v101, s[86:87] offset:768
	global_load_dwordx4 v[176:179], v150, s[86:87] offset:768
	global_load_dwordx4 v[180:183], v101, s[86:87] offset:832
	global_load_dwordx4 v[184:187], v150, s[86:87] offset:832
	s_add_u32 s86, s86, 0xc0000
	s_addc_u32 s87, s87, 0
	ds_read_b64_tr_b16 v[72:73], v231
	ds_read_b64_tr_b16 v[74:75], v231 offset:512
	ds_read_b64_tr_b16 v[76:77], v231 offset:2048
	ds_read_b64_tr_b16 v[78:79], v231 offset:2560
	ds_read_b64_tr_b16 v[220:221], v231 offset:1024
	ds_read_b64_tr_b16 v[222:223], v231 offset:1536
	ds_read_b64_tr_b16 v[224:225], v231 offset:3072
	ds_read_b64_tr_b16 v[226:227], v231 offset:3584
	v_exp_f32_e32 v188, v188
	v_exp_f32_e32 v189, v189
	v_exp_f32_e32 v190, v190
	v_exp_f32_e32 v191, v191
	s_waitcnt vmcnt(8)
	ds_write_b128 v247, v[116:119]
	ds_write_b128 v247, v[120:123] offset:1024
	ds_write_b128 v247, v[124:127] offset:2048
	ds_write_b128 v247, v[128:131] offset:3072
	ds_read_b128 v[116:119], v248
	ds_read_b128 v[120:123], v249
	ds_read_b128 v[124:127], v250
	ds_read_b128 v[128:131], v251
	ds_write_b128 v112, v[132:135]
	ds_write_b128 v112, v[136:139] offset:1024
	ds_write_b128 v112, v[140:143] offset:2048
	ds_write_b128 v112, v[144:147] offset:3072
	v_exp_f32_e32 v192, v192
	v_exp_f32_e32 v193, v193
	v_exp_f32_e32 v194, v194
	v_exp_f32_e32 v195, v195
	s_waitcnt lgkmcnt(4)
	v_mfma_f32_32x32x16_bf16 v[32:47], v[116:119], v[48:51], v[32:47]
	v_exp_f32_e32 v196, v196
	v_exp_f32_e32 v197, v197
	v_mfma_f32_32x32x16_bf16 v[32:47], v[120:123], v[52:55], v[32:47]
	v_exp_f32_e32 v198, v198
	v_exp_f32_e32 v199, v199
	v_mfma_f32_32x32x16_bf16 v[32:47], v[124:127], v[56:59], v[32:47]
	v_exp_f32_e32 v200, v200
	v_exp_f32_e32 v201, v201
	v_mfma_f32_32x32x16_bf16 v[32:47], v[128:131], v[60:63], v[32:47]
	v_exp_f32_e32 v202, v202
	v_exp_f32_e32 v203, v203
	v_cvt_pk_bf16_f32 v64, v188, v189
	v_cvt_pk_bf16_f32 v65, v190, v191
	v_cvt_pk_bf16_f32 v66, v192, v193
	v_cvt_pk_bf16_f32 v67, v194, v195
	v_cvt_pk_bf16_f32 v68, v196, v197
	v_cvt_pk_bf16_f32 v69, v198, v199
	v_cvt_pk_bf16_f32 v70, v200, v201
	v_cvt_pk_bf16_f32 v71, v202, v203
	v_pk_add_f32 v[232:233], v[232:233], v[188:189]
	v_pk_add_f32 v[232:233], v[232:233], v[190:191]
	v_pk_add_f32 v[232:233], v[232:233], v[192:193]
	v_pk_add_f32 v[232:233], v[232:233], v[194:195]
	v_pk_add_f32 v[232:233], v[232:233], v[196:197]
	v_pk_add_f32 v[232:233], v[232:233], v[198:199]
	v_pk_add_f32 v[232:233], v[232:233], v[200:201]
	v_pk_add_f32 v[232:233], v[232:233], v[202:203]
	ds_read2_b32 v[188:189], v115 offset0:160 offset1:161
	ds_read2_b32 v[190:191], v115 offset0:162 offset1:163
	ds_read2_b32 v[192:193], v115 offset0:168 offset1:169
	ds_read2_b32 v[194:195], v115 offset0:170 offset1:171
	ds_read2_b32 v[196:197], v115 offset0:176 offset1:177
	ds_read2_b32 v[198:199], v115 offset0:178 offset1:179
	ds_read2_b32 v[200:201], v115 offset0:184 offset1:185
	ds_read2_b32 v[202:203], v115 offset0:186 offset1:187
	v_mfma_f32_32x32x16_bf16 v[0:15], v[64:67], v[72:75], v[0:15]
	v_mfma_f32_32x32x16_bf16 v[16:31], v[64:67], v[76:79], v[16:31]
	v_mfma_f32_32x32x16_bf16 v[0:15], v[68:71], v[220:223], v[0:15]
	v_mfma_f32_32x32x16_bf16 v[16:31], v[68:71], v[224:227], v[16:31]
	global_load_dwordx4 v[116:119], v239, s[86:87]
	global_load_dwordx4 v[120:123], v240, s[86:87]
	global_load_dwordx4 v[124:127], v241, s[86:87]
	global_load_dwordx4 v[128:131], v242, s[86:87]
	global_load_dwordx4 v[132:135], v101, s[86:87] offset:768
	global_load_dwordx4 v[136:139], v150, s[86:87] offset:768
	global_load_dwordx4 v[140:143], v101, s[86:87] offset:832
	global_load_dwordx4 v[144:147], v150, s[86:87] offset:832
	s_add_u32 s86, s86, 0xc0000
	s_addc_u32 s87, s87, 0
	ds_read_b64_tr_b16 v[72:73], v231
	ds_read_b64_tr_b16 v[74:75], v231 offset:512
	ds_read_b64_tr_b16 v[76:77], v231 offset:2048
	ds_read_b64_tr_b16 v[78:79], v231 offset:2560
	ds_read_b64_tr_b16 v[220:221], v231 offset:1024
	ds_read_b64_tr_b16 v[222:223], v231 offset:1536
	ds_read_b64_tr_b16 v[224:225], v231 offset:3072
	ds_read_b64_tr_b16 v[226:227], v231 offset:3584
	v_exp_f32_e32 v32, v32
	v_exp_f32_e32 v33, v33
	v_exp_f32_e32 v34, v34
	v_exp_f32_e32 v35, v35
	s_waitcnt vmcnt(8)
	ds_write_b128 v247, v[156:159]
	ds_write_b128 v247, v[160:163] offset:1024
	ds_write_b128 v247, v[164:167] offset:2048
	ds_write_b128 v247, v[168:171] offset:3072
	ds_read_b128 v[156:159], v248
	ds_read_b128 v[160:163], v249
	ds_read_b128 v[164:167], v250
	ds_read_b128 v[168:171], v251
	ds_write_b128 v112, v[172:175]
	ds_write_b128 v112, v[176:179] offset:1024
	ds_write_b128 v112, v[180:183] offset:2048
	ds_write_b128 v112, v[184:187] offset:3072
	v_exp_f32_e32 v36, v36
	v_exp_f32_e32 v37, v37
	v_exp_f32_e32 v38, v38
	v_exp_f32_e32 v39, v39
	s_waitcnt lgkmcnt(4)
	v_mfma_f32_32x32x16_bf16 v[188:203], v[156:159], v[48:51], v[188:203]
	v_exp_f32_e32 v40, v40
	v_exp_f32_e32 v41, v41
	v_mfma_f32_32x32x16_bf16 v[188:203], v[160:163], v[52:55], v[188:203]
	v_exp_f32_e32 v42, v42
	v_exp_f32_e32 v43, v43
	v_mfma_f32_32x32x16_bf16 v[188:203], v[164:167], v[56:59], v[188:203]
	v_exp_f32_e32 v44, v44
	v_exp_f32_e32 v45, v45
	v_mfma_f32_32x32x16_bf16 v[188:203], v[168:171], v[60:63], v[188:203]
	v_exp_f32_e32 v46, v46
	v_exp_f32_e32 v47, v47
	v_cvt_pk_bf16_f32 v64, v32, v33
	v_cvt_pk_bf16_f32 v65, v34, v35
	v_cvt_pk_bf16_f32 v66, v36, v37
	v_cvt_pk_bf16_f32 v67, v38, v39
	v_cvt_pk_bf16_f32 v68, v40, v41
	v_cvt_pk_bf16_f32 v69, v42, v43
	v_cvt_pk_bf16_f32 v70, v44, v45
	v_cvt_pk_bf16_f32 v71, v46, v47
	v_pk_add_f32 v[232:233], v[232:233], v[32:33]
	v_pk_add_f32 v[232:233], v[232:233], v[34:35]
	v_pk_add_f32 v[232:233], v[232:233], v[36:37]
	v_pk_add_f32 v[232:233], v[232:233], v[38:39]
	v_pk_add_f32 v[232:233], v[232:233], v[40:41]
	v_pk_add_f32 v[232:233], v[232:233], v[42:43]
	v_pk_add_f32 v[232:233], v[232:233], v[44:45]
	v_pk_add_f32 v[232:233], v[232:233], v[46:47]
	ds_read2_b32 v[32:33], v115 offset0:192 offset1:193
	ds_read2_b32 v[34:35], v115 offset0:194 offset1:195
	ds_read2_b32 v[36:37], v115 offset0:200 offset1:201
	ds_read2_b32 v[38:39], v115 offset0:202 offset1:203
	ds_read2_b32 v[40:41], v115 offset0:208 offset1:209
	ds_read2_b32 v[42:43], v115 offset0:210 offset1:211
	ds_read2_b32 v[44:45], v115 offset0:216 offset1:217
	ds_read2_b32 v[46:47], v115 offset0:218 offset1:219
	v_mfma_f32_32x32x16_bf16 v[0:15], v[64:67], v[72:75], v[0:15]
	v_mfma_f32_32x32x16_bf16 v[16:31], v[64:67], v[76:79], v[16:31]
	v_mfma_f32_32x32x16_bf16 v[0:15], v[68:71], v[220:223], v[0:15]
	v_mfma_f32_32x32x16_bf16 v[16:31], v[68:71], v[224:227], v[16:31]
	global_load_dwordx4 v[156:159], v239, s[86:87]
	global_load_dwordx4 v[160:163], v240, s[86:87]
	global_load_dwordx4 v[164:167], v241, s[86:87]
	global_load_dwordx4 v[168:171], v242, s[86:87]
	global_load_dwordx4 v[172:175], v101, s[86:87] offset:768
	global_load_dwordx4 v[176:179], v150, s[86:87] offset:768
	global_load_dwordx4 v[180:183], v101, s[86:87] offset:832
	global_load_dwordx4 v[184:187], v150, s[86:87] offset:832
	ds_read_b64_tr_b16 v[72:73], v231
	ds_read_b64_tr_b16 v[74:75], v231 offset:512
	ds_read_b64_tr_b16 v[76:77], v231 offset:2048
	ds_read_b64_tr_b16 v[78:79], v231 offset:2560
	ds_read_b64_tr_b16 v[220:221], v231 offset:1024
	ds_read_b64_tr_b16 v[222:223], v231 offset:1536
	ds_read_b64_tr_b16 v[224:225], v231 offset:3072
	ds_read_b64_tr_b16 v[226:227], v231 offset:3584
	v_exp_f32_e32 v188, v188
	v_exp_f32_e32 v189, v189
	v_exp_f32_e32 v190, v190
	v_exp_f32_e32 v191, v191
	s_waitcnt vmcnt(8)
	ds_write_b128 v247, v[116:119]
	ds_write_b128 v247, v[120:123] offset:1024
	ds_write_b128 v247, v[124:127] offset:2048
	ds_write_b128 v247, v[128:131] offset:3072
	ds_read_b128 v[116:119], v248
	ds_read_b128 v[120:123], v249
	ds_read_b128 v[124:127], v250
	ds_read_b128 v[128:131], v251
	ds_write_b128 v112, v[132:135]
	ds_write_b128 v112, v[136:139] offset:1024
	ds_write_b128 v112, v[140:143] offset:2048
	ds_write_b128 v112, v[144:147] offset:3072
	v_exp_f32_e32 v192, v192
	v_exp_f32_e32 v193, v193
	v_exp_f32_e32 v194, v194
	v_exp_f32_e32 v195, v195
	s_waitcnt lgkmcnt(4)
	v_mfma_f32_32x32x16_bf16 v[32:47], v[116:119], v[48:51], v[32:47]
	v_exp_f32_e32 v196, v196
	v_exp_f32_e32 v197, v197
	v_mfma_f32_32x32x16_bf16 v[32:47], v[120:123], v[52:55], v[32:47]
	v_exp_f32_e32 v198, v198
	v_exp_f32_e32 v199, v199
	v_mfma_f32_32x32x16_bf16 v[32:47], v[124:127], v[56:59], v[32:47]
	v_exp_f32_e32 v200, v200
	v_exp_f32_e32 v201, v201
	v_mfma_f32_32x32x16_bf16 v[32:47], v[128:131], v[60:63], v[32:47]
	v_exp_f32_e32 v202, v202
	v_exp_f32_e32 v203, v203
	v_cvt_pk_bf16_f32 v64, v188, v189
	v_cvt_pk_bf16_f32 v65, v190, v191
	v_cvt_pk_bf16_f32 v66, v192, v193
	v_cvt_pk_bf16_f32 v67, v194, v195
	v_cvt_pk_bf16_f32 v68, v196, v197
	v_cvt_pk_bf16_f32 v69, v198, v199
	v_cvt_pk_bf16_f32 v70, v200, v201
	v_cvt_pk_bf16_f32 v71, v202, v203
	v_pk_add_f32 v[232:233], v[232:233], v[188:189]
	v_pk_add_f32 v[232:233], v[232:233], v[190:191]
	v_pk_add_f32 v[232:233], v[232:233], v[192:193]
	v_pk_add_f32 v[232:233], v[232:233], v[194:195]
	v_pk_add_f32 v[232:233], v[232:233], v[196:197]
	v_pk_add_f32 v[232:233], v[232:233], v[198:199]
	v_pk_add_f32 v[232:233], v[232:233], v[200:201]
	v_pk_add_f32 v[232:233], v[232:233], v[202:203]
	ds_read2_b32 v[188:189], v115 offset0:224 offset1:225
	ds_read2_b32 v[190:191], v115 offset0:226 offset1:227
	ds_read2_b32 v[192:193], v115 offset0:232 offset1:233
	ds_read2_b32 v[194:195], v115 offset0:234 offset1:235
	ds_read2_b32 v[196:197], v115 offset0:240 offset1:241
	ds_read2_b32 v[198:199], v115 offset0:242 offset1:243
	ds_read2_b32 v[200:201], v115 offset0:248 offset1:249
	ds_read2_b32 v[202:203], v115 offset0:250 offset1:251
	v_mfma_f32_32x32x16_bf16 v[0:15], v[64:67], v[72:75], v[0:15]
	v_mfma_f32_32x32x16_bf16 v[16:31], v[64:67], v[76:79], v[16:31]
	v_mfma_f32_32x32x16_bf16 v[0:15], v[68:71], v[220:223], v[0:15]
	v_mfma_f32_32x32x16_bf16 v[16:31], v[68:71], v[224:227], v[16:31]
	global_load_dwordx4 v[116:119], v243, s[88:89]
	global_load_dwordx4 v[120:123], v244, s[88:89]
	global_load_dwordx4 v[124:127], v245, s[88:89]
	global_load_dwordx4 v[128:131], v246, s[88:89]
	global_load_dwordx4 v[132:135], v148, s[88:89] offset:768
	global_load_dwordx4 v[136:139], v151, s[88:89] offset:768
	global_load_dwordx4 v[140:143], v148, s[88:89] offset:832
	global_load_dwordx4 v[144:147], v151, s[88:89] offset:832
	s_add_u32 s88, s88, 0x300000
	s_addc_u32 s89, s89, 0
	ds_read_b64_tr_b16 v[72:73], v231
	ds_read_b64_tr_b16 v[74:75], v231 offset:512
	ds_read_b64_tr_b16 v[76:77], v231 offset:2048
	ds_read_b64_tr_b16 v[78:79], v231 offset:2560
	ds_read_b64_tr_b16 v[220:221], v231 offset:1024
	ds_read_b64_tr_b16 v[222:223], v231 offset:1536
	ds_read_b64_tr_b16 v[224:225], v231 offset:3072
	ds_read_b64_tr_b16 v[226:227], v231 offset:3584
	v_exp_f32_e32 v32, v32
	v_exp_f32_e32 v33, v33
	v_exp_f32_e32 v34, v34
	v_exp_f32_e32 v35, v35
	s_waitcnt vmcnt(8)
	ds_write_b128 v247, v[156:159]
	ds_write_b128 v247, v[160:163] offset:1024
	ds_write_b128 v247, v[164:167] offset:2048
	ds_write_b128 v247, v[168:171] offset:3072
	ds_read_b128 v[156:159], v248
	ds_read_b128 v[160:163], v249
	ds_read_b128 v[164:167], v250
	ds_read_b128 v[168:171], v251
	ds_write_b128 v112, v[172:175]
	ds_write_b128 v112, v[176:179] offset:1024
	ds_write_b128 v112, v[180:183] offset:2048
	ds_write_b128 v112, v[184:187] offset:3072
	v_exp_f32_e32 v36, v36
	v_exp_f32_e32 v37, v37
	v_exp_f32_e32 v38, v38
	v_exp_f32_e32 v39, v39
	s_waitcnt lgkmcnt(4)
	v_mfma_f32_32x32x16_bf16 v[188:203], v[156:159], v[48:51], v[188:203]
	v_exp_f32_e32 v40, v40
	v_exp_f32_e32 v41, v41
	v_mfma_f32_32x32x16_bf16 v[188:203], v[160:163], v[52:55], v[188:203]
	v_exp_f32_e32 v42, v42
	v_exp_f32_e32 v43, v43
	v_mfma_f32_32x32x16_bf16 v[188:203], v[164:167], v[56:59], v[188:203]
	v_exp_f32_e32 v44, v44
	v_exp_f32_e32 v45, v45
	v_mfma_f32_32x32x16_bf16 v[188:203], v[168:171], v[60:63], v[188:203]
	v_exp_f32_e32 v46, v46
	v_exp_f32_e32 v47, v47
	v_cvt_pk_bf16_f32 v64, v32, v33
	v_cvt_pk_bf16_f32 v65, v34, v35
	v_cvt_pk_bf16_f32 v66, v36, v37
	v_cvt_pk_bf16_f32 v67, v38, v39
	v_cvt_pk_bf16_f32 v68, v40, v41
	v_cvt_pk_bf16_f32 v69, v42, v43
	v_cvt_pk_bf16_f32 v70, v44, v45
	v_cvt_pk_bf16_f32 v71, v46, v47
	v_pk_add_f32 v[232:233], v[232:233], v[32:33]
	v_pk_add_f32 v[232:233], v[232:233], v[34:35]
	v_pk_add_f32 v[232:233], v[232:233], v[36:37]
	v_pk_add_f32 v[232:233], v[232:233], v[38:39]
	v_pk_add_f32 v[232:233], v[232:233], v[40:41]
	v_pk_add_f32 v[232:233], v[232:233], v[42:43]
	v_pk_add_f32 v[232:233], v[232:233], v[44:45]
	v_pk_add_f32 v[232:233], v[232:233], v[46:47]
	v_mov_b32_e32 v115, v230
	ds_read2_b32 v[32:33], v115 offset0:0 offset1:1
	ds_read2_b32 v[34:35], v115 offset0:2 offset1:3
	ds_read2_b32 v[36:37], v115 offset0:8 offset1:9
	ds_read2_b32 v[38:39], v115 offset0:10 offset1:11
	ds_read2_b32 v[40:41], v115 offset0:16 offset1:17
	ds_read2_b32 v[42:43], v115 offset0:18 offset1:19
	ds_read2_b32 v[44:45], v115 offset0:24 offset1:25
	ds_read2_b32 v[46:47], v115 offset0:26 offset1:27
	v_mfma_f32_32x32x16_bf16 v[0:15], v[64:67], v[72:75], v[0:15]
	v_mfma_f32_32x32x16_bf16 v[16:31], v[64:67], v[76:79], v[16:31]
	v_mfma_f32_32x32x16_bf16 v[0:15], v[68:71], v[220:223], v[0:15]
	v_mfma_f32_32x32x16_bf16 v[16:31], v[68:71], v[224:227], v[16:31]
	global_load_dwordx4 v[156:159], v243, s[88:89]
	global_load_dwordx4 v[160:163], v244, s[88:89]
	global_load_dwordx4 v[164:167], v245, s[88:89]
	global_load_dwordx4 v[168:171], v246, s[88:89]
	global_load_dwordx4 v[172:175], v148, s[88:89] offset:768
	global_load_dwordx4 v[176:179], v151, s[88:89] offset:768
	global_load_dwordx4 v[180:183], v148, s[88:89] offset:832
	global_load_dwordx4 v[184:187], v151, s[88:89] offset:832
	s_add_u32 s88, s88, 0x300000
	s_addc_u32 s89, s89, 0
	ds_read_b64_tr_b16 v[72:73], v231
	ds_read_b64_tr_b16 v[74:75], v231 offset:512
	ds_read_b64_tr_b16 v[76:77], v231 offset:2048
	ds_read_b64_tr_b16 v[78:79], v231 offset:2560
	ds_read_b64_tr_b16 v[220:221], v231 offset:1024
	ds_read_b64_tr_b16 v[222:223], v231 offset:1536
	ds_read_b64_tr_b16 v[224:225], v231 offset:3072
	ds_read_b64_tr_b16 v[226:227], v231 offset:3584
	v_exp_f32_e32 v188, v188
	v_exp_f32_e32 v189, v189
	v_exp_f32_e32 v190, v190
	v_exp_f32_e32 v191, v191
	s_waitcnt vmcnt(8)
	ds_write_b128 v247, v[116:119]
	ds_write_b128 v247, v[120:123] offset:1024
	ds_write_b128 v247, v[124:127] offset:2048
	ds_write_b128 v247, v[128:131] offset:3072
	ds_read_b128 v[116:119], v248
	ds_read_b128 v[120:123], v249
	ds_read_b128 v[124:127], v250
	ds_read_b128 v[128:131], v251
	ds_write_b128 v112, v[132:135]
	ds_write_b128 v112, v[136:139] offset:1024
	ds_write_b128 v112, v[140:143] offset:2048
	ds_write_b128 v112, v[144:147] offset:3072
	v_exp_f32_e32 v192, v192
	v_exp_f32_e32 v193, v193
	v_exp_f32_e32 v194, v194
	v_exp_f32_e32 v195, v195
	s_waitcnt lgkmcnt(4)
	v_mfma_f32_32x32x16_bf16 v[32:47], v[116:119], v[48:51], v[32:47]
	v_exp_f32_e32 v196, v196
	v_exp_f32_e32 v197, v197
	v_mfma_f32_32x32x16_bf16 v[32:47], v[120:123], v[52:55], v[32:47]
	v_exp_f32_e32 v198, v198
	v_exp_f32_e32 v199, v199
	v_mfma_f32_32x32x16_bf16 v[32:47], v[124:127], v[56:59], v[32:47]
	v_exp_f32_e32 v200, v200
	v_exp_f32_e32 v201, v201
	v_mfma_f32_32x32x16_bf16 v[32:47], v[128:131], v[60:63], v[32:47]
	v_exp_f32_e32 v202, v202
	v_exp_f32_e32 v203, v203
	v_cvt_pk_bf16_f32 v64, v188, v189
	v_cvt_pk_bf16_f32 v65, v190, v191
	v_cvt_pk_bf16_f32 v66, v192, v193
	v_cvt_pk_bf16_f32 v67, v194, v195
	v_cvt_pk_bf16_f32 v68, v196, v197
	v_cvt_pk_bf16_f32 v69, v198, v199
	v_cvt_pk_bf16_f32 v70, v200, v201
	v_cvt_pk_bf16_f32 v71, v202, v203
	v_pk_add_f32 v[232:233], v[232:233], v[188:189]
	v_pk_add_f32 v[232:233], v[232:233], v[190:191]
	v_pk_add_f32 v[232:233], v[232:233], v[192:193]
	v_pk_add_f32 v[232:233], v[232:233], v[194:195]
	v_pk_add_f32 v[232:233], v[232:233], v[196:197]
	v_pk_add_f32 v[232:233], v[232:233], v[198:199]
	v_pk_add_f32 v[232:233], v[232:233], v[200:201]
	v_pk_add_f32 v[232:233], v[232:233], v[202:203]
	ds_read2_b32 v[188:189], v115 offset0:32 offset1:33
	ds_read2_b32 v[190:191], v115 offset0:34 offset1:35
	ds_read2_b32 v[192:193], v115 offset0:40 offset1:41
	ds_read2_b32 v[194:195], v115 offset0:42 offset1:43
	ds_read2_b32 v[196:197], v115 offset0:48 offset1:49
	ds_read2_b32 v[198:199], v115 offset0:50 offset1:51
	ds_read2_b32 v[200:201], v115 offset0:56 offset1:57
	ds_read2_b32 v[202:203], v115 offset0:58 offset1:59
	v_mfma_f32_32x32x16_bf16 v[0:15], v[64:67], v[72:75], v[0:15]
	v_mfma_f32_32x32x16_bf16 v[16:31], v[64:67], v[76:79], v[16:31]
	v_mfma_f32_32x32x16_bf16 v[0:15], v[68:71], v[220:223], v[0:15]
	v_mfma_f32_32x32x16_bf16 v[16:31], v[68:71], v[224:227], v[16:31]
	global_load_dwordx4 v[116:119], v243, s[88:89]
	global_load_dwordx4 v[120:123], v244, s[88:89]
	global_load_dwordx4 v[124:127], v245, s[88:89]
	global_load_dwordx4 v[128:131], v246, s[88:89]
	global_load_dwordx4 v[132:135], v148, s[88:89] offset:768
	global_load_dwordx4 v[136:139], v151, s[88:89] offset:768
	global_load_dwordx4 v[140:143], v148, s[88:89] offset:832
	global_load_dwordx4 v[144:147], v151, s[88:89] offset:832
	s_add_u32 s88, s88, 0x300000
	s_addc_u32 s89, s89, 0
	ds_read_b64_tr_b16 v[72:73], v231
	ds_read_b64_tr_b16 v[74:75], v231 offset:512
	ds_read_b64_tr_b16 v[76:77], v231 offset:2048
	ds_read_b64_tr_b16 v[78:79], v231 offset:2560
	ds_read_b64_tr_b16 v[220:221], v231 offset:1024
	ds_read_b64_tr_b16 v[222:223], v231 offset:1536
	ds_read_b64_tr_b16 v[224:225], v231 offset:3072
	ds_read_b64_tr_b16 v[226:227], v231 offset:3584
	v_exp_f32_e32 v32, v32
	v_exp_f32_e32 v33, v33
	v_exp_f32_e32 v34, v34
	v_exp_f32_e32 v35, v35
	s_waitcnt vmcnt(8)
	ds_write_b128 v247, v[156:159]
	ds_write_b128 v247, v[160:163] offset:1024
	ds_write_b128 v247, v[164:167] offset:2048
	ds_write_b128 v247, v[168:171] offset:3072
	ds_read_b128 v[156:159], v248
	ds_read_b128 v[160:163], v249
	ds_read_b128 v[164:167], v250
	ds_read_b128 v[168:171], v251
	ds_write_b128 v112, v[172:175]
	ds_write_b128 v112, v[176:179] offset:1024
	ds_write_b128 v112, v[180:183] offset:2048
	ds_write_b128 v112, v[184:187] offset:3072
	v_exp_f32_e32 v36, v36
	v_exp_f32_e32 v37, v37
	v_exp_f32_e32 v38, v38
	v_exp_f32_e32 v39, v39
	s_waitcnt lgkmcnt(4)
	v_mfma_f32_32x32x16_bf16 v[188:203], v[156:159], v[48:51], v[188:203]
	v_exp_f32_e32 v40, v40
	v_exp_f32_e32 v41, v41
	v_mfma_f32_32x32x16_bf16 v[188:203], v[160:163], v[52:55], v[188:203]
	v_exp_f32_e32 v42, v42
	v_exp_f32_e32 v43, v43
	v_mfma_f32_32x32x16_bf16 v[188:203], v[164:167], v[56:59], v[188:203]
	v_exp_f32_e32 v44, v44
	v_exp_f32_e32 v45, v45
	v_mfma_f32_32x32x16_bf16 v[188:203], v[168:171], v[60:63], v[188:203]
	v_exp_f32_e32 v46, v46
	v_exp_f32_e32 v47, v47
	v_cvt_pk_bf16_f32 v64, v32, v33
	v_cvt_pk_bf16_f32 v65, v34, v35
	v_cvt_pk_bf16_f32 v66, v36, v37
	v_cvt_pk_bf16_f32 v67, v38, v39
	v_cvt_pk_bf16_f32 v68, v40, v41
	v_cvt_pk_bf16_f32 v69, v42, v43
	v_cvt_pk_bf16_f32 v70, v44, v45
	v_cvt_pk_bf16_f32 v71, v46, v47
	v_pk_add_f32 v[232:233], v[232:233], v[32:33]
	v_pk_add_f32 v[232:233], v[232:233], v[34:35]
	v_pk_add_f32 v[232:233], v[232:233], v[36:37]
	v_pk_add_f32 v[232:233], v[232:233], v[38:39]
	v_pk_add_f32 v[232:233], v[232:233], v[40:41]
	v_pk_add_f32 v[232:233], v[232:233], v[42:43]
	v_pk_add_f32 v[232:233], v[232:233], v[44:45]
	v_pk_add_f32 v[232:233], v[232:233], v[46:47]
	ds_read2_b32 v[32:33], v115 offset0:64 offset1:65
	ds_read2_b32 v[34:35], v115 offset0:66 offset1:67
	ds_read2_b32 v[36:37], v115 offset0:72 offset1:73
	ds_read2_b32 v[38:39], v115 offset0:74 offset1:75
	ds_read2_b32 v[40:41], v115 offset0:80 offset1:81
	ds_read2_b32 v[42:43], v115 offset0:82 offset1:83
	ds_read2_b32 v[44:45], v115 offset0:88 offset1:89
	ds_read2_b32 v[46:47], v115 offset0:90 offset1:91
	v_mfma_f32_32x32x16_bf16 v[0:15], v[64:67], v[72:75], v[0:15]
	v_mfma_f32_32x32x16_bf16 v[16:31], v[64:67], v[76:79], v[16:31]
	v_mfma_f32_32x32x16_bf16 v[0:15], v[68:71], v[220:223], v[0:15]
	v_mfma_f32_32x32x16_bf16 v[16:31], v[68:71], v[224:227], v[16:31]
	global_load_dwordx4 v[156:159], v243, s[88:89]
	global_load_dwordx4 v[160:163], v244, s[88:89]
	global_load_dwordx4 v[164:167], v245, s[88:89]
	global_load_dwordx4 v[168:171], v246, s[88:89]
	global_load_dwordx4 v[172:175], v148, s[88:89] offset:768
	global_load_dwordx4 v[176:179], v151, s[88:89] offset:768
	global_load_dwordx4 v[180:183], v148, s[88:89] offset:832
	global_load_dwordx4 v[184:187], v151, s[88:89] offset:832
	s_add_u32 s88, s88, 0x300000
	s_addc_u32 s89, s89, 0
	ds_read_b64_tr_b16 v[72:73], v231
	ds_read_b64_tr_b16 v[74:75], v231 offset:512
	ds_read_b64_tr_b16 v[76:77], v231 offset:2048
	ds_read_b64_tr_b16 v[78:79], v231 offset:2560
	ds_read_b64_tr_b16 v[220:221], v231 offset:1024
	ds_read_b64_tr_b16 v[222:223], v231 offset:1536
	ds_read_b64_tr_b16 v[224:225], v231 offset:3072
	ds_read_b64_tr_b16 v[226:227], v231 offset:3584
	v_exp_f32_e32 v188, v188
	v_exp_f32_e32 v189, v189
	v_exp_f32_e32 v190, v190
	v_exp_f32_e32 v191, v191
	s_waitcnt vmcnt(8)
	ds_write_b128 v247, v[116:119]
	ds_write_b128 v247, v[120:123] offset:1024
	ds_write_b128 v247, v[124:127] offset:2048
	ds_write_b128 v247, v[128:131] offset:3072
	ds_read_b128 v[116:119], v248
	ds_read_b128 v[120:123], v249
	ds_read_b128 v[124:127], v250
	ds_read_b128 v[128:131], v251
	ds_write_b128 v112, v[132:135]
	ds_write_b128 v112, v[136:139] offset:1024
	ds_write_b128 v112, v[140:143] offset:2048
	ds_write_b128 v112, v[144:147] offset:3072
	v_exp_f32_e32 v192, v192
	v_exp_f32_e32 v193, v193
	v_exp_f32_e32 v194, v194
	v_exp_f32_e32 v195, v195
	s_waitcnt lgkmcnt(4)
	v_mfma_f32_32x32x16_bf16 v[32:47], v[116:119], v[48:51], v[32:47]
	v_exp_f32_e32 v196, v196
	v_exp_f32_e32 v197, v197
	v_mfma_f32_32x32x16_bf16 v[32:47], v[120:123], v[52:55], v[32:47]
	v_exp_f32_e32 v198, v198
	v_exp_f32_e32 v199, v199
	v_mfma_f32_32x32x16_bf16 v[32:47], v[124:127], v[56:59], v[32:47]
	v_exp_f32_e32 v200, v200
	v_exp_f32_e32 v201, v201
	v_mfma_f32_32x32x16_bf16 v[32:47], v[128:131], v[60:63], v[32:47]
	v_exp_f32_e32 v202, v202
	v_exp_f32_e32 v203, v203
	v_cvt_pk_bf16_f32 v64, v188, v189
	v_cvt_pk_bf16_f32 v65, v190, v191
	v_cvt_pk_bf16_f32 v66, v192, v193
	v_cvt_pk_bf16_f32 v67, v194, v195
	v_cvt_pk_bf16_f32 v68, v196, v197
	v_cvt_pk_bf16_f32 v69, v198, v199
	v_cvt_pk_bf16_f32 v70, v200, v201
	v_cvt_pk_bf16_f32 v71, v202, v203
	v_pk_add_f32 v[232:233], v[232:233], v[188:189]
	v_pk_add_f32 v[232:233], v[232:233], v[190:191]
	v_pk_add_f32 v[232:233], v[232:233], v[192:193]
	v_pk_add_f32 v[232:233], v[232:233], v[194:195]
	v_pk_add_f32 v[232:233], v[232:233], v[196:197]
	v_pk_add_f32 v[232:233], v[232:233], v[198:199]
	v_pk_add_f32 v[232:233], v[232:233], v[200:201]
	v_pk_add_f32 v[232:233], v[232:233], v[202:203]
	ds_read2_b32 v[188:189], v115 offset0:96 offset1:97
	ds_read2_b32 v[190:191], v115 offset0:98 offset1:99
	ds_read2_b32 v[192:193], v115 offset0:104 offset1:105
	ds_read2_b32 v[194:195], v115 offset0:106 offset1:107
	ds_read2_b32 v[196:197], v115 offset0:112 offset1:113
	ds_read2_b32 v[198:199], v115 offset0:114 offset1:115
	ds_read2_b32 v[200:201], v115 offset0:120 offset1:121
	ds_read2_b32 v[202:203], v115 offset0:122 offset1:123
	v_mfma_f32_32x32x16_bf16 v[0:15], v[64:67], v[72:75], v[0:15]
	v_mfma_f32_32x32x16_bf16 v[16:31], v[64:67], v[76:79], v[16:31]
	v_mfma_f32_32x32x16_bf16 v[0:15], v[68:71], v[220:223], v[0:15]
	v_mfma_f32_32x32x16_bf16 v[16:31], v[68:71], v[224:227], v[16:31]
	global_load_dwordx4 v[116:119], v243, s[88:89]
	global_load_dwordx4 v[120:123], v244, s[88:89]
	global_load_dwordx4 v[124:127], v245, s[88:89]
	global_load_dwordx4 v[128:131], v246, s[88:89]
	global_load_dwordx4 v[132:135], v148, s[88:89] offset:768
	global_load_dwordx4 v[136:139], v151, s[88:89] offset:768
	global_load_dwordx4 v[140:143], v148, s[88:89] offset:832
	global_load_dwordx4 v[144:147], v151, s[88:89] offset:832
	ds_read_b64_tr_b16 v[72:73], v231
	ds_read_b64_tr_b16 v[74:75], v231 offset:512
	ds_read_b64_tr_b16 v[76:77], v231 offset:2048
	ds_read_b64_tr_b16 v[78:79], v231 offset:2560
	ds_read_b64_tr_b16 v[220:221], v231 offset:1024
	ds_read_b64_tr_b16 v[222:223], v231 offset:1536
	ds_read_b64_tr_b16 v[224:225], v231 offset:3072
	ds_read_b64_tr_b16 v[226:227], v231 offset:3584
	v_exp_f32_e32 v32, v32
	v_exp_f32_e32 v33, v33
	v_exp_f32_e32 v34, v34
	v_exp_f32_e32 v35, v35
	s_waitcnt vmcnt(8)
	ds_write_b128 v247, v[156:159]
	ds_write_b128 v247, v[160:163] offset:1024
	ds_write_b128 v247, v[164:167] offset:2048
	ds_write_b128 v247, v[168:171] offset:3072
	ds_read_b128 v[156:159], v248
	ds_read_b128 v[160:163], v249
	ds_read_b128 v[164:167], v250
	ds_read_b128 v[168:171], v251
	ds_write_b128 v112, v[172:175]
	ds_write_b128 v112, v[176:179] offset:1024
	ds_write_b128 v112, v[180:183] offset:2048
	ds_write_b128 v112, v[184:187] offset:3072
	v_exp_f32_e32 v36, v36
	v_exp_f32_e32 v37, v37
	v_exp_f32_e32 v38, v38
	v_exp_f32_e32 v39, v39
	s_waitcnt lgkmcnt(4)
	v_mfma_f32_32x32x16_bf16 v[188:203], v[156:159], v[48:51], v[188:203]
	v_exp_f32_e32 v40, v40
	v_exp_f32_e32 v41, v41
	v_mfma_f32_32x32x16_bf16 v[188:203], v[160:163], v[52:55], v[188:203]
	v_exp_f32_e32 v42, v42
	v_exp_f32_e32 v43, v43
	v_mfma_f32_32x32x16_bf16 v[188:203], v[164:167], v[56:59], v[188:203]
	v_exp_f32_e32 v44, v44
	v_exp_f32_e32 v45, v45
	v_mfma_f32_32x32x16_bf16 v[188:203], v[168:171], v[60:63], v[188:203]
	v_exp_f32_e32 v46, v46
	v_exp_f32_e32 v47, v47
	v_cvt_pk_bf16_f32 v64, v32, v33
	v_cvt_pk_bf16_f32 v65, v34, v35
	v_cvt_pk_bf16_f32 v66, v36, v37
	v_cvt_pk_bf16_f32 v67, v38, v39
	v_cvt_pk_bf16_f32 v68, v40, v41
	v_cvt_pk_bf16_f32 v69, v42, v43
	v_cvt_pk_bf16_f32 v70, v44, v45
	v_cvt_pk_bf16_f32 v71, v46, v47
	v_pk_add_f32 v[232:233], v[232:233], v[32:33]
	v_pk_add_f32 v[232:233], v[232:233], v[34:35]
	v_pk_add_f32 v[232:233], v[232:233], v[36:37]
	v_pk_add_f32 v[232:233], v[232:233], v[38:39]
	v_pk_add_f32 v[232:233], v[232:233], v[40:41]
	v_pk_add_f32 v[232:233], v[232:233], v[42:43]
	v_pk_add_f32 v[232:233], v[232:233], v[44:45]
	v_pk_add_f32 v[232:233], v[232:233], v[46:47]
	ds_read2_b32 v[32:33], v115 offset0:128 offset1:129
	ds_read2_b32 v[34:35], v115 offset0:130 offset1:131
	ds_read2_b32 v[36:37], v115 offset0:136 offset1:137
	ds_read2_b32 v[38:39], v115 offset0:138 offset1:139
	ds_read2_b32 v[40:41], v115 offset0:144 offset1:145
	ds_read2_b32 v[42:43], v115 offset0:146 offset1:147
	ds_read2_b32 v[44:45], v115 offset0:152 offset1:153
	ds_read2_b32 v[46:47], v115 offset0:154 offset1:155
	v_mfma_f32_32x32x16_bf16 v[0:15], v[64:67], v[72:75], v[0:15]
	v_mfma_f32_32x32x16_bf16 v[16:31], v[64:67], v[76:79], v[16:31]
	v_mfma_f32_32x32x16_bf16 v[0:15], v[68:71], v[220:223], v[0:15]
	v_mfma_f32_32x32x16_bf16 v[16:31], v[68:71], v[224:227], v[16:31]
	ds_read_b64_tr_b16 v[72:73], v231
	ds_read_b64_tr_b16 v[74:75], v231 offset:512
	ds_read_b64_tr_b16 v[76:77], v231 offset:2048
	ds_read_b64_tr_b16 v[78:79], v231 offset:2560
	ds_read_b64_tr_b16 v[220:221], v231 offset:1024
	ds_read_b64_tr_b16 v[222:223], v231 offset:1536
	ds_read_b64_tr_b16 v[224:225], v231 offset:3072
	ds_read_b64_tr_b16 v[226:227], v231 offset:3584
	v_exp_f32_e32 v188, v188
	v_exp_f32_e32 v189, v189
	v_exp_f32_e32 v190, v190
	v_exp_f32_e32 v191, v191
	s_waitcnt vmcnt(0)
; __device__ __forceinline__ int crow(int r, int hi) { return (r & 3) + 8 * (r >> 2) + 4 * hi; }
; __device__ __forceinline__ void dil_unit(LAS unsigned char* lds, bf16_t* proj, int seq, int hd, int T0, int rho) {
;     ...
;     for (int rr = 0; rr < 16; ++rr) {
;         const int j = crow(rr, hi);
	ds_write_b128 v247, v[116:119]
	ds_write_b128 v247, v[120:123] offset:1024
	ds_write_b128 v247, v[124:127] offset:2048
	ds_write_b128 v247, v[128:131] offset:3072
	ds_read_b128 v[116:119], v248
	ds_read_b128 v[120:123], v249
	ds_read_b128 v[124:127], v250
	ds_read_b128 v[128:131], v251
	ds_write_b128 v112, v[132:135]
	ds_write_b128 v112, v[136:139] offset:1024
	ds_write_b128 v112, v[140:143] offset:2048
	ds_write_b128 v112, v[144:147] offset:3072
	v_exp_f32_e32 v192, v192
	v_exp_f32_e32 v193, v193
	v_exp_f32_e32 v194, v194
	v_exp_f32_e32 v195, v195
	s_waitcnt lgkmcnt(4)
	v_mfma_f32_32x32x16_bf16 v[32:47], v[116:119], v[48:51], v[32:47]
	v_exp_f32_e32 v196, v196
	v_exp_f32_e32 v197, v197
	v_mfma_f32_32x32x16_bf16 v[32:47], v[120:123], v[52:55], v[32:47]
	v_exp_f32_e32 v198, v198
	v_exp_f32_e32 v199, v199
	v_mfma_f32_32x32x16_bf16 v[32:47], v[124:127], v[56:59], v[32:47]
	v_exp_f32_e32 v200, v200
	v_exp_f32_e32 v201, v201
	v_mfma_f32_32x32x16_bf16 v[32:47], v[128:131], v[60:63], v[32:47]
	v_exp_f32_e32 v202, v202
	v_exp_f32_e32 v203, v203
	v_cvt_pk_bf16_f32 v64, v188, v189
	v_cvt_pk_bf16_f32 v65, v190, v191
	v_cvt_pk_bf16_f32 v66, v192, v193
	v_cvt_pk_bf16_f32 v67, v194, v195
	v_cvt_pk_bf16_f32 v68, v196, v197
	v_cvt_pk_bf16_f32 v69, v198, v199
	v_cvt_pk_bf16_f32 v70, v200, v201
	v_cvt_pk_bf16_f32 v71, v202, v203
	v_pk_add_f32 v[232:233], v[232:233], v[188:189]
	v_pk_add_f32 v[232:233], v[232:233], v[190:191]
	v_pk_add_f32 v[232:233], v[232:233], v[192:193]
	v_pk_add_f32 v[232:233], v[232:233], v[194:195]
	v_pk_add_f32 v[232:233], v[232:233], v[196:197]
	v_pk_add_f32 v[232:233], v[232:233], v[198:199]
	v_pk_add_f32 v[232:233], v[232:233], v[200:201]
	v_pk_add_f32 v[232:233], v[232:233], v[202:203]
	v_mfma_f32_32x32x16_bf16 v[0:15], v[64:67], v[72:75], v[0:15]
	v_mfma_f32_32x32x16_bf16 v[16:31], v[64:67], v[76:79], v[16:31]
	v_mfma_f32_32x32x16_bf16 v[0:15], v[68:71], v[220:223], v[0:15]
	v_mfma_f32_32x32x16_bf16 v[16:31], v[68:71], v[224:227], v[16:31]
	ds_read_b64_tr_b16 v[72:73], v231
	ds_read_b64_tr_b16 v[74:75], v231 offset:512
	ds_read_b64_tr_b16 v[76:77], v231 offset:2048
	ds_read_b64_tr_b16 v[78:79], v231 offset:2560
	ds_read_b64_tr_b16 v[220:221], v231 offset:1024
	ds_read_b64_tr_b16 v[222:223], v231 offset:1536
	ds_read_b64_tr_b16 v[224:225], v231 offset:3072
	ds_read_b64_tr_b16 v[226:227], v231 offset:3584
	s_waitcnt lgkmcnt(0)
	v_exp_f32_e32 v32, v32
	v_exp_f32_e32 v33, v33
	v_exp_f32_e32 v34, v34
	v_exp_f32_e32 v35, v35
	v_exp_f32_e32 v36, v36
	v_exp_f32_e32 v37, v37
	v_exp_f32_e32 v38, v38
	v_exp_f32_e32 v39, v39
	v_exp_f32_e32 v40, v40
	v_exp_f32_e32 v41, v41
	v_exp_f32_e32 v42, v42
	v_exp_f32_e32 v43, v43
	v_exp_f32_e32 v44, v44
	v_exp_f32_e32 v45, v45
	v_exp_f32_e32 v46, v46
	v_exp_f32_e32 v47, v47
	v_cvt_pk_bf16_f32 v64, v32, v33
	v_cvt_pk_bf16_f32 v65, v34, v35
	v_cvt_pk_bf16_f32 v66, v36, v37
	v_cvt_pk_bf16_f32 v67, v38, v39
	v_cvt_pk_bf16_f32 v68, v40, v41
	v_cvt_pk_bf16_f32 v69, v42, v43
	v_cvt_pk_bf16_f32 v70, v44, v45
	v_cvt_pk_bf16_f32 v71, v46, v47
	v_pk_add_f32 v[232:233], v[232:233], v[32:33]
	v_pk_add_f32 v[232:233], v[232:233], v[34:35]
	v_pk_add_f32 v[232:233], v[232:233], v[36:37]
	v_pk_add_f32 v[232:233], v[232:233], v[38:39]
	v_pk_add_f32 v[232:233], v[232:233], v[40:41]
	v_pk_add_f32 v[232:233], v[232:233], v[42:43]
	v_pk_add_f32 v[232:233], v[232:233], v[44:45]
	v_pk_add_f32 v[232:233], v[232:233], v[46:47]
	v_mfma_f32_32x32x16_bf16 v[0:15], v[64:67], v[72:75], v[0:15]
	v_mfma_f32_32x32x16_bf16 v[16:31], v[64:67], v[76:79], v[16:31]
	v_mfma_f32_32x32x16_bf16 v[0:15], v[68:71], v[220:223], v[0:15]
	v_mfma_f32_32x32x16_bf16 v[16:31], v[68:71], v[224:227], v[16:31]
	v_add_f32_e32 v113, v232, v233
	v_or_b32_e32 v114, 1, v107
	v_or_b32_e32 v97, 2, v107
	v_or_b32_e32 v96, 3, v107
	v_or_b32_e32 v95, 8, v107
	v_or_b32_e32 v94, 9, v107
	v_or_b32_e32 v93, 10, v107
	v_or_b32_e32 v92, 11, v107
	v_or_b32_e32 v91, 16, v107
	v_or_b32_e32 v90, 17, v107
	v_or_b32_e32 v89, 18, v107
	v_or_b32_e32 v88, 19, v107
	v_or_b32_e32 v87, 24, v107
	v_or_b32_e32 v86, 25, v107
	v_or_b32_e32 v85, 26, v107
	v_or_b32_e32 v84, 27, v107
	s_setprio 0
	s_nop 11
	s_branch .LBB0_553
.LBB0_558:
	v_readfirstlane_b32 s91, v154
	s_nop 3
	s_bitcmp1_b32 s91, 8
	s_cbranch_scc0 .Ldb0_noprio
	s_setprio 1
; __device__ __forceinline__ void dil_unit(LAS unsigned char* lds, bf16_t* proj, int seq, int hd, int T0, int rho) {
;     ...
;     f32x16 o0 = {}, o1 = {}; float l = 0.f;
;     const bool bound = (T0 < 1024) || (T0 >= 15360);
.Ldb0_noprio:
	s_movk_i32 s100, 0x1800
	s_add_i32 s101, s6, 0x15c00
	s_lshl_b32 s90, s58, 1
	s_add_u32 s82, s56, s90
	s_addc_u32 s83, s57, 0
	s_add_u32 s82, s82, 0x1200
	s_addc_u32 s83, s83, 0
	s_sub_i32 s90, s76, 64
	s_mul_i32 s90, s90, 0x1800
	s_add_u32 s84, s82, s90
	s_addc_u32 s85, s83, 0
	s_sub_i32 s90, s76, 256
	s_mul_i32 s90, s90, 0x1800
	s_add_u32 s86, s82, s90
	s_addc_u32 s87, s83, 0
	s_sub_i32 s90, s76, 1024
	s_mul_i32 s90, s90, 0x1800
	s_add_u32 s88, s82, s90
	s_addc_u32 s89, s83, 0
	v_lshlrev_b32_e32 v153, 1, v98
	v_mad_u32_u24 v80, v105, s100, v82
	v_mad_u32_u24 v100, v110, s100, v153
	v_add_u32_e32 v149, 0x18000, v100
	v_lshlrev_b32_e32 v83, 2, v105
	v_mad_u32_u24 v83, v83, s100, v82
	v_lshlrev_b32_e32 v101, 2, v110
	v_mad_u32_u24 v101, v101, s100, v153
	v_add_u32_e32 v150, 0x60000, v101
	v_lshlrev_b32_e32 v99, 4, v105
	v_mad_u32_u24 v99, v99, s100, v82
	v_lshlrev_b32_e32 v148, 4, v110
	v_mad_u32_u24 v148, v148, s100, v153
	v_add_u32_e32 v151, 0x180000, v148
	v_lshrrev_b32_e32 v249, 3, v103
	v_and_b32_e32 v250, 7, v103
	v_lshlrev_b32_e32 v250, 4, v250
	v_add_u32_e32 v235, 0, v249
	v_add_u32_e32 v236, 8, v249
	v_add_u32_e32 v237, 16, v249
	v_add_u32_e32 v238, 24, v249
	v_add_u32_e32 v239, 0, v249
	v_lshlrev_b32_e32 v239, 2, v239
	v_add_u32_e32 v240, 8, v249
	v_lshlrev_b32_e32 v240, 2, v240
	v_add_u32_e32 v241, 16, v249
	v_lshlrev_b32_e32 v241, 2, v241
	v_add_u32_e32 v242, 24, v249
	v_lshlrev_b32_e32 v242, 2, v242
	v_add_u32_e32 v243, 0, v249
	v_lshlrev_b32_e32 v243, 4, v243
	v_add_u32_e32 v244, 8, v249
	v_lshlrev_b32_e32 v244, 4, v244
	v_add_u32_e32 v245, 16, v249
	v_lshlrev_b32_e32 v245, 4, v245
	v_add_u32_e32 v246, 24, v249
	v_lshlrev_b32_e32 v246, 4, v246
	v_mov_b32_e32 v252, v250
	v_mov_b32_e32 v100, v110
	v_add_u32_e32 v149, 16, v100
	v_lshlrev_b32_e32 v101, 2, v110
	v_add_u32_e32 v150, 64, v101
	v_lshlrev_b32_e32 v148, 4, v110
	v_add_u32_e32 v151, 256, v148
	s_mov_b32 s98, 0x4000
	s_mov_b32 s99, 0x3fff
	v_and_b32_e32 v247, 7, v249
	v_lshlrev_b32_e32 v247, 4, v247
	v_xor_b32_e32 v247, v247, v112
	v_and_b32_e32 v153, 7, v105
	v_or_b32_e32 v248, 0, v106
	v_xor_b32_e32 v248, v248, v153
	v_lshlrev_b32_e32 v248, 4, v248
	v_lshl_add_u32 v248, v105, 7, v248
	v_add_u32_e32 v248, s77, v248
	v_or_b32_e32 v249, 2, v106
	v_xor_b32_e32 v249, v249, v153
	v_lshlrev_b32_e32 v249, 4, v249
	v_lshl_add_u32 v249, v105, 7, v249
	v_add_u32_e32 v249, s77, v249
	v_or_b32_e32 v250, 4, v106
	v_xor_b32_e32 v250, v250, v153
	v_lshlrev_b32_e32 v250, 4, v250
	v_lshl_add_u32 v250, v105, 7, v250
	v_add_u32_e32 v250, s77, v250
	v_or_b32_e32 v251, 6, v106
	v_xor_b32_e32 v251, v251, v153
	v_lshlrev_b32_e32 v251, 4, v251
	v_lshl_add_u32 v251, v105, 7, v251
	v_add_u32_e32 v251, s77, v251
	v_lshlrev_b32_e32 v153, 1, v98
	v_mul_u32_u24_e32 v228, 17, v105
	v_sub_u32_e32 v228, v107, v228
	s_mul_i32 s90, s58, 153
	s_lshr_b32 s90, s90, 1
	s_add_i32 s90, s90, 34876
	v_lshl_add_u32 v228, v228, 2, s90
	v_lshlrev_b32_e32 v229, 2, v105
	v_sub_u32_e32 v229, v107, v229
	s_add_i32 s90, s101, 5104
	v_lshl_add_u32 v229, v229, 2, s90
	v_sub_u32_e32 v230, v107, v105
	s_add_i32 s90, s101, 6364
	v_lshl_add_u32 v230, v230, 2, s90
	v_add_u32_e32 v231, v109, v108
	v_mov_b64_e32 v[232:233], 0
	v_mov_b64_e32 v[0:1], 0
	v_mov_b64_e32 v[2:3], 0
	v_mov_b64_e32 v[4:5], 0
	v_mov_b64_e32 v[6:7], 0
	v_mov_b64_e32 v[8:9], 0
	v_mov_b64_e32 v[10:11], 0
	v_mov_b64_e32 v[12:13], 0
	v_mov_b64_e32 v[14:15], 0
	v_mov_b64_e32 v[16:17], 0
	v_mov_b64_e32 v[18:19], 0
	v_mov_b64_e32 v[20:21], 0
	v_mov_b64_e32 v[22:23], 0
	v_mov_b64_e32 v[24:25], 0
	v_mov_b64_e32 v[26:27], 0
	v_mov_b64_e32 v[28:29], 0
	v_mov_b64_e32 v[30:31], 0
	s_add_i32 s90, s76, -64
	v_add_u32_e32 v80, s90, v235
	v_add_u32_e32 v83, s90, v236
	v_add_u32_e32 v99, s90, v237
	v_add_u32_e32 v253, s90, v238
	v_add_u32_e32 v254, s90, v100
	v_add_u32_e32 v255, s90, v149
	v_med3_i32 v80, v80, 0, s99
	v_med3_i32 v83, v83, 0, s99
	v_med3_i32 v99, v99, 0, s99
	v_med3_i32 v253, v253, 0, s99
	v_med3_i32 v254, v254, 0, s99
	v_med3_i32 v255, v255, 0, s99
	v_mad_u32_u24 v80, v80, s100, v252
	v_mad_u32_u24 v83, v83, s100, v252
	v_mad_u32_u24 v99, v99, s100, v252
	v_mad_u32_u24 v253, v253, s100, v252
	v_mad_u32_u24 v254, v254, s100, v153
	v_mad_u32_u24 v255, v255, s100, v153
	global_load_dwordx4 v[116:119], v80, s[82:83]
	global_load_dwordx4 v[120:123], v83, s[82:83]
	global_load_dwordx4 v[124:127], v99, s[82:83]
	global_load_dwordx4 v[128:131], v253, s[82:83]
	global_load_dwordx4 v[132:135], v254, s[82:83] offset:768
	global_load_dwordx4 v[136:139], v255, s[82:83] offset:768
	global_load_dwordx4 v[140:143], v254, s[82:83] offset:832
	global_load_dwordx4 v[144:147], v255, s[82:83] offset:832
	s_add_i32 s90, s76, -32
	v_add_u32_e32 v80, s90, v235
	v_add_u32_e32 v83, s90, v236
	v_add_u32_e32 v99, s90, v237
	v_add_u32_e32 v253, s90, v238
	v_add_u32_e32 v254, s90, v100
	v_add_u32_e32 v255, s90, v149
	v_med3_i32 v80, v80, 0, s99
	v_med3_i32 v83, v83, 0, s99
	v_med3_i32 v99, v99, 0, s99
	v_med3_i32 v253, v253, 0, s99
	v_med3_i32 v254, v254, 0, s99
	v_med3_i32 v255, v255, 0, s99
	v_mad_u32_u24 v80, v80, s100, v252
	v_mad_u32_u24 v83, v83, s100, v252
	v_mad_u32_u24 v99, v99, s100, v252
	v_mad_u32_u24 v253, v253, s100, v252
	v_mad_u32_u24 v254, v254, s100, v153
	v_mad_u32_u24 v255, v255, s100, v153
	global_load_dwordx4 v[156:159], v80, s[82:83]
	global_load_dwordx4 v[160:163], v83, s[82:83]
	global_load_dwordx4 v[164:167], v99, s[82:83]
	global_load_dwordx4 v[168:171], v253, s[82:83]
	global_load_dwordx4 v[172:175], v254, s[82:83] offset:768
	global_load_dwordx4 v[176:179], v255, s[82:83] offset:768
	global_load_dwordx4 v[180:183], v254, s[82:83] offset:832
	global_load_dwordx4 v[184:187], v255, s[82:83] offset:832
	v_mov_b32_e32 v115, v228
	ds_read2_b32 v[32:33], v115 offset0:0 offset1:1
	ds_read2_b32 v[34:35], v115 offset0:2 offset1:3
	ds_read2_b32 v[36:37], v115 offset0:8 offset1:9
	ds_read2_b32 v[38:39], v115 offset0:10 offset1:11
	ds_read2_b32 v[40:41], v115 offset0:17 offset1:18
	ds_read2_b32 v[42:43], v115 offset0:19 offset1:20
	ds_read2_b32 v[44:45], v115 offset0:25 offset1:26
	ds_read2_b32 v[46:47], v115 offset0:27 offset1:28
	s_waitcnt vmcnt(8)
	ds_write_b128 v247, v[116:119]
	ds_write_b128 v247, v[120:123] offset:1024
	ds_write_b128 v247, v[124:127] offset:2048
	ds_write_b128 v247, v[128:131] offset:3072
	ds_read_b128 v[116:119], v248
	ds_read_b128 v[120:123], v249
	ds_read_b128 v[124:127], v250
	ds_read_b128 v[128:131], v251
	ds_write_b128 v112, v[132:135]
	ds_write_b128 v112, v[136:139] offset:1024
	ds_write_b128 v112, v[140:143] offset:2048
	ds_write_b128 v112, v[144:147] offset:3072
	s_waitcnt lgkmcnt(4)
	v_mfma_f32_32x32x16_bf16 v[32:47], v[116:119], v[48:51], v[32:47]
	v_mfma_f32_32x32x16_bf16 v[32:47], v[120:123], v[52:55], v[32:47]
	v_mfma_f32_32x32x16_bf16 v[32:47], v[124:127], v[56:59], v[32:47]
	v_mfma_f32_32x32x16_bf16 v[32:47], v[128:131], v[60:63], v[32:47]
	ds_read2_b32 v[188:189], v115 offset0:34 offset1:35
	ds_read2_b32 v[190:191], v115 offset0:36 offset1:37
	ds_read2_b32 v[192:193], v115 offset0:42 offset1:43
	ds_read2_b32 v[194:195], v115 offset0:44 offset1:45
	ds_read2_b32 v[196:197], v115 offset0:51 offset1:52
	ds_read2_b32 v[198:199], v115 offset0:53 offset1:54
	ds_read2_b32 v[200:201], v115 offset0:59 offset1:60
	ds_read2_b32 v[202:203], v115 offset0:61 offset1:62
	s_add_i32 s90, s76, 0
	v_add_u32_e32 v80, s90, v235
	v_add_u32_e32 v83, s90, v236
	v_add_u32_e32 v99, s90, v237
	v_add_u32_e32 v253, s90, v238
	v_add_u32_e32 v254, s90, v100
	v_add_u32_e32 v255, s90, v149
	v_med3_i32 v80, v80, 0, s99
	v_med3_i32 v83, v83, 0, s99
	v_med3_i32 v99, v99, 0, s99
	v_med3_i32 v253, v253, 0, s99
	v_med3_i32 v254, v254, 0, s99
	v_med3_i32 v255, v255, 0, s99
	v_mad_u32_u24 v80, v80, s100, v252
	v_mad_u32_u24 v83, v83, s100, v252
	v_mad_u32_u24 v99, v99, s100, v252
	v_mad_u32_u24 v253, v253, s100, v252
	v_mad_u32_u24 v254, v254, s100, v153
	v_mad_u32_u24 v255, v255, s100, v153
	global_load_dwordx4 v[116:119], v80, s[82:83]
	global_load_dwordx4 v[120:123], v83, s[82:83]
	global_load_dwordx4 v[124:127], v99, s[82:83]
	global_load_dwordx4 v[128:131], v253, s[82:83]
	global_load_dwordx4 v[132:135], v254, s[82:83] offset:768
	global_load_dwordx4 v[136:139], v255, s[82:83] offset:768
	global_load_dwordx4 v[140:143], v254, s[82:83] offset:832
	global_load_dwordx4 v[144:147], v255, s[82:83] offset:832
	ds_read_b64_tr_b16 v[72:73], v231
	ds_read_b64_tr_b16 v[74:75], v231 offset:512
	ds_read_b64_tr_b16 v[76:77], v231 offset:2048
	ds_read_b64_tr_b16 v[78:79], v231 offset:2560
	ds_read_b64_tr_b16 v[220:221], v231 offset:1024
	ds_read_b64_tr_b16 v[222:223], v231 offset:1536
	ds_read_b64_tr_b16 v[224:225], v231 offset:3072
	ds_read_b64_tr_b16 v[226:227], v231 offset:3584
	v_exp_f32_e32 v32, v32
	v_exp_f32_e32 v33, v33
	v_exp_f32_e32 v34, v34
	v_exp_f32_e32 v35, v35
	s_waitcnt vmcnt(8)
	ds_write_b128 v247, v[156:159]
	ds_write_b128 v247, v[160:163] offset:1024
	ds_write_b128 v247, v[164:167] offset:2048
	ds_write_b128 v247, v[168:171] offset:3072
	ds_read_b128 v[156:159], v248
	ds_read_b128 v[160:163], v249
	ds_read_b128 v[164:167], v250
	ds_read_b128 v[168:171], v251
	ds_write_b128 v112, v[172:175]
	ds_write_b128 v112, v[176:179] offset:1024
	ds_write_b128 v112, v[180:183] offset:2048
	ds_write_b128 v112, v[184:187] offset:3072
	v_exp_f32_e32 v36, v36
	v_exp_f32_e32 v37, v37
	v_exp_f32_e32 v38, v38
	v_exp_f32_e32 v39, v39
	s_waitcnt lgkmcnt(4)
	v_mfma_f32_32x32x16_bf16 v[188:203], v[156:159], v[48:51], v[188:203]
	v_exp_f32_e32 v40, v40
	v_exp_f32_e32 v41, v41
	v_mfma_f32_32x32x16_bf16 v[188:203], v[160:163], v[52:55], v[188:203]
	v_exp_f32_e32 v42, v42
	v_exp_f32_e32 v43, v43
	v_mfma_f32_32x32x16_bf16 v[188:203], v[164:167], v[56:59], v[188:203]
	v_exp_f32_e32 v44, v44
	v_exp_f32_e32 v45, v45
	v_mfma_f32_32x32x16_bf16 v[188:203], v[168:171], v[60:63], v[188:203]
	v_exp_f32_e32 v46, v46
	v_exp_f32_e32 v47, v47
	s_add_i32 s90, s76, -64
	v_add_u32_e32 v84, s90, v107
	v_add_u32_e32 v85, 0, v84
	v_add_u32_e32 v86, 1, v84
	v_add_u32_e32 v87, 2, v84
	v_add_u32_e32 v88, 3, v84
	v_cmp_gt_u32_e64 s[30:31], s98, v85
	v_cmp_gt_u32_e64 s[36:37], s98, v86
	v_cmp_gt_u32_e64 s[78:79], s98, v87
	v_cmp_gt_u32_e64 s[50:51], s98, v88
	v_cndmask_b32_e64 v32, 0, v32, s[30:31]
	v_add_u32_e32 v85, 8, v84
	v_cmp_gt_u32_e64 s[30:31], s98, v85
	v_cndmask_b32_e64 v33, 0, v33, s[36:37]
	v_add_u32_e32 v86, 9, v84
	v_cmp_gt_u32_e64 s[36:37], s98, v86
	v_cndmask_b32_e64 v34, 0, v34, s[78:79]
	v_add_u32_e32 v87, 10, v84
	v_cmp_gt_u32_e64 s[78:79], s98, v87
	v_cndmask_b32_e64 v35, 0, v35, s[50:51]
	v_add_u32_e32 v88, 11, v84
	v_cmp_gt_u32_e64 s[50:51], s98, v88
	v_cndmask_b32_e64 v36, 0, v36, s[30:31]
	v_add_u32_e32 v85, 16, v84
	v_cmp_gt_u32_e64 s[30:31], s98, v85
	v_cndmask_b32_e64 v37, 0, v37, s[36:37]
	v_add_u32_e32 v86, 17, v84
	v_cmp_gt_u32_e64 s[36:37], s98, v86
	v_cndmask_b32_e64 v38, 0, v38, s[78:79]
	v_add_u32_e32 v87, 18, v84
	v_cmp_gt_u32_e64 s[78:79], s98, v87
	v_cndmask_b32_e64 v39, 0, v39, s[50:51]
	v_add_u32_e32 v88, 19, v84
	v_cmp_gt_u32_e64 s[50:51], s98, v88
	v_cndmask_b32_e64 v40, 0, v40, s[30:31]
	v_add_u32_e32 v85, 24, v84
	v_cmp_gt_u32_e64 s[30:31], s98, v85
	v_cndmask_b32_e64 v41, 0, v41, s[36:37]
	v_add_u32_e32 v86, 25, v84
	v_cmp_gt_u32_e64 s[36:37], s98, v86
	v_cndmask_b32_e64 v42, 0, v42, s[78:79]
	v_add_u32_e32 v87, 26, v84
	v_cmp_gt_u32_e64 s[78:79], s98, v87
	v_cndmask_b32_e64 v43, 0, v43, s[50:51]
	v_add_u32_e32 v88, 27, v84
	v_cmp_gt_u32_e64 s[50:51], s98, v88
	v_nop
	v_cndmask_b32_e64 v44, 0, v44, s[30:31]
	v_cndmask_b32_e64 v45, 0, v45, s[36:37]
	v_cndmask_b32_e64 v46, 0, v46, s[78:79]
	v_cndmask_b32_e64 v47, 0, v47, s[50:51]
	v_cvt_pk_bf16_f32 v64, v32, v33
	v_cvt_pk_bf16_f32 v65, v34, v35
	v_cvt_pk_bf16_f32 v66, v36, v37
	v_cvt_pk_bf16_f32 v67, v38, v39
	v_cvt_pk_bf16_f32 v68, v40, v41
	v_cvt_pk_bf16_f32 v69, v42, v43
	v_cvt_pk_bf16_f32 v70, v44, v45
	v_cvt_pk_bf16_f32 v71, v46, v47
	v_pk_add_f32 v[232:233], v[232:233], v[32:33]
	v_pk_add_f32 v[232:233], v[232:233], v[34:35]
	v_pk_add_f32 v[232:233], v[232:233], v[36:37]
	v_pk_add_f32 v[232:233], v[232:233], v[38:39]
	v_pk_add_f32 v[232:233], v[232:233], v[40:41]
	v_pk_add_f32 v[232:233], v[232:233], v[42:43]
	v_pk_add_f32 v[232:233], v[232:233], v[44:45]
	v_pk_add_f32 v[232:233], v[232:233], v[46:47]
	ds_read2_b32 v[32:33], v115 offset0:68 offset1:69
	ds_read2_b32 v[34:35], v115 offset0:70 offset1:71
	ds_read2_b32 v[36:37], v115 offset0:76 offset1:77
	ds_read2_b32 v[38:39], v115 offset0:78 offset1:79
	ds_read2_b32 v[40:41], v115 offset0:85 offset1:86
	ds_read2_b32 v[42:43], v115 offset0:87 offset1:88
	ds_read2_b32 v[44:45], v115 offset0:93 offset1:94
	ds_read2_b32 v[46:47], v115 offset0:95 offset1:96
	v_mfma_f32_32x32x16_bf16 v[0:15], v[64:67], v[72:75], v[0:15]
	v_mfma_f32_32x32x16_bf16 v[16:31], v[64:67], v[76:79], v[16:31]
	v_mfma_f32_32x32x16_bf16 v[0:15], v[68:71], v[220:223], v[0:15]
	v_mfma_f32_32x32x16_bf16 v[16:31], v[68:71], v[224:227], v[16:31]
	s_add_i32 s90, s76, 32
	v_add_u32_e32 v80, s90, v235
	v_add_u32_e32 v83, s90, v236
	v_add_u32_e32 v99, s90, v237
	v_add_u32_e32 v253, s90, v238
	v_add_u32_e32 v254, s90, v100
	v_add_u32_e32 v255, s90, v149
	v_med3_i32 v80, v80, 0, s99
	v_med3_i32 v83, v83, 0, s99
	v_med3_i32 v99, v99, 0, s99
	v_med3_i32 v253, v253, 0, s99
	v_med3_i32 v254, v254, 0, s99
	v_med3_i32 v255, v255, 0, s99
	v_mad_u32_u24 v80, v80, s100, v252
	v_mad_u32_u24 v83, v83, s100, v252
	v_mad_u32_u24 v99, v99, s100, v252
	v_mad_u32_u24 v253, v253, s100, v252
	v_mad_u32_u24 v254, v254, s100, v153
	v_mad_u32_u24 v255, v255, s100, v153
	global_load_dwordx4 v[156:159], v80, s[82:83]
	global_load_dwordx4 v[160:163], v83, s[82:83]
	global_load_dwordx4 v[164:167], v99, s[82:83]
	global_load_dwordx4 v[168:171], v253, s[82:83]
	global_load_dwordx4 v[172:175], v254, s[82:83] offset:768
	global_load_dwordx4 v[176:179], v255, s[82:83] offset:768
	global_load_dwordx4 v[180:183], v254, s[82:83] offset:832
	global_load_dwordx4 v[184:187], v255, s[82:83] offset:832
	ds_read_b64_tr_b16 v[72:73], v231
	ds_read_b64_tr_b16 v[74:75], v231 offset:512
	ds_read_b64_tr_b16 v[76:77], v231 offset:2048
	ds_read_b64_tr_b16 v[78:79], v231 offset:2560
	ds_read_b64_tr_b16 v[220:221], v231 offset:1024
	ds_read_b64_tr_b16 v[222:223], v231 offset:1536
	ds_read_b64_tr_b16 v[224:225], v231 offset:3072
	ds_read_b64_tr_b16 v[226:227], v231 offset:3584
	v_exp_f32_e32 v188, v188
	v_exp_f32_e32 v189, v189
	v_exp_f32_e32 v190, v190
	v_exp_f32_e32 v191, v191
	s_waitcnt vmcnt(8)
	ds_write_b128 v247, v[116:119]
	ds_write_b128 v247, v[120:123] offset:1024
	ds_write_b128 v247, v[124:127] offset:2048
	ds_write_b128 v247, v[128:131] offset:3072
	ds_read_b128 v[116:119], v248
	ds_read_b128 v[120:123], v249
	ds_read_b128 v[124:127], v250
	ds_read_b128 v[128:131], v251
	ds_write_b128 v112, v[132:135]
	ds_write_b128 v112, v[136:139] offset:1024
	ds_write_b128 v112, v[140:143] offset:2048
	ds_write_b128 v112, v[144:147] offset:3072
	v_exp_f32_e32 v192, v192
	v_exp_f32_e32 v193, v193
	v_exp_f32_e32 v194, v194
	v_exp_f32_e32 v195, v195
	s_waitcnt lgkmcnt(4)
	v_mfma_f32_32x32x16_bf16 v[32:47], v[116:119], v[48:51], v[32:47]
	v_exp_f32_e32 v196, v196
	v_exp_f32_e32 v197, v197
	v_mfma_f32_32x32x16_bf16 v[32:47], v[120:123], v[52:55], v[32:47]
	v_exp_f32_e32 v198, v198
	v_exp_f32_e32 v199, v199
	v_mfma_f32_32x32x16_bf16 v[32:47], v[124:127], v[56:59], v[32:47]
	v_exp_f32_e32 v200, v200
	v_exp_f32_e32 v201, v201
	v_mfma_f32_32x32x16_bf16 v[32:47], v[128:131], v[60:63], v[32:47]
	v_exp_f32_e32 v202, v202
	v_exp_f32_e32 v203, v203
	s_add_i32 s90, s76, -32
	v_add_u32_e32 v84, s90, v107
	v_add_u32_e32 v85, 0, v84
	v_add_u32_e32 v86, 1, v84
	v_add_u32_e32 v87, 2, v84
	v_add_u32_e32 v88, 3, v84
	v_cmp_gt_u32_e64 s[30:31], s98, v85
	v_cmp_gt_u32_e64 s[36:37], s98, v86
	v_cmp_gt_u32_e64 s[78:79], s98, v87
	v_cmp_gt_u32_e64 s[50:51], s98, v88
	v_cndmask_b32_e64 v188, 0, v188, s[30:31]
	v_add_u32_e32 v85, 8, v84
	v_cmp_gt_u32_e64 s[30:31], s98, v85
	v_cndmask_b32_e64 v189, 0, v189, s[36:37]
	v_add_u32_e32 v86, 9, v84
	v_cmp_gt_u32_e64 s[36:37], s98, v86
	v_cndmask_b32_e64 v190, 0, v190, s[78:79]
	v_add_u32_e32 v87, 10, v84
	v_cmp_gt_u32_e64 s[78:79], s98, v87
	v_cndmask_b32_e64 v191, 0, v191, s[50:51]
	v_add_u32_e32 v88, 11, v84
	v_cmp_gt_u32_e64 s[50:51], s98, v88
	v_cndmask_b32_e64 v192, 0, v192, s[30:31]
	v_add_u32_e32 v85, 16, v84
	v_cmp_gt_u32_e64 s[30:31], s98, v85
	v_cndmask_b32_e64 v193, 0, v193, s[36:37]
	v_add_u32_e32 v86, 17, v84
	v_cmp_gt_u32_e64 s[36:37], s98, v86
	v_cndmask_b32_e64 v194, 0, v194, s[78:79]
	v_add_u32_e32 v87, 18, v84
	v_cmp_gt_u32_e64 s[78:79], s98, v87
	v_cndmask_b32_e64 v195, 0, v195, s[50:51]
	v_add_u32_e32 v88, 19, v84
	v_cmp_gt_u32_e64 s[50:51], s98, v88
	v_cndmask_b32_e64 v196, 0, v196, s[30:31]
	v_add_u32_e32 v85, 24, v84
	v_cmp_gt_u32_e64 s[30:31], s98, v85
	v_cndmask_b32_e64 v197, 0, v197, s[36:37]
	v_add_u32_e32 v86, 25, v84
	v_cmp_gt_u32_e64 s[36:37], s98, v86
	v_cndmask_b32_e64 v198, 0, v198, s[78:79]
	v_add_u32_e32 v87, 26, v84
	v_cmp_gt_u32_e64 s[78:79], s98, v87
	v_cndmask_b32_e64 v199, 0, v199, s[50:51]
	v_add_u32_e32 v88, 27, v84
	v_cmp_gt_u32_e64 s[50:51], s98, v88
	v_nop
	v_cndmask_b32_e64 v200, 0, v200, s[30:31]
	v_cndmask_b32_e64 v201, 0, v201, s[36:37]
	v_cndmask_b32_e64 v202, 0, v202, s[78:79]
	v_cndmask_b32_e64 v203, 0, v203, s[50:51]
	v_cvt_pk_bf16_f32 v64, v188, v189
	v_cvt_pk_bf16_f32 v65, v190, v191
	v_cvt_pk_bf16_f32 v66, v192, v193
	v_cvt_pk_bf16_f32 v67, v194, v195
	v_cvt_pk_bf16_f32 v68, v196, v197
	v_cvt_pk_bf16_f32 v69, v198, v199
	v_cvt_pk_bf16_f32 v70, v200, v201
	v_cvt_pk_bf16_f32 v71, v202, v203
	v_pk_add_f32 v[232:233], v[232:233], v[188:189]
	v_pk_add_f32 v[232:233], v[232:233], v[190:191]
	v_pk_add_f32 v[232:233], v[232:233], v[192:193]
	v_pk_add_f32 v[232:233], v[232:233], v[194:195]
	v_pk_add_f32 v[232:233], v[232:233], v[196:197]
	v_pk_add_f32 v[232:233], v[232:233], v[198:199]
	v_pk_add_f32 v[232:233], v[232:233], v[200:201]
	v_pk_add_f32 v[232:233], v[232:233], v[202:203]
	ds_read2_b32 v[188:189], v115 offset0:102 offset1:103
	ds_read2_b32 v[190:191], v115 offset0:104 offset1:105
	ds_read2_b32 v[192:193], v115 offset0:110 offset1:111
	ds_read2_b32 v[194:195], v115 offset0:112 offset1:113
	ds_read2_b32 v[196:197], v115 offset0:119 offset1:120
	ds_read2_b32 v[198:199], v115 offset0:121 offset1:122
	ds_read2_b32 v[200:201], v115 offset0:127 offset1:128
	ds_read2_b32 v[202:203], v115 offset0:129 offset1:130
	v_mfma_f32_32x32x16_bf16 v[0:15], v[64:67], v[72:75], v[0:15]
	v_mfma_f32_32x32x16_bf16 v[16:31], v[64:67], v[76:79], v[16:31]
	v_mfma_f32_32x32x16_bf16 v[0:15], v[68:71], v[220:223], v[0:15]
	v_mfma_f32_32x32x16_bf16 v[16:31], v[68:71], v[224:227], v[16:31]
	s_add_i32 s90, s76, 64
	v_add_u32_e32 v80, s90, v235
	v_add_u32_e32 v83, s90, v236
	v_add_u32_e32 v99, s90, v237
	v_add_u32_e32 v253, s90, v238
	v_add_u32_e32 v254, s90, v100
	v_add_u32_e32 v255, s90, v149
	v_med3_i32 v80, v80, 0, s99
	v_med3_i32 v83, v83, 0, s99
	v_med3_i32 v99, v99, 0, s99
	v_med3_i32 v253, v253, 0, s99
	v_med3_i32 v254, v254, 0, s99
	v_med3_i32 v255, v255, 0, s99
	v_mad_u32_u24 v80, v80, s100, v252
	v_mad_u32_u24 v83, v83, s100, v252
	v_mad_u32_u24 v99, v99, s100, v252
	v_mad_u32_u24 v253, v253, s100, v252
	v_mad_u32_u24 v254, v254, s100, v153
	v_mad_u32_u24 v255, v255, s100, v153
	global_load_dwordx4 v[116:119], v80, s[82:83]
	global_load_dwordx4 v[120:123], v83, s[82:83]
	global_load_dwordx4 v[124:127], v99, s[82:83]
	global_load_dwordx4 v[128:131], v253, s[82:83]
	global_load_dwordx4 v[132:135], v254, s[82:83] offset:768
	global_load_dwordx4 v[136:139], v255, s[82:83] offset:768
	global_load_dwordx4 v[140:143], v254, s[82:83] offset:832
	global_load_dwordx4 v[144:147], v255, s[82:83] offset:832
	ds_read_b64_tr_b16 v[72:73], v231
	ds_read_b64_tr_b16 v[74:75], v231 offset:512
	ds_read_b64_tr_b16 v[76:77], v231 offset:2048
	ds_read_b64_tr_b16 v[78:79], v231 offset:2560
	ds_read_b64_tr_b16 v[220:221], v231 offset:1024
	ds_read_b64_tr_b16 v[222:223], v231 offset:1536
	ds_read_b64_tr_b16 v[224:225], v231 offset:3072
	ds_read_b64_tr_b16 v[226:227], v231 offset:3584
	v_exp_f32_e32 v32, v32
	v_exp_f32_e32 v33, v33
	v_exp_f32_e32 v34, v34
	v_exp_f32_e32 v35, v35
	s_waitcnt vmcnt(8)
	ds_write_b128 v247, v[156:159]
	ds_write_b128 v247, v[160:163] offset:1024
	ds_write_b128 v247, v[164:167] offset:2048
	ds_write_b128 v247, v[168:171] offset:3072
	ds_read_b128 v[156:159], v248
	ds_read_b128 v[160:163], v249
	ds_read_b128 v[164:167], v250
	ds_read_b128 v[168:171], v251
	ds_write_b128 v112, v[172:175]
	ds_write_b128 v112, v[176:179] offset:1024
	ds_write_b128 v112, v[180:183] offset:2048
	ds_write_b128 v112, v[184:187] offset:3072
	v_exp_f32_e32 v36, v36
	v_exp_f32_e32 v37, v37
	v_exp_f32_e32 v38, v38
	v_exp_f32_e32 v39, v39
	s_waitcnt lgkmcnt(4)
	v_mfma_f32_32x32x16_bf16 v[188:203], v[156:159], v[48:51], v[188:203]
	v_exp_f32_e32 v40, v40
	v_exp_f32_e32 v41, v41
	v_mfma_f32_32x32x16_bf16 v[188:203], v[160:163], v[52:55], v[188:203]
	v_exp_f32_e32 v42, v42
	v_exp_f32_e32 v43, v43
	v_mfma_f32_32x32x16_bf16 v[188:203], v[164:167], v[56:59], v[188:203]
	v_exp_f32_e32 v44, v44
	v_exp_f32_e32 v45, v45
	v_mfma_f32_32x32x16_bf16 v[188:203], v[168:171], v[60:63], v[188:203]
	v_exp_f32_e32 v46, v46
	v_exp_f32_e32 v47, v47
	s_add_i32 s90, s76, 0
	v_add_u32_e32 v84, s90, v107
	v_add_u32_e32 v85, 0, v84
	v_add_u32_e32 v86, 1, v84
	v_add_u32_e32 v87, 2, v84
	v_add_u32_e32 v88, 3, v84
	v_cmp_gt_u32_e64 s[30:31], s98, v85
	v_cmp_gt_u32_e64 s[36:37], s98, v86
	v_cmp_gt_u32_e64 s[78:79], s98, v87
	v_cmp_gt_u32_e64 s[50:51], s98, v88
	v_cndmask_b32_e64 v32, 0, v32, s[30:31]
	v_add_u32_e32 v85, 8, v84
	v_cmp_gt_u32_e64 s[30:31], s98, v85
	v_cndmask_b32_e64 v33, 0, v33, s[36:37]
	v_add_u32_e32 v86, 9, v84
	v_cmp_gt_u32_e64 s[36:37], s98, v86
	v_cndmask_b32_e64 v34, 0, v34, s[78:79]
	v_add_u32_e32 v87, 10, v84
	v_cmp_gt_u32_e64 s[78:79], s98, v87
	v_cndmask_b32_e64 v35, 0, v35, s[50:51]
	v_add_u32_e32 v88, 11, v84
	v_cmp_gt_u32_e64 s[50:51], s98, v88
	v_cndmask_b32_e64 v36, 0, v36, s[30:31]
	v_add_u32_e32 v85, 16, v84
	v_cmp_gt_u32_e64 s[30:31], s98, v85
	v_cndmask_b32_e64 v37, 0, v37, s[36:37]
	v_add_u32_e32 v86, 17, v84
	v_cmp_gt_u32_e64 s[36:37], s98, v86
	v_cndmask_b32_e64 v38, 0, v38, s[78:79]
	v_add_u32_e32 v87, 18, v84
	v_cmp_gt_u32_e64 s[78:79], s98, v87
	v_cndmask_b32_e64 v39, 0, v39, s[50:51]
	v_add_u32_e32 v88, 19, v84
	v_cmp_gt_u32_e64 s[50:51], s98, v88
	v_cndmask_b32_e64 v40, 0, v40, s[30:31]
	v_add_u32_e32 v85, 24, v84
	v_cmp_gt_u32_e64 s[30:31], s98, v85
	v_cndmask_b32_e64 v41, 0, v41, s[36:37]
	v_add_u32_e32 v86, 25, v84
	v_cmp_gt_u32_e64 s[36:37], s98, v86
	v_cndmask_b32_e64 v42, 0, v42, s[78:79]
	v_add_u32_e32 v87, 26, v84
	v_cmp_gt_u32_e64 s[78:79], s98, v87
	v_cndmask_b32_e64 v43, 0, v43, s[50:51]
	v_add_u32_e32 v88, 27, v84
	v_cmp_gt_u32_e64 s[50:51], s98, v88
	v_nop
	v_cndmask_b32_e64 v44, 0, v44, s[30:31]
	v_cndmask_b32_e64 v45, 0, v45, s[36:37]
	v_cndmask_b32_e64 v46, 0, v46, s[78:79]
	v_cndmask_b32_e64 v47, 0, v47, s[50:51]
	v_cvt_pk_bf16_f32 v64, v32, v33
	v_cvt_pk_bf16_f32 v65, v34, v35
	v_cvt_pk_bf16_f32 v66, v36, v37
	v_cvt_pk_bf16_f32 v67, v38, v39
	v_cvt_pk_bf16_f32 v68, v40, v41
	v_cvt_pk_bf16_f32 v69, v42, v43
	v_cvt_pk_bf16_f32 v70, v44, v45
	v_cvt_pk_bf16_f32 v71, v46, v47
	v_pk_add_f32 v[232:233], v[232:233], v[32:33]
	v_pk_add_f32 v[232:233], v[232:233], v[34:35]
	v_pk_add_f32 v[232:233], v[232:233], v[36:37]
	v_pk_add_f32 v[232:233], v[232:233], v[38:39]
	v_pk_add_f32 v[232:233], v[232:233], v[40:41]
	v_pk_add_f32 v[232:233], v[232:233], v[42:43]
	v_pk_add_f32 v[232:233], v[232:233], v[44:45]
	v_pk_add_f32 v[232:233], v[232:233], v[46:47]
	ds_read2_b32 v[32:33], v115 offset0:136 offset1:137
	ds_read2_b32 v[34:35], v115 offset0:138 offset1:139
	ds_read2_b32 v[36:37], v115 offset0:144 offset1:145
	ds_read2_b32 v[38:39], v115 offset0:146 offset1:147
	ds_read2_b32 v[40:41], v115 offset0:153 offset1:154
	ds_read2_b32 v[42:43], v115 offset0:155 offset1:156
	ds_read2_b32 v[44:45], v115 offset0:161 offset1:162
	ds_read2_b32 v[46:47], v115 offset0:163 offset1:164
	v_mfma_f32_32x32x16_bf16 v[0:15], v[64:67], v[72:75], v[0:15]
	v_mfma_f32_32x32x16_bf16 v[16:31], v[64:67], v[76:79], v[16:31]
	v_mfma_f32_32x32x16_bf16 v[0:15], v[68:71], v[220:223], v[0:15]
	v_mfma_f32_32x32x16_bf16 v[16:31], v[68:71], v[224:227], v[16:31]
	s_add_i32 s90, s76, 96
	v_add_u32_e32 v80, s90, v235
	v_add_u32_e32 v83, s90, v236
	v_add_u32_e32 v99, s90, v237
	v_add_u32_e32 v253, s90, v238
	v_add_u32_e32 v254, s90, v100
	v_add_u32_e32 v255, s90, v149
	v_med3_i32 v80, v80, 0, s99
	v_med3_i32 v83, v83, 0, s99
	v_med3_i32 v99, v99, 0, s99
	v_med3_i32 v253, v253, 0, s99
	v_med3_i32 v254, v254, 0, s99
	v_med3_i32 v255, v255, 0, s99
	v_mad_u32_u24 v80, v80, s100, v252
	v_mad_u32_u24 v83, v83, s100, v252
	v_mad_u32_u24 v99, v99, s100, v252
	v_mad_u32_u24 v253, v253, s100, v252
	v_mad_u32_u24 v254, v254, s100, v153
	v_mad_u32_u24 v255, v255, s100, v153
	global_load_dwordx4 v[156:159], v80, s[82:83]
	global_load_dwordx4 v[160:163], v83, s[82:83]
	global_load_dwordx4 v[164:167], v99, s[82:83]
	global_load_dwordx4 v[168:171], v253, s[82:83]
	global_load_dwordx4 v[172:175], v254, s[82:83] offset:768
	global_load_dwordx4 v[176:179], v255, s[82:83] offset:768
	global_load_dwordx4 v[180:183], v254, s[82:83] offset:832
	global_load_dwordx4 v[184:187], v255, s[82:83] offset:832
	ds_read_b64_tr_b16 v[72:73], v231
	ds_read_b64_tr_b16 v[74:75], v231 offset:512
	ds_read_b64_tr_b16 v[76:77], v231 offset:2048
	ds_read_b64_tr_b16 v[78:79], v231 offset:2560
	ds_read_b64_tr_b16 v[220:221], v231 offset:1024
	ds_read_b64_tr_b16 v[222:223], v231 offset:1536
	ds_read_b64_tr_b16 v[224:225], v231 offset:3072
	ds_read_b64_tr_b16 v[226:227], v231 offset:3584
	v_exp_f32_e32 v188, v188
	v_exp_f32_e32 v189, v189
	v_exp_f32_e32 v190, v190
	v_exp_f32_e32 v191, v191
	s_waitcnt vmcnt(8)
	ds_write_b128 v247, v[116:119]
	ds_write_b128 v247, v[120:123] offset:1024
	ds_write_b128 v247, v[124:127] offset:2048
	ds_write_b128 v247, v[128:131] offset:3072
	ds_read_b128 v[116:119], v248
	ds_read_b128 v[120:123], v249
	ds_read_b128 v[124:127], v250
	ds_read_b128 v[128:131], v251
	ds_write_b128 v112, v[132:135]
	ds_write_b128 v112, v[136:139] offset:1024
	ds_write_b128 v112, v[140:143] offset:2048
	ds_write_b128 v112, v[144:147] offset:3072
	v_exp_f32_e32 v192, v192
	v_exp_f32_e32 v193, v193
	v_exp_f32_e32 v194, v194
	v_exp_f32_e32 v195, v195
	s_waitcnt lgkmcnt(4)
	v_mfma_f32_32x32x16_bf16 v[32:47], v[116:119], v[48:51], v[32:47]
	v_exp_f32_e32 v196, v196
	v_exp_f32_e32 v197, v197
	v_mfma_f32_32x32x16_bf16 v[32:47], v[120:123], v[52:55], v[32:47]
	v_exp_f32_e32 v198, v198
	v_exp_f32_e32 v199, v199
	v_mfma_f32_32x32x16_bf16 v[32:47], v[124:127], v[56:59], v[32:47]
	v_exp_f32_e32 v200, v200
	v_exp_f32_e32 v201, v201
	v_mfma_f32_32x32x16_bf16 v[32:47], v[128:131], v[60:63], v[32:47]
	v_exp_f32_e32 v202, v202
	v_exp_f32_e32 v203, v203
	s_add_i32 s90, s76, 32
	v_add_u32_e32 v84, s90, v107
	v_add_u32_e32 v85, 0, v84
	v_add_u32_e32 v86, 1, v84
	v_add_u32_e32 v87, 2, v84
	v_add_u32_e32 v88, 3, v84
	v_cmp_gt_u32_e64 s[30:31], s98, v85
	v_cmp_gt_u32_e64 s[36:37], s98, v86
	v_cmp_gt_u32_e64 s[78:79], s98, v87
	v_cmp_gt_u32_e64 s[50:51], s98, v88
	v_cndmask_b32_e64 v188, 0, v188, s[30:31]
	v_add_u32_e32 v85, 8, v84
	v_cmp_gt_u32_e64 s[30:31], s98, v85
	v_cndmask_b32_e64 v189, 0, v189, s[36:37]
	v_add_u32_e32 v86, 9, v84
	v_cmp_gt_u32_e64 s[36:37], s98, v86
	v_cndmask_b32_e64 v190, 0, v190, s[78:79]
	v_add_u32_e32 v87, 10, v84
	v_cmp_gt_u32_e64 s[78:79], s98, v87
	v_cndmask_b32_e64 v191, 0, v191, s[50:51]
	v_add_u32_e32 v88, 11, v84
	v_cmp_gt_u32_e64 s[50:51], s98, v88
	v_cndmask_b32_e64 v192, 0, v192, s[30:31]
	v_add_u32_e32 v85, 16, v84
	v_cmp_gt_u32_e64 s[30:31], s98, v85
	v_cndmask_b32_e64 v193, 0, v193, s[36:37]
	v_add_u32_e32 v86, 17, v84
	v_cmp_gt_u32_e64 s[36:37], s98, v86
	v_cndmask_b32_e64 v194, 0, v194, s[78:79]
	v_add_u32_e32 v87, 18, v84
	v_cmp_gt_u32_e64 s[78:79], s98, v87
	v_cndmask_b32_e64 v195, 0, v195, s[50:51]
	v_add_u32_e32 v88, 19, v84
	v_cmp_gt_u32_e64 s[50:51], s98, v88
	v_cndmask_b32_e64 v196, 0, v196, s[30:31]
	v_add_u32_e32 v85, 24, v84
	v_cmp_gt_u32_e64 s[30:31], s98, v85
	v_cndmask_b32_e64 v197, 0, v197, s[36:37]
	v_add_u32_e32 v86, 25, v84
	v_cmp_gt_u32_e64 s[36:37], s98, v86
	v_cndmask_b32_e64 v198, 0, v198, s[78:79]
	v_add_u32_e32 v87, 26, v84
	v_cmp_gt_u32_e64 s[78:79], s98, v87
	v_cndmask_b32_e64 v199, 0, v199, s[50:51]
	v_add_u32_e32 v88, 27, v84
	v_cmp_gt_u32_e64 s[50:51], s98, v88
	v_nop
	v_cndmask_b32_e64 v200, 0, v200, s[30:31]
	v_cndmask_b32_e64 v201, 0, v201, s[36:37]
	v_cndmask_b32_e64 v202, 0, v202, s[78:79]
	v_cndmask_b32_e64 v203, 0, v203, s[50:51]
	v_cvt_pk_bf16_f32 v64, v188, v189
	v_cvt_pk_bf16_f32 v65, v190, v191
	v_cvt_pk_bf16_f32 v66, v192, v193
	v_cvt_pk_bf16_f32 v67, v194, v195
	v_cvt_pk_bf16_f32 v68, v196, v197
	v_cvt_pk_bf16_f32 v69, v198, v199
	v_cvt_pk_bf16_f32 v70, v200, v201
	v_cvt_pk_bf16_f32 v71, v202, v203
	v_pk_add_f32 v[232:233], v[232:233], v[188:189]
	v_pk_add_f32 v[232:233], v[232:233], v[190:191]
	v_pk_add_f32 v[232:233], v[232:233], v[192:193]
	v_pk_add_f32 v[232:233], v[232:233], v[194:195]
	v_pk_add_f32 v[232:233], v[232:233], v[196:197]
	v_pk_add_f32 v[232:233], v[232:233], v[198:199]
	v_pk_add_f32 v[232:233], v[232:233], v[200:201]
	v_pk_add_f32 v[232:233], v[232:233], v[202:203]
	ds_read2_b32 v[188:189], v115 offset0:170 offset1:171
	ds_read2_b32 v[190:191], v115 offset0:172 offset1:173
	ds_read2_b32 v[192:193], v115 offset0:178 offset1:179
	ds_read2_b32 v[194:195], v115 offset0:180 offset1:181
	ds_read2_b32 v[196:197], v115 offset0:187 offset1:188
	ds_read2_b32 v[198:199], v115 offset0:189 offset1:190
	ds_read2_b32 v[200:201], v115 offset0:195 offset1:196
	ds_read2_b32 v[202:203], v115 offset0:197 offset1:198
	v_mfma_f32_32x32x16_bf16 v[0:15], v[64:67], v[72:75], v[0:15]
	v_mfma_f32_32x32x16_bf16 v[16:31], v[64:67], v[76:79], v[16:31]
	v_mfma_f32_32x32x16_bf16 v[0:15], v[68:71], v[220:223], v[0:15]
	v_mfma_f32_32x32x16_bf16 v[16:31], v[68:71], v[224:227], v[16:31]
	s_add_i32 s90, s76, 128
	v_add_u32_e32 v80, s90, v235
	v_add_u32_e32 v83, s90, v236
	v_add_u32_e32 v99, s90, v237
	v_add_u32_e32 v253, s90, v238
	v_add_u32_e32 v254, s90, v100
	v_add_u32_e32 v255, s90, v149
	v_med3_i32 v80, v80, 0, s99
	v_med3_i32 v83, v83, 0, s99
	v_med3_i32 v99, v99, 0, s99
	v_med3_i32 v253, v253, 0, s99
	v_med3_i32 v254, v254, 0, s99
	v_med3_i32 v255, v255, 0, s99
	v_mad_u32_u24 v80, v80, s100, v252
	v_mad_u32_u24 v83, v83, s100, v252
	v_mad_u32_u24 v99, v99, s100, v252
	v_mad_u32_u24 v253, v253, s100, v252
	v_mad_u32_u24 v254, v254, s100, v153
	v_mad_u32_u24 v255, v255, s100, v153
	global_load_dwordx4 v[116:119], v80, s[82:83]
	global_load_dwordx4 v[120:123], v83, s[82:83]
	global_load_dwordx4 v[124:127], v99, s[82:83]
	global_load_dwordx4 v[128:131], v253, s[82:83]
	global_load_dwordx4 v[132:135], v254, s[82:83] offset:768
	global_load_dwordx4 v[136:139], v255, s[82:83] offset:768
	global_load_dwordx4 v[140:143], v254, s[82:83] offset:832
	global_load_dwordx4 v[144:147], v255, s[82:83] offset:832
	ds_read_b64_tr_b16 v[72:73], v231
	ds_read_b64_tr_b16 v[74:75], v231 offset:512
	ds_read_b64_tr_b16 v[76:77], v231 offset:2048
	ds_read_b64_tr_b16 v[78:79], v231 offset:2560
	ds_read_b64_tr_b16 v[220:221], v231 offset:1024
	ds_read_b64_tr_b16 v[222:223], v231 offset:1536
	ds_read_b64_tr_b16 v[224:225], v231 offset:3072
	ds_read_b64_tr_b16 v[226:227], v231 offset:3584
	v_exp_f32_e32 v32, v32
	v_exp_f32_e32 v33, v33
	v_exp_f32_e32 v34, v34
	v_exp_f32_e32 v35, v35
	s_waitcnt vmcnt(8)
	ds_write_b128 v247, v[156:159]
	ds_write_b128 v247, v[160:163] offset:1024
	ds_write_b128 v247, v[164:167] offset:2048
	ds_write_b128 v247, v[168:171] offset:3072
	ds_read_b128 v[156:159], v248
	ds_read_b128 v[160:163], v249
	ds_read_b128 v[164:167], v250
	ds_read_b128 v[168:171], v251
	ds_write_b128 v112, v[172:175]
	ds_write_b128 v112, v[176:179] offset:1024
	ds_write_b128 v112, v[180:183] offset:2048
	ds_write_b128 v112, v[184:187] offset:3072
	v_exp_f32_e32 v36, v36
	v_exp_f32_e32 v37, v37
	v_exp_f32_e32 v38, v38
	v_exp_f32_e32 v39, v39
	s_waitcnt lgkmcnt(4)
	v_mfma_f32_32x32x16_bf16 v[188:203], v[156:159], v[48:51], v[188:203]
	v_exp_f32_e32 v40, v40
	v_exp_f32_e32 v41, v41
	v_mfma_f32_32x32x16_bf16 v[188:203], v[160:163], v[52:55], v[188:203]
	v_exp_f32_e32 v42, v42
	v_exp_f32_e32 v43, v43
	v_mfma_f32_32x32x16_bf16 v[188:203], v[164:167], v[56:59], v[188:203]
	v_exp_f32_e32 v44, v44
	v_exp_f32_e32 v45, v45
	v_mfma_f32_32x32x16_bf16 v[188:203], v[168:171], v[60:63], v[188:203]
	v_exp_f32_e32 v46, v46
	v_exp_f32_e32 v47, v47
	s_add_i32 s90, s76, 64
	v_add_u32_e32 v84, s90, v107
	v_add_u32_e32 v85, 0, v84
	v_add_u32_e32 v86, 1, v84
	v_add_u32_e32 v87, 2, v84
	v_add_u32_e32 v88, 3, v84
	v_cmp_gt_u32_e64 s[30:31], s98, v85
	v_cmp_gt_u32_e64 s[36:37], s98, v86
	v_cmp_gt_u32_e64 s[78:79], s98, v87
	v_cmp_gt_u32_e64 s[50:51], s98, v88
	v_cndmask_b32_e64 v32, 0, v32, s[30:31]
	v_add_u32_e32 v85, 8, v84
	v_cmp_gt_u32_e64 s[30:31], s98, v85
	v_cndmask_b32_e64 v33, 0, v33, s[36:37]
	v_add_u32_e32 v86, 9, v84
	v_cmp_gt_u32_e64 s[36:37], s98, v86
	v_cndmask_b32_e64 v34, 0, v34, s[78:79]
	v_add_u32_e32 v87, 10, v84
	v_cmp_gt_u32_e64 s[78:79], s98, v87
	v_cndmask_b32_e64 v35, 0, v35, s[50:51]
	v_add_u32_e32 v88, 11, v84
	v_cmp_gt_u32_e64 s[50:51], s98, v88
	v_cndmask_b32_e64 v36, 0, v36, s[30:31]
	v_add_u32_e32 v85, 16, v84
	v_cmp_gt_u32_e64 s[30:31], s98, v85
	v_cndmask_b32_e64 v37, 0, v37, s[36:37]
	v_add_u32_e32 v86, 17, v84
	v_cmp_gt_u32_e64 s[36:37], s98, v86
	v_cndmask_b32_e64 v38, 0, v38, s[78:79]
	v_add_u32_e32 v87, 18, v84
	v_cmp_gt_u32_e64 s[78:79], s98, v87
	v_cndmask_b32_e64 v39, 0, v39, s[50:51]
	v_add_u32_e32 v88, 19, v84
	v_cmp_gt_u32_e64 s[50:51], s98, v88
	v_cndmask_b32_e64 v40, 0, v40, s[30:31]
	v_add_u32_e32 v85, 24, v84
	v_cmp_gt_u32_e64 s[30:31], s98, v85
	v_cndmask_b32_e64 v41, 0, v41, s[36:37]
	v_add_u32_e32 v86, 25, v84
	v_cmp_gt_u32_e64 s[36:37], s98, v86
	v_cndmask_b32_e64 v42, 0, v42, s[78:79]
	v_add_u32_e32 v87, 26, v84
	v_cmp_gt_u32_e64 s[78:79], s98, v87
	v_cndmask_b32_e64 v43, 0, v43, s[50:51]
	v_add_u32_e32 v88, 27, v84
	v_cmp_gt_u32_e64 s[50:51], s98, v88
	v_nop
	v_cndmask_b32_e64 v44, 0, v44, s[30:31]
	v_cndmask_b32_e64 v45, 0, v45, s[36:37]
	v_cndmask_b32_e64 v46, 0, v46, s[78:79]
	v_cndmask_b32_e64 v47, 0, v47, s[50:51]
	v_cvt_pk_bf16_f32 v64, v32, v33
	v_cvt_pk_bf16_f32 v65, v34, v35
	v_cvt_pk_bf16_f32 v66, v36, v37
	v_cvt_pk_bf16_f32 v67, v38, v39
	v_cvt_pk_bf16_f32 v68, v40, v41
	v_cvt_pk_bf16_f32 v69, v42, v43
	v_cvt_pk_bf16_f32 v70, v44, v45
	v_cvt_pk_bf16_f32 v71, v46, v47
	v_pk_add_f32 v[232:233], v[232:233], v[32:33]
	v_pk_add_f32 v[232:233], v[232:233], v[34:35]
	v_pk_add_f32 v[232:233], v[232:233], v[36:37]
	v_pk_add_f32 v[232:233], v[232:233], v[38:39]
	v_pk_add_f32 v[232:233], v[232:233], v[40:41]
	v_pk_add_f32 v[232:233], v[232:233], v[42:43]
	v_pk_add_f32 v[232:233], v[232:233], v[44:45]
	v_pk_add_f32 v[232:233], v[232:233], v[46:47]
	ds_read2_b32 v[32:33], v115 offset0:204 offset1:205
	ds_read2_b32 v[34:35], v115 offset0:206 offset1:207
	ds_read2_b32 v[36:37], v115 offset0:212 offset1:213
	ds_read2_b32 v[38:39], v115 offset0:214 offset1:215
	ds_read2_b32 v[40:41], v115 offset0:221 offset1:222
	ds_read2_b32 v[42:43], v115 offset0:223 offset1:224
	ds_read2_b32 v[44:45], v115 offset0:229 offset1:230
	ds_read2_b32 v[46:47], v115 offset0:231 offset1:232
	v_mfma_f32_32x32x16_bf16 v[0:15], v[64:67], v[72:75], v[0:15]
	v_mfma_f32_32x32x16_bf16 v[16:31], v[64:67], v[76:79], v[16:31]
	v_mfma_f32_32x32x16_bf16 v[0:15], v[68:71], v[220:223], v[0:15]
	v_mfma_f32_32x32x16_bf16 v[16:31], v[68:71], v[224:227], v[16:31]
	s_add_i32 s90, s76, 160
	v_add_u32_e32 v80, s90, v235
	v_add_u32_e32 v83, s90, v236
	v_add_u32_e32 v99, s90, v237
	v_add_u32_e32 v253, s90, v238
	v_add_u32_e32 v254, s90, v100
	v_add_u32_e32 v255, s90, v149
	v_med3_i32 v80, v80, 0, s99
	v_med3_i32 v83, v83, 0, s99
	v_med3_i32 v99, v99, 0, s99
	v_med3_i32 v253, v253, 0, s99
	v_med3_i32 v254, v254, 0, s99
	v_med3_i32 v255, v255, 0, s99
	v_mad_u32_u24 v80, v80, s100, v252
	v_mad_u32_u24 v83, v83, s100, v252
	v_mad_u32_u24 v99, v99, s100, v252
	v_mad_u32_u24 v253, v253, s100, v252
	v_mad_u32_u24 v254, v254, s100, v153
	v_mad_u32_u24 v255, v255, s100, v153
	global_load_dwordx4 v[156:159], v80, s[82:83]
	global_load_dwordx4 v[160:163], v83, s[82:83]
	global_load_dwordx4 v[164:167], v99, s[82:83]
	global_load_dwordx4 v[168:171], v253, s[82:83]
	global_load_dwordx4 v[172:175], v254, s[82:83] offset:768
	global_load_dwordx4 v[176:179], v255, s[82:83] offset:768
	global_load_dwordx4 v[180:183], v254, s[82:83] offset:832
	global_load_dwordx4 v[184:187], v255, s[82:83] offset:832
	ds_read_b64_tr_b16 v[72:73], v231
	ds_read_b64_tr_b16 v[74:75], v231 offset:512
	ds_read_b64_tr_b16 v[76:77], v231 offset:2048
	ds_read_b64_tr_b16 v[78:79], v231 offset:2560
	ds_read_b64_tr_b16 v[220:221], v231 offset:1024
	ds_read_b64_tr_b16 v[222:223], v231 offset:1536
	ds_read_b64_tr_b16 v[224:225], v231 offset:3072
	ds_read_b64_tr_b16 v[226:227], v231 offset:3584
	v_exp_f32_e32 v188, v188
	v_exp_f32_e32 v189, v189
	v_exp_f32_e32 v190, v190
	v_exp_f32_e32 v191, v191
	s_waitcnt vmcnt(8)
	ds_write_b128 v247, v[116:119]
	ds_write_b128 v247, v[120:123] offset:1024
	ds_write_b128 v247, v[124:127] offset:2048
	ds_write_b128 v247, v[128:131] offset:3072
	ds_read_b128 v[116:119], v248
	ds_read_b128 v[120:123], v249
	ds_read_b128 v[124:127], v250
	ds_read_b128 v[128:131], v251
	ds_write_b128 v112, v[132:135]
	ds_write_b128 v112, v[136:139] offset:1024
	ds_write_b128 v112, v[140:143] offset:2048
	ds_write_b128 v112, v[144:147] offset:3072
	v_exp_f32_e32 v192, v192
	v_exp_f32_e32 v193, v193
	v_exp_f32_e32 v194, v194
	v_exp_f32_e32 v195, v195
	s_waitcnt lgkmcnt(4)
	v_mfma_f32_32x32x16_bf16 v[32:47], v[116:119], v[48:51], v[32:47]
	v_exp_f32_e32 v196, v196
	v_exp_f32_e32 v197, v197
	v_mfma_f32_32x32x16_bf16 v[32:47], v[120:123], v[52:55], v[32:47]
	v_exp_f32_e32 v198, v198
	v_exp_f32_e32 v199, v199
	v_mfma_f32_32x32x16_bf16 v[32:47], v[124:127], v[56:59], v[32:47]
	v_exp_f32_e32 v200, v200
	v_exp_f32_e32 v201, v201
	v_mfma_f32_32x32x16_bf16 v[32:47], v[128:131], v[60:63], v[32:47]
	v_exp_f32_e32 v202, v202
	v_exp_f32_e32 v203, v203
	s_add_i32 s90, s76, 96
	v_add_u32_e32 v84, s90, v107
	v_add_u32_e32 v85, 0, v84
	v_add_u32_e32 v86, 1, v84
	v_add_u32_e32 v87, 2, v84
	v_add_u32_e32 v88, 3, v84
	v_cmp_gt_u32_e64 s[30:31], s98, v85
	v_cmp_gt_u32_e64 s[36:37], s98, v86
	v_cmp_gt_u32_e64 s[78:79], s98, v87
	v_cmp_gt_u32_e64 s[50:51], s98, v88
	v_cndmask_b32_e64 v188, 0, v188, s[30:31]
	v_add_u32_e32 v85, 8, v84
	v_cmp_gt_u32_e64 s[30:31], s98, v85
	v_cndmask_b32_e64 v189, 0, v189, s[36:37]
	v_add_u32_e32 v86, 9, v84
	v_cmp_gt_u32_e64 s[36:37], s98, v86
	v_cndmask_b32_e64 v190, 0, v190, s[78:79]
	v_add_u32_e32 v87, 10, v84
	v_cmp_gt_u32_e64 s[78:79], s98, v87
	v_cndmask_b32_e64 v191, 0, v191, s[50:51]
	v_add_u32_e32 v88, 11, v84
	v_cmp_gt_u32_e64 s[50:51], s98, v88
	v_cndmask_b32_e64 v192, 0, v192, s[30:31]
	v_add_u32_e32 v85, 16, v84
	v_cmp_gt_u32_e64 s[30:31], s98, v85
	v_cndmask_b32_e64 v193, 0, v193, s[36:37]
	v_add_u32_e32 v86, 17, v84
	v_cmp_gt_u32_e64 s[36:37], s98, v86
	v_cndmask_b32_e64 v194, 0, v194, s[78:79]
	v_add_u32_e32 v87, 18, v84
	v_cmp_gt_u32_e64 s[78:79], s98, v87
	v_cndmask_b32_e64 v195, 0, v195, s[50:51]
	v_add_u32_e32 v88, 19, v84
	v_cmp_gt_u32_e64 s[50:51], s98, v88
	v_cndmask_b32_e64 v196, 0, v196, s[30:31]
	v_add_u32_e32 v85, 24, v84
	v_cmp_gt_u32_e64 s[30:31], s98, v85
	v_cndmask_b32_e64 v197, 0, v197, s[36:37]
	v_add_u32_e32 v86, 25, v84
	v_cmp_gt_u32_e64 s[36:37], s98, v86
	v_cndmask_b32_e64 v198, 0, v198, s[78:79]
	v_add_u32_e32 v87, 26, v84
	v_cmp_gt_u32_e64 s[78:79], s98, v87
	v_cndmask_b32_e64 v199, 0, v199, s[50:51]
	v_add_u32_e32 v88, 27, v84
	v_cmp_gt_u32_e64 s[50:51], s98, v88
	v_nop
	v_cndmask_b32_e64 v200, 0, v200, s[30:31]
	v_cndmask_b32_e64 v201, 0, v201, s[36:37]
	v_cndmask_b32_e64 v202, 0, v202, s[78:79]
	v_cndmask_b32_e64 v203, 0, v203, s[50:51]
	v_cvt_pk_bf16_f32 v64, v188, v189
	v_cvt_pk_bf16_f32 v65, v190, v191
	v_cvt_pk_bf16_f32 v66, v192, v193
	v_cvt_pk_bf16_f32 v67, v194, v195
	v_cvt_pk_bf16_f32 v68, v196, v197
	v_cvt_pk_bf16_f32 v69, v198, v199
	v_cvt_pk_bf16_f32 v70, v200, v201
	v_cvt_pk_bf16_f32 v71, v202, v203
	v_pk_add_f32 v[232:233], v[232:233], v[188:189]
	v_pk_add_f32 v[232:233], v[232:233], v[190:191]
	v_pk_add_f32 v[232:233], v[232:233], v[192:193]
	v_pk_add_f32 v[232:233], v[232:233], v[194:195]
	v_pk_add_f32 v[232:233], v[232:233], v[196:197]
	v_pk_add_f32 v[232:233], v[232:233], v[198:199]
	v_pk_add_f32 v[232:233], v[232:233], v[200:201]
	v_pk_add_f32 v[232:233], v[232:233], v[202:203]
	v_add_u32_e32 v115, 952, v115
	ds_read2_b32 v[188:189], v115 offset0:0 offset1:1
	ds_read2_b32 v[190:191], v115 offset0:2 offset1:3
	ds_read2_b32 v[192:193], v115 offset0:8 offset1:9
	ds_read2_b32 v[194:195], v115 offset0:10 offset1:11
	ds_read2_b32 v[196:197], v115 offset0:17 offset1:18
	ds_read2_b32 v[198:199], v115 offset0:19 offset1:20
	ds_read2_b32 v[200:201], v115 offset0:25 offset1:26
	ds_read2_b32 v[202:203], v115 offset0:27 offset1:28
	v_mfma_f32_32x32x16_bf16 v[0:15], v[64:67], v[72:75], v[0:15]
	v_mfma_f32_32x32x16_bf16 v[16:31], v[64:67], v[76:79], v[16:31]
	v_mfma_f32_32x32x16_bf16 v[0:15], v[68:71], v[220:223], v[0:15]
	v_mfma_f32_32x32x16_bf16 v[16:31], v[68:71], v[224:227], v[16:31]
	s_add_i32 s90, s76, 192
	v_add_u32_e32 v80, s90, v235
	v_add_u32_e32 v83, s90, v236
	v_add_u32_e32 v99, s90, v237
	v_add_u32_e32 v253, s90, v238
	v_add_u32_e32 v254, s90, v100
	v_add_u32_e32 v255, s90, v149
	v_med3_i32 v80, v80, 0, s99
	v_med3_i32 v83, v83, 0, s99
	v_med3_i32 v99, v99, 0, s99
	v_med3_i32 v253, v253, 0, s99
	v_med3_i32 v254, v254, 0, s99
	v_med3_i32 v255, v255, 0, s99
	v_mad_u32_u24 v80, v80, s100, v252
	v_mad_u32_u24 v83, v83, s100, v252
	v_mad_u32_u24 v99, v99, s100, v252
	v_mad_u32_u24 v253, v253, s100, v252
	v_mad_u32_u24 v254, v254, s100, v153
	v_mad_u32_u24 v255, v255, s100, v153
	global_load_dwordx4 v[116:119], v80, s[82:83]
	global_load_dwordx4 v[120:123], v83, s[82:83]
	global_load_dwordx4 v[124:127], v99, s[82:83]
	global_load_dwordx4 v[128:131], v253, s[82:83]
	global_load_dwordx4 v[132:135], v254, s[82:83] offset:768
	global_load_dwordx4 v[136:139], v255, s[82:83] offset:768
	global_load_dwordx4 v[140:143], v254, s[82:83] offset:832
	global_load_dwordx4 v[144:147], v255, s[82:83] offset:832
	ds_read_b64_tr_b16 v[72:73], v231
	ds_read_b64_tr_b16 v[74:75], v231 offset:512
	ds_read_b64_tr_b16 v[76:77], v231 offset:2048
	ds_read_b64_tr_b16 v[78:79], v231 offset:2560
	ds_read_b64_tr_b16 v[220:221], v231 offset:1024
	ds_read_b64_tr_b16 v[222:223], v231 offset:1536
	ds_read_b64_tr_b16 v[224:225], v231 offset:3072
	ds_read_b64_tr_b16 v[226:227], v231 offset:3584
	v_exp_f32_e32 v32, v32
	v_exp_f32_e32 v33, v33
	v_exp_f32_e32 v34, v34
	v_exp_f32_e32 v35, v35
	s_waitcnt vmcnt(8)
	ds_write_b128 v247, v[156:159]
	ds_write_b128 v247, v[160:163] offset:1024
	ds_write_b128 v247, v[164:167] offset:2048
	ds_write_b128 v247, v[168:171] offset:3072
	ds_read_b128 v[156:159], v248
	ds_read_b128 v[160:163], v249
	ds_read_b128 v[164:167], v250
	ds_read_b128 v[168:171], v251
	ds_write_b128 v112, v[172:175]
	ds_write_b128 v112, v[176:179] offset:1024
	ds_write_b128 v112, v[180:183] offset:2048
	ds_write_b128 v112, v[184:187] offset:3072
	v_exp_f32_e32 v36, v36
	v_exp_f32_e32 v37, v37
	v_exp_f32_e32 v38, v38
	v_exp_f32_e32 v39, v39
	s_waitcnt lgkmcnt(4)
	v_mfma_f32_32x32x16_bf16 v[188:203], v[156:159], v[48:51], v[188:203]
	v_exp_f32_e32 v40, v40
	v_exp_f32_e32 v41, v41
	v_mfma_f32_32x32x16_bf16 v[188:203], v[160:163], v[52:55], v[188:203]
	v_exp_f32_e32 v42, v42
	v_exp_f32_e32 v43, v43
	v_mfma_f32_32x32x16_bf16 v[188:203], v[164:167], v[56:59], v[188:203]
	v_exp_f32_e32 v44, v44
	v_exp_f32_e32 v45, v45
	v_mfma_f32_32x32x16_bf16 v[188:203], v[168:171], v[60:63], v[188:203]
	v_exp_f32_e32 v46, v46
	v_exp_f32_e32 v47, v47
	s_add_i32 s90, s76, 128
	v_add_u32_e32 v84, s90, v107
	v_add_u32_e32 v85, 0, v84
	v_add_u32_e32 v86, 1, v84
	v_add_u32_e32 v87, 2, v84
	v_add_u32_e32 v88, 3, v84
	v_cmp_gt_u32_e64 s[30:31], s98, v85
	v_cmp_gt_u32_e64 s[36:37], s98, v86
	v_cmp_gt_u32_e64 s[78:79], s98, v87
	v_cmp_gt_u32_e64 s[50:51], s98, v88
	v_cndmask_b32_e64 v32, 0, v32, s[30:31]
	v_add_u32_e32 v85, 8, v84
	v_cmp_gt_u32_e64 s[30:31], s98, v85
	v_cndmask_b32_e64 v33, 0, v33, s[36:37]
	v_add_u32_e32 v86, 9, v84
	v_cmp_gt_u32_e64 s[36:37], s98, v86
	v_cndmask_b32_e64 v34, 0, v34, s[78:79]
	v_add_u32_e32 v87, 10, v84
	v_cmp_gt_u32_e64 s[78:79], s98, v87
	v_cndmask_b32_e64 v35, 0, v35, s[50:51]
	v_add_u32_e32 v88, 11, v84
	v_cmp_gt_u32_e64 s[50:51], s98, v88
	v_cndmask_b32_e64 v36, 0, v36, s[30:31]
	v_add_u32_e32 v85, 16, v84
	v_cmp_gt_u32_e64 s[30:31], s98, v85
	v_cndmask_b32_e64 v37, 0, v37, s[36:37]
	v_add_u32_e32 v86, 17, v84
	v_cmp_gt_u32_e64 s[36:37], s98, v86
	v_cndmask_b32_e64 v38, 0, v38, s[78:79]
	v_add_u32_e32 v87, 18, v84
	v_cmp_gt_u32_e64 s[78:79], s98, v87
	v_cndmask_b32_e64 v39, 0, v39, s[50:51]
	v_add_u32_e32 v88, 19, v84
	v_cmp_gt_u32_e64 s[50:51], s98, v88
	v_cndmask_b32_e64 v40, 0, v40, s[30:31]
	v_add_u32_e32 v85, 24, v84
	v_cmp_gt_u32_e64 s[30:31], s98, v85
	v_cndmask_b32_e64 v41, 0, v41, s[36:37]
	v_add_u32_e32 v86, 25, v84
	v_cmp_gt_u32_e64 s[36:37], s98, v86
	v_cndmask_b32_e64 v42, 0, v42, s[78:79]
	v_add_u32_e32 v87, 26, v84
	v_cmp_gt_u32_e64 s[78:79], s98, v87
	v_cndmask_b32_e64 v43, 0, v43, s[50:51]
	v_add_u32_e32 v88, 27, v84
	v_cmp_gt_u32_e64 s[50:51], s98, v88
	v_nop
	v_cndmask_b32_e64 v44, 0, v44, s[30:31]
	v_cndmask_b32_e64 v45, 0, v45, s[36:37]
	v_cndmask_b32_e64 v46, 0, v46, s[78:79]
	v_cndmask_b32_e64 v47, 0, v47, s[50:51]
	v_cvt_pk_bf16_f32 v64, v32, v33
	v_cvt_pk_bf16_f32 v65, v34, v35
	v_cvt_pk_bf16_f32 v66, v36, v37
	v_cvt_pk_bf16_f32 v67, v38, v39
	v_cvt_pk_bf16_f32 v68, v40, v41
	v_cvt_pk_bf16_f32 v69, v42, v43
	v_cvt_pk_bf16_f32 v70, v44, v45
	v_cvt_pk_bf16_f32 v71, v46, v47
	v_pk_add_f32 v[232:233], v[232:233], v[32:33]
	v_pk_add_f32 v[232:233], v[232:233], v[34:35]
	v_pk_add_f32 v[232:233], v[232:233], v[36:37]
	v_pk_add_f32 v[232:233], v[232:233], v[38:39]
	v_pk_add_f32 v[232:233], v[232:233], v[40:41]
	v_pk_add_f32 v[232:233], v[232:233], v[42:43]
	v_pk_add_f32 v[232:233], v[232:233], v[44:45]
	v_pk_add_f32 v[232:233], v[232:233], v[46:47]
	ds_read2_b32 v[32:33], v115 offset0:34 offset1:35
	ds_read2_b32 v[34:35], v115 offset0:36 offset1:37
	ds_read2_b32 v[36:37], v115 offset0:42 offset1:43
	ds_read2_b32 v[38:39], v115 offset0:44 offset1:45
	ds_read2_b32 v[40:41], v115 offset0:51 offset1:52
	ds_read2_b32 v[42:43], v115 offset0:53 offset1:54
	ds_read2_b32 v[44:45], v115 offset0:59 offset1:60
	ds_read2_b32 v[46:47], v115 offset0:61 offset1:62
	v_mfma_f32_32x32x16_bf16 v[0:15], v[64:67], v[72:75], v[0:15]
	v_mfma_f32_32x32x16_bf16 v[16:31], v[64:67], v[76:79], v[16:31]
	v_mfma_f32_32x32x16_bf16 v[0:15], v[68:71], v[220:223], v[0:15]
	v_mfma_f32_32x32x16_bf16 v[16:31], v[68:71], v[224:227], v[16:31]
	s_add_i32 s90, s76, 224
	v_add_u32_e32 v80, s90, v235
	v_add_u32_e32 v83, s90, v236
	v_add_u32_e32 v99, s90, v237
	v_add_u32_e32 v253, s90, v238
	v_add_u32_e32 v254, s90, v100
	v_add_u32_e32 v255, s90, v149
	v_med3_i32 v80, v80, 0, s99
	v_med3_i32 v83, v83, 0, s99
	v_med3_i32 v99, v99, 0, s99
	v_med3_i32 v253, v253, 0, s99
	v_med3_i32 v254, v254, 0, s99
	v_med3_i32 v255, v255, 0, s99
	v_mad_u32_u24 v80, v80, s100, v252
	v_mad_u32_u24 v83, v83, s100, v252
	v_mad_u32_u24 v99, v99, s100, v252
	v_mad_u32_u24 v253, v253, s100, v252
	v_mad_u32_u24 v254, v254, s100, v153
	v_mad_u32_u24 v255, v255, s100, v153
	global_load_dwordx4 v[156:159], v80, s[82:83]
	global_load_dwordx4 v[160:163], v83, s[82:83]
	global_load_dwordx4 v[164:167], v99, s[82:83]
	global_load_dwordx4 v[168:171], v253, s[82:83]
	global_load_dwordx4 v[172:175], v254, s[82:83] offset:768
	global_load_dwordx4 v[176:179], v255, s[82:83] offset:768
	global_load_dwordx4 v[180:183], v254, s[82:83] offset:832
	global_load_dwordx4 v[184:187], v255, s[82:83] offset:832
	ds_read_b64_tr_b16 v[72:73], v231
	ds_read_b64_tr_b16 v[74:75], v231 offset:512
	ds_read_b64_tr_b16 v[76:77], v231 offset:2048
	ds_read_b64_tr_b16 v[78:79], v231 offset:2560
	ds_read_b64_tr_b16 v[220:221], v231 offset:1024
	ds_read_b64_tr_b16 v[222:223], v231 offset:1536
	ds_read_b64_tr_b16 v[224:225], v231 offset:3072
	ds_read_b64_tr_b16 v[226:227], v231 offset:3584
	v_exp_f32_e32 v188, v188
	v_exp_f32_e32 v189, v189
	v_exp_f32_e32 v190, v190
	v_exp_f32_e32 v191, v191
	s_waitcnt vmcnt(8)
	ds_write_b128 v247, v[116:119]
	ds_write_b128 v247, v[120:123] offset:1024
	ds_write_b128 v247, v[124:127] offset:2048
	ds_write_b128 v247, v[128:131] offset:3072
	ds_read_b128 v[116:119], v248
	ds_read_b128 v[120:123], v249
	ds_read_b128 v[124:127], v250
	ds_read_b128 v[128:131], v251
	ds_write_b128 v112, v[132:135]
	ds_write_b128 v112, v[136:139] offset:1024
	ds_write_b128 v112, v[140:143] offset:2048
	ds_write_b128 v112, v[144:147] offset:3072
	v_exp_f32_e32 v192, v192
	v_exp_f32_e32 v193, v193
	v_exp_f32_e32 v194, v194
	v_exp_f32_e32 v195, v195
	s_waitcnt lgkmcnt(4)
	v_mfma_f32_32x32x16_bf16 v[32:47], v[116:119], v[48:51], v[32:47]
	v_exp_f32_e32 v196, v196
	v_exp_f32_e32 v197, v197
	v_mfma_f32_32x32x16_bf16 v[32:47], v[120:123], v[52:55], v[32:47]
	v_exp_f32_e32 v198, v198
	v_exp_f32_e32 v199, v199
	v_mfma_f32_32x32x16_bf16 v[32:47], v[124:127], v[56:59], v[32:47]
	v_exp_f32_e32 v200, v200
	v_exp_f32_e32 v201, v201
	v_mfma_f32_32x32x16_bf16 v[32:47], v[128:131], v[60:63], v[32:47]
	v_exp_f32_e32 v202, v202
	v_exp_f32_e32 v203, v203
	s_add_i32 s90, s76, 160
	v_add_u32_e32 v84, s90, v107
	v_add_u32_e32 v85, 0, v84
	v_add_u32_e32 v86, 1, v84
	v_add_u32_e32 v87, 2, v84
	v_add_u32_e32 v88, 3, v84
	v_cmp_gt_u32_e64 s[30:31], s98, v85
	v_cmp_gt_u32_e64 s[36:37], s98, v86
	v_cmp_gt_u32_e64 s[78:79], s98, v87
	v_cmp_gt_u32_e64 s[50:51], s98, v88
	v_cndmask_b32_e64 v188, 0, v188, s[30:31]
	v_add_u32_e32 v85, 8, v84
	v_cmp_gt_u32_e64 s[30:31], s98, v85
	v_cndmask_b32_e64 v189, 0, v189, s[36:37]
	v_add_u32_e32 v86, 9, v84
	v_cmp_gt_u32_e64 s[36:37], s98, v86
	v_cndmask_b32_e64 v190, 0, v190, s[78:79]
	v_add_u32_e32 v87, 10, v84
	v_cmp_gt_u32_e64 s[78:79], s98, v87
	v_cndmask_b32_e64 v191, 0, v191, s[50:51]
	v_add_u32_e32 v88, 11, v84
	v_cmp_gt_u32_e64 s[50:51], s98, v88
	v_cndmask_b32_e64 v192, 0, v192, s[30:31]
	v_add_u32_e32 v85, 16, v84
	v_cmp_gt_u32_e64 s[30:31], s98, v85
	v_cndmask_b32_e64 v193, 0, v193, s[36:37]
	v_add_u32_e32 v86, 17, v84
	v_cmp_gt_u32_e64 s[36:37], s98, v86
	v_cndmask_b32_e64 v194, 0, v194, s[78:79]
	v_add_u32_e32 v87, 18, v84
	v_cmp_gt_u32_e64 s[78:79], s98, v87
	v_cndmask_b32_e64 v195, 0, v195, s[50:51]
	v_add_u32_e32 v88, 19, v84
	v_cmp_gt_u32_e64 s[50:51], s98, v88
	v_cndmask_b32_e64 v196, 0, v196, s[30:31]
	v_add_u32_e32 v85, 24, v84
	v_cmp_gt_u32_e64 s[30:31], s98, v85
	v_cndmask_b32_e64 v197, 0, v197, s[36:37]
	v_add_u32_e32 v86, 25, v84
	v_cmp_gt_u32_e64 s[36:37], s98, v86
	v_cndmask_b32_e64 v198, 0, v198, s[78:79]
	v_add_u32_e32 v87, 26, v84
	v_cmp_gt_u32_e64 s[78:79], s98, v87
	v_cndmask_b32_e64 v199, 0, v199, s[50:51]
	v_add_u32_e32 v88, 27, v84
	v_cmp_gt_u32_e64 s[50:51], s98, v88
	v_nop
	v_cndmask_b32_e64 v200, 0, v200, s[30:31]
	v_cndmask_b32_e64 v201, 0, v201, s[36:37]
	v_cndmask_b32_e64 v202, 0, v202, s[78:79]
	v_cndmask_b32_e64 v203, 0, v203, s[50:51]
	v_cvt_pk_bf16_f32 v64, v188, v189
	v_cvt_pk_bf16_f32 v65, v190, v191
	v_cvt_pk_bf16_f32 v66, v192, v193
	v_cvt_pk_bf16_f32 v67, v194, v195
	v_cvt_pk_bf16_f32 v68, v196, v197
	v_cvt_pk_bf16_f32 v69, v198, v199
	v_cvt_pk_bf16_f32 v70, v200, v201
	v_cvt_pk_bf16_f32 v71, v202, v203
	v_pk_add_f32 v[232:233], v[232:233], v[188:189]
	v_pk_add_f32 v[232:233], v[232:233], v[190:191]
	v_pk_add_f32 v[232:233], v[232:233], v[192:193]
	v_pk_add_f32 v[232:233], v[232:233], v[194:195]
	v_pk_add_f32 v[232:233], v[232:233], v[196:197]
	v_pk_add_f32 v[232:233], v[232:233], v[198:199]
	v_pk_add_f32 v[232:233], v[232:233], v[200:201]
	v_pk_add_f32 v[232:233], v[232:233], v[202:203]
	ds_read2_b32 v[188:189], v115 offset0:68 offset1:69
	ds_read2_b32 v[190:191], v115 offset0:70 offset1:71
	ds_read2_b32 v[192:193], v115 offset0:76 offset1:77
	ds_read2_b32 v[194:195], v115 offset0:78 offset1:79
	ds_read2_b32 v[196:197], v115 offset0:85 offset1:86
	ds_read2_b32 v[198:199], v115 offset0:87 offset1:88
	ds_read2_b32 v[200:201], v115 offset0:93 offset1:94
	ds_read2_b32 v[202:203], v115 offset0:95 offset1:96
	v_mfma_f32_32x32x16_bf16 v[0:15], v[64:67], v[72:75], v[0:15]
	v_mfma_f32_32x32x16_bf16 v[16:31], v[64:67], v[76:79], v[16:31]
	v_mfma_f32_32x32x16_bf16 v[0:15], v[68:71], v[220:223], v[0:15]
	v_mfma_f32_32x32x16_bf16 v[16:31], v[68:71], v[224:227], v[16:31]
	s_add_i32 s90, s76, 256
	v_add_u32_e32 v80, s90, v235
	v_add_u32_e32 v83, s90, v236
	v_add_u32_e32 v99, s90, v237
	v_add_u32_e32 v253, s90, v238
	v_add_u32_e32 v254, s90, v100
	v_add_u32_e32 v255, s90, v149
	v_med3_i32 v80, v80, 0, s99
	v_med3_i32 v83, v83, 0, s99
	v_med3_i32 v99, v99, 0, s99
	v_med3_i32 v253, v253, 0, s99
	v_med3_i32 v254, v254, 0, s99
	v_med3_i32 v255, v255, 0, s99
	v_mad_u32_u24 v80, v80, s100, v252
	v_mad_u32_u24 v83, v83, s100, v252
	v_mad_u32_u24 v99, v99, s100, v252
	v_mad_u32_u24 v253, v253, s100, v252
	v_mad_u32_u24 v254, v254, s100, v153
	v_mad_u32_u24 v255, v255, s100, v153
	global_load_dwordx4 v[116:119], v80, s[82:83]
	global_load_dwordx4 v[120:123], v83, s[82:83]
	global_load_dwordx4 v[124:127], v99, s[82:83]
	global_load_dwordx4 v[128:131], v253, s[82:83]
	global_load_dwordx4 v[132:135], v254, s[82:83] offset:768
	global_load_dwordx4 v[136:139], v255, s[82:83] offset:768
	global_load_dwordx4 v[140:143], v254, s[82:83] offset:832
	global_load_dwordx4 v[144:147], v255, s[82:83] offset:832
	ds_read_b64_tr_b16 v[72:73], v231
	ds_read_b64_tr_b16 v[74:75], v231 offset:512
	ds_read_b64_tr_b16 v[76:77], v231 offset:2048
	ds_read_b64_tr_b16 v[78:79], v231 offset:2560
	ds_read_b64_tr_b16 v[220:221], v231 offset:1024
	ds_read_b64_tr_b16 v[222:223], v231 offset:1536
	ds_read_b64_tr_b16 v[224:225], v231 offset:3072
	ds_read_b64_tr_b16 v[226:227], v231 offset:3584
	v_exp_f32_e32 v32, v32
	v_exp_f32_e32 v33, v33
	v_exp_f32_e32 v34, v34
	v_exp_f32_e32 v35, v35
	s_waitcnt vmcnt(8)
	ds_write_b128 v247, v[156:159]
	ds_write_b128 v247, v[160:163] offset:1024
	ds_write_b128 v247, v[164:167] offset:2048
	ds_write_b128 v247, v[168:171] offset:3072
	ds_read_b128 v[156:159], v248
	ds_read_b128 v[160:163], v249
	ds_read_b128 v[164:167], v250
	ds_read_b128 v[168:171], v251
	ds_write_b128 v112, v[172:175]
	ds_write_b128 v112, v[176:179] offset:1024
	ds_write_b128 v112, v[180:183] offset:2048
	ds_write_b128 v112, v[184:187] offset:3072
	v_exp_f32_e32 v36, v36
	v_exp_f32_e32 v37, v37
	v_exp_f32_e32 v38, v38
	v_exp_f32_e32 v39, v39
	s_waitcnt lgkmcnt(4)
	v_mfma_f32_32x32x16_bf16 v[188:203], v[156:159], v[48:51], v[188:203]
	v_exp_f32_e32 v40, v40
	v_exp_f32_e32 v41, v41
	v_mfma_f32_32x32x16_bf16 v[188:203], v[160:163], v[52:55], v[188:203]
	v_exp_f32_e32 v42, v42
	v_exp_f32_e32 v43, v43
	v_mfma_f32_32x32x16_bf16 v[188:203], v[164:167], v[56:59], v[188:203]
	v_exp_f32_e32 v44, v44
	v_exp_f32_e32 v45, v45
	v_mfma_f32_32x32x16_bf16 v[188:203], v[168:171], v[60:63], v[188:203]
	v_exp_f32_e32 v46, v46
	v_exp_f32_e32 v47, v47
	s_add_i32 s90, s76, 192
	v_add_u32_e32 v84, s90, v107
	v_add_u32_e32 v85, 0, v84
	v_add_u32_e32 v86, 1, v84
	v_add_u32_e32 v87, 2, v84
	v_add_u32_e32 v88, 3, v84
	v_cmp_gt_u32_e64 s[30:31], s98, v85
	v_cmp_gt_u32_e64 s[36:37], s98, v86
	v_cmp_gt_u32_e64 s[78:79], s98, v87
	v_cmp_gt_u32_e64 s[50:51], s98, v88
	v_cndmask_b32_e64 v32, 0, v32, s[30:31]
	v_add_u32_e32 v85, 8, v84
	v_cmp_gt_u32_e64 s[30:31], s98, v85
	v_cndmask_b32_e64 v33, 0, v33, s[36:37]
	v_add_u32_e32 v86, 9, v84
	v_cmp_gt_u32_e64 s[36:37], s98, v86
	v_cndmask_b32_e64 v34, 0, v34, s[78:79]
	v_add_u32_e32 v87, 10, v84
	v_cmp_gt_u32_e64 s[78:79], s98, v87
	v_cndmask_b32_e64 v35, 0, v35, s[50:51]
	v_add_u32_e32 v88, 11, v84
	v_cmp_gt_u32_e64 s[50:51], s98, v88
	v_cndmask_b32_e64 v36, 0, v36, s[30:31]
	v_add_u32_e32 v85, 16, v84
	v_cmp_gt_u32_e64 s[30:31], s98, v85
	v_cndmask_b32_e64 v37, 0, v37, s[36:37]
	v_add_u32_e32 v86, 17, v84
	v_cmp_gt_u32_e64 s[36:37], s98, v86
	v_cndmask_b32_e64 v38, 0, v38, s[78:79]
	v_add_u32_e32 v87, 18, v84
	v_cmp_gt_u32_e64 s[78:79], s98, v87
	v_cndmask_b32_e64 v39, 0, v39, s[50:51]
	v_add_u32_e32 v88, 19, v84
	v_cmp_gt_u32_e64 s[50:51], s98, v88
	v_cndmask_b32_e64 v40, 0, v40, s[30:31]
	v_add_u32_e32 v85, 24, v84
	v_cmp_gt_u32_e64 s[30:31], s98, v85
	v_cndmask_b32_e64 v41, 0, v41, s[36:37]
	v_add_u32_e32 v86, 25, v84
	v_cmp_gt_u32_e64 s[36:37], s98, v86
	v_cndmask_b32_e64 v42, 0, v42, s[78:79]
	v_add_u32_e32 v87, 26, v84
	v_cmp_gt_u32_e64 s[78:79], s98, v87
	v_cndmask_b32_e64 v43, 0, v43, s[50:51]
	v_add_u32_e32 v88, 27, v84
	v_cmp_gt_u32_e64 s[50:51], s98, v88
	v_nop
	v_cndmask_b32_e64 v44, 0, v44, s[30:31]
	v_cndmask_b32_e64 v45, 0, v45, s[36:37]
	v_cndmask_b32_e64 v46, 0, v46, s[78:79]
	v_cndmask_b32_e64 v47, 0, v47, s[50:51]
	v_cvt_pk_bf16_f32 v64, v32, v33
	v_cvt_pk_bf16_f32 v65, v34, v35
	v_cvt_pk_bf16_f32 v66, v36, v37
	v_cvt_pk_bf16_f32 v67, v38, v39
	v_cvt_pk_bf16_f32 v68, v40, v41
	v_cvt_pk_bf16_f32 v69, v42, v43
	v_cvt_pk_bf16_f32 v70, v44, v45
	v_cvt_pk_bf16_f32 v71, v46, v47
	v_pk_add_f32 v[232:233], v[232:233], v[32:33]
	v_pk_add_f32 v[232:233], v[232:233], v[34:35]
	v_pk_add_f32 v[232:233], v[232:233], v[36:37]
	v_pk_add_f32 v[232:233], v[232:233], v[38:39]
	v_pk_add_f32 v[232:233], v[232:233], v[40:41]
	v_pk_add_f32 v[232:233], v[232:233], v[42:43]
	v_pk_add_f32 v[232:233], v[232:233], v[44:45]
	v_pk_add_f32 v[232:233], v[232:233], v[46:47]
	ds_read2_b32 v[32:33], v115 offset0:102 offset1:103
	ds_read2_b32 v[34:35], v115 offset0:104 offset1:105
	ds_read2_b32 v[36:37], v115 offset0:110 offset1:111
	ds_read2_b32 v[38:39], v115 offset0:112 offset1:113
	ds_read2_b32 v[40:41], v115 offset0:119 offset1:120
	ds_read2_b32 v[42:43], v115 offset0:121 offset1:122
	ds_read2_b32 v[44:45], v115 offset0:127 offset1:128
	ds_read2_b32 v[46:47], v115 offset0:129 offset1:130
	v_mfma_f32_32x32x16_bf16 v[0:15], v[64:67], v[72:75], v[0:15]
	v_mfma_f32_32x32x16_bf16 v[16:31], v[64:67], v[76:79], v[16:31]
	v_mfma_f32_32x32x16_bf16 v[0:15], v[68:71], v[220:223], v[0:15]
	v_mfma_f32_32x32x16_bf16 v[16:31], v[68:71], v[224:227], v[16:31]
	s_add_i32 s90, s76, 288
	v_add_u32_e32 v80, s90, v235
	v_add_u32_e32 v83, s90, v236
	v_add_u32_e32 v99, s90, v237
	v_add_u32_e32 v253, s90, v238
	v_add_u32_e32 v254, s90, v100
	v_add_u32_e32 v255, s90, v149
	v_med3_i32 v80, v80, 0, s99
	v_med3_i32 v83, v83, 0, s99
	v_med3_i32 v99, v99, 0, s99
	v_med3_i32 v253, v253, 0, s99
	v_med3_i32 v254, v254, 0, s99
	v_med3_i32 v255, v255, 0, s99
	v_mad_u32_u24 v80, v80, s100, v252
	v_mad_u32_u24 v83, v83, s100, v252
	v_mad_u32_u24 v99, v99, s100, v252
	v_mad_u32_u24 v253, v253, s100, v252
	v_mad_u32_u24 v254, v254, s100, v153
	v_mad_u32_u24 v255, v255, s100, v153
	global_load_dwordx4 v[156:159], v80, s[82:83]
	global_load_dwordx4 v[160:163], v83, s[82:83]
	global_load_dwordx4 v[164:167], v99, s[82:83]
	global_load_dwordx4 v[168:171], v253, s[82:83]
	global_load_dwordx4 v[172:175], v254, s[82:83] offset:768
	global_load_dwordx4 v[176:179], v255, s[82:83] offset:768
	global_load_dwordx4 v[180:183], v254, s[82:83] offset:832
	global_load_dwordx4 v[184:187], v255, s[82:83] offset:832
	ds_read_b64_tr_b16 v[72:73], v231
	ds_read_b64_tr_b16 v[74:75], v231 offset:512
	ds_read_b64_tr_b16 v[76:77], v231 offset:2048
	ds_read_b64_tr_b16 v[78:79], v231 offset:2560
	ds_read_b64_tr_b16 v[220:221], v231 offset:1024
	ds_read_b64_tr_b16 v[222:223], v231 offset:1536
	ds_read_b64_tr_b16 v[224:225], v231 offset:3072
	ds_read_b64_tr_b16 v[226:227], v231 offset:3584
	v_exp_f32_e32 v188, v188
	v_exp_f32_e32 v189, v189
	v_exp_f32_e32 v190, v190
	v_exp_f32_e32 v191, v191
	s_waitcnt vmcnt(8)
	ds_write_b128 v247, v[116:119]
	ds_write_b128 v247, v[120:123] offset:1024
	ds_write_b128 v247, v[124:127] offset:2048
	ds_write_b128 v247, v[128:131] offset:3072
	ds_read_b128 v[116:119], v248
	ds_read_b128 v[120:123], v249
	ds_read_b128 v[124:127], v250
	ds_read_b128 v[128:131], v251
	ds_write_b128 v112, v[132:135]
	ds_write_b128 v112, v[136:139] offset:1024
	ds_write_b128 v112, v[140:143] offset:2048
	ds_write_b128 v112, v[144:147] offset:3072
	v_exp_f32_e32 v192, v192
	v_exp_f32_e32 v193, v193
	v_exp_f32_e32 v194, v194
	v_exp_f32_e32 v195, v195
	s_waitcnt lgkmcnt(4)
	v_mfma_f32_32x32x16_bf16 v[32:47], v[116:119], v[48:51], v[32:47]
	v_exp_f32_e32 v196, v196
	v_exp_f32_e32 v197, v197
	v_mfma_f32_32x32x16_bf16 v[32:47], v[120:123], v[52:55], v[32:47]
	v_exp_f32_e32 v198, v198
	v_exp_f32_e32 v199, v199
	v_mfma_f32_32x32x16_bf16 v[32:47], v[124:127], v[56:59], v[32:47]
	v_exp_f32_e32 v200, v200
	v_exp_f32_e32 v201, v201
	v_mfma_f32_32x32x16_bf16 v[32:47], v[128:131], v[60:63], v[32:47]
	v_exp_f32_e32 v202, v202
	v_exp_f32_e32 v203, v203
	s_add_i32 s90, s76, 224
	v_add_u32_e32 v84, s90, v107
	v_add_u32_e32 v85, 0, v84
	v_add_u32_e32 v86, 1, v84
	v_add_u32_e32 v87, 2, v84
	v_add_u32_e32 v88, 3, v84
	v_cmp_gt_u32_e64 s[30:31], s98, v85
	v_cmp_gt_u32_e64 s[36:37], s98, v86
	v_cmp_gt_u32_e64 s[78:79], s98, v87
	v_cmp_gt_u32_e64 s[50:51], s98, v88
	v_cndmask_b32_e64 v188, 0, v188, s[30:31]
	v_add_u32_e32 v85, 8, v84
	v_cmp_gt_u32_e64 s[30:31], s98, v85
	v_cndmask_b32_e64 v189, 0, v189, s[36:37]
	v_add_u32_e32 v86, 9, v84
	v_cmp_gt_u32_e64 s[36:37], s98, v86
	v_cndmask_b32_e64 v190, 0, v190, s[78:79]
	v_add_u32_e32 v87, 10, v84
	v_cmp_gt_u32_e64 s[78:79], s98, v87
	v_cndmask_b32_e64 v191, 0, v191, s[50:51]
	v_add_u32_e32 v88, 11, v84
	v_cmp_gt_u32_e64 s[50:51], s98, v88
	v_cndmask_b32_e64 v192, 0, v192, s[30:31]
	v_add_u32_e32 v85, 16, v84
	v_cmp_gt_u32_e64 s[30:31], s98, v85
	v_cndmask_b32_e64 v193, 0, v193, s[36:37]
	v_add_u32_e32 v86, 17, v84
	v_cmp_gt_u32_e64 s[36:37], s98, v86
	v_cndmask_b32_e64 v194, 0, v194, s[78:79]
	v_add_u32_e32 v87, 18, v84
	v_cmp_gt_u32_e64 s[78:79], s98, v87
	v_cndmask_b32_e64 v195, 0, v195, s[50:51]
	v_add_u32_e32 v88, 19, v84
	v_cmp_gt_u32_e64 s[50:51], s98, v88
	v_cndmask_b32_e64 v196, 0, v196, s[30:31]
	v_add_u32_e32 v85, 24, v84
	v_cmp_gt_u32_e64 s[30:31], s98, v85
	v_cndmask_b32_e64 v197, 0, v197, s[36:37]
	v_add_u32_e32 v86, 25, v84
	v_cmp_gt_u32_e64 s[36:37], s98, v86
	v_cndmask_b32_e64 v198, 0, v198, s[78:79]
	v_add_u32_e32 v87, 26, v84
	v_cmp_gt_u32_e64 s[78:79], s98, v87
	v_cndmask_b32_e64 v199, 0, v199, s[50:51]
	v_add_u32_e32 v88, 27, v84
	v_cmp_gt_u32_e64 s[50:51], s98, v88
	v_nop
	v_cndmask_b32_e64 v200, 0, v200, s[30:31]
	v_cndmask_b32_e64 v201, 0, v201, s[36:37]
	v_cndmask_b32_e64 v202, 0, v202, s[78:79]
	v_cndmask_b32_e64 v203, 0, v203, s[50:51]
	v_cvt_pk_bf16_f32 v64, v188, v189
	v_cvt_pk_bf16_f32 v65, v190, v191
	v_cvt_pk_bf16_f32 v66, v192, v193
	v_cvt_pk_bf16_f32 v67, v194, v195
	v_cvt_pk_bf16_f32 v68, v196, v197
	v_cvt_pk_bf16_f32 v69, v198, v199
	v_cvt_pk_bf16_f32 v70, v200, v201
	v_cvt_pk_bf16_f32 v71, v202, v203
	v_pk_add_f32 v[232:233], v[232:233], v[188:189]
	v_pk_add_f32 v[232:233], v[232:233], v[190:191]
	v_pk_add_f32 v[232:233], v[232:233], v[192:193]
	v_pk_add_f32 v[232:233], v[232:233], v[194:195]
	v_pk_add_f32 v[232:233], v[232:233], v[196:197]
	v_pk_add_f32 v[232:233], v[232:233], v[198:199]
	v_pk_add_f32 v[232:233], v[232:233], v[200:201]
	v_pk_add_f32 v[232:233], v[232:233], v[202:203]
	ds_read2_b32 v[188:189], v115 offset0:136 offset1:137
	ds_read2_b32 v[190:191], v115 offset0:138 offset1:139
	ds_read2_b32 v[192:193], v115 offset0:144 offset1:145
	ds_read2_b32 v[194:195], v115 offset0:146 offset1:147
	ds_read2_b32 v[196:197], v115 offset0:153 offset1:154
	ds_read2_b32 v[198:199], v115 offset0:155 offset1:156
	ds_read2_b32 v[200:201], v115 offset0:161 offset1:162
	ds_read2_b32 v[202:203], v115 offset0:163 offset1:164
	v_mfma_f32_32x32x16_bf16 v[0:15], v[64:67], v[72:75], v[0:15]
	v_mfma_f32_32x32x16_bf16 v[16:31], v[64:67], v[76:79], v[16:31]
	v_mfma_f32_32x32x16_bf16 v[0:15], v[68:71], v[220:223], v[0:15]
	v_mfma_f32_32x32x16_bf16 v[16:31], v[68:71], v[224:227], v[16:31]
	s_add_i32 s90, s76, 320
	v_add_u32_e32 v80, s90, v235
	v_add_u32_e32 v83, s90, v236
	v_add_u32_e32 v99, s90, v237
	v_add_u32_e32 v253, s90, v238
	v_add_u32_e32 v254, s90, v100
	v_add_u32_e32 v255, s90, v149
	v_med3_i32 v80, v80, 0, s99
	v_med3_i32 v83, v83, 0, s99
	v_med3_i32 v99, v99, 0, s99
	v_med3_i32 v253, v253, 0, s99
	v_med3_i32 v254, v254, 0, s99
	v_med3_i32 v255, v255, 0, s99
	v_mad_u32_u24 v80, v80, s100, v252
	v_mad_u32_u24 v83, v83, s100, v252
	v_mad_u32_u24 v99, v99, s100, v252
	v_mad_u32_u24 v253, v253, s100, v252
	v_mad_u32_u24 v254, v254, s100, v153
	v_mad_u32_u24 v255, v255, s100, v153
	global_load_dwordx4 v[116:119], v80, s[82:83]
	global_load_dwordx4 v[120:123], v83, s[82:83]
	global_load_dwordx4 v[124:127], v99, s[82:83]
	global_load_dwordx4 v[128:131], v253, s[82:83]
	global_load_dwordx4 v[132:135], v254, s[82:83] offset:768
	global_load_dwordx4 v[136:139], v255, s[82:83] offset:768
	global_load_dwordx4 v[140:143], v254, s[82:83] offset:832
	global_load_dwordx4 v[144:147], v255, s[82:83] offset:832
	ds_read_b64_tr_b16 v[72:73], v231
	ds_read_b64_tr_b16 v[74:75], v231 offset:512
	ds_read_b64_tr_b16 v[76:77], v231 offset:2048
	ds_read_b64_tr_b16 v[78:79], v231 offset:2560
	ds_read_b64_tr_b16 v[220:221], v231 offset:1024
	ds_read_b64_tr_b16 v[222:223], v231 offset:1536
	ds_read_b64_tr_b16 v[224:225], v231 offset:3072
	ds_read_b64_tr_b16 v[226:227], v231 offset:3584
	v_exp_f32_e32 v32, v32
	v_exp_f32_e32 v33, v33
	v_exp_f32_e32 v34, v34
	v_exp_f32_e32 v35, v35
	s_waitcnt vmcnt(8)
	ds_write_b128 v247, v[156:159]
	ds_write_b128 v247, v[160:163] offset:1024
	ds_write_b128 v247, v[164:167] offset:2048
	ds_write_b128 v247, v[168:171] offset:3072
	ds_read_b128 v[156:159], v248
	ds_read_b128 v[160:163], v249
	ds_read_b128 v[164:167], v250
	ds_read_b128 v[168:171], v251
	ds_write_b128 v112, v[172:175]
	ds_write_b128 v112, v[176:179] offset:1024
	ds_write_b128 v112, v[180:183] offset:2048
	ds_write_b128 v112, v[184:187] offset:3072
	v_exp_f32_e32 v36, v36
	v_exp_f32_e32 v37, v37
	v_exp_f32_e32 v38, v38
	v_exp_f32_e32 v39, v39
	s_waitcnt lgkmcnt(4)
	v_mfma_f32_32x32x16_bf16 v[188:203], v[156:159], v[48:51], v[188:203]
	v_exp_f32_e32 v40, v40
	v_exp_f32_e32 v41, v41
	v_mfma_f32_32x32x16_bf16 v[188:203], v[160:163], v[52:55], v[188:203]
	v_exp_f32_e32 v42, v42
	v_exp_f32_e32 v43, v43
	v_mfma_f32_32x32x16_bf16 v[188:203], v[164:167], v[56:59], v[188:203]
	v_exp_f32_e32 v44, v44
	v_exp_f32_e32 v45, v45
	v_mfma_f32_32x32x16_bf16 v[188:203], v[168:171], v[60:63], v[188:203]
	v_exp_f32_e32 v46, v46
	v_exp_f32_e32 v47, v47
	s_add_i32 s90, s76, 256
	v_add_u32_e32 v84, s90, v107
	v_add_u32_e32 v85, 0, v84
	v_add_u32_e32 v86, 1, v84
	v_add_u32_e32 v87, 2, v84
	v_add_u32_e32 v88, 3, v84
	v_cmp_gt_u32_e64 s[30:31], s98, v85
	v_cmp_gt_u32_e64 s[36:37], s98, v86
	v_cmp_gt_u32_e64 s[78:79], s98, v87
	v_cmp_gt_u32_e64 s[50:51], s98, v88
	v_cndmask_b32_e64 v32, 0, v32, s[30:31]
	v_add_u32_e32 v85, 8, v84
	v_cmp_gt_u32_e64 s[30:31], s98, v85
	v_cndmask_b32_e64 v33, 0, v33, s[36:37]
	v_add_u32_e32 v86, 9, v84
	v_cmp_gt_u32_e64 s[36:37], s98, v86
	v_cndmask_b32_e64 v34, 0, v34, s[78:79]
	v_add_u32_e32 v87, 10, v84
	v_cmp_gt_u32_e64 s[78:79], s98, v87
	v_cndmask_b32_e64 v35, 0, v35, s[50:51]
	v_add_u32_e32 v88, 11, v84
	v_cmp_gt_u32_e64 s[50:51], s98, v88
	v_cndmask_b32_e64 v36, 0, v36, s[30:31]
	v_add_u32_e32 v85, 16, v84
	v_cmp_gt_u32_e64 s[30:31], s98, v85
	v_cndmask_b32_e64 v37, 0, v37, s[36:37]
	v_add_u32_e32 v86, 17, v84
	v_cmp_gt_u32_e64 s[36:37], s98, v86
	v_cndmask_b32_e64 v38, 0, v38, s[78:79]
	v_add_u32_e32 v87, 18, v84
	v_cmp_gt_u32_e64 s[78:79], s98, v87
	v_cndmask_b32_e64 v39, 0, v39, s[50:51]
	v_add_u32_e32 v88, 19, v84
	v_cmp_gt_u32_e64 s[50:51], s98, v88
	v_cndmask_b32_e64 v40, 0, v40, s[30:31]
	v_add_u32_e32 v85, 24, v84
	v_cmp_gt_u32_e64 s[30:31], s98, v85
	v_cndmask_b32_e64 v41, 0, v41, s[36:37]
	v_add_u32_e32 v86, 25, v84
	v_cmp_gt_u32_e64 s[36:37], s98, v86
	v_cndmask_b32_e64 v42, 0, v42, s[78:79]
	v_add_u32_e32 v87, 26, v84
	v_cmp_gt_u32_e64 s[78:79], s98, v87
	v_cndmask_b32_e64 v43, 0, v43, s[50:51]
	v_add_u32_e32 v88, 27, v84
	v_cmp_gt_u32_e64 s[50:51], s98, v88
	v_nop
	v_cndmask_b32_e64 v44, 0, v44, s[30:31]
	v_cndmask_b32_e64 v45, 0, v45, s[36:37]
	v_cndmask_b32_e64 v46, 0, v46, s[78:79]
	v_cndmask_b32_e64 v47, 0, v47, s[50:51]
	v_cvt_pk_bf16_f32 v64, v32, v33
	v_cvt_pk_bf16_f32 v65, v34, v35
	v_cvt_pk_bf16_f32 v66, v36, v37
	v_cvt_pk_bf16_f32 v67, v38, v39
	v_cvt_pk_bf16_f32 v68, v40, v41
	v_cvt_pk_bf16_f32 v69, v42, v43
	v_cvt_pk_bf16_f32 v70, v44, v45
	v_cvt_pk_bf16_f32 v71, v46, v47
	v_pk_add_f32 v[232:233], v[232:233], v[32:33]
	v_pk_add_f32 v[232:233], v[232:233], v[34:35]
	v_pk_add_f32 v[232:233], v[232:233], v[36:37]
	v_pk_add_f32 v[232:233], v[232:233], v[38:39]
	v_pk_add_f32 v[232:233], v[232:233], v[40:41]
	v_pk_add_f32 v[232:233], v[232:233], v[42:43]
	v_pk_add_f32 v[232:233], v[232:233], v[44:45]
	v_pk_add_f32 v[232:233], v[232:233], v[46:47]
	ds_read2_b32 v[32:33], v115 offset0:170 offset1:171
	ds_read2_b32 v[34:35], v115 offset0:172 offset1:173
	ds_read2_b32 v[36:37], v115 offset0:178 offset1:179
	ds_read2_b32 v[38:39], v115 offset0:180 offset1:181
	ds_read2_b32 v[40:41], v115 offset0:187 offset1:188
	ds_read2_b32 v[42:43], v115 offset0:189 offset1:190
	ds_read2_b32 v[44:45], v115 offset0:195 offset1:196
	ds_read2_b32 v[46:47], v115 offset0:197 offset1:198
	v_mfma_f32_32x32x16_bf16 v[0:15], v[64:67], v[72:75], v[0:15]
	v_mfma_f32_32x32x16_bf16 v[16:31], v[64:67], v[76:79], v[16:31]
	v_mfma_f32_32x32x16_bf16 v[0:15], v[68:71], v[220:223], v[0:15]
	v_mfma_f32_32x32x16_bf16 v[16:31], v[68:71], v[224:227], v[16:31]
	s_add_i32 s90, s76, 352
	v_add_u32_e32 v80, s90, v235
	v_add_u32_e32 v83, s90, v236
	v_add_u32_e32 v99, s90, v237
	v_add_u32_e32 v253, s90, v238
	v_add_u32_e32 v254, s90, v100
	v_add_u32_e32 v255, s90, v149
	v_med3_i32 v80, v80, 0, s99
	v_med3_i32 v83, v83, 0, s99
	v_med3_i32 v99, v99, 0, s99
	v_med3_i32 v253, v253, 0, s99
	v_med3_i32 v254, v254, 0, s99
	v_med3_i32 v255, v255, 0, s99
	v_mad_u32_u24 v80, v80, s100, v252
	v_mad_u32_u24 v83, v83, s100, v252
	v_mad_u32_u24 v99, v99, s100, v252
	v_mad_u32_u24 v253, v253, s100, v252
	v_mad_u32_u24 v254, v254, s100, v153
	v_mad_u32_u24 v255, v255, s100, v153
	global_load_dwordx4 v[156:159], v80, s[82:83]
	global_load_dwordx4 v[160:163], v83, s[82:83]
	global_load_dwordx4 v[164:167], v99, s[82:83]
	global_load_dwordx4 v[168:171], v253, s[82:83]
	global_load_dwordx4 v[172:175], v254, s[82:83] offset:768
	global_load_dwordx4 v[176:179], v255, s[82:83] offset:768
	global_load_dwordx4 v[180:183], v254, s[82:83] offset:832
	global_load_dwordx4 v[184:187], v255, s[82:83] offset:832
	ds_read_b64_tr_b16 v[72:73], v231
	ds_read_b64_tr_b16 v[74:75], v231 offset:512
	ds_read_b64_tr_b16 v[76:77], v231 offset:2048
	ds_read_b64_tr_b16 v[78:79], v231 offset:2560
	ds_read_b64_tr_b16 v[220:221], v231 offset:1024
	ds_read_b64_tr_b16 v[222:223], v231 offset:1536
	ds_read_b64_tr_b16 v[224:225], v231 offset:3072
	ds_read_b64_tr_b16 v[226:227], v231 offset:3584
	v_exp_f32_e32 v188, v188
	v_exp_f32_e32 v189, v189
	v_exp_f32_e32 v190, v190
	v_exp_f32_e32 v191, v191
	s_waitcnt vmcnt(8)
	ds_write_b128 v247, v[116:119]
	ds_write_b128 v247, v[120:123] offset:1024
	ds_write_b128 v247, v[124:127] offset:2048
	ds_write_b128 v247, v[128:131] offset:3072
	ds_read_b128 v[116:119], v248
	ds_read_b128 v[120:123], v249
	ds_read_b128 v[124:127], v250
	ds_read_b128 v[128:131], v251
	ds_write_b128 v112, v[132:135]
	ds_write_b128 v112, v[136:139] offset:1024
	ds_write_b128 v112, v[140:143] offset:2048
	ds_write_b128 v112, v[144:147] offset:3072
	v_exp_f32_e32 v192, v192
	v_exp_f32_e32 v193, v193
	v_exp_f32_e32 v194, v194
	v_exp_f32_e32 v195, v195
	s_waitcnt lgkmcnt(4)
	v_mfma_f32_32x32x16_bf16 v[32:47], v[116:119], v[48:51], v[32:47]
	v_exp_f32_e32 v196, v196
	v_exp_f32_e32 v197, v197
	v_mfma_f32_32x32x16_bf16 v[32:47], v[120:123], v[52:55], v[32:47]
	v_exp_f32_e32 v198, v198
	v_exp_f32_e32 v199, v199
	v_mfma_f32_32x32x16_bf16 v[32:47], v[124:127], v[56:59], v[32:47]
	v_exp_f32_e32 v200, v200
	v_exp_f32_e32 v201, v201
	v_mfma_f32_32x32x16_bf16 v[32:47], v[128:131], v[60:63], v[32:47]
	v_exp_f32_e32 v202, v202
	v_exp_f32_e32 v203, v203
	s_add_i32 s90, s76, 288
	v_add_u32_e32 v84, s90, v107
	v_add_u32_e32 v85, 0, v84
	v_add_u32_e32 v86, 1, v84
	v_add_u32_e32 v87, 2, v84
	v_add_u32_e32 v88, 3, v84
	v_cmp_gt_u32_e64 s[30:31], s98, v85
	v_cmp_gt_u32_e64 s[36:37], s98, v86
	v_cmp_gt_u32_e64 s[78:79], s98, v87
	v_cmp_gt_u32_e64 s[50:51], s98, v88
	v_cndmask_b32_e64 v188, 0, v188, s[30:31]
	v_add_u32_e32 v85, 8, v84
	v_cmp_gt_u32_e64 s[30:31], s98, v85
	v_cndmask_b32_e64 v189, 0, v189, s[36:37]
	v_add_u32_e32 v86, 9, v84
	v_cmp_gt_u32_e64 s[36:37], s98, v86
	v_cndmask_b32_e64 v190, 0, v190, s[78:79]
	v_add_u32_e32 v87, 10, v84
	v_cmp_gt_u32_e64 s[78:79], s98, v87
	v_cndmask_b32_e64 v191, 0, v191, s[50:51]
	v_add_u32_e32 v88, 11, v84
	v_cmp_gt_u32_e64 s[50:51], s98, v88
	v_cndmask_b32_e64 v192, 0, v192, s[30:31]
	v_add_u32_e32 v85, 16, v84
	v_cmp_gt_u32_e64 s[30:31], s98, v85
	v_cndmask_b32_e64 v193, 0, v193, s[36:37]
	v_add_u32_e32 v86, 17, v84
	v_cmp_gt_u32_e64 s[36:37], s98, v86
	v_cndmask_b32_e64 v194, 0, v194, s[78:79]
	v_add_u32_e32 v87, 18, v84
	v_cmp_gt_u32_e64 s[78:79], s98, v87
	v_cndmask_b32_e64 v195, 0, v195, s[50:51]
	v_add_u32_e32 v88, 19, v84
	v_cmp_gt_u32_e64 s[50:51], s98, v88
	v_cndmask_b32_e64 v196, 0, v196, s[30:31]
	v_add_u32_e32 v85, 24, v84
	v_cmp_gt_u32_e64 s[30:31], s98, v85
	v_cndmask_b32_e64 v197, 0, v197, s[36:37]
	v_add_u32_e32 v86, 25, v84
	v_cmp_gt_u32_e64 s[36:37], s98, v86
	v_cndmask_b32_e64 v198, 0, v198, s[78:79]
	v_add_u32_e32 v87, 26, v84
	v_cmp_gt_u32_e64 s[78:79], s98, v87
	v_cndmask_b32_e64 v199, 0, v199, s[50:51]
	v_add_u32_e32 v88, 27, v84
	v_cmp_gt_u32_e64 s[50:51], s98, v88
	v_nop
	v_cndmask_b32_e64 v200, 0, v200, s[30:31]
	v_cndmask_b32_e64 v201, 0, v201, s[36:37]
	v_cndmask_b32_e64 v202, 0, v202, s[78:79]
	v_cndmask_b32_e64 v203, 0, v203, s[50:51]
	v_cvt_pk_bf16_f32 v64, v188, v189
	v_cvt_pk_bf16_f32 v65, v190, v191
	v_cvt_pk_bf16_f32 v66, v192, v193
	v_cvt_pk_bf16_f32 v67, v194, v195
	v_cvt_pk_bf16_f32 v68, v196, v197
	v_cvt_pk_bf16_f32 v69, v198, v199
	v_cvt_pk_bf16_f32 v70, v200, v201
	v_cvt_pk_bf16_f32 v71, v202, v203
	v_pk_add_f32 v[232:233], v[232:233], v[188:189]
	v_pk_add_f32 v[232:233], v[232:233], v[190:191]
	v_pk_add_f32 v[232:233], v[232:233], v[192:193]
	v_pk_add_f32 v[232:233], v[232:233], v[194:195]
	v_pk_add_f32 v[232:233], v[232:233], v[196:197]
	v_pk_add_f32 v[232:233], v[232:233], v[198:199]
	v_pk_add_f32 v[232:233], v[232:233], v[200:201]
	v_pk_add_f32 v[232:233], v[232:233], v[202:203]
	ds_read2_b32 v[188:189], v115 offset0:204 offset1:205
	ds_read2_b32 v[190:191], v115 offset0:206 offset1:207
	ds_read2_b32 v[192:193], v115 offset0:212 offset1:213
	ds_read2_b32 v[194:195], v115 offset0:214 offset1:215
	ds_read2_b32 v[196:197], v115 offset0:221 offset1:222
	ds_read2_b32 v[198:199], v115 offset0:223 offset1:224
	ds_read2_b32 v[200:201], v115 offset0:229 offset1:230
	ds_read2_b32 v[202:203], v115 offset0:231 offset1:232
	v_mfma_f32_32x32x16_bf16 v[0:15], v[64:67], v[72:75], v[0:15]
	v_mfma_f32_32x32x16_bf16 v[16:31], v[64:67], v[76:79], v[16:31]
	v_mfma_f32_32x32x16_bf16 v[0:15], v[68:71], v[220:223], v[0:15]
	v_mfma_f32_32x32x16_bf16 v[16:31], v[68:71], v[224:227], v[16:31]
	s_add_i32 s90, s76, 384
	v_add_u32_e32 v80, s90, v235
	v_add_u32_e32 v83, s90, v236
	v_add_u32_e32 v99, s90, v237
	v_add_u32_e32 v253, s90, v238
	v_add_u32_e32 v254, s90, v100
	v_add_u32_e32 v255, s90, v149
	v_med3_i32 v80, v80, 0, s99
	v_med3_i32 v83, v83, 0, s99
	v_med3_i32 v99, v99, 0, s99
	v_med3_i32 v253, v253, 0, s99
	v_med3_i32 v254, v254, 0, s99
	v_med3_i32 v255, v255, 0, s99
	v_mad_u32_u24 v80, v80, s100, v252
	v_mad_u32_u24 v83, v83, s100, v252
	v_mad_u32_u24 v99, v99, s100, v252
	v_mad_u32_u24 v253, v253, s100, v252
	v_mad_u32_u24 v254, v254, s100, v153
	v_mad_u32_u24 v255, v255, s100, v153
	global_load_dwordx4 v[116:119], v80, s[82:83]
	global_load_dwordx4 v[120:123], v83, s[82:83]
	global_load_dwordx4 v[124:127], v99, s[82:83]
	global_load_dwordx4 v[128:131], v253, s[82:83]
	global_load_dwordx4 v[132:135], v254, s[82:83] offset:768
	global_load_dwordx4 v[136:139], v255, s[82:83] offset:768
	global_load_dwordx4 v[140:143], v254, s[82:83] offset:832
	global_load_dwordx4 v[144:147], v255, s[82:83] offset:832
	ds_read_b64_tr_b16 v[72:73], v231
	ds_read_b64_tr_b16 v[74:75], v231 offset:512
	ds_read_b64_tr_b16 v[76:77], v231 offset:2048
	ds_read_b64_tr_b16 v[78:79], v231 offset:2560
	ds_read_b64_tr_b16 v[220:221], v231 offset:1024
	ds_read_b64_tr_b16 v[222:223], v231 offset:1536
	ds_read_b64_tr_b16 v[224:225], v231 offset:3072
	ds_read_b64_tr_b16 v[226:227], v231 offset:3584
	v_exp_f32_e32 v32, v32
	v_exp_f32_e32 v33, v33
	v_exp_f32_e32 v34, v34
	v_exp_f32_e32 v35, v35
	s_waitcnt vmcnt(8)
	ds_write_b128 v247, v[156:159]
	ds_write_b128 v247, v[160:163] offset:1024
	ds_write_b128 v247, v[164:167] offset:2048
	ds_write_b128 v247, v[168:171] offset:3072
	ds_read_b128 v[156:159], v248
	ds_read_b128 v[160:163], v249
	ds_read_b128 v[164:167], v250
	ds_read_b128 v[168:171], v251
	ds_write_b128 v112, v[172:175]
	ds_write_b128 v112, v[176:179] offset:1024
	ds_write_b128 v112, v[180:183] offset:2048
	ds_write_b128 v112, v[184:187] offset:3072
	v_exp_f32_e32 v36, v36
	v_exp_f32_e32 v37, v37
	v_exp_f32_e32 v38, v38
	v_exp_f32_e32 v39, v39
	s_waitcnt lgkmcnt(4)
	v_mfma_f32_32x32x16_bf16 v[188:203], v[156:159], v[48:51], v[188:203]
	v_exp_f32_e32 v40, v40
	v_exp_f32_e32 v41, v41
	v_mfma_f32_32x32x16_bf16 v[188:203], v[160:163], v[52:55], v[188:203]
	v_exp_f32_e32 v42, v42
	v_exp_f32_e32 v43, v43
	v_mfma_f32_32x32x16_bf16 v[188:203], v[164:167], v[56:59], v[188:203]
	v_exp_f32_e32 v44, v44
	v_exp_f32_e32 v45, v45
	v_mfma_f32_32x32x16_bf16 v[188:203], v[168:171], v[60:63], v[188:203]
	v_exp_f32_e32 v46, v46
	v_exp_f32_e32 v47, v47
	s_add_i32 s90, s76, 320
	v_add_u32_e32 v84, s90, v107
	v_add_u32_e32 v85, 0, v84
	v_add_u32_e32 v86, 1, v84
	v_add_u32_e32 v87, 2, v84
	v_add_u32_e32 v88, 3, v84
	v_cmp_gt_u32_e64 s[30:31], s98, v85
	v_cmp_gt_u32_e64 s[36:37], s98, v86
	v_cmp_gt_u32_e64 s[78:79], s98, v87
	v_cmp_gt_u32_e64 s[50:51], s98, v88
	v_cndmask_b32_e64 v32, 0, v32, s[30:31]
	v_add_u32_e32 v85, 8, v84
	v_cmp_gt_u32_e64 s[30:31], s98, v85
	v_cndmask_b32_e64 v33, 0, v33, s[36:37]
	v_add_u32_e32 v86, 9, v84
	v_cmp_gt_u32_e64 s[36:37], s98, v86
	v_cndmask_b32_e64 v34, 0, v34, s[78:79]
	v_add_u32_e32 v87, 10, v84
	v_cmp_gt_u32_e64 s[78:79], s98, v87
	v_cndmask_b32_e64 v35, 0, v35, s[50:51]
	v_add_u32_e32 v88, 11, v84
	v_cmp_gt_u32_e64 s[50:51], s98, v88
	v_cndmask_b32_e64 v36, 0, v36, s[30:31]
	v_add_u32_e32 v85, 16, v84
	v_cmp_gt_u32_e64 s[30:31], s98, v85
	v_cndmask_b32_e64 v37, 0, v37, s[36:37]
	v_add_u32_e32 v86, 17, v84
	v_cmp_gt_u32_e64 s[36:37], s98, v86
	v_cndmask_b32_e64 v38, 0, v38, s[78:79]
	v_add_u32_e32 v87, 18, v84
	v_cmp_gt_u32_e64 s[78:79], s98, v87
	v_cndmask_b32_e64 v39, 0, v39, s[50:51]
	v_add_u32_e32 v88, 19, v84
	v_cmp_gt_u32_e64 s[50:51], s98, v88
	v_cndmask_b32_e64 v40, 0, v40, s[30:31]
	v_add_u32_e32 v85, 24, v84
	v_cmp_gt_u32_e64 s[30:31], s98, v85
	v_cndmask_b32_e64 v41, 0, v41, s[36:37]
	v_add_u32_e32 v86, 25, v84
	v_cmp_gt_u32_e64 s[36:37], s98, v86
	v_cndmask_b32_e64 v42, 0, v42, s[78:79]
	v_add_u32_e32 v87, 26, v84
	v_cmp_gt_u32_e64 s[78:79], s98, v87
	v_cndmask_b32_e64 v43, 0, v43, s[50:51]
	v_add_u32_e32 v88, 27, v84
	v_cmp_gt_u32_e64 s[50:51], s98, v88
	v_nop
	v_cndmask_b32_e64 v44, 0, v44, s[30:31]
	v_cndmask_b32_e64 v45, 0, v45, s[36:37]
	v_cndmask_b32_e64 v46, 0, v46, s[78:79]
	v_cndmask_b32_e64 v47, 0, v47, s[50:51]
	v_cvt_pk_bf16_f32 v64, v32, v33
	v_cvt_pk_bf16_f32 v65, v34, v35
	v_cvt_pk_bf16_f32 v66, v36, v37
	v_cvt_pk_bf16_f32 v67, v38, v39
	v_cvt_pk_bf16_f32 v68, v40, v41
	v_cvt_pk_bf16_f32 v69, v42, v43
	v_cvt_pk_bf16_f32 v70, v44, v45
	v_cvt_pk_bf16_f32 v71, v46, v47
	v_pk_add_f32 v[232:233], v[232:233], v[32:33]
	v_pk_add_f32 v[232:233], v[232:233], v[34:35]
	v_pk_add_f32 v[232:233], v[232:233], v[36:37]
	v_pk_add_f32 v[232:233], v[232:233], v[38:39]
	v_pk_add_f32 v[232:233], v[232:233], v[40:41]
	v_pk_add_f32 v[232:233], v[232:233], v[42:43]
	v_pk_add_f32 v[232:233], v[232:233], v[44:45]
	v_pk_add_f32 v[232:233], v[232:233], v[46:47]
	v_add_u32_e32 v115, 952, v115
	ds_read2_b32 v[32:33], v115 offset0:0 offset1:1
	ds_read2_b32 v[34:35], v115 offset0:2 offset1:3
	ds_read2_b32 v[36:37], v115 offset0:8 offset1:9
	ds_read2_b32 v[38:39], v115 offset0:10 offset1:11
	ds_read2_b32 v[40:41], v115 offset0:17 offset1:18
	ds_read2_b32 v[42:43], v115 offset0:19 offset1:20
	ds_read2_b32 v[44:45], v115 offset0:25 offset1:26
	ds_read2_b32 v[46:47], v115 offset0:27 offset1:28
	v_mfma_f32_32x32x16_bf16 v[0:15], v[64:67], v[72:75], v[0:15]
	v_mfma_f32_32x32x16_bf16 v[16:31], v[64:67], v[76:79], v[16:31]
	v_mfma_f32_32x32x16_bf16 v[0:15], v[68:71], v[220:223], v[0:15]
	v_mfma_f32_32x32x16_bf16 v[16:31], v[68:71], v[224:227], v[16:31]
	s_add_i32 s90, s76, 416
	v_add_u32_e32 v80, s90, v235
	v_add_u32_e32 v83, s90, v236
	v_add_u32_e32 v99, s90, v237
	v_add_u32_e32 v253, s90, v238
	v_add_u32_e32 v254, s90, v100
	v_add_u32_e32 v255, s90, v149
	v_med3_i32 v80, v80, 0, s99
	v_med3_i32 v83, v83, 0, s99
	v_med3_i32 v99, v99, 0, s99
	v_med3_i32 v253, v253, 0, s99
	v_med3_i32 v254, v254, 0, s99
	v_med3_i32 v255, v255, 0, s99
	v_mad_u32_u24 v80, v80, s100, v252
	v_mad_u32_u24 v83, v83, s100, v252
	v_mad_u32_u24 v99, v99, s100, v252
	v_mad_u32_u24 v253, v253, s100, v252
	v_mad_u32_u24 v254, v254, s100, v153
	v_mad_u32_u24 v255, v255, s100, v153
	global_load_dwordx4 v[156:159], v80, s[82:83]
	global_load_dwordx4 v[160:163], v83, s[82:83]
	global_load_dwordx4 v[164:167], v99, s[82:83]
	global_load_dwordx4 v[168:171], v253, s[82:83]
	global_load_dwordx4 v[172:175], v254, s[82:83] offset:768
	global_load_dwordx4 v[176:179], v255, s[82:83] offset:768
	global_load_dwordx4 v[180:183], v254, s[82:83] offset:832
	global_load_dwordx4 v[184:187], v255, s[82:83] offset:832
	ds_read_b64_tr_b16 v[72:73], v231
	ds_read_b64_tr_b16 v[74:75], v231 offset:512
	ds_read_b64_tr_b16 v[76:77], v231 offset:2048
	ds_read_b64_tr_b16 v[78:79], v231 offset:2560
	ds_read_b64_tr_b16 v[220:221], v231 offset:1024
	ds_read_b64_tr_b16 v[222:223], v231 offset:1536
	ds_read_b64_tr_b16 v[224:225], v231 offset:3072
	ds_read_b64_tr_b16 v[226:227], v231 offset:3584
	v_exp_f32_e32 v188, v188
	v_exp_f32_e32 v189, v189
	v_exp_f32_e32 v190, v190
	v_exp_f32_e32 v191, v191
	s_waitcnt vmcnt(8)
	ds_write_b128 v247, v[116:119]
	ds_write_b128 v247, v[120:123] offset:1024
	ds_write_b128 v247, v[124:127] offset:2048
	ds_write_b128 v247, v[128:131] offset:3072
	ds_read_b128 v[116:119], v248
	ds_read_b128 v[120:123], v249
	ds_read_b128 v[124:127], v250
	ds_read_b128 v[128:131], v251
	ds_write_b128 v112, v[132:135]
	ds_write_b128 v112, v[136:139] offset:1024
	ds_write_b128 v112, v[140:143] offset:2048
	ds_write_b128 v112, v[144:147] offset:3072
	v_exp_f32_e32 v192, v192
	v_exp_f32_e32 v193, v193
	v_exp_f32_e32 v194, v194
	v_exp_f32_e32 v195, v195
	s_waitcnt lgkmcnt(4)
	v_mfma_f32_32x32x16_bf16 v[32:47], v[116:119], v[48:51], v[32:47]
	v_exp_f32_e32 v196, v196
	v_exp_f32_e32 v197, v197
	v_mfma_f32_32x32x16_bf16 v[32:47], v[120:123], v[52:55], v[32:47]
	v_exp_f32_e32 v198, v198
	v_exp_f32_e32 v199, v199
	v_mfma_f32_32x32x16_bf16 v[32:47], v[124:127], v[56:59], v[32:47]
	v_exp_f32_e32 v200, v200
	v_exp_f32_e32 v201, v201
	v_mfma_f32_32x32x16_bf16 v[32:47], v[128:131], v[60:63], v[32:47]
	v_exp_f32_e32 v202, v202
	v_exp_f32_e32 v203, v203
	s_add_i32 s90, s76, 352
	v_add_u32_e32 v84, s90, v107
	v_add_u32_e32 v85, 0, v84
	v_add_u32_e32 v86, 1, v84
	v_add_u32_e32 v87, 2, v84
	v_add_u32_e32 v88, 3, v84
	v_cmp_gt_u32_e64 s[30:31], s98, v85
	v_cmp_gt_u32_e64 s[36:37], s98, v86
	v_cmp_gt_u32_e64 s[78:79], s98, v87
	v_cmp_gt_u32_e64 s[50:51], s98, v88
	v_cndmask_b32_e64 v188, 0, v188, s[30:31]
	v_add_u32_e32 v85, 8, v84
	v_cmp_gt_u32_e64 s[30:31], s98, v85
	v_cndmask_b32_e64 v189, 0, v189, s[36:37]
	v_add_u32_e32 v86, 9, v84
	v_cmp_gt_u32_e64 s[36:37], s98, v86
	v_cndmask_b32_e64 v190, 0, v190, s[78:79]
	v_add_u32_e32 v87, 10, v84
	v_cmp_gt_u32_e64 s[78:79], s98, v87
	v_cndmask_b32_e64 v191, 0, v191, s[50:51]
	v_add_u32_e32 v88, 11, v84
	v_cmp_gt_u32_e64 s[50:51], s98, v88
	v_cndmask_b32_e64 v192, 0, v192, s[30:31]
	v_add_u32_e32 v85, 16, v84
	v_cmp_gt_u32_e64 s[30:31], s98, v85
	v_cndmask_b32_e64 v193, 0, v193, s[36:37]
	v_add_u32_e32 v86, 17, v84
	v_cmp_gt_u32_e64 s[36:37], s98, v86
	v_cndmask_b32_e64 v194, 0, v194, s[78:79]
	v_add_u32_e32 v87, 18, v84
	v_cmp_gt_u32_e64 s[78:79], s98, v87
	v_cndmask_b32_e64 v195, 0, v195, s[50:51]
	v_add_u32_e32 v88, 19, v84
	v_cmp_gt_u32_e64 s[50:51], s98, v88
	v_cndmask_b32_e64 v196, 0, v196, s[30:31]
	v_add_u32_e32 v85, 24, v84
	v_cmp_gt_u32_e64 s[30:31], s98, v85
	v_cndmask_b32_e64 v197, 0, v197, s[36:37]
	v_add_u32_e32 v86, 25, v84
	v_cmp_gt_u32_e64 s[36:37], s98, v86
	v_cndmask_b32_e64 v198, 0, v198, s[78:79]
	v_add_u32_e32 v87, 26, v84
	v_cmp_gt_u32_e64 s[78:79], s98, v87
	v_cndmask_b32_e64 v199, 0, v199, s[50:51]
	v_add_u32_e32 v88, 27, v84
	v_cmp_gt_u32_e64 s[50:51], s98, v88
	v_nop
	v_cndmask_b32_e64 v200, 0, v200, s[30:31]
	v_cndmask_b32_e64 v201, 0, v201, s[36:37]
	v_cndmask_b32_e64 v202, 0, v202, s[78:79]
	v_cndmask_b32_e64 v203, 0, v203, s[50:51]
	v_cvt_pk_bf16_f32 v64, v188, v189
	v_cvt_pk_bf16_f32 v65, v190, v191
	v_cvt_pk_bf16_f32 v66, v192, v193
	v_cvt_pk_bf16_f32 v67, v194, v195
	v_cvt_pk_bf16_f32 v68, v196, v197
	v_cvt_pk_bf16_f32 v69, v198, v199
	v_cvt_pk_bf16_f32 v70, v200, v201
	v_cvt_pk_bf16_f32 v71, v202, v203
	v_pk_add_f32 v[232:233], v[232:233], v[188:189]
	v_pk_add_f32 v[232:233], v[232:233], v[190:191]
	v_pk_add_f32 v[232:233], v[232:233], v[192:193]
	v_pk_add_f32 v[232:233], v[232:233], v[194:195]
	v_pk_add_f32 v[232:233], v[232:233], v[196:197]
	v_pk_add_f32 v[232:233], v[232:233], v[198:199]
	v_pk_add_f32 v[232:233], v[232:233], v[200:201]
	v_pk_add_f32 v[232:233], v[232:233], v[202:203]
	ds_read2_b32 v[188:189], v115 offset0:34 offset1:35
	ds_read2_b32 v[190:191], v115 offset0:36 offset1:37
	ds_read2_b32 v[192:193], v115 offset0:42 offset1:43
	ds_read2_b32 v[194:195], v115 offset0:44 offset1:45
	ds_read2_b32 v[196:197], v115 offset0:51 offset1:52
	ds_read2_b32 v[198:199], v115 offset0:53 offset1:54
	ds_read2_b32 v[200:201], v115 offset0:59 offset1:60
	ds_read2_b32 v[202:203], v115 offset0:61 offset1:62
	v_mfma_f32_32x32x16_bf16 v[0:15], v[64:67], v[72:75], v[0:15]
	v_mfma_f32_32x32x16_bf16 v[16:31], v[64:67], v[76:79], v[16:31]
	v_mfma_f32_32x32x16_bf16 v[0:15], v[68:71], v[220:223], v[0:15]
	v_mfma_f32_32x32x16_bf16 v[16:31], v[68:71], v[224:227], v[16:31]
	s_add_i32 s90, s76, 448
	v_add_u32_e32 v80, s90, v235
	v_add_u32_e32 v83, s90, v236
	v_add_u32_e32 v99, s90, v237
	v_add_u32_e32 v253, s90, v238
	v_add_u32_e32 v254, s90, v100
	v_add_u32_e32 v255, s90, v149
	v_med3_i32 v80, v80, 0, s99
	v_med3_i32 v83, v83, 0, s99
	v_med3_i32 v99, v99, 0, s99
	v_med3_i32 v253, v253, 0, s99
	v_med3_i32 v254, v254, 0, s99
	v_med3_i32 v255, v255, 0, s99
	v_mad_u32_u24 v80, v80, s100, v252
	v_mad_u32_u24 v83, v83, s100, v252
	v_mad_u32_u24 v99, v99, s100, v252
	v_mad_u32_u24 v253, v253, s100, v252
	v_mad_u32_u24 v254, v254, s100, v153
	v_mad_u32_u24 v255, v255, s100, v153
	global_load_dwordx4 v[116:119], v80, s[82:83]
	global_load_dwordx4 v[120:123], v83, s[82:83]
	global_load_dwordx4 v[124:127], v99, s[82:83]
	global_load_dwordx4 v[128:131], v253, s[82:83]
	global_load_dwordx4 v[132:135], v254, s[82:83] offset:768
	global_load_dwordx4 v[136:139], v255, s[82:83] offset:768
	global_load_dwordx4 v[140:143], v254, s[82:83] offset:832
	global_load_dwordx4 v[144:147], v255, s[82:83] offset:832
	ds_read_b64_tr_b16 v[72:73], v231
	ds_read_b64_tr_b16 v[74:75], v231 offset:512
	ds_read_b64_tr_b16 v[76:77], v231 offset:2048
	ds_read_b64_tr_b16 v[78:79], v231 offset:2560
	ds_read_b64_tr_b16 v[220:221], v231 offset:1024
	ds_read_b64_tr_b16 v[222:223], v231 offset:1536
	ds_read_b64_tr_b16 v[224:225], v231 offset:3072
	ds_read_b64_tr_b16 v[226:227], v231 offset:3584
	v_exp_f32_e32 v32, v32
	v_exp_f32_e32 v33, v33
	v_exp_f32_e32 v34, v34
	v_exp_f32_e32 v35, v35
	s_waitcnt vmcnt(8)
	ds_write_b128 v247, v[156:159]
	ds_write_b128 v247, v[160:163] offset:1024
	ds_write_b128 v247, v[164:167] offset:2048
	ds_write_b128 v247, v[168:171] offset:3072
	ds_read_b128 v[156:159], v248
	ds_read_b128 v[160:163], v249
	ds_read_b128 v[164:167], v250
	ds_read_b128 v[168:171], v251
	ds_write_b128 v112, v[172:175]
	ds_write_b128 v112, v[176:179] offset:1024
	ds_write_b128 v112, v[180:183] offset:2048
	ds_write_b128 v112, v[184:187] offset:3072
	v_exp_f32_e32 v36, v36
	v_exp_f32_e32 v37, v37
	v_exp_f32_e32 v38, v38
	v_exp_f32_e32 v39, v39
	s_waitcnt lgkmcnt(4)
	v_mfma_f32_32x32x16_bf16 v[188:203], v[156:159], v[48:51], v[188:203]
	v_exp_f32_e32 v40, v40
	v_exp_f32_e32 v41, v41
	v_mfma_f32_32x32x16_bf16 v[188:203], v[160:163], v[52:55], v[188:203]
	v_exp_f32_e32 v42, v42
	v_exp_f32_e32 v43, v43
	v_mfma_f32_32x32x16_bf16 v[188:203], v[164:167], v[56:59], v[188:203]
	v_exp_f32_e32 v44, v44
	v_exp_f32_e32 v45, v45
	v_mfma_f32_32x32x16_bf16 v[188:203], v[168:171], v[60:63], v[188:203]
	v_exp_f32_e32 v46, v46
	v_exp_f32_e32 v47, v47
	s_add_i32 s90, s76, 384
	v_add_u32_e32 v84, s90, v107
	v_add_u32_e32 v85, 0, v84
	v_add_u32_e32 v86, 1, v84
	v_add_u32_e32 v87, 2, v84
	v_add_u32_e32 v88, 3, v84
	v_cmp_gt_u32_e64 s[30:31], s98, v85
	v_cmp_gt_u32_e64 s[36:37], s98, v86
	v_cmp_gt_u32_e64 s[78:79], s98, v87
	v_cmp_gt_u32_e64 s[50:51], s98, v88
	v_cndmask_b32_e64 v32, 0, v32, s[30:31]
	v_add_u32_e32 v85, 8, v84
	v_cmp_gt_u32_e64 s[30:31], s98, v85
	v_cndmask_b32_e64 v33, 0, v33, s[36:37]
	v_add_u32_e32 v86, 9, v84
	v_cmp_gt_u32_e64 s[36:37], s98, v86
	v_cndmask_b32_e64 v34, 0, v34, s[78:79]
	v_add_u32_e32 v87, 10, v84
	v_cmp_gt_u32_e64 s[78:79], s98, v87
	v_cndmask_b32_e64 v35, 0, v35, s[50:51]
	v_add_u32_e32 v88, 11, v84
	v_cmp_gt_u32_e64 s[50:51], s98, v88
	v_cndmask_b32_e64 v36, 0, v36, s[30:31]
	v_add_u32_e32 v85, 16, v84
	v_cmp_gt_u32_e64 s[30:31], s98, v85
	v_cndmask_b32_e64 v37, 0, v37, s[36:37]
	v_add_u32_e32 v86, 17, v84
	v_cmp_gt_u32_e64 s[36:37], s98, v86
	v_cndmask_b32_e64 v38, 0, v38, s[78:79]
	v_add_u32_e32 v87, 18, v84
	v_cmp_gt_u32_e64 s[78:79], s98, v87
	v_cndmask_b32_e64 v39, 0, v39, s[50:51]
	v_add_u32_e32 v88, 19, v84
	v_cmp_gt_u32_e64 s[50:51], s98, v88
	v_cndmask_b32_e64 v40, 0, v40, s[30:31]
	v_add_u32_e32 v85, 24, v84
	v_cmp_gt_u32_e64 s[30:31], s98, v85
	v_cndmask_b32_e64 v41, 0, v41, s[36:37]
	v_add_u32_e32 v86, 25, v84
	v_cmp_gt_u32_e64 s[36:37], s98, v86
	v_cndmask_b32_e64 v42, 0, v42, s[78:79]
	v_add_u32_e32 v87, 26, v84
	v_cmp_gt_u32_e64 s[78:79], s98, v87
	v_cndmask_b32_e64 v43, 0, v43, s[50:51]
	v_add_u32_e32 v88, 27, v84
	v_cmp_gt_u32_e64 s[50:51], s98, v88
	v_nop
	v_cndmask_b32_e64 v44, 0, v44, s[30:31]
	v_cndmask_b32_e64 v45, 0, v45, s[36:37]
	v_cndmask_b32_e64 v46, 0, v46, s[78:79]
	v_cndmask_b32_e64 v47, 0, v47, s[50:51]
	v_cvt_pk_bf16_f32 v64, v32, v33
	v_cvt_pk_bf16_f32 v65, v34, v35
	v_cvt_pk_bf16_f32 v66, v36, v37
	v_cvt_pk_bf16_f32 v67, v38, v39
	v_cvt_pk_bf16_f32 v68, v40, v41
	v_cvt_pk_bf16_f32 v69, v42, v43
	v_cvt_pk_bf16_f32 v70, v44, v45
	v_cvt_pk_bf16_f32 v71, v46, v47
	v_pk_add_f32 v[232:233], v[232:233], v[32:33]
	v_pk_add_f32 v[232:233], v[232:233], v[34:35]
	v_pk_add_f32 v[232:233], v[232:233], v[36:37]
	v_pk_add_f32 v[232:233], v[232:233], v[38:39]
	v_pk_add_f32 v[232:233], v[232:233], v[40:41]
	v_pk_add_f32 v[232:233], v[232:233], v[42:43]
	v_pk_add_f32 v[232:233], v[232:233], v[44:45]
	v_pk_add_f32 v[232:233], v[232:233], v[46:47]
	ds_read2_b32 v[32:33], v115 offset0:68 offset1:69
	ds_read2_b32 v[34:35], v115 offset0:70 offset1:71
	ds_read2_b32 v[36:37], v115 offset0:76 offset1:77
	ds_read2_b32 v[38:39], v115 offset0:78 offset1:79
	ds_read2_b32 v[40:41], v115 offset0:85 offset1:86
	ds_read2_b32 v[42:43], v115 offset0:87 offset1:88
	ds_read2_b32 v[44:45], v115 offset0:93 offset1:94
	ds_read2_b32 v[46:47], v115 offset0:95 offset1:96
	v_mfma_f32_32x32x16_bf16 v[0:15], v[64:67], v[72:75], v[0:15]
	v_mfma_f32_32x32x16_bf16 v[16:31], v[64:67], v[76:79], v[16:31]
	v_mfma_f32_32x32x16_bf16 v[0:15], v[68:71], v[220:223], v[0:15]
	v_mfma_f32_32x32x16_bf16 v[16:31], v[68:71], v[224:227], v[16:31]
	s_add_i32 s90, s76, 480
	v_add_u32_e32 v80, s90, v235
	v_add_u32_e32 v83, s90, v236
	v_add_u32_e32 v99, s90, v237
	v_add_u32_e32 v253, s90, v238
	v_add_u32_e32 v254, s90, v100
	v_add_u32_e32 v255, s90, v149
	v_med3_i32 v80, v80, 0, s99
	v_med3_i32 v83, v83, 0, s99
	v_med3_i32 v99, v99, 0, s99
	v_med3_i32 v253, v253, 0, s99
	v_med3_i32 v254, v254, 0, s99
	v_med3_i32 v255, v255, 0, s99
	v_mad_u32_u24 v80, v80, s100, v252
	v_mad_u32_u24 v83, v83, s100, v252
	v_mad_u32_u24 v99, v99, s100, v252
	v_mad_u32_u24 v253, v253, s100, v252
	v_mad_u32_u24 v254, v254, s100, v153
	v_mad_u32_u24 v255, v255, s100, v153
	global_load_dwordx4 v[156:159], v80, s[82:83]
	global_load_dwordx4 v[160:163], v83, s[82:83]
	global_load_dwordx4 v[164:167], v99, s[82:83]
	global_load_dwordx4 v[168:171], v253, s[82:83]
	global_load_dwordx4 v[172:175], v254, s[82:83] offset:768
	global_load_dwordx4 v[176:179], v255, s[82:83] offset:768
	global_load_dwordx4 v[180:183], v254, s[82:83] offset:832
	global_load_dwordx4 v[184:187], v255, s[82:83] offset:832
	ds_read_b64_tr_b16 v[72:73], v231
	ds_read_b64_tr_b16 v[74:75], v231 offset:512
	ds_read_b64_tr_b16 v[76:77], v231 offset:2048
	ds_read_b64_tr_b16 v[78:79], v231 offset:2560
	ds_read_b64_tr_b16 v[220:221], v231 offset:1024
	ds_read_b64_tr_b16 v[222:223], v231 offset:1536
	ds_read_b64_tr_b16 v[224:225], v231 offset:3072
	ds_read_b64_tr_b16 v[226:227], v231 offset:3584
	v_exp_f32_e32 v188, v188
	v_exp_f32_e32 v189, v189
	v_exp_f32_e32 v190, v190
	v_exp_f32_e32 v191, v191
	s_waitcnt vmcnt(8)
	ds_write_b128 v247, v[116:119]
	ds_write_b128 v247, v[120:123] offset:1024
	ds_write_b128 v247, v[124:127] offset:2048
	ds_write_b128 v247, v[128:131] offset:3072
	ds_read_b128 v[116:119], v248
	ds_read_b128 v[120:123], v249
	ds_read_b128 v[124:127], v250
	ds_read_b128 v[128:131], v251
	ds_write_b128 v112, v[132:135]
	ds_write_b128 v112, v[136:139] offset:1024
	ds_write_b128 v112, v[140:143] offset:2048
	ds_write_b128 v112, v[144:147] offset:3072
	v_exp_f32_e32 v192, v192
	v_exp_f32_e32 v193, v193
	v_exp_f32_e32 v194, v194
	v_exp_f32_e32 v195, v195
	s_waitcnt lgkmcnt(4)
	v_mfma_f32_32x32x16_bf16 v[32:47], v[116:119], v[48:51], v[32:47]
	v_exp_f32_e32 v196, v196
	v_exp_f32_e32 v197, v197
	v_mfma_f32_32x32x16_bf16 v[32:47], v[120:123], v[52:55], v[32:47]
	v_exp_f32_e32 v198, v198
	v_exp_f32_e32 v199, v199
	v_mfma_f32_32x32x16_bf16 v[32:47], v[124:127], v[56:59], v[32:47]
	v_exp_f32_e32 v200, v200
	v_exp_f32_e32 v201, v201
	v_mfma_f32_32x32x16_bf16 v[32:47], v[128:131], v[60:63], v[32:47]
	v_exp_f32_e32 v202, v202
	v_exp_f32_e32 v203, v203
	s_add_i32 s90, s76, 416
	v_add_u32_e32 v84, s90, v107
	v_add_u32_e32 v85, 0, v84
	v_add_u32_e32 v86, 1, v84
	v_add_u32_e32 v87, 2, v84
	v_add_u32_e32 v88, 3, v84
	v_cmp_gt_u32_e64 s[30:31], s98, v85
	v_cmp_gt_u32_e64 s[36:37], s98, v86
	v_cmp_gt_u32_e64 s[78:79], s98, v87
	v_cmp_gt_u32_e64 s[50:51], s98, v88
	v_cndmask_b32_e64 v188, 0, v188, s[30:31]
	v_add_u32_e32 v85, 8, v84
	v_cmp_gt_u32_e64 s[30:31], s98, v85
	v_cndmask_b32_e64 v189, 0, v189, s[36:37]
	v_add_u32_e32 v86, 9, v84
	v_cmp_gt_u32_e64 s[36:37], s98, v86
	v_cndmask_b32_e64 v190, 0, v190, s[78:79]
	v_add_u32_e32 v87, 10, v84
	v_cmp_gt_u32_e64 s[78:79], s98, v87
	v_cndmask_b32_e64 v191, 0, v191, s[50:51]
	v_add_u32_e32 v88, 11, v84
	v_cmp_gt_u32_e64 s[50:51], s98, v88
	v_cndmask_b32_e64 v192, 0, v192, s[30:31]
	v_add_u32_e32 v85, 16, v84
	v_cmp_gt_u32_e64 s[30:31], s98, v85
	v_cndmask_b32_e64 v193, 0, v193, s[36:37]
	v_add_u32_e32 v86, 17, v84
	v_cmp_gt_u32_e64 s[36:37], s98, v86
	v_cndmask_b32_e64 v194, 0, v194, s[78:79]
	v_add_u32_e32 v87, 18, v84
	v_cmp_gt_u32_e64 s[78:79], s98, v87
	v_cndmask_b32_e64 v195, 0, v195, s[50:51]
	v_add_u32_e32 v88, 19, v84
	v_cmp_gt_u32_e64 s[50:51], s98, v88
	v_cndmask_b32_e64 v196, 0, v196, s[30:31]
	v_add_u32_e32 v85, 24, v84
	v_cmp_gt_u32_e64 s[30:31], s98, v85
	v_cndmask_b32_e64 v197, 0, v197, s[36:37]
	v_add_u32_e32 v86, 25, v84
	v_cmp_gt_u32_e64 s[36:37], s98, v86
	v_cndmask_b32_e64 v198, 0, v198, s[78:79]
	v_add_u32_e32 v87, 26, v84
	v_cmp_gt_u32_e64 s[78:79], s98, v87
	v_cndmask_b32_e64 v199, 0, v199, s[50:51]
	v_add_u32_e32 v88, 27, v84
	v_cmp_gt_u32_e64 s[50:51], s98, v88
	v_nop
	v_cndmask_b32_e64 v200, 0, v200, s[30:31]
	v_cndmask_b32_e64 v201, 0, v201, s[36:37]
	v_cndmask_b32_e64 v202, 0, v202, s[78:79]
	v_cndmask_b32_e64 v203, 0, v203, s[50:51]
	v_cvt_pk_bf16_f32 v64, v188, v189
	v_cvt_pk_bf16_f32 v65, v190, v191
	v_cvt_pk_bf16_f32 v66, v192, v193
	v_cvt_pk_bf16_f32 v67, v194, v195
	v_cvt_pk_bf16_f32 v68, v196, v197
	v_cvt_pk_bf16_f32 v69, v198, v199
	v_cvt_pk_bf16_f32 v70, v200, v201
	v_cvt_pk_bf16_f32 v71, v202, v203
	v_pk_add_f32 v[232:233], v[232:233], v[188:189]
	v_pk_add_f32 v[232:233], v[232:233], v[190:191]
	v_pk_add_f32 v[232:233], v[232:233], v[192:193]
	v_pk_add_f32 v[232:233], v[232:233], v[194:195]
	v_pk_add_f32 v[232:233], v[232:233], v[196:197]
	v_pk_add_f32 v[232:233], v[232:233], v[198:199]
	v_pk_add_f32 v[232:233], v[232:233], v[200:201]
	v_pk_add_f32 v[232:233], v[232:233], v[202:203]
	ds_read2_b32 v[188:189], v115 offset0:102 offset1:103
	ds_read2_b32 v[190:191], v115 offset0:104 offset1:105
	ds_read2_b32 v[192:193], v115 offset0:110 offset1:111
	ds_read2_b32 v[194:195], v115 offset0:112 offset1:113
	ds_read2_b32 v[196:197], v115 offset0:119 offset1:120
	ds_read2_b32 v[198:199], v115 offset0:121 offset1:122
	ds_read2_b32 v[200:201], v115 offset0:127 offset1:128
	ds_read2_b32 v[202:203], v115 offset0:129 offset1:130
	v_mfma_f32_32x32x16_bf16 v[0:15], v[64:67], v[72:75], v[0:15]
	v_mfma_f32_32x32x16_bf16 v[16:31], v[64:67], v[76:79], v[16:31]
	v_mfma_f32_32x32x16_bf16 v[0:15], v[68:71], v[220:223], v[0:15]
	v_mfma_f32_32x32x16_bf16 v[16:31], v[68:71], v[224:227], v[16:31]
	s_add_i32 s90, s76, 512
	v_add_u32_e32 v80, s90, v235
	v_add_u32_e32 v83, s90, v236
	v_add_u32_e32 v99, s90, v237
	v_add_u32_e32 v253, s90, v238
	v_add_u32_e32 v254, s90, v100
	v_add_u32_e32 v255, s90, v149
	v_med3_i32 v80, v80, 0, s99
	v_med3_i32 v83, v83, 0, s99
	v_med3_i32 v99, v99, 0, s99
	v_med3_i32 v253, v253, 0, s99
	v_med3_i32 v254, v254, 0, s99
	v_med3_i32 v255, v255, 0, s99
	v_mad_u32_u24 v80, v80, s100, v252
	v_mad_u32_u24 v83, v83, s100, v252
	v_mad_u32_u24 v99, v99, s100, v252
	v_mad_u32_u24 v253, v253, s100, v252
	v_mad_u32_u24 v254, v254, s100, v153
	v_mad_u32_u24 v255, v255, s100, v153
	global_load_dwordx4 v[116:119], v80, s[82:83]
	global_load_dwordx4 v[120:123], v83, s[82:83]
	global_load_dwordx4 v[124:127], v99, s[82:83]
	global_load_dwordx4 v[128:131], v253, s[82:83]
	global_load_dwordx4 v[132:135], v254, s[82:83] offset:768
	global_load_dwordx4 v[136:139], v255, s[82:83] offset:768
	global_load_dwordx4 v[140:143], v254, s[82:83] offset:832
	global_load_dwordx4 v[144:147], v255, s[82:83] offset:832
	ds_read_b64_tr_b16 v[72:73], v231
	ds_read_b64_tr_b16 v[74:75], v231 offset:512
	ds_read_b64_tr_b16 v[76:77], v231 offset:2048
	ds_read_b64_tr_b16 v[78:79], v231 offset:2560
	ds_read_b64_tr_b16 v[220:221], v231 offset:1024
	ds_read_b64_tr_b16 v[222:223], v231 offset:1536
	ds_read_b64_tr_b16 v[224:225], v231 offset:3072
	ds_read_b64_tr_b16 v[226:227], v231 offset:3584
	v_exp_f32_e32 v32, v32
	v_exp_f32_e32 v33, v33
	v_exp_f32_e32 v34, v34
	v_exp_f32_e32 v35, v35
	s_waitcnt vmcnt(8)
	ds_write_b128 v247, v[156:159]
	ds_write_b128 v247, v[160:163] offset:1024
	ds_write_b128 v247, v[164:167] offset:2048
	ds_write_b128 v247, v[168:171] offset:3072
	ds_read_b128 v[156:159], v248
	ds_read_b128 v[160:163], v249
	ds_read_b128 v[164:167], v250
	ds_read_b128 v[168:171], v251
	ds_write_b128 v112, v[172:175]
	ds_write_b128 v112, v[176:179] offset:1024
	ds_write_b128 v112, v[180:183] offset:2048
	ds_write_b128 v112, v[184:187] offset:3072
	v_exp_f32_e32 v36, v36
	v_exp_f32_e32 v37, v37
	v_exp_f32_e32 v38, v38
	v_exp_f32_e32 v39, v39
	s_waitcnt lgkmcnt(4)
	v_mfma_f32_32x32x16_bf16 v[188:203], v[156:159], v[48:51], v[188:203]
	v_exp_f32_e32 v40, v40
	v_exp_f32_e32 v41, v41
	v_mfma_f32_32x32x16_bf16 v[188:203], v[160:163], v[52:55], v[188:203]
	v_exp_f32_e32 v42, v42
	v_exp_f32_e32 v43, v43
	v_mfma_f32_32x32x16_bf16 v[188:203], v[164:167], v[56:59], v[188:203]
	v_exp_f32_e32 v44, v44
	v_exp_f32_e32 v45, v45
	v_mfma_f32_32x32x16_bf16 v[188:203], v[168:171], v[60:63], v[188:203]
	v_exp_f32_e32 v46, v46
	v_exp_f32_e32 v47, v47
	s_add_i32 s90, s76, 448
	v_add_u32_e32 v84, s90, v107
	v_add_u32_e32 v85, 0, v84
	v_add_u32_e32 v86, 1, v84
	v_add_u32_e32 v87, 2, v84
	v_add_u32_e32 v88, 3, v84
	v_cmp_gt_u32_e64 s[30:31], s98, v85
	v_cmp_gt_u32_e64 s[36:37], s98, v86
	v_cmp_gt_u32_e64 s[78:79], s98, v87
	v_cmp_gt_u32_e64 s[50:51], s98, v88
	v_cndmask_b32_e64 v32, 0, v32, s[30:31]
	v_add_u32_e32 v85, 8, v84
	v_cmp_gt_u32_e64 s[30:31], s98, v85
	v_cndmask_b32_e64 v33, 0, v33, s[36:37]
	v_add_u32_e32 v86, 9, v84
	v_cmp_gt_u32_e64 s[36:37], s98, v86
	v_cndmask_b32_e64 v34, 0, v34, s[78:79]
	v_add_u32_e32 v87, 10, v84
	v_cmp_gt_u32_e64 s[78:79], s98, v87
	v_cndmask_b32_e64 v35, 0, v35, s[50:51]
	v_add_u32_e32 v88, 11, v84
	v_cmp_gt_u32_e64 s[50:51], s98, v88
	v_cndmask_b32_e64 v36, 0, v36, s[30:31]
	v_add_u32_e32 v85, 16, v84
	v_cmp_gt_u32_e64 s[30:31], s98, v85
	v_cndmask_b32_e64 v37, 0, v37, s[36:37]
	v_add_u32_e32 v86, 17, v84
	v_cmp_gt_u32_e64 s[36:37], s98, v86
	v_cndmask_b32_e64 v38, 0, v38, s[78:79]
	v_add_u32_e32 v87, 18, v84
	v_cmp_gt_u32_e64 s[78:79], s98, v87
	v_cndmask_b32_e64 v39, 0, v39, s[50:51]
	v_add_u32_e32 v88, 19, v84
	v_cmp_gt_u32_e64 s[50:51], s98, v88
	v_cndmask_b32_e64 v40, 0, v40, s[30:31]
	v_add_u32_e32 v85, 24, v84
	v_cmp_gt_u32_e64 s[30:31], s98, v85
	v_cndmask_b32_e64 v41, 0, v41, s[36:37]
	v_add_u32_e32 v86, 25, v84
	v_cmp_gt_u32_e64 s[36:37], s98, v86
	v_cndmask_b32_e64 v42, 0, v42, s[78:79]
	v_add_u32_e32 v87, 26, v84
	v_cmp_gt_u32_e64 s[78:79], s98, v87
	v_cndmask_b32_e64 v43, 0, v43, s[50:51]
	v_add_u32_e32 v88, 27, v84
	v_cmp_gt_u32_e64 s[50:51], s98, v88
	v_nop
	v_cndmask_b32_e64 v44, 0, v44, s[30:31]
	v_cndmask_b32_e64 v45, 0, v45, s[36:37]
	v_cndmask_b32_e64 v46, 0, v46, s[78:79]
	v_cndmask_b32_e64 v47, 0, v47, s[50:51]
	v_cvt_pk_bf16_f32 v64, v32, v33
	v_cvt_pk_bf16_f32 v65, v34, v35
	v_cvt_pk_bf16_f32 v66, v36, v37
	v_cvt_pk_bf16_f32 v67, v38, v39
	v_cvt_pk_bf16_f32 v68, v40, v41
	v_cvt_pk_bf16_f32 v69, v42, v43
	v_cvt_pk_bf16_f32 v70, v44, v45
	v_cvt_pk_bf16_f32 v71, v46, v47
	v_pk_add_f32 v[232:233], v[232:233], v[32:33]
	v_pk_add_f32 v[232:233], v[232:233], v[34:35]
	v_pk_add_f32 v[232:233], v[232:233], v[36:37]
	v_pk_add_f32 v[232:233], v[232:233], v[38:39]
	v_pk_add_f32 v[232:233], v[232:233], v[40:41]
	v_pk_add_f32 v[232:233], v[232:233], v[42:43]
	v_pk_add_f32 v[232:233], v[232:233], v[44:45]
	v_pk_add_f32 v[232:233], v[232:233], v[46:47]
	ds_read2_b32 v[32:33], v115 offset0:136 offset1:137
	ds_read2_b32 v[34:35], v115 offset0:138 offset1:139
	ds_read2_b32 v[36:37], v115 offset0:144 offset1:145
	ds_read2_b32 v[38:39], v115 offset0:146 offset1:147
	ds_read2_b32 v[40:41], v115 offset0:153 offset1:154
	ds_read2_b32 v[42:43], v115 offset0:155 offset1:156
	ds_read2_b32 v[44:45], v115 offset0:161 offset1:162
	ds_read2_b32 v[46:47], v115 offset0:163 offset1:164
	v_mfma_f32_32x32x16_bf16 v[0:15], v[64:67], v[72:75], v[0:15]
	v_mfma_f32_32x32x16_bf16 v[16:31], v[64:67], v[76:79], v[16:31]
	v_mfma_f32_32x32x16_bf16 v[0:15], v[68:71], v[220:223], v[0:15]
	v_mfma_f32_32x32x16_bf16 v[16:31], v[68:71], v[224:227], v[16:31]
	s_add_i32 s90, s76, 544
	v_add_u32_e32 v80, s90, v235
	v_add_u32_e32 v83, s90, v236
	v_add_u32_e32 v99, s90, v237
	v_add_u32_e32 v253, s90, v238
	v_add_u32_e32 v254, s90, v100
	v_add_u32_e32 v255, s90, v149
	v_med3_i32 v80, v80, 0, s99
	v_med3_i32 v83, v83, 0, s99
	v_med3_i32 v99, v99, 0, s99
	v_med3_i32 v253, v253, 0, s99
	v_med3_i32 v254, v254, 0, s99
	v_med3_i32 v255, v255, 0, s99
	v_mad_u32_u24 v80, v80, s100, v252
	v_mad_u32_u24 v83, v83, s100, v252
	v_mad_u32_u24 v99, v99, s100, v252
	v_mad_u32_u24 v253, v253, s100, v252
	v_mad_u32_u24 v254, v254, s100, v153
	v_mad_u32_u24 v255, v255, s100, v153
	global_load_dwordx4 v[156:159], v80, s[82:83]
	global_load_dwordx4 v[160:163], v83, s[82:83]
	global_load_dwordx4 v[164:167], v99, s[82:83]
	global_load_dwordx4 v[168:171], v253, s[82:83]
	global_load_dwordx4 v[172:175], v254, s[82:83] offset:768
	global_load_dwordx4 v[176:179], v255, s[82:83] offset:768
	global_load_dwordx4 v[180:183], v254, s[82:83] offset:832
	global_load_dwordx4 v[184:187], v255, s[82:83] offset:832
	ds_read_b64_tr_b16 v[72:73], v231
	ds_read_b64_tr_b16 v[74:75], v231 offset:512
	ds_read_b64_tr_b16 v[76:77], v231 offset:2048
	ds_read_b64_tr_b16 v[78:79], v231 offset:2560
	ds_read_b64_tr_b16 v[220:221], v231 offset:1024
	ds_read_b64_tr_b16 v[222:223], v231 offset:1536
	ds_read_b64_tr_b16 v[224:225], v231 offset:3072
	ds_read_b64_tr_b16 v[226:227], v231 offset:3584
	v_exp_f32_e32 v188, v188
	v_exp_f32_e32 v189, v189
	v_exp_f32_e32 v190, v190
	v_exp_f32_e32 v191, v191
	s_waitcnt vmcnt(8)
	ds_write_b128 v247, v[116:119]
	ds_write_b128 v247, v[120:123] offset:1024
	ds_write_b128 v247, v[124:127] offset:2048
	ds_write_b128 v247, v[128:131] offset:3072
	ds_read_b128 v[116:119], v248
	ds_read_b128 v[120:123], v249
	ds_read_b128 v[124:127], v250
	ds_read_b128 v[128:131], v251
	ds_write_b128 v112, v[132:135]
	ds_write_b128 v112, v[136:139] offset:1024
	ds_write_b128 v112, v[140:143] offset:2048
	ds_write_b128 v112, v[144:147] offset:3072
	v_exp_f32_e32 v192, v192
	v_exp_f32_e32 v193, v193
	v_exp_f32_e32 v194, v194
	v_exp_f32_e32 v195, v195
	s_waitcnt lgkmcnt(4)
	v_mfma_f32_32x32x16_bf16 v[32:47], v[116:119], v[48:51], v[32:47]
	v_exp_f32_e32 v196, v196
	v_exp_f32_e32 v197, v197
	v_mfma_f32_32x32x16_bf16 v[32:47], v[120:123], v[52:55], v[32:47]
	v_exp_f32_e32 v198, v198
	v_exp_f32_e32 v199, v199
	v_mfma_f32_32x32x16_bf16 v[32:47], v[124:127], v[56:59], v[32:47]
	v_exp_f32_e32 v200, v200
	v_exp_f32_e32 v201, v201
	v_mfma_f32_32x32x16_bf16 v[32:47], v[128:131], v[60:63], v[32:47]
	v_exp_f32_e32 v202, v202
	v_exp_f32_e32 v203, v203
	s_add_i32 s90, s76, 480
	v_add_u32_e32 v84, s90, v107
	v_add_u32_e32 v85, 0, v84
	v_add_u32_e32 v86, 1, v84
	v_add_u32_e32 v87, 2, v84
	v_add_u32_e32 v88, 3, v84
	v_cmp_gt_u32_e64 s[30:31], s98, v85
	v_cmp_gt_u32_e64 s[36:37], s98, v86
	v_cmp_gt_u32_e64 s[78:79], s98, v87
	v_cmp_gt_u32_e64 s[50:51], s98, v88
	v_cndmask_b32_e64 v188, 0, v188, s[30:31]
	v_add_u32_e32 v85, 8, v84
	v_cmp_gt_u32_e64 s[30:31], s98, v85
	v_cndmask_b32_e64 v189, 0, v189, s[36:37]
	v_add_u32_e32 v86, 9, v84
	v_cmp_gt_u32_e64 s[36:37], s98, v86
	v_cndmask_b32_e64 v190, 0, v190, s[78:79]
	v_add_u32_e32 v87, 10, v84
	v_cmp_gt_u32_e64 s[78:79], s98, v87
	v_cndmask_b32_e64 v191, 0, v191, s[50:51]
	v_add_u32_e32 v88, 11, v84
	v_cmp_gt_u32_e64 s[50:51], s98, v88
	v_cndmask_b32_e64 v192, 0, v192, s[30:31]
	v_add_u32_e32 v85, 16, v84
	v_cmp_gt_u32_e64 s[30:31], s98, v85
	v_cndmask_b32_e64 v193, 0, v193, s[36:37]
	v_add_u32_e32 v86, 17, v84
	v_cmp_gt_u32_e64 s[36:37], s98, v86
	v_cndmask_b32_e64 v194, 0, v194, s[78:79]
	v_add_u32_e32 v87, 18, v84
	v_cmp_gt_u32_e64 s[78:79], s98, v87
	v_cndmask_b32_e64 v195, 0, v195, s[50:51]
	v_add_u32_e32 v88, 19, v84
	v_cmp_gt_u32_e64 s[50:51], s98, v88
	v_cndmask_b32_e64 v196, 0, v196, s[30:31]
	v_add_u32_e32 v85, 24, v84
	v_cmp_gt_u32_e64 s[30:31], s98, v85
	v_cndmask_b32_e64 v197, 0, v197, s[36:37]
	v_add_u32_e32 v86, 25, v84
	v_cmp_gt_u32_e64 s[36:37], s98, v86
	v_cndmask_b32_e64 v198, 0, v198, s[78:79]
	v_add_u32_e32 v87, 26, v84
	v_cmp_gt_u32_e64 s[78:79], s98, v87
	v_cndmask_b32_e64 v199, 0, v199, s[50:51]
	v_add_u32_e32 v88, 27, v84
	v_cmp_gt_u32_e64 s[50:51], s98, v88
	v_nop
	v_cndmask_b32_e64 v200, 0, v200, s[30:31]
	v_cndmask_b32_e64 v201, 0, v201, s[36:37]
	v_cndmask_b32_e64 v202, 0, v202, s[78:79]
	v_cndmask_b32_e64 v203, 0, v203, s[50:51]
	v_cvt_pk_bf16_f32 v64, v188, v189
	v_cvt_pk_bf16_f32 v65, v190, v191
	v_cvt_pk_bf16_f32 v66, v192, v193
	v_cvt_pk_bf16_f32 v67, v194, v195
	v_cvt_pk_bf16_f32 v68, v196, v197
	v_cvt_pk_bf16_f32 v69, v198, v199
	v_cvt_pk_bf16_f32 v70, v200, v201
	v_cvt_pk_bf16_f32 v71, v202, v203
	v_pk_add_f32 v[232:233], v[232:233], v[188:189]
	v_pk_add_f32 v[232:233], v[232:233], v[190:191]
	v_pk_add_f32 v[232:233], v[232:233], v[192:193]
	v_pk_add_f32 v[232:233], v[232:233], v[194:195]
	v_pk_add_f32 v[232:233], v[232:233], v[196:197]
	v_pk_add_f32 v[232:233], v[232:233], v[198:199]
	v_pk_add_f32 v[232:233], v[232:233], v[200:201]
	v_pk_add_f32 v[232:233], v[232:233], v[202:203]
	ds_read2_b32 v[188:189], v115 offset0:170 offset1:171
	ds_read2_b32 v[190:191], v115 offset0:172 offset1:173
	ds_read2_b32 v[192:193], v115 offset0:178 offset1:179
	ds_read2_b32 v[194:195], v115 offset0:180 offset1:181
	ds_read2_b32 v[196:197], v115 offset0:187 offset1:188
	ds_read2_b32 v[198:199], v115 offset0:189 offset1:190
	ds_read2_b32 v[200:201], v115 offset0:195 offset1:196
	ds_read2_b32 v[202:203], v115 offset0:197 offset1:198
	v_mfma_f32_32x32x16_bf16 v[0:15], v[64:67], v[72:75], v[0:15]
	v_mfma_f32_32x32x16_bf16 v[16:31], v[64:67], v[76:79], v[16:31]
	v_mfma_f32_32x32x16_bf16 v[0:15], v[68:71], v[220:223], v[0:15]
	v_mfma_f32_32x32x16_bf16 v[16:31], v[68:71], v[224:227], v[16:31]
	s_add_i32 s90, s76, -256
	v_add_u32_e32 v80, s90, v239
	v_add_u32_e32 v83, s90, v240
	v_add_u32_e32 v99, s90, v241
	v_add_u32_e32 v253, s90, v242
	v_add_u32_e32 v254, s90, v101
	v_add_u32_e32 v255, s90, v150
	v_med3_i32 v80, v80, 0, s99
	v_med3_i32 v83, v83, 0, s99
	v_med3_i32 v99, v99, 0, s99
	v_med3_i32 v253, v253, 0, s99
	v_med3_i32 v254, v254, 0, s99
	v_med3_i32 v255, v255, 0, s99
	v_mad_u32_u24 v80, v80, s100, v252
	v_mad_u32_u24 v83, v83, s100, v252
	v_mad_u32_u24 v99, v99, s100, v252
	v_mad_u32_u24 v253, v253, s100, v252
	v_mad_u32_u24 v254, v254, s100, v153
	v_mad_u32_u24 v255, v255, s100, v153
	global_load_dwordx4 v[116:119], v80, s[82:83]
	global_load_dwordx4 v[120:123], v83, s[82:83]
	global_load_dwordx4 v[124:127], v99, s[82:83]
	global_load_dwordx4 v[128:131], v253, s[82:83]
	global_load_dwordx4 v[132:135], v254, s[82:83] offset:768
	global_load_dwordx4 v[136:139], v255, s[82:83] offset:768
	global_load_dwordx4 v[140:143], v254, s[82:83] offset:832
	global_load_dwordx4 v[144:147], v255, s[82:83] offset:832
	ds_read_b64_tr_b16 v[72:73], v231
	ds_read_b64_tr_b16 v[74:75], v231 offset:512
	ds_read_b64_tr_b16 v[76:77], v231 offset:2048
	ds_read_b64_tr_b16 v[78:79], v231 offset:2560
	ds_read_b64_tr_b16 v[220:221], v231 offset:1024
	ds_read_b64_tr_b16 v[222:223], v231 offset:1536
	ds_read_b64_tr_b16 v[224:225], v231 offset:3072
	ds_read_b64_tr_b16 v[226:227], v231 offset:3584
	v_exp_f32_e32 v32, v32
	v_exp_f32_e32 v33, v33
	v_exp_f32_e32 v34, v34
	v_exp_f32_e32 v35, v35
	s_waitcnt vmcnt(8)
	ds_write_b128 v247, v[156:159]
	ds_write_b128 v247, v[160:163] offset:1024
	ds_write_b128 v247, v[164:167] offset:2048
	ds_write_b128 v247, v[168:171] offset:3072
	ds_read_b128 v[156:159], v248
	ds_read_b128 v[160:163], v249
	ds_read_b128 v[164:167], v250
	ds_read_b128 v[168:171], v251
	ds_write_b128 v112, v[172:175]
	ds_write_b128 v112, v[176:179] offset:1024
	ds_write_b128 v112, v[180:183] offset:2048
	ds_write_b128 v112, v[184:187] offset:3072
	v_exp_f32_e32 v36, v36
	v_exp_f32_e32 v37, v37
	v_exp_f32_e32 v38, v38
	v_exp_f32_e32 v39, v39
	s_waitcnt lgkmcnt(4)
	v_mfma_f32_32x32x16_bf16 v[188:203], v[156:159], v[48:51], v[188:203]
	v_exp_f32_e32 v40, v40
	v_exp_f32_e32 v41, v41
	v_mfma_f32_32x32x16_bf16 v[188:203], v[160:163], v[52:55], v[188:203]
	v_exp_f32_e32 v42, v42
	v_exp_f32_e32 v43, v43
	v_mfma_f32_32x32x16_bf16 v[188:203], v[164:167], v[56:59], v[188:203]
	v_exp_f32_e32 v44, v44
	v_exp_f32_e32 v45, v45
	v_mfma_f32_32x32x16_bf16 v[188:203], v[168:171], v[60:63], v[188:203]
	v_exp_f32_e32 v46, v46
	v_exp_f32_e32 v47, v47
	s_add_i32 s90, s76, 512
	v_add_u32_e32 v84, s90, v107
	v_add_u32_e32 v85, 0, v84
	v_add_u32_e32 v86, 1, v84
	v_add_u32_e32 v87, 2, v84
	v_add_u32_e32 v88, 3, v84
	v_cmp_gt_u32_e64 s[30:31], s98, v85
	v_cmp_gt_u32_e64 s[36:37], s98, v86
	v_cmp_gt_u32_e64 s[78:79], s98, v87
	v_cmp_gt_u32_e64 s[50:51], s98, v88
	v_cndmask_b32_e64 v32, 0, v32, s[30:31]
	v_add_u32_e32 v85, 8, v84
	v_cmp_gt_u32_e64 s[30:31], s98, v85
	v_cndmask_b32_e64 v33, 0, v33, s[36:37]
	v_add_u32_e32 v86, 9, v84
	v_cmp_gt_u32_e64 s[36:37], s98, v86
	v_cndmask_b32_e64 v34, 0, v34, s[78:79]
	v_add_u32_e32 v87, 10, v84
	v_cmp_gt_u32_e64 s[78:79], s98, v87
	v_cndmask_b32_e64 v35, 0, v35, s[50:51]
	v_add_u32_e32 v88, 11, v84
	v_cmp_gt_u32_e64 s[50:51], s98, v88
	v_cndmask_b32_e64 v36, 0, v36, s[30:31]
	v_add_u32_e32 v85, 16, v84
	v_cmp_gt_u32_e64 s[30:31], s98, v85
	v_cndmask_b32_e64 v37, 0, v37, s[36:37]
	v_add_u32_e32 v86, 17, v84
	v_cmp_gt_u32_e64 s[36:37], s98, v86
	v_cndmask_b32_e64 v38, 0, v38, s[78:79]
	v_add_u32_e32 v87, 18, v84
	v_cmp_gt_u32_e64 s[78:79], s98, v87
	v_cndmask_b32_e64 v39, 0, v39, s[50:51]
	v_add_u32_e32 v88, 19, v84
	v_cmp_gt_u32_e64 s[50:51], s98, v88
	v_cndmask_b32_e64 v40, 0, v40, s[30:31]
	v_add_u32_e32 v85, 24, v84
	v_cmp_gt_u32_e64 s[30:31], s98, v85
	v_cndmask_b32_e64 v41, 0, v41, s[36:37]
	v_add_u32_e32 v86, 25, v84
	v_cmp_gt_u32_e64 s[36:37], s98, v86
	v_cndmask_b32_e64 v42, 0, v42, s[78:79]
	v_add_u32_e32 v87, 26, v84
	v_cmp_gt_u32_e64 s[78:79], s98, v87
	v_cndmask_b32_e64 v43, 0, v43, s[50:51]
	v_add_u32_e32 v88, 27, v84
	v_cmp_gt_u32_e64 s[50:51], s98, v88
	v_nop
	v_cndmask_b32_e64 v44, 0, v44, s[30:31]
	v_cndmask_b32_e64 v45, 0, v45, s[36:37]
	v_cndmask_b32_e64 v46, 0, v46, s[78:79]
	v_cndmask_b32_e64 v47, 0, v47, s[50:51]
	v_cvt_pk_bf16_f32 v64, v32, v33
	v_cvt_pk_bf16_f32 v65, v34, v35
	v_cvt_pk_bf16_f32 v66, v36, v37
	v_cvt_pk_bf16_f32 v67, v38, v39
	v_cvt_pk_bf16_f32 v68, v40, v41
	v_cvt_pk_bf16_f32 v69, v42, v43
	v_cvt_pk_bf16_f32 v70, v44, v45
	v_cvt_pk_bf16_f32 v71, v46, v47
	v_pk_add_f32 v[232:233], v[232:233], v[32:33]
	v_pk_add_f32 v[232:233], v[232:233], v[34:35]
	v_pk_add_f32 v[232:233], v[232:233], v[36:37]
	v_pk_add_f32 v[232:233], v[232:233], v[38:39]
	v_pk_add_f32 v[232:233], v[232:233], v[40:41]
	v_pk_add_f32 v[232:233], v[232:233], v[42:43]
	v_pk_add_f32 v[232:233], v[232:233], v[44:45]
	v_pk_add_f32 v[232:233], v[232:233], v[46:47]
	v_mov_b32_e32 v115, v229
	ds_read2_b32 v[32:33], v115 offset0:0 offset1:1
	ds_read2_b32 v[34:35], v115 offset0:2 offset1:3
	ds_read2_b32 v[36:37], v115 offset0:8 offset1:9
	ds_read2_b32 v[38:39], v115 offset0:10 offset1:11
	ds_read2_b32 v[40:41], v115 offset0:16 offset1:17
	ds_read2_b32 v[42:43], v115 offset0:18 offset1:19
	ds_read2_b32 v[44:45], v115 offset0:24 offset1:25
	ds_read2_b32 v[46:47], v115 offset0:26 offset1:27
	v_mfma_f32_32x32x16_bf16 v[0:15], v[64:67], v[72:75], v[0:15]
	v_mfma_f32_32x32x16_bf16 v[16:31], v[64:67], v[76:79], v[16:31]
	v_mfma_f32_32x32x16_bf16 v[0:15], v[68:71], v[220:223], v[0:15]
	v_mfma_f32_32x32x16_bf16 v[16:31], v[68:71], v[224:227], v[16:31]
	s_add_i32 s90, s76, -128
	v_add_u32_e32 v80, s90, v239
	v_add_u32_e32 v83, s90, v240
	v_add_u32_e32 v99, s90, v241
	v_add_u32_e32 v253, s90, v242
	v_add_u32_e32 v254, s90, v101
	v_add_u32_e32 v255, s90, v150
	v_med3_i32 v80, v80, 0, s99
	v_med3_i32 v83, v83, 0, s99
	v_med3_i32 v99, v99, 0, s99
	v_med3_i32 v253, v253, 0, s99
	v_med3_i32 v254, v254, 0, s99
	v_med3_i32 v255, v255, 0, s99
	v_mad_u32_u24 v80, v80, s100, v252
	v_mad_u32_u24 v83, v83, s100, v252
	v_mad_u32_u24 v99, v99, s100, v252
	v_mad_u32_u24 v253, v253, s100, v252
	v_mad_u32_u24 v254, v254, s100, v153
	v_mad_u32_u24 v255, v255, s100, v153
	global_load_dwordx4 v[156:159], v80, s[82:83]
	global_load_dwordx4 v[160:163], v83, s[82:83]
	global_load_dwordx4 v[164:167], v99, s[82:83]
	global_load_dwordx4 v[168:171], v253, s[82:83]
	global_load_dwordx4 v[172:175], v254, s[82:83] offset:768
	global_load_dwordx4 v[176:179], v255, s[82:83] offset:768
	global_load_dwordx4 v[180:183], v254, s[82:83] offset:832
	global_load_dwordx4 v[184:187], v255, s[82:83] offset:832
	ds_read_b64_tr_b16 v[72:73], v231
	ds_read_b64_tr_b16 v[74:75], v231 offset:512
	ds_read_b64_tr_b16 v[76:77], v231 offset:2048
	ds_read_b64_tr_b16 v[78:79], v231 offset:2560
	ds_read_b64_tr_b16 v[220:221], v231 offset:1024
	ds_read_b64_tr_b16 v[222:223], v231 offset:1536
	ds_read_b64_tr_b16 v[224:225], v231 offset:3072
	ds_read_b64_tr_b16 v[226:227], v231 offset:3584
	v_exp_f32_e32 v188, v188
	v_exp_f32_e32 v189, v189
	v_exp_f32_e32 v190, v190
	v_exp_f32_e32 v191, v191
	s_waitcnt vmcnt(8)
	ds_write_b128 v247, v[116:119]
	ds_write_b128 v247, v[120:123] offset:1024
	ds_write_b128 v247, v[124:127] offset:2048
	ds_write_b128 v247, v[128:131] offset:3072
	ds_read_b128 v[116:119], v248
	ds_read_b128 v[120:123], v249
	ds_read_b128 v[124:127], v250
	ds_read_b128 v[128:131], v251
	ds_write_b128 v112, v[132:135]
	ds_write_b128 v112, v[136:139] offset:1024
	ds_write_b128 v112, v[140:143] offset:2048
	ds_write_b128 v112, v[144:147] offset:3072
	v_exp_f32_e32 v192, v192
	v_exp_f32_e32 v193, v193
	v_exp_f32_e32 v194, v194
	v_exp_f32_e32 v195, v195
	s_waitcnt lgkmcnt(4)
	v_mfma_f32_32x32x16_bf16 v[32:47], v[116:119], v[48:51], v[32:47]
	v_exp_f32_e32 v196, v196
	v_exp_f32_e32 v197, v197
	v_mfma_f32_32x32x16_bf16 v[32:47], v[120:123], v[52:55], v[32:47]
	v_exp_f32_e32 v198, v198
	v_exp_f32_e32 v199, v199
	v_mfma_f32_32x32x16_bf16 v[32:47], v[124:127], v[56:59], v[32:47]
	v_exp_f32_e32 v200, v200
	v_exp_f32_e32 v201, v201
	v_mfma_f32_32x32x16_bf16 v[32:47], v[128:131], v[60:63], v[32:47]
	v_exp_f32_e32 v202, v202
	v_exp_f32_e32 v203, v203
	s_add_i32 s90, s76, 544
	v_add_u32_e32 v84, s90, v107
	v_add_u32_e32 v85, 0, v84
	v_add_u32_e32 v86, 1, v84
	v_add_u32_e32 v87, 2, v84
	v_add_u32_e32 v88, 3, v84
	v_cmp_gt_u32_e64 s[30:31], s98, v85
	v_cmp_gt_u32_e64 s[36:37], s98, v86
	v_cmp_gt_u32_e64 s[78:79], s98, v87
	v_cmp_gt_u32_e64 s[50:51], s98, v88
	v_cndmask_b32_e64 v188, 0, v188, s[30:31]
	v_add_u32_e32 v85, 8, v84
	v_cmp_gt_u32_e64 s[30:31], s98, v85
	v_cndmask_b32_e64 v189, 0, v189, s[36:37]
	v_add_u32_e32 v86, 9, v84
	v_cmp_gt_u32_e64 s[36:37], s98, v86
	v_cndmask_b32_e64 v190, 0, v190, s[78:79]
	v_add_u32_e32 v87, 10, v84
	v_cmp_gt_u32_e64 s[78:79], s98, v87
	v_cndmask_b32_e64 v191, 0, v191, s[50:51]
	v_add_u32_e32 v88, 11, v84
	v_cmp_gt_u32_e64 s[50:51], s98, v88
	v_cndmask_b32_e64 v192, 0, v192, s[30:31]
	v_add_u32_e32 v85, 16, v84
	v_cmp_gt_u32_e64 s[30:31], s98, v85
	v_cndmask_b32_e64 v193, 0, v193, s[36:37]
	v_add_u32_e32 v86, 17, v84
	v_cmp_gt_u32_e64 s[36:37], s98, v86
	v_cndmask_b32_e64 v194, 0, v194, s[78:79]
	v_add_u32_e32 v87, 18, v84
	v_cmp_gt_u32_e64 s[78:79], s98, v87
	v_cndmask_b32_e64 v195, 0, v195, s[50:51]
	v_add_u32_e32 v88, 19, v84
	v_cmp_gt_u32_e64 s[50:51], s98, v88
	v_cndmask_b32_e64 v196, 0, v196, s[30:31]
	v_add_u32_e32 v85, 24, v84
	v_cmp_gt_u32_e64 s[30:31], s98, v85
	v_cndmask_b32_e64 v197, 0, v197, s[36:37]
	v_add_u32_e32 v86, 25, v84
	v_cmp_gt_u32_e64 s[36:37], s98, v86
	v_cndmask_b32_e64 v198, 0, v198, s[78:79]
	v_add_u32_e32 v87, 26, v84
	v_cmp_gt_u32_e64 s[78:79], s98, v87
	v_cndmask_b32_e64 v199, 0, v199, s[50:51]
	v_add_u32_e32 v88, 27, v84
	v_cmp_gt_u32_e64 s[50:51], s98, v88
	v_nop
	v_cndmask_b32_e64 v200, 0, v200, s[30:31]
	v_cndmask_b32_e64 v201, 0, v201, s[36:37]
	v_cndmask_b32_e64 v202, 0, v202, s[78:79]
	v_cndmask_b32_e64 v203, 0, v203, s[50:51]
	v_cvt_pk_bf16_f32 v64, v188, v189
	v_cvt_pk_bf16_f32 v65, v190, v191
	v_cvt_pk_bf16_f32 v66, v192, v193
	v_cvt_pk_bf16_f32 v67, v194, v195
	v_cvt_pk_bf16_f32 v68, v196, v197
	v_cvt_pk_bf16_f32 v69, v198, v199
	v_cvt_pk_bf16_f32 v70, v200, v201
	v_cvt_pk_bf16_f32 v71, v202, v203
	v_pk_add_f32 v[232:233], v[232:233], v[188:189]
	v_pk_add_f32 v[232:233], v[232:233], v[190:191]
	v_pk_add_f32 v[232:233], v[232:233], v[192:193]
	v_pk_add_f32 v[232:233], v[232:233], v[194:195]
	v_pk_add_f32 v[232:233], v[232:233], v[196:197]
	v_pk_add_f32 v[232:233], v[232:233], v[198:199]
	v_pk_add_f32 v[232:233], v[232:233], v[200:201]
	v_pk_add_f32 v[232:233], v[232:233], v[202:203]
	ds_read2_b32 v[188:189], v115 offset0:32 offset1:33
	ds_read2_b32 v[190:191], v115 offset0:34 offset1:35
	ds_read2_b32 v[192:193], v115 offset0:40 offset1:41
	ds_read2_b32 v[194:195], v115 offset0:42 offset1:43
	ds_read2_b32 v[196:197], v115 offset0:48 offset1:49
	ds_read2_b32 v[198:199], v115 offset0:50 offset1:51
	ds_read2_b32 v[200:201], v115 offset0:56 offset1:57
	ds_read2_b32 v[202:203], v115 offset0:58 offset1:59
	v_mfma_f32_32x32x16_bf16 v[0:15], v[64:67], v[72:75], v[0:15]
	v_mfma_f32_32x32x16_bf16 v[16:31], v[64:67], v[76:79], v[16:31]
	v_mfma_f32_32x32x16_bf16 v[0:15], v[68:71], v[220:223], v[0:15]
	v_mfma_f32_32x32x16_bf16 v[16:31], v[68:71], v[224:227], v[16:31]
	s_add_i32 s90, s76, 0
	v_add_u32_e32 v80, s90, v239
	v_add_u32_e32 v83, s90, v240
	v_add_u32_e32 v99, s90, v241
	v_add_u32_e32 v253, s90, v242
	v_add_u32_e32 v254, s90, v101
	v_add_u32_e32 v255, s90, v150
	v_med3_i32 v80, v80, 0, s99
	v_med3_i32 v83, v83, 0, s99
	v_med3_i32 v99, v99, 0, s99
	v_med3_i32 v253, v253, 0, s99
	v_med3_i32 v254, v254, 0, s99
	v_med3_i32 v255, v255, 0, s99
	v_mad_u32_u24 v80, v80, s100, v252
	v_mad_u32_u24 v83, v83, s100, v252
	v_mad_u32_u24 v99, v99, s100, v252
	v_mad_u32_u24 v253, v253, s100, v252
	v_mad_u32_u24 v254, v254, s100, v153
	v_mad_u32_u24 v255, v255, s100, v153
	global_load_dwordx4 v[116:119], v80, s[82:83]
	global_load_dwordx4 v[120:123], v83, s[82:83]
	global_load_dwordx4 v[124:127], v99, s[82:83]
	global_load_dwordx4 v[128:131], v253, s[82:83]
	global_load_dwordx4 v[132:135], v254, s[82:83] offset:768
	global_load_dwordx4 v[136:139], v255, s[82:83] offset:768
	global_load_dwordx4 v[140:143], v254, s[82:83] offset:832
	global_load_dwordx4 v[144:147], v255, s[82:83] offset:832
	ds_read_b64_tr_b16 v[72:73], v231
	ds_read_b64_tr_b16 v[74:75], v231 offset:512
	ds_read_b64_tr_b16 v[76:77], v231 offset:2048
	ds_read_b64_tr_b16 v[78:79], v231 offset:2560
	ds_read_b64_tr_b16 v[220:221], v231 offset:1024
	ds_read_b64_tr_b16 v[222:223], v231 offset:1536
	ds_read_b64_tr_b16 v[224:225], v231 offset:3072
	ds_read_b64_tr_b16 v[226:227], v231 offset:3584
	v_exp_f32_e32 v32, v32
	v_exp_f32_e32 v33, v33
	v_exp_f32_e32 v34, v34
	v_exp_f32_e32 v35, v35
	s_waitcnt vmcnt(8)
	ds_write_b128 v247, v[156:159]
	ds_write_b128 v247, v[160:163] offset:1024
	ds_write_b128 v247, v[164:167] offset:2048
	ds_write_b128 v247, v[168:171] offset:3072
	ds_read_b128 v[156:159], v248
	ds_read_b128 v[160:163], v249
	ds_read_b128 v[164:167], v250
	ds_read_b128 v[168:171], v251
	ds_write_b128 v112, v[172:175]
	ds_write_b128 v112, v[176:179] offset:1024
	ds_write_b128 v112, v[180:183] offset:2048
	ds_write_b128 v112, v[184:187] offset:3072
	v_exp_f32_e32 v36, v36
	v_exp_f32_e32 v37, v37
	v_exp_f32_e32 v38, v38
	v_exp_f32_e32 v39, v39
	s_waitcnt lgkmcnt(4)
	v_mfma_f32_32x32x16_bf16 v[188:203], v[156:159], v[48:51], v[188:203]
	v_exp_f32_e32 v40, v40
	v_exp_f32_e32 v41, v41
	v_mfma_f32_32x32x16_bf16 v[188:203], v[160:163], v[52:55], v[188:203]
	v_exp_f32_e32 v42, v42
	v_exp_f32_e32 v43, v43
	v_mfma_f32_32x32x16_bf16 v[188:203], v[164:167], v[56:59], v[188:203]
	v_exp_f32_e32 v44, v44
	v_exp_f32_e32 v45, v45
	v_mfma_f32_32x32x16_bf16 v[188:203], v[168:171], v[60:63], v[188:203]
	v_exp_f32_e32 v46, v46
	v_exp_f32_e32 v47, v47
	s_add_i32 s90, s76, -256
	v_lshlrev_b32_e32 v84, 2, v107
	v_add_u32_e32 v84, s90, v84
	v_add_u32_e32 v85, 0, v84
	v_add_u32_e32 v86, 4, v84
	v_add_u32_e32 v87, 8, v84
	v_add_u32_e32 v88, 12, v84
	v_cmp_gt_u32_e64 s[30:31], s98, v85
	v_cmp_gt_u32_e64 s[36:37], s98, v86
	v_cmp_gt_u32_e64 s[78:79], s98, v87
	v_cmp_gt_u32_e64 s[50:51], s98, v88
	v_cndmask_b32_e64 v32, 0, v32, s[30:31]
	v_add_u32_e32 v85, 32, v84
	v_cmp_gt_u32_e64 s[30:31], s98, v85
	v_cndmask_b32_e64 v33, 0, v33, s[36:37]
	v_add_u32_e32 v86, 36, v84
	v_cmp_gt_u32_e64 s[36:37], s98, v86
	v_cndmask_b32_e64 v34, 0, v34, s[78:79]
	v_add_u32_e32 v87, 40, v84
	v_cmp_gt_u32_e64 s[78:79], s98, v87
	v_cndmask_b32_e64 v35, 0, v35, s[50:51]
	v_add_u32_e32 v88, 44, v84
	v_cmp_gt_u32_e64 s[50:51], s98, v88
	v_cndmask_b32_e64 v36, 0, v36, s[30:31]
	v_add_u32_e32 v85, 64, v84
	v_cmp_gt_u32_e64 s[30:31], s98, v85
	v_cndmask_b32_e64 v37, 0, v37, s[36:37]
	v_add_u32_e32 v86, 68, v84
	v_cmp_gt_u32_e64 s[36:37], s98, v86
	v_cndmask_b32_e64 v38, 0, v38, s[78:79]
	v_add_u32_e32 v87, 72, v84
	v_cmp_gt_u32_e64 s[78:79], s98, v87
	v_cndmask_b32_e64 v39, 0, v39, s[50:51]
	v_add_u32_e32 v88, 76, v84
	v_cmp_gt_u32_e64 s[50:51], s98, v88
	v_cndmask_b32_e64 v40, 0, v40, s[30:31]
	v_add_u32_e32 v85, 96, v84
	v_cmp_gt_u32_e64 s[30:31], s98, v85
	v_cndmask_b32_e64 v41, 0, v41, s[36:37]
	v_add_u32_e32 v86, 100, v84
	v_cmp_gt_u32_e64 s[36:37], s98, v86
	v_cndmask_b32_e64 v42, 0, v42, s[78:79]
	v_add_u32_e32 v87, 104, v84
	v_cmp_gt_u32_e64 s[78:79], s98, v87
	v_cndmask_b32_e64 v43, 0, v43, s[50:51]
	v_add_u32_e32 v88, 108, v84
	v_cmp_gt_u32_e64 s[50:51], s98, v88
	v_nop
	v_cndmask_b32_e64 v44, 0, v44, s[30:31]
	v_cndmask_b32_e64 v45, 0, v45, s[36:37]
	v_cndmask_b32_e64 v46, 0, v46, s[78:79]
	v_cndmask_b32_e64 v47, 0, v47, s[50:51]
	v_cvt_pk_bf16_f32 v64, v32, v33
	v_cvt_pk_bf16_f32 v65, v34, v35
	v_cvt_pk_bf16_f32 v66, v36, v37
	v_cvt_pk_bf16_f32 v67, v38, v39
	v_cvt_pk_bf16_f32 v68, v40, v41
	v_cvt_pk_bf16_f32 v69, v42, v43
	v_cvt_pk_bf16_f32 v70, v44, v45
	v_cvt_pk_bf16_f32 v71, v46, v47
	v_pk_add_f32 v[232:233], v[232:233], v[32:33]
	v_pk_add_f32 v[232:233], v[232:233], v[34:35]
	v_pk_add_f32 v[232:233], v[232:233], v[36:37]
	v_pk_add_f32 v[232:233], v[232:233], v[38:39]
	v_pk_add_f32 v[232:233], v[232:233], v[40:41]
	v_pk_add_f32 v[232:233], v[232:233], v[42:43]
	v_pk_add_f32 v[232:233], v[232:233], v[44:45]
	v_pk_add_f32 v[232:233], v[232:233], v[46:47]
	ds_read2_b32 v[32:33], v115 offset0:64 offset1:65
	ds_read2_b32 v[34:35], v115 offset0:66 offset1:67
	ds_read2_b32 v[36:37], v115 offset0:72 offset1:73
	ds_read2_b32 v[38:39], v115 offset0:74 offset1:75
	ds_read2_b32 v[40:41], v115 offset0:80 offset1:81
	ds_read2_b32 v[42:43], v115 offset0:82 offset1:83
	ds_read2_b32 v[44:45], v115 offset0:88 offset1:89
	ds_read2_b32 v[46:47], v115 offset0:90 offset1:91
	v_mfma_f32_32x32x16_bf16 v[0:15], v[64:67], v[72:75], v[0:15]
	v_mfma_f32_32x32x16_bf16 v[16:31], v[64:67], v[76:79], v[16:31]
	v_mfma_f32_32x32x16_bf16 v[0:15], v[68:71], v[220:223], v[0:15]
	v_mfma_f32_32x32x16_bf16 v[16:31], v[68:71], v[224:227], v[16:31]
	s_add_i32 s90, s76, 128
	v_add_u32_e32 v80, s90, v239
	v_add_u32_e32 v83, s90, v240
	v_add_u32_e32 v99, s90, v241
	v_add_u32_e32 v253, s90, v242
	v_add_u32_e32 v254, s90, v101
	v_add_u32_e32 v255, s90, v150
	v_med3_i32 v80, v80, 0, s99
	v_med3_i32 v83, v83, 0, s99
	v_med3_i32 v99, v99, 0, s99
	v_med3_i32 v253, v253, 0, s99
	v_med3_i32 v254, v254, 0, s99
	v_med3_i32 v255, v255, 0, s99
	v_mad_u32_u24 v80, v80, s100, v252
	v_mad_u32_u24 v83, v83, s100, v252
	v_mad_u32_u24 v99, v99, s100, v252
	v_mad_u32_u24 v253, v253, s100, v252
	v_mad_u32_u24 v254, v254, s100, v153
	v_mad_u32_u24 v255, v255, s100, v153
	global_load_dwordx4 v[156:159], v80, s[82:83]
	global_load_dwordx4 v[160:163], v83, s[82:83]
	global_load_dwordx4 v[164:167], v99, s[82:83]
	global_load_dwordx4 v[168:171], v253, s[82:83]
	global_load_dwordx4 v[172:175], v254, s[82:83] offset:768
	global_load_dwordx4 v[176:179], v255, s[82:83] offset:768
	global_load_dwordx4 v[180:183], v254, s[82:83] offset:832
	global_load_dwordx4 v[184:187], v255, s[82:83] offset:832
	ds_read_b64_tr_b16 v[72:73], v231
	ds_read_b64_tr_b16 v[74:75], v231 offset:512
	ds_read_b64_tr_b16 v[76:77], v231 offset:2048
	ds_read_b64_tr_b16 v[78:79], v231 offset:2560
	ds_read_b64_tr_b16 v[220:221], v231 offset:1024
	ds_read_b64_tr_b16 v[222:223], v231 offset:1536
	ds_read_b64_tr_b16 v[224:225], v231 offset:3072
	ds_read_b64_tr_b16 v[226:227], v231 offset:3584
	v_exp_f32_e32 v188, v188
	v_exp_f32_e32 v189, v189
	v_exp_f32_e32 v190, v190
	v_exp_f32_e32 v191, v191
	s_waitcnt vmcnt(8)
	ds_write_b128 v247, v[116:119]
	ds_write_b128 v247, v[120:123] offset:1024
	ds_write_b128 v247, v[124:127] offset:2048
	ds_write_b128 v247, v[128:131] offset:3072
	ds_read_b128 v[116:119], v248
	ds_read_b128 v[120:123], v249
	ds_read_b128 v[124:127], v250
	ds_read_b128 v[128:131], v251
	ds_write_b128 v112, v[132:135]
	ds_write_b128 v112, v[136:139] offset:1024
	ds_write_b128 v112, v[140:143] offset:2048
	ds_write_b128 v112, v[144:147] offset:3072
	v_exp_f32_e32 v192, v192
	v_exp_f32_e32 v193, v193
	v_exp_f32_e32 v194, v194
	v_exp_f32_e32 v195, v195
	s_waitcnt lgkmcnt(4)
	v_mfma_f32_32x32x16_bf16 v[32:47], v[116:119], v[48:51], v[32:47]
	v_exp_f32_e32 v196, v196
	v_exp_f32_e32 v197, v197
	v_mfma_f32_32x32x16_bf16 v[32:47], v[120:123], v[52:55], v[32:47]
	v_exp_f32_e32 v198, v198
	v_exp_f32_e32 v199, v199
	v_mfma_f32_32x32x16_bf16 v[32:47], v[124:127], v[56:59], v[32:47]
	v_exp_f32_e32 v200, v200
	v_exp_f32_e32 v201, v201
	v_mfma_f32_32x32x16_bf16 v[32:47], v[128:131], v[60:63], v[32:47]
	v_exp_f32_e32 v202, v202
	v_exp_f32_e32 v203, v203
	s_add_i32 s90, s76, -128
	v_lshlrev_b32_e32 v84, 2, v107
	v_add_u32_e32 v84, s90, v84
	v_add_u32_e32 v85, 0, v84
	v_add_u32_e32 v86, 4, v84
	v_add_u32_e32 v87, 8, v84
	v_add_u32_e32 v88, 12, v84
	v_cmp_gt_u32_e64 s[30:31], s98, v85
	v_cmp_gt_u32_e64 s[36:37], s98, v86
	v_cmp_gt_u32_e64 s[78:79], s98, v87
	v_cmp_gt_u32_e64 s[50:51], s98, v88
	v_cndmask_b32_e64 v188, 0, v188, s[30:31]
	v_add_u32_e32 v85, 32, v84
	v_cmp_gt_u32_e64 s[30:31], s98, v85
	v_cndmask_b32_e64 v189, 0, v189, s[36:37]
	v_add_u32_e32 v86, 36, v84
	v_cmp_gt_u32_e64 s[36:37], s98, v86
	v_cndmask_b32_e64 v190, 0, v190, s[78:79]
	v_add_u32_e32 v87, 40, v84
	v_cmp_gt_u32_e64 s[78:79], s98, v87
	v_cndmask_b32_e64 v191, 0, v191, s[50:51]
	v_add_u32_e32 v88, 44, v84
	v_cmp_gt_u32_e64 s[50:51], s98, v88
	v_cndmask_b32_e64 v192, 0, v192, s[30:31]
	v_add_u32_e32 v85, 64, v84
	v_cmp_gt_u32_e64 s[30:31], s98, v85
	v_cndmask_b32_e64 v193, 0, v193, s[36:37]
	v_add_u32_e32 v86, 68, v84
	v_cmp_gt_u32_e64 s[36:37], s98, v86
	v_cndmask_b32_e64 v194, 0, v194, s[78:79]
	v_add_u32_e32 v87, 72, v84
	v_cmp_gt_u32_e64 s[78:79], s98, v87
	v_cndmask_b32_e64 v195, 0, v195, s[50:51]
	v_add_u32_e32 v88, 76, v84
	v_cmp_gt_u32_e64 s[50:51], s98, v88
	v_cndmask_b32_e64 v196, 0, v196, s[30:31]
	v_add_u32_e32 v85, 96, v84
	v_cmp_gt_u32_e64 s[30:31], s98, v85
	v_cndmask_b32_e64 v197, 0, v197, s[36:37]
	v_add_u32_e32 v86, 100, v84
	v_cmp_gt_u32_e64 s[36:37], s98, v86
	v_cndmask_b32_e64 v198, 0, v198, s[78:79]
	v_add_u32_e32 v87, 104, v84
	v_cmp_gt_u32_e64 s[78:79], s98, v87
	v_cndmask_b32_e64 v199, 0, v199, s[50:51]
	v_add_u32_e32 v88, 108, v84
	v_cmp_gt_u32_e64 s[50:51], s98, v88
	v_nop
	v_cndmask_b32_e64 v200, 0, v200, s[30:31]
	v_cndmask_b32_e64 v201, 0, v201, s[36:37]
	v_cndmask_b32_e64 v202, 0, v202, s[78:79]
	v_cndmask_b32_e64 v203, 0, v203, s[50:51]
	v_cvt_pk_bf16_f32 v64, v188, v189
	v_cvt_pk_bf16_f32 v65, v190, v191
	v_cvt_pk_bf16_f32 v66, v192, v193
	v_cvt_pk_bf16_f32 v67, v194, v195
	v_cvt_pk_bf16_f32 v68, v196, v197
	v_cvt_pk_bf16_f32 v69, v198, v199
	v_cvt_pk_bf16_f32 v70, v200, v201
	v_cvt_pk_bf16_f32 v71, v202, v203
	v_pk_add_f32 v[232:233], v[232:233], v[188:189]
	v_pk_add_f32 v[232:233], v[232:233], v[190:191]
	v_pk_add_f32 v[232:233], v[232:233], v[192:193]
	v_pk_add_f32 v[232:233], v[232:233], v[194:195]
	v_pk_add_f32 v[232:233], v[232:233], v[196:197]
	v_pk_add_f32 v[232:233], v[232:233], v[198:199]
	v_pk_add_f32 v[232:233], v[232:233], v[200:201]
	v_pk_add_f32 v[232:233], v[232:233], v[202:203]
	ds_read2_b32 v[188:189], v115 offset0:96 offset1:97
	ds_read2_b32 v[190:191], v115 offset0:98 offset1:99
	ds_read2_b32 v[192:193], v115 offset0:104 offset1:105
	ds_read2_b32 v[194:195], v115 offset0:106 offset1:107
	ds_read2_b32 v[196:197], v115 offset0:112 offset1:113
	ds_read2_b32 v[198:199], v115 offset0:114 offset1:115
	ds_read2_b32 v[200:201], v115 offset0:120 offset1:121
	ds_read2_b32 v[202:203], v115 offset0:122 offset1:123
	v_mfma_f32_32x32x16_bf16 v[0:15], v[64:67], v[72:75], v[0:15]
	v_mfma_f32_32x32x16_bf16 v[16:31], v[64:67], v[76:79], v[16:31]
	v_mfma_f32_32x32x16_bf16 v[0:15], v[68:71], v[220:223], v[0:15]
	v_mfma_f32_32x32x16_bf16 v[16:31], v[68:71], v[224:227], v[16:31]
	s_add_i32 s90, s76, 256
	v_add_u32_e32 v80, s90, v239
	v_add_u32_e32 v83, s90, v240
	v_add_u32_e32 v99, s90, v241
	v_add_u32_e32 v253, s90, v242
	v_add_u32_e32 v254, s90, v101
	v_add_u32_e32 v255, s90, v150
	v_med3_i32 v80, v80, 0, s99
	v_med3_i32 v83, v83, 0, s99
	v_med3_i32 v99, v99, 0, s99
	v_med3_i32 v253, v253, 0, s99
	v_med3_i32 v254, v254, 0, s99
	v_med3_i32 v255, v255, 0, s99
	v_mad_u32_u24 v80, v80, s100, v252
	v_mad_u32_u24 v83, v83, s100, v252
	v_mad_u32_u24 v99, v99, s100, v252
	v_mad_u32_u24 v253, v253, s100, v252
	v_mad_u32_u24 v254, v254, s100, v153
	v_mad_u32_u24 v255, v255, s100, v153
	global_load_dwordx4 v[116:119], v80, s[82:83]
	global_load_dwordx4 v[120:123], v83, s[82:83]
	global_load_dwordx4 v[124:127], v99, s[82:83]
	global_load_dwordx4 v[128:131], v253, s[82:83]
	global_load_dwordx4 v[132:135], v254, s[82:83] offset:768
	global_load_dwordx4 v[136:139], v255, s[82:83] offset:768
	global_load_dwordx4 v[140:143], v254, s[82:83] offset:832
	global_load_dwordx4 v[144:147], v255, s[82:83] offset:832
	ds_read_b64_tr_b16 v[72:73], v231
	ds_read_b64_tr_b16 v[74:75], v231 offset:512
	ds_read_b64_tr_b16 v[76:77], v231 offset:2048
	ds_read_b64_tr_b16 v[78:79], v231 offset:2560
	ds_read_b64_tr_b16 v[220:221], v231 offset:1024
	ds_read_b64_tr_b16 v[222:223], v231 offset:1536
	ds_read_b64_tr_b16 v[224:225], v231 offset:3072
	ds_read_b64_tr_b16 v[226:227], v231 offset:3584
	v_exp_f32_e32 v32, v32
	v_exp_f32_e32 v33, v33
	v_exp_f32_e32 v34, v34
	v_exp_f32_e32 v35, v35
	s_waitcnt vmcnt(8)
	ds_write_b128 v247, v[156:159]
	ds_write_b128 v247, v[160:163] offset:1024
	ds_write_b128 v247, v[164:167] offset:2048
	ds_write_b128 v247, v[168:171] offset:3072
	ds_read_b128 v[156:159], v248
	ds_read_b128 v[160:163], v249
	ds_read_b128 v[164:167], v250
	ds_read_b128 v[168:171], v251
	ds_write_b128 v112, v[172:175]
	ds_write_b128 v112, v[176:179] offset:1024
	ds_write_b128 v112, v[180:183] offset:2048
	ds_write_b128 v112, v[184:187] offset:3072
	v_exp_f32_e32 v36, v36
	v_exp_f32_e32 v37, v37
	v_exp_f32_e32 v38, v38
	v_exp_f32_e32 v39, v39
	s_waitcnt lgkmcnt(4)
	v_mfma_f32_32x32x16_bf16 v[188:203], v[156:159], v[48:51], v[188:203]
	v_exp_f32_e32 v40, v40
	v_exp_f32_e32 v41, v41
	v_mfma_f32_32x32x16_bf16 v[188:203], v[160:163], v[52:55], v[188:203]
	v_exp_f32_e32 v42, v42
	v_exp_f32_e32 v43, v43
	v_mfma_f32_32x32x16_bf16 v[188:203], v[164:167], v[56:59], v[188:203]
	v_exp_f32_e32 v44, v44
	v_exp_f32_e32 v45, v45
	v_mfma_f32_32x32x16_bf16 v[188:203], v[168:171], v[60:63], v[188:203]
	v_exp_f32_e32 v46, v46
	v_exp_f32_e32 v47, v47
	s_add_i32 s90, s76, 0
	v_lshlrev_b32_e32 v84, 2, v107
	v_add_u32_e32 v84, s90, v84
	v_add_u32_e32 v85, 0, v84
	v_add_u32_e32 v86, 4, v84
	v_add_u32_e32 v87, 8, v84
	v_add_u32_e32 v88, 12, v84
	v_cmp_gt_u32_e64 s[30:31], s98, v85
	v_cmp_gt_u32_e64 s[36:37], s98, v86
	v_cmp_gt_u32_e64 s[78:79], s98, v87
	v_cmp_gt_u32_e64 s[50:51], s98, v88
	v_cndmask_b32_e64 v32, 0, v32, s[30:31]
	v_add_u32_e32 v85, 32, v84
	v_cmp_gt_u32_e64 s[30:31], s98, v85
	v_cndmask_b32_e64 v33, 0, v33, s[36:37]
	v_add_u32_e32 v86, 36, v84
	v_cmp_gt_u32_e64 s[36:37], s98, v86
	v_cndmask_b32_e64 v34, 0, v34, s[78:79]
	v_add_u32_e32 v87, 40, v84
	v_cmp_gt_u32_e64 s[78:79], s98, v87
	v_cndmask_b32_e64 v35, 0, v35, s[50:51]
	v_add_u32_e32 v88, 44, v84
	v_cmp_gt_u32_e64 s[50:51], s98, v88
	v_cndmask_b32_e64 v36, 0, v36, s[30:31]
	v_add_u32_e32 v85, 64, v84
	v_cmp_gt_u32_e64 s[30:31], s98, v85
	v_cndmask_b32_e64 v37, 0, v37, s[36:37]
	v_add_u32_e32 v86, 68, v84
	v_cmp_gt_u32_e64 s[36:37], s98, v86
	v_cndmask_b32_e64 v38, 0, v38, s[78:79]
	v_add_u32_e32 v87, 72, v84
	v_cmp_gt_u32_e64 s[78:79], s98, v87
	v_cndmask_b32_e64 v39, 0, v39, s[50:51]
	v_add_u32_e32 v88, 76, v84
	v_cmp_gt_u32_e64 s[50:51], s98, v88
	v_cndmask_b32_e64 v40, 0, v40, s[30:31]
	v_add_u32_e32 v85, 96, v84
	v_cmp_gt_u32_e64 s[30:31], s98, v85
	v_cndmask_b32_e64 v41, 0, v41, s[36:37]
	v_add_u32_e32 v86, 100, v84
	v_cmp_gt_u32_e64 s[36:37], s98, v86
	v_cndmask_b32_e64 v42, 0, v42, s[78:79]
	v_add_u32_e32 v87, 104, v84
	v_cmp_gt_u32_e64 s[78:79], s98, v87
	v_cndmask_b32_e64 v43, 0, v43, s[50:51]
	v_add_u32_e32 v88, 108, v84
	v_cmp_gt_u32_e64 s[50:51], s98, v88
	v_nop
	v_cndmask_b32_e64 v44, 0, v44, s[30:31]
	v_cndmask_b32_e64 v45, 0, v45, s[36:37]
	v_cndmask_b32_e64 v46, 0, v46, s[78:79]
	v_cndmask_b32_e64 v47, 0, v47, s[50:51]
	v_cvt_pk_bf16_f32 v64, v32, v33
	v_cvt_pk_bf16_f32 v65, v34, v35
	v_cvt_pk_bf16_f32 v66, v36, v37
	v_cvt_pk_bf16_f32 v67, v38, v39
	v_cvt_pk_bf16_f32 v68, v40, v41
	v_cvt_pk_bf16_f32 v69, v42, v43
	v_cvt_pk_bf16_f32 v70, v44, v45
	v_cvt_pk_bf16_f32 v71, v46, v47
	v_pk_add_f32 v[232:233], v[232:233], v[32:33]
	v_pk_add_f32 v[232:233], v[232:233], v[34:35]
	v_pk_add_f32 v[232:233], v[232:233], v[36:37]
	v_pk_add_f32 v[232:233], v[232:233], v[38:39]
	v_pk_add_f32 v[232:233], v[232:233], v[40:41]
	v_pk_add_f32 v[232:233], v[232:233], v[42:43]
	v_pk_add_f32 v[232:233], v[232:233], v[44:45]
	v_pk_add_f32 v[232:233], v[232:233], v[46:47]
	ds_read2_b32 v[32:33], v115 offset0:128 offset1:129
	ds_read2_b32 v[34:35], v115 offset0:130 offset1:131
	ds_read2_b32 v[36:37], v115 offset0:136 offset1:137
	ds_read2_b32 v[38:39], v115 offset0:138 offset1:139
	ds_read2_b32 v[40:41], v115 offset0:144 offset1:145
	ds_read2_b32 v[42:43], v115 offset0:146 offset1:147
	ds_read2_b32 v[44:45], v115 offset0:152 offset1:153
	ds_read2_b32 v[46:47], v115 offset0:154 offset1:155
	v_mfma_f32_32x32x16_bf16 v[0:15], v[64:67], v[72:75], v[0:15]
	v_mfma_f32_32x32x16_bf16 v[16:31], v[64:67], v[76:79], v[16:31]
	v_mfma_f32_32x32x16_bf16 v[0:15], v[68:71], v[220:223], v[0:15]
	v_mfma_f32_32x32x16_bf16 v[16:31], v[68:71], v[224:227], v[16:31]
	s_add_i32 s90, s76, 384
	v_add_u32_e32 v80, s90, v239
	v_add_u32_e32 v83, s90, v240
	v_add_u32_e32 v99, s90, v241
	v_add_u32_e32 v253, s90, v242
	v_add_u32_e32 v254, s90, v101
	v_add_u32_e32 v255, s90, v150
	v_med3_i32 v80, v80, 0, s99
	v_med3_i32 v83, v83, 0, s99
	v_med3_i32 v99, v99, 0, s99
	v_med3_i32 v253, v253, 0, s99
	v_med3_i32 v254, v254, 0, s99
	v_med3_i32 v255, v255, 0, s99
	v_mad_u32_u24 v80, v80, s100, v252
	v_mad_u32_u24 v83, v83, s100, v252
	v_mad_u32_u24 v99, v99, s100, v252
	v_mad_u32_u24 v253, v253, s100, v252
	v_mad_u32_u24 v254, v254, s100, v153
	v_mad_u32_u24 v255, v255, s100, v153
	global_load_dwordx4 v[156:159], v80, s[82:83]
	global_load_dwordx4 v[160:163], v83, s[82:83]
	global_load_dwordx4 v[164:167], v99, s[82:83]
	global_load_dwordx4 v[168:171], v253, s[82:83]
	global_load_dwordx4 v[172:175], v254, s[82:83] offset:768
	global_load_dwordx4 v[176:179], v255, s[82:83] offset:768
	global_load_dwordx4 v[180:183], v254, s[82:83] offset:832
	global_load_dwordx4 v[184:187], v255, s[82:83] offset:832
	ds_read_b64_tr_b16 v[72:73], v231
	ds_read_b64_tr_b16 v[74:75], v231 offset:512
	ds_read_b64_tr_b16 v[76:77], v231 offset:2048
	ds_read_b64_tr_b16 v[78:79], v231 offset:2560
	ds_read_b64_tr_b16 v[220:221], v231 offset:1024
	ds_read_b64_tr_b16 v[222:223], v231 offset:1536
	ds_read_b64_tr_b16 v[224:225], v231 offset:3072
	ds_read_b64_tr_b16 v[226:227], v231 offset:3584
	v_exp_f32_e32 v188, v188
	v_exp_f32_e32 v189, v189
	v_exp_f32_e32 v190, v190
	v_exp_f32_e32 v191, v191
	s_waitcnt vmcnt(8)
	ds_write_b128 v247, v[116:119]
	ds_write_b128 v247, v[120:123] offset:1024
	ds_write_b128 v247, v[124:127] offset:2048
	ds_write_b128 v247, v[128:131] offset:3072
	ds_read_b128 v[116:119], v248
	ds_read_b128 v[120:123], v249
	ds_read_b128 v[124:127], v250
	ds_read_b128 v[128:131], v251
	ds_write_b128 v112, v[132:135]
	ds_write_b128 v112, v[136:139] offset:1024
	ds_write_b128 v112, v[140:143] offset:2048
	ds_write_b128 v112, v[144:147] offset:3072
	v_exp_f32_e32 v192, v192
	v_exp_f32_e32 v193, v193
	v_exp_f32_e32 v194, v194
	v_exp_f32_e32 v195, v195
	s_waitcnt lgkmcnt(4)
	v_mfma_f32_32x32x16_bf16 v[32:47], v[116:119], v[48:51], v[32:47]
	v_exp_f32_e32 v196, v196
	v_exp_f32_e32 v197, v197
	v_mfma_f32_32x32x16_bf16 v[32:47], v[120:123], v[52:55], v[32:47]
	v_exp_f32_e32 v198, v198
	v_exp_f32_e32 v199, v199
	v_mfma_f32_32x32x16_bf16 v[32:47], v[124:127], v[56:59], v[32:47]
	v_exp_f32_e32 v200, v200
	v_exp_f32_e32 v201, v201
	v_mfma_f32_32x32x16_bf16 v[32:47], v[128:131], v[60:63], v[32:47]
	v_exp_f32_e32 v202, v202
	v_exp_f32_e32 v203, v203
	s_add_i32 s90, s76, 128
	v_lshlrev_b32_e32 v84, 2, v107
	v_add_u32_e32 v84, s90, v84
	v_add_u32_e32 v85, 0, v84
	v_add_u32_e32 v86, 4, v84
	v_add_u32_e32 v87, 8, v84
	v_add_u32_e32 v88, 12, v84
	v_cmp_gt_u32_e64 s[30:31], s98, v85
	v_cmp_gt_u32_e64 s[36:37], s98, v86
	v_cmp_gt_u32_e64 s[78:79], s98, v87
	v_cmp_gt_u32_e64 s[50:51], s98, v88
	v_cndmask_b32_e64 v188, 0, v188, s[30:31]
	v_add_u32_e32 v85, 32, v84
	v_cmp_gt_u32_e64 s[30:31], s98, v85
	v_cndmask_b32_e64 v189, 0, v189, s[36:37]
	v_add_u32_e32 v86, 36, v84
	v_cmp_gt_u32_e64 s[36:37], s98, v86
	v_cndmask_b32_e64 v190, 0, v190, s[78:79]
	v_add_u32_e32 v87, 40, v84
	v_cmp_gt_u32_e64 s[78:79], s98, v87
	v_cndmask_b32_e64 v191, 0, v191, s[50:51]
	v_add_u32_e32 v88, 44, v84
	v_cmp_gt_u32_e64 s[50:51], s98, v88
	v_cndmask_b32_e64 v192, 0, v192, s[30:31]
	v_add_u32_e32 v85, 64, v84
	v_cmp_gt_u32_e64 s[30:31], s98, v85
	v_cndmask_b32_e64 v193, 0, v193, s[36:37]
	v_add_u32_e32 v86, 68, v84
	v_cmp_gt_u32_e64 s[36:37], s98, v86
	v_cndmask_b32_e64 v194, 0, v194, s[78:79]
	v_add_u32_e32 v87, 72, v84
	v_cmp_gt_u32_e64 s[78:79], s98, v87
	v_cndmask_b32_e64 v195, 0, v195, s[50:51]
	v_add_u32_e32 v88, 76, v84
	v_cmp_gt_u32_e64 s[50:51], s98, v88
	v_cndmask_b32_e64 v196, 0, v196, s[30:31]
	v_add_u32_e32 v85, 96, v84
	v_cmp_gt_u32_e64 s[30:31], s98, v85
	v_cndmask_b32_e64 v197, 0, v197, s[36:37]
	v_add_u32_e32 v86, 100, v84
	v_cmp_gt_u32_e64 s[36:37], s98, v86
	v_cndmask_b32_e64 v198, 0, v198, s[78:79]
	v_add_u32_e32 v87, 104, v84
	v_cmp_gt_u32_e64 s[78:79], s98, v87
	v_cndmask_b32_e64 v199, 0, v199, s[50:51]
	v_add_u32_e32 v88, 108, v84
	v_cmp_gt_u32_e64 s[50:51], s98, v88
	v_nop
	v_cndmask_b32_e64 v200, 0, v200, s[30:31]
	v_cndmask_b32_e64 v201, 0, v201, s[36:37]
	v_cndmask_b32_e64 v202, 0, v202, s[78:79]
	v_cndmask_b32_e64 v203, 0, v203, s[50:51]
	v_cvt_pk_bf16_f32 v64, v188, v189
	v_cvt_pk_bf16_f32 v65, v190, v191
	v_cvt_pk_bf16_f32 v66, v192, v193
	v_cvt_pk_bf16_f32 v67, v194, v195
	v_cvt_pk_bf16_f32 v68, v196, v197
	v_cvt_pk_bf16_f32 v69, v198, v199
	v_cvt_pk_bf16_f32 v70, v200, v201
	v_cvt_pk_bf16_f32 v71, v202, v203
	v_pk_add_f32 v[232:233], v[232:233], v[188:189]
	v_pk_add_f32 v[232:233], v[232:233], v[190:191]
	v_pk_add_f32 v[232:233], v[232:233], v[192:193]
	v_pk_add_f32 v[232:233], v[232:233], v[194:195]
	v_pk_add_f32 v[232:233], v[232:233], v[196:197]
	v_pk_add_f32 v[232:233], v[232:233], v[198:199]
	v_pk_add_f32 v[232:233], v[232:233], v[200:201]
	v_pk_add_f32 v[232:233], v[232:233], v[202:203]
	ds_read2_b32 v[188:189], v115 offset0:160 offset1:161
	ds_read2_b32 v[190:191], v115 offset0:162 offset1:163
	ds_read2_b32 v[192:193], v115 offset0:168 offset1:169
	ds_read2_b32 v[194:195], v115 offset0:170 offset1:171
	ds_read2_b32 v[196:197], v115 offset0:176 offset1:177
	ds_read2_b32 v[198:199], v115 offset0:178 offset1:179
	ds_read2_b32 v[200:201], v115 offset0:184 offset1:185
	ds_read2_b32 v[202:203], v115 offset0:186 offset1:187
	v_mfma_f32_32x32x16_bf16 v[0:15], v[64:67], v[72:75], v[0:15]
	v_mfma_f32_32x32x16_bf16 v[16:31], v[64:67], v[76:79], v[16:31]
	v_mfma_f32_32x32x16_bf16 v[0:15], v[68:71], v[220:223], v[0:15]
	v_mfma_f32_32x32x16_bf16 v[16:31], v[68:71], v[224:227], v[16:31]
	s_add_i32 s90, s76, 512
	v_add_u32_e32 v80, s90, v239
	v_add_u32_e32 v83, s90, v240
	v_add_u32_e32 v99, s90, v241
	v_add_u32_e32 v253, s90, v242
	v_add_u32_e32 v254, s90, v101
	v_add_u32_e32 v255, s90, v150
	v_med3_i32 v80, v80, 0, s99
	v_med3_i32 v83, v83, 0, s99
	v_med3_i32 v99, v99, 0, s99
	v_med3_i32 v253, v253, 0, s99
	v_med3_i32 v254, v254, 0, s99
	v_med3_i32 v255, v255, 0, s99
	v_mad_u32_u24 v80, v80, s100, v252
	v_mad_u32_u24 v83, v83, s100, v252
	v_mad_u32_u24 v99, v99, s100, v252
	v_mad_u32_u24 v253, v253, s100, v252
	v_mad_u32_u24 v254, v254, s100, v153
	v_mad_u32_u24 v255, v255, s100, v153
	global_load_dwordx4 v[116:119], v80, s[82:83]
	global_load_dwordx4 v[120:123], v83, s[82:83]
	global_load_dwordx4 v[124:127], v99, s[82:83]
	global_load_dwordx4 v[128:131], v253, s[82:83]
	global_load_dwordx4 v[132:135], v254, s[82:83] offset:768
	global_load_dwordx4 v[136:139], v255, s[82:83] offset:768
	global_load_dwordx4 v[140:143], v254, s[82:83] offset:832
	global_load_dwordx4 v[144:147], v255, s[82:83] offset:832
	ds_read_b64_tr_b16 v[72:73], v231
	ds_read_b64_tr_b16 v[74:75], v231 offset:512
	ds_read_b64_tr_b16 v[76:77], v231 offset:2048
	ds_read_b64_tr_b16 v[78:79], v231 offset:2560
	ds_read_b64_tr_b16 v[220:221], v231 offset:1024
	ds_read_b64_tr_b16 v[222:223], v231 offset:1536
	ds_read_b64_tr_b16 v[224:225], v231 offset:3072
	ds_read_b64_tr_b16 v[226:227], v231 offset:3584
	v_exp_f32_e32 v32, v32
	v_exp_f32_e32 v33, v33
	v_exp_f32_e32 v34, v34
	v_exp_f32_e32 v35, v35
	s_waitcnt vmcnt(8)
	ds_write_b128 v247, v[156:159]
	ds_write_b128 v247, v[160:163] offset:1024
	ds_write_b128 v247, v[164:167] offset:2048
	ds_write_b128 v247, v[168:171] offset:3072
	ds_read_b128 v[156:159], v248
	ds_read_b128 v[160:163], v249
	ds_read_b128 v[164:167], v250
	ds_read_b128 v[168:171], v251
	ds_write_b128 v112, v[172:175]
	ds_write_b128 v112, v[176:179] offset:1024
	ds_write_b128 v112, v[180:183] offset:2048
	ds_write_b128 v112, v[184:187] offset:3072
	v_exp_f32_e32 v36, v36
	v_exp_f32_e32 v37, v37
	v_exp_f32_e32 v38, v38
	v_exp_f32_e32 v39, v39
	s_waitcnt lgkmcnt(4)
	v_mfma_f32_32x32x16_bf16 v[188:203], v[156:159], v[48:51], v[188:203]
	v_exp_f32_e32 v40, v40
	v_exp_f32_e32 v41, v41
	v_mfma_f32_32x32x16_bf16 v[188:203], v[160:163], v[52:55], v[188:203]
	v_exp_f32_e32 v42, v42
	v_exp_f32_e32 v43, v43
	v_mfma_f32_32x32x16_bf16 v[188:203], v[164:167], v[56:59], v[188:203]
	v_exp_f32_e32 v44, v44
	v_exp_f32_e32 v45, v45
	v_mfma_f32_32x32x16_bf16 v[188:203], v[168:171], v[60:63], v[188:203]
	v_exp_f32_e32 v46, v46
	v_exp_f32_e32 v47, v47
	s_add_i32 s90, s76, 256
	v_lshlrev_b32_e32 v84, 2, v107
	v_add_u32_e32 v84, s90, v84
	v_add_u32_e32 v85, 0, v84
	v_add_u32_e32 v86, 4, v84
	v_add_u32_e32 v87, 8, v84
	v_add_u32_e32 v88, 12, v84
	v_cmp_gt_u32_e64 s[30:31], s98, v85
	v_cmp_gt_u32_e64 s[36:37], s98, v86
	v_cmp_gt_u32_e64 s[78:79], s98, v87
	v_cmp_gt_u32_e64 s[50:51], s98, v88
	v_cndmask_b32_e64 v32, 0, v32, s[30:31]
	v_add_u32_e32 v85, 32, v84
	v_cmp_gt_u32_e64 s[30:31], s98, v85
	v_cndmask_b32_e64 v33, 0, v33, s[36:37]
	v_add_u32_e32 v86, 36, v84
	v_cmp_gt_u32_e64 s[36:37], s98, v86
	v_cndmask_b32_e64 v34, 0, v34, s[78:79]
	v_add_u32_e32 v87, 40, v84
	v_cmp_gt_u32_e64 s[78:79], s98, v87
	v_cndmask_b32_e64 v35, 0, v35, s[50:51]
	v_add_u32_e32 v88, 44, v84
	v_cmp_gt_u32_e64 s[50:51], s98, v88
	v_cndmask_b32_e64 v36, 0, v36, s[30:31]
	v_add_u32_e32 v85, 64, v84
	v_cmp_gt_u32_e64 s[30:31], s98, v85
	v_cndmask_b32_e64 v37, 0, v37, s[36:37]
	v_add_u32_e32 v86, 68, v84
	v_cmp_gt_u32_e64 s[36:37], s98, v86
	v_cndmask_b32_e64 v38, 0, v38, s[78:79]
	v_add_u32_e32 v87, 72, v84
	v_cmp_gt_u32_e64 s[78:79], s98, v87
	v_cndmask_b32_e64 v39, 0, v39, s[50:51]
	v_add_u32_e32 v88, 76, v84
	v_cmp_gt_u32_e64 s[50:51], s98, v88
	v_cndmask_b32_e64 v40, 0, v40, s[30:31]
	v_add_u32_e32 v85, 96, v84
	v_cmp_gt_u32_e64 s[30:31], s98, v85
	v_cndmask_b32_e64 v41, 0, v41, s[36:37]
	v_add_u32_e32 v86, 100, v84
	v_cmp_gt_u32_e64 s[36:37], s98, v86
	v_cndmask_b32_e64 v42, 0, v42, s[78:79]
	v_add_u32_e32 v87, 104, v84
	v_cmp_gt_u32_e64 s[78:79], s98, v87
	v_cndmask_b32_e64 v43, 0, v43, s[50:51]
	v_add_u32_e32 v88, 108, v84
	v_cmp_gt_u32_e64 s[50:51], s98, v88
	v_nop
	v_cndmask_b32_e64 v44, 0, v44, s[30:31]
	v_cndmask_b32_e64 v45, 0, v45, s[36:37]
	v_cndmask_b32_e64 v46, 0, v46, s[78:79]
	v_cndmask_b32_e64 v47, 0, v47, s[50:51]
	v_cvt_pk_bf16_f32 v64, v32, v33
	v_cvt_pk_bf16_f32 v65, v34, v35
	v_cvt_pk_bf16_f32 v66, v36, v37
	v_cvt_pk_bf16_f32 v67, v38, v39
	v_cvt_pk_bf16_f32 v68, v40, v41
	v_cvt_pk_bf16_f32 v69, v42, v43
	v_cvt_pk_bf16_f32 v70, v44, v45
	v_cvt_pk_bf16_f32 v71, v46, v47
	v_pk_add_f32 v[232:233], v[232:233], v[32:33]
	v_pk_add_f32 v[232:233], v[232:233], v[34:35]
	v_pk_add_f32 v[232:233], v[232:233], v[36:37]
	v_pk_add_f32 v[232:233], v[232:233], v[38:39]
	v_pk_add_f32 v[232:233], v[232:233], v[40:41]
	v_pk_add_f32 v[232:233], v[232:233], v[42:43]
	v_pk_add_f32 v[232:233], v[232:233], v[44:45]
	v_pk_add_f32 v[232:233], v[232:233], v[46:47]
	ds_read2_b32 v[32:33], v115 offset0:192 offset1:193
	ds_read2_b32 v[34:35], v115 offset0:194 offset1:195
	ds_read2_b32 v[36:37], v115 offset0:200 offset1:201
	ds_read2_b32 v[38:39], v115 offset0:202 offset1:203
	ds_read2_b32 v[40:41], v115 offset0:208 offset1:209
	ds_read2_b32 v[42:43], v115 offset0:210 offset1:211
	ds_read2_b32 v[44:45], v115 offset0:216 offset1:217
	ds_read2_b32 v[46:47], v115 offset0:218 offset1:219
	v_mfma_f32_32x32x16_bf16 v[0:15], v[64:67], v[72:75], v[0:15]
	v_mfma_f32_32x32x16_bf16 v[16:31], v[64:67], v[76:79], v[16:31]
	v_mfma_f32_32x32x16_bf16 v[0:15], v[68:71], v[220:223], v[0:15]
	v_mfma_f32_32x32x16_bf16 v[16:31], v[68:71], v[224:227], v[16:31]
	s_add_i32 s90, s76, 640
	v_add_u32_e32 v80, s90, v239
	v_add_u32_e32 v83, s90, v240
	v_add_u32_e32 v99, s90, v241
	v_add_u32_e32 v253, s90, v242
	v_add_u32_e32 v254, s90, v101
	v_add_u32_e32 v255, s90, v150
	v_med3_i32 v80, v80, 0, s99
	v_med3_i32 v83, v83, 0, s99
	v_med3_i32 v99, v99, 0, s99
	v_med3_i32 v253, v253, 0, s99
	v_med3_i32 v254, v254, 0, s99
	v_med3_i32 v255, v255, 0, s99
	v_mad_u32_u24 v80, v80, s100, v252
	v_mad_u32_u24 v83, v83, s100, v252
	v_mad_u32_u24 v99, v99, s100, v252
	v_mad_u32_u24 v253, v253, s100, v252
	v_mad_u32_u24 v254, v254, s100, v153
	v_mad_u32_u24 v255, v255, s100, v153
	global_load_dwordx4 v[156:159], v80, s[82:83]
	global_load_dwordx4 v[160:163], v83, s[82:83]
	global_load_dwordx4 v[164:167], v99, s[82:83]
	global_load_dwordx4 v[168:171], v253, s[82:83]
	global_load_dwordx4 v[172:175], v254, s[82:83] offset:768
	global_load_dwordx4 v[176:179], v255, s[82:83] offset:768
	global_load_dwordx4 v[180:183], v254, s[82:83] offset:832
	global_load_dwordx4 v[184:187], v255, s[82:83] offset:832
	ds_read_b64_tr_b16 v[72:73], v231
	ds_read_b64_tr_b16 v[74:75], v231 offset:512
	ds_read_b64_tr_b16 v[76:77], v231 offset:2048
	ds_read_b64_tr_b16 v[78:79], v231 offset:2560
	ds_read_b64_tr_b16 v[220:221], v231 offset:1024
	ds_read_b64_tr_b16 v[222:223], v231 offset:1536
	ds_read_b64_tr_b16 v[224:225], v231 offset:3072
	ds_read_b64_tr_b16 v[226:227], v231 offset:3584
	v_exp_f32_e32 v188, v188
	v_exp_f32_e32 v189, v189
	v_exp_f32_e32 v190, v190
	v_exp_f32_e32 v191, v191
	s_waitcnt vmcnt(8)
	ds_write_b128 v247, v[116:119]
	ds_write_b128 v247, v[120:123] offset:1024
	ds_write_b128 v247, v[124:127] offset:2048
	ds_write_b128 v247, v[128:131] offset:3072
	ds_read_b128 v[116:119], v248
	ds_read_b128 v[120:123], v249
	ds_read_b128 v[124:127], v250
	ds_read_b128 v[128:131], v251
	ds_write_b128 v112, v[132:135]
	ds_write_b128 v112, v[136:139] offset:1024
	ds_write_b128 v112, v[140:143] offset:2048
	ds_write_b128 v112, v[144:147] offset:3072
	v_exp_f32_e32 v192, v192
	v_exp_f32_e32 v193, v193
	v_exp_f32_e32 v194, v194
	v_exp_f32_e32 v195, v195
	s_waitcnt lgkmcnt(4)
	v_mfma_f32_32x32x16_bf16 v[32:47], v[116:119], v[48:51], v[32:47]
	v_exp_f32_e32 v196, v196
	v_exp_f32_e32 v197, v197
	v_mfma_f32_32x32x16_bf16 v[32:47], v[120:123], v[52:55], v[32:47]
	v_exp_f32_e32 v198, v198
	v_exp_f32_e32 v199, v199
	v_mfma_f32_32x32x16_bf16 v[32:47], v[124:127], v[56:59], v[32:47]
	v_exp_f32_e32 v200, v200
	v_exp_f32_e32 v201, v201
	v_mfma_f32_32x32x16_bf16 v[32:47], v[128:131], v[60:63], v[32:47]
	v_exp_f32_e32 v202, v202
	v_exp_f32_e32 v203, v203
	s_add_i32 s90, s76, 384
	v_lshlrev_b32_e32 v84, 2, v107
	v_add_u32_e32 v84, s90, v84
	v_add_u32_e32 v85, 0, v84
	v_add_u32_e32 v86, 4, v84
	v_add_u32_e32 v87, 8, v84
	v_add_u32_e32 v88, 12, v84
	v_cmp_gt_u32_e64 s[30:31], s98, v85
	v_cmp_gt_u32_e64 s[36:37], s98, v86
	v_cmp_gt_u32_e64 s[78:79], s98, v87
	v_cmp_gt_u32_e64 s[50:51], s98, v88
	v_cndmask_b32_e64 v188, 0, v188, s[30:31]
	v_add_u32_e32 v85, 32, v84
	v_cmp_gt_u32_e64 s[30:31], s98, v85
	v_cndmask_b32_e64 v189, 0, v189, s[36:37]
	v_add_u32_e32 v86, 36, v84
	v_cmp_gt_u32_e64 s[36:37], s98, v86
	v_cndmask_b32_e64 v190, 0, v190, s[78:79]
	v_add_u32_e32 v87, 40, v84
	v_cmp_gt_u32_e64 s[78:79], s98, v87
	v_cndmask_b32_e64 v191, 0, v191, s[50:51]
	v_add_u32_e32 v88, 44, v84
	v_cmp_gt_u32_e64 s[50:51], s98, v88
	v_cndmask_b32_e64 v192, 0, v192, s[30:31]
	v_add_u32_e32 v85, 64, v84
	v_cmp_gt_u32_e64 s[30:31], s98, v85
	v_cndmask_b32_e64 v193, 0, v193, s[36:37]
	v_add_u32_e32 v86, 68, v84
	v_cmp_gt_u32_e64 s[36:37], s98, v86
	v_cndmask_b32_e64 v194, 0, v194, s[78:79]
	v_add_u32_e32 v87, 72, v84
	v_cmp_gt_u32_e64 s[78:79], s98, v87
	v_cndmask_b32_e64 v195, 0, v195, s[50:51]
	v_add_u32_e32 v88, 76, v84
	v_cmp_gt_u32_e64 s[50:51], s98, v88
	v_cndmask_b32_e64 v196, 0, v196, s[30:31]
	v_add_u32_e32 v85, 96, v84
	v_cmp_gt_u32_e64 s[30:31], s98, v85
	v_cndmask_b32_e64 v197, 0, v197, s[36:37]
	v_add_u32_e32 v86, 100, v84
	v_cmp_gt_u32_e64 s[36:37], s98, v86
	v_cndmask_b32_e64 v198, 0, v198, s[78:79]
	v_add_u32_e32 v87, 104, v84
	v_cmp_gt_u32_e64 s[78:79], s98, v87
	v_cndmask_b32_e64 v199, 0, v199, s[50:51]
	v_add_u32_e32 v88, 108, v84
	v_cmp_gt_u32_e64 s[50:51], s98, v88
	v_nop
	v_cndmask_b32_e64 v200, 0, v200, s[30:31]
	v_cndmask_b32_e64 v201, 0, v201, s[36:37]
	v_cndmask_b32_e64 v202, 0, v202, s[78:79]
	v_cndmask_b32_e64 v203, 0, v203, s[50:51]
	v_cvt_pk_bf16_f32 v64, v188, v189
	v_cvt_pk_bf16_f32 v65, v190, v191
	v_cvt_pk_bf16_f32 v66, v192, v193
	v_cvt_pk_bf16_f32 v67, v194, v195
	v_cvt_pk_bf16_f32 v68, v196, v197
	v_cvt_pk_bf16_f32 v69, v198, v199
	v_cvt_pk_bf16_f32 v70, v200, v201
	v_cvt_pk_bf16_f32 v71, v202, v203
	v_pk_add_f32 v[232:233], v[232:233], v[188:189]
	v_pk_add_f32 v[232:233], v[232:233], v[190:191]
	v_pk_add_f32 v[232:233], v[232:233], v[192:193]
	v_pk_add_f32 v[232:233], v[232:233], v[194:195]
	v_pk_add_f32 v[232:233], v[232:233], v[196:197]
	v_pk_add_f32 v[232:233], v[232:233], v[198:199]
	v_pk_add_f32 v[232:233], v[232:233], v[200:201]
	v_pk_add_f32 v[232:233], v[232:233], v[202:203]
	ds_read2_b32 v[188:189], v115 offset0:224 offset1:225
	ds_read2_b32 v[190:191], v115 offset0:226 offset1:227
	ds_read2_b32 v[192:193], v115 offset0:232 offset1:233
	ds_read2_b32 v[194:195], v115 offset0:234 offset1:235
	ds_read2_b32 v[196:197], v115 offset0:240 offset1:241
	ds_read2_b32 v[198:199], v115 offset0:242 offset1:243
	ds_read2_b32 v[200:201], v115 offset0:248 offset1:249
	ds_read2_b32 v[202:203], v115 offset0:250 offset1:251
	v_mfma_f32_32x32x16_bf16 v[0:15], v[64:67], v[72:75], v[0:15]
	v_mfma_f32_32x32x16_bf16 v[16:31], v[64:67], v[76:79], v[16:31]
	v_mfma_f32_32x32x16_bf16 v[0:15], v[68:71], v[220:223], v[0:15]
	v_mfma_f32_32x32x16_bf16 v[16:31], v[68:71], v[224:227], v[16:31]
	s_add_i32 s90, s76, -1024
	v_add_u32_e32 v80, s90, v243
	v_add_u32_e32 v83, s90, v244
	v_add_u32_e32 v99, s90, v245
	v_add_u32_e32 v253, s90, v246
	v_add_u32_e32 v254, s90, v148
	v_add_u32_e32 v255, s90, v151
	v_med3_i32 v80, v80, 0, s99
	v_med3_i32 v83, v83, 0, s99
	v_med3_i32 v99, v99, 0, s99
	v_med3_i32 v253, v253, 0, s99
	v_med3_i32 v254, v254, 0, s99
	v_med3_i32 v255, v255, 0, s99
	v_mad_u32_u24 v80, v80, s100, v252
	v_mad_u32_u24 v83, v83, s100, v252
	v_mad_u32_u24 v99, v99, s100, v252
	v_mad_u32_u24 v253, v253, s100, v252
	v_mad_u32_u24 v254, v254, s100, v153
	v_mad_u32_u24 v255, v255, s100, v153
	global_load_dwordx4 v[116:119], v80, s[82:83]
	global_load_dwordx4 v[120:123], v83, s[82:83]
	global_load_dwordx4 v[124:127], v99, s[82:83]
	global_load_dwordx4 v[128:131], v253, s[82:83]
	global_load_dwordx4 v[132:135], v254, s[82:83] offset:768
	global_load_dwordx4 v[136:139], v255, s[82:83] offset:768
	global_load_dwordx4 v[140:143], v254, s[82:83] offset:832
	global_load_dwordx4 v[144:147], v255, s[82:83] offset:832
	ds_read_b64_tr_b16 v[72:73], v231
	ds_read_b64_tr_b16 v[74:75], v231 offset:512
	ds_read_b64_tr_b16 v[76:77], v231 offset:2048
	ds_read_b64_tr_b16 v[78:79], v231 offset:2560
	ds_read_b64_tr_b16 v[220:221], v231 offset:1024
	ds_read_b64_tr_b16 v[222:223], v231 offset:1536
	ds_read_b64_tr_b16 v[224:225], v231 offset:3072
	ds_read_b64_tr_b16 v[226:227], v231 offset:3584
	v_exp_f32_e32 v32, v32
	v_exp_f32_e32 v33, v33
	v_exp_f32_e32 v34, v34
	v_exp_f32_e32 v35, v35
	s_waitcnt vmcnt(8)
	ds_write_b128 v247, v[156:159]
	ds_write_b128 v247, v[160:163] offset:1024
	ds_write_b128 v247, v[164:167] offset:2048
	ds_write_b128 v247, v[168:171] offset:3072
	ds_read_b128 v[156:159], v248
	ds_read_b128 v[160:163], v249
	ds_read_b128 v[164:167], v250
	ds_read_b128 v[168:171], v251
	ds_write_b128 v112, v[172:175]
	ds_write_b128 v112, v[176:179] offset:1024
	ds_write_b128 v112, v[180:183] offset:2048
	ds_write_b128 v112, v[184:187] offset:3072
	v_exp_f32_e32 v36, v36
	v_exp_f32_e32 v37, v37
	v_exp_f32_e32 v38, v38
	v_exp_f32_e32 v39, v39
	s_waitcnt lgkmcnt(4)
	v_mfma_f32_32x32x16_bf16 v[188:203], v[156:159], v[48:51], v[188:203]
	v_exp_f32_e32 v40, v40
	v_exp_f32_e32 v41, v41
	v_mfma_f32_32x32x16_bf16 v[188:203], v[160:163], v[52:55], v[188:203]
	v_exp_f32_e32 v42, v42
	v_exp_f32_e32 v43, v43
	v_mfma_f32_32x32x16_bf16 v[188:203], v[164:167], v[56:59], v[188:203]
	v_exp_f32_e32 v44, v44
	v_exp_f32_e32 v45, v45
	v_mfma_f32_32x32x16_bf16 v[188:203], v[168:171], v[60:63], v[188:203]
	v_exp_f32_e32 v46, v46
	v_exp_f32_e32 v47, v47
	s_add_i32 s90, s76, 512
	v_lshlrev_b32_e32 v84, 2, v107
	v_add_u32_e32 v84, s90, v84
	v_add_u32_e32 v85, 0, v84
	v_add_u32_e32 v86, 4, v84
	v_add_u32_e32 v87, 8, v84
	v_add_u32_e32 v88, 12, v84
	v_cmp_gt_u32_e64 s[30:31], s98, v85
	v_cmp_gt_u32_e64 s[36:37], s98, v86
	v_cmp_gt_u32_e64 s[78:79], s98, v87
	v_cmp_gt_u32_e64 s[50:51], s98, v88
	v_cndmask_b32_e64 v32, 0, v32, s[30:31]
	v_add_u32_e32 v85, 32, v84
	v_cmp_gt_u32_e64 s[30:31], s98, v85
	v_cndmask_b32_e64 v33, 0, v33, s[36:37]
	v_add_u32_e32 v86, 36, v84
	v_cmp_gt_u32_e64 s[36:37], s98, v86
	v_cndmask_b32_e64 v34, 0, v34, s[78:79]
	v_add_u32_e32 v87, 40, v84
	v_cmp_gt_u32_e64 s[78:79], s98, v87
	v_cndmask_b32_e64 v35, 0, v35, s[50:51]
	v_add_u32_e32 v88, 44, v84
	v_cmp_gt_u32_e64 s[50:51], s98, v88
	v_cndmask_b32_e64 v36, 0, v36, s[30:31]
	v_add_u32_e32 v85, 64, v84
	v_cmp_gt_u32_e64 s[30:31], s98, v85
	v_cndmask_b32_e64 v37, 0, v37, s[36:37]
	v_add_u32_e32 v86, 68, v84
	v_cmp_gt_u32_e64 s[36:37], s98, v86
	v_cndmask_b32_e64 v38, 0, v38, s[78:79]
	v_add_u32_e32 v87, 72, v84
	v_cmp_gt_u32_e64 s[78:79], s98, v87
	v_cndmask_b32_e64 v39, 0, v39, s[50:51]
	v_add_u32_e32 v88, 76, v84
	v_cmp_gt_u32_e64 s[50:51], s98, v88
	v_cndmask_b32_e64 v40, 0, v40, s[30:31]
	v_add_u32_e32 v85, 96, v84
	v_cmp_gt_u32_e64 s[30:31], s98, v85
	v_cndmask_b32_e64 v41, 0, v41, s[36:37]
	v_add_u32_e32 v86, 100, v84
	v_cmp_gt_u32_e64 s[36:37], s98, v86
	v_cndmask_b32_e64 v42, 0, v42, s[78:79]
	v_add_u32_e32 v87, 104, v84
	v_cmp_gt_u32_e64 s[78:79], s98, v87
	v_cndmask_b32_e64 v43, 0, v43, s[50:51]
	v_add_u32_e32 v88, 108, v84
	v_cmp_gt_u32_e64 s[50:51], s98, v88
	v_nop
	v_cndmask_b32_e64 v44, 0, v44, s[30:31]
	v_cndmask_b32_e64 v45, 0, v45, s[36:37]
	v_cndmask_b32_e64 v46, 0, v46, s[78:79]
	v_cndmask_b32_e64 v47, 0, v47, s[50:51]
	v_cvt_pk_bf16_f32 v64, v32, v33
	v_cvt_pk_bf16_f32 v65, v34, v35
	v_cvt_pk_bf16_f32 v66, v36, v37
	v_cvt_pk_bf16_f32 v67, v38, v39
	v_cvt_pk_bf16_f32 v68, v40, v41
	v_cvt_pk_bf16_f32 v69, v42, v43
	v_cvt_pk_bf16_f32 v70, v44, v45
	v_cvt_pk_bf16_f32 v71, v46, v47
	v_pk_add_f32 v[232:233], v[232:233], v[32:33]
	v_pk_add_f32 v[232:233], v[232:233], v[34:35]
	v_pk_add_f32 v[232:233], v[232:233], v[36:37]
	v_pk_add_f32 v[232:233], v[232:233], v[38:39]
	v_pk_add_f32 v[232:233], v[232:233], v[40:41]
	v_pk_add_f32 v[232:233], v[232:233], v[42:43]
	v_pk_add_f32 v[232:233], v[232:233], v[44:45]
	v_pk_add_f32 v[232:233], v[232:233], v[46:47]
	v_mov_b32_e32 v115, v230
	ds_read2_b32 v[32:33], v115 offset0:0 offset1:1
	ds_read2_b32 v[34:35], v115 offset0:2 offset1:3
	ds_read2_b32 v[36:37], v115 offset0:8 offset1:9
	ds_read2_b32 v[38:39], v115 offset0:10 offset1:11
	ds_read2_b32 v[40:41], v115 offset0:16 offset1:17
	ds_read2_b32 v[42:43], v115 offset0:18 offset1:19
	ds_read2_b32 v[44:45], v115 offset0:24 offset1:25
	ds_read2_b32 v[46:47], v115 offset0:26 offset1:27
	v_mfma_f32_32x32x16_bf16 v[0:15], v[64:67], v[72:75], v[0:15]
	v_mfma_f32_32x32x16_bf16 v[16:31], v[64:67], v[76:79], v[16:31]
	v_mfma_f32_32x32x16_bf16 v[0:15], v[68:71], v[220:223], v[0:15]
	v_mfma_f32_32x32x16_bf16 v[16:31], v[68:71], v[224:227], v[16:31]
	s_add_i32 s90, s76, -512
	v_add_u32_e32 v80, s90, v243
	v_add_u32_e32 v83, s90, v244
	v_add_u32_e32 v99, s90, v245
	v_add_u32_e32 v253, s90, v246
	v_add_u32_e32 v254, s90, v148
	v_add_u32_e32 v255, s90, v151
	v_med3_i32 v80, v80, 0, s99
	v_med3_i32 v83, v83, 0, s99
	v_med3_i32 v99, v99, 0, s99
	v_med3_i32 v253, v253, 0, s99
	v_med3_i32 v254, v254, 0, s99
	v_med3_i32 v255, v255, 0, s99
	v_mad_u32_u24 v80, v80, s100, v252
	v_mad_u32_u24 v83, v83, s100, v252
	v_mad_u32_u24 v99, v99, s100, v252
	v_mad_u32_u24 v253, v253, s100, v252
	v_mad_u32_u24 v254, v254, s100, v153
	v_mad_u32_u24 v255, v255, s100, v153
	global_load_dwordx4 v[156:159], v80, s[82:83]
	global_load_dwordx4 v[160:163], v83, s[82:83]
	global_load_dwordx4 v[164:167], v99, s[82:83]
	global_load_dwordx4 v[168:171], v253, s[82:83]
	global_load_dwordx4 v[172:175], v254, s[82:83] offset:768
	global_load_dwordx4 v[176:179], v255, s[82:83] offset:768
	global_load_dwordx4 v[180:183], v254, s[82:83] offset:832
	global_load_dwordx4 v[184:187], v255, s[82:83] offset:832
	ds_read_b64_tr_b16 v[72:73], v231
	ds_read_b64_tr_b16 v[74:75], v231 offset:512
	ds_read_b64_tr_b16 v[76:77], v231 offset:2048
	ds_read_b64_tr_b16 v[78:79], v231 offset:2560
	ds_read_b64_tr_b16 v[220:221], v231 offset:1024
	ds_read_b64_tr_b16 v[222:223], v231 offset:1536
	ds_read_b64_tr_b16 v[224:225], v231 offset:3072
	ds_read_b64_tr_b16 v[226:227], v231 offset:3584
	v_exp_f32_e32 v188, v188
	v_exp_f32_e32 v189, v189
	v_exp_f32_e32 v190, v190
	v_exp_f32_e32 v191, v191
	s_waitcnt vmcnt(8)
	ds_write_b128 v247, v[116:119]
	ds_write_b128 v247, v[120:123] offset:1024
	ds_write_b128 v247, v[124:127] offset:2048
	ds_write_b128 v247, v[128:131] offset:3072
	ds_read_b128 v[116:119], v248
	ds_read_b128 v[120:123], v249
	ds_read_b128 v[124:127], v250
	ds_read_b128 v[128:131], v251
	ds_write_b128 v112, v[132:135]
	ds_write_b128 v112, v[136:139] offset:1024
	ds_write_b128 v112, v[140:143] offset:2048
	ds_write_b128 v112, v[144:147] offset:3072
	v_exp_f32_e32 v192, v192
	v_exp_f32_e32 v193, v193
	v_exp_f32_e32 v194, v194
	v_exp_f32_e32 v195, v195
	s_waitcnt lgkmcnt(4)
	v_mfma_f32_32x32x16_bf16 v[32:47], v[116:119], v[48:51], v[32:47]
	v_exp_f32_e32 v196, v196
	v_exp_f32_e32 v197, v197
	v_mfma_f32_32x32x16_bf16 v[32:47], v[120:123], v[52:55], v[32:47]
	v_exp_f32_e32 v198, v198
	v_exp_f32_e32 v199, v199
	v_mfma_f32_32x32x16_bf16 v[32:47], v[124:127], v[56:59], v[32:47]
	v_exp_f32_e32 v200, v200
	v_exp_f32_e32 v201, v201
	v_mfma_f32_32x32x16_bf16 v[32:47], v[128:131], v[60:63], v[32:47]
	v_exp_f32_e32 v202, v202
	v_exp_f32_e32 v203, v203
	s_add_i32 s90, s76, 640
	v_lshlrev_b32_e32 v84, 2, v107
	v_add_u32_e32 v84, s90, v84
	v_add_u32_e32 v85, 0, v84
	v_add_u32_e32 v86, 4, v84
	v_add_u32_e32 v87, 8, v84
	v_add_u32_e32 v88, 12, v84
	v_cmp_gt_u32_e64 s[30:31], s98, v85
	v_cmp_gt_u32_e64 s[36:37], s98, v86
	v_cmp_gt_u32_e64 s[78:79], s98, v87
	v_cmp_gt_u32_e64 s[50:51], s98, v88
	v_cndmask_b32_e64 v188, 0, v188, s[30:31]
	v_add_u32_e32 v85, 32, v84
	v_cmp_gt_u32_e64 s[30:31], s98, v85
	v_cndmask_b32_e64 v189, 0, v189, s[36:37]
	v_add_u32_e32 v86, 36, v84
	v_cmp_gt_u32_e64 s[36:37], s98, v86
	v_cndmask_b32_e64 v190, 0, v190, s[78:79]
	v_add_u32_e32 v87, 40, v84
	v_cmp_gt_u32_e64 s[78:79], s98, v87
	v_cndmask_b32_e64 v191, 0, v191, s[50:51]
	v_add_u32_e32 v88, 44, v84
	v_cmp_gt_u32_e64 s[50:51], s98, v88
	v_cndmask_b32_e64 v192, 0, v192, s[30:31]
	v_add_u32_e32 v85, 64, v84
	v_cmp_gt_u32_e64 s[30:31], s98, v85
	v_cndmask_b32_e64 v193, 0, v193, s[36:37]
	v_add_u32_e32 v86, 68, v84
	v_cmp_gt_u32_e64 s[36:37], s98, v86
	v_cndmask_b32_e64 v194, 0, v194, s[78:79]
	v_add_u32_e32 v87, 72, v84
	v_cmp_gt_u32_e64 s[78:79], s98, v87
	v_cndmask_b32_e64 v195, 0, v195, s[50:51]
	v_add_u32_e32 v88, 76, v84
	v_cmp_gt_u32_e64 s[50:51], s98, v88
	v_cndmask_b32_e64 v196, 0, v196, s[30:31]
	v_add_u32_e32 v85, 96, v84
	v_cmp_gt_u32_e64 s[30:31], s98, v85
	v_cndmask_b32_e64 v197, 0, v197, s[36:37]
	v_add_u32_e32 v86, 100, v84
	v_cmp_gt_u32_e64 s[36:37], s98, v86
	v_cndmask_b32_e64 v198, 0, v198, s[78:79]
	v_add_u32_e32 v87, 104, v84
	v_cmp_gt_u32_e64 s[78:79], s98, v87
	v_cndmask_b32_e64 v199, 0, v199, s[50:51]
	v_add_u32_e32 v88, 108, v84
	v_cmp_gt_u32_e64 s[50:51], s98, v88
	v_nop
	v_cndmask_b32_e64 v200, 0, v200, s[30:31]
	v_cndmask_b32_e64 v201, 0, v201, s[36:37]
	v_cndmask_b32_e64 v202, 0, v202, s[78:79]
	v_cndmask_b32_e64 v203, 0, v203, s[50:51]
	v_cvt_pk_bf16_f32 v64, v188, v189
	v_cvt_pk_bf16_f32 v65, v190, v191
	v_cvt_pk_bf16_f32 v66, v192, v193
	v_cvt_pk_bf16_f32 v67, v194, v195
	v_cvt_pk_bf16_f32 v68, v196, v197
	v_cvt_pk_bf16_f32 v69, v198, v199
	v_cvt_pk_bf16_f32 v70, v200, v201
	v_cvt_pk_bf16_f32 v71, v202, v203
	v_pk_add_f32 v[232:233], v[232:233], v[188:189]
	v_pk_add_f32 v[232:233], v[232:233], v[190:191]
	v_pk_add_f32 v[232:233], v[232:233], v[192:193]
	v_pk_add_f32 v[232:233], v[232:233], v[194:195]
	v_pk_add_f32 v[232:233], v[232:233], v[196:197]
	v_pk_add_f32 v[232:233], v[232:233], v[198:199]
	v_pk_add_f32 v[232:233], v[232:233], v[200:201]
	v_pk_add_f32 v[232:233], v[232:233], v[202:203]
	ds_read2_b32 v[188:189], v115 offset0:32 offset1:33
	ds_read2_b32 v[190:191], v115 offset0:34 offset1:35
	ds_read2_b32 v[192:193], v115 offset0:40 offset1:41
	ds_read2_b32 v[194:195], v115 offset0:42 offset1:43
	ds_read2_b32 v[196:197], v115 offset0:48 offset1:49
	ds_read2_b32 v[198:199], v115 offset0:50 offset1:51
	ds_read2_b32 v[200:201], v115 offset0:56 offset1:57
	ds_read2_b32 v[202:203], v115 offset0:58 offset1:59
	v_mfma_f32_32x32x16_bf16 v[0:15], v[64:67], v[72:75], v[0:15]
	v_mfma_f32_32x32x16_bf16 v[16:31], v[64:67], v[76:79], v[16:31]
	v_mfma_f32_32x32x16_bf16 v[0:15], v[68:71], v[220:223], v[0:15]
	v_mfma_f32_32x32x16_bf16 v[16:31], v[68:71], v[224:227], v[16:31]
	s_add_i32 s90, s76, 0
	v_add_u32_e32 v80, s90, v243
	v_add_u32_e32 v83, s90, v244
	v_add_u32_e32 v99, s90, v245
	v_add_u32_e32 v253, s90, v246
	v_add_u32_e32 v254, s90, v148
	v_add_u32_e32 v255, s90, v151
	v_med3_i32 v80, v80, 0, s99
	v_med3_i32 v83, v83, 0, s99
	v_med3_i32 v99, v99, 0, s99
	v_med3_i32 v253, v253, 0, s99
	v_med3_i32 v254, v254, 0, s99
	v_med3_i32 v255, v255, 0, s99
	v_mad_u32_u24 v80, v80, s100, v252
	v_mad_u32_u24 v83, v83, s100, v252
	v_mad_u32_u24 v99, v99, s100, v252
	v_mad_u32_u24 v253, v253, s100, v252
	v_mad_u32_u24 v254, v254, s100, v153
	v_mad_u32_u24 v255, v255, s100, v153
	global_load_dwordx4 v[116:119], v80, s[82:83]
	global_load_dwordx4 v[120:123], v83, s[82:83]
	global_load_dwordx4 v[124:127], v99, s[82:83]
	global_load_dwordx4 v[128:131], v253, s[82:83]
	global_load_dwordx4 v[132:135], v254, s[82:83] offset:768
	global_load_dwordx4 v[136:139], v255, s[82:83] offset:768
	global_load_dwordx4 v[140:143], v254, s[82:83] offset:832
	global_load_dwordx4 v[144:147], v255, s[82:83] offset:832
	ds_read_b64_tr_b16 v[72:73], v231
	ds_read_b64_tr_b16 v[74:75], v231 offset:512
	ds_read_b64_tr_b16 v[76:77], v231 offset:2048
	ds_read_b64_tr_b16 v[78:79], v231 offset:2560
	ds_read_b64_tr_b16 v[220:221], v231 offset:1024
	ds_read_b64_tr_b16 v[222:223], v231 offset:1536
	ds_read_b64_tr_b16 v[224:225], v231 offset:3072
	ds_read_b64_tr_b16 v[226:227], v231 offset:3584
	v_exp_f32_e32 v32, v32
	v_exp_f32_e32 v33, v33
	v_exp_f32_e32 v34, v34
	v_exp_f32_e32 v35, v35
	s_waitcnt vmcnt(8)
	ds_write_b128 v247, v[156:159]
	ds_write_b128 v247, v[160:163] offset:1024
	ds_write_b128 v247, v[164:167] offset:2048
	ds_write_b128 v247, v[168:171] offset:3072
	ds_read_b128 v[156:159], v248
	ds_read_b128 v[160:163], v249
	ds_read_b128 v[164:167], v250
	ds_read_b128 v[168:171], v251
	ds_write_b128 v112, v[172:175]
	ds_write_b128 v112, v[176:179] offset:1024
	ds_write_b128 v112, v[180:183] offset:2048
	ds_write_b128 v112, v[184:187] offset:3072
	v_exp_f32_e32 v36, v36
	v_exp_f32_e32 v37, v37
	v_exp_f32_e32 v38, v38
	v_exp_f32_e32 v39, v39
	s_waitcnt lgkmcnt(4)
	v_mfma_f32_32x32x16_bf16 v[188:203], v[156:159], v[48:51], v[188:203]
	v_exp_f32_e32 v40, v40
	v_exp_f32_e32 v41, v41
	v_mfma_f32_32x32x16_bf16 v[188:203], v[160:163], v[52:55], v[188:203]
	v_exp_f32_e32 v42, v42
	v_exp_f32_e32 v43, v43
	v_mfma_f32_32x32x16_bf16 v[188:203], v[164:167], v[56:59], v[188:203]
	v_exp_f32_e32 v44, v44
	v_exp_f32_e32 v45, v45
	v_mfma_f32_32x32x16_bf16 v[188:203], v[168:171], v[60:63], v[188:203]
	v_exp_f32_e32 v46, v46
	v_exp_f32_e32 v47, v47
	s_add_i32 s90, s76, -1024
	v_lshlrev_b32_e32 v84, 4, v107
	v_add_u32_e32 v84, s90, v84
	v_add_u32_e32 v85, 0, v84
	v_add_u32_e32 v86, 16, v84
	v_add_u32_e32 v87, 32, v84
	v_add_u32_e32 v88, 48, v84
	v_cmp_gt_u32_e64 s[30:31], s98, v85
	v_cmp_gt_u32_e64 s[36:37], s98, v86
	v_cmp_gt_u32_e64 s[78:79], s98, v87
	v_cmp_gt_u32_e64 s[50:51], s98, v88
	v_cndmask_b32_e64 v32, 0, v32, s[30:31]
	v_add_u32_e32 v85, 128, v84
	v_cmp_gt_u32_e64 s[30:31], s98, v85
	v_cndmask_b32_e64 v33, 0, v33, s[36:37]
	v_add_u32_e32 v86, 144, v84
	v_cmp_gt_u32_e64 s[36:37], s98, v86
	v_cndmask_b32_e64 v34, 0, v34, s[78:79]
	v_add_u32_e32 v87, 160, v84
	v_cmp_gt_u32_e64 s[78:79], s98, v87
	v_cndmask_b32_e64 v35, 0, v35, s[50:51]
	v_add_u32_e32 v88, 176, v84
	v_cmp_gt_u32_e64 s[50:51], s98, v88
	v_cndmask_b32_e64 v36, 0, v36, s[30:31]
	v_add_u32_e32 v85, 256, v84
	v_cmp_gt_u32_e64 s[30:31], s98, v85
	v_cndmask_b32_e64 v37, 0, v37, s[36:37]
	v_add_u32_e32 v86, 272, v84
	v_cmp_gt_u32_e64 s[36:37], s98, v86
	v_cndmask_b32_e64 v38, 0, v38, s[78:79]
	v_add_u32_e32 v87, 288, v84
	v_cmp_gt_u32_e64 s[78:79], s98, v87
	v_cndmask_b32_e64 v39, 0, v39, s[50:51]
	v_add_u32_e32 v88, 304, v84
	v_cmp_gt_u32_e64 s[50:51], s98, v88
	v_cndmask_b32_e64 v40, 0, v40, s[30:31]
	v_add_u32_e32 v85, 384, v84
	v_cmp_gt_u32_e64 s[30:31], s98, v85
	v_cndmask_b32_e64 v41, 0, v41, s[36:37]
	v_add_u32_e32 v86, 400, v84
	v_cmp_gt_u32_e64 s[36:37], s98, v86
	v_cndmask_b32_e64 v42, 0, v42, s[78:79]
	v_add_u32_e32 v87, 416, v84
	v_cmp_gt_u32_e64 s[78:79], s98, v87
	v_cndmask_b32_e64 v43, 0, v43, s[50:51]
	v_add_u32_e32 v88, 432, v84
	v_cmp_gt_u32_e64 s[50:51], s98, v88
	v_nop
	v_cndmask_b32_e64 v44, 0, v44, s[30:31]
	v_cndmask_b32_e64 v45, 0, v45, s[36:37]
	v_cndmask_b32_e64 v46, 0, v46, s[78:79]
	v_cndmask_b32_e64 v47, 0, v47, s[50:51]
	v_cvt_pk_bf16_f32 v64, v32, v33
	v_cvt_pk_bf16_f32 v65, v34, v35
	v_cvt_pk_bf16_f32 v66, v36, v37
	v_cvt_pk_bf16_f32 v67, v38, v39
	v_cvt_pk_bf16_f32 v68, v40, v41
	v_cvt_pk_bf16_f32 v69, v42, v43
	v_cvt_pk_bf16_f32 v70, v44, v45
	v_cvt_pk_bf16_f32 v71, v46, v47
	v_pk_add_f32 v[232:233], v[232:233], v[32:33]
	v_pk_add_f32 v[232:233], v[232:233], v[34:35]
	v_pk_add_f32 v[232:233], v[232:233], v[36:37]
	v_pk_add_f32 v[232:233], v[232:233], v[38:39]
	v_pk_add_f32 v[232:233], v[232:233], v[40:41]
	v_pk_add_f32 v[232:233], v[232:233], v[42:43]
	v_pk_add_f32 v[232:233], v[232:233], v[44:45]
	v_pk_add_f32 v[232:233], v[232:233], v[46:47]
	ds_read2_b32 v[32:33], v115 offset0:64 offset1:65
	ds_read2_b32 v[34:35], v115 offset0:66 offset1:67
	ds_read2_b32 v[36:37], v115 offset0:72 offset1:73
	ds_read2_b32 v[38:39], v115 offset0:74 offset1:75
	ds_read2_b32 v[40:41], v115 offset0:80 offset1:81
	ds_read2_b32 v[42:43], v115 offset0:82 offset1:83
	ds_read2_b32 v[44:45], v115 offset0:88 offset1:89
	ds_read2_b32 v[46:47], v115 offset0:90 offset1:91
	v_mfma_f32_32x32x16_bf16 v[0:15], v[64:67], v[72:75], v[0:15]
	v_mfma_f32_32x32x16_bf16 v[16:31], v[64:67], v[76:79], v[16:31]
	v_mfma_f32_32x32x16_bf16 v[0:15], v[68:71], v[220:223], v[0:15]
	v_mfma_f32_32x32x16_bf16 v[16:31], v[68:71], v[224:227], v[16:31]
	s_add_i32 s90, s76, 512
	v_add_u32_e32 v80, s90, v243
	v_add_u32_e32 v83, s90, v244
	v_add_u32_e32 v99, s90, v245
	v_add_u32_e32 v253, s90, v246
	v_add_u32_e32 v254, s90, v148
	v_add_u32_e32 v255, s90, v151
	v_med3_i32 v80, v80, 0, s99
	v_med3_i32 v83, v83, 0, s99
	v_med3_i32 v99, v99, 0, s99
	v_med3_i32 v253, v253, 0, s99
	v_med3_i32 v254, v254, 0, s99
	v_med3_i32 v255, v255, 0, s99
	v_mad_u32_u24 v80, v80, s100, v252
	v_mad_u32_u24 v83, v83, s100, v252
	v_mad_u32_u24 v99, v99, s100, v252
	v_mad_u32_u24 v253, v253, s100, v252
	v_mad_u32_u24 v254, v254, s100, v153
	v_mad_u32_u24 v255, v255, s100, v153
	global_load_dwordx4 v[156:159], v80, s[82:83]
	global_load_dwordx4 v[160:163], v83, s[82:83]
	global_load_dwordx4 v[164:167], v99, s[82:83]
	global_load_dwordx4 v[168:171], v253, s[82:83]
	global_load_dwordx4 v[172:175], v254, s[82:83] offset:768
	global_load_dwordx4 v[176:179], v255, s[82:83] offset:768
	global_load_dwordx4 v[180:183], v254, s[82:83] offset:832
	global_load_dwordx4 v[184:187], v255, s[82:83] offset:832
	ds_read_b64_tr_b16 v[72:73], v231
	ds_read_b64_tr_b16 v[74:75], v231 offset:512
	ds_read_b64_tr_b16 v[76:77], v231 offset:2048
	ds_read_b64_tr_b16 v[78:79], v231 offset:2560
	ds_read_b64_tr_b16 v[220:221], v231 offset:1024
	ds_read_b64_tr_b16 v[222:223], v231 offset:1536
	ds_read_b64_tr_b16 v[224:225], v231 offset:3072
	ds_read_b64_tr_b16 v[226:227], v231 offset:3584
	v_exp_f32_e32 v188, v188
	v_exp_f32_e32 v189, v189
	v_exp_f32_e32 v190, v190
	v_exp_f32_e32 v191, v191
	s_waitcnt vmcnt(8)
	ds_write_b128 v247, v[116:119]
	ds_write_b128 v247, v[120:123] offset:1024
	ds_write_b128 v247, v[124:127] offset:2048
	ds_write_b128 v247, v[128:131] offset:3072
	ds_read_b128 v[116:119], v248
	ds_read_b128 v[120:123], v249
	ds_read_b128 v[124:127], v250
	ds_read_b128 v[128:131], v251
	ds_write_b128 v112, v[132:135]
	ds_write_b128 v112, v[136:139] offset:1024
	ds_write_b128 v112, v[140:143] offset:2048
	ds_write_b128 v112, v[144:147] offset:3072
	v_exp_f32_e32 v192, v192
	v_exp_f32_e32 v193, v193
	v_exp_f32_e32 v194, v194
	v_exp_f32_e32 v195, v195
	s_waitcnt lgkmcnt(4)
	v_mfma_f32_32x32x16_bf16 v[32:47], v[116:119], v[48:51], v[32:47]
	v_exp_f32_e32 v196, v196
	v_exp_f32_e32 v197, v197
	v_mfma_f32_32x32x16_bf16 v[32:47], v[120:123], v[52:55], v[32:47]
	v_exp_f32_e32 v198, v198
	v_exp_f32_e32 v199, v199
	v_mfma_f32_32x32x16_bf16 v[32:47], v[124:127], v[56:59], v[32:47]
	v_exp_f32_e32 v200, v200
	v_exp_f32_e32 v201, v201
	v_mfma_f32_32x32x16_bf16 v[32:47], v[128:131], v[60:63], v[32:47]
	v_exp_f32_e32 v202, v202
	v_exp_f32_e32 v203, v203
	s_add_i32 s90, s76, -512
	v_lshlrev_b32_e32 v84, 4, v107
	v_add_u32_e32 v84, s90, v84
	v_add_u32_e32 v85, 0, v84
	v_add_u32_e32 v86, 16, v84
	v_add_u32_e32 v87, 32, v84
	v_add_u32_e32 v88, 48, v84
	v_cmp_gt_u32_e64 s[30:31], s98, v85
	v_cmp_gt_u32_e64 s[36:37], s98, v86
	v_cmp_gt_u32_e64 s[78:79], s98, v87
	v_cmp_gt_u32_e64 s[50:51], s98, v88
	v_cndmask_b32_e64 v188, 0, v188, s[30:31]
	v_add_u32_e32 v85, 128, v84
	v_cmp_gt_u32_e64 s[30:31], s98, v85
	v_cndmask_b32_e64 v189, 0, v189, s[36:37]
	v_add_u32_e32 v86, 144, v84
	v_cmp_gt_u32_e64 s[36:37], s98, v86
	v_cndmask_b32_e64 v190, 0, v190, s[78:79]
	v_add_u32_e32 v87, 160, v84
	v_cmp_gt_u32_e64 s[78:79], s98, v87
	v_cndmask_b32_e64 v191, 0, v191, s[50:51]
	v_add_u32_e32 v88, 176, v84
	v_cmp_gt_u32_e64 s[50:51], s98, v88
	v_cndmask_b32_e64 v192, 0, v192, s[30:31]
	v_add_u32_e32 v85, 256, v84
	v_cmp_gt_u32_e64 s[30:31], s98, v85
	v_cndmask_b32_e64 v193, 0, v193, s[36:37]
	v_add_u32_e32 v86, 272, v84
	v_cmp_gt_u32_e64 s[36:37], s98, v86
	v_cndmask_b32_e64 v194, 0, v194, s[78:79]
	v_add_u32_e32 v87, 288, v84
	v_cmp_gt_u32_e64 s[78:79], s98, v87
	v_cndmask_b32_e64 v195, 0, v195, s[50:51]
	v_add_u32_e32 v88, 304, v84
	v_cmp_gt_u32_e64 s[50:51], s98, v88
	v_cndmask_b32_e64 v196, 0, v196, s[30:31]
	v_add_u32_e32 v85, 384, v84
	v_cmp_gt_u32_e64 s[30:31], s98, v85
	v_cndmask_b32_e64 v197, 0, v197, s[36:37]
	v_add_u32_e32 v86, 400, v84
	v_cmp_gt_u32_e64 s[36:37], s98, v86
	v_cndmask_b32_e64 v198, 0, v198, s[78:79]
	v_add_u32_e32 v87, 416, v84
	v_cmp_gt_u32_e64 s[78:79], s98, v87
	v_cndmask_b32_e64 v199, 0, v199, s[50:51]
	v_add_u32_e32 v88, 432, v84
	v_cmp_gt_u32_e64 s[50:51], s98, v88
	v_nop
	v_cndmask_b32_e64 v200, 0, v200, s[30:31]
	v_cndmask_b32_e64 v201, 0, v201, s[36:37]
	v_cndmask_b32_e64 v202, 0, v202, s[78:79]
	v_cndmask_b32_e64 v203, 0, v203, s[50:51]
	v_cvt_pk_bf16_f32 v64, v188, v189
	v_cvt_pk_bf16_f32 v65, v190, v191
	v_cvt_pk_bf16_f32 v66, v192, v193
	v_cvt_pk_bf16_f32 v67, v194, v195
	v_cvt_pk_bf16_f32 v68, v196, v197
	v_cvt_pk_bf16_f32 v69, v198, v199
	v_cvt_pk_bf16_f32 v70, v200, v201
	v_cvt_pk_bf16_f32 v71, v202, v203
	v_pk_add_f32 v[232:233], v[232:233], v[188:189]
	v_pk_add_f32 v[232:233], v[232:233], v[190:191]
	v_pk_add_f32 v[232:233], v[232:233], v[192:193]
	v_pk_add_f32 v[232:233], v[232:233], v[194:195]
	v_pk_add_f32 v[232:233], v[232:233], v[196:197]
	v_pk_add_f32 v[232:233], v[232:233], v[198:199]
	v_pk_add_f32 v[232:233], v[232:233], v[200:201]
	v_pk_add_f32 v[232:233], v[232:233], v[202:203]
	ds_read2_b32 v[188:189], v115 offset0:96 offset1:97
	ds_read2_b32 v[190:191], v115 offset0:98 offset1:99
	ds_read2_b32 v[192:193], v115 offset0:104 offset1:105
	ds_read2_b32 v[194:195], v115 offset0:106 offset1:107
	ds_read2_b32 v[196:197], v115 offset0:112 offset1:113
	ds_read2_b32 v[198:199], v115 offset0:114 offset1:115
	ds_read2_b32 v[200:201], v115 offset0:120 offset1:121
	ds_read2_b32 v[202:203], v115 offset0:122 offset1:123
	v_mfma_f32_32x32x16_bf16 v[0:15], v[64:67], v[72:75], v[0:15]
	v_mfma_f32_32x32x16_bf16 v[16:31], v[64:67], v[76:79], v[16:31]
	v_mfma_f32_32x32x16_bf16 v[0:15], v[68:71], v[220:223], v[0:15]
	v_mfma_f32_32x32x16_bf16 v[16:31], v[68:71], v[224:227], v[16:31]
	s_add_i32 s90, s76, 1024
	v_add_u32_e32 v80, s90, v243
	v_add_u32_e32 v83, s90, v244
	v_add_u32_e32 v99, s90, v245
	v_add_u32_e32 v253, s90, v246
	v_add_u32_e32 v254, s90, v148
	v_add_u32_e32 v255, s90, v151
	v_med3_i32 v80, v80, 0, s99
	v_med3_i32 v83, v83, 0, s99
	v_med3_i32 v99, v99, 0, s99
	v_med3_i32 v253, v253, 0, s99
	v_med3_i32 v254, v254, 0, s99
	v_med3_i32 v255, v255, 0, s99
	v_mad_u32_u24 v80, v80, s100, v252
	v_mad_u32_u24 v83, v83, s100, v252
	v_mad_u32_u24 v99, v99, s100, v252
	v_mad_u32_u24 v253, v253, s100, v252
	v_mad_u32_u24 v254, v254, s100, v153
	v_mad_u32_u24 v255, v255, s100, v153
	global_load_dwordx4 v[116:119], v80, s[82:83]
	global_load_dwordx4 v[120:123], v83, s[82:83]
	global_load_dwordx4 v[124:127], v99, s[82:83]
	global_load_dwordx4 v[128:131], v253, s[82:83]
	global_load_dwordx4 v[132:135], v254, s[82:83] offset:768
	global_load_dwordx4 v[136:139], v255, s[82:83] offset:768
	global_load_dwordx4 v[140:143], v254, s[82:83] offset:832
	global_load_dwordx4 v[144:147], v255, s[82:83] offset:832
	ds_read_b64_tr_b16 v[72:73], v231
	ds_read_b64_tr_b16 v[74:75], v231 offset:512
	ds_read_b64_tr_b16 v[76:77], v231 offset:2048
	ds_read_b64_tr_b16 v[78:79], v231 offset:2560
	ds_read_b64_tr_b16 v[220:221], v231 offset:1024
	ds_read_b64_tr_b16 v[222:223], v231 offset:1536
	ds_read_b64_tr_b16 v[224:225], v231 offset:3072
	ds_read_b64_tr_b16 v[226:227], v231 offset:3584
	v_exp_f32_e32 v32, v32
	v_exp_f32_e32 v33, v33
	v_exp_f32_e32 v34, v34
	v_exp_f32_e32 v35, v35
	s_waitcnt vmcnt(8)
	ds_write_b128 v247, v[156:159]
	ds_write_b128 v247, v[160:163] offset:1024
	ds_write_b128 v247, v[164:167] offset:2048
	ds_write_b128 v247, v[168:171] offset:3072
	ds_read_b128 v[156:159], v248
	ds_read_b128 v[160:163], v249
	ds_read_b128 v[164:167], v250
	ds_read_b128 v[168:171], v251
	ds_write_b128 v112, v[172:175]
	ds_write_b128 v112, v[176:179] offset:1024
	ds_write_b128 v112, v[180:183] offset:2048
	ds_write_b128 v112, v[184:187] offset:3072
	v_exp_f32_e32 v36, v36
	v_exp_f32_e32 v37, v37
	v_exp_f32_e32 v38, v38
	v_exp_f32_e32 v39, v39
	s_waitcnt lgkmcnt(4)
	v_mfma_f32_32x32x16_bf16 v[188:203], v[156:159], v[48:51], v[188:203]
	v_exp_f32_e32 v40, v40
	v_exp_f32_e32 v41, v41
	v_mfma_f32_32x32x16_bf16 v[188:203], v[160:163], v[52:55], v[188:203]
	v_exp_f32_e32 v42, v42
	v_exp_f32_e32 v43, v43
	v_mfma_f32_32x32x16_bf16 v[188:203], v[164:167], v[56:59], v[188:203]
	v_exp_f32_e32 v44, v44
	v_exp_f32_e32 v45, v45
	v_mfma_f32_32x32x16_bf16 v[188:203], v[168:171], v[60:63], v[188:203]
	v_exp_f32_e32 v46, v46
	v_exp_f32_e32 v47, v47
	s_add_i32 s90, s76, 0
	v_lshlrev_b32_e32 v84, 4, v107
	v_add_u32_e32 v84, s90, v84
	v_add_u32_e32 v85, 0, v84
	v_add_u32_e32 v86, 16, v84
	v_add_u32_e32 v87, 32, v84
	v_add_u32_e32 v88, 48, v84
	v_cmp_gt_u32_e64 s[30:31], s98, v85
	v_cmp_gt_u32_e64 s[36:37], s98, v86
	v_cmp_gt_u32_e64 s[78:79], s98, v87
	v_cmp_gt_u32_e64 s[50:51], s98, v88
	v_cndmask_b32_e64 v32, 0, v32, s[30:31]
	v_add_u32_e32 v85, 128, v84
	v_cmp_gt_u32_e64 s[30:31], s98, v85
	v_cndmask_b32_e64 v33, 0, v33, s[36:37]
	v_add_u32_e32 v86, 144, v84
	v_cmp_gt_u32_e64 s[36:37], s98, v86
	v_cndmask_b32_e64 v34, 0, v34, s[78:79]
	v_add_u32_e32 v87, 160, v84
	v_cmp_gt_u32_e64 s[78:79], s98, v87
	v_cndmask_b32_e64 v35, 0, v35, s[50:51]
	v_add_u32_e32 v88, 176, v84
	v_cmp_gt_u32_e64 s[50:51], s98, v88
	v_cndmask_b32_e64 v36, 0, v36, s[30:31]
	v_add_u32_e32 v85, 256, v84
	v_cmp_gt_u32_e64 s[30:31], s98, v85
	v_cndmask_b32_e64 v37, 0, v37, s[36:37]
	v_add_u32_e32 v86, 272, v84
	v_cmp_gt_u32_e64 s[36:37], s98, v86
	v_cndmask_b32_e64 v38, 0, v38, s[78:79]
	v_add_u32_e32 v87, 288, v84
	v_cmp_gt_u32_e64 s[78:79], s98, v87
	v_cndmask_b32_e64 v39, 0, v39, s[50:51]
	v_add_u32_e32 v88, 304, v84
	v_cmp_gt_u32_e64 s[50:51], s98, v88
	v_cndmask_b32_e64 v40, 0, v40, s[30:31]
	v_add_u32_e32 v85, 384, v84
	v_cmp_gt_u32_e64 s[30:31], s98, v85
	v_cndmask_b32_e64 v41, 0, v41, s[36:37]
	v_add_u32_e32 v86, 400, v84
	v_cmp_gt_u32_e64 s[36:37], s98, v86
	v_cndmask_b32_e64 v42, 0, v42, s[78:79]
	v_add_u32_e32 v87, 416, v84
	v_cmp_gt_u32_e64 s[78:79], s98, v87
	v_cndmask_b32_e64 v43, 0, v43, s[50:51]
	v_add_u32_e32 v88, 432, v84
	v_cmp_gt_u32_e64 s[50:51], s98, v88
	v_nop
	v_cndmask_b32_e64 v44, 0, v44, s[30:31]
	v_cndmask_b32_e64 v45, 0, v45, s[36:37]
	v_cndmask_b32_e64 v46, 0, v46, s[78:79]
	v_cndmask_b32_e64 v47, 0, v47, s[50:51]
	v_cvt_pk_bf16_f32 v64, v32, v33
	v_cvt_pk_bf16_f32 v65, v34, v35
	v_cvt_pk_bf16_f32 v66, v36, v37
	v_cvt_pk_bf16_f32 v67, v38, v39
	v_cvt_pk_bf16_f32 v68, v40, v41
	v_cvt_pk_bf16_f32 v69, v42, v43
	v_cvt_pk_bf16_f32 v70, v44, v45
	v_cvt_pk_bf16_f32 v71, v46, v47
	v_pk_add_f32 v[232:233], v[232:233], v[32:33]
	v_pk_add_f32 v[232:233], v[232:233], v[34:35]
	v_pk_add_f32 v[232:233], v[232:233], v[36:37]
	v_pk_add_f32 v[232:233], v[232:233], v[38:39]
	v_pk_add_f32 v[232:233], v[232:233], v[40:41]
	v_pk_add_f32 v[232:233], v[232:233], v[42:43]
	v_pk_add_f32 v[232:233], v[232:233], v[44:45]
	v_pk_add_f32 v[232:233], v[232:233], v[46:47]
	ds_read2_b32 v[32:33], v115 offset0:128 offset1:129
	ds_read2_b32 v[34:35], v115 offset0:130 offset1:131
	ds_read2_b32 v[36:37], v115 offset0:136 offset1:137
	ds_read2_b32 v[38:39], v115 offset0:138 offset1:139
	ds_read2_b32 v[40:41], v115 offset0:144 offset1:145
	ds_read2_b32 v[42:43], v115 offset0:146 offset1:147
	ds_read2_b32 v[44:45], v115 offset0:152 offset1:153
	ds_read2_b32 v[46:47], v115 offset0:154 offset1:155
	v_mfma_f32_32x32x16_bf16 v[0:15], v[64:67], v[72:75], v[0:15]
	v_mfma_f32_32x32x16_bf16 v[16:31], v[64:67], v[76:79], v[16:31]
	v_mfma_f32_32x32x16_bf16 v[0:15], v[68:71], v[220:223], v[0:15]
	v_mfma_f32_32x32x16_bf16 v[16:31], v[68:71], v[224:227], v[16:31]
	ds_read_b64_tr_b16 v[72:73], v231
	ds_read_b64_tr_b16 v[74:75], v231 offset:512
	ds_read_b64_tr_b16 v[76:77], v231 offset:2048
	ds_read_b64_tr_b16 v[78:79], v231 offset:2560
	ds_read_b64_tr_b16 v[220:221], v231 offset:1024
	ds_read_b64_tr_b16 v[222:223], v231 offset:1536
	ds_read_b64_tr_b16 v[224:225], v231 offset:3072
	ds_read_b64_tr_b16 v[226:227], v231 offset:3584
	v_exp_f32_e32 v188, v188
	v_exp_f32_e32 v189, v189
	v_exp_f32_e32 v190, v190
	v_exp_f32_e32 v191, v191
	s_waitcnt vmcnt(0)
	ds_write_b128 v247, v[116:119]
	ds_write_b128 v247, v[120:123] offset:1024
	ds_write_b128 v247, v[124:127] offset:2048
	ds_write_b128 v247, v[128:131] offset:3072
	ds_read_b128 v[116:119], v248
	ds_read_b128 v[120:123], v249
	ds_read_b128 v[124:127], v250
	ds_read_b128 v[128:131], v251
	ds_write_b128 v112, v[132:135]
	ds_write_b128 v112, v[136:139] offset:1024
	ds_write_b128 v112, v[140:143] offset:2048
	ds_write_b128 v112, v[144:147] offset:3072
	v_exp_f32_e32 v192, v192
	v_exp_f32_e32 v193, v193
	v_exp_f32_e32 v194, v194
	v_exp_f32_e32 v195, v195
	s_waitcnt lgkmcnt(4)
	v_mfma_f32_32x32x16_bf16 v[32:47], v[116:119], v[48:51], v[32:47]
	v_exp_f32_e32 v196, v196
	v_exp_f32_e32 v197, v197
	v_mfma_f32_32x32x16_bf16 v[32:47], v[120:123], v[52:55], v[32:47]
	v_exp_f32_e32 v198, v198
	v_exp_f32_e32 v199, v199
	v_mfma_f32_32x32x16_bf16 v[32:47], v[124:127], v[56:59], v[32:47]
	v_exp_f32_e32 v200, v200
	v_exp_f32_e32 v201, v201
	v_mfma_f32_32x32x16_bf16 v[32:47], v[128:131], v[60:63], v[32:47]
	v_exp_f32_e32 v202, v202
	v_exp_f32_e32 v203, v203
	s_add_i32 s90, s76, 512
	v_lshlrev_b32_e32 v84, 4, v107
	v_add_u32_e32 v84, s90, v84
	v_add_u32_e32 v85, 0, v84
	v_add_u32_e32 v86, 16, v84
	v_add_u32_e32 v87, 32, v84
	v_add_u32_e32 v88, 48, v84
	v_cmp_gt_u32_e64 s[30:31], s98, v85
	v_cmp_gt_u32_e64 s[36:37], s98, v86
	v_cmp_gt_u32_e64 s[78:79], s98, v87
	v_cmp_gt_u32_e64 s[50:51], s98, v88
	v_cndmask_b32_e64 v188, 0, v188, s[30:31]
	v_add_u32_e32 v85, 128, v84
	v_cmp_gt_u32_e64 s[30:31], s98, v85
	v_cndmask_b32_e64 v189, 0, v189, s[36:37]
	v_add_u32_e32 v86, 144, v84
	v_cmp_gt_u32_e64 s[36:37], s98, v86
	v_cndmask_b32_e64 v190, 0, v190, s[78:79]
	v_add_u32_e32 v87, 160, v84
	v_cmp_gt_u32_e64 s[78:79], s98, v87
	v_cndmask_b32_e64 v191, 0, v191, s[50:51]
	v_add_u32_e32 v88, 176, v84
	v_cmp_gt_u32_e64 s[50:51], s98, v88
	v_cndmask_b32_e64 v192, 0, v192, s[30:31]
	v_add_u32_e32 v85, 256, v84
	v_cmp_gt_u32_e64 s[30:31], s98, v85
	v_cndmask_b32_e64 v193, 0, v193, s[36:37]
	v_add_u32_e32 v86, 272, v84
	v_cmp_gt_u32_e64 s[36:37], s98, v86
	v_cndmask_b32_e64 v194, 0, v194, s[78:79]
	v_add_u32_e32 v87, 288, v84
	v_cmp_gt_u32_e64 s[78:79], s98, v87
	v_cndmask_b32_e64 v195, 0, v195, s[50:51]
	v_add_u32_e32 v88, 304, v84
	v_cmp_gt_u32_e64 s[50:51], s98, v88
	v_cndmask_b32_e64 v196, 0, v196, s[30:31]
	v_add_u32_e32 v85, 384, v84
	v_cmp_gt_u32_e64 s[30:31], s98, v85
	v_cndmask_b32_e64 v197, 0, v197, s[36:37]
	v_add_u32_e32 v86, 400, v84
	v_cmp_gt_u32_e64 s[36:37], s98, v86
	v_cndmask_b32_e64 v198, 0, v198, s[78:79]
	v_add_u32_e32 v87, 416, v84
	v_cmp_gt_u32_e64 s[78:79], s98, v87
	v_cndmask_b32_e64 v199, 0, v199, s[50:51]
	v_add_u32_e32 v88, 432, v84
	v_cmp_gt_u32_e64 s[50:51], s98, v88
	v_nop
	v_cndmask_b32_e64 v200, 0, v200, s[30:31]
	v_cndmask_b32_e64 v201, 0, v201, s[36:37]
	v_cndmask_b32_e64 v202, 0, v202, s[78:79]
	v_cndmask_b32_e64 v203, 0, v203, s[50:51]
	v_cvt_pk_bf16_f32 v64, v188, v189
	v_cvt_pk_bf16_f32 v65, v190, v191
	v_cvt_pk_bf16_f32 v66, v192, v193
	v_cvt_pk_bf16_f32 v67, v194, v195
	v_cvt_pk_bf16_f32 v68, v196, v197
	v_cvt_pk_bf16_f32 v69, v198, v199
	v_cvt_pk_bf16_f32 v70, v200, v201
	v_cvt_pk_bf16_f32 v71, v202, v203
	v_pk_add_f32 v[232:233], v[232:233], v[188:189]
	v_pk_add_f32 v[232:233], v[232:233], v[190:191]
	v_pk_add_f32 v[232:233], v[232:233], v[192:193]
	v_pk_add_f32 v[232:233], v[232:233], v[194:195]
	v_pk_add_f32 v[232:233], v[232:233], v[196:197]
	v_pk_add_f32 v[232:233], v[232:233], v[198:199]
	v_pk_add_f32 v[232:233], v[232:233], v[200:201]
	v_pk_add_f32 v[232:233], v[232:233], v[202:203]
	v_mfma_f32_32x32x16_bf16 v[0:15], v[64:67], v[72:75], v[0:15]
	v_mfma_f32_32x32x16_bf16 v[16:31], v[64:67], v[76:79], v[16:31]
	v_mfma_f32_32x32x16_bf16 v[0:15], v[68:71], v[220:223], v[0:15]
	v_mfma_f32_32x32x16_bf16 v[16:31], v[68:71], v[224:227], v[16:31]
	ds_read_b64_tr_b16 v[72:73], v231
	ds_read_b64_tr_b16 v[74:75], v231 offset:512
	ds_read_b64_tr_b16 v[76:77], v231 offset:2048
	ds_read_b64_tr_b16 v[78:79], v231 offset:2560
	ds_read_b64_tr_b16 v[220:221], v231 offset:1024
	ds_read_b64_tr_b16 v[222:223], v231 offset:1536
	ds_read_b64_tr_b16 v[224:225], v231 offset:3072
	ds_read_b64_tr_b16 v[226:227], v231 offset:3584
	s_waitcnt lgkmcnt(0)
; __device__ __forceinline__ int crow(int r, int hi) { return (r & 3) + 8 * (r >> 2) + 4 * hi; }
; __device__ __forceinline__ void dil_unit(LAS unsigned char* lds, bf16_t* proj, int seq, int hd, int T0, int rho) {
;     ...
;     l += __shfl_xor(l, 32);
; #pragma unroll
;     for (int rr = 0; rr < 16; ++rr) {
;         const int j = crow(rr, hi);
	v_exp_f32_e32 v32, v32
	v_exp_f32_e32 v33, v33
	v_exp_f32_e32 v34, v34
	v_exp_f32_e32 v35, v35
	v_exp_f32_e32 v36, v36
	v_exp_f32_e32 v37, v37
	v_exp_f32_e32 v38, v38
	v_exp_f32_e32 v39, v39
	v_exp_f32_e32 v40, v40
	v_exp_f32_e32 v41, v41
	v_exp_f32_e32 v42, v42
	v_exp_f32_e32 v43, v43
	v_exp_f32_e32 v44, v44
	v_exp_f32_e32 v45, v45
	v_exp_f32_e32 v46, v46
	v_exp_f32_e32 v47, v47
	s_add_i32 s90, s76, 1024
	v_lshlrev_b32_e32 v84, 4, v107
	v_add_u32_e32 v84, s90, v84
	v_add_u32_e32 v85, 0, v84
	v_add_u32_e32 v86, 16, v84
	v_add_u32_e32 v87, 32, v84
	v_add_u32_e32 v88, 48, v84
	v_cmp_gt_u32_e64 s[30:31], s98, v85
	v_cmp_gt_u32_e64 s[36:37], s98, v86
	v_cmp_gt_u32_e64 s[78:79], s98, v87
	v_cmp_gt_u32_e64 s[50:51], s98, v88
	v_cndmask_b32_e64 v32, 0, v32, s[30:31]
	v_add_u32_e32 v85, 128, v84
	v_cmp_gt_u32_e64 s[30:31], s98, v85
	v_cndmask_b32_e64 v33, 0, v33, s[36:37]
	v_add_u32_e32 v86, 144, v84
	v_cmp_gt_u32_e64 s[36:37], s98, v86
	v_cndmask_b32_e64 v34, 0, v34, s[78:79]
	v_add_u32_e32 v87, 160, v84
	v_cmp_gt_u32_e64 s[78:79], s98, v87
	v_cndmask_b32_e64 v35, 0, v35, s[50:51]
	v_add_u32_e32 v88, 176, v84
	v_cmp_gt_u32_e64 s[50:51], s98, v88
	v_cndmask_b32_e64 v36, 0, v36, s[30:31]
	v_add_u32_e32 v85, 256, v84
	v_cmp_gt_u32_e64 s[30:31], s98, v85
	v_cndmask_b32_e64 v37, 0, v37, s[36:37]
	v_add_u32_e32 v86, 272, v84
	v_cmp_gt_u32_e64 s[36:37], s98, v86
	v_cndmask_b32_e64 v38, 0, v38, s[78:79]
	v_add_u32_e32 v87, 288, v84
	v_cmp_gt_u32_e64 s[78:79], s98, v87
	v_cndmask_b32_e64 v39, 0, v39, s[50:51]
	v_add_u32_e32 v88, 304, v84
	v_cmp_gt_u32_e64 s[50:51], s98, v88
	v_cndmask_b32_e64 v40, 0, v40, s[30:31]
	v_add_u32_e32 v85, 384, v84
	v_cmp_gt_u32_e64 s[30:31], s98, v85
	v_cndmask_b32_e64 v41, 0, v41, s[36:37]
	v_add_u32_e32 v86, 400, v84
	v_cmp_gt_u32_e64 s[36:37], s98, v86
	v_cndmask_b32_e64 v42, 0, v42, s[78:79]
	v_add_u32_e32 v87, 416, v84
	v_cmp_gt_u32_e64 s[78:79], s98, v87
	v_cndmask_b32_e64 v43, 0, v43, s[50:51]
	v_add_u32_e32 v88, 432, v84
	v_cmp_gt_u32_e64 s[50:51], s98, v88
	v_nop
	v_cndmask_b32_e64 v44, 0, v44, s[30:31]
	v_cndmask_b32_e64 v45, 0, v45, s[36:37]
	v_cndmask_b32_e64 v46, 0, v46, s[78:79]
	v_cndmask_b32_e64 v47, 0, v47, s[50:51]
	v_cvt_pk_bf16_f32 v64, v32, v33
	v_cvt_pk_bf16_f32 v65, v34, v35
	v_cvt_pk_bf16_f32 v66, v36, v37
	v_cvt_pk_bf16_f32 v67, v38, v39
	v_cvt_pk_bf16_f32 v68, v40, v41
	v_cvt_pk_bf16_f32 v69, v42, v43
	v_cvt_pk_bf16_f32 v70, v44, v45
	v_cvt_pk_bf16_f32 v71, v46, v47
	v_pk_add_f32 v[232:233], v[232:233], v[32:33]
	v_pk_add_f32 v[232:233], v[232:233], v[34:35]
	v_pk_add_f32 v[232:233], v[232:233], v[36:37]
	v_pk_add_f32 v[232:233], v[232:233], v[38:39]
	v_pk_add_f32 v[232:233], v[232:233], v[40:41]
	v_pk_add_f32 v[232:233], v[232:233], v[42:43]
	v_pk_add_f32 v[232:233], v[232:233], v[44:45]
	v_pk_add_f32 v[232:233], v[232:233], v[46:47]
	v_mfma_f32_32x32x16_bf16 v[0:15], v[64:67], v[72:75], v[0:15]
	v_mfma_f32_32x32x16_bf16 v[16:31], v[64:67], v[76:79], v[16:31]
	v_mfma_f32_32x32x16_bf16 v[0:15], v[68:71], v[220:223], v[0:15]
	v_mfma_f32_32x32x16_bf16 v[16:31], v[68:71], v[224:227], v[16:31]
	v_add_f32_e32 v113, v232, v233
	v_or_b32_e32 v114, 1, v107
	v_or_b32_e32 v97, 2, v107
	v_or_b32_e32 v96, 3, v107
	v_or_b32_e32 v95, 8, v107
	v_or_b32_e32 v94, 9, v107
	v_or_b32_e32 v93, 10, v107
	v_or_b32_e32 v92, 11, v107
	v_or_b32_e32 v91, 16, v107
	v_or_b32_e32 v90, 17, v107
	v_or_b32_e32 v89, 18, v107
	v_or_b32_e32 v88, 19, v107
	v_or_b32_e32 v87, 24, v107
	v_or_b32_e32 v86, 25, v107
	v_or_b32_e32 v85, 26, v107
	v_or_b32_e32 v84, 27, v107
	s_setprio 0
	s_nop 11
	s_branch .LBB0_553

; #define LAS __attribute__((address_space(3)))
; #define GAS __attribute__((address_space(1)))
; __device__ __forceinline__ void dil_unit(LAS unsigned char* lds, bf16_t* proj, int seq, int hd, int T0, int rho) {
;     int tid_ = threadIdx.x; asm volatile("" : "+v"(tid_));
;     const int tid = tid_, lane = tid & 63, r32 = lane & 31, hi = lane >> 5, wid = __builtin_amdgcn_readfirstlane(tid >> 6);
;     bf16_t* base = proj + (size_t)seq * SEQ * NIN;
;     LAS unsigned char* wbuf = lds + wid * 4096;
;     const LAS unsigned char* vp = wbuf + ((lane >> 4) & 1) * 32 + (lane & 3) * 8 + (4 * hi + ((lane & 15) >> 2)) * 64;
;     const int P0 = T0 + rho;
;     bf16x8 qr[4];
; #pragma unroll
;     for (int ks = 0; ks < 4; ++ks) qr[ks] = *(const GAS bf16x8*)(base + (size_t)(P0 + 16 * r32) * NIN + PC_LQ + hd * 64 + 16 * ks + 8 * hi);
;     f32x16 o0 = {}, o1 = {}; float l = 0.f;
;     const bool bound = (T0 < 1024) || (T0 >= 15360);
; __device__ __forceinline__ void attn_phase(unsigned char* ws, int l, LAS unsigned char* lds, int G) {
;     ...
;     for (int bu = vb; bu < 1152; bu += G) {
;         const int sh = bu >> 6, rem = bu & 63, T0 = (rem >> 1) * 512, rho = (rem & 1) * 8 + wid;
;         dil_unit(lds, proj, sh / 6, sh % 6, T0, rho);
.LBB0_1266:
	s_lshr_b32 s82, s60, 8
	s_mul_i32 s82, s82, 13
	s_add_i32 s82, s82, s60
	s_ashr_i32 s4, s60, 6
	s_mul_hi_i32 s9, s4, 0x2aaaaaab
	s_lshl_b32 s5, s82, 8
	s_lshr_b32 s10, s9, 31
	s_and_b32 s8, s5, 0x3e00
	s_lshl_b32 s5, s82, 3
	s_add_i32 s9, s9, s10
	s_and_b32 s5, s5, 8
	s_mul_i32 s10, s9, 6
	s_add_i32 s5, s5, s61
	s_sub_i32 s10, s4, s10
	s_mul_hi_i32 s4, s9, 0x6000000
	s_mul_i32 s9, s9, 0x6000000
	v_mov_b32_e32 v2, v154
	s_add_u32 s52, s44, s9
	s_addc_u32 s53, s45, s4
	v_and_b32_e32 v105, 31, v2
	s_add_i32 s67, s5, s8
	v_lshl_add_u32 v3, v105, 4, s67
	v_mov_b64_e32 v[0:1], s[52:53]
	s_lshl_b32 s54, s10, 6
	v_bfe_u32 v106, v2, 5, 1
	v_mad_u64_u32 v[0:1], s[4:5], v3, s62, v[0:1]
	s_ashr_i32 s55, s54, 31
	v_lshl_add_u64 v[0:1], s[54:55], 1, v[0:1]
	v_lshlrev_b32_e32 v80, 4, v106
	v_lshl_add_u64 v[0:1], v[0:1], 0, v[80:81]
	global_load_dwordx4 v[48:51], v[0:1], off offset:1280
	global_load_dwordx4 v[52:55], v[0:1], off offset:1312
	global_load_dwordx4 v[56:59], v[0:1], off offset:1344
	global_load_dwordx4 v[60:63], v[0:1], off offset:1376
	v_readfirstlane_b32 s4, v2
	s_lshl_b32 s4, s4, 6
	s_and_b32 s4, s4, 0xfffff000
	v_lshlrev_b32_e32 v0, 1, v2
	v_lshlrev_b32_e32 v104, 3, v2
	v_lshlrev_b32_e32 v107, 2, v106
	v_lshrrev_b32_e32 v1, 2, v2
	v_and_b32_e32 v103, 63, v2
	v_and_b32_e32 v0, 32, v0
	v_and_b32_e32 v98, 24, v104
	v_and_or_b32 v1, v1, 3, v107
	s_add_i32 s69, s4, 0
	v_lshlrev_b32_e32 v108, 6, v1
	v_lshlrev_b32_e32 v1, 3, v106
	v_add3_u32 v109, s69, v0, v98
	s_addk_i32 s8, 0xc400
	v_lshrrev_b32_e32 v110, 2, v103
	v_lshlrev_b32_e32 v0, 4, v103
	s_mov_b64 s[4:5], -1
	s_cmp_gt_u32 s8, 0xffffc7ff
	v_lshlrev_b32_e32 v100, 1, v98
	s_mul_i32 s8, s10, 0x1c00
	v_lshlrev_b32_e32 v82, 1, v1
	v_or_b32_e32 v111, 16, v110
	v_add_u32_e32 v112, s69, v0
	s_cbranch_scc0 .LBB0_1270
	v_readfirstlane_b32 s91, v154
	s_nop 3
	s_bitcmp1_b32 s91, 8
	s_cbranch_scc0 .Ldn1_noprio
	s_setprio 1
.Ldn1_noprio:
	s_movk_i32 s100, 0x1800
	s_add_i32 s101, s8, 0x15c00
	s_lshl_b32 s90, s54, 1
	s_add_u32 s82, s52, s90
	s_addc_u32 s83, s53, 0
	s_add_u32 s82, s82, 0x1200
	s_addc_u32 s83, s83, 0
	s_sub_i32 s90, s67, 64
	s_mul_i32 s90, s90, 0x1800
	s_add_u32 s84, s82, s90
	s_addc_u32 s85, s83, 0
	s_sub_i32 s90, s67, 256
	s_mul_i32 s90, s90, 0x1800
	s_add_u32 s86, s82, s90
	s_addc_u32 s87, s83, 0
	s_sub_i32 s90, s67, 1024
	s_mul_i32 s90, s90, 0x1800
	s_add_u32 s88, s82, s90
	s_addc_u32 s89, s83, 0
	v_lshlrev_b32_e32 v153, 1, v98
	v_mad_u32_u24 v80, v105, s100, v82
	v_mad_u32_u24 v100, v110, s100, v153
	v_add_u32_e32 v149, 0x18000, v100
	v_lshlrev_b32_e32 v83, 2, v105
	v_mad_u32_u24 v83, v83, s100, v82
	v_lshlrev_b32_e32 v101, 2, v110
	v_mad_u32_u24 v101, v101, s100, v153
	v_add_u32_e32 v150, 0x60000, v101
	v_lshlrev_b32_e32 v99, 4, v105
	v_mad_u32_u24 v99, v99, s100, v82
	v_lshlrev_b32_e32 v148, 4, v110
	v_mad_u32_u24 v148, v148, s100, v153
	v_add_u32_e32 v151, 0x180000, v148
	v_lshrrev_b32_e32 v249, 3, v103
	v_and_b32_e32 v250, 7, v103
	v_lshlrev_b32_e32 v250, 4, v250
	v_add_u32_e32 v235, 0, v249
	v_mad_u32_u24 v235, v235, s100, v250
	v_add_u32_e32 v236, 8, v249
	v_mad_u32_u24 v236, v236, s100, v250
	v_add_u32_e32 v237, 16, v249
	v_mad_u32_u24 v237, v237, s100, v250
	v_add_u32_e32 v238, 24, v249
	v_mad_u32_u24 v238, v238, s100, v250
	v_add_u32_e32 v239, 0, v249
	v_lshlrev_b32_e32 v239, 2, v239
	v_mad_u32_u24 v239, v239, s100, v250
	v_add_u32_e32 v240, 8, v249
	v_lshlrev_b32_e32 v240, 2, v240
	v_mad_u32_u24 v240, v240, s100, v250
	v_add_u32_e32 v241, 16, v249
	v_lshlrev_b32_e32 v241, 2, v241
	v_mad_u32_u24 v241, v241, s100, v250
	v_add_u32_e32 v242, 24, v249
	v_lshlrev_b32_e32 v242, 2, v242
	v_mad_u32_u24 v242, v242, s100, v250
	v_add_u32_e32 v243, 0, v249
	v_lshlrev_b32_e32 v243, 4, v243
	v_mad_u32_u24 v243, v243, s100, v250
	v_add_u32_e32 v244, 8, v249
	v_lshlrev_b32_e32 v244, 4, v244
	v_mad_u32_u24 v244, v244, s100, v250
	v_add_u32_e32 v245, 16, v249
	v_lshlrev_b32_e32 v245, 4, v245
	v_mad_u32_u24 v245, v245, s100, v250
	v_add_u32_e32 v246, 24, v249
	v_lshlrev_b32_e32 v246, 4, v246
	v_mad_u32_u24 v246, v246, s100, v250
	v_and_b32_e32 v247, 7, v249
	v_lshlrev_b32_e32 v247, 4, v247
	v_xor_b32_e32 v247, v247, v112
	v_and_b32_e32 v153, 7, v105
	v_or_b32_e32 v248, 0, v106
	v_xor_b32_e32 v248, v248, v153
	v_lshlrev_b32_e32 v248, 4, v248
	v_lshl_add_u32 v248, v105, 7, v248
	v_add_u32_e32 v248, s69, v248
	v_or_b32_e32 v249, 2, v106
	v_xor_b32_e32 v249, v249, v153
	v_lshlrev_b32_e32 v249, 4, v249
	v_lshl_add_u32 v249, v105, 7, v249
	v_add_u32_e32 v249, s69, v249
	v_or_b32_e32 v250, 4, v106
	v_xor_b32_e32 v250, v250, v153
	v_lshlrev_b32_e32 v250, 4, v250
	v_lshl_add_u32 v250, v105, 7, v250
	v_add_u32_e32 v250, s69, v250
	v_or_b32_e32 v251, 6, v106
	v_xor_b32_e32 v251, v251, v153
	v_lshlrev_b32_e32 v251, 4, v251
	v_lshl_add_u32 v251, v105, 7, v251
	v_add_u32_e32 v251, s69, v251
	v_lshlrev_b32_e32 v153, 1, v98
	v_mul_u32_u24_e32 v228, 17, v105
	v_sub_u32_e32 v228, v107, v228
	s_mul_i32 s90, s54, 153
	s_lshr_b32 s90, s90, 1
	s_add_i32 s90, s90, 34876
	v_lshl_add_u32 v228, v228, 2, s90
	v_lshlrev_b32_e32 v229, 2, v105
	v_sub_u32_e32 v229, v107, v229
	s_add_i32 s90, s101, 5104
	v_lshl_add_u32 v229, v229, 2, s90
	v_sub_u32_e32 v230, v107, v105
	s_add_i32 s90, s101, 6364
	v_lshl_add_u32 v230, v230, 2, s90
	v_add_u32_e32 v231, v109, v108
	v_mov_b64_e32 v[232:233], 0
	v_mov_b64_e32 v[0:1], 0
	v_mov_b64_e32 v[2:3], 0
	v_mov_b64_e32 v[4:5], 0
	v_mov_b64_e32 v[6:7], 0
	v_mov_b64_e32 v[8:9], 0
	v_mov_b64_e32 v[10:11], 0
	v_mov_b64_e32 v[12:13], 0
	v_mov_b64_e32 v[14:15], 0
	v_mov_b64_e32 v[16:17], 0
	v_mov_b64_e32 v[18:19], 0
	v_mov_b64_e32 v[20:21], 0
	v_mov_b64_e32 v[22:23], 0
; __device__ __forceinline__ void dil_unit(LAS unsigned char* lds, bf16_t* proj, int seq, int hd, int T0, int rho) {
;     ...
;     f32x16 o0 = {}, o1 = {}; float l = 0.f;
;     const bool bound = (T0 < 1024) || (T0 >= 15360);
	v_mov_b64_e32 v[24:25], 0
	v_mov_b64_e32 v[26:27], 0
	v_mov_b64_e32 v[28:29], 0
	v_mov_b64_e32 v[30:31], 0
	global_load_dwordx4 v[116:119], v235, s[84:85]
	global_load_dwordx4 v[120:123], v236, s[84:85]
	global_load_dwordx4 v[124:127], v237, s[84:85]
	global_load_dwordx4 v[128:131], v238, s[84:85]
	global_load_dwordx4 v[132:135], v100, s[84:85] offset:768
	global_load_dwordx4 v[136:139], v149, s[84:85] offset:768
	global_load_dwordx4 v[140:143], v100, s[84:85] offset:832
	global_load_dwordx4 v[144:147], v149, s[84:85] offset:832
	s_add_u32 s84, s84, 0x30000
	s_addc_u32 s85, s85, 0
	global_load_dwordx4 v[156:159], v235, s[84:85]
	global_load_dwordx4 v[160:163], v236, s[84:85]
	global_load_dwordx4 v[164:167], v237, s[84:85]
	global_load_dwordx4 v[168:171], v238, s[84:85]
	global_load_dwordx4 v[172:175], v100, s[84:85] offset:768
	global_load_dwordx4 v[176:179], v149, s[84:85] offset:768
	global_load_dwordx4 v[180:183], v100, s[84:85] offset:832
	global_load_dwordx4 v[184:187], v149, s[84:85] offset:832
	s_add_u32 s84, s84, 0x30000
	s_addc_u32 s85, s85, 0
	v_mov_b32_e32 v115, v228
	ds_read2_b32 v[32:33], v115 offset0:0 offset1:1
	ds_read2_b32 v[34:35], v115 offset0:2 offset1:3
	ds_read2_b32 v[36:37], v115 offset0:8 offset1:9
	ds_read2_b32 v[38:39], v115 offset0:10 offset1:11
	ds_read2_b32 v[40:41], v115 offset0:17 offset1:18
	ds_read2_b32 v[42:43], v115 offset0:19 offset1:20
	ds_read2_b32 v[44:45], v115 offset0:25 offset1:26
	ds_read2_b32 v[46:47], v115 offset0:27 offset1:28
	s_waitcnt vmcnt(8)
	ds_write_b128 v247, v[116:119]
	ds_write_b128 v247, v[120:123] offset:1024
	ds_write_b128 v247, v[124:127] offset:2048
	ds_write_b128 v247, v[128:131] offset:3072
	ds_read_b128 v[116:119], v248
	ds_read_b128 v[120:123], v249
	ds_read_b128 v[124:127], v250
	ds_read_b128 v[128:131], v251
	ds_write_b128 v112, v[132:135]
	ds_write_b128 v112, v[136:139] offset:1024
	ds_write_b128 v112, v[140:143] offset:2048
	ds_write_b128 v112, v[144:147] offset:3072
	s_waitcnt lgkmcnt(4)
	v_mfma_f32_32x32x16_bf16 v[32:47], v[116:119], v[48:51], v[32:47]
	v_mfma_f32_32x32x16_bf16 v[32:47], v[120:123], v[52:55], v[32:47]
	v_mfma_f32_32x32x16_bf16 v[32:47], v[124:127], v[56:59], v[32:47]
	v_mfma_f32_32x32x16_bf16 v[32:47], v[128:131], v[60:63], v[32:47]
	ds_read2_b32 v[188:189], v115 offset0:34 offset1:35
	ds_read2_b32 v[190:191], v115 offset0:36 offset1:37
	ds_read2_b32 v[192:193], v115 offset0:42 offset1:43
	ds_read2_b32 v[194:195], v115 offset0:44 offset1:45
	ds_read2_b32 v[196:197], v115 offset0:51 offset1:52
	ds_read2_b32 v[198:199], v115 offset0:53 offset1:54
	ds_read2_b32 v[200:201], v115 offset0:59 offset1:60
	ds_read2_b32 v[202:203], v115 offset0:61 offset1:62
	global_load_dwordx4 v[116:119], v235, s[84:85]
	global_load_dwordx4 v[120:123], v236, s[84:85]
	global_load_dwordx4 v[124:127], v237, s[84:85]
	global_load_dwordx4 v[128:131], v238, s[84:85]
	global_load_dwordx4 v[132:135], v100, s[84:85] offset:768
	global_load_dwordx4 v[136:139], v149, s[84:85] offset:768
	global_load_dwordx4 v[140:143], v100, s[84:85] offset:832
	global_load_dwordx4 v[144:147], v149, s[84:85] offset:832
	s_add_u32 s84, s84, 0x30000
	s_addc_u32 s85, s85, 0
	ds_read_b64_tr_b16 v[72:73], v231
	ds_read_b64_tr_b16 v[74:75], v231 offset:512
	ds_read_b64_tr_b16 v[76:77], v231 offset:2048
	ds_read_b64_tr_b16 v[78:79], v231 offset:2560
	ds_read_b64_tr_b16 v[220:221], v231 offset:1024
	ds_read_b64_tr_b16 v[222:223], v231 offset:1536
	ds_read_b64_tr_b16 v[224:225], v231 offset:3072
	ds_read_b64_tr_b16 v[226:227], v231 offset:3584
	v_exp_f32_e32 v32, v32
	v_exp_f32_e32 v33, v33
	v_exp_f32_e32 v34, v34
	v_exp_f32_e32 v35, v35
	s_waitcnt vmcnt(8)
	ds_write_b128 v247, v[156:159]
	ds_write_b128 v247, v[160:163] offset:1024
	ds_write_b128 v247, v[164:167] offset:2048
	ds_write_b128 v247, v[168:171] offset:3072
	ds_read_b128 v[156:159], v248
	ds_read_b128 v[160:163], v249
	ds_read_b128 v[164:167], v250
	ds_read_b128 v[168:171], v251
	ds_write_b128 v112, v[172:175]
	ds_write_b128 v112, v[176:179] offset:1024
	ds_write_b128 v112, v[180:183] offset:2048
	ds_write_b128 v112, v[184:187] offset:3072
	v_exp_f32_e32 v36, v36
	v_exp_f32_e32 v37, v37
	v_exp_f32_e32 v38, v38
	v_exp_f32_e32 v39, v39
	s_waitcnt lgkmcnt(4)
	v_mfma_f32_32x32x16_bf16 v[188:203], v[156:159], v[48:51], v[188:203]
	v_exp_f32_e32 v40, v40
	v_exp_f32_e32 v41, v41
	v_mfma_f32_32x32x16_bf16 v[188:203], v[160:163], v[52:55], v[188:203]
	v_exp_f32_e32 v42, v42
	v_exp_f32_e32 v43, v43
	v_mfma_f32_32x32x16_bf16 v[188:203], v[164:167], v[56:59], v[188:203]
	v_exp_f32_e32 v44, v44
	v_exp_f32_e32 v45, v45
	v_mfma_f32_32x32x16_bf16 v[188:203], v[168:171], v[60:63], v[188:203]
	v_exp_f32_e32 v46, v46
	v_exp_f32_e32 v47, v47
	v_cvt_pk_bf16_f32 v64, v32, v33
	v_cvt_pk_bf16_f32 v65, v34, v35
	v_cvt_pk_bf16_f32 v66, v36, v37
	v_cvt_pk_bf16_f32 v67, v38, v39
	v_cvt_pk_bf16_f32 v68, v40, v41
	v_cvt_pk_bf16_f32 v69, v42, v43
	v_cvt_pk_bf16_f32 v70, v44, v45
	v_cvt_pk_bf16_f32 v71, v46, v47
	v_pk_add_f32 v[232:233], v[232:233], v[32:33]
	v_pk_add_f32 v[232:233], v[232:233], v[34:35]
	v_pk_add_f32 v[232:233], v[232:233], v[36:37]
	v_pk_add_f32 v[232:233], v[232:233], v[38:39]
	v_pk_add_f32 v[232:233], v[232:233], v[40:41]
	v_pk_add_f32 v[232:233], v[232:233], v[42:43]
	v_pk_add_f32 v[232:233], v[232:233], v[44:45]
	v_pk_add_f32 v[232:233], v[232:233], v[46:47]
	ds_read2_b32 v[32:33], v115 offset0:68 offset1:69
	ds_read2_b32 v[34:35], v115 offset0:70 offset1:71
	ds_read2_b32 v[36:37], v115 offset0:76 offset1:77
	ds_read2_b32 v[38:39], v115 offset0:78 offset1:79
	ds_read2_b32 v[40:41], v115 offset0:85 offset1:86
	ds_read2_b32 v[42:43], v115 offset0:87 offset1:88
	ds_read2_b32 v[44:45], v115 offset0:93 offset1:94
	ds_read2_b32 v[46:47], v115 offset0:95 offset1:96
	v_mfma_f32_32x32x16_bf16 v[0:15], v[64:67], v[72:75], v[0:15]
	v_mfma_f32_32x32x16_bf16 v[16:31], v[64:67], v[76:79], v[16:31]
	v_mfma_f32_32x32x16_bf16 v[0:15], v[68:71], v[220:223], v[0:15]
	v_mfma_f32_32x32x16_bf16 v[16:31], v[68:71], v[224:227], v[16:31]
	global_load_dwordx4 v[156:159], v235, s[84:85]
	global_load_dwordx4 v[160:163], v236, s[84:85]
	global_load_dwordx4 v[164:167], v237, s[84:85]
	global_load_dwordx4 v[168:171], v238, s[84:85]
	global_load_dwordx4 v[172:175], v100, s[84:85] offset:768
	global_load_dwordx4 v[176:179], v149, s[84:85] offset:768
	global_load_dwordx4 v[180:183], v100, s[84:85] offset:832
	global_load_dwordx4 v[184:187], v149, s[84:85] offset:832
	s_add_u32 s84, s84, 0x30000
	s_addc_u32 s85, s85, 0
	ds_read_b64_tr_b16 v[72:73], v231
	ds_read_b64_tr_b16 v[74:75], v231 offset:512
	ds_read_b64_tr_b16 v[76:77], v231 offset:2048
	ds_read_b64_tr_b16 v[78:79], v231 offset:2560
	ds_read_b64_tr_b16 v[220:221], v231 offset:1024
	ds_read_b64_tr_b16 v[222:223], v231 offset:1536
	ds_read_b64_tr_b16 v[224:225], v231 offset:3072
	ds_read_b64_tr_b16 v[226:227], v231 offset:3584
	v_exp_f32_e32 v188, v188
	v_exp_f32_e32 v189, v189
	v_exp_f32_e32 v190, v190
	v_exp_f32_e32 v191, v191
	s_waitcnt vmcnt(8)
	ds_write_b128 v247, v[116:119]
	ds_write_b128 v247, v[120:123] offset:1024
	ds_write_b128 v247, v[124:127] offset:2048
	ds_write_b128 v247, v[128:131] offset:3072
	ds_read_b128 v[116:119], v248
	ds_read_b128 v[120:123], v249
	ds_read_b128 v[124:127], v250
	ds_read_b128 v[128:131], v251
	ds_write_b128 v112, v[132:135]
	ds_write_b128 v112, v[136:139] offset:1024
	ds_write_b128 v112, v[140:143] offset:2048
	ds_write_b128 v112, v[144:147] offset:3072
	v_exp_f32_e32 v192, v192
	v_exp_f32_e32 v193, v193
	v_exp_f32_e32 v194, v194
	v_exp_f32_e32 v195, v195
	s_waitcnt lgkmcnt(4)
	v_mfma_f32_32x32x16_bf16 v[32:47], v[116:119], v[48:51], v[32:47]
	v_exp_f32_e32 v196, v196
	v_exp_f32_e32 v197, v197
	v_mfma_f32_32x32x16_bf16 v[32:47], v[120:123], v[52:55], v[32:47]
	v_exp_f32_e32 v198, v198
	v_exp_f32_e32 v199, v199
	v_mfma_f32_32x32x16_bf16 v[32:47], v[124:127], v[56:59], v[32:47]
	v_exp_f32_e32 v200, v200
	v_exp_f32_e32 v201, v201
	v_mfma_f32_32x32x16_bf16 v[32:47], v[128:131], v[60:63], v[32:47]
	v_exp_f32_e32 v202, v202
	v_exp_f32_e32 v203, v203
	v_cvt_pk_bf16_f32 v64, v188, v189
	v_cvt_pk_bf16_f32 v65, v190, v191
	v_cvt_pk_bf16_f32 v66, v192, v193
	v_cvt_pk_bf16_f32 v67, v194, v195
	v_cvt_pk_bf16_f32 v68, v196, v197
	v_cvt_pk_bf16_f32 v69, v198, v199
	v_cvt_pk_bf16_f32 v70, v200, v201
	v_cvt_pk_bf16_f32 v71, v202, v203
	v_pk_add_f32 v[232:233], v[232:233], v[188:189]
	v_pk_add_f32 v[232:233], v[232:233], v[190:191]
	v_pk_add_f32 v[232:233], v[232:233], v[192:193]
	v_pk_add_f32 v[232:233], v[232:233], v[194:195]
	v_pk_add_f32 v[232:233], v[232:233], v[196:197]
	v_pk_add_f32 v[232:233], v[232:233], v[198:199]
	v_pk_add_f32 v[232:233], v[232:233], v[200:201]
	v_pk_add_f32 v[232:233], v[232:233], v[202:203]
	ds_read2_b32 v[188:189], v115 offset0:102 offset1:103
	ds_read2_b32 v[190:191], v115 offset0:104 offset1:105
	ds_read2_b32 v[192:193], v115 offset0:110 offset1:111
	ds_read2_b32 v[194:195], v115 offset0:112 offset1:113
	ds_read2_b32 v[196:197], v115 offset0:119 offset1:120
	ds_read2_b32 v[198:199], v115 offset0:121 offset1:122
	ds_read2_b32 v[200:201], v115 offset0:127 offset1:128
	ds_read2_b32 v[202:203], v115 offset0:129 offset1:130
	v_mfma_f32_32x32x16_bf16 v[0:15], v[64:67], v[72:75], v[0:15]
	v_mfma_f32_32x32x16_bf16 v[16:31], v[64:67], v[76:79], v[16:31]
	v_mfma_f32_32x32x16_bf16 v[0:15], v[68:71], v[220:223], v[0:15]
	v_mfma_f32_32x32x16_bf16 v[16:31], v[68:71], v[224:227], v[16:31]
	global_load_dwordx4 v[116:119], v235, s[84:85]
	global_load_dwordx4 v[120:123], v236, s[84:85]
	global_load_dwordx4 v[124:127], v237, s[84:85]
	global_load_dwordx4 v[128:131], v238, s[84:85]
	global_load_dwordx4 v[132:135], v100, s[84:85] offset:768
	global_load_dwordx4 v[136:139], v149, s[84:85] offset:768
	global_load_dwordx4 v[140:143], v100, s[84:85] offset:832
	global_load_dwordx4 v[144:147], v149, s[84:85] offset:832
	s_add_u32 s84, s84, 0x30000
	s_addc_u32 s85, s85, 0
	ds_read_b64_tr_b16 v[72:73], v231
	ds_read_b64_tr_b16 v[74:75], v231 offset:512
	ds_read_b64_tr_b16 v[76:77], v231 offset:2048
	ds_read_b64_tr_b16 v[78:79], v231 offset:2560
	ds_read_b64_tr_b16 v[220:221], v231 offset:1024
	ds_read_b64_tr_b16 v[222:223], v231 offset:1536
	ds_read_b64_tr_b16 v[224:225], v231 offset:3072
	ds_read_b64_tr_b16 v[226:227], v231 offset:3584
	v_exp_f32_e32 v32, v32
	v_exp_f32_e32 v33, v33
	v_exp_f32_e32 v34, v34
	v_exp_f32_e32 v35, v35
	s_waitcnt vmcnt(8)
	ds_write_b128 v247, v[156:159]
	ds_write_b128 v247, v[160:163] offset:1024
	ds_write_b128 v247, v[164:167] offset:2048
	ds_write_b128 v247, v[168:171] offset:3072
	ds_read_b128 v[156:159], v248
	ds_read_b128 v[160:163], v249
	ds_read_b128 v[164:167], v250
	ds_read_b128 v[168:171], v251
	ds_write_b128 v112, v[172:175]
	ds_write_b128 v112, v[176:179] offset:1024
	ds_write_b128 v112, v[180:183] offset:2048
	ds_write_b128 v112, v[184:187] offset:3072
	v_exp_f32_e32 v36, v36
	v_exp_f32_e32 v37, v37
	v_exp_f32_e32 v38, v38
	v_exp_f32_e32 v39, v39
	s_waitcnt lgkmcnt(4)
	v_mfma_f32_32x32x16_bf16 v[188:203], v[156:159], v[48:51], v[188:203]
	v_exp_f32_e32 v40, v40
	v_exp_f32_e32 v41, v41
	v_mfma_f32_32x32x16_bf16 v[188:203], v[160:163], v[52:55], v[188:203]
	v_exp_f32_e32 v42, v42
	v_exp_f32_e32 v43, v43
	v_mfma_f32_32x32x16_bf16 v[188:203], v[164:167], v[56:59], v[188:203]
	v_exp_f32_e32 v44, v44
	v_exp_f32_e32 v45, v45
	v_mfma_f32_32x32x16_bf16 v[188:203], v[168:171], v[60:63], v[188:203]
	v_exp_f32_e32 v46, v46
	v_exp_f32_e32 v47, v47
	v_cvt_pk_bf16_f32 v64, v32, v33
	v_cvt_pk_bf16_f32 v65, v34, v35
	v_cvt_pk_bf16_f32 v66, v36, v37
	v_cvt_pk_bf16_f32 v67, v38, v39
	v_cvt_pk_bf16_f32 v68, v40, v41
	v_cvt_pk_bf16_f32 v69, v42, v43
	v_cvt_pk_bf16_f32 v70, v44, v45
	v_cvt_pk_bf16_f32 v71, v46, v47
	v_pk_add_f32 v[232:233], v[232:233], v[32:33]
	v_pk_add_f32 v[232:233], v[232:233], v[34:35]
	v_pk_add_f32 v[232:233], v[232:233], v[36:37]
	v_pk_add_f32 v[232:233], v[232:233], v[38:39]
	v_pk_add_f32 v[232:233], v[232:233], v[40:41]
	v_pk_add_f32 v[232:233], v[232:233], v[42:43]
	v_pk_add_f32 v[232:233], v[232:233], v[44:45]
	v_pk_add_f32 v[232:233], v[232:233], v[46:47]
	ds_read2_b32 v[32:33], v115 offset0:136 offset1:137
	ds_read2_b32 v[34:35], v115 offset0:138 offset1:139
	ds_read2_b32 v[36:37], v115 offset0:144 offset1:145
	ds_read2_b32 v[38:39], v115 offset0:146 offset1:147
	ds_read2_b32 v[40:41], v115 offset0:153 offset1:154
	ds_read2_b32 v[42:43], v115 offset0:155 offset1:156
	ds_read2_b32 v[44:45], v115 offset0:161 offset1:162
	ds_read2_b32 v[46:47], v115 offset0:163 offset1:164
	v_mfma_f32_32x32x16_bf16 v[0:15], v[64:67], v[72:75], v[0:15]
	v_mfma_f32_32x32x16_bf16 v[16:31], v[64:67], v[76:79], v[16:31]
	v_mfma_f32_32x32x16_bf16 v[0:15], v[68:71], v[220:223], v[0:15]
	v_mfma_f32_32x32x16_bf16 v[16:31], v[68:71], v[224:227], v[16:31]
	global_load_dwordx4 v[156:159], v235, s[84:85]
	global_load_dwordx4 v[160:163], v236, s[84:85]
	global_load_dwordx4 v[164:167], v237, s[84:85]
	global_load_dwordx4 v[168:171], v238, s[84:85]
	global_load_dwordx4 v[172:175], v100, s[84:85] offset:768
	global_load_dwordx4 v[176:179], v149, s[84:85] offset:768
	global_load_dwordx4 v[180:183], v100, s[84:85] offset:832
	global_load_dwordx4 v[184:187], v149, s[84:85] offset:832
	s_add_u32 s84, s84, 0x30000
	s_addc_u32 s85, s85, 0
	ds_read_b64_tr_b16 v[72:73], v231
	ds_read_b64_tr_b16 v[74:75], v231 offset:512
	ds_read_b64_tr_b16 v[76:77], v231 offset:2048
	ds_read_b64_tr_b16 v[78:79], v231 offset:2560
	ds_read_b64_tr_b16 v[220:221], v231 offset:1024
	ds_read_b64_tr_b16 v[222:223], v231 offset:1536
	ds_read_b64_tr_b16 v[224:225], v231 offset:3072
	ds_read_b64_tr_b16 v[226:227], v231 offset:3584
	v_exp_f32_e32 v188, v188
	v_exp_f32_e32 v189, v189
	v_exp_f32_e32 v190, v190
	v_exp_f32_e32 v191, v191
	s_waitcnt vmcnt(8)
	ds_write_b128 v247, v[116:119]
	ds_write_b128 v247, v[120:123] offset:1024
	ds_write_b128 v247, v[124:127] offset:2048
	ds_write_b128 v247, v[128:131] offset:3072
	ds_read_b128 v[116:119], v248
	ds_read_b128 v[120:123], v249
	ds_read_b128 v[124:127], v250
	ds_read_b128 v[128:131], v251
	ds_write_b128 v112, v[132:135]
	ds_write_b128 v112, v[136:139] offset:1024
	ds_write_b128 v112, v[140:143] offset:2048
	ds_write_b128 v112, v[144:147] offset:3072
	v_exp_f32_e32 v192, v192
	v_exp_f32_e32 v193, v193
	v_exp_f32_e32 v194, v194
	v_exp_f32_e32 v195, v195
	s_waitcnt lgkmcnt(4)
	v_mfma_f32_32x32x16_bf16 v[32:47], v[116:119], v[48:51], v[32:47]
	v_exp_f32_e32 v196, v196
	v_exp_f32_e32 v197, v197
	v_mfma_f32_32x32x16_bf16 v[32:47], v[120:123], v[52:55], v[32:47]
	v_exp_f32_e32 v198, v198
	v_exp_f32_e32 v199, v199
	v_mfma_f32_32x32x16_bf16 v[32:47], v[124:127], v[56:59], v[32:47]
	v_exp_f32_e32 v200, v200
	v_exp_f32_e32 v201, v201
	v_mfma_f32_32x32x16_bf16 v[32:47], v[128:131], v[60:63], v[32:47]
	v_exp_f32_e32 v202, v202
	v_exp_f32_e32 v203, v203
	v_cvt_pk_bf16_f32 v64, v188, v189
	v_cvt_pk_bf16_f32 v65, v190, v191
	v_cvt_pk_bf16_f32 v66, v192, v193
	v_cvt_pk_bf16_f32 v67, v194, v195
	v_cvt_pk_bf16_f32 v68, v196, v197
	v_cvt_pk_bf16_f32 v69, v198, v199
	v_cvt_pk_bf16_f32 v70, v200, v201
	v_cvt_pk_bf16_f32 v71, v202, v203
	v_pk_add_f32 v[232:233], v[232:233], v[188:189]
	v_pk_add_f32 v[232:233], v[232:233], v[190:191]
	v_pk_add_f32 v[232:233], v[232:233], v[192:193]
	v_pk_add_f32 v[232:233], v[232:233], v[194:195]
	v_pk_add_f32 v[232:233], v[232:233], v[196:197]
	v_pk_add_f32 v[232:233], v[232:233], v[198:199]
	v_pk_add_f32 v[232:233], v[232:233], v[200:201]
	v_pk_add_f32 v[232:233], v[232:233], v[202:203]
	ds_read2_b32 v[188:189], v115 offset0:170 offset1:171
	ds_read2_b32 v[190:191], v115 offset0:172 offset1:173
	ds_read2_b32 v[192:193], v115 offset0:178 offset1:179
	ds_read2_b32 v[194:195], v115 offset0:180 offset1:181
	ds_read2_b32 v[196:197], v115 offset0:187 offset1:188
	ds_read2_b32 v[198:199], v115 offset0:189 offset1:190
	ds_read2_b32 v[200:201], v115 offset0:195 offset1:196
	ds_read2_b32 v[202:203], v115 offset0:197 offset1:198
	v_mfma_f32_32x32x16_bf16 v[0:15], v[64:67], v[72:75], v[0:15]
	v_mfma_f32_32x32x16_bf16 v[16:31], v[64:67], v[76:79], v[16:31]
	v_mfma_f32_32x32x16_bf16 v[0:15], v[68:71], v[220:223], v[0:15]
	v_mfma_f32_32x32x16_bf16 v[16:31], v[68:71], v[224:227], v[16:31]
	global_load_dwordx4 v[116:119], v235, s[84:85]
	global_load_dwordx4 v[120:123], v236, s[84:85]
	global_load_dwordx4 v[124:127], v237, s[84:85]
	global_load_dwordx4 v[128:131], v238, s[84:85]
	global_load_dwordx4 v[132:135], v100, s[84:85] offset:768
	global_load_dwordx4 v[136:139], v149, s[84:85] offset:768
	global_load_dwordx4 v[140:143], v100, s[84:85] offset:832
	global_load_dwordx4 v[144:147], v149, s[84:85] offset:832
	s_add_u32 s84, s84, 0x30000
	s_addc_u32 s85, s85, 0
	ds_read_b64_tr_b16 v[72:73], v231
	ds_read_b64_tr_b16 v[74:75], v231 offset:512
	ds_read_b64_tr_b16 v[76:77], v231 offset:2048
	ds_read_b64_tr_b16 v[78:79], v231 offset:2560
	ds_read_b64_tr_b16 v[220:221], v231 offset:1024
	ds_read_b64_tr_b16 v[222:223], v231 offset:1536
	ds_read_b64_tr_b16 v[224:225], v231 offset:3072
	ds_read_b64_tr_b16 v[226:227], v231 offset:3584
	v_exp_f32_e32 v32, v32
	v_exp_f32_e32 v33, v33
	v_exp_f32_e32 v34, v34
	v_exp_f32_e32 v35, v35
	s_waitcnt vmcnt(8)
	ds_write_b128 v247, v[156:159]
	ds_write_b128 v247, v[160:163] offset:1024
	ds_write_b128 v247, v[164:167] offset:2048
	ds_write_b128 v247, v[168:171] offset:3072
	ds_read_b128 v[156:159], v248
	ds_read_b128 v[160:163], v249
	ds_read_b128 v[164:167], v250
	ds_read_b128 v[168:171], v251
	ds_write_b128 v112, v[172:175]
	ds_write_b128 v112, v[176:179] offset:1024
	ds_write_b128 v112, v[180:183] offset:2048
	ds_write_b128 v112, v[184:187] offset:3072
	v_exp_f32_e32 v36, v36
	v_exp_f32_e32 v37, v37
	v_exp_f32_e32 v38, v38
	v_exp_f32_e32 v39, v39
	s_waitcnt lgkmcnt(4)
	v_mfma_f32_32x32x16_bf16 v[188:203], v[156:159], v[48:51], v[188:203]
	v_exp_f32_e32 v40, v40
	v_exp_f32_e32 v41, v41
	v_mfma_f32_32x32x16_bf16 v[188:203], v[160:163], v[52:55], v[188:203]
	v_exp_f32_e32 v42, v42
	v_exp_f32_e32 v43, v43
	v_mfma_f32_32x32x16_bf16 v[188:203], v[164:167], v[56:59], v[188:203]
	v_exp_f32_e32 v44, v44
	v_exp_f32_e32 v45, v45
	v_mfma_f32_32x32x16_bf16 v[188:203], v[168:171], v[60:63], v[188:203]
	v_exp_f32_e32 v46, v46
	v_exp_f32_e32 v47, v47
	v_cvt_pk_bf16_f32 v64, v32, v33
	v_cvt_pk_bf16_f32 v65, v34, v35
	v_cvt_pk_bf16_f32 v66, v36, v37
	v_cvt_pk_bf16_f32 v67, v38, v39
	v_cvt_pk_bf16_f32 v68, v40, v41
	v_cvt_pk_bf16_f32 v69, v42, v43
	v_cvt_pk_bf16_f32 v70, v44, v45
	v_cvt_pk_bf16_f32 v71, v46, v47
	v_pk_add_f32 v[232:233], v[232:233], v[32:33]
	v_pk_add_f32 v[232:233], v[232:233], v[34:35]
	v_pk_add_f32 v[232:233], v[232:233], v[36:37]
	v_pk_add_f32 v[232:233], v[232:233], v[38:39]
	v_pk_add_f32 v[232:233], v[232:233], v[40:41]
	v_pk_add_f32 v[232:233], v[232:233], v[42:43]
	v_pk_add_f32 v[232:233], v[232:233], v[44:45]
	v_pk_add_f32 v[232:233], v[232:233], v[46:47]
	ds_read2_b32 v[32:33], v115 offset0:204 offset1:205
	ds_read2_b32 v[34:35], v115 offset0:206 offset1:207
	ds_read2_b32 v[36:37], v115 offset0:212 offset1:213
	ds_read2_b32 v[38:39], v115 offset0:214 offset1:215
	ds_read2_b32 v[40:41], v115 offset0:221 offset1:222
	ds_read2_b32 v[42:43], v115 offset0:223 offset1:224
	ds_read2_b32 v[44:45], v115 offset0:229 offset1:230
	ds_read2_b32 v[46:47], v115 offset0:231 offset1:232
	v_mfma_f32_32x32x16_bf16 v[0:15], v[64:67], v[72:75], v[0:15]
	v_mfma_f32_32x32x16_bf16 v[16:31], v[64:67], v[76:79], v[16:31]
	v_mfma_f32_32x32x16_bf16 v[0:15], v[68:71], v[220:223], v[0:15]
	v_mfma_f32_32x32x16_bf16 v[16:31], v[68:71], v[224:227], v[16:31]
	global_load_dwordx4 v[156:159], v235, s[84:85]
	global_load_dwordx4 v[160:163], v236, s[84:85]
	global_load_dwordx4 v[164:167], v237, s[84:85]
	global_load_dwordx4 v[168:171], v238, s[84:85]
	global_load_dwordx4 v[172:175], v100, s[84:85] offset:768
	global_load_dwordx4 v[176:179], v149, s[84:85] offset:768
	global_load_dwordx4 v[180:183], v100, s[84:85] offset:832
	global_load_dwordx4 v[184:187], v149, s[84:85] offset:832
	s_add_u32 s84, s84, 0x30000
	s_addc_u32 s85, s85, 0
	ds_read_b64_tr_b16 v[72:73], v231
	ds_read_b64_tr_b16 v[74:75], v231 offset:512
	ds_read_b64_tr_b16 v[76:77], v231 offset:2048
	ds_read_b64_tr_b16 v[78:79], v231 offset:2560
	ds_read_b64_tr_b16 v[220:221], v231 offset:1024
	ds_read_b64_tr_b16 v[222:223], v231 offset:1536
	ds_read_b64_tr_b16 v[224:225], v231 offset:3072
	ds_read_b64_tr_b16 v[226:227], v231 offset:3584
	v_exp_f32_e32 v188, v188
	v_exp_f32_e32 v189, v189
	v_exp_f32_e32 v190, v190
	v_exp_f32_e32 v191, v191
	s_waitcnt vmcnt(8)
	ds_write_b128 v247, v[116:119]
	ds_write_b128 v247, v[120:123] offset:1024
	ds_write_b128 v247, v[124:127] offset:2048
	ds_write_b128 v247, v[128:131] offset:3072
	ds_read_b128 v[116:119], v248
	ds_read_b128 v[120:123], v249
	ds_read_b128 v[124:127], v250
	ds_read_b128 v[128:131], v251
	ds_write_b128 v112, v[132:135]
	ds_write_b128 v112, v[136:139] offset:1024
	ds_write_b128 v112, v[140:143] offset:2048
	ds_write_b128 v112, v[144:147] offset:3072
	v_exp_f32_e32 v192, v192
	v_exp_f32_e32 v193, v193
	v_exp_f32_e32 v194, v194
	v_exp_f32_e32 v195, v195
	s_waitcnt lgkmcnt(4)
	v_mfma_f32_32x32x16_bf16 v[32:47], v[116:119], v[48:51], v[32:47]
	v_exp_f32_e32 v196, v196
	v_exp_f32_e32 v197, v197
	v_mfma_f32_32x32x16_bf16 v[32:47], v[120:123], v[52:55], v[32:47]
	v_exp_f32_e32 v198, v198
	v_exp_f32_e32 v199, v199
	v_mfma_f32_32x32x16_bf16 v[32:47], v[124:127], v[56:59], v[32:47]
	v_exp_f32_e32 v200, v200
	v_exp_f32_e32 v201, v201
	v_mfma_f32_32x32x16_bf16 v[32:47], v[128:131], v[60:63], v[32:47]
	v_exp_f32_e32 v202, v202
	v_exp_f32_e32 v203, v203
	v_cvt_pk_bf16_f32 v64, v188, v189
	v_cvt_pk_bf16_f32 v65, v190, v191
	v_cvt_pk_bf16_f32 v66, v192, v193
	v_cvt_pk_bf16_f32 v67, v194, v195
	v_cvt_pk_bf16_f32 v68, v196, v197
	v_cvt_pk_bf16_f32 v69, v198, v199
	v_cvt_pk_bf16_f32 v70, v200, v201
	v_cvt_pk_bf16_f32 v71, v202, v203
	v_pk_add_f32 v[232:233], v[232:233], v[188:189]
	v_pk_add_f32 v[232:233], v[232:233], v[190:191]
	v_pk_add_f32 v[232:233], v[232:233], v[192:193]
	v_pk_add_f32 v[232:233], v[232:233], v[194:195]
	v_pk_add_f32 v[232:233], v[232:233], v[196:197]
	v_pk_add_f32 v[232:233], v[232:233], v[198:199]
	v_pk_add_f32 v[232:233], v[232:233], v[200:201]
	v_pk_add_f32 v[232:233], v[232:233], v[202:203]
	v_add_u32_e32 v115, 952, v115
	ds_read2_b32 v[188:189], v115 offset0:0 offset1:1
	ds_read2_b32 v[190:191], v115 offset0:2 offset1:3
	ds_read2_b32 v[192:193], v115 offset0:8 offset1:9
	ds_read2_b32 v[194:195], v115 offset0:10 offset1:11
	ds_read2_b32 v[196:197], v115 offset0:17 offset1:18
	ds_read2_b32 v[198:199], v115 offset0:19 offset1:20
	ds_read2_b32 v[200:201], v115 offset0:25 offset1:26
	ds_read2_b32 v[202:203], v115 offset0:27 offset1:28
	v_mfma_f32_32x32x16_bf16 v[0:15], v[64:67], v[72:75], v[0:15]
	v_mfma_f32_32x32x16_bf16 v[16:31], v[64:67], v[76:79], v[16:31]
	v_mfma_f32_32x32x16_bf16 v[0:15], v[68:71], v[220:223], v[0:15]
	v_mfma_f32_32x32x16_bf16 v[16:31], v[68:71], v[224:227], v[16:31]
	global_load_dwordx4 v[116:119], v235, s[84:85]
	global_load_dwordx4 v[120:123], v236, s[84:85]
	global_load_dwordx4 v[124:127], v237, s[84:85]
	global_load_dwordx4 v[128:131], v238, s[84:85]
	global_load_dwordx4 v[132:135], v100, s[84:85] offset:768
	global_load_dwordx4 v[136:139], v149, s[84:85] offset:768
	global_load_dwordx4 v[140:143], v100, s[84:85] offset:832
	global_load_dwordx4 v[144:147], v149, s[84:85] offset:832
	s_add_u32 s84, s84, 0x30000
	s_addc_u32 s85, s85, 0
	ds_read_b64_tr_b16 v[72:73], v231
	ds_read_b64_tr_b16 v[74:75], v231 offset:512
	ds_read_b64_tr_b16 v[76:77], v231 offset:2048
	ds_read_b64_tr_b16 v[78:79], v231 offset:2560
	ds_read_b64_tr_b16 v[220:221], v231 offset:1024
	ds_read_b64_tr_b16 v[222:223], v231 offset:1536
	ds_read_b64_tr_b16 v[224:225], v231 offset:3072
	ds_read_b64_tr_b16 v[226:227], v231 offset:3584
	v_exp_f32_e32 v32, v32
	v_exp_f32_e32 v33, v33
	v_exp_f32_e32 v34, v34
	v_exp_f32_e32 v35, v35
	s_waitcnt vmcnt(8)
	ds_write_b128 v247, v[156:159]
	ds_write_b128 v247, v[160:163] offset:1024
	ds_write_b128 v247, v[164:167] offset:2048
	ds_write_b128 v247, v[168:171] offset:3072
	ds_read_b128 v[156:159], v248
	ds_read_b128 v[160:163], v249
	ds_read_b128 v[164:167], v250
	ds_read_b128 v[168:171], v251
	ds_write_b128 v112, v[172:175]
	ds_write_b128 v112, v[176:179] offset:1024
	ds_write_b128 v112, v[180:183] offset:2048
	ds_write_b128 v112, v[184:187] offset:3072
	v_exp_f32_e32 v36, v36
	v_exp_f32_e32 v37, v37
	v_exp_f32_e32 v38, v38
	v_exp_f32_e32 v39, v39
	s_waitcnt lgkmcnt(4)
	v_mfma_f32_32x32x16_bf16 v[188:203], v[156:159], v[48:51], v[188:203]
	v_exp_f32_e32 v40, v40
	v_exp_f32_e32 v41, v41
	v_mfma_f32_32x32x16_bf16 v[188:203], v[160:163], v[52:55], v[188:203]
	v_exp_f32_e32 v42, v42
	v_exp_f32_e32 v43, v43
	v_mfma_f32_32x32x16_bf16 v[188:203], v[164:167], v[56:59], v[188:203]
	v_exp_f32_e32 v44, v44
	v_exp_f32_e32 v45, v45
	v_mfma_f32_32x32x16_bf16 v[188:203], v[168:171], v[60:63], v[188:203]
	v_exp_f32_e32 v46, v46
	v_exp_f32_e32 v47, v47
	v_cvt_pk_bf16_f32 v64, v32, v33
	v_cvt_pk_bf16_f32 v65, v34, v35
	v_cvt_pk_bf16_f32 v66, v36, v37
	v_cvt_pk_bf16_f32 v67, v38, v39
	v_cvt_pk_bf16_f32 v68, v40, v41
	v_cvt_pk_bf16_f32 v69, v42, v43
	v_cvt_pk_bf16_f32 v70, v44, v45
	v_cvt_pk_bf16_f32 v71, v46, v47
	v_pk_add_f32 v[232:233], v[232:233], v[32:33]
	v_pk_add_f32 v[232:233], v[232:233], v[34:35]
	v_pk_add_f32 v[232:233], v[232:233], v[36:37]
	v_pk_add_f32 v[232:233], v[232:233], v[38:39]
	v_pk_add_f32 v[232:233], v[232:233], v[40:41]
	v_pk_add_f32 v[232:233], v[232:233], v[42:43]
	v_pk_add_f32 v[232:233], v[232:233], v[44:45]
	v_pk_add_f32 v[232:233], v[232:233], v[46:47]
	ds_read2_b32 v[32:33], v115 offset0:34 offset1:35
	ds_read2_b32 v[34:35], v115 offset0:36 offset1:37
	ds_read2_b32 v[36:37], v115 offset0:42 offset1:43
	ds_read2_b32 v[38:39], v115 offset0:44 offset1:45
	ds_read2_b32 v[40:41], v115 offset0:51 offset1:52
	ds_read2_b32 v[42:43], v115 offset0:53 offset1:54
	ds_read2_b32 v[44:45], v115 offset0:59 offset1:60
	ds_read2_b32 v[46:47], v115 offset0:61 offset1:62
	v_mfma_f32_32x32x16_bf16 v[0:15], v[64:67], v[72:75], v[0:15]
	v_mfma_f32_32x32x16_bf16 v[16:31], v[64:67], v[76:79], v[16:31]
	v_mfma_f32_32x32x16_bf16 v[0:15], v[68:71], v[220:223], v[0:15]
	v_mfma_f32_32x32x16_bf16 v[16:31], v[68:71], v[224:227], v[16:31]
	global_load_dwordx4 v[156:159], v235, s[84:85]
	global_load_dwordx4 v[160:163], v236, s[84:85]
	global_load_dwordx4 v[164:167], v237, s[84:85]
	global_load_dwordx4 v[168:171], v238, s[84:85]
	global_load_dwordx4 v[172:175], v100, s[84:85] offset:768
	global_load_dwordx4 v[176:179], v149, s[84:85] offset:768
	global_load_dwordx4 v[180:183], v100, s[84:85] offset:832
	global_load_dwordx4 v[184:187], v149, s[84:85] offset:832
	s_add_u32 s84, s84, 0x30000
	s_addc_u32 s85, s85, 0
	ds_read_b64_tr_b16 v[72:73], v231
	ds_read_b64_tr_b16 v[74:75], v231 offset:512
	ds_read_b64_tr_b16 v[76:77], v231 offset:2048
	ds_read_b64_tr_b16 v[78:79], v231 offset:2560
	ds_read_b64_tr_b16 v[220:221], v231 offset:1024
	ds_read_b64_tr_b16 v[222:223], v231 offset:1536
	ds_read_b64_tr_b16 v[224:225], v231 offset:3072
	ds_read_b64_tr_b16 v[226:227], v231 offset:3584
	v_exp_f32_e32 v188, v188
	v_exp_f32_e32 v189, v189
	v_exp_f32_e32 v190, v190
	v_exp_f32_e32 v191, v191
	s_waitcnt vmcnt(8)
	ds_write_b128 v247, v[116:119]
	ds_write_b128 v247, v[120:123] offset:1024
	ds_write_b128 v247, v[124:127] offset:2048
	ds_write_b128 v247, v[128:131] offset:3072
	ds_read_b128 v[116:119], v248
	ds_read_b128 v[120:123], v249
	ds_read_b128 v[124:127], v250
	ds_read_b128 v[128:131], v251
	ds_write_b128 v112, v[132:135]
	ds_write_b128 v112, v[136:139] offset:1024
	ds_write_b128 v112, v[140:143] offset:2048
	ds_write_b128 v112, v[144:147] offset:3072
	v_exp_f32_e32 v192, v192
	v_exp_f32_e32 v193, v193
	v_exp_f32_e32 v194, v194
	v_exp_f32_e32 v195, v195
	s_waitcnt lgkmcnt(4)
	v_mfma_f32_32x32x16_bf16 v[32:47], v[116:119], v[48:51], v[32:47]
	v_exp_f32_e32 v196, v196
	v_exp_f32_e32 v197, v197
	v_mfma_f32_32x32x16_bf16 v[32:47], v[120:123], v[52:55], v[32:47]
	v_exp_f32_e32 v198, v198
	v_exp_f32_e32 v199, v199
	v_mfma_f32_32x32x16_bf16 v[32:47], v[124:127], v[56:59], v[32:47]
	v_exp_f32_e32 v200, v200
	v_exp_f32_e32 v201, v201
	v_mfma_f32_32x32x16_bf16 v[32:47], v[128:131], v[60:63], v[32:47]
	v_exp_f32_e32 v202, v202
	v_exp_f32_e32 v203, v203
	v_cvt_pk_bf16_f32 v64, v188, v189
	v_cvt_pk_bf16_f32 v65, v190, v191
	v_cvt_pk_bf16_f32 v66, v192, v193
	v_cvt_pk_bf16_f32 v67, v194, v195
	v_cvt_pk_bf16_f32 v68, v196, v197
	v_cvt_pk_bf16_f32 v69, v198, v199
	v_cvt_pk_bf16_f32 v70, v200, v201
	v_cvt_pk_bf16_f32 v71, v202, v203
	v_pk_add_f32 v[232:233], v[232:233], v[188:189]
	v_pk_add_f32 v[232:233], v[232:233], v[190:191]
	v_pk_add_f32 v[232:233], v[232:233], v[192:193]
	v_pk_add_f32 v[232:233], v[232:233], v[194:195]
	v_pk_add_f32 v[232:233], v[232:233], v[196:197]
	v_pk_add_f32 v[232:233], v[232:233], v[198:199]
	v_pk_add_f32 v[232:233], v[232:233], v[200:201]
	v_pk_add_f32 v[232:233], v[232:233], v[202:203]
	ds_read2_b32 v[188:189], v115 offset0:68 offset1:69
	ds_read2_b32 v[190:191], v115 offset0:70 offset1:71
	ds_read2_b32 v[192:193], v115 offset0:76 offset1:77
	ds_read2_b32 v[194:195], v115 offset0:78 offset1:79
	ds_read2_b32 v[196:197], v115 offset0:85 offset1:86
	ds_read2_b32 v[198:199], v115 offset0:87 offset1:88
	ds_read2_b32 v[200:201], v115 offset0:93 offset1:94
	ds_read2_b32 v[202:203], v115 offset0:95 offset1:96
	v_mfma_f32_32x32x16_bf16 v[0:15], v[64:67], v[72:75], v[0:15]
	v_mfma_f32_32x32x16_bf16 v[16:31], v[64:67], v[76:79], v[16:31]
	v_mfma_f32_32x32x16_bf16 v[0:15], v[68:71], v[220:223], v[0:15]
	v_mfma_f32_32x32x16_bf16 v[16:31], v[68:71], v[224:227], v[16:31]
	global_load_dwordx4 v[116:119], v235, s[84:85]
	global_load_dwordx4 v[120:123], v236, s[84:85]
	global_load_dwordx4 v[124:127], v237, s[84:85]
	global_load_dwordx4 v[128:131], v238, s[84:85]
	global_load_dwordx4 v[132:135], v100, s[84:85] offset:768
	global_load_dwordx4 v[136:139], v149, s[84:85] offset:768
	global_load_dwordx4 v[140:143], v100, s[84:85] offset:832
	global_load_dwordx4 v[144:147], v149, s[84:85] offset:832
	s_add_u32 s84, s84, 0x30000
	s_addc_u32 s85, s85, 0
	ds_read_b64_tr_b16 v[72:73], v231
	ds_read_b64_tr_b16 v[74:75], v231 offset:512
	ds_read_b64_tr_b16 v[76:77], v231 offset:2048
	ds_read_b64_tr_b16 v[78:79], v231 offset:2560
	ds_read_b64_tr_b16 v[220:221], v231 offset:1024
	ds_read_b64_tr_b16 v[222:223], v231 offset:1536
	ds_read_b64_tr_b16 v[224:225], v231 offset:3072
	ds_read_b64_tr_b16 v[226:227], v231 offset:3584
	v_exp_f32_e32 v32, v32
	v_exp_f32_e32 v33, v33
	v_exp_f32_e32 v34, v34
	v_exp_f32_e32 v35, v35
	s_waitcnt vmcnt(8)
	ds_write_b128 v247, v[156:159]
	ds_write_b128 v247, v[160:163] offset:1024
	ds_write_b128 v247, v[164:167] offset:2048
	ds_write_b128 v247, v[168:171] offset:3072
	ds_read_b128 v[156:159], v248
	ds_read_b128 v[160:163], v249
	ds_read_b128 v[164:167], v250
	ds_read_b128 v[168:171], v251
	ds_write_b128 v112, v[172:175]
	ds_write_b128 v112, v[176:179] offset:1024
	ds_write_b128 v112, v[180:183] offset:2048
	ds_write_b128 v112, v[184:187] offset:3072
	v_exp_f32_e32 v36, v36
	v_exp_f32_e32 v37, v37
	v_exp_f32_e32 v38, v38
	v_exp_f32_e32 v39, v39
	s_waitcnt lgkmcnt(4)
	v_mfma_f32_32x32x16_bf16 v[188:203], v[156:159], v[48:51], v[188:203]
	v_exp_f32_e32 v40, v40
	v_exp_f32_e32 v41, v41
	v_mfma_f32_32x32x16_bf16 v[188:203], v[160:163], v[52:55], v[188:203]
	v_exp_f32_e32 v42, v42
	v_exp_f32_e32 v43, v43
	v_mfma_f32_32x32x16_bf16 v[188:203], v[164:167], v[56:59], v[188:203]
	v_exp_f32_e32 v44, v44
	v_exp_f32_e32 v45, v45
	v_mfma_f32_32x32x16_bf16 v[188:203], v[168:171], v[60:63], v[188:203]
	v_exp_f32_e32 v46, v46
	v_exp_f32_e32 v47, v47
	v_cvt_pk_bf16_f32 v64, v32, v33
	v_cvt_pk_bf16_f32 v65, v34, v35
	v_cvt_pk_bf16_f32 v66, v36, v37
	v_cvt_pk_bf16_f32 v67, v38, v39
	v_cvt_pk_bf16_f32 v68, v40, v41
	v_cvt_pk_bf16_f32 v69, v42, v43
	v_cvt_pk_bf16_f32 v70, v44, v45
	v_cvt_pk_bf16_f32 v71, v46, v47
	v_pk_add_f32 v[232:233], v[232:233], v[32:33]
	v_pk_add_f32 v[232:233], v[232:233], v[34:35]
	v_pk_add_f32 v[232:233], v[232:233], v[36:37]
	v_pk_add_f32 v[232:233], v[232:233], v[38:39]
	v_pk_add_f32 v[232:233], v[232:233], v[40:41]
	v_pk_add_f32 v[232:233], v[232:233], v[42:43]
	v_pk_add_f32 v[232:233], v[232:233], v[44:45]
	v_pk_add_f32 v[232:233], v[232:233], v[46:47]
	ds_read2_b32 v[32:33], v115 offset0:102 offset1:103
	ds_read2_b32 v[34:35], v115 offset0:104 offset1:105
	ds_read2_b32 v[36:37], v115 offset0:110 offset1:111
	ds_read2_b32 v[38:39], v115 offset0:112 offset1:113
	ds_read2_b32 v[40:41], v115 offset0:119 offset1:120
	ds_read2_b32 v[42:43], v115 offset0:121 offset1:122
	ds_read2_b32 v[44:45], v115 offset0:127 offset1:128
	ds_read2_b32 v[46:47], v115 offset0:129 offset1:130
	v_mfma_f32_32x32x16_bf16 v[0:15], v[64:67], v[72:75], v[0:15]
	v_mfma_f32_32x32x16_bf16 v[16:31], v[64:67], v[76:79], v[16:31]
	v_mfma_f32_32x32x16_bf16 v[0:15], v[68:71], v[220:223], v[0:15]
	v_mfma_f32_32x32x16_bf16 v[16:31], v[68:71], v[224:227], v[16:31]
	global_load_dwordx4 v[156:159], v235, s[84:85]
	global_load_dwordx4 v[160:163], v236, s[84:85]
	global_load_dwordx4 v[164:167], v237, s[84:85]
	global_load_dwordx4 v[168:171], v238, s[84:85]
	global_load_dwordx4 v[172:175], v100, s[84:85] offset:768
	global_load_dwordx4 v[176:179], v149, s[84:85] offset:768
	global_load_dwordx4 v[180:183], v100, s[84:85] offset:832
	global_load_dwordx4 v[184:187], v149, s[84:85] offset:832
	s_add_u32 s84, s84, 0x30000
	s_addc_u32 s85, s85, 0
	ds_read_b64_tr_b16 v[72:73], v231
	ds_read_b64_tr_b16 v[74:75], v231 offset:512
	ds_read_b64_tr_b16 v[76:77], v231 offset:2048
	ds_read_b64_tr_b16 v[78:79], v231 offset:2560
	ds_read_b64_tr_b16 v[220:221], v231 offset:1024
	ds_read_b64_tr_b16 v[222:223], v231 offset:1536
	ds_read_b64_tr_b16 v[224:225], v231 offset:3072
	ds_read_b64_tr_b16 v[226:227], v231 offset:3584
	v_exp_f32_e32 v188, v188
	v_exp_f32_e32 v189, v189
	v_exp_f32_e32 v190, v190
	v_exp_f32_e32 v191, v191
	s_waitcnt vmcnt(8)
	ds_write_b128 v247, v[116:119]
	ds_write_b128 v247, v[120:123] offset:1024
	ds_write_b128 v247, v[124:127] offset:2048
	ds_write_b128 v247, v[128:131] offset:3072
	ds_read_b128 v[116:119], v248
	ds_read_b128 v[120:123], v249
	ds_read_b128 v[124:127], v250
	ds_read_b128 v[128:131], v251
	ds_write_b128 v112, v[132:135]
	ds_write_b128 v112, v[136:139] offset:1024
	ds_write_b128 v112, v[140:143] offset:2048
	ds_write_b128 v112, v[144:147] offset:3072
	v_exp_f32_e32 v192, v192
	v_exp_f32_e32 v193, v193
	v_exp_f32_e32 v194, v194
	v_exp_f32_e32 v195, v195
	s_waitcnt lgkmcnt(4)
	v_mfma_f32_32x32x16_bf16 v[32:47], v[116:119], v[48:51], v[32:47]
	v_exp_f32_e32 v196, v196
	v_exp_f32_e32 v197, v197
	v_mfma_f32_32x32x16_bf16 v[32:47], v[120:123], v[52:55], v[32:47]
	v_exp_f32_e32 v198, v198
	v_exp_f32_e32 v199, v199
	v_mfma_f32_32x32x16_bf16 v[32:47], v[124:127], v[56:59], v[32:47]
	v_exp_f32_e32 v200, v200
	v_exp_f32_e32 v201, v201
	v_mfma_f32_32x32x16_bf16 v[32:47], v[128:131], v[60:63], v[32:47]
	v_exp_f32_e32 v202, v202
	v_exp_f32_e32 v203, v203
	v_cvt_pk_bf16_f32 v64, v188, v189
	v_cvt_pk_bf16_f32 v65, v190, v191
	v_cvt_pk_bf16_f32 v66, v192, v193
	v_cvt_pk_bf16_f32 v67, v194, v195
	v_cvt_pk_bf16_f32 v68, v196, v197
	v_cvt_pk_bf16_f32 v69, v198, v199
	v_cvt_pk_bf16_f32 v70, v200, v201
	v_cvt_pk_bf16_f32 v71, v202, v203
	v_pk_add_f32 v[232:233], v[232:233], v[188:189]
	v_pk_add_f32 v[232:233], v[232:233], v[190:191]
	v_pk_add_f32 v[232:233], v[232:233], v[192:193]
	v_pk_add_f32 v[232:233], v[232:233], v[194:195]
	v_pk_add_f32 v[232:233], v[232:233], v[196:197]
	v_pk_add_f32 v[232:233], v[232:233], v[198:199]
	v_pk_add_f32 v[232:233], v[232:233], v[200:201]
	v_pk_add_f32 v[232:233], v[232:233], v[202:203]
	ds_read2_b32 v[188:189], v115 offset0:136 offset1:137
	ds_read2_b32 v[190:191], v115 offset0:138 offset1:139
	ds_read2_b32 v[192:193], v115 offset0:144 offset1:145
	ds_read2_b32 v[194:195], v115 offset0:146 offset1:147
	ds_read2_b32 v[196:197], v115 offset0:153 offset1:154
	ds_read2_b32 v[198:199], v115 offset0:155 offset1:156
	ds_read2_b32 v[200:201], v115 offset0:161 offset1:162
	ds_read2_b32 v[202:203], v115 offset0:163 offset1:164
	v_mfma_f32_32x32x16_bf16 v[0:15], v[64:67], v[72:75], v[0:15]
	v_mfma_f32_32x32x16_bf16 v[16:31], v[64:67], v[76:79], v[16:31]
	v_mfma_f32_32x32x16_bf16 v[0:15], v[68:71], v[220:223], v[0:15]
	v_mfma_f32_32x32x16_bf16 v[16:31], v[68:71], v[224:227], v[16:31]
	global_load_dwordx4 v[116:119], v235, s[84:85]
	global_load_dwordx4 v[120:123], v236, s[84:85]
	global_load_dwordx4 v[124:127], v237, s[84:85]
	global_load_dwordx4 v[128:131], v238, s[84:85]
	global_load_dwordx4 v[132:135], v100, s[84:85] offset:768
	global_load_dwordx4 v[136:139], v149, s[84:85] offset:768
	global_load_dwordx4 v[140:143], v100, s[84:85] offset:832
	global_load_dwordx4 v[144:147], v149, s[84:85] offset:832
	s_add_u32 s84, s84, 0x30000
	s_addc_u32 s85, s85, 0
	ds_read_b64_tr_b16 v[72:73], v231
	ds_read_b64_tr_b16 v[74:75], v231 offset:512
	ds_read_b64_tr_b16 v[76:77], v231 offset:2048
	ds_read_b64_tr_b16 v[78:79], v231 offset:2560
	ds_read_b64_tr_b16 v[220:221], v231 offset:1024
	ds_read_b64_tr_b16 v[222:223], v231 offset:1536
	ds_read_b64_tr_b16 v[224:225], v231 offset:3072
	ds_read_b64_tr_b16 v[226:227], v231 offset:3584
	v_exp_f32_e32 v32, v32
	v_exp_f32_e32 v33, v33
	v_exp_f32_e32 v34, v34
	v_exp_f32_e32 v35, v35
	s_waitcnt vmcnt(8)
	ds_write_b128 v247, v[156:159]
	ds_write_b128 v247, v[160:163] offset:1024
	ds_write_b128 v247, v[164:167] offset:2048
	ds_write_b128 v247, v[168:171] offset:3072
	ds_read_b128 v[156:159], v248
	ds_read_b128 v[160:163], v249
	ds_read_b128 v[164:167], v250
	ds_read_b128 v[168:171], v251
	ds_write_b128 v112, v[172:175]
	ds_write_b128 v112, v[176:179] offset:1024
	ds_write_b128 v112, v[180:183] offset:2048
	ds_write_b128 v112, v[184:187] offset:3072
	v_exp_f32_e32 v36, v36
	v_exp_f32_e32 v37, v37
	v_exp_f32_e32 v38, v38
	v_exp_f32_e32 v39, v39
	s_waitcnt lgkmcnt(4)
	v_mfma_f32_32x32x16_bf16 v[188:203], v[156:159], v[48:51], v[188:203]
	v_exp_f32_e32 v40, v40
	v_exp_f32_e32 v41, v41
	v_mfma_f32_32x32x16_bf16 v[188:203], v[160:163], v[52:55], v[188:203]
	v_exp_f32_e32 v42, v42
	v_exp_f32_e32 v43, v43
	v_mfma_f32_32x32x16_bf16 v[188:203], v[164:167], v[56:59], v[188:203]
	v_exp_f32_e32 v44, v44
	v_exp_f32_e32 v45, v45
	v_mfma_f32_32x32x16_bf16 v[188:203], v[168:171], v[60:63], v[188:203]
	v_exp_f32_e32 v46, v46
	v_exp_f32_e32 v47, v47
	v_cvt_pk_bf16_f32 v64, v32, v33
	v_cvt_pk_bf16_f32 v65, v34, v35
	v_cvt_pk_bf16_f32 v66, v36, v37
	v_cvt_pk_bf16_f32 v67, v38, v39
	v_cvt_pk_bf16_f32 v68, v40, v41
	v_cvt_pk_bf16_f32 v69, v42, v43
	v_cvt_pk_bf16_f32 v70, v44, v45
	v_cvt_pk_bf16_f32 v71, v46, v47
	v_pk_add_f32 v[232:233], v[232:233], v[32:33]
	v_pk_add_f32 v[232:233], v[232:233], v[34:35]
	v_pk_add_f32 v[232:233], v[232:233], v[36:37]
	v_pk_add_f32 v[232:233], v[232:233], v[38:39]
	v_pk_add_f32 v[232:233], v[232:233], v[40:41]
	v_pk_add_f32 v[232:233], v[232:233], v[42:43]
	v_pk_add_f32 v[232:233], v[232:233], v[44:45]
	v_pk_add_f32 v[232:233], v[232:233], v[46:47]
	ds_read2_b32 v[32:33], v115 offset0:170 offset1:171
	ds_read2_b32 v[34:35], v115 offset0:172 offset1:173
	ds_read2_b32 v[36:37], v115 offset0:178 offset1:179
	ds_read2_b32 v[38:39], v115 offset0:180 offset1:181
	ds_read2_b32 v[40:41], v115 offset0:187 offset1:188
	ds_read2_b32 v[42:43], v115 offset0:189 offset1:190
	ds_read2_b32 v[44:45], v115 offset0:195 offset1:196
	ds_read2_b32 v[46:47], v115 offset0:197 offset1:198
	v_mfma_f32_32x32x16_bf16 v[0:15], v[64:67], v[72:75], v[0:15]
	v_mfma_f32_32x32x16_bf16 v[16:31], v[64:67], v[76:79], v[16:31]
	v_mfma_f32_32x32x16_bf16 v[0:15], v[68:71], v[220:223], v[0:15]
	v_mfma_f32_32x32x16_bf16 v[16:31], v[68:71], v[224:227], v[16:31]
	global_load_dwordx4 v[156:159], v235, s[84:85]
	global_load_dwordx4 v[160:163], v236, s[84:85]
	global_load_dwordx4 v[164:167], v237, s[84:85]
	global_load_dwordx4 v[168:171], v238, s[84:85]
	global_load_dwordx4 v[172:175], v100, s[84:85] offset:768
	global_load_dwordx4 v[176:179], v149, s[84:85] offset:768
	global_load_dwordx4 v[180:183], v100, s[84:85] offset:832
	global_load_dwordx4 v[184:187], v149, s[84:85] offset:832
	s_add_u32 s84, s84, 0x30000
	s_addc_u32 s85, s85, 0
	ds_read_b64_tr_b16 v[72:73], v231
	ds_read_b64_tr_b16 v[74:75], v231 offset:512
	ds_read_b64_tr_b16 v[76:77], v231 offset:2048
	ds_read_b64_tr_b16 v[78:79], v231 offset:2560
	ds_read_b64_tr_b16 v[220:221], v231 offset:1024
	ds_read_b64_tr_b16 v[222:223], v231 offset:1536
	ds_read_b64_tr_b16 v[224:225], v231 offset:3072
	ds_read_b64_tr_b16 v[226:227], v231 offset:3584
	v_exp_f32_e32 v188, v188
	v_exp_f32_e32 v189, v189
	v_exp_f32_e32 v190, v190
	v_exp_f32_e32 v191, v191
	s_waitcnt vmcnt(8)
	ds_write_b128 v247, v[116:119]
	ds_write_b128 v247, v[120:123] offset:1024
	ds_write_b128 v247, v[124:127] offset:2048
	ds_write_b128 v247, v[128:131] offset:3072
	ds_read_b128 v[116:119], v248
	ds_read_b128 v[120:123], v249
	ds_read_b128 v[124:127], v250
	ds_read_b128 v[128:131], v251
	ds_write_b128 v112, v[132:135]
	ds_write_b128 v112, v[136:139] offset:1024
	ds_write_b128 v112, v[140:143] offset:2048
	ds_write_b128 v112, v[144:147] offset:3072
	v_exp_f32_e32 v192, v192
	v_exp_f32_e32 v193, v193
	v_exp_f32_e32 v194, v194
	v_exp_f32_e32 v195, v195
	s_waitcnt lgkmcnt(4)
	v_mfma_f32_32x32x16_bf16 v[32:47], v[116:119], v[48:51], v[32:47]
	v_exp_f32_e32 v196, v196
	v_exp_f32_e32 v197, v197
	v_mfma_f32_32x32x16_bf16 v[32:47], v[120:123], v[52:55], v[32:47]
	v_exp_f32_e32 v198, v198
	v_exp_f32_e32 v199, v199
	v_mfma_f32_32x32x16_bf16 v[32:47], v[124:127], v[56:59], v[32:47]
	v_exp_f32_e32 v200, v200
	v_exp_f32_e32 v201, v201
	v_mfma_f32_32x32x16_bf16 v[32:47], v[128:131], v[60:63], v[32:47]
	v_exp_f32_e32 v202, v202
	v_exp_f32_e32 v203, v203
	v_cvt_pk_bf16_f32 v64, v188, v189
	v_cvt_pk_bf16_f32 v65, v190, v191
	v_cvt_pk_bf16_f32 v66, v192, v193
	v_cvt_pk_bf16_f32 v67, v194, v195
	v_cvt_pk_bf16_f32 v68, v196, v197
	v_cvt_pk_bf16_f32 v69, v198, v199
	v_cvt_pk_bf16_f32 v70, v200, v201
	v_cvt_pk_bf16_f32 v71, v202, v203
	v_pk_add_f32 v[232:233], v[232:233], v[188:189]
	v_pk_add_f32 v[232:233], v[232:233], v[190:191]
	v_pk_add_f32 v[232:233], v[232:233], v[192:193]
	v_pk_add_f32 v[232:233], v[232:233], v[194:195]
	v_pk_add_f32 v[232:233], v[232:233], v[196:197]
	v_pk_add_f32 v[232:233], v[232:233], v[198:199]
	v_pk_add_f32 v[232:233], v[232:233], v[200:201]
	v_pk_add_f32 v[232:233], v[232:233], v[202:203]
	ds_read2_b32 v[188:189], v115 offset0:204 offset1:205
	ds_read2_b32 v[190:191], v115 offset0:206 offset1:207
	ds_read2_b32 v[192:193], v115 offset0:212 offset1:213
	ds_read2_b32 v[194:195], v115 offset0:214 offset1:215
	ds_read2_b32 v[196:197], v115 offset0:221 offset1:222
	ds_read2_b32 v[198:199], v115 offset0:223 offset1:224
	ds_read2_b32 v[200:201], v115 offset0:229 offset1:230
	ds_read2_b32 v[202:203], v115 offset0:231 offset1:232
	v_mfma_f32_32x32x16_bf16 v[0:15], v[64:67], v[72:75], v[0:15]
	v_mfma_f32_32x32x16_bf16 v[16:31], v[64:67], v[76:79], v[16:31]
	v_mfma_f32_32x32x16_bf16 v[0:15], v[68:71], v[220:223], v[0:15]
	v_mfma_f32_32x32x16_bf16 v[16:31], v[68:71], v[224:227], v[16:31]
	global_load_dwordx4 v[116:119], v235, s[84:85]
	global_load_dwordx4 v[120:123], v236, s[84:85]
	global_load_dwordx4 v[124:127], v237, s[84:85]
	global_load_dwordx4 v[128:131], v238, s[84:85]
	global_load_dwordx4 v[132:135], v100, s[84:85] offset:768
	global_load_dwordx4 v[136:139], v149, s[84:85] offset:768
	global_load_dwordx4 v[140:143], v100, s[84:85] offset:832
	global_load_dwordx4 v[144:147], v149, s[84:85] offset:832
	s_add_u32 s84, s84, 0x30000
	s_addc_u32 s85, s85, 0
	ds_read_b64_tr_b16 v[72:73], v231
	ds_read_b64_tr_b16 v[74:75], v231 offset:512
	ds_read_b64_tr_b16 v[76:77], v231 offset:2048
	ds_read_b64_tr_b16 v[78:79], v231 offset:2560
	ds_read_b64_tr_b16 v[220:221], v231 offset:1024
	ds_read_b64_tr_b16 v[222:223], v231 offset:1536
	ds_read_b64_tr_b16 v[224:225], v231 offset:3072
	ds_read_b64_tr_b16 v[226:227], v231 offset:3584
	v_exp_f32_e32 v32, v32
	v_exp_f32_e32 v33, v33
	v_exp_f32_e32 v34, v34
	v_exp_f32_e32 v35, v35
	s_waitcnt vmcnt(8)
	ds_write_b128 v247, v[156:159]
	ds_write_b128 v247, v[160:163] offset:1024
	ds_write_b128 v247, v[164:167] offset:2048
	ds_write_b128 v247, v[168:171] offset:3072
	ds_read_b128 v[156:159], v248
	ds_read_b128 v[160:163], v249
	ds_read_b128 v[164:167], v250
	ds_read_b128 v[168:171], v251
	ds_write_b128 v112, v[172:175]
	ds_write_b128 v112, v[176:179] offset:1024
	ds_write_b128 v112, v[180:183] offset:2048
	ds_write_b128 v112, v[184:187] offset:3072
	v_exp_f32_e32 v36, v36
	v_exp_f32_e32 v37, v37
	v_exp_f32_e32 v38, v38
	v_exp_f32_e32 v39, v39
	s_waitcnt lgkmcnt(4)
	v_mfma_f32_32x32x16_bf16 v[188:203], v[156:159], v[48:51], v[188:203]
	v_exp_f32_e32 v40, v40
	v_exp_f32_e32 v41, v41
	v_mfma_f32_32x32x16_bf16 v[188:203], v[160:163], v[52:55], v[188:203]
	v_exp_f32_e32 v42, v42
	v_exp_f32_e32 v43, v43
	v_mfma_f32_32x32x16_bf16 v[188:203], v[164:167], v[56:59], v[188:203]
	v_exp_f32_e32 v44, v44
	v_exp_f32_e32 v45, v45
	v_mfma_f32_32x32x16_bf16 v[188:203], v[168:171], v[60:63], v[188:203]
	v_exp_f32_e32 v46, v46
	v_exp_f32_e32 v47, v47
	v_cvt_pk_bf16_f32 v64, v32, v33
	v_cvt_pk_bf16_f32 v65, v34, v35
	v_cvt_pk_bf16_f32 v66, v36, v37
	v_cvt_pk_bf16_f32 v67, v38, v39
	v_cvt_pk_bf16_f32 v68, v40, v41
	v_cvt_pk_bf16_f32 v69, v42, v43
	v_cvt_pk_bf16_f32 v70, v44, v45
	v_cvt_pk_bf16_f32 v71, v46, v47
	v_pk_add_f32 v[232:233], v[232:233], v[32:33]
	v_pk_add_f32 v[232:233], v[232:233], v[34:35]
	v_pk_add_f32 v[232:233], v[232:233], v[36:37]
	v_pk_add_f32 v[232:233], v[232:233], v[38:39]
	v_pk_add_f32 v[232:233], v[232:233], v[40:41]
	v_pk_add_f32 v[232:233], v[232:233], v[42:43]
	v_pk_add_f32 v[232:233], v[232:233], v[44:45]
	v_pk_add_f32 v[232:233], v[232:233], v[46:47]
	v_add_u32_e32 v115, 952, v115
	ds_read2_b32 v[32:33], v115 offset0:0 offset1:1
	ds_read2_b32 v[34:35], v115 offset0:2 offset1:3
	ds_read2_b32 v[36:37], v115 offset0:8 offset1:9
	ds_read2_b32 v[38:39], v115 offset0:10 offset1:11
	ds_read2_b32 v[40:41], v115 offset0:17 offset1:18
	ds_read2_b32 v[42:43], v115 offset0:19 offset1:20
	ds_read2_b32 v[44:45], v115 offset0:25 offset1:26
	ds_read2_b32 v[46:47], v115 offset0:27 offset1:28
	v_mfma_f32_32x32x16_bf16 v[0:15], v[64:67], v[72:75], v[0:15]
	v_mfma_f32_32x32x16_bf16 v[16:31], v[64:67], v[76:79], v[16:31]
	v_mfma_f32_32x32x16_bf16 v[0:15], v[68:71], v[220:223], v[0:15]
	v_mfma_f32_32x32x16_bf16 v[16:31], v[68:71], v[224:227], v[16:31]
	global_load_dwordx4 v[156:159], v235, s[84:85]
	global_load_dwordx4 v[160:163], v236, s[84:85]
	global_load_dwordx4 v[164:167], v237, s[84:85]
	global_load_dwordx4 v[168:171], v238, s[84:85]
	global_load_dwordx4 v[172:175], v100, s[84:85] offset:768
	global_load_dwordx4 v[176:179], v149, s[84:85] offset:768
	global_load_dwordx4 v[180:183], v100, s[84:85] offset:832
	global_load_dwordx4 v[184:187], v149, s[84:85] offset:832
	s_add_u32 s84, s84, 0x30000
	s_addc_u32 s85, s85, 0
	ds_read_b64_tr_b16 v[72:73], v231
	ds_read_b64_tr_b16 v[74:75], v231 offset:512
	ds_read_b64_tr_b16 v[76:77], v231 offset:2048
	ds_read_b64_tr_b16 v[78:79], v231 offset:2560
	ds_read_b64_tr_b16 v[220:221], v231 offset:1024
	ds_read_b64_tr_b16 v[222:223], v231 offset:1536
	ds_read_b64_tr_b16 v[224:225], v231 offset:3072
	ds_read_b64_tr_b16 v[226:227], v231 offset:3584
	v_exp_f32_e32 v188, v188
	v_exp_f32_e32 v189, v189
	v_exp_f32_e32 v190, v190
	v_exp_f32_e32 v191, v191
	s_waitcnt vmcnt(8)
	ds_write_b128 v247, v[116:119]
	ds_write_b128 v247, v[120:123] offset:1024
	ds_write_b128 v247, v[124:127] offset:2048
	ds_write_b128 v247, v[128:131] offset:3072
	ds_read_b128 v[116:119], v248
	ds_read_b128 v[120:123], v249
	ds_read_b128 v[124:127], v250
	ds_read_b128 v[128:131], v251
	ds_write_b128 v112, v[132:135]
	ds_write_b128 v112, v[136:139] offset:1024
	ds_write_b128 v112, v[140:143] offset:2048
	ds_write_b128 v112, v[144:147] offset:3072
	v_exp_f32_e32 v192, v192
	v_exp_f32_e32 v193, v193
	v_exp_f32_e32 v194, v194
	v_exp_f32_e32 v195, v195
	s_waitcnt lgkmcnt(4)
	v_mfma_f32_32x32x16_bf16 v[32:47], v[116:119], v[48:51], v[32:47]
	v_exp_f32_e32 v196, v196
	v_exp_f32_e32 v197, v197
	v_mfma_f32_32x32x16_bf16 v[32:47], v[120:123], v[52:55], v[32:47]
	v_exp_f32_e32 v198, v198
	v_exp_f32_e32 v199, v199
	v_mfma_f32_32x32x16_bf16 v[32:47], v[124:127], v[56:59], v[32:47]
	v_exp_f32_e32 v200, v200
	v_exp_f32_e32 v201, v201
	v_mfma_f32_32x32x16_bf16 v[32:47], v[128:131], v[60:63], v[32:47]
	v_exp_f32_e32 v202, v202
	v_exp_f32_e32 v203, v203
	v_cvt_pk_bf16_f32 v64, v188, v189
	v_cvt_pk_bf16_f32 v65, v190, v191
	v_cvt_pk_bf16_f32 v66, v192, v193
	v_cvt_pk_bf16_f32 v67, v194, v195
	v_cvt_pk_bf16_f32 v68, v196, v197
	v_cvt_pk_bf16_f32 v69, v198, v199
	v_cvt_pk_bf16_f32 v70, v200, v201
	v_cvt_pk_bf16_f32 v71, v202, v203
	v_pk_add_f32 v[232:233], v[232:233], v[188:189]
	v_pk_add_f32 v[232:233], v[232:233], v[190:191]
	v_pk_add_f32 v[232:233], v[232:233], v[192:193]
	v_pk_add_f32 v[232:233], v[232:233], v[194:195]
	v_pk_add_f32 v[232:233], v[232:233], v[196:197]
	v_pk_add_f32 v[232:233], v[232:233], v[198:199]
	v_pk_add_f32 v[232:233], v[232:233], v[200:201]
	v_pk_add_f32 v[232:233], v[232:233], v[202:203]
	ds_read2_b32 v[188:189], v115 offset0:34 offset1:35
	ds_read2_b32 v[190:191], v115 offset0:36 offset1:37
	ds_read2_b32 v[192:193], v115 offset0:42 offset1:43
	ds_read2_b32 v[194:195], v115 offset0:44 offset1:45
	ds_read2_b32 v[196:197], v115 offset0:51 offset1:52
	ds_read2_b32 v[198:199], v115 offset0:53 offset1:54
	ds_read2_b32 v[200:201], v115 offset0:59 offset1:60
	ds_read2_b32 v[202:203], v115 offset0:61 offset1:62
	v_mfma_f32_32x32x16_bf16 v[0:15], v[64:67], v[72:75], v[0:15]
	v_mfma_f32_32x32x16_bf16 v[16:31], v[64:67], v[76:79], v[16:31]
	v_mfma_f32_32x32x16_bf16 v[0:15], v[68:71], v[220:223], v[0:15]
	v_mfma_f32_32x32x16_bf16 v[16:31], v[68:71], v[224:227], v[16:31]
	global_load_dwordx4 v[116:119], v235, s[84:85]
	global_load_dwordx4 v[120:123], v236, s[84:85]
	global_load_dwordx4 v[124:127], v237, s[84:85]
	global_load_dwordx4 v[128:131], v238, s[84:85]
	global_load_dwordx4 v[132:135], v100, s[84:85] offset:768
	global_load_dwordx4 v[136:139], v149, s[84:85] offset:768
	global_load_dwordx4 v[140:143], v100, s[84:85] offset:832
	global_load_dwordx4 v[144:147], v149, s[84:85] offset:832
	s_add_u32 s84, s84, 0x30000
	s_addc_u32 s85, s85, 0
	ds_read_b64_tr_b16 v[72:73], v231
	ds_read_b64_tr_b16 v[74:75], v231 offset:512
	ds_read_b64_tr_b16 v[76:77], v231 offset:2048
	ds_read_b64_tr_b16 v[78:79], v231 offset:2560
	ds_read_b64_tr_b16 v[220:221], v231 offset:1024
	ds_read_b64_tr_b16 v[222:223], v231 offset:1536
	ds_read_b64_tr_b16 v[224:225], v231 offset:3072
	ds_read_b64_tr_b16 v[226:227], v231 offset:3584
	v_exp_f32_e32 v32, v32
	v_exp_f32_e32 v33, v33
	v_exp_f32_e32 v34, v34
	v_exp_f32_e32 v35, v35
	s_waitcnt vmcnt(8)
	ds_write_b128 v247, v[156:159]
	ds_write_b128 v247, v[160:163] offset:1024
	ds_write_b128 v247, v[164:167] offset:2048
	ds_write_b128 v247, v[168:171] offset:3072
	ds_read_b128 v[156:159], v248
	ds_read_b128 v[160:163], v249
	ds_read_b128 v[164:167], v250
	ds_read_b128 v[168:171], v251
	ds_write_b128 v112, v[172:175]
	ds_write_b128 v112, v[176:179] offset:1024
	ds_write_b128 v112, v[180:183] offset:2048
	ds_write_b128 v112, v[184:187] offset:3072
	v_exp_f32_e32 v36, v36
	v_exp_f32_e32 v37, v37
	v_exp_f32_e32 v38, v38
	v_exp_f32_e32 v39, v39
	s_waitcnt lgkmcnt(4)
	v_mfma_f32_32x32x16_bf16 v[188:203], v[156:159], v[48:51], v[188:203]
	v_exp_f32_e32 v40, v40
	v_exp_f32_e32 v41, v41
	v_mfma_f32_32x32x16_bf16 v[188:203], v[160:163], v[52:55], v[188:203]
	v_exp_f32_e32 v42, v42
	v_exp_f32_e32 v43, v43
	v_mfma_f32_32x32x16_bf16 v[188:203], v[164:167], v[56:59], v[188:203]
	v_exp_f32_e32 v44, v44
	v_exp_f32_e32 v45, v45
	v_mfma_f32_32x32x16_bf16 v[188:203], v[168:171], v[60:63], v[188:203]
	v_exp_f32_e32 v46, v46
	v_exp_f32_e32 v47, v47
	v_cvt_pk_bf16_f32 v64, v32, v33
	v_cvt_pk_bf16_f32 v65, v34, v35
	v_cvt_pk_bf16_f32 v66, v36, v37
	v_cvt_pk_bf16_f32 v67, v38, v39
	v_cvt_pk_bf16_f32 v68, v40, v41
	v_cvt_pk_bf16_f32 v69, v42, v43
	v_cvt_pk_bf16_f32 v70, v44, v45
	v_cvt_pk_bf16_f32 v71, v46, v47
	v_pk_add_f32 v[232:233], v[232:233], v[32:33]
	v_pk_add_f32 v[232:233], v[232:233], v[34:35]
	v_pk_add_f32 v[232:233], v[232:233], v[36:37]
	v_pk_add_f32 v[232:233], v[232:233], v[38:39]
	v_pk_add_f32 v[232:233], v[232:233], v[40:41]
	v_pk_add_f32 v[232:233], v[232:233], v[42:43]
	v_pk_add_f32 v[232:233], v[232:233], v[44:45]
	v_pk_add_f32 v[232:233], v[232:233], v[46:47]
	ds_read2_b32 v[32:33], v115 offset0:68 offset1:69
	ds_read2_b32 v[34:35], v115 offset0:70 offset1:71
	ds_read2_b32 v[36:37], v115 offset0:76 offset1:77
	ds_read2_b32 v[38:39], v115 offset0:78 offset1:79
	ds_read2_b32 v[40:41], v115 offset0:85 offset1:86
	ds_read2_b32 v[42:43], v115 offset0:87 offset1:88
	ds_read2_b32 v[44:45], v115 offset0:93 offset1:94
	ds_read2_b32 v[46:47], v115 offset0:95 offset1:96
	v_mfma_f32_32x32x16_bf16 v[0:15], v[64:67], v[72:75], v[0:15]
	v_mfma_f32_32x32x16_bf16 v[16:31], v[64:67], v[76:79], v[16:31]
	v_mfma_f32_32x32x16_bf16 v[0:15], v[68:71], v[220:223], v[0:15]
	v_mfma_f32_32x32x16_bf16 v[16:31], v[68:71], v[224:227], v[16:31]
	global_load_dwordx4 v[156:159], v235, s[84:85]
	global_load_dwordx4 v[160:163], v236, s[84:85]
	global_load_dwordx4 v[164:167], v237, s[84:85]
	global_load_dwordx4 v[168:171], v238, s[84:85]
	global_load_dwordx4 v[172:175], v100, s[84:85] offset:768
	global_load_dwordx4 v[176:179], v149, s[84:85] offset:768
	global_load_dwordx4 v[180:183], v100, s[84:85] offset:832
	global_load_dwordx4 v[184:187], v149, s[84:85] offset:832
	s_add_u32 s84, s84, 0x30000
	s_addc_u32 s85, s85, 0
	ds_read_b64_tr_b16 v[72:73], v231
	ds_read_b64_tr_b16 v[74:75], v231 offset:512
	ds_read_b64_tr_b16 v[76:77], v231 offset:2048
	ds_read_b64_tr_b16 v[78:79], v231 offset:2560
	ds_read_b64_tr_b16 v[220:221], v231 offset:1024
	ds_read_b64_tr_b16 v[222:223], v231 offset:1536
	ds_read_b64_tr_b16 v[224:225], v231 offset:3072
	ds_read_b64_tr_b16 v[226:227], v231 offset:3584
	v_exp_f32_e32 v188, v188
	v_exp_f32_e32 v189, v189
	v_exp_f32_e32 v190, v190
	v_exp_f32_e32 v191, v191
	s_waitcnt vmcnt(8)
	ds_write_b128 v247, v[116:119]
	ds_write_b128 v247, v[120:123] offset:1024
	ds_write_b128 v247, v[124:127] offset:2048
	ds_write_b128 v247, v[128:131] offset:3072
	ds_read_b128 v[116:119], v248
	ds_read_b128 v[120:123], v249
	ds_read_b128 v[124:127], v250
	ds_read_b128 v[128:131], v251
	ds_write_b128 v112, v[132:135]
	ds_write_b128 v112, v[136:139] offset:1024
	ds_write_b128 v112, v[140:143] offset:2048
	ds_write_b128 v112, v[144:147] offset:3072
	v_exp_f32_e32 v192, v192
	v_exp_f32_e32 v193, v193
	v_exp_f32_e32 v194, v194
	v_exp_f32_e32 v195, v195
	s_waitcnt lgkmcnt(4)
	v_mfma_f32_32x32x16_bf16 v[32:47], v[116:119], v[48:51], v[32:47]
	v_exp_f32_e32 v196, v196
	v_exp_f32_e32 v197, v197
	v_mfma_f32_32x32x16_bf16 v[32:47], v[120:123], v[52:55], v[32:47]
	v_exp_f32_e32 v198, v198
	v_exp_f32_e32 v199, v199
	v_mfma_f32_32x32x16_bf16 v[32:47], v[124:127], v[56:59], v[32:47]
	v_exp_f32_e32 v200, v200
	v_exp_f32_e32 v201, v201
	v_mfma_f32_32x32x16_bf16 v[32:47], v[128:131], v[60:63], v[32:47]
	v_exp_f32_e32 v202, v202
	v_exp_f32_e32 v203, v203
	v_cvt_pk_bf16_f32 v64, v188, v189
	v_cvt_pk_bf16_f32 v65, v190, v191
	v_cvt_pk_bf16_f32 v66, v192, v193
	v_cvt_pk_bf16_f32 v67, v194, v195
	v_cvt_pk_bf16_f32 v68, v196, v197
	v_cvt_pk_bf16_f32 v69, v198, v199
	v_cvt_pk_bf16_f32 v70, v200, v201
	v_cvt_pk_bf16_f32 v71, v202, v203
	v_pk_add_f32 v[232:233], v[232:233], v[188:189]
	v_pk_add_f32 v[232:233], v[232:233], v[190:191]
	v_pk_add_f32 v[232:233], v[232:233], v[192:193]
	v_pk_add_f32 v[232:233], v[232:233], v[194:195]
	v_pk_add_f32 v[232:233], v[232:233], v[196:197]
	v_pk_add_f32 v[232:233], v[232:233], v[198:199]
	v_pk_add_f32 v[232:233], v[232:233], v[200:201]
	v_pk_add_f32 v[232:233], v[232:233], v[202:203]
	ds_read2_b32 v[188:189], v115 offset0:102 offset1:103
	ds_read2_b32 v[190:191], v115 offset0:104 offset1:105
	ds_read2_b32 v[192:193], v115 offset0:110 offset1:111
	ds_read2_b32 v[194:195], v115 offset0:112 offset1:113
	ds_read2_b32 v[196:197], v115 offset0:119 offset1:120
	ds_read2_b32 v[198:199], v115 offset0:121 offset1:122
	ds_read2_b32 v[200:201], v115 offset0:127 offset1:128
	ds_read2_b32 v[202:203], v115 offset0:129 offset1:130
	v_mfma_f32_32x32x16_bf16 v[0:15], v[64:67], v[72:75], v[0:15]
	v_mfma_f32_32x32x16_bf16 v[16:31], v[64:67], v[76:79], v[16:31]
	v_mfma_f32_32x32x16_bf16 v[0:15], v[68:71], v[220:223], v[0:15]
	v_mfma_f32_32x32x16_bf16 v[16:31], v[68:71], v[224:227], v[16:31]
	global_load_dwordx4 v[116:119], v235, s[84:85]
	global_load_dwordx4 v[120:123], v236, s[84:85]
	global_load_dwordx4 v[124:127], v237, s[84:85]
	global_load_dwordx4 v[128:131], v238, s[84:85]
	global_load_dwordx4 v[132:135], v100, s[84:85] offset:768
	global_load_dwordx4 v[136:139], v149, s[84:85] offset:768
	global_load_dwordx4 v[140:143], v100, s[84:85] offset:832
	global_load_dwordx4 v[144:147], v149, s[84:85] offset:832
	s_add_u32 s84, s84, 0x30000
	s_addc_u32 s85, s85, 0
	ds_read_b64_tr_b16 v[72:73], v231
	ds_read_b64_tr_b16 v[74:75], v231 offset:512
	ds_read_b64_tr_b16 v[76:77], v231 offset:2048
	ds_read_b64_tr_b16 v[78:79], v231 offset:2560
	ds_read_b64_tr_b16 v[220:221], v231 offset:1024
	ds_read_b64_tr_b16 v[222:223], v231 offset:1536
	ds_read_b64_tr_b16 v[224:225], v231 offset:3072
	ds_read_b64_tr_b16 v[226:227], v231 offset:3584
	v_exp_f32_e32 v32, v32
	v_exp_f32_e32 v33, v33
	v_exp_f32_e32 v34, v34
	v_exp_f32_e32 v35, v35
	s_waitcnt vmcnt(8)
	ds_write_b128 v247, v[156:159]
	ds_write_b128 v247, v[160:163] offset:1024
	ds_write_b128 v247, v[164:167] offset:2048
	ds_write_b128 v247, v[168:171] offset:3072
	ds_read_b128 v[156:159], v248
	ds_read_b128 v[160:163], v249
	ds_read_b128 v[164:167], v250
	ds_read_b128 v[168:171], v251
	ds_write_b128 v112, v[172:175]
	ds_write_b128 v112, v[176:179] offset:1024
	ds_write_b128 v112, v[180:183] offset:2048
	ds_write_b128 v112, v[184:187] offset:3072
	v_exp_f32_e32 v36, v36
	v_exp_f32_e32 v37, v37
	v_exp_f32_e32 v38, v38
	v_exp_f32_e32 v39, v39
	s_waitcnt lgkmcnt(4)
	v_mfma_f32_32x32x16_bf16 v[188:203], v[156:159], v[48:51], v[188:203]
	v_exp_f32_e32 v40, v40
	v_exp_f32_e32 v41, v41
	v_mfma_f32_32x32x16_bf16 v[188:203], v[160:163], v[52:55], v[188:203]
	v_exp_f32_e32 v42, v42
	v_exp_f32_e32 v43, v43
	v_mfma_f32_32x32x16_bf16 v[188:203], v[164:167], v[56:59], v[188:203]
	v_exp_f32_e32 v44, v44
	v_exp_f32_e32 v45, v45
	v_mfma_f32_32x32x16_bf16 v[188:203], v[168:171], v[60:63], v[188:203]
	v_exp_f32_e32 v46, v46
	v_exp_f32_e32 v47, v47
	v_cvt_pk_bf16_f32 v64, v32, v33
	v_cvt_pk_bf16_f32 v65, v34, v35
	v_cvt_pk_bf16_f32 v66, v36, v37
	v_cvt_pk_bf16_f32 v67, v38, v39
	v_cvt_pk_bf16_f32 v68, v40, v41
	v_cvt_pk_bf16_f32 v69, v42, v43
	v_cvt_pk_bf16_f32 v70, v44, v45
	v_cvt_pk_bf16_f32 v71, v46, v47
	v_pk_add_f32 v[232:233], v[232:233], v[32:33]
	v_pk_add_f32 v[232:233], v[232:233], v[34:35]
	v_pk_add_f32 v[232:233], v[232:233], v[36:37]
	v_pk_add_f32 v[232:233], v[232:233], v[38:39]
	v_pk_add_f32 v[232:233], v[232:233], v[40:41]
	v_pk_add_f32 v[232:233], v[232:233], v[42:43]
	v_pk_add_f32 v[232:233], v[232:233], v[44:45]
	v_pk_add_f32 v[232:233], v[232:233], v[46:47]
	ds_read2_b32 v[32:33], v115 offset0:136 offset1:137
	ds_read2_b32 v[34:35], v115 offset0:138 offset1:139
	ds_read2_b32 v[36:37], v115 offset0:144 offset1:145
	ds_read2_b32 v[38:39], v115 offset0:146 offset1:147
	ds_read2_b32 v[40:41], v115 offset0:153 offset1:154
	ds_read2_b32 v[42:43], v115 offset0:155 offset1:156
	ds_read2_b32 v[44:45], v115 offset0:161 offset1:162
	ds_read2_b32 v[46:47], v115 offset0:163 offset1:164
	v_mfma_f32_32x32x16_bf16 v[0:15], v[64:67], v[72:75], v[0:15]
	v_mfma_f32_32x32x16_bf16 v[16:31], v[64:67], v[76:79], v[16:31]
	v_mfma_f32_32x32x16_bf16 v[0:15], v[68:71], v[220:223], v[0:15]
	v_mfma_f32_32x32x16_bf16 v[16:31], v[68:71], v[224:227], v[16:31]
	global_load_dwordx4 v[156:159], v235, s[84:85]
	global_load_dwordx4 v[160:163], v236, s[84:85]
	global_load_dwordx4 v[164:167], v237, s[84:85]
	global_load_dwordx4 v[168:171], v238, s[84:85]
	global_load_dwordx4 v[172:175], v100, s[84:85] offset:768
	global_load_dwordx4 v[176:179], v149, s[84:85] offset:768
	global_load_dwordx4 v[180:183], v100, s[84:85] offset:832
	global_load_dwordx4 v[184:187], v149, s[84:85] offset:832
	ds_read_b64_tr_b16 v[72:73], v231
	ds_read_b64_tr_b16 v[74:75], v231 offset:512
	ds_read_b64_tr_b16 v[76:77], v231 offset:2048
	ds_read_b64_tr_b16 v[78:79], v231 offset:2560
	ds_read_b64_tr_b16 v[220:221], v231 offset:1024
	ds_read_b64_tr_b16 v[222:223], v231 offset:1536
	ds_read_b64_tr_b16 v[224:225], v231 offset:3072
	ds_read_b64_tr_b16 v[226:227], v231 offset:3584
	v_exp_f32_e32 v188, v188
	v_exp_f32_e32 v189, v189
	v_exp_f32_e32 v190, v190
	v_exp_f32_e32 v191, v191
	s_waitcnt vmcnt(8)
	ds_write_b128 v247, v[116:119]
	ds_write_b128 v247, v[120:123] offset:1024
	ds_write_b128 v247, v[124:127] offset:2048
	ds_write_b128 v247, v[128:131] offset:3072
	ds_read_b128 v[116:119], v248
	ds_read_b128 v[120:123], v249
	ds_read_b128 v[124:127], v250
	ds_read_b128 v[128:131], v251
	ds_write_b128 v112, v[132:135]
	ds_write_b128 v112, v[136:139] offset:1024
	ds_write_b128 v112, v[140:143] offset:2048
	ds_write_b128 v112, v[144:147] offset:3072
	v_exp_f32_e32 v192, v192
	v_exp_f32_e32 v193, v193
	v_exp_f32_e32 v194, v194
	v_exp_f32_e32 v195, v195
	s_waitcnt lgkmcnt(4)
	v_mfma_f32_32x32x16_bf16 v[32:47], v[116:119], v[48:51], v[32:47]
	v_exp_f32_e32 v196, v196
	v_exp_f32_e32 v197, v197
	v_mfma_f32_32x32x16_bf16 v[32:47], v[120:123], v[52:55], v[32:47]
	v_exp_f32_e32 v198, v198
	v_exp_f32_e32 v199, v199
	v_mfma_f32_32x32x16_bf16 v[32:47], v[124:127], v[56:59], v[32:47]
	v_exp_f32_e32 v200, v200
	v_exp_f32_e32 v201, v201
	v_mfma_f32_32x32x16_bf16 v[32:47], v[128:131], v[60:63], v[32:47]
	v_exp_f32_e32 v202, v202
	v_exp_f32_e32 v203, v203
	v_cvt_pk_bf16_f32 v64, v188, v189
	v_cvt_pk_bf16_f32 v65, v190, v191
	v_cvt_pk_bf16_f32 v66, v192, v193
	v_cvt_pk_bf16_f32 v67, v194, v195
	v_cvt_pk_bf16_f32 v68, v196, v197
	v_cvt_pk_bf16_f32 v69, v198, v199
	v_cvt_pk_bf16_f32 v70, v200, v201
	v_cvt_pk_bf16_f32 v71, v202, v203
	v_pk_add_f32 v[232:233], v[232:233], v[188:189]
	v_pk_add_f32 v[232:233], v[232:233], v[190:191]
	v_pk_add_f32 v[232:233], v[232:233], v[192:193]
	v_pk_add_f32 v[232:233], v[232:233], v[194:195]
	v_pk_add_f32 v[232:233], v[232:233], v[196:197]
	v_pk_add_f32 v[232:233], v[232:233], v[198:199]
	v_pk_add_f32 v[232:233], v[232:233], v[200:201]
	v_pk_add_f32 v[232:233], v[232:233], v[202:203]
	ds_read2_b32 v[188:189], v115 offset0:170 offset1:171
	ds_read2_b32 v[190:191], v115 offset0:172 offset1:173
	ds_read2_b32 v[192:193], v115 offset0:178 offset1:179
	ds_read2_b32 v[194:195], v115 offset0:180 offset1:181
	ds_read2_b32 v[196:197], v115 offset0:187 offset1:188
	ds_read2_b32 v[198:199], v115 offset0:189 offset1:190
	ds_read2_b32 v[200:201], v115 offset0:195 offset1:196
	ds_read2_b32 v[202:203], v115 offset0:197 offset1:198
	v_mfma_f32_32x32x16_bf16 v[0:15], v[64:67], v[72:75], v[0:15]
	v_mfma_f32_32x32x16_bf16 v[16:31], v[64:67], v[76:79], v[16:31]
	v_mfma_f32_32x32x16_bf16 v[0:15], v[68:71], v[220:223], v[0:15]
	v_mfma_f32_32x32x16_bf16 v[16:31], v[68:71], v[224:227], v[16:31]
	global_load_dwordx4 v[116:119], v239, s[86:87]
	global_load_dwordx4 v[120:123], v240, s[86:87]
	global_load_dwordx4 v[124:127], v241, s[86:87]
	global_load_dwordx4 v[128:131], v242, s[86:87]
	global_load_dwordx4 v[132:135], v101, s[86:87] offset:768
	global_load_dwordx4 v[136:139], v150, s[86:87] offset:768
	global_load_dwordx4 v[140:143], v101, s[86:87] offset:832
	global_load_dwordx4 v[144:147], v150, s[86:87] offset:832
	s_add_u32 s86, s86, 0xc0000
	s_addc_u32 s87, s87, 0
	ds_read_b64_tr_b16 v[72:73], v231
	ds_read_b64_tr_b16 v[74:75], v231 offset:512
	ds_read_b64_tr_b16 v[76:77], v231 offset:2048
	ds_read_b64_tr_b16 v[78:79], v231 offset:2560
	ds_read_b64_tr_b16 v[220:221], v231 offset:1024
	ds_read_b64_tr_b16 v[222:223], v231 offset:1536
	ds_read_b64_tr_b16 v[224:225], v231 offset:3072
	ds_read_b64_tr_b16 v[226:227], v231 offset:3584
	v_exp_f32_e32 v32, v32
	v_exp_f32_e32 v33, v33
	v_exp_f32_e32 v34, v34
	v_exp_f32_e32 v35, v35
	s_waitcnt vmcnt(8)
	ds_write_b128 v247, v[156:159]
	ds_write_b128 v247, v[160:163] offset:1024
	ds_write_b128 v247, v[164:167] offset:2048
	ds_write_b128 v247, v[168:171] offset:3072
	ds_read_b128 v[156:159], v248
	ds_read_b128 v[160:163], v249
	ds_read_b128 v[164:167], v250
	ds_read_b128 v[168:171], v251
	ds_write_b128 v112, v[172:175]
	ds_write_b128 v112, v[176:179] offset:1024
	ds_write_b128 v112, v[180:183] offset:2048
	ds_write_b128 v112, v[184:187] offset:3072
	v_exp_f32_e32 v36, v36
	v_exp_f32_e32 v37, v37
	v_exp_f32_e32 v38, v38
	v_exp_f32_e32 v39, v39
	s_waitcnt lgkmcnt(4)
	v_mfma_f32_32x32x16_bf16 v[188:203], v[156:159], v[48:51], v[188:203]
	v_exp_f32_e32 v40, v40
	v_exp_f32_e32 v41, v41
	v_mfma_f32_32x32x16_bf16 v[188:203], v[160:163], v[52:55], v[188:203]
	v_exp_f32_e32 v42, v42
	v_exp_f32_e32 v43, v43
	v_mfma_f32_32x32x16_bf16 v[188:203], v[164:167], v[56:59], v[188:203]
	v_exp_f32_e32 v44, v44
	v_exp_f32_e32 v45, v45
	v_mfma_f32_32x32x16_bf16 v[188:203], v[168:171], v[60:63], v[188:203]
	v_exp_f32_e32 v46, v46
	v_exp_f32_e32 v47, v47
	v_cvt_pk_bf16_f32 v64, v32, v33
	v_cvt_pk_bf16_f32 v65, v34, v35
	v_cvt_pk_bf16_f32 v66, v36, v37
	v_cvt_pk_bf16_f32 v67, v38, v39
	v_cvt_pk_bf16_f32 v68, v40, v41
	v_cvt_pk_bf16_f32 v69, v42, v43
	v_cvt_pk_bf16_f32 v70, v44, v45
	v_cvt_pk_bf16_f32 v71, v46, v47
	v_pk_add_f32 v[232:233], v[232:233], v[32:33]
	v_pk_add_f32 v[232:233], v[232:233], v[34:35]
	v_pk_add_f32 v[232:233], v[232:233], v[36:37]
	v_pk_add_f32 v[232:233], v[232:233], v[38:39]
	v_pk_add_f32 v[232:233], v[232:233], v[40:41]
	v_pk_add_f32 v[232:233], v[232:233], v[42:43]
	v_pk_add_f32 v[232:233], v[232:233], v[44:45]
	v_pk_add_f32 v[232:233], v[232:233], v[46:47]
	v_mov_b32_e32 v115, v229
	ds_read2_b32 v[32:33], v115 offset0:0 offset1:1
	ds_read2_b32 v[34:35], v115 offset0:2 offset1:3
	ds_read2_b32 v[36:37], v115 offset0:8 offset1:9
	ds_read2_b32 v[38:39], v115 offset0:10 offset1:11
	ds_read2_b32 v[40:41], v115 offset0:16 offset1:17
	ds_read2_b32 v[42:43], v115 offset0:18 offset1:19
	ds_read2_b32 v[44:45], v115 offset0:24 offset1:25
	ds_read2_b32 v[46:47], v115 offset0:26 offset1:27
	v_mfma_f32_32x32x16_bf16 v[0:15], v[64:67], v[72:75], v[0:15]
	v_mfma_f32_32x32x16_bf16 v[16:31], v[64:67], v[76:79], v[16:31]
	v_mfma_f32_32x32x16_bf16 v[0:15], v[68:71], v[220:223], v[0:15]
	v_mfma_f32_32x32x16_bf16 v[16:31], v[68:71], v[224:227], v[16:31]
	global_load_dwordx4 v[156:159], v239, s[86:87]
	global_load_dwordx4 v[160:163], v240, s[86:87]
	global_load_dwordx4 v[164:167], v241, s[86:87]
	global_load_dwordx4 v[168:171], v242, s[86:87]
	global_load_dwordx4 v[172:175], v101, s[86:87] offset:768
	global_load_dwordx4 v[176:179], v150, s[86:87] offset:768
	global_load_dwordx4 v[180:183], v101, s[86:87] offset:832
	global_load_dwordx4 v[184:187], v150, s[86:87] offset:832
	s_add_u32 s86, s86, 0xc0000
	s_addc_u32 s87, s87, 0
	ds_read_b64_tr_b16 v[72:73], v231
	ds_read_b64_tr_b16 v[74:75], v231 offset:512
	ds_read_b64_tr_b16 v[76:77], v231 offset:2048
	ds_read_b64_tr_b16 v[78:79], v231 offset:2560
	ds_read_b64_tr_b16 v[220:221], v231 offset:1024
	ds_read_b64_tr_b16 v[222:223], v231 offset:1536
	ds_read_b64_tr_b16 v[224:225], v231 offset:3072
	ds_read_b64_tr_b16 v[226:227], v231 offset:3584
	v_exp_f32_e32 v188, v188
	v_exp_f32_e32 v189, v189
	v_exp_f32_e32 v190, v190
	v_exp_f32_e32 v191, v191
	s_waitcnt vmcnt(8)
	ds_write_b128 v247, v[116:119]
	ds_write_b128 v247, v[120:123] offset:1024
	ds_write_b128 v247, v[124:127] offset:2048
	ds_write_b128 v247, v[128:131] offset:3072
	ds_read_b128 v[116:119], v248
	ds_read_b128 v[120:123], v249
	ds_read_b128 v[124:127], v250
	ds_read_b128 v[128:131], v251
	ds_write_b128 v112, v[132:135]
	ds_write_b128 v112, v[136:139] offset:1024
	ds_write_b128 v112, v[140:143] offset:2048
	ds_write_b128 v112, v[144:147] offset:3072
	v_exp_f32_e32 v192, v192
	v_exp_f32_e32 v193, v193
	v_exp_f32_e32 v194, v194
	v_exp_f32_e32 v195, v195
	s_waitcnt lgkmcnt(4)
	v_mfma_f32_32x32x16_bf16 v[32:47], v[116:119], v[48:51], v[32:47]
	v_exp_f32_e32 v196, v196
	v_exp_f32_e32 v197, v197
	v_mfma_f32_32x32x16_bf16 v[32:47], v[120:123], v[52:55], v[32:47]
	v_exp_f32_e32 v198, v198
	v_exp_f32_e32 v199, v199
	v_mfma_f32_32x32x16_bf16 v[32:47], v[124:127], v[56:59], v[32:47]
	v_exp_f32_e32 v200, v200
	v_exp_f32_e32 v201, v201
	v_mfma_f32_32x32x16_bf16 v[32:47], v[128:131], v[60:63], v[32:47]
	v_exp_f32_e32 v202, v202
	v_exp_f32_e32 v203, v203
	v_cvt_pk_bf16_f32 v64, v188, v189
	v_cvt_pk_bf16_f32 v65, v190, v191
	v_cvt_pk_bf16_f32 v66, v192, v193
	v_cvt_pk_bf16_f32 v67, v194, v195
	v_cvt_pk_bf16_f32 v68, v196, v197
	v_cvt_pk_bf16_f32 v69, v198, v199
	v_cvt_pk_bf16_f32 v70, v200, v201
	v_cvt_pk_bf16_f32 v71, v202, v203
	v_pk_add_f32 v[232:233], v[232:233], v[188:189]
	v_pk_add_f32 v[232:233], v[232:233], v[190:191]
	v_pk_add_f32 v[232:233], v[232:233], v[192:193]
	v_pk_add_f32 v[232:233], v[232:233], v[194:195]
	v_pk_add_f32 v[232:233], v[232:233], v[196:197]
	v_pk_add_f32 v[232:233], v[232:233], v[198:199]
	v_pk_add_f32 v[232:233], v[232:233], v[200:201]
	v_pk_add_f32 v[232:233], v[232:233], v[202:203]
	ds_read2_b32 v[188:189], v115 offset0:32 offset1:33
	ds_read2_b32 v[190:191], v115 offset0:34 offset1:35
	ds_read2_b32 v[192:193], v115 offset0:40 offset1:41
	ds_read2_b32 v[194:195], v115 offset0:42 offset1:43
	ds_read2_b32 v[196:197], v115 offset0:48 offset1:49
	ds_read2_b32 v[198:199], v115 offset0:50 offset1:51
	ds_read2_b32 v[200:201], v115 offset0:56 offset1:57
	ds_read2_b32 v[202:203], v115 offset0:58 offset1:59
	v_mfma_f32_32x32x16_bf16 v[0:15], v[64:67], v[72:75], v[0:15]
	v_mfma_f32_32x32x16_bf16 v[16:31], v[64:67], v[76:79], v[16:31]
	v_mfma_f32_32x32x16_bf16 v[0:15], v[68:71], v[220:223], v[0:15]
	v_mfma_f32_32x32x16_bf16 v[16:31], v[68:71], v[224:227], v[16:31]
	global_load_dwordx4 v[116:119], v239, s[86:87]
	global_load_dwordx4 v[120:123], v240, s[86:87]
	global_load_dwordx4 v[124:127], v241, s[86:87]
	global_load_dwordx4 v[128:131], v242, s[86:87]
	global_load_dwordx4 v[132:135], v101, s[86:87] offset:768
	global_load_dwordx4 v[136:139], v150, s[86:87] offset:768
	global_load_dwordx4 v[140:143], v101, s[86:87] offset:832
	global_load_dwordx4 v[144:147], v150, s[86:87] offset:832
	s_add_u32 s86, s86, 0xc0000
	s_addc_u32 s87, s87, 0
	ds_read_b64_tr_b16 v[72:73], v231
	ds_read_b64_tr_b16 v[74:75], v231 offset:512
	ds_read_b64_tr_b16 v[76:77], v231 offset:2048
	ds_read_b64_tr_b16 v[78:79], v231 offset:2560
	ds_read_b64_tr_b16 v[220:221], v231 offset:1024
	ds_read_b64_tr_b16 v[222:223], v231 offset:1536
	ds_read_b64_tr_b16 v[224:225], v231 offset:3072
	ds_read_b64_tr_b16 v[226:227], v231 offset:3584
	v_exp_f32_e32 v32, v32
	v_exp_f32_e32 v33, v33
	v_exp_f32_e32 v34, v34
	v_exp_f32_e32 v35, v35
	s_waitcnt vmcnt(8)
	ds_write_b128 v247, v[156:159]
	ds_write_b128 v247, v[160:163] offset:1024
	ds_write_b128 v247, v[164:167] offset:2048
	ds_write_b128 v247, v[168:171] offset:3072
	ds_read_b128 v[156:159], v248
	ds_read_b128 v[160:163], v249
	ds_read_b128 v[164:167], v250
	ds_read_b128 v[168:171], v251
	ds_write_b128 v112, v[172:175]
	ds_write_b128 v112, v[176:179] offset:1024
	ds_write_b128 v112, v[180:183] offset:2048
	ds_write_b128 v112, v[184:187] offset:3072
	v_exp_f32_e32 v36, v36
	v_exp_f32_e32 v37, v37
	v_exp_f32_e32 v38, v38
	v_exp_f32_e32 v39, v39
	s_waitcnt lgkmcnt(4)
	v_mfma_f32_32x32x16_bf16 v[188:203], v[156:159], v[48:51], v[188:203]
	v_exp_f32_e32 v40, v40
	v_exp_f32_e32 v41, v41
	v_mfma_f32_32x32x16_bf16 v[188:203], v[160:163], v[52:55], v[188:203]
	v_exp_f32_e32 v42, v42
	v_exp_f32_e32 v43, v43
	v_mfma_f32_32x32x16_bf16 v[188:203], v[164:167], v[56:59], v[188:203]
	v_exp_f32_e32 v44, v44
	v_exp_f32_e32 v45, v45
	v_mfma_f32_32x32x16_bf16 v[188:203], v[168:171], v[60:63], v[188:203]
	v_exp_f32_e32 v46, v46
	v_exp_f32_e32 v47, v47
	v_cvt_pk_bf16_f32 v64, v32, v33
	v_cvt_pk_bf16_f32 v65, v34, v35
	v_cvt_pk_bf16_f32 v66, v36, v37
	v_cvt_pk_bf16_f32 v67, v38, v39
	v_cvt_pk_bf16_f32 v68, v40, v41
	v_cvt_pk_bf16_f32 v69, v42, v43
	v_cvt_pk_bf16_f32 v70, v44, v45
	v_cvt_pk_bf16_f32 v71, v46, v47
	v_pk_add_f32 v[232:233], v[232:233], v[32:33]
	v_pk_add_f32 v[232:233], v[232:233], v[34:35]
	v_pk_add_f32 v[232:233], v[232:233], v[36:37]
	v_pk_add_f32 v[232:233], v[232:233], v[38:39]
	v_pk_add_f32 v[232:233], v[232:233], v[40:41]
	v_pk_add_f32 v[232:233], v[232:233], v[42:43]
	v_pk_add_f32 v[232:233], v[232:233], v[44:45]
	v_pk_add_f32 v[232:233], v[232:233], v[46:47]
	ds_read2_b32 v[32:33], v115 offset0:64 offset1:65
	ds_read2_b32 v[34:35], v115 offset0:66 offset1:67
	ds_read2_b32 v[36:37], v115 offset0:72 offset1:73
	ds_read2_b32 v[38:39], v115 offset0:74 offset1:75
	ds_read2_b32 v[40:41], v115 offset0:80 offset1:81
	ds_read2_b32 v[42:43], v115 offset0:82 offset1:83
	ds_read2_b32 v[44:45], v115 offset0:88 offset1:89
	ds_read2_b32 v[46:47], v115 offset0:90 offset1:91
	v_mfma_f32_32x32x16_bf16 v[0:15], v[64:67], v[72:75], v[0:15]
	v_mfma_f32_32x32x16_bf16 v[16:31], v[64:67], v[76:79], v[16:31]
	v_mfma_f32_32x32x16_bf16 v[0:15], v[68:71], v[220:223], v[0:15]
	v_mfma_f32_32x32x16_bf16 v[16:31], v[68:71], v[224:227], v[16:31]
	global_load_dwordx4 v[156:159], v239, s[86:87]
	global_load_dwordx4 v[160:163], v240, s[86:87]
	global_load_dwordx4 v[164:167], v241, s[86:87]
	global_load_dwordx4 v[168:171], v242, s[86:87]
	global_load_dwordx4 v[172:175], v101, s[86:87] offset:768
	global_load_dwordx4 v[176:179], v150, s[86:87] offset:768
	global_load_dwordx4 v[180:183], v101, s[86:87] offset:832
	global_load_dwordx4 v[184:187], v150, s[86:87] offset:832
	s_add_u32 s86, s86, 0xc0000
	s_addc_u32 s87, s87, 0
	ds_read_b64_tr_b16 v[72:73], v231
	ds_read_b64_tr_b16 v[74:75], v231 offset:512
	ds_read_b64_tr_b16 v[76:77], v231 offset:2048
	ds_read_b64_tr_b16 v[78:79], v231 offset:2560
	ds_read_b64_tr_b16 v[220:221], v231 offset:1024
	ds_read_b64_tr_b16 v[222:223], v231 offset:1536
	ds_read_b64_tr_b16 v[224:225], v231 offset:3072
	ds_read_b64_tr_b16 v[226:227], v231 offset:3584
	v_exp_f32_e32 v188, v188
	v_exp_f32_e32 v189, v189
	v_exp_f32_e32 v190, v190
	v_exp_f32_e32 v191, v191
	s_waitcnt vmcnt(8)
	ds_write_b128 v247, v[116:119]
	ds_write_b128 v247, v[120:123] offset:1024
	ds_write_b128 v247, v[124:127] offset:2048
	ds_write_b128 v247, v[128:131] offset:3072
	ds_read_b128 v[116:119], v248
	ds_read_b128 v[120:123], v249
	ds_read_b128 v[124:127], v250
	ds_read_b128 v[128:131], v251
	ds_write_b128 v112, v[132:135]
	ds_write_b128 v112, v[136:139] offset:1024
	ds_write_b128 v112, v[140:143] offset:2048
	ds_write_b128 v112, v[144:147] offset:3072
	v_exp_f32_e32 v192, v192
	v_exp_f32_e32 v193, v193
	v_exp_f32_e32 v194, v194
	v_exp_f32_e32 v195, v195
	s_waitcnt lgkmcnt(4)
	v_mfma_f32_32x32x16_bf16 v[32:47], v[116:119], v[48:51], v[32:47]
	v_exp_f32_e32 v196, v196
	v_exp_f32_e32 v197, v197
	v_mfma_f32_32x32x16_bf16 v[32:47], v[120:123], v[52:55], v[32:47]
	v_exp_f32_e32 v198, v198
	v_exp_f32_e32 v199, v199
	v_mfma_f32_32x32x16_bf16 v[32:47], v[124:127], v[56:59], v[32:47]
	v_exp_f32_e32 v200, v200
	v_exp_f32_e32 v201, v201
	v_mfma_f32_32x32x16_bf16 v[32:47], v[128:131], v[60:63], v[32:47]
	v_exp_f32_e32 v202, v202
	v_exp_f32_e32 v203, v203
	v_cvt_pk_bf16_f32 v64, v188, v189
	v_cvt_pk_bf16_f32 v65, v190, v191
	v_cvt_pk_bf16_f32 v66, v192, v193
	v_cvt_pk_bf16_f32 v67, v194, v195
	v_cvt_pk_bf16_f32 v68, v196, v197
	v_cvt_pk_bf16_f32 v69, v198, v199
	v_cvt_pk_bf16_f32 v70, v200, v201
	v_cvt_pk_bf16_f32 v71, v202, v203
	v_pk_add_f32 v[232:233], v[232:233], v[188:189]
	v_pk_add_f32 v[232:233], v[232:233], v[190:191]
	v_pk_add_f32 v[232:233], v[232:233], v[192:193]
	v_pk_add_f32 v[232:233], v[232:233], v[194:195]
	v_pk_add_f32 v[232:233], v[232:233], v[196:197]
	v_pk_add_f32 v[232:233], v[232:233], v[198:199]
	v_pk_add_f32 v[232:233], v[232:233], v[200:201]
	v_pk_add_f32 v[232:233], v[232:233], v[202:203]
	ds_read2_b32 v[188:189], v115 offset0:96 offset1:97
	ds_read2_b32 v[190:191], v115 offset0:98 offset1:99
	ds_read2_b32 v[192:193], v115 offset0:104 offset1:105
	ds_read2_b32 v[194:195], v115 offset0:106 offset1:107
	ds_read2_b32 v[196:197], v115 offset0:112 offset1:113
	ds_read2_b32 v[198:199], v115 offset0:114 offset1:115
	ds_read2_b32 v[200:201], v115 offset0:120 offset1:121
	ds_read2_b32 v[202:203], v115 offset0:122 offset1:123
	v_mfma_f32_32x32x16_bf16 v[0:15], v[64:67], v[72:75], v[0:15]
	v_mfma_f32_32x32x16_bf16 v[16:31], v[64:67], v[76:79], v[16:31]
	v_mfma_f32_32x32x16_bf16 v[0:15], v[68:71], v[220:223], v[0:15]
	v_mfma_f32_32x32x16_bf16 v[16:31], v[68:71], v[224:227], v[16:31]
	global_load_dwordx4 v[116:119], v239, s[86:87]
	global_load_dwordx4 v[120:123], v240, s[86:87]
	global_load_dwordx4 v[124:127], v241, s[86:87]
	global_load_dwordx4 v[128:131], v242, s[86:87]
	global_load_dwordx4 v[132:135], v101, s[86:87] offset:768
	global_load_dwordx4 v[136:139], v150, s[86:87] offset:768
	global_load_dwordx4 v[140:143], v101, s[86:87] offset:832
	global_load_dwordx4 v[144:147], v150, s[86:87] offset:832
	s_add_u32 s86, s86, 0xc0000
	s_addc_u32 s87, s87, 0
	ds_read_b64_tr_b16 v[72:73], v231
	ds_read_b64_tr_b16 v[74:75], v231 offset:512
	ds_read_b64_tr_b16 v[76:77], v231 offset:2048
	ds_read_b64_tr_b16 v[78:79], v231 offset:2560
	ds_read_b64_tr_b16 v[220:221], v231 offset:1024
	ds_read_b64_tr_b16 v[222:223], v231 offset:1536
	ds_read_b64_tr_b16 v[224:225], v231 offset:3072
	ds_read_b64_tr_b16 v[226:227], v231 offset:3584
	v_exp_f32_e32 v32, v32
	v_exp_f32_e32 v33, v33
	v_exp_f32_e32 v34, v34
	v_exp_f32_e32 v35, v35
	s_waitcnt vmcnt(8)
	ds_write_b128 v247, v[156:159]
	ds_write_b128 v247, v[160:163] offset:1024
	ds_write_b128 v247, v[164:167] offset:2048
	ds_write_b128 v247, v[168:171] offset:3072
	ds_read_b128 v[156:159], v248
	ds_read_b128 v[160:163], v249
	ds_read_b128 v[164:167], v250
	ds_read_b128 v[168:171], v251
	ds_write_b128 v112, v[172:175]
	ds_write_b128 v112, v[176:179] offset:1024
	ds_write_b128 v112, v[180:183] offset:2048
	ds_write_b128 v112, v[184:187] offset:3072
	v_exp_f32_e32 v36, v36
	v_exp_f32_e32 v37, v37
	v_exp_f32_e32 v38, v38
	v_exp_f32_e32 v39, v39
	s_waitcnt lgkmcnt(4)
	v_mfma_f32_32x32x16_bf16 v[188:203], v[156:159], v[48:51], v[188:203]
	v_exp_f32_e32 v40, v40
	v_exp_f32_e32 v41, v41
	v_mfma_f32_32x32x16_bf16 v[188:203], v[160:163], v[52:55], v[188:203]
	v_exp_f32_e32 v42, v42
	v_exp_f32_e32 v43, v43
	v_mfma_f32_32x32x16_bf16 v[188:203], v[164:167], v[56:59], v[188:203]
	v_exp_f32_e32 v44, v44
	v_exp_f32_e32 v45, v45
	v_mfma_f32_32x32x16_bf16 v[188:203], v[168:171], v[60:63], v[188:203]
	v_exp_f32_e32 v46, v46
	v_exp_f32_e32 v47, v47
	v_cvt_pk_bf16_f32 v64, v32, v33
	v_cvt_pk_bf16_f32 v65, v34, v35
	v_cvt_pk_bf16_f32 v66, v36, v37
	v_cvt_pk_bf16_f32 v67, v38, v39
	v_cvt_pk_bf16_f32 v68, v40, v41
	v_cvt_pk_bf16_f32 v69, v42, v43
	v_cvt_pk_bf16_f32 v70, v44, v45
	v_cvt_pk_bf16_f32 v71, v46, v47
	v_pk_add_f32 v[232:233], v[232:233], v[32:33]
	v_pk_add_f32 v[232:233], v[232:233], v[34:35]
	v_pk_add_f32 v[232:233], v[232:233], v[36:37]
	v_pk_add_f32 v[232:233], v[232:233], v[38:39]
	v_pk_add_f32 v[232:233], v[232:233], v[40:41]
	v_pk_add_f32 v[232:233], v[232:233], v[42:43]
	v_pk_add_f32 v[232:233], v[232:233], v[44:45]
	v_pk_add_f32 v[232:233], v[232:233], v[46:47]
	ds_read2_b32 v[32:33], v115 offset0:128 offset1:129
	ds_read2_b32 v[34:35], v115 offset0:130 offset1:131
	ds_read2_b32 v[36:37], v115 offset0:136 offset1:137
	ds_read2_b32 v[38:39], v115 offset0:138 offset1:139
	ds_read2_b32 v[40:41], v115 offset0:144 offset1:145
	ds_read2_b32 v[42:43], v115 offset0:146 offset1:147
	ds_read2_b32 v[44:45], v115 offset0:152 offset1:153
	ds_read2_b32 v[46:47], v115 offset0:154 offset1:155
	v_mfma_f32_32x32x16_bf16 v[0:15], v[64:67], v[72:75], v[0:15]
	v_mfma_f32_32x32x16_bf16 v[16:31], v[64:67], v[76:79], v[16:31]
	v_mfma_f32_32x32x16_bf16 v[0:15], v[68:71], v[220:223], v[0:15]
	v_mfma_f32_32x32x16_bf16 v[16:31], v[68:71], v[224:227], v[16:31]
	global_load_dwordx4 v[156:159], v239, s[86:87]
	global_load_dwordx4 v[160:163], v240, s[86:87]
	global_load_dwordx4 v[164:167], v241, s[86:87]
	global_load_dwordx4 v[168:171], v242, s[86:87]
	global_load_dwordx4 v[172:175], v101, s[86:87] offset:768
	global_load_dwordx4 v[176:179], v150, s[86:87] offset:768
	global_load_dwordx4 v[180:183], v101, s[86:87] offset:832
	global_load_dwordx4 v[184:187], v150, s[86:87] offset:832
	s_add_u32 s86, s86, 0xc0000
	s_addc_u32 s87, s87, 0
	ds_read_b64_tr_b16 v[72:73], v231
	ds_read_b64_tr_b16 v[74:75], v231 offset:512
	ds_read_b64_tr_b16 v[76:77], v231 offset:2048
	ds_read_b64_tr_b16 v[78:79], v231 offset:2560
	ds_read_b64_tr_b16 v[220:221], v231 offset:1024
	ds_read_b64_tr_b16 v[222:223], v231 offset:1536
	ds_read_b64_tr_b16 v[224:225], v231 offset:3072
	ds_read_b64_tr_b16 v[226:227], v231 offset:3584
	v_exp_f32_e32 v188, v188
	v_exp_f32_e32 v189, v189
	v_exp_f32_e32 v190, v190
	v_exp_f32_e32 v191, v191
	s_waitcnt vmcnt(8)
	ds_write_b128 v247, v[116:119]
	ds_write_b128 v247, v[120:123] offset:1024
	ds_write_b128 v247, v[124:127] offset:2048
	ds_write_b128 v247, v[128:131] offset:3072
	ds_read_b128 v[116:119], v248
	ds_read_b128 v[120:123], v249
	ds_read_b128 v[124:127], v250
	ds_read_b128 v[128:131], v251
	ds_write_b128 v112, v[132:135]
	ds_write_b128 v112, v[136:139] offset:1024
	ds_write_b128 v112, v[140:143] offset:2048
	ds_write_b128 v112, v[144:147] offset:3072
	v_exp_f32_e32 v192, v192
	v_exp_f32_e32 v193, v193
	v_exp_f32_e32 v194, v194
	v_exp_f32_e32 v195, v195
	s_waitcnt lgkmcnt(4)
	v_mfma_f32_32x32x16_bf16 v[32:47], v[116:119], v[48:51], v[32:47]
	v_exp_f32_e32 v196, v196
	v_exp_f32_e32 v197, v197
	v_mfma_f32_32x32x16_bf16 v[32:47], v[120:123], v[52:55], v[32:47]
	v_exp_f32_e32 v198, v198
	v_exp_f32_e32 v199, v199
	v_mfma_f32_32x32x16_bf16 v[32:47], v[124:127], v[56:59], v[32:47]
	v_exp_f32_e32 v200, v200
	v_exp_f32_e32 v201, v201
	v_mfma_f32_32x32x16_bf16 v[32:47], v[128:131], v[60:63], v[32:47]
	v_exp_f32_e32 v202, v202
	v_exp_f32_e32 v203, v203
	v_cvt_pk_bf16_f32 v64, v188, v189
	v_cvt_pk_bf16_f32 v65, v190, v191
	v_cvt_pk_bf16_f32 v66, v192, v193
	v_cvt_pk_bf16_f32 v67, v194, v195
	v_cvt_pk_bf16_f32 v68, v196, v197
	v_cvt_pk_bf16_f32 v69, v198, v199
	v_cvt_pk_bf16_f32 v70, v200, v201
	v_cvt_pk_bf16_f32 v71, v202, v203
	v_pk_add_f32 v[232:233], v[232:233], v[188:189]
	v_pk_add_f32 v[232:233], v[232:233], v[190:191]
	v_pk_add_f32 v[232:233], v[232:233], v[192:193]
	v_pk_add_f32 v[232:233], v[232:233], v[194:195]
	v_pk_add_f32 v[232:233], v[232:233], v[196:197]
	v_pk_add_f32 v[232:233], v[232:233], v[198:199]
	v_pk_add_f32 v[232:233], v[232:233], v[200:201]
	v_pk_add_f32 v[232:233], v[232:233], v[202:203]
	ds_read2_b32 v[188:189], v115 offset0:160 offset1:161
	ds_read2_b32 v[190:191], v115 offset0:162 offset1:163
	ds_read2_b32 v[192:193], v115 offset0:168 offset1:169
	ds_read2_b32 v[194:195], v115 offset0:170 offset1:171
	ds_read2_b32 v[196:197], v115 offset0:176 offset1:177
	ds_read2_b32 v[198:199], v115 offset0:178 offset1:179
	ds_read2_b32 v[200:201], v115 offset0:184 offset1:185
	ds_read2_b32 v[202:203], v115 offset0:186 offset1:187
	v_mfma_f32_32x32x16_bf16 v[0:15], v[64:67], v[72:75], v[0:15]
	v_mfma_f32_32x32x16_bf16 v[16:31], v[64:67], v[76:79], v[16:31]
	v_mfma_f32_32x32x16_bf16 v[0:15], v[68:71], v[220:223], v[0:15]
	v_mfma_f32_32x32x16_bf16 v[16:31], v[68:71], v[224:227], v[16:31]
	global_load_dwordx4 v[116:119], v239, s[86:87]
	global_load_dwordx4 v[120:123], v240, s[86:87]
	global_load_dwordx4 v[124:127], v241, s[86:87]
	global_load_dwordx4 v[128:131], v242, s[86:87]
	global_load_dwordx4 v[132:135], v101, s[86:87] offset:768
	global_load_dwordx4 v[136:139], v150, s[86:87] offset:768
	global_load_dwordx4 v[140:143], v101, s[86:87] offset:832
	global_load_dwordx4 v[144:147], v150, s[86:87] offset:832
	s_add_u32 s86, s86, 0xc0000
	s_addc_u32 s87, s87, 0
	ds_read_b64_tr_b16 v[72:73], v231
	ds_read_b64_tr_b16 v[74:75], v231 offset:512
	ds_read_b64_tr_b16 v[76:77], v231 offset:2048
	ds_read_b64_tr_b16 v[78:79], v231 offset:2560
	ds_read_b64_tr_b16 v[220:221], v231 offset:1024
	ds_read_b64_tr_b16 v[222:223], v231 offset:1536
	ds_read_b64_tr_b16 v[224:225], v231 offset:3072
	ds_read_b64_tr_b16 v[226:227], v231 offset:3584
	v_exp_f32_e32 v32, v32
	v_exp_f32_e32 v33, v33
	v_exp_f32_e32 v34, v34
	v_exp_f32_e32 v35, v35
	s_waitcnt vmcnt(8)
	ds_write_b128 v247, v[156:159]
	ds_write_b128 v247, v[160:163] offset:1024
	ds_write_b128 v247, v[164:167] offset:2048
	ds_write_b128 v247, v[168:171] offset:3072
	ds_read_b128 v[156:159], v248
	ds_read_b128 v[160:163], v249
	ds_read_b128 v[164:167], v250
	ds_read_b128 v[168:171], v251
	ds_write_b128 v112, v[172:175]
	ds_write_b128 v112, v[176:179] offset:1024
	ds_write_b128 v112, v[180:183] offset:2048
	ds_write_b128 v112, v[184:187] offset:3072
	v_exp_f32_e32 v36, v36
	v_exp_f32_e32 v37, v37
	v_exp_f32_e32 v38, v38
	v_exp_f32_e32 v39, v39
	s_waitcnt lgkmcnt(4)
	v_mfma_f32_32x32x16_bf16 v[188:203], v[156:159], v[48:51], v[188:203]
	v_exp_f32_e32 v40, v40
	v_exp_f32_e32 v41, v41
	v_mfma_f32_32x32x16_bf16 v[188:203], v[160:163], v[52:55], v[188:203]
	v_exp_f32_e32 v42, v42
	v_exp_f32_e32 v43, v43
	v_mfma_f32_32x32x16_bf16 v[188:203], v[164:167], v[56:59], v[188:203]
	v_exp_f32_e32 v44, v44
	v_exp_f32_e32 v45, v45
	v_mfma_f32_32x32x16_bf16 v[188:203], v[168:171], v[60:63], v[188:203]
	v_exp_f32_e32 v46, v46
	v_exp_f32_e32 v47, v47
	v_cvt_pk_bf16_f32 v64, v32, v33
	v_cvt_pk_bf16_f32 v65, v34, v35
	v_cvt_pk_bf16_f32 v66, v36, v37
	v_cvt_pk_bf16_f32 v67, v38, v39
	v_cvt_pk_bf16_f32 v68, v40, v41
	v_cvt_pk_bf16_f32 v69, v42, v43
	v_cvt_pk_bf16_f32 v70, v44, v45
	v_cvt_pk_bf16_f32 v71, v46, v47
	v_pk_add_f32 v[232:233], v[232:233], v[32:33]
	v_pk_add_f32 v[232:233], v[232:233], v[34:35]
	v_pk_add_f32 v[232:233], v[232:233], v[36:37]
	v_pk_add_f32 v[232:233], v[232:233], v[38:39]
	v_pk_add_f32 v[232:233], v[232:233], v[40:41]
	v_pk_add_f32 v[232:233], v[232:233], v[42:43]
	v_pk_add_f32 v[232:233], v[232:233], v[44:45]
	v_pk_add_f32 v[232:233], v[232:233], v[46:47]
	ds_read2_b32 v[32:33], v115 offset0:192 offset1:193
	ds_read2_b32 v[34:35], v115 offset0:194 offset1:195
	ds_read2_b32 v[36:37], v115 offset0:200 offset1:201
	ds_read2_b32 v[38:39], v115 offset0:202 offset1:203
	ds_read2_b32 v[40:41], v115 offset0:208 offset1:209
	ds_read2_b32 v[42:43], v115 offset0:210 offset1:211
	ds_read2_b32 v[44:45], v115 offset0:216 offset1:217
	ds_read2_b32 v[46:47], v115 offset0:218 offset1:219
	v_mfma_f32_32x32x16_bf16 v[0:15], v[64:67], v[72:75], v[0:15]
	v_mfma_f32_32x32x16_bf16 v[16:31], v[64:67], v[76:79], v[16:31]
	v_mfma_f32_32x32x16_bf16 v[0:15], v[68:71], v[220:223], v[0:15]
	v_mfma_f32_32x32x16_bf16 v[16:31], v[68:71], v[224:227], v[16:31]
	global_load_dwordx4 v[156:159], v239, s[86:87]
	global_load_dwordx4 v[160:163], v240, s[86:87]
	global_load_dwordx4 v[164:167], v241, s[86:87]
	global_load_dwordx4 v[168:171], v242, s[86:87]
	global_load_dwordx4 v[172:175], v101, s[86:87] offset:768
	global_load_dwordx4 v[176:179], v150, s[86:87] offset:768
	global_load_dwordx4 v[180:183], v101, s[86:87] offset:832
	global_load_dwordx4 v[184:187], v150, s[86:87] offset:832
	ds_read_b64_tr_b16 v[72:73], v231
	ds_read_b64_tr_b16 v[74:75], v231 offset:512
	ds_read_b64_tr_b16 v[76:77], v231 offset:2048
	ds_read_b64_tr_b16 v[78:79], v231 offset:2560
	ds_read_b64_tr_b16 v[220:221], v231 offset:1024
	ds_read_b64_tr_b16 v[222:223], v231 offset:1536
	ds_read_b64_tr_b16 v[224:225], v231 offset:3072
	ds_read_b64_tr_b16 v[226:227], v231 offset:3584
	v_exp_f32_e32 v188, v188
	v_exp_f32_e32 v189, v189
	v_exp_f32_e32 v190, v190
	v_exp_f32_e32 v191, v191
	s_waitcnt vmcnt(8)
	ds_write_b128 v247, v[116:119]
	ds_write_b128 v247, v[120:123] offset:1024
	ds_write_b128 v247, v[124:127] offset:2048
	ds_write_b128 v247, v[128:131] offset:3072
	ds_read_b128 v[116:119], v248
	ds_read_b128 v[120:123], v249
	ds_read_b128 v[124:127], v250
	ds_read_b128 v[128:131], v251
	ds_write_b128 v112, v[132:135]
	ds_write_b128 v112, v[136:139] offset:1024
	ds_write_b128 v112, v[140:143] offset:2048
	ds_write_b128 v112, v[144:147] offset:3072
	v_exp_f32_e32 v192, v192
	v_exp_f32_e32 v193, v193
	v_exp_f32_e32 v194, v194
	v_exp_f32_e32 v195, v195
	s_waitcnt lgkmcnt(4)
	v_mfma_f32_32x32x16_bf16 v[32:47], v[116:119], v[48:51], v[32:47]
	v_exp_f32_e32 v196, v196
	v_exp_f32_e32 v197, v197
	v_mfma_f32_32x32x16_bf16 v[32:47], v[120:123], v[52:55], v[32:47]
	v_exp_f32_e32 v198, v198
	v_exp_f32_e32 v199, v199
	v_mfma_f32_32x32x16_bf16 v[32:47], v[124:127], v[56:59], v[32:47]
	v_exp_f32_e32 v200, v200
	v_exp_f32_e32 v201, v201
	v_mfma_f32_32x32x16_bf16 v[32:47], v[128:131], v[60:63], v[32:47]
	v_exp_f32_e32 v202, v202
	v_exp_f32_e32 v203, v203
	v_cvt_pk_bf16_f32 v64, v188, v189
	v_cvt_pk_bf16_f32 v65, v190, v191
	v_cvt_pk_bf16_f32 v66, v192, v193
	v_cvt_pk_bf16_f32 v67, v194, v195
	v_cvt_pk_bf16_f32 v68, v196, v197
	v_cvt_pk_bf16_f32 v69, v198, v199
	v_cvt_pk_bf16_f32 v70, v200, v201
	v_cvt_pk_bf16_f32 v71, v202, v203
	v_pk_add_f32 v[232:233], v[232:233], v[188:189]
	v_pk_add_f32 v[232:233], v[232:233], v[190:191]
	v_pk_add_f32 v[232:233], v[232:233], v[192:193]
	v_pk_add_f32 v[232:233], v[232:233], v[194:195]
	v_pk_add_f32 v[232:233], v[232:233], v[196:197]
	v_pk_add_f32 v[232:233], v[232:233], v[198:199]
	v_pk_add_f32 v[232:233], v[232:233], v[200:201]
	v_pk_add_f32 v[232:233], v[232:233], v[202:203]
	ds_read2_b32 v[188:189], v115 offset0:224 offset1:225
	ds_read2_b32 v[190:191], v115 offset0:226 offset1:227
	ds_read2_b32 v[192:193], v115 offset0:232 offset1:233
	ds_read2_b32 v[194:195], v115 offset0:234 offset1:235
	ds_read2_b32 v[196:197], v115 offset0:240 offset1:241
	ds_read2_b32 v[198:199], v115 offset0:242 offset1:243
	ds_read2_b32 v[200:201], v115 offset0:248 offset1:249
	ds_read2_b32 v[202:203], v115 offset0:250 offset1:251
	v_mfma_f32_32x32x16_bf16 v[0:15], v[64:67], v[72:75], v[0:15]
	v_mfma_f32_32x32x16_bf16 v[16:31], v[64:67], v[76:79], v[16:31]
	v_mfma_f32_32x32x16_bf16 v[0:15], v[68:71], v[220:223], v[0:15]
	v_mfma_f32_32x32x16_bf16 v[16:31], v[68:71], v[224:227], v[16:31]
	global_load_dwordx4 v[116:119], v243, s[88:89]
	global_load_dwordx4 v[120:123], v244, s[88:89]
	global_load_dwordx4 v[124:127], v245, s[88:89]
	global_load_dwordx4 v[128:131], v246, s[88:89]
	global_load_dwordx4 v[132:135], v148, s[88:89] offset:768
	global_load_dwordx4 v[136:139], v151, s[88:89] offset:768
	global_load_dwordx4 v[140:143], v148, s[88:89] offset:832
	global_load_dwordx4 v[144:147], v151, s[88:89] offset:832
	s_add_u32 s88, s88, 0x300000
	s_addc_u32 s89, s89, 0
	ds_read_b64_tr_b16 v[72:73], v231
	ds_read_b64_tr_b16 v[74:75], v231 offset:512
	ds_read_b64_tr_b16 v[76:77], v231 offset:2048
	ds_read_b64_tr_b16 v[78:79], v231 offset:2560
	ds_read_b64_tr_b16 v[220:221], v231 offset:1024
	ds_read_b64_tr_b16 v[222:223], v231 offset:1536
	ds_read_b64_tr_b16 v[224:225], v231 offset:3072
	ds_read_b64_tr_b16 v[226:227], v231 offset:3584
	v_exp_f32_e32 v32, v32
	v_exp_f32_e32 v33, v33
	v_exp_f32_e32 v34, v34
	v_exp_f32_e32 v35, v35
	s_waitcnt vmcnt(8)
	ds_write_b128 v247, v[156:159]
	ds_write_b128 v247, v[160:163] offset:1024
	ds_write_b128 v247, v[164:167] offset:2048
	ds_write_b128 v247, v[168:171] offset:3072
	ds_read_b128 v[156:159], v248
	ds_read_b128 v[160:163], v249
	ds_read_b128 v[164:167], v250
	ds_read_b128 v[168:171], v251
	ds_write_b128 v112, v[172:175]
	ds_write_b128 v112, v[176:179] offset:1024
	ds_write_b128 v112, v[180:183] offset:2048
	ds_write_b128 v112, v[184:187] offset:3072
	v_exp_f32_e32 v36, v36
	v_exp_f32_e32 v37, v37
	v_exp_f32_e32 v38, v38
	v_exp_f32_e32 v39, v39
	s_waitcnt lgkmcnt(4)
	v_mfma_f32_32x32x16_bf16 v[188:203], v[156:159], v[48:51], v[188:203]
	v_exp_f32_e32 v40, v40
	v_exp_f32_e32 v41, v41
	v_mfma_f32_32x32x16_bf16 v[188:203], v[160:163], v[52:55], v[188:203]
	v_exp_f32_e32 v42, v42
	v_exp_f32_e32 v43, v43
	v_mfma_f32_32x32x16_bf16 v[188:203], v[164:167], v[56:59], v[188:203]
	v_exp_f32_e32 v44, v44
	v_exp_f32_e32 v45, v45
	v_mfma_f32_32x32x16_bf16 v[188:203], v[168:171], v[60:63], v[188:203]
	v_exp_f32_e32 v46, v46
	v_exp_f32_e32 v47, v47
	v_cvt_pk_bf16_f32 v64, v32, v33
	v_cvt_pk_bf16_f32 v65, v34, v35
	v_cvt_pk_bf16_f32 v66, v36, v37
	v_cvt_pk_bf16_f32 v67, v38, v39
	v_cvt_pk_bf16_f32 v68, v40, v41
	v_cvt_pk_bf16_f32 v69, v42, v43
	v_cvt_pk_bf16_f32 v70, v44, v45
	v_cvt_pk_bf16_f32 v71, v46, v47
	v_pk_add_f32 v[232:233], v[232:233], v[32:33]
	v_pk_add_f32 v[232:233], v[232:233], v[34:35]
	v_pk_add_f32 v[232:233], v[232:233], v[36:37]
	v_pk_add_f32 v[232:233], v[232:233], v[38:39]
	v_pk_add_f32 v[232:233], v[232:233], v[40:41]
	v_pk_add_f32 v[232:233], v[232:233], v[42:43]
	v_pk_add_f32 v[232:233], v[232:233], v[44:45]
	v_pk_add_f32 v[232:233], v[232:233], v[46:47]
	v_mov_b32_e32 v115, v230
	ds_read2_b32 v[32:33], v115 offset0:0 offset1:1
	ds_read2_b32 v[34:35], v115 offset0:2 offset1:3
	ds_read2_b32 v[36:37], v115 offset0:8 offset1:9
	ds_read2_b32 v[38:39], v115 offset0:10 offset1:11
	ds_read2_b32 v[40:41], v115 offset0:16 offset1:17
	ds_read2_b32 v[42:43], v115 offset0:18 offset1:19
	ds_read2_b32 v[44:45], v115 offset0:24 offset1:25
	ds_read2_b32 v[46:47], v115 offset0:26 offset1:27
	v_mfma_f32_32x32x16_bf16 v[0:15], v[64:67], v[72:75], v[0:15]
	v_mfma_f32_32x32x16_bf16 v[16:31], v[64:67], v[76:79], v[16:31]
	v_mfma_f32_32x32x16_bf16 v[0:15], v[68:71], v[220:223], v[0:15]
	v_mfma_f32_32x32x16_bf16 v[16:31], v[68:71], v[224:227], v[16:31]
	global_load_dwordx4 v[156:159], v243, s[88:89]
	global_load_dwordx4 v[160:163], v244, s[88:89]
	global_load_dwordx4 v[164:167], v245, s[88:89]
	global_load_dwordx4 v[168:171], v246, s[88:89]
	global_load_dwordx4 v[172:175], v148, s[88:89] offset:768
	global_load_dwordx4 v[176:179], v151, s[88:89] offset:768
	global_load_dwordx4 v[180:183], v148, s[88:89] offset:832
	global_load_dwordx4 v[184:187], v151, s[88:89] offset:832
	s_add_u32 s88, s88, 0x300000
	s_addc_u32 s89, s89, 0
	ds_read_b64_tr_b16 v[72:73], v231
	ds_read_b64_tr_b16 v[74:75], v231 offset:512
	ds_read_b64_tr_b16 v[76:77], v231 offset:2048
	ds_read_b64_tr_b16 v[78:79], v231 offset:2560
	ds_read_b64_tr_b16 v[220:221], v231 offset:1024
	ds_read_b64_tr_b16 v[222:223], v231 offset:1536
	ds_read_b64_tr_b16 v[224:225], v231 offset:3072
	ds_read_b64_tr_b16 v[226:227], v231 offset:3584
	v_exp_f32_e32 v188, v188
	v_exp_f32_e32 v189, v189
	v_exp_f32_e32 v190, v190
	v_exp_f32_e32 v191, v191
	s_waitcnt vmcnt(8)
	ds_write_b128 v247, v[116:119]
	ds_write_b128 v247, v[120:123] offset:1024
	ds_write_b128 v247, v[124:127] offset:2048
	ds_write_b128 v247, v[128:131] offset:3072
	ds_read_b128 v[116:119], v248
	ds_read_b128 v[120:123], v249
	ds_read_b128 v[124:127], v250
	ds_read_b128 v[128:131], v251
	ds_write_b128 v112, v[132:135]
	ds_write_b128 v112, v[136:139] offset:1024
	ds_write_b128 v112, v[140:143] offset:2048
	ds_write_b128 v112, v[144:147] offset:3072
	v_exp_f32_e32 v192, v192
	v_exp_f32_e32 v193, v193
	v_exp_f32_e32 v194, v194
	v_exp_f32_e32 v195, v195
	s_waitcnt lgkmcnt(4)
	v_mfma_f32_32x32x16_bf16 v[32:47], v[116:119], v[48:51], v[32:47]
	v_exp_f32_e32 v196, v196
	v_exp_f32_e32 v197, v197
	v_mfma_f32_32x32x16_bf16 v[32:47], v[120:123], v[52:55], v[32:47]
	v_exp_f32_e32 v198, v198
	v_exp_f32_e32 v199, v199
	v_mfma_f32_32x32x16_bf16 v[32:47], v[124:127], v[56:59], v[32:47]
	v_exp_f32_e32 v200, v200
	v_exp_f32_e32 v201, v201
	v_mfma_f32_32x32x16_bf16 v[32:47], v[128:131], v[60:63], v[32:47]
	v_exp_f32_e32 v202, v202
	v_exp_f32_e32 v203, v203
	v_cvt_pk_bf16_f32 v64, v188, v189
	v_cvt_pk_bf16_f32 v65, v190, v191
	v_cvt_pk_bf16_f32 v66, v192, v193
	v_cvt_pk_bf16_f32 v67, v194, v195
	v_cvt_pk_bf16_f32 v68, v196, v197
	v_cvt_pk_bf16_f32 v69, v198, v199
	v_cvt_pk_bf16_f32 v70, v200, v201
	v_cvt_pk_bf16_f32 v71, v202, v203
	v_pk_add_f32 v[232:233], v[232:233], v[188:189]
	v_pk_add_f32 v[232:233], v[232:233], v[190:191]
	v_pk_add_f32 v[232:233], v[232:233], v[192:193]
	v_pk_add_f32 v[232:233], v[232:233], v[194:195]
	v_pk_add_f32 v[232:233], v[232:233], v[196:197]
	v_pk_add_f32 v[232:233], v[232:233], v[198:199]
	v_pk_add_f32 v[232:233], v[232:233], v[200:201]
	v_pk_add_f32 v[232:233], v[232:233], v[202:203]
	ds_read2_b32 v[188:189], v115 offset0:32 offset1:33
	ds_read2_b32 v[190:191], v115 offset0:34 offset1:35
	ds_read2_b32 v[192:193], v115 offset0:40 offset1:41
	ds_read2_b32 v[194:195], v115 offset0:42 offset1:43
	ds_read2_b32 v[196:197], v115 offset0:48 offset1:49
	ds_read2_b32 v[198:199], v115 offset0:50 offset1:51
	ds_read2_b32 v[200:201], v115 offset0:56 offset1:57
	ds_read2_b32 v[202:203], v115 offset0:58 offset1:59
	v_mfma_f32_32x32x16_bf16 v[0:15], v[64:67], v[72:75], v[0:15]
	v_mfma_f32_32x32x16_bf16 v[16:31], v[64:67], v[76:79], v[16:31]
	v_mfma_f32_32x32x16_bf16 v[0:15], v[68:71], v[220:223], v[0:15]
	v_mfma_f32_32x32x16_bf16 v[16:31], v[68:71], v[224:227], v[16:31]
	global_load_dwordx4 v[116:119], v243, s[88:89]
	global_load_dwordx4 v[120:123], v244, s[88:89]
	global_load_dwordx4 v[124:127], v245, s[88:89]
	global_load_dwordx4 v[128:131], v246, s[88:89]
	global_load_dwordx4 v[132:135], v148, s[88:89] offset:768
	global_load_dwordx4 v[136:139], v151, s[88:89] offset:768
	global_load_dwordx4 v[140:143], v148, s[88:89] offset:832
	global_load_dwordx4 v[144:147], v151, s[88:89] offset:832
	s_add_u32 s88, s88, 0x300000
	s_addc_u32 s89, s89, 0
	ds_read_b64_tr_b16 v[72:73], v231
	ds_read_b64_tr_b16 v[74:75], v231 offset:512
	ds_read_b64_tr_b16 v[76:77], v231 offset:2048
	ds_read_b64_tr_b16 v[78:79], v231 offset:2560
	ds_read_b64_tr_b16 v[220:221], v231 offset:1024
	ds_read_b64_tr_b16 v[222:223], v231 offset:1536
	ds_read_b64_tr_b16 v[224:225], v231 offset:3072
	ds_read_b64_tr_b16 v[226:227], v231 offset:3584
	v_exp_f32_e32 v32, v32
	v_exp_f32_e32 v33, v33
	v_exp_f32_e32 v34, v34
	v_exp_f32_e32 v35, v35
	s_waitcnt vmcnt(8)
	ds_write_b128 v247, v[156:159]
	ds_write_b128 v247, v[160:163] offset:1024
	ds_write_b128 v247, v[164:167] offset:2048
	ds_write_b128 v247, v[168:171] offset:3072
	ds_read_b128 v[156:159], v248
	ds_read_b128 v[160:163], v249
	ds_read_b128 v[164:167], v250
	ds_read_b128 v[168:171], v251
	ds_write_b128 v112, v[172:175]
	ds_write_b128 v112, v[176:179] offset:1024
	ds_write_b128 v112, v[180:183] offset:2048
	ds_write_b128 v112, v[184:187] offset:3072
	v_exp_f32_e32 v36, v36
	v_exp_f32_e32 v37, v37
	v_exp_f32_e32 v38, v38
	v_exp_f32_e32 v39, v39
	s_waitcnt lgkmcnt(4)
	v_mfma_f32_32x32x16_bf16 v[188:203], v[156:159], v[48:51], v[188:203]
	v_exp_f32_e32 v40, v40
	v_exp_f32_e32 v41, v41
	v_mfma_f32_32x32x16_bf16 v[188:203], v[160:163], v[52:55], v[188:203]
	v_exp_f32_e32 v42, v42
	v_exp_f32_e32 v43, v43
	v_mfma_f32_32x32x16_bf16 v[188:203], v[164:167], v[56:59], v[188:203]
	v_exp_f32_e32 v44, v44
	v_exp_f32_e32 v45, v45
	v_mfma_f32_32x32x16_bf16 v[188:203], v[168:171], v[60:63], v[188:203]
	v_exp_f32_e32 v46, v46
	v_exp_f32_e32 v47, v47
	v_cvt_pk_bf16_f32 v64, v32, v33
	v_cvt_pk_bf16_f32 v65, v34, v35
	v_cvt_pk_bf16_f32 v66, v36, v37
	v_cvt_pk_bf16_f32 v67, v38, v39
	v_cvt_pk_bf16_f32 v68, v40, v41
	v_cvt_pk_bf16_f32 v69, v42, v43
	v_cvt_pk_bf16_f32 v70, v44, v45
	v_cvt_pk_bf16_f32 v71, v46, v47
	v_pk_add_f32 v[232:233], v[232:233], v[32:33]
	v_pk_add_f32 v[232:233], v[232:233], v[34:35]
	v_pk_add_f32 v[232:233], v[232:233], v[36:37]
	v_pk_add_f32 v[232:233], v[232:233], v[38:39]
	v_pk_add_f32 v[232:233], v[232:233], v[40:41]
	v_pk_add_f32 v[232:233], v[232:233], v[42:43]
	v_pk_add_f32 v[232:233], v[232:233], v[44:45]
	v_pk_add_f32 v[232:233], v[232:233], v[46:47]
	ds_read2_b32 v[32:33], v115 offset0:64 offset1:65
	ds_read2_b32 v[34:35], v115 offset0:66 offset1:67
	ds_read2_b32 v[36:37], v115 offset0:72 offset1:73
	ds_read2_b32 v[38:39], v115 offset0:74 offset1:75
	ds_read2_b32 v[40:41], v115 offset0:80 offset1:81
	ds_read2_b32 v[42:43], v115 offset0:82 offset1:83
	ds_read2_b32 v[44:45], v115 offset0:88 offset1:89
	ds_read2_b32 v[46:47], v115 offset0:90 offset1:91
	v_mfma_f32_32x32x16_bf16 v[0:15], v[64:67], v[72:75], v[0:15]
	v_mfma_f32_32x32x16_bf16 v[16:31], v[64:67], v[76:79], v[16:31]
	v_mfma_f32_32x32x16_bf16 v[0:15], v[68:71], v[220:223], v[0:15]
	v_mfma_f32_32x32x16_bf16 v[16:31], v[68:71], v[224:227], v[16:31]
	global_load_dwordx4 v[156:159], v243, s[88:89]
	global_load_dwordx4 v[160:163], v244, s[88:89]
	global_load_dwordx4 v[164:167], v245, s[88:89]
	global_load_dwordx4 v[168:171], v246, s[88:89]
	global_load_dwordx4 v[172:175], v148, s[88:89] offset:768
	global_load_dwordx4 v[176:179], v151, s[88:89] offset:768
	global_load_dwordx4 v[180:183], v148, s[88:89] offset:832
	global_load_dwordx4 v[184:187], v151, s[88:89] offset:832
	s_add_u32 s88, s88, 0x300000
	s_addc_u32 s89, s89, 0
	ds_read_b64_tr_b16 v[72:73], v231
	ds_read_b64_tr_b16 v[74:75], v231 offset:512
	ds_read_b64_tr_b16 v[76:77], v231 offset:2048
	ds_read_b64_tr_b16 v[78:79], v231 offset:2560
	ds_read_b64_tr_b16 v[220:221], v231 offset:1024
	ds_read_b64_tr_b16 v[222:223], v231 offset:1536
	ds_read_b64_tr_b16 v[224:225], v231 offset:3072
	ds_read_b64_tr_b16 v[226:227], v231 offset:3584
	v_exp_f32_e32 v188, v188
	v_exp_f32_e32 v189, v189
	v_exp_f32_e32 v190, v190
	v_exp_f32_e32 v191, v191
	s_waitcnt vmcnt(8)
	ds_write_b128 v247, v[116:119]
	ds_write_b128 v247, v[120:123] offset:1024
	ds_write_b128 v247, v[124:127] offset:2048
	ds_write_b128 v247, v[128:131] offset:3072
	ds_read_b128 v[116:119], v248
	ds_read_b128 v[120:123], v249
	ds_read_b128 v[124:127], v250
	ds_read_b128 v[128:131], v251
	ds_write_b128 v112, v[132:135]
	ds_write_b128 v112, v[136:139] offset:1024
	ds_write_b128 v112, v[140:143] offset:2048
	ds_write_b128 v112, v[144:147] offset:3072
	v_exp_f32_e32 v192, v192
	v_exp_f32_e32 v193, v193
	v_exp_f32_e32 v194, v194
	v_exp_f32_e32 v195, v195
	s_waitcnt lgkmcnt(4)
	v_mfma_f32_32x32x16_bf16 v[32:47], v[116:119], v[48:51], v[32:47]
	v_exp_f32_e32 v196, v196
	v_exp_f32_e32 v197, v197
	v_mfma_f32_32x32x16_bf16 v[32:47], v[120:123], v[52:55], v[32:47]
	v_exp_f32_e32 v198, v198
	v_exp_f32_e32 v199, v199
	v_mfma_f32_32x32x16_bf16 v[32:47], v[124:127], v[56:59], v[32:47]
	v_exp_f32_e32 v200, v200
	v_exp_f32_e32 v201, v201
	v_mfma_f32_32x32x16_bf16 v[32:47], v[128:131], v[60:63], v[32:47]
	v_exp_f32_e32 v202, v202
	v_exp_f32_e32 v203, v203
	v_cvt_pk_bf16_f32 v64, v188, v189
	v_cvt_pk_bf16_f32 v65, v190, v191
	v_cvt_pk_bf16_f32 v66, v192, v193
	v_cvt_pk_bf16_f32 v67, v194, v195
	v_cvt_pk_bf16_f32 v68, v196, v197
	v_cvt_pk_bf16_f32 v69, v198, v199
	v_cvt_pk_bf16_f32 v70, v200, v201
	v_cvt_pk_bf16_f32 v71, v202, v203
	v_pk_add_f32 v[232:233], v[232:233], v[188:189]
	v_pk_add_f32 v[232:233], v[232:233], v[190:191]
	v_pk_add_f32 v[232:233], v[232:233], v[192:193]
	v_pk_add_f32 v[232:233], v[232:233], v[194:195]
	v_pk_add_f32 v[232:233], v[232:233], v[196:197]
	v_pk_add_f32 v[232:233], v[232:233], v[198:199]
	v_pk_add_f32 v[232:233], v[232:233], v[200:201]
	v_pk_add_f32 v[232:233], v[232:233], v[202:203]
	ds_read2_b32 v[188:189], v115 offset0:96 offset1:97
	ds_read2_b32 v[190:191], v115 offset0:98 offset1:99
	ds_read2_b32 v[192:193], v115 offset0:104 offset1:105
	ds_read2_b32 v[194:195], v115 offset0:106 offset1:107
	ds_read2_b32 v[196:197], v115 offset0:112 offset1:113
	ds_read2_b32 v[198:199], v115 offset0:114 offset1:115
	ds_read2_b32 v[200:201], v115 offset0:120 offset1:121
	ds_read2_b32 v[202:203], v115 offset0:122 offset1:123
	v_mfma_f32_32x32x16_bf16 v[0:15], v[64:67], v[72:75], v[0:15]
	v_mfma_f32_32x32x16_bf16 v[16:31], v[64:67], v[76:79], v[16:31]
	v_mfma_f32_32x32x16_bf16 v[0:15], v[68:71], v[220:223], v[0:15]
	v_mfma_f32_32x32x16_bf16 v[16:31], v[68:71], v[224:227], v[16:31]
	global_load_dwordx4 v[116:119], v243, s[88:89]
	global_load_dwordx4 v[120:123], v244, s[88:89]
	global_load_dwordx4 v[124:127], v245, s[88:89]
	global_load_dwordx4 v[128:131], v246, s[88:89]
	global_load_dwordx4 v[132:135], v148, s[88:89] offset:768
	global_load_dwordx4 v[136:139], v151, s[88:89] offset:768
	global_load_dwordx4 v[140:143], v148, s[88:89] offset:832
	global_load_dwordx4 v[144:147], v151, s[88:89] offset:832
	ds_read_b64_tr_b16 v[72:73], v231
	ds_read_b64_tr_b16 v[74:75], v231 offset:512
	ds_read_b64_tr_b16 v[76:77], v231 offset:2048
	ds_read_b64_tr_b16 v[78:79], v231 offset:2560
	ds_read_b64_tr_b16 v[220:221], v231 offset:1024
	ds_read_b64_tr_b16 v[222:223], v231 offset:1536
	ds_read_b64_tr_b16 v[224:225], v231 offset:3072
	ds_read_b64_tr_b16 v[226:227], v231 offset:3584
	v_exp_f32_e32 v32, v32
	v_exp_f32_e32 v33, v33
	v_exp_f32_e32 v34, v34
	v_exp_f32_e32 v35, v35
	s_waitcnt vmcnt(8)
	ds_write_b128 v247, v[156:159]
	ds_write_b128 v247, v[160:163] offset:1024
	ds_write_b128 v247, v[164:167] offset:2048
	ds_write_b128 v247, v[168:171] offset:3072
	ds_read_b128 v[156:159], v248
	ds_read_b128 v[160:163], v249
	ds_read_b128 v[164:167], v250
	ds_read_b128 v[168:171], v251
	ds_write_b128 v112, v[172:175]
	ds_write_b128 v112, v[176:179] offset:1024
	ds_write_b128 v112, v[180:183] offset:2048
	ds_write_b128 v112, v[184:187] offset:3072
	v_exp_f32_e32 v36, v36
	v_exp_f32_e32 v37, v37
	v_exp_f32_e32 v38, v38
	v_exp_f32_e32 v39, v39
	s_waitcnt lgkmcnt(4)
	v_mfma_f32_32x32x16_bf16 v[188:203], v[156:159], v[48:51], v[188:203]
	v_exp_f32_e32 v40, v40
	v_exp_f32_e32 v41, v41
	v_mfma_f32_32x32x16_bf16 v[188:203], v[160:163], v[52:55], v[188:203]
	v_exp_f32_e32 v42, v42
	v_exp_f32_e32 v43, v43
	v_mfma_f32_32x32x16_bf16 v[188:203], v[164:167], v[56:59], v[188:203]
	v_exp_f32_e32 v44, v44
	v_exp_f32_e32 v45, v45
	v_mfma_f32_32x32x16_bf16 v[188:203], v[168:171], v[60:63], v[188:203]
	v_exp_f32_e32 v46, v46
	v_exp_f32_e32 v47, v47
	v_cvt_pk_bf16_f32 v64, v32, v33
	v_cvt_pk_bf16_f32 v65, v34, v35
	v_cvt_pk_bf16_f32 v66, v36, v37
	v_cvt_pk_bf16_f32 v67, v38, v39
	v_cvt_pk_bf16_f32 v68, v40, v41
	v_cvt_pk_bf16_f32 v69, v42, v43
	v_cvt_pk_bf16_f32 v70, v44, v45
	v_cvt_pk_bf16_f32 v71, v46, v47
	v_pk_add_f32 v[232:233], v[232:233], v[32:33]
	v_pk_add_f32 v[232:233], v[232:233], v[34:35]
	v_pk_add_f32 v[232:233], v[232:233], v[36:37]
	v_pk_add_f32 v[232:233], v[232:233], v[38:39]
	v_pk_add_f32 v[232:233], v[232:233], v[40:41]
	v_pk_add_f32 v[232:233], v[232:233], v[42:43]
	v_pk_add_f32 v[232:233], v[232:233], v[44:45]
	v_pk_add_f32 v[232:233], v[232:233], v[46:47]
	ds_read2_b32 v[32:33], v115 offset0:128 offset1:129
	ds_read2_b32 v[34:35], v115 offset0:130 offset1:131
	ds_read2_b32 v[36:37], v115 offset0:136 offset1:137
	ds_read2_b32 v[38:39], v115 offset0:138 offset1:139
	ds_read2_b32 v[40:41], v115 offset0:144 offset1:145
	ds_read2_b32 v[42:43], v115 offset0:146 offset1:147
	ds_read2_b32 v[44:45], v115 offset0:152 offset1:153
	ds_read2_b32 v[46:47], v115 offset0:154 offset1:155
	v_mfma_f32_32x32x16_bf16 v[0:15], v[64:67], v[72:75], v[0:15]
	v_mfma_f32_32x32x16_bf16 v[16:31], v[64:67], v[76:79], v[16:31]
	v_mfma_f32_32x32x16_bf16 v[0:15], v[68:71], v[220:223], v[0:15]
	v_mfma_f32_32x32x16_bf16 v[16:31], v[68:71], v[224:227], v[16:31]
	ds_read_b64_tr_b16 v[72:73], v231
	ds_read_b64_tr_b16 v[74:75], v231 offset:512
	ds_read_b64_tr_b16 v[76:77], v231 offset:2048
	ds_read_b64_tr_b16 v[78:79], v231 offset:2560
	ds_read_b64_tr_b16 v[220:221], v231 offset:1024
	ds_read_b64_tr_b16 v[222:223], v231 offset:1536
	ds_read_b64_tr_b16 v[224:225], v231 offset:3072
	ds_read_b64_tr_b16 v[226:227], v231 offset:3584
	v_exp_f32_e32 v188, v188
	v_exp_f32_e32 v189, v189
	v_exp_f32_e32 v190, v190
	v_exp_f32_e32 v191, v191
	s_waitcnt vmcnt(0)
; __device__ __forceinline__ int crow(int r, int hi) { return (r & 3) + 8 * (r >> 2) + 4 * hi; }
; __device__ __forceinline__ void dil_unit(LAS unsigned char* lds, bf16_t* proj, int seq, int hd, int T0, int rho) {
;     ...
;     l += __shfl_xor(l, 32);
; #pragma unroll
;     for (int rr = 0; rr < 16; ++rr) {
;         const int j = crow(rr, hi);
;         const float il = __builtin_amdgcn_rcpf(__shfl(l, j));
	ds_write_b128 v247, v[116:119]
	ds_write_b128 v247, v[120:123] offset:1024
	ds_write_b128 v247, v[124:127] offset:2048
	ds_write_b128 v247, v[128:131] offset:3072
	ds_read_b128 v[116:119], v248
	ds_read_b128 v[120:123], v249
	ds_read_b128 v[124:127], v250
	ds_read_b128 v[128:131], v251
	ds_write_b128 v112, v[132:135]
	ds_write_b128 v112, v[136:139] offset:1024
	ds_write_b128 v112, v[140:143] offset:2048
	ds_write_b128 v112, v[144:147] offset:3072
	v_exp_f32_e32 v192, v192
	v_exp_f32_e32 v193, v193
	v_exp_f32_e32 v194, v194
	v_exp_f32_e32 v195, v195
	s_waitcnt lgkmcnt(4)
	v_mfma_f32_32x32x16_bf16 v[32:47], v[116:119], v[48:51], v[32:47]
	v_exp_f32_e32 v196, v196
	v_exp_f32_e32 v197, v197
	v_mfma_f32_32x32x16_bf16 v[32:47], v[120:123], v[52:55], v[32:47]
	v_exp_f32_e32 v198, v198
	v_exp_f32_e32 v199, v199
	v_mfma_f32_32x32x16_bf16 v[32:47], v[124:127], v[56:59], v[32:47]
	v_exp_f32_e32 v200, v200
	v_exp_f32_e32 v201, v201
	v_mfma_f32_32x32x16_bf16 v[32:47], v[128:131], v[60:63], v[32:47]
	v_exp_f32_e32 v202, v202
	v_exp_f32_e32 v203, v203
	v_cvt_pk_bf16_f32 v64, v188, v189
	v_cvt_pk_bf16_f32 v65, v190, v191
	v_cvt_pk_bf16_f32 v66, v192, v193
	v_cvt_pk_bf16_f32 v67, v194, v195
	v_cvt_pk_bf16_f32 v68, v196, v197
	v_cvt_pk_bf16_f32 v69, v198, v199
	v_cvt_pk_bf16_f32 v70, v200, v201
	v_cvt_pk_bf16_f32 v71, v202, v203
	v_pk_add_f32 v[232:233], v[232:233], v[188:189]
	v_pk_add_f32 v[232:233], v[232:233], v[190:191]
	v_pk_add_f32 v[232:233], v[232:233], v[192:193]
	v_pk_add_f32 v[232:233], v[232:233], v[194:195]
	v_pk_add_f32 v[232:233], v[232:233], v[196:197]
	v_pk_add_f32 v[232:233], v[232:233], v[198:199]
	v_pk_add_f32 v[232:233], v[232:233], v[200:201]
	v_pk_add_f32 v[232:233], v[232:233], v[202:203]
	v_mfma_f32_32x32x16_bf16 v[0:15], v[64:67], v[72:75], v[0:15]
	v_mfma_f32_32x32x16_bf16 v[16:31], v[64:67], v[76:79], v[16:31]
	v_mfma_f32_32x32x16_bf16 v[0:15], v[68:71], v[220:223], v[0:15]
	v_mfma_f32_32x32x16_bf16 v[16:31], v[68:71], v[224:227], v[16:31]
	ds_read_b64_tr_b16 v[72:73], v231
	ds_read_b64_tr_b16 v[74:75], v231 offset:512
	ds_read_b64_tr_b16 v[76:77], v231 offset:2048
	ds_read_b64_tr_b16 v[78:79], v231 offset:2560
	ds_read_b64_tr_b16 v[220:221], v231 offset:1024
	ds_read_b64_tr_b16 v[222:223], v231 offset:1536
	ds_read_b64_tr_b16 v[224:225], v231 offset:3072
	ds_read_b64_tr_b16 v[226:227], v231 offset:3584
	s_waitcnt lgkmcnt(0)
	v_exp_f32_e32 v32, v32
	v_exp_f32_e32 v33, v33
	v_exp_f32_e32 v34, v34
	v_exp_f32_e32 v35, v35
	v_exp_f32_e32 v36, v36
	v_exp_f32_e32 v37, v37
	v_exp_f32_e32 v38, v38
	v_exp_f32_e32 v39, v39
	v_exp_f32_e32 v40, v40
	v_exp_f32_e32 v41, v41
	v_exp_f32_e32 v42, v42
	v_exp_f32_e32 v43, v43
	v_exp_f32_e32 v44, v44
	v_exp_f32_e32 v45, v45
	v_exp_f32_e32 v46, v46
	v_exp_f32_e32 v47, v47
	v_cvt_pk_bf16_f32 v64, v32, v33
	v_cvt_pk_bf16_f32 v65, v34, v35
	v_cvt_pk_bf16_f32 v66, v36, v37
	v_cvt_pk_bf16_f32 v67, v38, v39
	v_cvt_pk_bf16_f32 v68, v40, v41
	v_cvt_pk_bf16_f32 v69, v42, v43
	v_cvt_pk_bf16_f32 v70, v44, v45
	v_cvt_pk_bf16_f32 v71, v46, v47
	v_pk_add_f32 v[232:233], v[232:233], v[32:33]
	v_pk_add_f32 v[232:233], v[232:233], v[34:35]
	v_pk_add_f32 v[232:233], v[232:233], v[36:37]
	v_pk_add_f32 v[232:233], v[232:233], v[38:39]
	v_pk_add_f32 v[232:233], v[232:233], v[40:41]
	v_pk_add_f32 v[232:233], v[232:233], v[42:43]
	v_pk_add_f32 v[232:233], v[232:233], v[44:45]
	v_pk_add_f32 v[232:233], v[232:233], v[46:47]
	v_mfma_f32_32x32x16_bf16 v[0:15], v[64:67], v[72:75], v[0:15]
	v_mfma_f32_32x32x16_bf16 v[16:31], v[64:67], v[76:79], v[16:31]
	v_mfma_f32_32x32x16_bf16 v[0:15], v[68:71], v[220:223], v[0:15]
	v_mfma_f32_32x32x16_bf16 v[16:31], v[68:71], v[224:227], v[16:31]
	v_add_f32_e32 v113, v232, v233
	v_or_b32_e32 v114, 1, v107
	v_or_b32_e32 v97, 2, v107
	v_or_b32_e32 v96, 3, v107
	v_or_b32_e32 v95, 8, v107
	v_or_b32_e32 v94, 9, v107
	v_or_b32_e32 v93, 10, v107
	v_or_b32_e32 v92, 11, v107
	v_or_b32_e32 v91, 16, v107
	v_or_b32_e32 v90, 17, v107
	v_or_b32_e32 v89, 18, v107
	v_or_b32_e32 v88, 19, v107
	v_or_b32_e32 v87, 24, v107
	v_or_b32_e32 v86, 25, v107
	v_or_b32_e32 v85, 26, v107
	v_or_b32_e32 v84, 27, v107
	s_setprio 0
	s_nop 11
	s_branch .LBB0_1265

; #define LAS __attribute__((address_space(3)))
; #define GAS __attribute__((address_space(1)))
; __device__ __forceinline__ void dil_unit(LAS unsigned char* lds, bf16_t* proj, int seq, int hd, int T0, int rho) {
;     ...
;     LAS unsigned char* wbuf = lds + wid * 4096;
;     const LAS unsigned char* vp = wbuf + ((lane >> 4) & 1) * 32 + (lane & 3) * 8 + (4 * hi + ((lane & 15) >> 2)) * 64;
;     const int P0 = T0 + rho;
;     bf16x8 qr[4];
; #pragma unroll
;     for (int ks = 0; ks < 4; ++ks) qr[ks] = *(const GAS bf16x8*)(base + (size_t)(P0 + 16 * r32) * NIN + PC_LQ + hd * 64 + 16 * ks + 8 * hi);
;     f32x16 o0 = {}, o1 = {}; float l = 0.f;
;     const bool bound = (T0 < 1024) || (T0 >= 15360);
.Ldb1_noprio:
	s_movk_i32 s100, 0x1800
	s_add_i32 s101, s8, 0x15c00
	s_lshl_b32 s90, s54, 1
	s_add_u32 s82, s52, s90
	s_addc_u32 s83, s53, 0
	s_add_u32 s82, s82, 0x1200
	s_addc_u32 s83, s83, 0
	s_sub_i32 s90, s67, 64
	s_mul_i32 s90, s90, 0x1800
	s_add_u32 s84, s82, s90
	s_addc_u32 s85, s83, 0
	s_sub_i32 s90, s67, 256
	s_mul_i32 s90, s90, 0x1800
	s_add_u32 s86, s82, s90
	s_addc_u32 s87, s83, 0
	s_sub_i32 s90, s67, 1024
	s_mul_i32 s90, s90, 0x1800
	s_add_u32 s88, s82, s90
	s_addc_u32 s89, s83, 0
	v_lshlrev_b32_e32 v153, 1, v98
	v_mad_u32_u24 v80, v105, s100, v82
	v_mad_u32_u24 v100, v110, s100, v153
	v_add_u32_e32 v149, 0x18000, v100
	v_lshlrev_b32_e32 v83, 2, v105
	v_mad_u32_u24 v83, v83, s100, v82
	v_lshlrev_b32_e32 v101, 2, v110
	v_mad_u32_u24 v101, v101, s100, v153
	v_add_u32_e32 v150, 0x60000, v101
	v_lshlrev_b32_e32 v99, 4, v105
	v_mad_u32_u24 v99, v99, s100, v82
	v_lshlrev_b32_e32 v148, 4, v110
	v_mad_u32_u24 v148, v148, s100, v153
	v_add_u32_e32 v151, 0x180000, v148
	v_lshrrev_b32_e32 v249, 3, v103
	v_and_b32_e32 v250, 7, v103
	v_lshlrev_b32_e32 v250, 4, v250
	v_add_u32_e32 v235, 0, v249
	v_add_u32_e32 v236, 8, v249
	v_add_u32_e32 v237, 16, v249
	v_add_u32_e32 v238, 24, v249
	v_add_u32_e32 v239, 0, v249
	v_lshlrev_b32_e32 v239, 2, v239
	v_add_u32_e32 v240, 8, v249
	v_lshlrev_b32_e32 v240, 2, v240
	v_add_u32_e32 v241, 16, v249
	v_lshlrev_b32_e32 v241, 2, v241
	v_add_u32_e32 v242, 24, v249
	v_lshlrev_b32_e32 v242, 2, v242
	v_add_u32_e32 v243, 0, v249
	v_lshlrev_b32_e32 v243, 4, v243
	v_add_u32_e32 v244, 8, v249
	v_lshlrev_b32_e32 v244, 4, v244
	v_add_u32_e32 v245, 16, v249
	v_lshlrev_b32_e32 v245, 4, v245
	v_add_u32_e32 v246, 24, v249
	v_lshlrev_b32_e32 v246, 4, v246
	v_mov_b32_e32 v252, v250
	v_mov_b32_e32 v100, v110
	v_add_u32_e32 v149, 16, v100
	v_lshlrev_b32_e32 v101, 2, v110
	v_add_u32_e32 v150, 64, v101
	v_lshlrev_b32_e32 v148, 4, v110
	v_add_u32_e32 v151, 256, v148
	s_mov_b32 s98, 0x4000
	s_mov_b32 s99, 0x3fff
	v_and_b32_e32 v247, 7, v249
	v_lshlrev_b32_e32 v247, 4, v247
	v_xor_b32_e32 v247, v247, v112
	v_and_b32_e32 v153, 7, v105
	v_or_b32_e32 v248, 0, v106
	v_xor_b32_e32 v248, v248, v153
	v_lshlrev_b32_e32 v248, 4, v248
	v_lshl_add_u32 v248, v105, 7, v248
	v_add_u32_e32 v248, s69, v248
	v_or_b32_e32 v249, 2, v106
	v_xor_b32_e32 v249, v249, v153
	v_lshlrev_b32_e32 v249, 4, v249
	v_lshl_add_u32 v249, v105, 7, v249
	v_add_u32_e32 v249, s69, v249
	v_or_b32_e32 v250, 4, v106
	v_xor_b32_e32 v250, v250, v153
	v_lshlrev_b32_e32 v250, 4, v250
	v_lshl_add_u32 v250, v105, 7, v250
	v_add_u32_e32 v250, s69, v250
	v_or_b32_e32 v251, 6, v106
	v_xor_b32_e32 v251, v251, v153
	v_lshlrev_b32_e32 v251, 4, v251
	v_lshl_add_u32 v251, v105, 7, v251
	v_add_u32_e32 v251, s69, v251
	v_lshlrev_b32_e32 v153, 1, v98
	v_mul_u32_u24_e32 v228, 17, v105
	v_sub_u32_e32 v228, v107, v228
	s_mul_i32 s90, s54, 153
	s_lshr_b32 s90, s90, 1
	s_add_i32 s90, s90, 34876
	v_lshl_add_u32 v228, v228, 2, s90
	v_lshlrev_b32_e32 v229, 2, v105
	v_sub_u32_e32 v229, v107, v229
	s_add_i32 s90, s101, 5104
	v_lshl_add_u32 v229, v229, 2, s90
	v_sub_u32_e32 v230, v107, v105
	s_add_i32 s90, s101, 6364
	v_lshl_add_u32 v230, v230, 2, s90
	v_add_u32_e32 v231, v109, v108
	v_mov_b64_e32 v[232:233], 0
	v_mov_b64_e32 v[0:1], 0
	v_mov_b64_e32 v[2:3], 0
	v_mov_b64_e32 v[4:5], 0
	v_mov_b64_e32 v[6:7], 0
	v_mov_b64_e32 v[8:9], 0
	v_mov_b64_e32 v[10:11], 0
	v_mov_b64_e32 v[12:13], 0
	v_mov_b64_e32 v[14:15], 0
	v_mov_b64_e32 v[16:17], 0
	v_mov_b64_e32 v[18:19], 0
	v_mov_b64_e32 v[20:21], 0
	v_mov_b64_e32 v[22:23], 0
	v_mov_b64_e32 v[24:25], 0
	v_mov_b64_e32 v[26:27], 0
	v_mov_b64_e32 v[28:29], 0
	v_mov_b64_e32 v[30:31], 0
	s_add_i32 s90, s67, -64
	v_add_u32_e32 v80, s90, v235
	v_add_u32_e32 v83, s90, v236
	v_add_u32_e32 v99, s90, v237
	v_add_u32_e32 v253, s90, v238
	v_add_u32_e32 v254, s90, v100
	v_add_u32_e32 v255, s90, v149
	v_med3_i32 v80, v80, 0, s99
	v_med3_i32 v83, v83, 0, s99
	v_med3_i32 v99, v99, 0, s99
	v_med3_i32 v253, v253, 0, s99
	v_med3_i32 v254, v254, 0, s99
	v_med3_i32 v255, v255, 0, s99
	v_mad_u32_u24 v80, v80, s100, v252
	v_mad_u32_u24 v83, v83, s100, v252
	v_mad_u32_u24 v99, v99, s100, v252
	v_mad_u32_u24 v253, v253, s100, v252
	v_mad_u32_u24 v254, v254, s100, v153
	v_mad_u32_u24 v255, v255, s100, v153
	global_load_dwordx4 v[116:119], v80, s[82:83]
	global_load_dwordx4 v[120:123], v83, s[82:83]
	global_load_dwordx4 v[124:127], v99, s[82:83]
	global_load_dwordx4 v[128:131], v253, s[82:83]
	global_load_dwordx4 v[132:135], v254, s[82:83] offset:768
	global_load_dwordx4 v[136:139], v255, s[82:83] offset:768
	global_load_dwordx4 v[140:143], v254, s[82:83] offset:832
	global_load_dwordx4 v[144:147], v255, s[82:83] offset:832
	s_add_i32 s90, s67, -32
	v_add_u32_e32 v80, s90, v235
	v_add_u32_e32 v83, s90, v236
	v_add_u32_e32 v99, s90, v237
	v_add_u32_e32 v253, s90, v238
	v_add_u32_e32 v254, s90, v100
	v_add_u32_e32 v255, s90, v149
	v_med3_i32 v80, v80, 0, s99
	v_med3_i32 v83, v83, 0, s99
	v_med3_i32 v99, v99, 0, s99
	v_med3_i32 v253, v253, 0, s99
	v_med3_i32 v254, v254, 0, s99
	v_med3_i32 v255, v255, 0, s99
	v_mad_u32_u24 v80, v80, s100, v252
	v_mad_u32_u24 v83, v83, s100, v252
	v_mad_u32_u24 v99, v99, s100, v252
	v_mad_u32_u24 v253, v253, s100, v252
	v_mad_u32_u24 v254, v254, s100, v153
	v_mad_u32_u24 v255, v255, s100, v153
	global_load_dwordx4 v[156:159], v80, s[82:83]
	global_load_dwordx4 v[160:163], v83, s[82:83]
	global_load_dwordx4 v[164:167], v99, s[82:83]
	global_load_dwordx4 v[168:171], v253, s[82:83]
	global_load_dwordx4 v[172:175], v254, s[82:83] offset:768
	global_load_dwordx4 v[176:179], v255, s[82:83] offset:768
	global_load_dwordx4 v[180:183], v254, s[82:83] offset:832
	global_load_dwordx4 v[184:187], v255, s[82:83] offset:832
	v_mov_b32_e32 v115, v228
	ds_read2_b32 v[32:33], v115 offset0:0 offset1:1
	ds_read2_b32 v[34:35], v115 offset0:2 offset1:3
	ds_read2_b32 v[36:37], v115 offset0:8 offset1:9
	ds_read2_b32 v[38:39], v115 offset0:10 offset1:11
	ds_read2_b32 v[40:41], v115 offset0:17 offset1:18
	ds_read2_b32 v[42:43], v115 offset0:19 offset1:20
	ds_read2_b32 v[44:45], v115 offset0:25 offset1:26
	ds_read2_b32 v[46:47], v115 offset0:27 offset1:28
	s_waitcnt vmcnt(8)
	ds_write_b128 v247, v[116:119]
	ds_write_b128 v247, v[120:123] offset:1024
	ds_write_b128 v247, v[124:127] offset:2048
	ds_write_b128 v247, v[128:131] offset:3072
	ds_read_b128 v[116:119], v248
	ds_read_b128 v[120:123], v249
	ds_read_b128 v[124:127], v250
	ds_read_b128 v[128:131], v251
	ds_write_b128 v112, v[132:135]
	ds_write_b128 v112, v[136:139] offset:1024
	ds_write_b128 v112, v[140:143] offset:2048
	ds_write_b128 v112, v[144:147] offset:3072
	s_waitcnt lgkmcnt(4)
	v_mfma_f32_32x32x16_bf16 v[32:47], v[116:119], v[48:51], v[32:47]
	v_mfma_f32_32x32x16_bf16 v[32:47], v[120:123], v[52:55], v[32:47]
	v_mfma_f32_32x32x16_bf16 v[32:47], v[124:127], v[56:59], v[32:47]
	v_mfma_f32_32x32x16_bf16 v[32:47], v[128:131], v[60:63], v[32:47]
	ds_read2_b32 v[188:189], v115 offset0:34 offset1:35
	ds_read2_b32 v[190:191], v115 offset0:36 offset1:37
	ds_read2_b32 v[192:193], v115 offset0:42 offset1:43
	ds_read2_b32 v[194:195], v115 offset0:44 offset1:45
	ds_read2_b32 v[196:197], v115 offset0:51 offset1:52
	ds_read2_b32 v[198:199], v115 offset0:53 offset1:54
	ds_read2_b32 v[200:201], v115 offset0:59 offset1:60
	ds_read2_b32 v[202:203], v115 offset0:61 offset1:62
	s_add_i32 s90, s67, 0
	v_add_u32_e32 v80, s90, v235
	v_add_u32_e32 v83, s90, v236
	v_add_u32_e32 v99, s90, v237
	v_add_u32_e32 v253, s90, v238
	v_add_u32_e32 v254, s90, v100
	v_add_u32_e32 v255, s90, v149
	v_med3_i32 v80, v80, 0, s99
	v_med3_i32 v83, v83, 0, s99
	v_med3_i32 v99, v99, 0, s99
	v_med3_i32 v253, v253, 0, s99
	v_med3_i32 v254, v254, 0, s99
	v_med3_i32 v255, v255, 0, s99
	v_mad_u32_u24 v80, v80, s100, v252
	v_mad_u32_u24 v83, v83, s100, v252
	v_mad_u32_u24 v99, v99, s100, v252
	v_mad_u32_u24 v253, v253, s100, v252
	v_mad_u32_u24 v254, v254, s100, v153
	v_mad_u32_u24 v255, v255, s100, v153
	global_load_dwordx4 v[116:119], v80, s[82:83]
	global_load_dwordx4 v[120:123], v83, s[82:83]
	global_load_dwordx4 v[124:127], v99, s[82:83]
	global_load_dwordx4 v[128:131], v253, s[82:83]
	global_load_dwordx4 v[132:135], v254, s[82:83] offset:768
	global_load_dwordx4 v[136:139], v255, s[82:83] offset:768
	global_load_dwordx4 v[140:143], v254, s[82:83] offset:832
	global_load_dwordx4 v[144:147], v255, s[82:83] offset:832
	ds_read_b64_tr_b16 v[72:73], v231
	ds_read_b64_tr_b16 v[74:75], v231 offset:512
	ds_read_b64_tr_b16 v[76:77], v231 offset:2048
	ds_read_b64_tr_b16 v[78:79], v231 offset:2560
	ds_read_b64_tr_b16 v[220:221], v231 offset:1024
	ds_read_b64_tr_b16 v[222:223], v231 offset:1536
	ds_read_b64_tr_b16 v[224:225], v231 offset:3072
	ds_read_b64_tr_b16 v[226:227], v231 offset:3584
	v_exp_f32_e32 v32, v32
	v_exp_f32_e32 v33, v33
	v_exp_f32_e32 v34, v34
	v_exp_f32_e32 v35, v35
	s_waitcnt vmcnt(8)
	ds_write_b128 v247, v[156:159]
	ds_write_b128 v247, v[160:163] offset:1024
	ds_write_b128 v247, v[164:167] offset:2048
	ds_write_b128 v247, v[168:171] offset:3072
	ds_read_b128 v[156:159], v248
	ds_read_b128 v[160:163], v249
	ds_read_b128 v[164:167], v250
	ds_read_b128 v[168:171], v251
	ds_write_b128 v112, v[172:175]
	ds_write_b128 v112, v[176:179] offset:1024
	ds_write_b128 v112, v[180:183] offset:2048
	ds_write_b128 v112, v[184:187] offset:3072
	v_exp_f32_e32 v36, v36
	v_exp_f32_e32 v37, v37
	v_exp_f32_e32 v38, v38
	v_exp_f32_e32 v39, v39
	s_waitcnt lgkmcnt(4)
	v_mfma_f32_32x32x16_bf16 v[188:203], v[156:159], v[48:51], v[188:203]
	v_exp_f32_e32 v40, v40
	v_exp_f32_e32 v41, v41
	v_mfma_f32_32x32x16_bf16 v[188:203], v[160:163], v[52:55], v[188:203]
	v_exp_f32_e32 v42, v42
	v_exp_f32_e32 v43, v43
	v_mfma_f32_32x32x16_bf16 v[188:203], v[164:167], v[56:59], v[188:203]
	v_exp_f32_e32 v44, v44
	v_exp_f32_e32 v45, v45
	v_mfma_f32_32x32x16_bf16 v[188:203], v[168:171], v[60:63], v[188:203]
	v_exp_f32_e32 v46, v46
	v_exp_f32_e32 v47, v47
	s_add_i32 s90, s67, -64
	v_add_u32_e32 v84, s90, v107
	v_add_u32_e32 v85, 0, v84
	v_add_u32_e32 v86, 1, v84
	v_add_u32_e32 v87, 2, v84
	v_add_u32_e32 v88, 3, v84
	v_cmp_gt_u32_e64 s[30:31], s98, v85
	v_cmp_gt_u32_e64 s[36:37], s98, v86
	v_cmp_gt_u32_e64 s[78:79], s98, v87
	v_cmp_gt_u32_e64 s[50:51], s98, v88
	v_cndmask_b32_e64 v32, 0, v32, s[30:31]
	v_add_u32_e32 v85, 8, v84
	v_cmp_gt_u32_e64 s[30:31], s98, v85
	v_cndmask_b32_e64 v33, 0, v33, s[36:37]
	v_add_u32_e32 v86, 9, v84
	v_cmp_gt_u32_e64 s[36:37], s98, v86
	v_cndmask_b32_e64 v34, 0, v34, s[78:79]
	v_add_u32_e32 v87, 10, v84
	v_cmp_gt_u32_e64 s[78:79], s98, v87
	v_cndmask_b32_e64 v35, 0, v35, s[50:51]
	v_add_u32_e32 v88, 11, v84
	v_cmp_gt_u32_e64 s[50:51], s98, v88
	v_cndmask_b32_e64 v36, 0, v36, s[30:31]
	v_add_u32_e32 v85, 16, v84
	v_cmp_gt_u32_e64 s[30:31], s98, v85
	v_cndmask_b32_e64 v37, 0, v37, s[36:37]
	v_add_u32_e32 v86, 17, v84
	v_cmp_gt_u32_e64 s[36:37], s98, v86
	v_cndmask_b32_e64 v38, 0, v38, s[78:79]
	v_add_u32_e32 v87, 18, v84
	v_cmp_gt_u32_e64 s[78:79], s98, v87
	v_cndmask_b32_e64 v39, 0, v39, s[50:51]
	v_add_u32_e32 v88, 19, v84
	v_cmp_gt_u32_e64 s[50:51], s98, v88
	v_cndmask_b32_e64 v40, 0, v40, s[30:31]
	v_add_u32_e32 v85, 24, v84
	v_cmp_gt_u32_e64 s[30:31], s98, v85
	v_cndmask_b32_e64 v41, 0, v41, s[36:37]
	v_add_u32_e32 v86, 25, v84
	v_cmp_gt_u32_e64 s[36:37], s98, v86
	v_cndmask_b32_e64 v42, 0, v42, s[78:79]
	v_add_u32_e32 v87, 26, v84
	v_cmp_gt_u32_e64 s[78:79], s98, v87
	v_cndmask_b32_e64 v43, 0, v43, s[50:51]
	v_add_u32_e32 v88, 27, v84
	v_cmp_gt_u32_e64 s[50:51], s98, v88
	v_nop
	v_cndmask_b32_e64 v44, 0, v44, s[30:31]
	v_cndmask_b32_e64 v45, 0, v45, s[36:37]
	v_cndmask_b32_e64 v46, 0, v46, s[78:79]
	v_cndmask_b32_e64 v47, 0, v47, s[50:51]
	v_cvt_pk_bf16_f32 v64, v32, v33
	v_cvt_pk_bf16_f32 v65, v34, v35
	v_cvt_pk_bf16_f32 v66, v36, v37
	v_cvt_pk_bf16_f32 v67, v38, v39
	v_cvt_pk_bf16_f32 v68, v40, v41
	v_cvt_pk_bf16_f32 v69, v42, v43
	v_cvt_pk_bf16_f32 v70, v44, v45
	v_cvt_pk_bf16_f32 v71, v46, v47
	v_pk_add_f32 v[232:233], v[232:233], v[32:33]
	v_pk_add_f32 v[232:233], v[232:233], v[34:35]
	v_pk_add_f32 v[232:233], v[232:233], v[36:37]
	v_pk_add_f32 v[232:233], v[232:233], v[38:39]
	v_pk_add_f32 v[232:233], v[232:233], v[40:41]
	v_pk_add_f32 v[232:233], v[232:233], v[42:43]
	v_pk_add_f32 v[232:233], v[232:233], v[44:45]
	v_pk_add_f32 v[232:233], v[232:233], v[46:47]
	ds_read2_b32 v[32:33], v115 offset0:68 offset1:69
	ds_read2_b32 v[34:35], v115 offset0:70 offset1:71
	ds_read2_b32 v[36:37], v115 offset0:76 offset1:77
	ds_read2_b32 v[38:39], v115 offset0:78 offset1:79
	ds_read2_b32 v[40:41], v115 offset0:85 offset1:86
	ds_read2_b32 v[42:43], v115 offset0:87 offset1:88
	ds_read2_b32 v[44:45], v115 offset0:93 offset1:94
	ds_read2_b32 v[46:47], v115 offset0:95 offset1:96
	v_mfma_f32_32x32x16_bf16 v[0:15], v[64:67], v[72:75], v[0:15]
	v_mfma_f32_32x32x16_bf16 v[16:31], v[64:67], v[76:79], v[16:31]
	v_mfma_f32_32x32x16_bf16 v[0:15], v[68:71], v[220:223], v[0:15]
	v_mfma_f32_32x32x16_bf16 v[16:31], v[68:71], v[224:227], v[16:31]
	s_add_i32 s90, s67, 32
	v_add_u32_e32 v80, s90, v235
	v_add_u32_e32 v83, s90, v236
	v_add_u32_e32 v99, s90, v237
	v_add_u32_e32 v253, s90, v238
	v_add_u32_e32 v254, s90, v100
	v_add_u32_e32 v255, s90, v149
	v_med3_i32 v80, v80, 0, s99
	v_med3_i32 v83, v83, 0, s99
	v_med3_i32 v99, v99, 0, s99
	v_med3_i32 v253, v253, 0, s99
	v_med3_i32 v254, v254, 0, s99
	v_med3_i32 v255, v255, 0, s99
	v_mad_u32_u24 v80, v80, s100, v252
	v_mad_u32_u24 v83, v83, s100, v252
	v_mad_u32_u24 v99, v99, s100, v252
	v_mad_u32_u24 v253, v253, s100, v252
	v_mad_u32_u24 v254, v254, s100, v153
	v_mad_u32_u24 v255, v255, s100, v153
	global_load_dwordx4 v[156:159], v80, s[82:83]
	global_load_dwordx4 v[160:163], v83, s[82:83]
	global_load_dwordx4 v[164:167], v99, s[82:83]
	global_load_dwordx4 v[168:171], v253, s[82:83]
	global_load_dwordx4 v[172:175], v254, s[82:83] offset:768
	global_load_dwordx4 v[176:179], v255, s[82:83] offset:768
	global_load_dwordx4 v[180:183], v254, s[82:83] offset:832
	global_load_dwordx4 v[184:187], v255, s[82:83] offset:832
	ds_read_b64_tr_b16 v[72:73], v231
	ds_read_b64_tr_b16 v[74:75], v231 offset:512
	ds_read_b64_tr_b16 v[76:77], v231 offset:2048
	ds_read_b64_tr_b16 v[78:79], v231 offset:2560
	ds_read_b64_tr_b16 v[220:221], v231 offset:1024
	ds_read_b64_tr_b16 v[222:223], v231 offset:1536
	ds_read_b64_tr_b16 v[224:225], v231 offset:3072
	ds_read_b64_tr_b16 v[226:227], v231 offset:3584
	v_exp_f32_e32 v188, v188
	v_exp_f32_e32 v189, v189
	v_exp_f32_e32 v190, v190
	v_exp_f32_e32 v191, v191
	s_waitcnt vmcnt(8)
	ds_write_b128 v247, v[116:119]
	ds_write_b128 v247, v[120:123] offset:1024
	ds_write_b128 v247, v[124:127] offset:2048
	ds_write_b128 v247, v[128:131] offset:3072
	ds_read_b128 v[116:119], v248
	ds_read_b128 v[120:123], v249
	ds_read_b128 v[124:127], v250
	ds_read_b128 v[128:131], v251
	ds_write_b128 v112, v[132:135]
	ds_write_b128 v112, v[136:139] offset:1024
	ds_write_b128 v112, v[140:143] offset:2048
	ds_write_b128 v112, v[144:147] offset:3072
	v_exp_f32_e32 v192, v192
	v_exp_f32_e32 v193, v193
	v_exp_f32_e32 v194, v194
	v_exp_f32_e32 v195, v195
	s_waitcnt lgkmcnt(4)
	v_mfma_f32_32x32x16_bf16 v[32:47], v[116:119], v[48:51], v[32:47]
	v_exp_f32_e32 v196, v196
	v_exp_f32_e32 v197, v197
	v_mfma_f32_32x32x16_bf16 v[32:47], v[120:123], v[52:55], v[32:47]
	v_exp_f32_e32 v198, v198
	v_exp_f32_e32 v199, v199
	v_mfma_f32_32x32x16_bf16 v[32:47], v[124:127], v[56:59], v[32:47]
	v_exp_f32_e32 v200, v200
	v_exp_f32_e32 v201, v201
	v_mfma_f32_32x32x16_bf16 v[32:47], v[128:131], v[60:63], v[32:47]
	v_exp_f32_e32 v202, v202
	v_exp_f32_e32 v203, v203
	s_add_i32 s90, s67, -32
	v_add_u32_e32 v84, s90, v107
	v_add_u32_e32 v85, 0, v84
	v_add_u32_e32 v86, 1, v84
	v_add_u32_e32 v87, 2, v84
	v_add_u32_e32 v88, 3, v84
	v_cmp_gt_u32_e64 s[30:31], s98, v85
	v_cmp_gt_u32_e64 s[36:37], s98, v86
	v_cmp_gt_u32_e64 s[78:79], s98, v87
	v_cmp_gt_u32_e64 s[50:51], s98, v88
	v_cndmask_b32_e64 v188, 0, v188, s[30:31]
	v_add_u32_e32 v85, 8, v84
	v_cmp_gt_u32_e64 s[30:31], s98, v85
	v_cndmask_b32_e64 v189, 0, v189, s[36:37]
	v_add_u32_e32 v86, 9, v84
	v_cmp_gt_u32_e64 s[36:37], s98, v86
	v_cndmask_b32_e64 v190, 0, v190, s[78:79]
	v_add_u32_e32 v87, 10, v84
	v_cmp_gt_u32_e64 s[78:79], s98, v87
	v_cndmask_b32_e64 v191, 0, v191, s[50:51]
	v_add_u32_e32 v88, 11, v84
	v_cmp_gt_u32_e64 s[50:51], s98, v88
	v_cndmask_b32_e64 v192, 0, v192, s[30:31]
	v_add_u32_e32 v85, 16, v84
	v_cmp_gt_u32_e64 s[30:31], s98, v85
	v_cndmask_b32_e64 v193, 0, v193, s[36:37]
	v_add_u32_e32 v86, 17, v84
	v_cmp_gt_u32_e64 s[36:37], s98, v86
	v_cndmask_b32_e64 v194, 0, v194, s[78:79]
	v_add_u32_e32 v87, 18, v84
	v_cmp_gt_u32_e64 s[78:79], s98, v87
	v_cndmask_b32_e64 v195, 0, v195, s[50:51]
	v_add_u32_e32 v88, 19, v84
	v_cmp_gt_u32_e64 s[50:51], s98, v88
	v_cndmask_b32_e64 v196, 0, v196, s[30:31]
	v_add_u32_e32 v85, 24, v84
	v_cmp_gt_u32_e64 s[30:31], s98, v85
	v_cndmask_b32_e64 v197, 0, v197, s[36:37]
	v_add_u32_e32 v86, 25, v84
	v_cmp_gt_u32_e64 s[36:37], s98, v86
	v_cndmask_b32_e64 v198, 0, v198, s[78:79]
	v_add_u32_e32 v87, 26, v84
	v_cmp_gt_u32_e64 s[78:79], s98, v87
	v_cndmask_b32_e64 v199, 0, v199, s[50:51]
	v_add_u32_e32 v88, 27, v84
	v_cmp_gt_u32_e64 s[50:51], s98, v88
	v_nop
	v_cndmask_b32_e64 v200, 0, v200, s[30:31]
	v_cndmask_b32_e64 v201, 0, v201, s[36:37]
	v_cndmask_b32_e64 v202, 0, v202, s[78:79]
	v_cndmask_b32_e64 v203, 0, v203, s[50:51]
	v_cvt_pk_bf16_f32 v64, v188, v189
	v_cvt_pk_bf16_f32 v65, v190, v191
	v_cvt_pk_bf16_f32 v66, v192, v193
	v_cvt_pk_bf16_f32 v67, v194, v195
	v_cvt_pk_bf16_f32 v68, v196, v197
	v_cvt_pk_bf16_f32 v69, v198, v199
	v_cvt_pk_bf16_f32 v70, v200, v201
	v_cvt_pk_bf16_f32 v71, v202, v203
	v_pk_add_f32 v[232:233], v[232:233], v[188:189]
	v_pk_add_f32 v[232:233], v[232:233], v[190:191]
	v_pk_add_f32 v[232:233], v[232:233], v[192:193]
	v_pk_add_f32 v[232:233], v[232:233], v[194:195]
	v_pk_add_f32 v[232:233], v[232:233], v[196:197]
	v_pk_add_f32 v[232:233], v[232:233], v[198:199]
	v_pk_add_f32 v[232:233], v[232:233], v[200:201]
	v_pk_add_f32 v[232:233], v[232:233], v[202:203]
	ds_read2_b32 v[188:189], v115 offset0:102 offset1:103
	ds_read2_b32 v[190:191], v115 offset0:104 offset1:105
	ds_read2_b32 v[192:193], v115 offset0:110 offset1:111
	ds_read2_b32 v[194:195], v115 offset0:112 offset1:113
	ds_read2_b32 v[196:197], v115 offset0:119 offset1:120
	ds_read2_b32 v[198:199], v115 offset0:121 offset1:122
	ds_read2_b32 v[200:201], v115 offset0:127 offset1:128
	ds_read2_b32 v[202:203], v115 offset0:129 offset1:130
	v_mfma_f32_32x32x16_bf16 v[0:15], v[64:67], v[72:75], v[0:15]
	v_mfma_f32_32x32x16_bf16 v[16:31], v[64:67], v[76:79], v[16:31]
	v_mfma_f32_32x32x16_bf16 v[0:15], v[68:71], v[220:223], v[0:15]
	v_mfma_f32_32x32x16_bf16 v[16:31], v[68:71], v[224:227], v[16:31]
	s_add_i32 s90, s67, 64
	v_add_u32_e32 v80, s90, v235
	v_add_u32_e32 v83, s90, v236
	v_add_u32_e32 v99, s90, v237
	v_add_u32_e32 v253, s90, v238
	v_add_u32_e32 v254, s90, v100
	v_add_u32_e32 v255, s90, v149
	v_med3_i32 v80, v80, 0, s99
	v_med3_i32 v83, v83, 0, s99
	v_med3_i32 v99, v99, 0, s99
	v_med3_i32 v253, v253, 0, s99
	v_med3_i32 v254, v254, 0, s99
	v_med3_i32 v255, v255, 0, s99
	v_mad_u32_u24 v80, v80, s100, v252
	v_mad_u32_u24 v83, v83, s100, v252
	v_mad_u32_u24 v99, v99, s100, v252
	v_mad_u32_u24 v253, v253, s100, v252
	v_mad_u32_u24 v254, v254, s100, v153
	v_mad_u32_u24 v255, v255, s100, v153
	global_load_dwordx4 v[116:119], v80, s[82:83]
	global_load_dwordx4 v[120:123], v83, s[82:83]
	global_load_dwordx4 v[124:127], v99, s[82:83]
	global_load_dwordx4 v[128:131], v253, s[82:83]
	global_load_dwordx4 v[132:135], v254, s[82:83] offset:768
	global_load_dwordx4 v[136:139], v255, s[82:83] offset:768
	global_load_dwordx4 v[140:143], v254, s[82:83] offset:832
	global_load_dwordx4 v[144:147], v255, s[82:83] offset:832
	ds_read_b64_tr_b16 v[72:73], v231
	ds_read_b64_tr_b16 v[74:75], v231 offset:512
	ds_read_b64_tr_b16 v[76:77], v231 offset:2048
	ds_read_b64_tr_b16 v[78:79], v231 offset:2560
	ds_read_b64_tr_b16 v[220:221], v231 offset:1024
	ds_read_b64_tr_b16 v[222:223], v231 offset:1536
	ds_read_b64_tr_b16 v[224:225], v231 offset:3072
	ds_read_b64_tr_b16 v[226:227], v231 offset:3584
	v_exp_f32_e32 v32, v32
	v_exp_f32_e32 v33, v33
	v_exp_f32_e32 v34, v34
	v_exp_f32_e32 v35, v35
	s_waitcnt vmcnt(8)
	ds_write_b128 v247, v[156:159]
	ds_write_b128 v247, v[160:163] offset:1024
	ds_write_b128 v247, v[164:167] offset:2048
	ds_write_b128 v247, v[168:171] offset:3072
	ds_read_b128 v[156:159], v248
	ds_read_b128 v[160:163], v249
	ds_read_b128 v[164:167], v250
	ds_read_b128 v[168:171], v251
	ds_write_b128 v112, v[172:175]
	ds_write_b128 v112, v[176:179] offset:1024
	ds_write_b128 v112, v[180:183] offset:2048
	ds_write_b128 v112, v[184:187] offset:3072
	v_exp_f32_e32 v36, v36
	v_exp_f32_e32 v37, v37
	v_exp_f32_e32 v38, v38
	v_exp_f32_e32 v39, v39
	s_waitcnt lgkmcnt(4)
	v_mfma_f32_32x32x16_bf16 v[188:203], v[156:159], v[48:51], v[188:203]
	v_exp_f32_e32 v40, v40
	v_exp_f32_e32 v41, v41
	v_mfma_f32_32x32x16_bf16 v[188:203], v[160:163], v[52:55], v[188:203]
	v_exp_f32_e32 v42, v42
	v_exp_f32_e32 v43, v43
	v_mfma_f32_32x32x16_bf16 v[188:203], v[164:167], v[56:59], v[188:203]
	v_exp_f32_e32 v44, v44
	v_exp_f32_e32 v45, v45
	v_mfma_f32_32x32x16_bf16 v[188:203], v[168:171], v[60:63], v[188:203]
	v_exp_f32_e32 v46, v46
	v_exp_f32_e32 v47, v47
	s_add_i32 s90, s67, 0
	v_add_u32_e32 v84, s90, v107
	v_add_u32_e32 v85, 0, v84
	v_add_u32_e32 v86, 1, v84
	v_add_u32_e32 v87, 2, v84
	v_add_u32_e32 v88, 3, v84
	v_cmp_gt_u32_e64 s[30:31], s98, v85
	v_cmp_gt_u32_e64 s[36:37], s98, v86
	v_cmp_gt_u32_e64 s[78:79], s98, v87
	v_cmp_gt_u32_e64 s[50:51], s98, v88
	v_cndmask_b32_e64 v32, 0, v32, s[30:31]
	v_add_u32_e32 v85, 8, v84
	v_cmp_gt_u32_e64 s[30:31], s98, v85
	v_cndmask_b32_e64 v33, 0, v33, s[36:37]
	v_add_u32_e32 v86, 9, v84
	v_cmp_gt_u32_e64 s[36:37], s98, v86
	v_cndmask_b32_e64 v34, 0, v34, s[78:79]
	v_add_u32_e32 v87, 10, v84
	v_cmp_gt_u32_e64 s[78:79], s98, v87
	v_cndmask_b32_e64 v35, 0, v35, s[50:51]
	v_add_u32_e32 v88, 11, v84
	v_cmp_gt_u32_e64 s[50:51], s98, v88
	v_cndmask_b32_e64 v36, 0, v36, s[30:31]
	v_add_u32_e32 v85, 16, v84
	v_cmp_gt_u32_e64 s[30:31], s98, v85
	v_cndmask_b32_e64 v37, 0, v37, s[36:37]
	v_add_u32_e32 v86, 17, v84
	v_cmp_gt_u32_e64 s[36:37], s98, v86
	v_cndmask_b32_e64 v38, 0, v38, s[78:79]
	v_add_u32_e32 v87, 18, v84
	v_cmp_gt_u32_e64 s[78:79], s98, v87
	v_cndmask_b32_e64 v39, 0, v39, s[50:51]
	v_add_u32_e32 v88, 19, v84
	v_cmp_gt_u32_e64 s[50:51], s98, v88
	v_cndmask_b32_e64 v40, 0, v40, s[30:31]
	v_add_u32_e32 v85, 24, v84
	v_cmp_gt_u32_e64 s[30:31], s98, v85
	v_cndmask_b32_e64 v41, 0, v41, s[36:37]
	v_add_u32_e32 v86, 25, v84
	v_cmp_gt_u32_e64 s[36:37], s98, v86
	v_cndmask_b32_e64 v42, 0, v42, s[78:79]
	v_add_u32_e32 v87, 26, v84
	v_cmp_gt_u32_e64 s[78:79], s98, v87
	v_cndmask_b32_e64 v43, 0, v43, s[50:51]
	v_add_u32_e32 v88, 27, v84
	v_cmp_gt_u32_e64 s[50:51], s98, v88
	v_nop
	v_cndmask_b32_e64 v44, 0, v44, s[30:31]
	v_cndmask_b32_e64 v45, 0, v45, s[36:37]
	v_cndmask_b32_e64 v46, 0, v46, s[78:79]
	v_cndmask_b32_e64 v47, 0, v47, s[50:51]
	v_cvt_pk_bf16_f32 v64, v32, v33
	v_cvt_pk_bf16_f32 v65, v34, v35
	v_cvt_pk_bf16_f32 v66, v36, v37
	v_cvt_pk_bf16_f32 v67, v38, v39
	v_cvt_pk_bf16_f32 v68, v40, v41
	v_cvt_pk_bf16_f32 v69, v42, v43
	v_cvt_pk_bf16_f32 v70, v44, v45
	v_cvt_pk_bf16_f32 v71, v46, v47
	v_pk_add_f32 v[232:233], v[232:233], v[32:33]
	v_pk_add_f32 v[232:233], v[232:233], v[34:35]
	v_pk_add_f32 v[232:233], v[232:233], v[36:37]
	v_pk_add_f32 v[232:233], v[232:233], v[38:39]
	v_pk_add_f32 v[232:233], v[232:233], v[40:41]
	v_pk_add_f32 v[232:233], v[232:233], v[42:43]
	v_pk_add_f32 v[232:233], v[232:233], v[44:45]
	v_pk_add_f32 v[232:233], v[232:233], v[46:47]
	ds_read2_b32 v[32:33], v115 offset0:136 offset1:137
	ds_read2_b32 v[34:35], v115 offset0:138 offset1:139
	ds_read2_b32 v[36:37], v115 offset0:144 offset1:145
	ds_read2_b32 v[38:39], v115 offset0:146 offset1:147
	ds_read2_b32 v[40:41], v115 offset0:153 offset1:154
	ds_read2_b32 v[42:43], v115 offset0:155 offset1:156
	ds_read2_b32 v[44:45], v115 offset0:161 offset1:162
	ds_read2_b32 v[46:47], v115 offset0:163 offset1:164
	v_mfma_f32_32x32x16_bf16 v[0:15], v[64:67], v[72:75], v[0:15]
	v_mfma_f32_32x32x16_bf16 v[16:31], v[64:67], v[76:79], v[16:31]
	v_mfma_f32_32x32x16_bf16 v[0:15], v[68:71], v[220:223], v[0:15]
	v_mfma_f32_32x32x16_bf16 v[16:31], v[68:71], v[224:227], v[16:31]
	s_add_i32 s90, s67, 96
	v_add_u32_e32 v80, s90, v235
	v_add_u32_e32 v83, s90, v236
	v_add_u32_e32 v99, s90, v237
	v_add_u32_e32 v253, s90, v238
	v_add_u32_e32 v254, s90, v100
	v_add_u32_e32 v255, s90, v149
	v_med3_i32 v80, v80, 0, s99
	v_med3_i32 v83, v83, 0, s99
	v_med3_i32 v99, v99, 0, s99
	v_med3_i32 v253, v253, 0, s99
	v_med3_i32 v254, v254, 0, s99
	v_med3_i32 v255, v255, 0, s99
	v_mad_u32_u24 v80, v80, s100, v252
	v_mad_u32_u24 v83, v83, s100, v252
	v_mad_u32_u24 v99, v99, s100, v252
	v_mad_u32_u24 v253, v253, s100, v252
	v_mad_u32_u24 v254, v254, s100, v153
	v_mad_u32_u24 v255, v255, s100, v153
	global_load_dwordx4 v[156:159], v80, s[82:83]
	global_load_dwordx4 v[160:163], v83, s[82:83]
	global_load_dwordx4 v[164:167], v99, s[82:83]
	global_load_dwordx4 v[168:171], v253, s[82:83]
	global_load_dwordx4 v[172:175], v254, s[82:83] offset:768
	global_load_dwordx4 v[176:179], v255, s[82:83] offset:768
	global_load_dwordx4 v[180:183], v254, s[82:83] offset:832
	global_load_dwordx4 v[184:187], v255, s[82:83] offset:832
	ds_read_b64_tr_b16 v[72:73], v231
	ds_read_b64_tr_b16 v[74:75], v231 offset:512
	ds_read_b64_tr_b16 v[76:77], v231 offset:2048
	ds_read_b64_tr_b16 v[78:79], v231 offset:2560
	ds_read_b64_tr_b16 v[220:221], v231 offset:1024
	ds_read_b64_tr_b16 v[222:223], v231 offset:1536
	ds_read_b64_tr_b16 v[224:225], v231 offset:3072
	ds_read_b64_tr_b16 v[226:227], v231 offset:3584
	v_exp_f32_e32 v188, v188
	v_exp_f32_e32 v189, v189
	v_exp_f32_e32 v190, v190
	v_exp_f32_e32 v191, v191
	s_waitcnt vmcnt(8)
	ds_write_b128 v247, v[116:119]
	ds_write_b128 v247, v[120:123] offset:1024
	ds_write_b128 v247, v[124:127] offset:2048
	ds_write_b128 v247, v[128:131] offset:3072
	ds_read_b128 v[116:119], v248
	ds_read_b128 v[120:123], v249
	ds_read_b128 v[124:127], v250
	ds_read_b128 v[128:131], v251
	ds_write_b128 v112, v[132:135]
	ds_write_b128 v112, v[136:139] offset:1024
	ds_write_b128 v112, v[140:143] offset:2048
	ds_write_b128 v112, v[144:147] offset:3072
	v_exp_f32_e32 v192, v192
	v_exp_f32_e32 v193, v193
	v_exp_f32_e32 v194, v194
	v_exp_f32_e32 v195, v195
	s_waitcnt lgkmcnt(4)
	v_mfma_f32_32x32x16_bf16 v[32:47], v[116:119], v[48:51], v[32:47]
	v_exp_f32_e32 v196, v196
	v_exp_f32_e32 v197, v197
	v_mfma_f32_32x32x16_bf16 v[32:47], v[120:123], v[52:55], v[32:47]
	v_exp_f32_e32 v198, v198
	v_exp_f32_e32 v199, v199
	v_mfma_f32_32x32x16_bf16 v[32:47], v[124:127], v[56:59], v[32:47]
	v_exp_f32_e32 v200, v200
	v_exp_f32_e32 v201, v201
	v_mfma_f32_32x32x16_bf16 v[32:47], v[128:131], v[60:63], v[32:47]
	v_exp_f32_e32 v202, v202
	v_exp_f32_e32 v203, v203
	s_add_i32 s90, s67, 32
	v_add_u32_e32 v84, s90, v107
	v_add_u32_e32 v85, 0, v84
	v_add_u32_e32 v86, 1, v84
	v_add_u32_e32 v87, 2, v84
	v_add_u32_e32 v88, 3, v84
	v_cmp_gt_u32_e64 s[30:31], s98, v85
	v_cmp_gt_u32_e64 s[36:37], s98, v86
	v_cmp_gt_u32_e64 s[78:79], s98, v87
	v_cmp_gt_u32_e64 s[50:51], s98, v88
	v_cndmask_b32_e64 v188, 0, v188, s[30:31]
	v_add_u32_e32 v85, 8, v84
	v_cmp_gt_u32_e64 s[30:31], s98, v85
	v_cndmask_b32_e64 v189, 0, v189, s[36:37]
	v_add_u32_e32 v86, 9, v84
	v_cmp_gt_u32_e64 s[36:37], s98, v86
	v_cndmask_b32_e64 v190, 0, v190, s[78:79]
	v_add_u32_e32 v87, 10, v84
	v_cmp_gt_u32_e64 s[78:79], s98, v87
	v_cndmask_b32_e64 v191, 0, v191, s[50:51]
	v_add_u32_e32 v88, 11, v84
	v_cmp_gt_u32_e64 s[50:51], s98, v88
	v_cndmask_b32_e64 v192, 0, v192, s[30:31]
	v_add_u32_e32 v85, 16, v84
	v_cmp_gt_u32_e64 s[30:31], s98, v85
	v_cndmask_b32_e64 v193, 0, v193, s[36:37]
	v_add_u32_e32 v86, 17, v84
	v_cmp_gt_u32_e64 s[36:37], s98, v86
	v_cndmask_b32_e64 v194, 0, v194, s[78:79]
	v_add_u32_e32 v87, 18, v84
	v_cmp_gt_u32_e64 s[78:79], s98, v87
	v_cndmask_b32_e64 v195, 0, v195, s[50:51]
	v_add_u32_e32 v88, 19, v84
	v_cmp_gt_u32_e64 s[50:51], s98, v88
	v_cndmask_b32_e64 v196, 0, v196, s[30:31]
	v_add_u32_e32 v85, 24, v84
	v_cmp_gt_u32_e64 s[30:31], s98, v85
	v_cndmask_b32_e64 v197, 0, v197, s[36:37]
	v_add_u32_e32 v86, 25, v84
	v_cmp_gt_u32_e64 s[36:37], s98, v86
	v_cndmask_b32_e64 v198, 0, v198, s[78:79]
	v_add_u32_e32 v87, 26, v84
	v_cmp_gt_u32_e64 s[78:79], s98, v87
	v_cndmask_b32_e64 v199, 0, v199, s[50:51]
	v_add_u32_e32 v88, 27, v84
	v_cmp_gt_u32_e64 s[50:51], s98, v88
	v_nop
	v_cndmask_b32_e64 v200, 0, v200, s[30:31]
	v_cndmask_b32_e64 v201, 0, v201, s[36:37]
	v_cndmask_b32_e64 v202, 0, v202, s[78:79]
	v_cndmask_b32_e64 v203, 0, v203, s[50:51]
	v_cvt_pk_bf16_f32 v64, v188, v189
	v_cvt_pk_bf16_f32 v65, v190, v191
	v_cvt_pk_bf16_f32 v66, v192, v193
	v_cvt_pk_bf16_f32 v67, v194, v195
	v_cvt_pk_bf16_f32 v68, v196, v197
	v_cvt_pk_bf16_f32 v69, v198, v199
	v_cvt_pk_bf16_f32 v70, v200, v201
	v_cvt_pk_bf16_f32 v71, v202, v203
	v_pk_add_f32 v[232:233], v[232:233], v[188:189]
	v_pk_add_f32 v[232:233], v[232:233], v[190:191]
	v_pk_add_f32 v[232:233], v[232:233], v[192:193]
	v_pk_add_f32 v[232:233], v[232:233], v[194:195]
	v_pk_add_f32 v[232:233], v[232:233], v[196:197]
	v_pk_add_f32 v[232:233], v[232:233], v[198:199]
	v_pk_add_f32 v[232:233], v[232:233], v[200:201]
	v_pk_add_f32 v[232:233], v[232:233], v[202:203]
	ds_read2_b32 v[188:189], v115 offset0:170 offset1:171
	ds_read2_b32 v[190:191], v115 offset0:172 offset1:173
	ds_read2_b32 v[192:193], v115 offset0:178 offset1:179
	ds_read2_b32 v[194:195], v115 offset0:180 offset1:181
	ds_read2_b32 v[196:197], v115 offset0:187 offset1:188
	ds_read2_b32 v[198:199], v115 offset0:189 offset1:190
	ds_read2_b32 v[200:201], v115 offset0:195 offset1:196
	ds_read2_b32 v[202:203], v115 offset0:197 offset1:198
	v_mfma_f32_32x32x16_bf16 v[0:15], v[64:67], v[72:75], v[0:15]
	v_mfma_f32_32x32x16_bf16 v[16:31], v[64:67], v[76:79], v[16:31]
	v_mfma_f32_32x32x16_bf16 v[0:15], v[68:71], v[220:223], v[0:15]
	v_mfma_f32_32x32x16_bf16 v[16:31], v[68:71], v[224:227], v[16:31]
	s_add_i32 s90, s67, 128
	v_add_u32_e32 v80, s90, v235
	v_add_u32_e32 v83, s90, v236
	v_add_u32_e32 v99, s90, v237
	v_add_u32_e32 v253, s90, v238
	v_add_u32_e32 v254, s90, v100
	v_add_u32_e32 v255, s90, v149
	v_med3_i32 v80, v80, 0, s99
	v_med3_i32 v83, v83, 0, s99
	v_med3_i32 v99, v99, 0, s99
	v_med3_i32 v253, v253, 0, s99
	v_med3_i32 v254, v254, 0, s99
	v_med3_i32 v255, v255, 0, s99
	v_mad_u32_u24 v80, v80, s100, v252
	v_mad_u32_u24 v83, v83, s100, v252
	v_mad_u32_u24 v99, v99, s100, v252
	v_mad_u32_u24 v253, v253, s100, v252
	v_mad_u32_u24 v254, v254, s100, v153
	v_mad_u32_u24 v255, v255, s100, v153
	global_load_dwordx4 v[116:119], v80, s[82:83]
	global_load_dwordx4 v[120:123], v83, s[82:83]
	global_load_dwordx4 v[124:127], v99, s[82:83]
	global_load_dwordx4 v[128:131], v253, s[82:83]
	global_load_dwordx4 v[132:135], v254, s[82:83] offset:768
	global_load_dwordx4 v[136:139], v255, s[82:83] offset:768
	global_load_dwordx4 v[140:143], v254, s[82:83] offset:832
	global_load_dwordx4 v[144:147], v255, s[82:83] offset:832
	ds_read_b64_tr_b16 v[72:73], v231
	ds_read_b64_tr_b16 v[74:75], v231 offset:512
	ds_read_b64_tr_b16 v[76:77], v231 offset:2048
	ds_read_b64_tr_b16 v[78:79], v231 offset:2560
	ds_read_b64_tr_b16 v[220:221], v231 offset:1024
	ds_read_b64_tr_b16 v[222:223], v231 offset:1536
	ds_read_b64_tr_b16 v[224:225], v231 offset:3072
	ds_read_b64_tr_b16 v[226:227], v231 offset:3584
	v_exp_f32_e32 v32, v32
	v_exp_f32_e32 v33, v33
	v_exp_f32_e32 v34, v34
	v_exp_f32_e32 v35, v35
	s_waitcnt vmcnt(8)
	ds_write_b128 v247, v[156:159]
	ds_write_b128 v247, v[160:163] offset:1024
	ds_write_b128 v247, v[164:167] offset:2048
	ds_write_b128 v247, v[168:171] offset:3072
	ds_read_b128 v[156:159], v248
	ds_read_b128 v[160:163], v249
	ds_read_b128 v[164:167], v250
	ds_read_b128 v[168:171], v251
	ds_write_b128 v112, v[172:175]
	ds_write_b128 v112, v[176:179] offset:1024
	ds_write_b128 v112, v[180:183] offset:2048
	ds_write_b128 v112, v[184:187] offset:3072
	v_exp_f32_e32 v36, v36
	v_exp_f32_e32 v37, v37
	v_exp_f32_e32 v38, v38
	v_exp_f32_e32 v39, v39
	s_waitcnt lgkmcnt(4)
	v_mfma_f32_32x32x16_bf16 v[188:203], v[156:159], v[48:51], v[188:203]
	v_exp_f32_e32 v40, v40
	v_exp_f32_e32 v41, v41
	v_mfma_f32_32x32x16_bf16 v[188:203], v[160:163], v[52:55], v[188:203]
	v_exp_f32_e32 v42, v42
	v_exp_f32_e32 v43, v43
	v_mfma_f32_32x32x16_bf16 v[188:203], v[164:167], v[56:59], v[188:203]
	v_exp_f32_e32 v44, v44
	v_exp_f32_e32 v45, v45
	v_mfma_f32_32x32x16_bf16 v[188:203], v[168:171], v[60:63], v[188:203]
	v_exp_f32_e32 v46, v46
	v_exp_f32_e32 v47, v47
	s_add_i32 s90, s67, 64
	v_add_u32_e32 v84, s90, v107
	v_add_u32_e32 v85, 0, v84
	v_add_u32_e32 v86, 1, v84
	v_add_u32_e32 v87, 2, v84
	v_add_u32_e32 v88, 3, v84
	v_cmp_gt_u32_e64 s[30:31], s98, v85
	v_cmp_gt_u32_e64 s[36:37], s98, v86
	v_cmp_gt_u32_e64 s[78:79], s98, v87
	v_cmp_gt_u32_e64 s[50:51], s98, v88
	v_cndmask_b32_e64 v32, 0, v32, s[30:31]
	v_add_u32_e32 v85, 8, v84
	v_cmp_gt_u32_e64 s[30:31], s98, v85
	v_cndmask_b32_e64 v33, 0, v33, s[36:37]
	v_add_u32_e32 v86, 9, v84
	v_cmp_gt_u32_e64 s[36:37], s98, v86
	v_cndmask_b32_e64 v34, 0, v34, s[78:79]
	v_add_u32_e32 v87, 10, v84
	v_cmp_gt_u32_e64 s[78:79], s98, v87
	v_cndmask_b32_e64 v35, 0, v35, s[50:51]
	v_add_u32_e32 v88, 11, v84
	v_cmp_gt_u32_e64 s[50:51], s98, v88
	v_cndmask_b32_e64 v36, 0, v36, s[30:31]
	v_add_u32_e32 v85, 16, v84
	v_cmp_gt_u32_e64 s[30:31], s98, v85
	v_cndmask_b32_e64 v37, 0, v37, s[36:37]
	v_add_u32_e32 v86, 17, v84
	v_cmp_gt_u32_e64 s[36:37], s98, v86
	v_cndmask_b32_e64 v38, 0, v38, s[78:79]
	v_add_u32_e32 v87, 18, v84
	v_cmp_gt_u32_e64 s[78:79], s98, v87
	v_cndmask_b32_e64 v39, 0, v39, s[50:51]
	v_add_u32_e32 v88, 19, v84
	v_cmp_gt_u32_e64 s[50:51], s98, v88
	v_cndmask_b32_e64 v40, 0, v40, s[30:31]
	v_add_u32_e32 v85, 24, v84
	v_cmp_gt_u32_e64 s[30:31], s98, v85
	v_cndmask_b32_e64 v41, 0, v41, s[36:37]
	v_add_u32_e32 v86, 25, v84
	v_cmp_gt_u32_e64 s[36:37], s98, v86
	v_cndmask_b32_e64 v42, 0, v42, s[78:79]
	v_add_u32_e32 v87, 26, v84
	v_cmp_gt_u32_e64 s[78:79], s98, v87
	v_cndmask_b32_e64 v43, 0, v43, s[50:51]
	v_add_u32_e32 v88, 27, v84
	v_cmp_gt_u32_e64 s[50:51], s98, v88
	v_nop
	v_cndmask_b32_e64 v44, 0, v44, s[30:31]
	v_cndmask_b32_e64 v45, 0, v45, s[36:37]
	v_cndmask_b32_e64 v46, 0, v46, s[78:79]
	v_cndmask_b32_e64 v47, 0, v47, s[50:51]
	v_cvt_pk_bf16_f32 v64, v32, v33
	v_cvt_pk_bf16_f32 v65, v34, v35
	v_cvt_pk_bf16_f32 v66, v36, v37
	v_cvt_pk_bf16_f32 v67, v38, v39
	v_cvt_pk_bf16_f32 v68, v40, v41
	v_cvt_pk_bf16_f32 v69, v42, v43
	v_cvt_pk_bf16_f32 v70, v44, v45
	v_cvt_pk_bf16_f32 v71, v46, v47
	v_pk_add_f32 v[232:233], v[232:233], v[32:33]
	v_pk_add_f32 v[232:233], v[232:233], v[34:35]
	v_pk_add_f32 v[232:233], v[232:233], v[36:37]
	v_pk_add_f32 v[232:233], v[232:233], v[38:39]
	v_pk_add_f32 v[232:233], v[232:233], v[40:41]
	v_pk_add_f32 v[232:233], v[232:233], v[42:43]
	v_pk_add_f32 v[232:233], v[232:233], v[44:45]
	v_pk_add_f32 v[232:233], v[232:233], v[46:47]
	ds_read2_b32 v[32:33], v115 offset0:204 offset1:205
	ds_read2_b32 v[34:35], v115 offset0:206 offset1:207
	ds_read2_b32 v[36:37], v115 offset0:212 offset1:213
	ds_read2_b32 v[38:39], v115 offset0:214 offset1:215
	ds_read2_b32 v[40:41], v115 offset0:221 offset1:222
	ds_read2_b32 v[42:43], v115 offset0:223 offset1:224
	ds_read2_b32 v[44:45], v115 offset0:229 offset1:230
	ds_read2_b32 v[46:47], v115 offset0:231 offset1:232
	v_mfma_f32_32x32x16_bf16 v[0:15], v[64:67], v[72:75], v[0:15]
	v_mfma_f32_32x32x16_bf16 v[16:31], v[64:67], v[76:79], v[16:31]
	v_mfma_f32_32x32x16_bf16 v[0:15], v[68:71], v[220:223], v[0:15]
	v_mfma_f32_32x32x16_bf16 v[16:31], v[68:71], v[224:227], v[16:31]
	s_add_i32 s90, s67, 160
	v_add_u32_e32 v80, s90, v235
	v_add_u32_e32 v83, s90, v236
	v_add_u32_e32 v99, s90, v237
	v_add_u32_e32 v253, s90, v238
	v_add_u32_e32 v254, s90, v100
	v_add_u32_e32 v255, s90, v149
	v_med3_i32 v80, v80, 0, s99
	v_med3_i32 v83, v83, 0, s99
	v_med3_i32 v99, v99, 0, s99
	v_med3_i32 v253, v253, 0, s99
	v_med3_i32 v254, v254, 0, s99
	v_med3_i32 v255, v255, 0, s99
	v_mad_u32_u24 v80, v80, s100, v252
	v_mad_u32_u24 v83, v83, s100, v252
	v_mad_u32_u24 v99, v99, s100, v252
	v_mad_u32_u24 v253, v253, s100, v252
	v_mad_u32_u24 v254, v254, s100, v153
	v_mad_u32_u24 v255, v255, s100, v153
	global_load_dwordx4 v[156:159], v80, s[82:83]
	global_load_dwordx4 v[160:163], v83, s[82:83]
	global_load_dwordx4 v[164:167], v99, s[82:83]
	global_load_dwordx4 v[168:171], v253, s[82:83]
	global_load_dwordx4 v[172:175], v254, s[82:83] offset:768
	global_load_dwordx4 v[176:179], v255, s[82:83] offset:768
	global_load_dwordx4 v[180:183], v254, s[82:83] offset:832
	global_load_dwordx4 v[184:187], v255, s[82:83] offset:832
	ds_read_b64_tr_b16 v[72:73], v231
	ds_read_b64_tr_b16 v[74:75], v231 offset:512
	ds_read_b64_tr_b16 v[76:77], v231 offset:2048
	ds_read_b64_tr_b16 v[78:79], v231 offset:2560
	ds_read_b64_tr_b16 v[220:221], v231 offset:1024
	ds_read_b64_tr_b16 v[222:223], v231 offset:1536
	ds_read_b64_tr_b16 v[224:225], v231 offset:3072
	ds_read_b64_tr_b16 v[226:227], v231 offset:3584
	v_exp_f32_e32 v188, v188
	v_exp_f32_e32 v189, v189
	v_exp_f32_e32 v190, v190
	v_exp_f32_e32 v191, v191
	s_waitcnt vmcnt(8)
	ds_write_b128 v247, v[116:119]
	ds_write_b128 v247, v[120:123] offset:1024
	ds_write_b128 v247, v[124:127] offset:2048
	ds_write_b128 v247, v[128:131] offset:3072
	ds_read_b128 v[116:119], v248
	ds_read_b128 v[120:123], v249
	ds_read_b128 v[124:127], v250
	ds_read_b128 v[128:131], v251
	ds_write_b128 v112, v[132:135]
	ds_write_b128 v112, v[136:139] offset:1024
	ds_write_b128 v112, v[140:143] offset:2048
	ds_write_b128 v112, v[144:147] offset:3072
	v_exp_f32_e32 v192, v192
	v_exp_f32_e32 v193, v193
	v_exp_f32_e32 v194, v194
	v_exp_f32_e32 v195, v195
	s_waitcnt lgkmcnt(4)
	v_mfma_f32_32x32x16_bf16 v[32:47], v[116:119], v[48:51], v[32:47]
	v_exp_f32_e32 v196, v196
	v_exp_f32_e32 v197, v197
	v_mfma_f32_32x32x16_bf16 v[32:47], v[120:123], v[52:55], v[32:47]
	v_exp_f32_e32 v198, v198
	v_exp_f32_e32 v199, v199
	v_mfma_f32_32x32x16_bf16 v[32:47], v[124:127], v[56:59], v[32:47]
	v_exp_f32_e32 v200, v200
	v_exp_f32_e32 v201, v201
	v_mfma_f32_32x32x16_bf16 v[32:47], v[128:131], v[60:63], v[32:47]
	v_exp_f32_e32 v202, v202
	v_exp_f32_e32 v203, v203
	s_add_i32 s90, s67, 96
	v_add_u32_e32 v84, s90, v107
	v_add_u32_e32 v85, 0, v84
	v_add_u32_e32 v86, 1, v84
	v_add_u32_e32 v87, 2, v84
	v_add_u32_e32 v88, 3, v84
	v_cmp_gt_u32_e64 s[30:31], s98, v85
	v_cmp_gt_u32_e64 s[36:37], s98, v86
	v_cmp_gt_u32_e64 s[78:79], s98, v87
	v_cmp_gt_u32_e64 s[50:51], s98, v88
	v_cndmask_b32_e64 v188, 0, v188, s[30:31]
	v_add_u32_e32 v85, 8, v84
	v_cmp_gt_u32_e64 s[30:31], s98, v85
	v_cndmask_b32_e64 v189, 0, v189, s[36:37]
	v_add_u32_e32 v86, 9, v84
	v_cmp_gt_u32_e64 s[36:37], s98, v86
	v_cndmask_b32_e64 v190, 0, v190, s[78:79]
	v_add_u32_e32 v87, 10, v84
	v_cmp_gt_u32_e64 s[78:79], s98, v87
	v_cndmask_b32_e64 v191, 0, v191, s[50:51]
	v_add_u32_e32 v88, 11, v84
	v_cmp_gt_u32_e64 s[50:51], s98, v88
	v_cndmask_b32_e64 v192, 0, v192, s[30:31]
	v_add_u32_e32 v85, 16, v84
	v_cmp_gt_u32_e64 s[30:31], s98, v85
	v_cndmask_b32_e64 v193, 0, v193, s[36:37]
	v_add_u32_e32 v86, 17, v84
	v_cmp_gt_u32_e64 s[36:37], s98, v86
	v_cndmask_b32_e64 v194, 0, v194, s[78:79]
	v_add_u32_e32 v87, 18, v84
	v_cmp_gt_u32_e64 s[78:79], s98, v87
	v_cndmask_b32_e64 v195, 0, v195, s[50:51]
	v_add_u32_e32 v88, 19, v84
	v_cmp_gt_u32_e64 s[50:51], s98, v88
	v_cndmask_b32_e64 v196, 0, v196, s[30:31]
	v_add_u32_e32 v85, 24, v84
	v_cmp_gt_u32_e64 s[30:31], s98, v85
	v_cndmask_b32_e64 v197, 0, v197, s[36:37]
	v_add_u32_e32 v86, 25, v84
	v_cmp_gt_u32_e64 s[36:37], s98, v86
	v_cndmask_b32_e64 v198, 0, v198, s[78:79]
	v_add_u32_e32 v87, 26, v84
	v_cmp_gt_u32_e64 s[78:79], s98, v87
	v_cndmask_b32_e64 v199, 0, v199, s[50:51]
	v_add_u32_e32 v88, 27, v84
	v_cmp_gt_u32_e64 s[50:51], s98, v88
	v_nop
	v_cndmask_b32_e64 v200, 0, v200, s[30:31]
	v_cndmask_b32_e64 v201, 0, v201, s[36:37]
	v_cndmask_b32_e64 v202, 0, v202, s[78:79]
	v_cndmask_b32_e64 v203, 0, v203, s[50:51]
	v_cvt_pk_bf16_f32 v64, v188, v189
	v_cvt_pk_bf16_f32 v65, v190, v191
	v_cvt_pk_bf16_f32 v66, v192, v193
	v_cvt_pk_bf16_f32 v67, v194, v195
	v_cvt_pk_bf16_f32 v68, v196, v197
	v_cvt_pk_bf16_f32 v69, v198, v199
	v_cvt_pk_bf16_f32 v70, v200, v201
	v_cvt_pk_bf16_f32 v71, v202, v203
	v_pk_add_f32 v[232:233], v[232:233], v[188:189]
	v_pk_add_f32 v[232:233], v[232:233], v[190:191]
	v_pk_add_f32 v[232:233], v[232:233], v[192:193]
	v_pk_add_f32 v[232:233], v[232:233], v[194:195]
	v_pk_add_f32 v[232:233], v[232:233], v[196:197]
	v_pk_add_f32 v[232:233], v[232:233], v[198:199]
	v_pk_add_f32 v[232:233], v[232:233], v[200:201]
	v_pk_add_f32 v[232:233], v[232:233], v[202:203]
	v_add_u32_e32 v115, 952, v115
	ds_read2_b32 v[188:189], v115 offset0:0 offset1:1
	ds_read2_b32 v[190:191], v115 offset0:2 offset1:3
	ds_read2_b32 v[192:193], v115 offset0:8 offset1:9
	ds_read2_b32 v[194:195], v115 offset0:10 offset1:11
	ds_read2_b32 v[196:197], v115 offset0:17 offset1:18
	ds_read2_b32 v[198:199], v115 offset0:19 offset1:20
	ds_read2_b32 v[200:201], v115 offset0:25 offset1:26
	ds_read2_b32 v[202:203], v115 offset0:27 offset1:28
	v_mfma_f32_32x32x16_bf16 v[0:15], v[64:67], v[72:75], v[0:15]
	v_mfma_f32_32x32x16_bf16 v[16:31], v[64:67], v[76:79], v[16:31]
	v_mfma_f32_32x32x16_bf16 v[0:15], v[68:71], v[220:223], v[0:15]
	v_mfma_f32_32x32x16_bf16 v[16:31], v[68:71], v[224:227], v[16:31]
	s_add_i32 s90, s67, 192
	v_add_u32_e32 v80, s90, v235
	v_add_u32_e32 v83, s90, v236
	v_add_u32_e32 v99, s90, v237
	v_add_u32_e32 v253, s90, v238
	v_add_u32_e32 v254, s90, v100
	v_add_u32_e32 v255, s90, v149
	v_med3_i32 v80, v80, 0, s99
	v_med3_i32 v83, v83, 0, s99
	v_med3_i32 v99, v99, 0, s99
	v_med3_i32 v253, v253, 0, s99
	v_med3_i32 v254, v254, 0, s99
	v_med3_i32 v255, v255, 0, s99
	v_mad_u32_u24 v80, v80, s100, v252
	v_mad_u32_u24 v83, v83, s100, v252
	v_mad_u32_u24 v99, v99, s100, v252
	v_mad_u32_u24 v253, v253, s100, v252
	v_mad_u32_u24 v254, v254, s100, v153
	v_mad_u32_u24 v255, v255, s100, v153
	global_load_dwordx4 v[116:119], v80, s[82:83]
	global_load_dwordx4 v[120:123], v83, s[82:83]
	global_load_dwordx4 v[124:127], v99, s[82:83]
	global_load_dwordx4 v[128:131], v253, s[82:83]
	global_load_dwordx4 v[132:135], v254, s[82:83] offset:768
	global_load_dwordx4 v[136:139], v255, s[82:83] offset:768
	global_load_dwordx4 v[140:143], v254, s[82:83] offset:832
	global_load_dwordx4 v[144:147], v255, s[82:83] offset:832
	ds_read_b64_tr_b16 v[72:73], v231
	ds_read_b64_tr_b16 v[74:75], v231 offset:512
	ds_read_b64_tr_b16 v[76:77], v231 offset:2048
	ds_read_b64_tr_b16 v[78:79], v231 offset:2560
	ds_read_b64_tr_b16 v[220:221], v231 offset:1024
	ds_read_b64_tr_b16 v[222:223], v231 offset:1536
	ds_read_b64_tr_b16 v[224:225], v231 offset:3072
	ds_read_b64_tr_b16 v[226:227], v231 offset:3584
	v_exp_f32_e32 v32, v32
	v_exp_f32_e32 v33, v33
	v_exp_f32_e32 v34, v34
	v_exp_f32_e32 v35, v35
	s_waitcnt vmcnt(8)
	ds_write_b128 v247, v[156:159]
	ds_write_b128 v247, v[160:163] offset:1024
	ds_write_b128 v247, v[164:167] offset:2048
	ds_write_b128 v247, v[168:171] offset:3072
	ds_read_b128 v[156:159], v248
	ds_read_b128 v[160:163], v249
	ds_read_b128 v[164:167], v250
	ds_read_b128 v[168:171], v251
	ds_write_b128 v112, v[172:175]
	ds_write_b128 v112, v[176:179] offset:1024
	ds_write_b128 v112, v[180:183] offset:2048
	ds_write_b128 v112, v[184:187] offset:3072
	v_exp_f32_e32 v36, v36
	v_exp_f32_e32 v37, v37
	v_exp_f32_e32 v38, v38
	v_exp_f32_e32 v39, v39
	s_waitcnt lgkmcnt(4)
	v_mfma_f32_32x32x16_bf16 v[188:203], v[156:159], v[48:51], v[188:203]
	v_exp_f32_e32 v40, v40
	v_exp_f32_e32 v41, v41
	v_mfma_f32_32x32x16_bf16 v[188:203], v[160:163], v[52:55], v[188:203]
	v_exp_f32_e32 v42, v42
	v_exp_f32_e32 v43, v43
	v_mfma_f32_32x32x16_bf16 v[188:203], v[164:167], v[56:59], v[188:203]
	v_exp_f32_e32 v44, v44
	v_exp_f32_e32 v45, v45
	v_mfma_f32_32x32x16_bf16 v[188:203], v[168:171], v[60:63], v[188:203]
	v_exp_f32_e32 v46, v46
	v_exp_f32_e32 v47, v47
	s_add_i32 s90, s67, 128
	v_add_u32_e32 v84, s90, v107
	v_add_u32_e32 v85, 0, v84
	v_add_u32_e32 v86, 1, v84
	v_add_u32_e32 v87, 2, v84
	v_add_u32_e32 v88, 3, v84
	v_cmp_gt_u32_e64 s[30:31], s98, v85
	v_cmp_gt_u32_e64 s[36:37], s98, v86
	v_cmp_gt_u32_e64 s[78:79], s98, v87
	v_cmp_gt_u32_e64 s[50:51], s98, v88
	v_cndmask_b32_e64 v32, 0, v32, s[30:31]
	v_add_u32_e32 v85, 8, v84
	v_cmp_gt_u32_e64 s[30:31], s98, v85
	v_cndmask_b32_e64 v33, 0, v33, s[36:37]
	v_add_u32_e32 v86, 9, v84
	v_cmp_gt_u32_e64 s[36:37], s98, v86
	v_cndmask_b32_e64 v34, 0, v34, s[78:79]
	v_add_u32_e32 v87, 10, v84
	v_cmp_gt_u32_e64 s[78:79], s98, v87
	v_cndmask_b32_e64 v35, 0, v35, s[50:51]
	v_add_u32_e32 v88, 11, v84
	v_cmp_gt_u32_e64 s[50:51], s98, v88
	v_cndmask_b32_e64 v36, 0, v36, s[30:31]
	v_add_u32_e32 v85, 16, v84
	v_cmp_gt_u32_e64 s[30:31], s98, v85
	v_cndmask_b32_e64 v37, 0, v37, s[36:37]
	v_add_u32_e32 v86, 17, v84
	v_cmp_gt_u32_e64 s[36:37], s98, v86
	v_cndmask_b32_e64 v38, 0, v38, s[78:79]
	v_add_u32_e32 v87, 18, v84
	v_cmp_gt_u32_e64 s[78:79], s98, v87
	v_cndmask_b32_e64 v39, 0, v39, s[50:51]
	v_add_u32_e32 v88, 19, v84
	v_cmp_gt_u32_e64 s[50:51], s98, v88
	v_cndmask_b32_e64 v40, 0, v40, s[30:31]
	v_add_u32_e32 v85, 24, v84
	v_cmp_gt_u32_e64 s[30:31], s98, v85
	v_cndmask_b32_e64 v41, 0, v41, s[36:37]
	v_add_u32_e32 v86, 25, v84
	v_cmp_gt_u32_e64 s[36:37], s98, v86
	v_cndmask_b32_e64 v42, 0, v42, s[78:79]
	v_add_u32_e32 v87, 26, v84
	v_cmp_gt_u32_e64 s[78:79], s98, v87
	v_cndmask_b32_e64 v43, 0, v43, s[50:51]
	v_add_u32_e32 v88, 27, v84
	v_cmp_gt_u32_e64 s[50:51], s98, v88
	v_nop
	v_cndmask_b32_e64 v44, 0, v44, s[30:31]
	v_cndmask_b32_e64 v45, 0, v45, s[36:37]
	v_cndmask_b32_e64 v46, 0, v46, s[78:79]
	v_cndmask_b32_e64 v47, 0, v47, s[50:51]
	v_cvt_pk_bf16_f32 v64, v32, v33
	v_cvt_pk_bf16_f32 v65, v34, v35
	v_cvt_pk_bf16_f32 v66, v36, v37
	v_cvt_pk_bf16_f32 v67, v38, v39
	v_cvt_pk_bf16_f32 v68, v40, v41
	v_cvt_pk_bf16_f32 v69, v42, v43
	v_cvt_pk_bf16_f32 v70, v44, v45
	v_cvt_pk_bf16_f32 v71, v46, v47
	v_pk_add_f32 v[232:233], v[232:233], v[32:33]
	v_pk_add_f32 v[232:233], v[232:233], v[34:35]
	v_pk_add_f32 v[232:233], v[232:233], v[36:37]
	v_pk_add_f32 v[232:233], v[232:233], v[38:39]
	v_pk_add_f32 v[232:233], v[232:233], v[40:41]
	v_pk_add_f32 v[232:233], v[232:233], v[42:43]
	v_pk_add_f32 v[232:233], v[232:233], v[44:45]
	v_pk_add_f32 v[232:233], v[232:233], v[46:47]
	ds_read2_b32 v[32:33], v115 offset0:34 offset1:35
	ds_read2_b32 v[34:35], v115 offset0:36 offset1:37
	ds_read2_b32 v[36:37], v115 offset0:42 offset1:43
	ds_read2_b32 v[38:39], v115 offset0:44 offset1:45
	ds_read2_b32 v[40:41], v115 offset0:51 offset1:52
	ds_read2_b32 v[42:43], v115 offset0:53 offset1:54
	ds_read2_b32 v[44:45], v115 offset0:59 offset1:60
	ds_read2_b32 v[46:47], v115 offset0:61 offset1:62
	v_mfma_f32_32x32x16_bf16 v[0:15], v[64:67], v[72:75], v[0:15]
	v_mfma_f32_32x32x16_bf16 v[16:31], v[64:67], v[76:79], v[16:31]
	v_mfma_f32_32x32x16_bf16 v[0:15], v[68:71], v[220:223], v[0:15]
	v_mfma_f32_32x32x16_bf16 v[16:31], v[68:71], v[224:227], v[16:31]
	s_add_i32 s90, s67, 224
	v_add_u32_e32 v80, s90, v235
	v_add_u32_e32 v83, s90, v236
	v_add_u32_e32 v99, s90, v237
	v_add_u32_e32 v253, s90, v238
	v_add_u32_e32 v254, s90, v100
	v_add_u32_e32 v255, s90, v149
	v_med3_i32 v80, v80, 0, s99
	v_med3_i32 v83, v83, 0, s99
	v_med3_i32 v99, v99, 0, s99
	v_med3_i32 v253, v253, 0, s99
	v_med3_i32 v254, v254, 0, s99
	v_med3_i32 v255, v255, 0, s99
	v_mad_u32_u24 v80, v80, s100, v252
	v_mad_u32_u24 v83, v83, s100, v252
	v_mad_u32_u24 v99, v99, s100, v252
	v_mad_u32_u24 v253, v253, s100, v252
	v_mad_u32_u24 v254, v254, s100, v153
	v_mad_u32_u24 v255, v255, s100, v153
	global_load_dwordx4 v[156:159], v80, s[82:83]
	global_load_dwordx4 v[160:163], v83, s[82:83]
	global_load_dwordx4 v[164:167], v99, s[82:83]
	global_load_dwordx4 v[168:171], v253, s[82:83]
	global_load_dwordx4 v[172:175], v254, s[82:83] offset:768
	global_load_dwordx4 v[176:179], v255, s[82:83] offset:768
	global_load_dwordx4 v[180:183], v254, s[82:83] offset:832
	global_load_dwordx4 v[184:187], v255, s[82:83] offset:832
	ds_read_b64_tr_b16 v[72:73], v231
	ds_read_b64_tr_b16 v[74:75], v231 offset:512
	ds_read_b64_tr_b16 v[76:77], v231 offset:2048
	ds_read_b64_tr_b16 v[78:79], v231 offset:2560
	ds_read_b64_tr_b16 v[220:221], v231 offset:1024
	ds_read_b64_tr_b16 v[222:223], v231 offset:1536
	ds_read_b64_tr_b16 v[224:225], v231 offset:3072
	ds_read_b64_tr_b16 v[226:227], v231 offset:3584
	v_exp_f32_e32 v188, v188
	v_exp_f32_e32 v189, v189
	v_exp_f32_e32 v190, v190
	v_exp_f32_e32 v191, v191
	s_waitcnt vmcnt(8)
	ds_write_b128 v247, v[116:119]
	ds_write_b128 v247, v[120:123] offset:1024
	ds_write_b128 v247, v[124:127] offset:2048
	ds_write_b128 v247, v[128:131] offset:3072
	ds_read_b128 v[116:119], v248
	ds_read_b128 v[120:123], v249
	ds_read_b128 v[124:127], v250
	ds_read_b128 v[128:131], v251
	ds_write_b128 v112, v[132:135]
	ds_write_b128 v112, v[136:139] offset:1024
	ds_write_b128 v112, v[140:143] offset:2048
	ds_write_b128 v112, v[144:147] offset:3072
	v_exp_f32_e32 v192, v192
	v_exp_f32_e32 v193, v193
	v_exp_f32_e32 v194, v194
	v_exp_f32_e32 v195, v195
	s_waitcnt lgkmcnt(4)
	v_mfma_f32_32x32x16_bf16 v[32:47], v[116:119], v[48:51], v[32:47]
	v_exp_f32_e32 v196, v196
	v_exp_f32_e32 v197, v197
	v_mfma_f32_32x32x16_bf16 v[32:47], v[120:123], v[52:55], v[32:47]
	v_exp_f32_e32 v198, v198
	v_exp_f32_e32 v199, v199
	v_mfma_f32_32x32x16_bf16 v[32:47], v[124:127], v[56:59], v[32:47]
	v_exp_f32_e32 v200, v200
	v_exp_f32_e32 v201, v201
	v_mfma_f32_32x32x16_bf16 v[32:47], v[128:131], v[60:63], v[32:47]
	v_exp_f32_e32 v202, v202
	v_exp_f32_e32 v203, v203
	s_add_i32 s90, s67, 160
	v_add_u32_e32 v84, s90, v107
	v_add_u32_e32 v85, 0, v84
	v_add_u32_e32 v86, 1, v84
	v_add_u32_e32 v87, 2, v84
	v_add_u32_e32 v88, 3, v84
	v_cmp_gt_u32_e64 s[30:31], s98, v85
	v_cmp_gt_u32_e64 s[36:37], s98, v86
	v_cmp_gt_u32_e64 s[78:79], s98, v87
	v_cmp_gt_u32_e64 s[50:51], s98, v88
	v_cndmask_b32_e64 v188, 0, v188, s[30:31]
	v_add_u32_e32 v85, 8, v84
	v_cmp_gt_u32_e64 s[30:31], s98, v85
	v_cndmask_b32_e64 v189, 0, v189, s[36:37]
	v_add_u32_e32 v86, 9, v84
	v_cmp_gt_u32_e64 s[36:37], s98, v86
	v_cndmask_b32_e64 v190, 0, v190, s[78:79]
	v_add_u32_e32 v87, 10, v84
	v_cmp_gt_u32_e64 s[78:79], s98, v87
	v_cndmask_b32_e64 v191, 0, v191, s[50:51]
	v_add_u32_e32 v88, 11, v84
	v_cmp_gt_u32_e64 s[50:51], s98, v88
	v_cndmask_b32_e64 v192, 0, v192, s[30:31]
	v_add_u32_e32 v85, 16, v84
	v_cmp_gt_u32_e64 s[30:31], s98, v85
	v_cndmask_b32_e64 v193, 0, v193, s[36:37]
	v_add_u32_e32 v86, 17, v84
	v_cmp_gt_u32_e64 s[36:37], s98, v86
	v_cndmask_b32_e64 v194, 0, v194, s[78:79]
	v_add_u32_e32 v87, 18, v84
	v_cmp_gt_u32_e64 s[78:79], s98, v87
	v_cndmask_b32_e64 v195, 0, v195, s[50:51]
	v_add_u32_e32 v88, 19, v84
	v_cmp_gt_u32_e64 s[50:51], s98, v88
	v_cndmask_b32_e64 v196, 0, v196, s[30:31]
	v_add_u32_e32 v85, 24, v84
	v_cmp_gt_u32_e64 s[30:31], s98, v85
	v_cndmask_b32_e64 v197, 0, v197, s[36:37]
	v_add_u32_e32 v86, 25, v84
	v_cmp_gt_u32_e64 s[36:37], s98, v86
	v_cndmask_b32_e64 v198, 0, v198, s[78:79]
	v_add_u32_e32 v87, 26, v84
	v_cmp_gt_u32_e64 s[78:79], s98, v87
	v_cndmask_b32_e64 v199, 0, v199, s[50:51]
	v_add_u32_e32 v88, 27, v84
	v_cmp_gt_u32_e64 s[50:51], s98, v88
	v_nop
	v_cndmask_b32_e64 v200, 0, v200, s[30:31]
	v_cndmask_b32_e64 v201, 0, v201, s[36:37]
	v_cndmask_b32_e64 v202, 0, v202, s[78:79]
	v_cndmask_b32_e64 v203, 0, v203, s[50:51]
	v_cvt_pk_bf16_f32 v64, v188, v189
	v_cvt_pk_bf16_f32 v65, v190, v191
	v_cvt_pk_bf16_f32 v66, v192, v193
	v_cvt_pk_bf16_f32 v67, v194, v195
	v_cvt_pk_bf16_f32 v68, v196, v197
	v_cvt_pk_bf16_f32 v69, v198, v199
	v_cvt_pk_bf16_f32 v70, v200, v201
	v_cvt_pk_bf16_f32 v71, v202, v203
	v_pk_add_f32 v[232:233], v[232:233], v[188:189]
	v_pk_add_f32 v[232:233], v[232:233], v[190:191]
	v_pk_add_f32 v[232:233], v[232:233], v[192:193]
	v_pk_add_f32 v[232:233], v[232:233], v[194:195]
	v_pk_add_f32 v[232:233], v[232:233], v[196:197]
	v_pk_add_f32 v[232:233], v[232:233], v[198:199]
	v_pk_add_f32 v[232:233], v[232:233], v[200:201]
	v_pk_add_f32 v[232:233], v[232:233], v[202:203]
	ds_read2_b32 v[188:189], v115 offset0:68 offset1:69
	ds_read2_b32 v[190:191], v115 offset0:70 offset1:71
	ds_read2_b32 v[192:193], v115 offset0:76 offset1:77
	ds_read2_b32 v[194:195], v115 offset0:78 offset1:79
	ds_read2_b32 v[196:197], v115 offset0:85 offset1:86
	ds_read2_b32 v[198:199], v115 offset0:87 offset1:88
	ds_read2_b32 v[200:201], v115 offset0:93 offset1:94
	ds_read2_b32 v[202:203], v115 offset0:95 offset1:96
	v_mfma_f32_32x32x16_bf16 v[0:15], v[64:67], v[72:75], v[0:15]
	v_mfma_f32_32x32x16_bf16 v[16:31], v[64:67], v[76:79], v[16:31]
	v_mfma_f32_32x32x16_bf16 v[0:15], v[68:71], v[220:223], v[0:15]
	v_mfma_f32_32x32x16_bf16 v[16:31], v[68:71], v[224:227], v[16:31]
	s_add_i32 s90, s67, 256
	v_add_u32_e32 v80, s90, v235
	v_add_u32_e32 v83, s90, v236
	v_add_u32_e32 v99, s90, v237
	v_add_u32_e32 v253, s90, v238
	v_add_u32_e32 v254, s90, v100
	v_add_u32_e32 v255, s90, v149
	v_med3_i32 v80, v80, 0, s99
	v_med3_i32 v83, v83, 0, s99
	v_med3_i32 v99, v99, 0, s99
	v_med3_i32 v253, v253, 0, s99
	v_med3_i32 v254, v254, 0, s99
	v_med3_i32 v255, v255, 0, s99
	v_mad_u32_u24 v80, v80, s100, v252
	v_mad_u32_u24 v83, v83, s100, v252
	v_mad_u32_u24 v99, v99, s100, v252
	v_mad_u32_u24 v253, v253, s100, v252
	v_mad_u32_u24 v254, v254, s100, v153
	v_mad_u32_u24 v255, v255, s100, v153
	global_load_dwordx4 v[116:119], v80, s[82:83]
	global_load_dwordx4 v[120:123], v83, s[82:83]
	global_load_dwordx4 v[124:127], v99, s[82:83]
	global_load_dwordx4 v[128:131], v253, s[82:83]
	global_load_dwordx4 v[132:135], v254, s[82:83] offset:768
	global_load_dwordx4 v[136:139], v255, s[82:83] offset:768
	global_load_dwordx4 v[140:143], v254, s[82:83] offset:832
	global_load_dwordx4 v[144:147], v255, s[82:83] offset:832
	ds_read_b64_tr_b16 v[72:73], v231
	ds_read_b64_tr_b16 v[74:75], v231 offset:512
	ds_read_b64_tr_b16 v[76:77], v231 offset:2048
	ds_read_b64_tr_b16 v[78:79], v231 offset:2560
	ds_read_b64_tr_b16 v[220:221], v231 offset:1024
	ds_read_b64_tr_b16 v[222:223], v231 offset:1536
	ds_read_b64_tr_b16 v[224:225], v231 offset:3072
	ds_read_b64_tr_b16 v[226:227], v231 offset:3584
	v_exp_f32_e32 v32, v32
	v_exp_f32_e32 v33, v33
	v_exp_f32_e32 v34, v34
	v_exp_f32_e32 v35, v35
	s_waitcnt vmcnt(8)
	ds_write_b128 v247, v[156:159]
	ds_write_b128 v247, v[160:163] offset:1024
	ds_write_b128 v247, v[164:167] offset:2048
	ds_write_b128 v247, v[168:171] offset:3072
	ds_read_b128 v[156:159], v248
	ds_read_b128 v[160:163], v249
	ds_read_b128 v[164:167], v250
	ds_read_b128 v[168:171], v251
	ds_write_b128 v112, v[172:175]
	ds_write_b128 v112, v[176:179] offset:1024
	ds_write_b128 v112, v[180:183] offset:2048
	ds_write_b128 v112, v[184:187] offset:3072
	v_exp_f32_e32 v36, v36
	v_exp_f32_e32 v37, v37
	v_exp_f32_e32 v38, v38
	v_exp_f32_e32 v39, v39
	s_waitcnt lgkmcnt(4)
	v_mfma_f32_32x32x16_bf16 v[188:203], v[156:159], v[48:51], v[188:203]
	v_exp_f32_e32 v40, v40
	v_exp_f32_e32 v41, v41
	v_mfma_f32_32x32x16_bf16 v[188:203], v[160:163], v[52:55], v[188:203]
	v_exp_f32_e32 v42, v42
	v_exp_f32_e32 v43, v43
	v_mfma_f32_32x32x16_bf16 v[188:203], v[164:167], v[56:59], v[188:203]
	v_exp_f32_e32 v44, v44
	v_exp_f32_e32 v45, v45
	v_mfma_f32_32x32x16_bf16 v[188:203], v[168:171], v[60:63], v[188:203]
	v_exp_f32_e32 v46, v46
	v_exp_f32_e32 v47, v47
	s_add_i32 s90, s67, 192
	v_add_u32_e32 v84, s90, v107
	v_add_u32_e32 v85, 0, v84
	v_add_u32_e32 v86, 1, v84
	v_add_u32_e32 v87, 2, v84
	v_add_u32_e32 v88, 3, v84
	v_cmp_gt_u32_e64 s[30:31], s98, v85
	v_cmp_gt_u32_e64 s[36:37], s98, v86
	v_cmp_gt_u32_e64 s[78:79], s98, v87
	v_cmp_gt_u32_e64 s[50:51], s98, v88
	v_cndmask_b32_e64 v32, 0, v32, s[30:31]
	v_add_u32_e32 v85, 8, v84
	v_cmp_gt_u32_e64 s[30:31], s98, v85
	v_cndmask_b32_e64 v33, 0, v33, s[36:37]
	v_add_u32_e32 v86, 9, v84
	v_cmp_gt_u32_e64 s[36:37], s98, v86
	v_cndmask_b32_e64 v34, 0, v34, s[78:79]
	v_add_u32_e32 v87, 10, v84
	v_cmp_gt_u32_e64 s[78:79], s98, v87
	v_cndmask_b32_e64 v35, 0, v35, s[50:51]
	v_add_u32_e32 v88, 11, v84
	v_cmp_gt_u32_e64 s[50:51], s98, v88
	v_cndmask_b32_e64 v36, 0, v36, s[30:31]
	v_add_u32_e32 v85, 16, v84
	v_cmp_gt_u32_e64 s[30:31], s98, v85
	v_cndmask_b32_e64 v37, 0, v37, s[36:37]
	v_add_u32_e32 v86, 17, v84
	v_cmp_gt_u32_e64 s[36:37], s98, v86
	v_cndmask_b32_e64 v38, 0, v38, s[78:79]
	v_add_u32_e32 v87, 18, v84
	v_cmp_gt_u32_e64 s[78:79], s98, v87
	v_cndmask_b32_e64 v39, 0, v39, s[50:51]
	v_add_u32_e32 v88, 19, v84
	v_cmp_gt_u32_e64 s[50:51], s98, v88
	v_cndmask_b32_e64 v40, 0, v40, s[30:31]
	v_add_u32_e32 v85, 24, v84
	v_cmp_gt_u32_e64 s[30:31], s98, v85
	v_cndmask_b32_e64 v41, 0, v41, s[36:37]
	v_add_u32_e32 v86, 25, v84
	v_cmp_gt_u32_e64 s[36:37], s98, v86
	v_cndmask_b32_e64 v42, 0, v42, s[78:79]
	v_add_u32_e32 v87, 26, v84
	v_cmp_gt_u32_e64 s[78:79], s98, v87
	v_cndmask_b32_e64 v43, 0, v43, s[50:51]
	v_add_u32_e32 v88, 27, v84
	v_cmp_gt_u32_e64 s[50:51], s98, v88
	v_nop
	v_cndmask_b32_e64 v44, 0, v44, s[30:31]
	v_cndmask_b32_e64 v45, 0, v45, s[36:37]
	v_cndmask_b32_e64 v46, 0, v46, s[78:79]
	v_cndmask_b32_e64 v47, 0, v47, s[50:51]
	v_cvt_pk_bf16_f32 v64, v32, v33
	v_cvt_pk_bf16_f32 v65, v34, v35
	v_cvt_pk_bf16_f32 v66, v36, v37
	v_cvt_pk_bf16_f32 v67, v38, v39
	v_cvt_pk_bf16_f32 v68, v40, v41
	v_cvt_pk_bf16_f32 v69, v42, v43
	v_cvt_pk_bf16_f32 v70, v44, v45
	v_cvt_pk_bf16_f32 v71, v46, v47
	v_pk_add_f32 v[232:233], v[232:233], v[32:33]
	v_pk_add_f32 v[232:233], v[232:233], v[34:35]
	v_pk_add_f32 v[232:233], v[232:233], v[36:37]
	v_pk_add_f32 v[232:233], v[232:233], v[38:39]
	v_pk_add_f32 v[232:233], v[232:233], v[40:41]
	v_pk_add_f32 v[232:233], v[232:233], v[42:43]
	v_pk_add_f32 v[232:233], v[232:233], v[44:45]
	v_pk_add_f32 v[232:233], v[232:233], v[46:47]
	ds_read2_b32 v[32:33], v115 offset0:102 offset1:103
	ds_read2_b32 v[34:35], v115 offset0:104 offset1:105
	ds_read2_b32 v[36:37], v115 offset0:110 offset1:111
	ds_read2_b32 v[38:39], v115 offset0:112 offset1:113
	ds_read2_b32 v[40:41], v115 offset0:119 offset1:120
	ds_read2_b32 v[42:43], v115 offset0:121 offset1:122
	ds_read2_b32 v[44:45], v115 offset0:127 offset1:128
	ds_read2_b32 v[46:47], v115 offset0:129 offset1:130
	v_mfma_f32_32x32x16_bf16 v[0:15], v[64:67], v[72:75], v[0:15]
	v_mfma_f32_32x32x16_bf16 v[16:31], v[64:67], v[76:79], v[16:31]
	v_mfma_f32_32x32x16_bf16 v[0:15], v[68:71], v[220:223], v[0:15]
	v_mfma_f32_32x32x16_bf16 v[16:31], v[68:71], v[224:227], v[16:31]
	s_add_i32 s90, s67, 288
	v_add_u32_e32 v80, s90, v235
	v_add_u32_e32 v83, s90, v236
	v_add_u32_e32 v99, s90, v237
	v_add_u32_e32 v253, s90, v238
	v_add_u32_e32 v254, s90, v100
	v_add_u32_e32 v255, s90, v149
	v_med3_i32 v80, v80, 0, s99
	v_med3_i32 v83, v83, 0, s99
	v_med3_i32 v99, v99, 0, s99
	v_med3_i32 v253, v253, 0, s99
	v_med3_i32 v254, v254, 0, s99
	v_med3_i32 v255, v255, 0, s99
	v_mad_u32_u24 v80, v80, s100, v252
	v_mad_u32_u24 v83, v83, s100, v252
	v_mad_u32_u24 v99, v99, s100, v252
	v_mad_u32_u24 v253, v253, s100, v252
	v_mad_u32_u24 v254, v254, s100, v153
	v_mad_u32_u24 v255, v255, s100, v153
	global_load_dwordx4 v[156:159], v80, s[82:83]
	global_load_dwordx4 v[160:163], v83, s[82:83]
	global_load_dwordx4 v[164:167], v99, s[82:83]
	global_load_dwordx4 v[168:171], v253, s[82:83]
	global_load_dwordx4 v[172:175], v254, s[82:83] offset:768
	global_load_dwordx4 v[176:179], v255, s[82:83] offset:768
	global_load_dwordx4 v[180:183], v254, s[82:83] offset:832
	global_load_dwordx4 v[184:187], v255, s[82:83] offset:832
	ds_read_b64_tr_b16 v[72:73], v231
	ds_read_b64_tr_b16 v[74:75], v231 offset:512
	ds_read_b64_tr_b16 v[76:77], v231 offset:2048
	ds_read_b64_tr_b16 v[78:79], v231 offset:2560
	ds_read_b64_tr_b16 v[220:221], v231 offset:1024
	ds_read_b64_tr_b16 v[222:223], v231 offset:1536
	ds_read_b64_tr_b16 v[224:225], v231 offset:3072
	ds_read_b64_tr_b16 v[226:227], v231 offset:3584
	v_exp_f32_e32 v188, v188
	v_exp_f32_e32 v189, v189
	v_exp_f32_e32 v190, v190
	v_exp_f32_e32 v191, v191
	s_waitcnt vmcnt(8)
	ds_write_b128 v247, v[116:119]
	ds_write_b128 v247, v[120:123] offset:1024
	ds_write_b128 v247, v[124:127] offset:2048
	ds_write_b128 v247, v[128:131] offset:3072
	ds_read_b128 v[116:119], v248
	ds_read_b128 v[120:123], v249
	ds_read_b128 v[124:127], v250
	ds_read_b128 v[128:131], v251
	ds_write_b128 v112, v[132:135]
	ds_write_b128 v112, v[136:139] offset:1024
	ds_write_b128 v112, v[140:143] offset:2048
	ds_write_b128 v112, v[144:147] offset:3072
	v_exp_f32_e32 v192, v192
	v_exp_f32_e32 v193, v193
	v_exp_f32_e32 v194, v194
	v_exp_f32_e32 v195, v195
	s_waitcnt lgkmcnt(4)
	v_mfma_f32_32x32x16_bf16 v[32:47], v[116:119], v[48:51], v[32:47]
	v_exp_f32_e32 v196, v196
	v_exp_f32_e32 v197, v197
	v_mfma_f32_32x32x16_bf16 v[32:47], v[120:123], v[52:55], v[32:47]
	v_exp_f32_e32 v198, v198
	v_exp_f32_e32 v199, v199
	v_mfma_f32_32x32x16_bf16 v[32:47], v[124:127], v[56:59], v[32:47]
	v_exp_f32_e32 v200, v200
	v_exp_f32_e32 v201, v201
	v_mfma_f32_32x32x16_bf16 v[32:47], v[128:131], v[60:63], v[32:47]
	v_exp_f32_e32 v202, v202
	v_exp_f32_e32 v203, v203
	s_add_i32 s90, s67, 224
	v_add_u32_e32 v84, s90, v107
	v_add_u32_e32 v85, 0, v84
	v_add_u32_e32 v86, 1, v84
	v_add_u32_e32 v87, 2, v84
	v_add_u32_e32 v88, 3, v84
	v_cmp_gt_u32_e64 s[30:31], s98, v85
	v_cmp_gt_u32_e64 s[36:37], s98, v86
	v_cmp_gt_u32_e64 s[78:79], s98, v87
	v_cmp_gt_u32_e64 s[50:51], s98, v88
	v_cndmask_b32_e64 v188, 0, v188, s[30:31]
	v_add_u32_e32 v85, 8, v84
	v_cmp_gt_u32_e64 s[30:31], s98, v85
	v_cndmask_b32_e64 v189, 0, v189, s[36:37]
	v_add_u32_e32 v86, 9, v84
	v_cmp_gt_u32_e64 s[36:37], s98, v86
	v_cndmask_b32_e64 v190, 0, v190, s[78:79]
	v_add_u32_e32 v87, 10, v84
	v_cmp_gt_u32_e64 s[78:79], s98, v87
	v_cndmask_b32_e64 v191, 0, v191, s[50:51]
	v_add_u32_e32 v88, 11, v84
	v_cmp_gt_u32_e64 s[50:51], s98, v88
	v_cndmask_b32_e64 v192, 0, v192, s[30:31]
	v_add_u32_e32 v85, 16, v84
	v_cmp_gt_u32_e64 s[30:31], s98, v85
	v_cndmask_b32_e64 v193, 0, v193, s[36:37]
	v_add_u32_e32 v86, 17, v84
	v_cmp_gt_u32_e64 s[36:37], s98, v86
	v_cndmask_b32_e64 v194, 0, v194, s[78:79]
	v_add_u32_e32 v87, 18, v84
	v_cmp_gt_u32_e64 s[78:79], s98, v87
	v_cndmask_b32_e64 v195, 0, v195, s[50:51]
	v_add_u32_e32 v88, 19, v84
	v_cmp_gt_u32_e64 s[50:51], s98, v88
	v_cndmask_b32_e64 v196, 0, v196, s[30:31]
	v_add_u32_e32 v85, 24, v84
	v_cmp_gt_u32_e64 s[30:31], s98, v85
	v_cndmask_b32_e64 v197, 0, v197, s[36:37]
	v_add_u32_e32 v86, 25, v84
	v_cmp_gt_u32_e64 s[36:37], s98, v86
	v_cndmask_b32_e64 v198, 0, v198, s[78:79]
	v_add_u32_e32 v87, 26, v84
	v_cmp_gt_u32_e64 s[78:79], s98, v87
	v_cndmask_b32_e64 v199, 0, v199, s[50:51]
	v_add_u32_e32 v88, 27, v84
	v_cmp_gt_u32_e64 s[50:51], s98, v88
	v_nop
	v_cndmask_b32_e64 v200, 0, v200, s[30:31]
	v_cndmask_b32_e64 v201, 0, v201, s[36:37]
	v_cndmask_b32_e64 v202, 0, v202, s[78:79]
	v_cndmask_b32_e64 v203, 0, v203, s[50:51]
	v_cvt_pk_bf16_f32 v64, v188, v189
	v_cvt_pk_bf16_f32 v65, v190, v191
	v_cvt_pk_bf16_f32 v66, v192, v193
	v_cvt_pk_bf16_f32 v67, v194, v195
	v_cvt_pk_bf16_f32 v68, v196, v197
	v_cvt_pk_bf16_f32 v69, v198, v199
	v_cvt_pk_bf16_f32 v70, v200, v201
	v_cvt_pk_bf16_f32 v71, v202, v203
	v_pk_add_f32 v[232:233], v[232:233], v[188:189]
	v_pk_add_f32 v[232:233], v[232:233], v[190:191]
	v_pk_add_f32 v[232:233], v[232:233], v[192:193]
	v_pk_add_f32 v[232:233], v[232:233], v[194:195]
	v_pk_add_f32 v[232:233], v[232:233], v[196:197]
	v_pk_add_f32 v[232:233], v[232:233], v[198:199]
	v_pk_add_f32 v[232:233], v[232:233], v[200:201]
	v_pk_add_f32 v[232:233], v[232:233], v[202:203]
	ds_read2_b32 v[188:189], v115 offset0:136 offset1:137
	ds_read2_b32 v[190:191], v115 offset0:138 offset1:139
	ds_read2_b32 v[192:193], v115 offset0:144 offset1:145
	ds_read2_b32 v[194:195], v115 offset0:146 offset1:147
	ds_read2_b32 v[196:197], v115 offset0:153 offset1:154
	ds_read2_b32 v[198:199], v115 offset0:155 offset1:156
	ds_read2_b32 v[200:201], v115 offset0:161 offset1:162
	ds_read2_b32 v[202:203], v115 offset0:163 offset1:164
	v_mfma_f32_32x32x16_bf16 v[0:15], v[64:67], v[72:75], v[0:15]
	v_mfma_f32_32x32x16_bf16 v[16:31], v[64:67], v[76:79], v[16:31]
	v_mfma_f32_32x32x16_bf16 v[0:15], v[68:71], v[220:223], v[0:15]
	v_mfma_f32_32x32x16_bf16 v[16:31], v[68:71], v[224:227], v[16:31]
	s_add_i32 s90, s67, 320
	v_add_u32_e32 v80, s90, v235
	v_add_u32_e32 v83, s90, v236
	v_add_u32_e32 v99, s90, v237
	v_add_u32_e32 v253, s90, v238
	v_add_u32_e32 v254, s90, v100
	v_add_u32_e32 v255, s90, v149
	v_med3_i32 v80, v80, 0, s99
	v_med3_i32 v83, v83, 0, s99
	v_med3_i32 v99, v99, 0, s99
	v_med3_i32 v253, v253, 0, s99
	v_med3_i32 v254, v254, 0, s99
	v_med3_i32 v255, v255, 0, s99
	v_mad_u32_u24 v80, v80, s100, v252
	v_mad_u32_u24 v83, v83, s100, v252
	v_mad_u32_u24 v99, v99, s100, v252
	v_mad_u32_u24 v253, v253, s100, v252
	v_mad_u32_u24 v254, v254, s100, v153
	v_mad_u32_u24 v255, v255, s100, v153
	global_load_dwordx4 v[116:119], v80, s[82:83]
	global_load_dwordx4 v[120:123], v83, s[82:83]
	global_load_dwordx4 v[124:127], v99, s[82:83]
	global_load_dwordx4 v[128:131], v253, s[82:83]
	global_load_dwordx4 v[132:135], v254, s[82:83] offset:768
	global_load_dwordx4 v[136:139], v255, s[82:83] offset:768
	global_load_dwordx4 v[140:143], v254, s[82:83] offset:832
	global_load_dwordx4 v[144:147], v255, s[82:83] offset:832
	ds_read_b64_tr_b16 v[72:73], v231
	ds_read_b64_tr_b16 v[74:75], v231 offset:512
	ds_read_b64_tr_b16 v[76:77], v231 offset:2048
	ds_read_b64_tr_b16 v[78:79], v231 offset:2560
	ds_read_b64_tr_b16 v[220:221], v231 offset:1024
	ds_read_b64_tr_b16 v[222:223], v231 offset:1536
	ds_read_b64_tr_b16 v[224:225], v231 offset:3072
	ds_read_b64_tr_b16 v[226:227], v231 offset:3584
	v_exp_f32_e32 v32, v32
	v_exp_f32_e32 v33, v33
	v_exp_f32_e32 v34, v34
	v_exp_f32_e32 v35, v35
	s_waitcnt vmcnt(8)
	ds_write_b128 v247, v[156:159]
	ds_write_b128 v247, v[160:163] offset:1024
	ds_write_b128 v247, v[164:167] offset:2048
	ds_write_b128 v247, v[168:171] offset:3072
	ds_read_b128 v[156:159], v248
	ds_read_b128 v[160:163], v249
	ds_read_b128 v[164:167], v250
	ds_read_b128 v[168:171], v251
	ds_write_b128 v112, v[172:175]
	ds_write_b128 v112, v[176:179] offset:1024
	ds_write_b128 v112, v[180:183] offset:2048
	ds_write_b128 v112, v[184:187] offset:3072
	v_exp_f32_e32 v36, v36
	v_exp_f32_e32 v37, v37
	v_exp_f32_e32 v38, v38
	v_exp_f32_e32 v39, v39
	s_waitcnt lgkmcnt(4)
	v_mfma_f32_32x32x16_bf16 v[188:203], v[156:159], v[48:51], v[188:203]
	v_exp_f32_e32 v40, v40
	v_exp_f32_e32 v41, v41
	v_mfma_f32_32x32x16_bf16 v[188:203], v[160:163], v[52:55], v[188:203]
	v_exp_f32_e32 v42, v42
	v_exp_f32_e32 v43, v43
	v_mfma_f32_32x32x16_bf16 v[188:203], v[164:167], v[56:59], v[188:203]
	v_exp_f32_e32 v44, v44
	v_exp_f32_e32 v45, v45
	v_mfma_f32_32x32x16_bf16 v[188:203], v[168:171], v[60:63], v[188:203]
	v_exp_f32_e32 v46, v46
	v_exp_f32_e32 v47, v47
	s_add_i32 s90, s67, 256
	v_add_u32_e32 v84, s90, v107
	v_add_u32_e32 v85, 0, v84
	v_add_u32_e32 v86, 1, v84
	v_add_u32_e32 v87, 2, v84
	v_add_u32_e32 v88, 3, v84
	v_cmp_gt_u32_e64 s[30:31], s98, v85
	v_cmp_gt_u32_e64 s[36:37], s98, v86
	v_cmp_gt_u32_e64 s[78:79], s98, v87
	v_cmp_gt_u32_e64 s[50:51], s98, v88
	v_cndmask_b32_e64 v32, 0, v32, s[30:31]
	v_add_u32_e32 v85, 8, v84
	v_cmp_gt_u32_e64 s[30:31], s98, v85
	v_cndmask_b32_e64 v33, 0, v33, s[36:37]
	v_add_u32_e32 v86, 9, v84
	v_cmp_gt_u32_e64 s[36:37], s98, v86
	v_cndmask_b32_e64 v34, 0, v34, s[78:79]
	v_add_u32_e32 v87, 10, v84
	v_cmp_gt_u32_e64 s[78:79], s98, v87
	v_cndmask_b32_e64 v35, 0, v35, s[50:51]
	v_add_u32_e32 v88, 11, v84
	v_cmp_gt_u32_e64 s[50:51], s98, v88
	v_cndmask_b32_e64 v36, 0, v36, s[30:31]
	v_add_u32_e32 v85, 16, v84
	v_cmp_gt_u32_e64 s[30:31], s98, v85
	v_cndmask_b32_e64 v37, 0, v37, s[36:37]
	v_add_u32_e32 v86, 17, v84
	v_cmp_gt_u32_e64 s[36:37], s98, v86
	v_cndmask_b32_e64 v38, 0, v38, s[78:79]
	v_add_u32_e32 v87, 18, v84
	v_cmp_gt_u32_e64 s[78:79], s98, v87
	v_cndmask_b32_e64 v39, 0, v39, s[50:51]
	v_add_u32_e32 v88, 19, v84
	v_cmp_gt_u32_e64 s[50:51], s98, v88
	v_cndmask_b32_e64 v40, 0, v40, s[30:31]
	v_add_u32_e32 v85, 24, v84
	v_cmp_gt_u32_e64 s[30:31], s98, v85
	v_cndmask_b32_e64 v41, 0, v41, s[36:37]
	v_add_u32_e32 v86, 25, v84
	v_cmp_gt_u32_e64 s[36:37], s98, v86
	v_cndmask_b32_e64 v42, 0, v42, s[78:79]
	v_add_u32_e32 v87, 26, v84
	v_cmp_gt_u32_e64 s[78:79], s98, v87
	v_cndmask_b32_e64 v43, 0, v43, s[50:51]
	v_add_u32_e32 v88, 27, v84
	v_cmp_gt_u32_e64 s[50:51], s98, v88
	v_nop
	v_cndmask_b32_e64 v44, 0, v44, s[30:31]
	v_cndmask_b32_e64 v45, 0, v45, s[36:37]
	v_cndmask_b32_e64 v46, 0, v46, s[78:79]
	v_cndmask_b32_e64 v47, 0, v47, s[50:51]
	v_cvt_pk_bf16_f32 v64, v32, v33
	v_cvt_pk_bf16_f32 v65, v34, v35
	v_cvt_pk_bf16_f32 v66, v36, v37
	v_cvt_pk_bf16_f32 v67, v38, v39
	v_cvt_pk_bf16_f32 v68, v40, v41
	v_cvt_pk_bf16_f32 v69, v42, v43
	v_cvt_pk_bf16_f32 v70, v44, v45
	v_cvt_pk_bf16_f32 v71, v46, v47
	v_pk_add_f32 v[232:233], v[232:233], v[32:33]
	v_pk_add_f32 v[232:233], v[232:233], v[34:35]
	v_pk_add_f32 v[232:233], v[232:233], v[36:37]
	v_pk_add_f32 v[232:233], v[232:233], v[38:39]
	v_pk_add_f32 v[232:233], v[232:233], v[40:41]
	v_pk_add_f32 v[232:233], v[232:233], v[42:43]
	v_pk_add_f32 v[232:233], v[232:233], v[44:45]
	v_pk_add_f32 v[232:233], v[232:233], v[46:47]
	ds_read2_b32 v[32:33], v115 offset0:170 offset1:171
	ds_read2_b32 v[34:35], v115 offset0:172 offset1:173
	ds_read2_b32 v[36:37], v115 offset0:178 offset1:179
	ds_read2_b32 v[38:39], v115 offset0:180 offset1:181
	ds_read2_b32 v[40:41], v115 offset0:187 offset1:188
	ds_read2_b32 v[42:43], v115 offset0:189 offset1:190
	ds_read2_b32 v[44:45], v115 offset0:195 offset1:196
	ds_read2_b32 v[46:47], v115 offset0:197 offset1:198
	v_mfma_f32_32x32x16_bf16 v[0:15], v[64:67], v[72:75], v[0:15]
	v_mfma_f32_32x32x16_bf16 v[16:31], v[64:67], v[76:79], v[16:31]
	v_mfma_f32_32x32x16_bf16 v[0:15], v[68:71], v[220:223], v[0:15]
	v_mfma_f32_32x32x16_bf16 v[16:31], v[68:71], v[224:227], v[16:31]
	s_add_i32 s90, s67, 352
	v_add_u32_e32 v80, s90, v235
	v_add_u32_e32 v83, s90, v236
	v_add_u32_e32 v99, s90, v237
	v_add_u32_e32 v253, s90, v238
	v_add_u32_e32 v254, s90, v100
	v_add_u32_e32 v255, s90, v149
	v_med3_i32 v80, v80, 0, s99
	v_med3_i32 v83, v83, 0, s99
	v_med3_i32 v99, v99, 0, s99
	v_med3_i32 v253, v253, 0, s99
	v_med3_i32 v254, v254, 0, s99
	v_med3_i32 v255, v255, 0, s99
	v_mad_u32_u24 v80, v80, s100, v252
	v_mad_u32_u24 v83, v83, s100, v252
	v_mad_u32_u24 v99, v99, s100, v252
	v_mad_u32_u24 v253, v253, s100, v252
	v_mad_u32_u24 v254, v254, s100, v153
	v_mad_u32_u24 v255, v255, s100, v153
	global_load_dwordx4 v[156:159], v80, s[82:83]
	global_load_dwordx4 v[160:163], v83, s[82:83]
	global_load_dwordx4 v[164:167], v99, s[82:83]
	global_load_dwordx4 v[168:171], v253, s[82:83]
	global_load_dwordx4 v[172:175], v254, s[82:83] offset:768
	global_load_dwordx4 v[176:179], v255, s[82:83] offset:768
	global_load_dwordx4 v[180:183], v254, s[82:83] offset:832
	global_load_dwordx4 v[184:187], v255, s[82:83] offset:832
	ds_read_b64_tr_b16 v[72:73], v231
	ds_read_b64_tr_b16 v[74:75], v231 offset:512
	ds_read_b64_tr_b16 v[76:77], v231 offset:2048
	ds_read_b64_tr_b16 v[78:79], v231 offset:2560
	ds_read_b64_tr_b16 v[220:221], v231 offset:1024
	ds_read_b64_tr_b16 v[222:223], v231 offset:1536
	ds_read_b64_tr_b16 v[224:225], v231 offset:3072
	ds_read_b64_tr_b16 v[226:227], v231 offset:3584
	v_exp_f32_e32 v188, v188
	v_exp_f32_e32 v189, v189
	v_exp_f32_e32 v190, v190
	v_exp_f32_e32 v191, v191
	s_waitcnt vmcnt(8)
	ds_write_b128 v247, v[116:119]
	ds_write_b128 v247, v[120:123] offset:1024
	ds_write_b128 v247, v[124:127] offset:2048
	ds_write_b128 v247, v[128:131] offset:3072
	ds_read_b128 v[116:119], v248
	ds_read_b128 v[120:123], v249
	ds_read_b128 v[124:127], v250
	ds_read_b128 v[128:131], v251
	ds_write_b128 v112, v[132:135]
	ds_write_b128 v112, v[136:139] offset:1024
	ds_write_b128 v112, v[140:143] offset:2048
	ds_write_b128 v112, v[144:147] offset:3072
	v_exp_f32_e32 v192, v192
	v_exp_f32_e32 v193, v193
	v_exp_f32_e32 v194, v194
	v_exp_f32_e32 v195, v195
	s_waitcnt lgkmcnt(4)
	v_mfma_f32_32x32x16_bf16 v[32:47], v[116:119], v[48:51], v[32:47]
	v_exp_f32_e32 v196, v196
	v_exp_f32_e32 v197, v197
	v_mfma_f32_32x32x16_bf16 v[32:47], v[120:123], v[52:55], v[32:47]
	v_exp_f32_e32 v198, v198
	v_exp_f32_e32 v199, v199
	v_mfma_f32_32x32x16_bf16 v[32:47], v[124:127], v[56:59], v[32:47]
	v_exp_f32_e32 v200, v200
	v_exp_f32_e32 v201, v201
	v_mfma_f32_32x32x16_bf16 v[32:47], v[128:131], v[60:63], v[32:47]
	v_exp_f32_e32 v202, v202
	v_exp_f32_e32 v203, v203
	s_add_i32 s90, s67, 288
	v_add_u32_e32 v84, s90, v107
	v_add_u32_e32 v85, 0, v84
	v_add_u32_e32 v86, 1, v84
	v_add_u32_e32 v87, 2, v84
	v_add_u32_e32 v88, 3, v84
	v_cmp_gt_u32_e64 s[30:31], s98, v85
	v_cmp_gt_u32_e64 s[36:37], s98, v86
	v_cmp_gt_u32_e64 s[78:79], s98, v87
	v_cmp_gt_u32_e64 s[50:51], s98, v88
	v_cndmask_b32_e64 v188, 0, v188, s[30:31]
	v_add_u32_e32 v85, 8, v84
	v_cmp_gt_u32_e64 s[30:31], s98, v85
	v_cndmask_b32_e64 v189, 0, v189, s[36:37]
	v_add_u32_e32 v86, 9, v84
	v_cmp_gt_u32_e64 s[36:37], s98, v86
	v_cndmask_b32_e64 v190, 0, v190, s[78:79]
	v_add_u32_e32 v87, 10, v84
	v_cmp_gt_u32_e64 s[78:79], s98, v87
	v_cndmask_b32_e64 v191, 0, v191, s[50:51]
	v_add_u32_e32 v88, 11, v84
	v_cmp_gt_u32_e64 s[50:51], s98, v88
	v_cndmask_b32_e64 v192, 0, v192, s[30:31]
	v_add_u32_e32 v85, 16, v84
	v_cmp_gt_u32_e64 s[30:31], s98, v85
	v_cndmask_b32_e64 v193, 0, v193, s[36:37]
	v_add_u32_e32 v86, 17, v84
	v_cmp_gt_u32_e64 s[36:37], s98, v86
	v_cndmask_b32_e64 v194, 0, v194, s[78:79]
	v_add_u32_e32 v87, 18, v84
	v_cmp_gt_u32_e64 s[78:79], s98, v87
	v_cndmask_b32_e64 v195, 0, v195, s[50:51]
	v_add_u32_e32 v88, 19, v84
	v_cmp_gt_u32_e64 s[50:51], s98, v88
	v_cndmask_b32_e64 v196, 0, v196, s[30:31]
	v_add_u32_e32 v85, 24, v84
	v_cmp_gt_u32_e64 s[30:31], s98, v85
	v_cndmask_b32_e64 v197, 0, v197, s[36:37]
	v_add_u32_e32 v86, 25, v84
	v_cmp_gt_u32_e64 s[36:37], s98, v86
	v_cndmask_b32_e64 v198, 0, v198, s[78:79]
	v_add_u32_e32 v87, 26, v84
	v_cmp_gt_u32_e64 s[78:79], s98, v87
	v_cndmask_b32_e64 v199, 0, v199, s[50:51]
	v_add_u32_e32 v88, 27, v84
	v_cmp_gt_u32_e64 s[50:51], s98, v88
	v_nop
	v_cndmask_b32_e64 v200, 0, v200, s[30:31]
	v_cndmask_b32_e64 v201, 0, v201, s[36:37]
	v_cndmask_b32_e64 v202, 0, v202, s[78:79]
	v_cndmask_b32_e64 v203, 0, v203, s[50:51]
	v_cvt_pk_bf16_f32 v64, v188, v189
	v_cvt_pk_bf16_f32 v65, v190, v191
	v_cvt_pk_bf16_f32 v66, v192, v193
	v_cvt_pk_bf16_f32 v67, v194, v195
	v_cvt_pk_bf16_f32 v68, v196, v197
	v_cvt_pk_bf16_f32 v69, v198, v199
	v_cvt_pk_bf16_f32 v70, v200, v201
	v_cvt_pk_bf16_f32 v71, v202, v203
	v_pk_add_f32 v[232:233], v[232:233], v[188:189]
	v_pk_add_f32 v[232:233], v[232:233], v[190:191]
	v_pk_add_f32 v[232:233], v[232:233], v[192:193]
	v_pk_add_f32 v[232:233], v[232:233], v[194:195]
	v_pk_add_f32 v[232:233], v[232:233], v[196:197]
	v_pk_add_f32 v[232:233], v[232:233], v[198:199]
	v_pk_add_f32 v[232:233], v[232:233], v[200:201]
	v_pk_add_f32 v[232:233], v[232:233], v[202:203]
	ds_read2_b32 v[188:189], v115 offset0:204 offset1:205
	ds_read2_b32 v[190:191], v115 offset0:206 offset1:207
	ds_read2_b32 v[192:193], v115 offset0:212 offset1:213
	ds_read2_b32 v[194:195], v115 offset0:214 offset1:215
	ds_read2_b32 v[196:197], v115 offset0:221 offset1:222
	ds_read2_b32 v[198:199], v115 offset0:223 offset1:224
	ds_read2_b32 v[200:201], v115 offset0:229 offset1:230
	ds_read2_b32 v[202:203], v115 offset0:231 offset1:232
	v_mfma_f32_32x32x16_bf16 v[0:15], v[64:67], v[72:75], v[0:15]
	v_mfma_f32_32x32x16_bf16 v[16:31], v[64:67], v[76:79], v[16:31]
	v_mfma_f32_32x32x16_bf16 v[0:15], v[68:71], v[220:223], v[0:15]
	v_mfma_f32_32x32x16_bf16 v[16:31], v[68:71], v[224:227], v[16:31]
	s_add_i32 s90, s67, 384
	v_add_u32_e32 v80, s90, v235
	v_add_u32_e32 v83, s90, v236
	v_add_u32_e32 v99, s90, v237
	v_add_u32_e32 v253, s90, v238
	v_add_u32_e32 v254, s90, v100
	v_add_u32_e32 v255, s90, v149
	v_med3_i32 v80, v80, 0, s99
	v_med3_i32 v83, v83, 0, s99
	v_med3_i32 v99, v99, 0, s99
	v_med3_i32 v253, v253, 0, s99
	v_med3_i32 v254, v254, 0, s99
	v_med3_i32 v255, v255, 0, s99
	v_mad_u32_u24 v80, v80, s100, v252
	v_mad_u32_u24 v83, v83, s100, v252
	v_mad_u32_u24 v99, v99, s100, v252
	v_mad_u32_u24 v253, v253, s100, v252
	v_mad_u32_u24 v254, v254, s100, v153
	v_mad_u32_u24 v255, v255, s100, v153
	global_load_dwordx4 v[116:119], v80, s[82:83]
	global_load_dwordx4 v[120:123], v83, s[82:83]
	global_load_dwordx4 v[124:127], v99, s[82:83]
	global_load_dwordx4 v[128:131], v253, s[82:83]
	global_load_dwordx4 v[132:135], v254, s[82:83] offset:768
	global_load_dwordx4 v[136:139], v255, s[82:83] offset:768
	global_load_dwordx4 v[140:143], v254, s[82:83] offset:832
	global_load_dwordx4 v[144:147], v255, s[82:83] offset:832
	ds_read_b64_tr_b16 v[72:73], v231
	ds_read_b64_tr_b16 v[74:75], v231 offset:512
	ds_read_b64_tr_b16 v[76:77], v231 offset:2048
	ds_read_b64_tr_b16 v[78:79], v231 offset:2560
	ds_read_b64_tr_b16 v[220:221], v231 offset:1024
	ds_read_b64_tr_b16 v[222:223], v231 offset:1536
	ds_read_b64_tr_b16 v[224:225], v231 offset:3072
	ds_read_b64_tr_b16 v[226:227], v231 offset:3584
	v_exp_f32_e32 v32, v32
	v_exp_f32_e32 v33, v33
	v_exp_f32_e32 v34, v34
	v_exp_f32_e32 v35, v35
	s_waitcnt vmcnt(8)
	ds_write_b128 v247, v[156:159]
	ds_write_b128 v247, v[160:163] offset:1024
	ds_write_b128 v247, v[164:167] offset:2048
	ds_write_b128 v247, v[168:171] offset:3072
	ds_read_b128 v[156:159], v248
	ds_read_b128 v[160:163], v249
	ds_read_b128 v[164:167], v250
	ds_read_b128 v[168:171], v251
	ds_write_b128 v112, v[172:175]
	ds_write_b128 v112, v[176:179] offset:1024
	ds_write_b128 v112, v[180:183] offset:2048
	ds_write_b128 v112, v[184:187] offset:3072
	v_exp_f32_e32 v36, v36
	v_exp_f32_e32 v37, v37
	v_exp_f32_e32 v38, v38
	v_exp_f32_e32 v39, v39
	s_waitcnt lgkmcnt(4)
	v_mfma_f32_32x32x16_bf16 v[188:203], v[156:159], v[48:51], v[188:203]
	v_exp_f32_e32 v40, v40
	v_exp_f32_e32 v41, v41
	v_mfma_f32_32x32x16_bf16 v[188:203], v[160:163], v[52:55], v[188:203]
	v_exp_f32_e32 v42, v42
	v_exp_f32_e32 v43, v43
	v_mfma_f32_32x32x16_bf16 v[188:203], v[164:167], v[56:59], v[188:203]
	v_exp_f32_e32 v44, v44
	v_exp_f32_e32 v45, v45
	v_mfma_f32_32x32x16_bf16 v[188:203], v[168:171], v[60:63], v[188:203]
	v_exp_f32_e32 v46, v46
	v_exp_f32_e32 v47, v47
	s_add_i32 s90, s67, 320
	v_add_u32_e32 v84, s90, v107
	v_add_u32_e32 v85, 0, v84
	v_add_u32_e32 v86, 1, v84
	v_add_u32_e32 v87, 2, v84
	v_add_u32_e32 v88, 3, v84
	v_cmp_gt_u32_e64 s[30:31], s98, v85
	v_cmp_gt_u32_e64 s[36:37], s98, v86
	v_cmp_gt_u32_e64 s[78:79], s98, v87
	v_cmp_gt_u32_e64 s[50:51], s98, v88
	v_cndmask_b32_e64 v32, 0, v32, s[30:31]
	v_add_u32_e32 v85, 8, v84
	v_cmp_gt_u32_e64 s[30:31], s98, v85
	v_cndmask_b32_e64 v33, 0, v33, s[36:37]
	v_add_u32_e32 v86, 9, v84
	v_cmp_gt_u32_e64 s[36:37], s98, v86
	v_cndmask_b32_e64 v34, 0, v34, s[78:79]
	v_add_u32_e32 v87, 10, v84
	v_cmp_gt_u32_e64 s[78:79], s98, v87
	v_cndmask_b32_e64 v35, 0, v35, s[50:51]
	v_add_u32_e32 v88, 11, v84
	v_cmp_gt_u32_e64 s[50:51], s98, v88
	v_cndmask_b32_e64 v36, 0, v36, s[30:31]
	v_add_u32_e32 v85, 16, v84
	v_cmp_gt_u32_e64 s[30:31], s98, v85
	v_cndmask_b32_e64 v37, 0, v37, s[36:37]
	v_add_u32_e32 v86, 17, v84
	v_cmp_gt_u32_e64 s[36:37], s98, v86
	v_cndmask_b32_e64 v38, 0, v38, s[78:79]
	v_add_u32_e32 v87, 18, v84
	v_cmp_gt_u32_e64 s[78:79], s98, v87
	v_cndmask_b32_e64 v39, 0, v39, s[50:51]
	v_add_u32_e32 v88, 19, v84
	v_cmp_gt_u32_e64 s[50:51], s98, v88
	v_cndmask_b32_e64 v40, 0, v40, s[30:31]
	v_add_u32_e32 v85, 24, v84
	v_cmp_gt_u32_e64 s[30:31], s98, v85
	v_cndmask_b32_e64 v41, 0, v41, s[36:37]
	v_add_u32_e32 v86, 25, v84
	v_cmp_gt_u32_e64 s[36:37], s98, v86
	v_cndmask_b32_e64 v42, 0, v42, s[78:79]
	v_add_u32_e32 v87, 26, v84
	v_cmp_gt_u32_e64 s[78:79], s98, v87
	v_cndmask_b32_e64 v43, 0, v43, s[50:51]
	v_add_u32_e32 v88, 27, v84
	v_cmp_gt_u32_e64 s[50:51], s98, v88
	v_nop
	v_cndmask_b32_e64 v44, 0, v44, s[30:31]
	v_cndmask_b32_e64 v45, 0, v45, s[36:37]
	v_cndmask_b32_e64 v46, 0, v46, s[78:79]
	v_cndmask_b32_e64 v47, 0, v47, s[50:51]
	v_cvt_pk_bf16_f32 v64, v32, v33
	v_cvt_pk_bf16_f32 v65, v34, v35
	v_cvt_pk_bf16_f32 v66, v36, v37
	v_cvt_pk_bf16_f32 v67, v38, v39
	v_cvt_pk_bf16_f32 v68, v40, v41
	v_cvt_pk_bf16_f32 v69, v42, v43
	v_cvt_pk_bf16_f32 v70, v44, v45
	v_cvt_pk_bf16_f32 v71, v46, v47
	v_pk_add_f32 v[232:233], v[232:233], v[32:33]
	v_pk_add_f32 v[232:233], v[232:233], v[34:35]
	v_pk_add_f32 v[232:233], v[232:233], v[36:37]
	v_pk_add_f32 v[232:233], v[232:233], v[38:39]
	v_pk_add_f32 v[232:233], v[232:233], v[40:41]
	v_pk_add_f32 v[232:233], v[232:233], v[42:43]
	v_pk_add_f32 v[232:233], v[232:233], v[44:45]
	v_pk_add_f32 v[232:233], v[232:233], v[46:47]
	v_add_u32_e32 v115, 952, v115
	ds_read2_b32 v[32:33], v115 offset0:0 offset1:1
	ds_read2_b32 v[34:35], v115 offset0:2 offset1:3
	ds_read2_b32 v[36:37], v115 offset0:8 offset1:9
	ds_read2_b32 v[38:39], v115 offset0:10 offset1:11
	ds_read2_b32 v[40:41], v115 offset0:17 offset1:18
	ds_read2_b32 v[42:43], v115 offset0:19 offset1:20
	ds_read2_b32 v[44:45], v115 offset0:25 offset1:26
	ds_read2_b32 v[46:47], v115 offset0:27 offset1:28
	v_mfma_f32_32x32x16_bf16 v[0:15], v[64:67], v[72:75], v[0:15]
	v_mfma_f32_32x32x16_bf16 v[16:31], v[64:67], v[76:79], v[16:31]
	v_mfma_f32_32x32x16_bf16 v[0:15], v[68:71], v[220:223], v[0:15]
	v_mfma_f32_32x32x16_bf16 v[16:31], v[68:71], v[224:227], v[16:31]
	s_add_i32 s90, s67, 416
	v_add_u32_e32 v80, s90, v235
	v_add_u32_e32 v83, s90, v236
	v_add_u32_e32 v99, s90, v237
	v_add_u32_e32 v253, s90, v238
	v_add_u32_e32 v254, s90, v100
	v_add_u32_e32 v255, s90, v149
	v_med3_i32 v80, v80, 0, s99
	v_med3_i32 v83, v83, 0, s99
	v_med3_i32 v99, v99, 0, s99
	v_med3_i32 v253, v253, 0, s99
	v_med3_i32 v254, v254, 0, s99
	v_med3_i32 v255, v255, 0, s99
	v_mad_u32_u24 v80, v80, s100, v252
	v_mad_u32_u24 v83, v83, s100, v252
	v_mad_u32_u24 v99, v99, s100, v252
	v_mad_u32_u24 v253, v253, s100, v252
	v_mad_u32_u24 v254, v254, s100, v153
	v_mad_u32_u24 v255, v255, s100, v153
	global_load_dwordx4 v[156:159], v80, s[82:83]
	global_load_dwordx4 v[160:163], v83, s[82:83]
	global_load_dwordx4 v[164:167], v99, s[82:83]
	global_load_dwordx4 v[168:171], v253, s[82:83]
	global_load_dwordx4 v[172:175], v254, s[82:83] offset:768
	global_load_dwordx4 v[176:179], v255, s[82:83] offset:768
	global_load_dwordx4 v[180:183], v254, s[82:83] offset:832
	global_load_dwordx4 v[184:187], v255, s[82:83] offset:832
	ds_read_b64_tr_b16 v[72:73], v231
	ds_read_b64_tr_b16 v[74:75], v231 offset:512
	ds_read_b64_tr_b16 v[76:77], v231 offset:2048
	ds_read_b64_tr_b16 v[78:79], v231 offset:2560
	ds_read_b64_tr_b16 v[220:221], v231 offset:1024
	ds_read_b64_tr_b16 v[222:223], v231 offset:1536
	ds_read_b64_tr_b16 v[224:225], v231 offset:3072
	ds_read_b64_tr_b16 v[226:227], v231 offset:3584
	v_exp_f32_e32 v188, v188
	v_exp_f32_e32 v189, v189
	v_exp_f32_e32 v190, v190
	v_exp_f32_e32 v191, v191
	s_waitcnt vmcnt(8)
	ds_write_b128 v247, v[116:119]
	ds_write_b128 v247, v[120:123] offset:1024
	ds_write_b128 v247, v[124:127] offset:2048
	ds_write_b128 v247, v[128:131] offset:3072
	ds_read_b128 v[116:119], v248
	ds_read_b128 v[120:123], v249
	ds_read_b128 v[124:127], v250
	ds_read_b128 v[128:131], v251
	ds_write_b128 v112, v[132:135]
	ds_write_b128 v112, v[136:139] offset:1024
	ds_write_b128 v112, v[140:143] offset:2048
	ds_write_b128 v112, v[144:147] offset:3072
	v_exp_f32_e32 v192, v192
	v_exp_f32_e32 v193, v193
	v_exp_f32_e32 v194, v194
	v_exp_f32_e32 v195, v195
	s_waitcnt lgkmcnt(4)
	v_mfma_f32_32x32x16_bf16 v[32:47], v[116:119], v[48:51], v[32:47]
	v_exp_f32_e32 v196, v196
	v_exp_f32_e32 v197, v197
	v_mfma_f32_32x32x16_bf16 v[32:47], v[120:123], v[52:55], v[32:47]
	v_exp_f32_e32 v198, v198
	v_exp_f32_e32 v199, v199
	v_mfma_f32_32x32x16_bf16 v[32:47], v[124:127], v[56:59], v[32:47]
	v_exp_f32_e32 v200, v200
	v_exp_f32_e32 v201, v201
	v_mfma_f32_32x32x16_bf16 v[32:47], v[128:131], v[60:63], v[32:47]
	v_exp_f32_e32 v202, v202
	v_exp_f32_e32 v203, v203
	s_add_i32 s90, s67, 352
	v_add_u32_e32 v84, s90, v107
	v_add_u32_e32 v85, 0, v84
	v_add_u32_e32 v86, 1, v84
	v_add_u32_e32 v87, 2, v84
	v_add_u32_e32 v88, 3, v84
	v_cmp_gt_u32_e64 s[30:31], s98, v85
	v_cmp_gt_u32_e64 s[36:37], s98, v86
	v_cmp_gt_u32_e64 s[78:79], s98, v87
	v_cmp_gt_u32_e64 s[50:51], s98, v88
	v_cndmask_b32_e64 v188, 0, v188, s[30:31]
	v_add_u32_e32 v85, 8, v84
	v_cmp_gt_u32_e64 s[30:31], s98, v85
	v_cndmask_b32_e64 v189, 0, v189, s[36:37]
	v_add_u32_e32 v86, 9, v84
	v_cmp_gt_u32_e64 s[36:37], s98, v86
	v_cndmask_b32_e64 v190, 0, v190, s[78:79]
	v_add_u32_e32 v87, 10, v84
	v_cmp_gt_u32_e64 s[78:79], s98, v87
	v_cndmask_b32_e64 v191, 0, v191, s[50:51]
	v_add_u32_e32 v88, 11, v84
	v_cmp_gt_u32_e64 s[50:51], s98, v88
	v_cndmask_b32_e64 v192, 0, v192, s[30:31]
	v_add_u32_e32 v85, 16, v84
	v_cmp_gt_u32_e64 s[30:31], s98, v85
	v_cndmask_b32_e64 v193, 0, v193, s[36:37]
	v_add_u32_e32 v86, 17, v84
	v_cmp_gt_u32_e64 s[36:37], s98, v86
	v_cndmask_b32_e64 v194, 0, v194, s[78:79]
	v_add_u32_e32 v87, 18, v84
	v_cmp_gt_u32_e64 s[78:79], s98, v87
	v_cndmask_b32_e64 v195, 0, v195, s[50:51]
	v_add_u32_e32 v88, 19, v84
	v_cmp_gt_u32_e64 s[50:51], s98, v88
	v_cndmask_b32_e64 v196, 0, v196, s[30:31]
	v_add_u32_e32 v85, 24, v84
	v_cmp_gt_u32_e64 s[30:31], s98, v85
	v_cndmask_b32_e64 v197, 0, v197, s[36:37]
	v_add_u32_e32 v86, 25, v84
	v_cmp_gt_u32_e64 s[36:37], s98, v86
	v_cndmask_b32_e64 v198, 0, v198, s[78:79]
	v_add_u32_e32 v87, 26, v84
	v_cmp_gt_u32_e64 s[78:79], s98, v87
	v_cndmask_b32_e64 v199, 0, v199, s[50:51]
	v_add_u32_e32 v88, 27, v84
	v_cmp_gt_u32_e64 s[50:51], s98, v88
	v_nop
	v_cndmask_b32_e64 v200, 0, v200, s[30:31]
	v_cndmask_b32_e64 v201, 0, v201, s[36:37]
	v_cndmask_b32_e64 v202, 0, v202, s[78:79]
	v_cndmask_b32_e64 v203, 0, v203, s[50:51]
	v_cvt_pk_bf16_f32 v64, v188, v189
	v_cvt_pk_bf16_f32 v65, v190, v191
	v_cvt_pk_bf16_f32 v66, v192, v193
	v_cvt_pk_bf16_f32 v67, v194, v195
	v_cvt_pk_bf16_f32 v68, v196, v197
	v_cvt_pk_bf16_f32 v69, v198, v199
	v_cvt_pk_bf16_f32 v70, v200, v201
	v_cvt_pk_bf16_f32 v71, v202, v203
	v_pk_add_f32 v[232:233], v[232:233], v[188:189]
	v_pk_add_f32 v[232:233], v[232:233], v[190:191]
	v_pk_add_f32 v[232:233], v[232:233], v[192:193]
	v_pk_add_f32 v[232:233], v[232:233], v[194:195]
	v_pk_add_f32 v[232:233], v[232:233], v[196:197]
	v_pk_add_f32 v[232:233], v[232:233], v[198:199]
	v_pk_add_f32 v[232:233], v[232:233], v[200:201]
	v_pk_add_f32 v[232:233], v[232:233], v[202:203]
	ds_read2_b32 v[188:189], v115 offset0:34 offset1:35
	ds_read2_b32 v[190:191], v115 offset0:36 offset1:37
	ds_read2_b32 v[192:193], v115 offset0:42 offset1:43
	ds_read2_b32 v[194:195], v115 offset0:44 offset1:45
	ds_read2_b32 v[196:197], v115 offset0:51 offset1:52
	ds_read2_b32 v[198:199], v115 offset0:53 offset1:54
	ds_read2_b32 v[200:201], v115 offset0:59 offset1:60
	ds_read2_b32 v[202:203], v115 offset0:61 offset1:62
	v_mfma_f32_32x32x16_bf16 v[0:15], v[64:67], v[72:75], v[0:15]
	v_mfma_f32_32x32x16_bf16 v[16:31], v[64:67], v[76:79], v[16:31]
	v_mfma_f32_32x32x16_bf16 v[0:15], v[68:71], v[220:223], v[0:15]
	v_mfma_f32_32x32x16_bf16 v[16:31], v[68:71], v[224:227], v[16:31]
	s_add_i32 s90, s67, 448
	v_add_u32_e32 v80, s90, v235
	v_add_u32_e32 v83, s90, v236
	v_add_u32_e32 v99, s90, v237
	v_add_u32_e32 v253, s90, v238
	v_add_u32_e32 v254, s90, v100
	v_add_u32_e32 v255, s90, v149
	v_med3_i32 v80, v80, 0, s99
	v_med3_i32 v83, v83, 0, s99
	v_med3_i32 v99, v99, 0, s99
	v_med3_i32 v253, v253, 0, s99
	v_med3_i32 v254, v254, 0, s99
	v_med3_i32 v255, v255, 0, s99
	v_mad_u32_u24 v80, v80, s100, v252
	v_mad_u32_u24 v83, v83, s100, v252
	v_mad_u32_u24 v99, v99, s100, v252
	v_mad_u32_u24 v253, v253, s100, v252
	v_mad_u32_u24 v254, v254, s100, v153
	v_mad_u32_u24 v255, v255, s100, v153
	global_load_dwordx4 v[116:119], v80, s[82:83]
	global_load_dwordx4 v[120:123], v83, s[82:83]
	global_load_dwordx4 v[124:127], v99, s[82:83]
	global_load_dwordx4 v[128:131], v253, s[82:83]
	global_load_dwordx4 v[132:135], v254, s[82:83] offset:768
	global_load_dwordx4 v[136:139], v255, s[82:83] offset:768
	global_load_dwordx4 v[140:143], v254, s[82:83] offset:832
	global_load_dwordx4 v[144:147], v255, s[82:83] offset:832
	ds_read_b64_tr_b16 v[72:73], v231
	ds_read_b64_tr_b16 v[74:75], v231 offset:512
	ds_read_b64_tr_b16 v[76:77], v231 offset:2048
	ds_read_b64_tr_b16 v[78:79], v231 offset:2560
	ds_read_b64_tr_b16 v[220:221], v231 offset:1024
	ds_read_b64_tr_b16 v[222:223], v231 offset:1536
	ds_read_b64_tr_b16 v[224:225], v231 offset:3072
	ds_read_b64_tr_b16 v[226:227], v231 offset:3584
	v_exp_f32_e32 v32, v32
	v_exp_f32_e32 v33, v33
	v_exp_f32_e32 v34, v34
	v_exp_f32_e32 v35, v35
	s_waitcnt vmcnt(8)
	ds_write_b128 v247, v[156:159]
	ds_write_b128 v247, v[160:163] offset:1024
	ds_write_b128 v247, v[164:167] offset:2048
	ds_write_b128 v247, v[168:171] offset:3072
	ds_read_b128 v[156:159], v248
	ds_read_b128 v[160:163], v249
	ds_read_b128 v[164:167], v250
	ds_read_b128 v[168:171], v251
	ds_write_b128 v112, v[172:175]
	ds_write_b128 v112, v[176:179] offset:1024
	ds_write_b128 v112, v[180:183] offset:2048
	ds_write_b128 v112, v[184:187] offset:3072
	v_exp_f32_e32 v36, v36
	v_exp_f32_e32 v37, v37
	v_exp_f32_e32 v38, v38
	v_exp_f32_e32 v39, v39
	s_waitcnt lgkmcnt(4)
	v_mfma_f32_32x32x16_bf16 v[188:203], v[156:159], v[48:51], v[188:203]
	v_exp_f32_e32 v40, v40
	v_exp_f32_e32 v41, v41
	v_mfma_f32_32x32x16_bf16 v[188:203], v[160:163], v[52:55], v[188:203]
	v_exp_f32_e32 v42, v42
	v_exp_f32_e32 v43, v43
	v_mfma_f32_32x32x16_bf16 v[188:203], v[164:167], v[56:59], v[188:203]
	v_exp_f32_e32 v44, v44
	v_exp_f32_e32 v45, v45
	v_mfma_f32_32x32x16_bf16 v[188:203], v[168:171], v[60:63], v[188:203]
	v_exp_f32_e32 v46, v46
	v_exp_f32_e32 v47, v47
	s_add_i32 s90, s67, 384
	v_add_u32_e32 v84, s90, v107
	v_add_u32_e32 v85, 0, v84
	v_add_u32_e32 v86, 1, v84
	v_add_u32_e32 v87, 2, v84
	v_add_u32_e32 v88, 3, v84
	v_cmp_gt_u32_e64 s[30:31], s98, v85
	v_cmp_gt_u32_e64 s[36:37], s98, v86
	v_cmp_gt_u32_e64 s[78:79], s98, v87
	v_cmp_gt_u32_e64 s[50:51], s98, v88
	v_cndmask_b32_e64 v32, 0, v32, s[30:31]
	v_add_u32_e32 v85, 8, v84
	v_cmp_gt_u32_e64 s[30:31], s98, v85
	v_cndmask_b32_e64 v33, 0, v33, s[36:37]
	v_add_u32_e32 v86, 9, v84
	v_cmp_gt_u32_e64 s[36:37], s98, v86
	v_cndmask_b32_e64 v34, 0, v34, s[78:79]
	v_add_u32_e32 v87, 10, v84
	v_cmp_gt_u32_e64 s[78:79], s98, v87
	v_cndmask_b32_e64 v35, 0, v35, s[50:51]
	v_add_u32_e32 v88, 11, v84
	v_cmp_gt_u32_e64 s[50:51], s98, v88
	v_cndmask_b32_e64 v36, 0, v36, s[30:31]
	v_add_u32_e32 v85, 16, v84
	v_cmp_gt_u32_e64 s[30:31], s98, v85
	v_cndmask_b32_e64 v37, 0, v37, s[36:37]
	v_add_u32_e32 v86, 17, v84
	v_cmp_gt_u32_e64 s[36:37], s98, v86
	v_cndmask_b32_e64 v38, 0, v38, s[78:79]
	v_add_u32_e32 v87, 18, v84
	v_cmp_gt_u32_e64 s[78:79], s98, v87
	v_cndmask_b32_e64 v39, 0, v39, s[50:51]
	v_add_u32_e32 v88, 19, v84
	v_cmp_gt_u32_e64 s[50:51], s98, v88
	v_cndmask_b32_e64 v40, 0, v40, s[30:31]
	v_add_u32_e32 v85, 24, v84
	v_cmp_gt_u32_e64 s[30:31], s98, v85
	v_cndmask_b32_e64 v41, 0, v41, s[36:37]
	v_add_u32_e32 v86, 25, v84
	v_cmp_gt_u32_e64 s[36:37], s98, v86
	v_cndmask_b32_e64 v42, 0, v42, s[78:79]
	v_add_u32_e32 v87, 26, v84
	v_cmp_gt_u32_e64 s[78:79], s98, v87
	v_cndmask_b32_e64 v43, 0, v43, s[50:51]
	v_add_u32_e32 v88, 27, v84
	v_cmp_gt_u32_e64 s[50:51], s98, v88
	v_nop
	v_cndmask_b32_e64 v44, 0, v44, s[30:31]
	v_cndmask_b32_e64 v45, 0, v45, s[36:37]
	v_cndmask_b32_e64 v46, 0, v46, s[78:79]
	v_cndmask_b32_e64 v47, 0, v47, s[50:51]
	v_cvt_pk_bf16_f32 v64, v32, v33
	v_cvt_pk_bf16_f32 v65, v34, v35
	v_cvt_pk_bf16_f32 v66, v36, v37
	v_cvt_pk_bf16_f32 v67, v38, v39
	v_cvt_pk_bf16_f32 v68, v40, v41
	v_cvt_pk_bf16_f32 v69, v42, v43
	v_cvt_pk_bf16_f32 v70, v44, v45
	v_cvt_pk_bf16_f32 v71, v46, v47
	v_pk_add_f32 v[232:233], v[232:233], v[32:33]
	v_pk_add_f32 v[232:233], v[232:233], v[34:35]
	v_pk_add_f32 v[232:233], v[232:233], v[36:37]
	v_pk_add_f32 v[232:233], v[232:233], v[38:39]
	v_pk_add_f32 v[232:233], v[232:233], v[40:41]
	v_pk_add_f32 v[232:233], v[232:233], v[42:43]
	v_pk_add_f32 v[232:233], v[232:233], v[44:45]
	v_pk_add_f32 v[232:233], v[232:233], v[46:47]
	ds_read2_b32 v[32:33], v115 offset0:68 offset1:69
	ds_read2_b32 v[34:35], v115 offset0:70 offset1:71
	ds_read2_b32 v[36:37], v115 offset0:76 offset1:77
	ds_read2_b32 v[38:39], v115 offset0:78 offset1:79
	ds_read2_b32 v[40:41], v115 offset0:85 offset1:86
	ds_read2_b32 v[42:43], v115 offset0:87 offset1:88
	ds_read2_b32 v[44:45], v115 offset0:93 offset1:94
	ds_read2_b32 v[46:47], v115 offset0:95 offset1:96
	v_mfma_f32_32x32x16_bf16 v[0:15], v[64:67], v[72:75], v[0:15]
	v_mfma_f32_32x32x16_bf16 v[16:31], v[64:67], v[76:79], v[16:31]
	v_mfma_f32_32x32x16_bf16 v[0:15], v[68:71], v[220:223], v[0:15]
	v_mfma_f32_32x32x16_bf16 v[16:31], v[68:71], v[224:227], v[16:31]
	s_add_i32 s90, s67, 480
	v_add_u32_e32 v80, s90, v235
	v_add_u32_e32 v83, s90, v236
	v_add_u32_e32 v99, s90, v237
	v_add_u32_e32 v253, s90, v238
	v_add_u32_e32 v254, s90, v100
	v_add_u32_e32 v255, s90, v149
	v_med3_i32 v80, v80, 0, s99
	v_med3_i32 v83, v83, 0, s99
	v_med3_i32 v99, v99, 0, s99
	v_med3_i32 v253, v253, 0, s99
	v_med3_i32 v254, v254, 0, s99
	v_med3_i32 v255, v255, 0, s99
	v_mad_u32_u24 v80, v80, s100, v252
	v_mad_u32_u24 v83, v83, s100, v252
	v_mad_u32_u24 v99, v99, s100, v252
	v_mad_u32_u24 v253, v253, s100, v252
	v_mad_u32_u24 v254, v254, s100, v153
	v_mad_u32_u24 v255, v255, s100, v153
	global_load_dwordx4 v[156:159], v80, s[82:83]
	global_load_dwordx4 v[160:163], v83, s[82:83]
	global_load_dwordx4 v[164:167], v99, s[82:83]
	global_load_dwordx4 v[168:171], v253, s[82:83]
	global_load_dwordx4 v[172:175], v254, s[82:83] offset:768
	global_load_dwordx4 v[176:179], v255, s[82:83] offset:768
	global_load_dwordx4 v[180:183], v254, s[82:83] offset:832
	global_load_dwordx4 v[184:187], v255, s[82:83] offset:832
	ds_read_b64_tr_b16 v[72:73], v231
	ds_read_b64_tr_b16 v[74:75], v231 offset:512
	ds_read_b64_tr_b16 v[76:77], v231 offset:2048
	ds_read_b64_tr_b16 v[78:79], v231 offset:2560
	ds_read_b64_tr_b16 v[220:221], v231 offset:1024
	ds_read_b64_tr_b16 v[222:223], v231 offset:1536
	ds_read_b64_tr_b16 v[224:225], v231 offset:3072
	ds_read_b64_tr_b16 v[226:227], v231 offset:3584
	v_exp_f32_e32 v188, v188
	v_exp_f32_e32 v189, v189
	v_exp_f32_e32 v190, v190
	v_exp_f32_e32 v191, v191
	s_waitcnt vmcnt(8)
	ds_write_b128 v247, v[116:119]
	ds_write_b128 v247, v[120:123] offset:1024
	ds_write_b128 v247, v[124:127] offset:2048
	ds_write_b128 v247, v[128:131] offset:3072
	ds_read_b128 v[116:119], v248
	ds_read_b128 v[120:123], v249
	ds_read_b128 v[124:127], v250
	ds_read_b128 v[128:131], v251
	ds_write_b128 v112, v[132:135]
	ds_write_b128 v112, v[136:139] offset:1024
	ds_write_b128 v112, v[140:143] offset:2048
	ds_write_b128 v112, v[144:147] offset:3072
	v_exp_f32_e32 v192, v192
	v_exp_f32_e32 v193, v193
	v_exp_f32_e32 v194, v194
	v_exp_f32_e32 v195, v195
	s_waitcnt lgkmcnt(4)
	v_mfma_f32_32x32x16_bf16 v[32:47], v[116:119], v[48:51], v[32:47]
	v_exp_f32_e32 v196, v196
	v_exp_f32_e32 v197, v197
	v_mfma_f32_32x32x16_bf16 v[32:47], v[120:123], v[52:55], v[32:47]
	v_exp_f32_e32 v198, v198
	v_exp_f32_e32 v199, v199
	v_mfma_f32_32x32x16_bf16 v[32:47], v[124:127], v[56:59], v[32:47]
	v_exp_f32_e32 v200, v200
	v_exp_f32_e32 v201, v201
	v_mfma_f32_32x32x16_bf16 v[32:47], v[128:131], v[60:63], v[32:47]
	v_exp_f32_e32 v202, v202
	v_exp_f32_e32 v203, v203
	s_add_i32 s90, s67, 416
	v_add_u32_e32 v84, s90, v107
	v_add_u32_e32 v85, 0, v84
	v_add_u32_e32 v86, 1, v84
	v_add_u32_e32 v87, 2, v84
	v_add_u32_e32 v88, 3, v84
	v_cmp_gt_u32_e64 s[30:31], s98, v85
	v_cmp_gt_u32_e64 s[36:37], s98, v86
	v_cmp_gt_u32_e64 s[78:79], s98, v87
	v_cmp_gt_u32_e64 s[50:51], s98, v88
	v_cndmask_b32_e64 v188, 0, v188, s[30:31]
	v_add_u32_e32 v85, 8, v84
	v_cmp_gt_u32_e64 s[30:31], s98, v85
	v_cndmask_b32_e64 v189, 0, v189, s[36:37]
	v_add_u32_e32 v86, 9, v84
	v_cmp_gt_u32_e64 s[36:37], s98, v86
	v_cndmask_b32_e64 v190, 0, v190, s[78:79]
	v_add_u32_e32 v87, 10, v84
	v_cmp_gt_u32_e64 s[78:79], s98, v87
	v_cndmask_b32_e64 v191, 0, v191, s[50:51]
	v_add_u32_e32 v88, 11, v84
	v_cmp_gt_u32_e64 s[50:51], s98, v88
	v_cndmask_b32_e64 v192, 0, v192, s[30:31]
	v_add_u32_e32 v85, 16, v84
	v_cmp_gt_u32_e64 s[30:31], s98, v85
	v_cndmask_b32_e64 v193, 0, v193, s[36:37]
	v_add_u32_e32 v86, 17, v84
	v_cmp_gt_u32_e64 s[36:37], s98, v86
	v_cndmask_b32_e64 v194, 0, v194, s[78:79]
	v_add_u32_e32 v87, 18, v84
	v_cmp_gt_u32_e64 s[78:79], s98, v87
	v_cndmask_b32_e64 v195, 0, v195, s[50:51]
	v_add_u32_e32 v88, 19, v84
	v_cmp_gt_u32_e64 s[50:51], s98, v88
	v_cndmask_b32_e64 v196, 0, v196, s[30:31]
	v_add_u32_e32 v85, 24, v84
	v_cmp_gt_u32_e64 s[30:31], s98, v85
	v_cndmask_b32_e64 v197, 0, v197, s[36:37]
	v_add_u32_e32 v86, 25, v84
	v_cmp_gt_u32_e64 s[36:37], s98, v86
	v_cndmask_b32_e64 v198, 0, v198, s[78:79]
	v_add_u32_e32 v87, 26, v84
	v_cmp_gt_u32_e64 s[78:79], s98, v87
	v_cndmask_b32_e64 v199, 0, v199, s[50:51]
	v_add_u32_e32 v88, 27, v84
	v_cmp_gt_u32_e64 s[50:51], s98, v88
	v_nop
	v_cndmask_b32_e64 v200, 0, v200, s[30:31]
	v_cndmask_b32_e64 v201, 0, v201, s[36:37]
	v_cndmask_b32_e64 v202, 0, v202, s[78:79]
	v_cndmask_b32_e64 v203, 0, v203, s[50:51]
	v_cvt_pk_bf16_f32 v64, v188, v189
	v_cvt_pk_bf16_f32 v65, v190, v191
	v_cvt_pk_bf16_f32 v66, v192, v193
	v_cvt_pk_bf16_f32 v67, v194, v195
	v_cvt_pk_bf16_f32 v68, v196, v197
	v_cvt_pk_bf16_f32 v69, v198, v199
	v_cvt_pk_bf16_f32 v70, v200, v201
	v_cvt_pk_bf16_f32 v71, v202, v203
	v_pk_add_f32 v[232:233], v[232:233], v[188:189]
	v_pk_add_f32 v[232:233], v[232:233], v[190:191]
	v_pk_add_f32 v[232:233], v[232:233], v[192:193]
	v_pk_add_f32 v[232:233], v[232:233], v[194:195]
	v_pk_add_f32 v[232:233], v[232:233], v[196:197]
	v_pk_add_f32 v[232:233], v[232:233], v[198:199]
	v_pk_add_f32 v[232:233], v[232:233], v[200:201]
	v_pk_add_f32 v[232:233], v[232:233], v[202:203]
	ds_read2_b32 v[188:189], v115 offset0:102 offset1:103
	ds_read2_b32 v[190:191], v115 offset0:104 offset1:105
	ds_read2_b32 v[192:193], v115 offset0:110 offset1:111
	ds_read2_b32 v[194:195], v115 offset0:112 offset1:113
	ds_read2_b32 v[196:197], v115 offset0:119 offset1:120
	ds_read2_b32 v[198:199], v115 offset0:121 offset1:122
	ds_read2_b32 v[200:201], v115 offset0:127 offset1:128
	ds_read2_b32 v[202:203], v115 offset0:129 offset1:130
	v_mfma_f32_32x32x16_bf16 v[0:15], v[64:67], v[72:75], v[0:15]
	v_mfma_f32_32x32x16_bf16 v[16:31], v[64:67], v[76:79], v[16:31]
	v_mfma_f32_32x32x16_bf16 v[0:15], v[68:71], v[220:223], v[0:15]
	v_mfma_f32_32x32x16_bf16 v[16:31], v[68:71], v[224:227], v[16:31]
	s_add_i32 s90, s67, 512
	v_add_u32_e32 v80, s90, v235
	v_add_u32_e32 v83, s90, v236
	v_add_u32_e32 v99, s90, v237
	v_add_u32_e32 v253, s90, v238
	v_add_u32_e32 v254, s90, v100
	v_add_u32_e32 v255, s90, v149
	v_med3_i32 v80, v80, 0, s99
	v_med3_i32 v83, v83, 0, s99
	v_med3_i32 v99, v99, 0, s99
	v_med3_i32 v253, v253, 0, s99
	v_med3_i32 v254, v254, 0, s99
	v_med3_i32 v255, v255, 0, s99
	v_mad_u32_u24 v80, v80, s100, v252
	v_mad_u32_u24 v83, v83, s100, v252
	v_mad_u32_u24 v99, v99, s100, v252
	v_mad_u32_u24 v253, v253, s100, v252
	v_mad_u32_u24 v254, v254, s100, v153
	v_mad_u32_u24 v255, v255, s100, v153
	global_load_dwordx4 v[116:119], v80, s[82:83]
	global_load_dwordx4 v[120:123], v83, s[82:83]
	global_load_dwordx4 v[124:127], v99, s[82:83]
	global_load_dwordx4 v[128:131], v253, s[82:83]
	global_load_dwordx4 v[132:135], v254, s[82:83] offset:768
	global_load_dwordx4 v[136:139], v255, s[82:83] offset:768
	global_load_dwordx4 v[140:143], v254, s[82:83] offset:832
	global_load_dwordx4 v[144:147], v255, s[82:83] offset:832
	ds_read_b64_tr_b16 v[72:73], v231
	ds_read_b64_tr_b16 v[74:75], v231 offset:512
	ds_read_b64_tr_b16 v[76:77], v231 offset:2048
	ds_read_b64_tr_b16 v[78:79], v231 offset:2560
	ds_read_b64_tr_b16 v[220:221], v231 offset:1024
	ds_read_b64_tr_b16 v[222:223], v231 offset:1536
	ds_read_b64_tr_b16 v[224:225], v231 offset:3072
	ds_read_b64_tr_b16 v[226:227], v231 offset:3584
	v_exp_f32_e32 v32, v32
	v_exp_f32_e32 v33, v33
	v_exp_f32_e32 v34, v34
	v_exp_f32_e32 v35, v35
	s_waitcnt vmcnt(8)
	ds_write_b128 v247, v[156:159]
	ds_write_b128 v247, v[160:163] offset:1024
	ds_write_b128 v247, v[164:167] offset:2048
	ds_write_b128 v247, v[168:171] offset:3072
	ds_read_b128 v[156:159], v248
	ds_read_b128 v[160:163], v249
	ds_read_b128 v[164:167], v250
	ds_read_b128 v[168:171], v251
	ds_write_b128 v112, v[172:175]
	ds_write_b128 v112, v[176:179] offset:1024
	ds_write_b128 v112, v[180:183] offset:2048
	ds_write_b128 v112, v[184:187] offset:3072
	v_exp_f32_e32 v36, v36
	v_exp_f32_e32 v37, v37
	v_exp_f32_e32 v38, v38
	v_exp_f32_e32 v39, v39
	s_waitcnt lgkmcnt(4)
	v_mfma_f32_32x32x16_bf16 v[188:203], v[156:159], v[48:51], v[188:203]
	v_exp_f32_e32 v40, v40
	v_exp_f32_e32 v41, v41
	v_mfma_f32_32x32x16_bf16 v[188:203], v[160:163], v[52:55], v[188:203]
	v_exp_f32_e32 v42, v42
	v_exp_f32_e32 v43, v43
	v_mfma_f32_32x32x16_bf16 v[188:203], v[164:167], v[56:59], v[188:203]
	v_exp_f32_e32 v44, v44
	v_exp_f32_e32 v45, v45
	v_mfma_f32_32x32x16_bf16 v[188:203], v[168:171], v[60:63], v[188:203]
	v_exp_f32_e32 v46, v46
	v_exp_f32_e32 v47, v47
	s_add_i32 s90, s67, 448
	v_add_u32_e32 v84, s90, v107
	v_add_u32_e32 v85, 0, v84
	v_add_u32_e32 v86, 1, v84
	v_add_u32_e32 v87, 2, v84
	v_add_u32_e32 v88, 3, v84
	v_cmp_gt_u32_e64 s[30:31], s98, v85
	v_cmp_gt_u32_e64 s[36:37], s98, v86
	v_cmp_gt_u32_e64 s[78:79], s98, v87
	v_cmp_gt_u32_e64 s[50:51], s98, v88
	v_cndmask_b32_e64 v32, 0, v32, s[30:31]
	v_add_u32_e32 v85, 8, v84
	v_cmp_gt_u32_e64 s[30:31], s98, v85
	v_cndmask_b32_e64 v33, 0, v33, s[36:37]
	v_add_u32_e32 v86, 9, v84
	v_cmp_gt_u32_e64 s[36:37], s98, v86
	v_cndmask_b32_e64 v34, 0, v34, s[78:79]
	v_add_u32_e32 v87, 10, v84
	v_cmp_gt_u32_e64 s[78:79], s98, v87
	v_cndmask_b32_e64 v35, 0, v35, s[50:51]
	v_add_u32_e32 v88, 11, v84
	v_cmp_gt_u32_e64 s[50:51], s98, v88
	v_cndmask_b32_e64 v36, 0, v36, s[30:31]
	v_add_u32_e32 v85, 16, v84
	v_cmp_gt_u32_e64 s[30:31], s98, v85
	v_cndmask_b32_e64 v37, 0, v37, s[36:37]
	v_add_u32_e32 v86, 17, v84
	v_cmp_gt_u32_e64 s[36:37], s98, v86
	v_cndmask_b32_e64 v38, 0, v38, s[78:79]
	v_add_u32_e32 v87, 18, v84
	v_cmp_gt_u32_e64 s[78:79], s98, v87
	v_cndmask_b32_e64 v39, 0, v39, s[50:51]
	v_add_u32_e32 v88, 19, v84
	v_cmp_gt_u32_e64 s[50:51], s98, v88
	v_cndmask_b32_e64 v40, 0, v40, s[30:31]
	v_add_u32_e32 v85, 24, v84
	v_cmp_gt_u32_e64 s[30:31], s98, v85
	v_cndmask_b32_e64 v41, 0, v41, s[36:37]
	v_add_u32_e32 v86, 25, v84
	v_cmp_gt_u32_e64 s[36:37], s98, v86
	v_cndmask_b32_e64 v42, 0, v42, s[78:79]
	v_add_u32_e32 v87, 26, v84
	v_cmp_gt_u32_e64 s[78:79], s98, v87
	v_cndmask_b32_e64 v43, 0, v43, s[50:51]
	v_add_u32_e32 v88, 27, v84
	v_cmp_gt_u32_e64 s[50:51], s98, v88
	v_nop
	v_cndmask_b32_e64 v44, 0, v44, s[30:31]
	v_cndmask_b32_e64 v45, 0, v45, s[36:37]
	v_cndmask_b32_e64 v46, 0, v46, s[78:79]
	v_cndmask_b32_e64 v47, 0, v47, s[50:51]
	v_cvt_pk_bf16_f32 v64, v32, v33
	v_cvt_pk_bf16_f32 v65, v34, v35
	v_cvt_pk_bf16_f32 v66, v36, v37
	v_cvt_pk_bf16_f32 v67, v38, v39
	v_cvt_pk_bf16_f32 v68, v40, v41
	v_cvt_pk_bf16_f32 v69, v42, v43
	v_cvt_pk_bf16_f32 v70, v44, v45
	v_cvt_pk_bf16_f32 v71, v46, v47
	v_pk_add_f32 v[232:233], v[232:233], v[32:33]
	v_pk_add_f32 v[232:233], v[232:233], v[34:35]
	v_pk_add_f32 v[232:233], v[232:233], v[36:37]
	v_pk_add_f32 v[232:233], v[232:233], v[38:39]
	v_pk_add_f32 v[232:233], v[232:233], v[40:41]
	v_pk_add_f32 v[232:233], v[232:233], v[42:43]
	v_pk_add_f32 v[232:233], v[232:233], v[44:45]
	v_pk_add_f32 v[232:233], v[232:233], v[46:47]
	ds_read2_b32 v[32:33], v115 offset0:136 offset1:137
	ds_read2_b32 v[34:35], v115 offset0:138 offset1:139
	ds_read2_b32 v[36:37], v115 offset0:144 offset1:145
	ds_read2_b32 v[38:39], v115 offset0:146 offset1:147
	ds_read2_b32 v[40:41], v115 offset0:153 offset1:154
	ds_read2_b32 v[42:43], v115 offset0:155 offset1:156
	ds_read2_b32 v[44:45], v115 offset0:161 offset1:162
	ds_read2_b32 v[46:47], v115 offset0:163 offset1:164
	v_mfma_f32_32x32x16_bf16 v[0:15], v[64:67], v[72:75], v[0:15]
	v_mfma_f32_32x32x16_bf16 v[16:31], v[64:67], v[76:79], v[16:31]
	v_mfma_f32_32x32x16_bf16 v[0:15], v[68:71], v[220:223], v[0:15]
	v_mfma_f32_32x32x16_bf16 v[16:31], v[68:71], v[224:227], v[16:31]
	s_add_i32 s90, s67, 544
	v_add_u32_e32 v80, s90, v235
	v_add_u32_e32 v83, s90, v236
	v_add_u32_e32 v99, s90, v237
	v_add_u32_e32 v253, s90, v238
	v_add_u32_e32 v254, s90, v100
	v_add_u32_e32 v255, s90, v149
	v_med3_i32 v80, v80, 0, s99
	v_med3_i32 v83, v83, 0, s99
	v_med3_i32 v99, v99, 0, s99
	v_med3_i32 v253, v253, 0, s99
	v_med3_i32 v254, v254, 0, s99
	v_med3_i32 v255, v255, 0, s99
	v_mad_u32_u24 v80, v80, s100, v252
	v_mad_u32_u24 v83, v83, s100, v252
	v_mad_u32_u24 v99, v99, s100, v252
	v_mad_u32_u24 v253, v253, s100, v252
	v_mad_u32_u24 v254, v254, s100, v153
	v_mad_u32_u24 v255, v255, s100, v153
	global_load_dwordx4 v[156:159], v80, s[82:83]
	global_load_dwordx4 v[160:163], v83, s[82:83]
	global_load_dwordx4 v[164:167], v99, s[82:83]
	global_load_dwordx4 v[168:171], v253, s[82:83]
	global_load_dwordx4 v[172:175], v254, s[82:83] offset:768
	global_load_dwordx4 v[176:179], v255, s[82:83] offset:768
	global_load_dwordx4 v[180:183], v254, s[82:83] offset:832
	global_load_dwordx4 v[184:187], v255, s[82:83] offset:832
	ds_read_b64_tr_b16 v[72:73], v231
	ds_read_b64_tr_b16 v[74:75], v231 offset:512
	ds_read_b64_tr_b16 v[76:77], v231 offset:2048
	ds_read_b64_tr_b16 v[78:79], v231 offset:2560
	ds_read_b64_tr_b16 v[220:221], v231 offset:1024
	ds_read_b64_tr_b16 v[222:223], v231 offset:1536
	ds_read_b64_tr_b16 v[224:225], v231 offset:3072
	ds_read_b64_tr_b16 v[226:227], v231 offset:3584
	v_exp_f32_e32 v188, v188
	v_exp_f32_e32 v189, v189
	v_exp_f32_e32 v190, v190
	v_exp_f32_e32 v191, v191
	s_waitcnt vmcnt(8)
	ds_write_b128 v247, v[116:119]
	ds_write_b128 v247, v[120:123] offset:1024
	ds_write_b128 v247, v[124:127] offset:2048
	ds_write_b128 v247, v[128:131] offset:3072
	ds_read_b128 v[116:119], v248
	ds_read_b128 v[120:123], v249
	ds_read_b128 v[124:127], v250
	ds_read_b128 v[128:131], v251
	ds_write_b128 v112, v[132:135]
	ds_write_b128 v112, v[136:139] offset:1024
	ds_write_b128 v112, v[140:143] offset:2048
	ds_write_b128 v112, v[144:147] offset:3072
	v_exp_f32_e32 v192, v192
	v_exp_f32_e32 v193, v193
	v_exp_f32_e32 v194, v194
	v_exp_f32_e32 v195, v195
	s_waitcnt lgkmcnt(4)
	v_mfma_f32_32x32x16_bf16 v[32:47], v[116:119], v[48:51], v[32:47]
	v_exp_f32_e32 v196, v196
	v_exp_f32_e32 v197, v197
	v_mfma_f32_32x32x16_bf16 v[32:47], v[120:123], v[52:55], v[32:47]
	v_exp_f32_e32 v198, v198
	v_exp_f32_e32 v199, v199
	v_mfma_f32_32x32x16_bf16 v[32:47], v[124:127], v[56:59], v[32:47]
	v_exp_f32_e32 v200, v200
	v_exp_f32_e32 v201, v201
	v_mfma_f32_32x32x16_bf16 v[32:47], v[128:131], v[60:63], v[32:47]
	v_exp_f32_e32 v202, v202
	v_exp_f32_e32 v203, v203
	s_add_i32 s90, s67, 480
	v_add_u32_e32 v84, s90, v107
	v_add_u32_e32 v85, 0, v84
	v_add_u32_e32 v86, 1, v84
	v_add_u32_e32 v87, 2, v84
	v_add_u32_e32 v88, 3, v84
	v_cmp_gt_u32_e64 s[30:31], s98, v85
	v_cmp_gt_u32_e64 s[36:37], s98, v86
	v_cmp_gt_u32_e64 s[78:79], s98, v87
	v_cmp_gt_u32_e64 s[50:51], s98, v88
	v_cndmask_b32_e64 v188, 0, v188, s[30:31]
	v_add_u32_e32 v85, 8, v84
	v_cmp_gt_u32_e64 s[30:31], s98, v85
	v_cndmask_b32_e64 v189, 0, v189, s[36:37]
	v_add_u32_e32 v86, 9, v84
	v_cmp_gt_u32_e64 s[36:37], s98, v86
	v_cndmask_b32_e64 v190, 0, v190, s[78:79]
	v_add_u32_e32 v87, 10, v84
	v_cmp_gt_u32_e64 s[78:79], s98, v87
	v_cndmask_b32_e64 v191, 0, v191, s[50:51]
	v_add_u32_e32 v88, 11, v84
	v_cmp_gt_u32_e64 s[50:51], s98, v88
	v_cndmask_b32_e64 v192, 0, v192, s[30:31]
	v_add_u32_e32 v85, 16, v84
	v_cmp_gt_u32_e64 s[30:31], s98, v85
	v_cndmask_b32_e64 v193, 0, v193, s[36:37]
	v_add_u32_e32 v86, 17, v84
	v_cmp_gt_u32_e64 s[36:37], s98, v86
	v_cndmask_b32_e64 v194, 0, v194, s[78:79]
	v_add_u32_e32 v87, 18, v84
	v_cmp_gt_u32_e64 s[78:79], s98, v87
	v_cndmask_b32_e64 v195, 0, v195, s[50:51]
	v_add_u32_e32 v88, 19, v84
	v_cmp_gt_u32_e64 s[50:51], s98, v88
	v_cndmask_b32_e64 v196, 0, v196, s[30:31]
	v_add_u32_e32 v85, 24, v84
	v_cmp_gt_u32_e64 s[30:31], s98, v85
	v_cndmask_b32_e64 v197, 0, v197, s[36:37]
	v_add_u32_e32 v86, 25, v84
	v_cmp_gt_u32_e64 s[36:37], s98, v86
	v_cndmask_b32_e64 v198, 0, v198, s[78:79]
	v_add_u32_e32 v87, 26, v84
	v_cmp_gt_u32_e64 s[78:79], s98, v87
	v_cndmask_b32_e64 v199, 0, v199, s[50:51]
	v_add_u32_e32 v88, 27, v84
	v_cmp_gt_u32_e64 s[50:51], s98, v88
	v_nop
	v_cndmask_b32_e64 v200, 0, v200, s[30:31]
	v_cndmask_b32_e64 v201, 0, v201, s[36:37]
	v_cndmask_b32_e64 v202, 0, v202, s[78:79]
	v_cndmask_b32_e64 v203, 0, v203, s[50:51]
	v_cvt_pk_bf16_f32 v64, v188, v189
	v_cvt_pk_bf16_f32 v65, v190, v191
	v_cvt_pk_bf16_f32 v66, v192, v193
	v_cvt_pk_bf16_f32 v67, v194, v195
	v_cvt_pk_bf16_f32 v68, v196, v197
	v_cvt_pk_bf16_f32 v69, v198, v199
	v_cvt_pk_bf16_f32 v70, v200, v201
	v_cvt_pk_bf16_f32 v71, v202, v203
	v_pk_add_f32 v[232:233], v[232:233], v[188:189]
	v_pk_add_f32 v[232:233], v[232:233], v[190:191]
	v_pk_add_f32 v[232:233], v[232:233], v[192:193]
	v_pk_add_f32 v[232:233], v[232:233], v[194:195]
	v_pk_add_f32 v[232:233], v[232:233], v[196:197]
	v_pk_add_f32 v[232:233], v[232:233], v[198:199]
	v_pk_add_f32 v[232:233], v[232:233], v[200:201]
	v_pk_add_f32 v[232:233], v[232:233], v[202:203]
	ds_read2_b32 v[188:189], v115 offset0:170 offset1:171
	ds_read2_b32 v[190:191], v115 offset0:172 offset1:173
	ds_read2_b32 v[192:193], v115 offset0:178 offset1:179
	ds_read2_b32 v[194:195], v115 offset0:180 offset1:181
	ds_read2_b32 v[196:197], v115 offset0:187 offset1:188
	ds_read2_b32 v[198:199], v115 offset0:189 offset1:190
	ds_read2_b32 v[200:201], v115 offset0:195 offset1:196
	ds_read2_b32 v[202:203], v115 offset0:197 offset1:198
	v_mfma_f32_32x32x16_bf16 v[0:15], v[64:67], v[72:75], v[0:15]
	v_mfma_f32_32x32x16_bf16 v[16:31], v[64:67], v[76:79], v[16:31]
	v_mfma_f32_32x32x16_bf16 v[0:15], v[68:71], v[220:223], v[0:15]
	v_mfma_f32_32x32x16_bf16 v[16:31], v[68:71], v[224:227], v[16:31]
	s_add_i32 s90, s67, -256
	v_add_u32_e32 v80, s90, v239
	v_add_u32_e32 v83, s90, v240
	v_add_u32_e32 v99, s90, v241
	v_add_u32_e32 v253, s90, v242
	v_add_u32_e32 v254, s90, v101
	v_add_u32_e32 v255, s90, v150
	v_med3_i32 v80, v80, 0, s99
	v_med3_i32 v83, v83, 0, s99
	v_med3_i32 v99, v99, 0, s99
	v_med3_i32 v253, v253, 0, s99
	v_med3_i32 v254, v254, 0, s99
	v_med3_i32 v255, v255, 0, s99
	v_mad_u32_u24 v80, v80, s100, v252
	v_mad_u32_u24 v83, v83, s100, v252
	v_mad_u32_u24 v99, v99, s100, v252
	v_mad_u32_u24 v253, v253, s100, v252
	v_mad_u32_u24 v254, v254, s100, v153
	v_mad_u32_u24 v255, v255, s100, v153
	global_load_dwordx4 v[116:119], v80, s[82:83]
	global_load_dwordx4 v[120:123], v83, s[82:83]
	global_load_dwordx4 v[124:127], v99, s[82:83]
	global_load_dwordx4 v[128:131], v253, s[82:83]
	global_load_dwordx4 v[132:135], v254, s[82:83] offset:768
	global_load_dwordx4 v[136:139], v255, s[82:83] offset:768
	global_load_dwordx4 v[140:143], v254, s[82:83] offset:832
	global_load_dwordx4 v[144:147], v255, s[82:83] offset:832
	ds_read_b64_tr_b16 v[72:73], v231
	ds_read_b64_tr_b16 v[74:75], v231 offset:512
	ds_read_b64_tr_b16 v[76:77], v231 offset:2048
	ds_read_b64_tr_b16 v[78:79], v231 offset:2560
	ds_read_b64_tr_b16 v[220:221], v231 offset:1024
	ds_read_b64_tr_b16 v[222:223], v231 offset:1536
	ds_read_b64_tr_b16 v[224:225], v231 offset:3072
	ds_read_b64_tr_b16 v[226:227], v231 offset:3584
	v_exp_f32_e32 v32, v32
	v_exp_f32_e32 v33, v33
	v_exp_f32_e32 v34, v34
	v_exp_f32_e32 v35, v35
	s_waitcnt vmcnt(8)
	ds_write_b128 v247, v[156:159]
	ds_write_b128 v247, v[160:163] offset:1024
	ds_write_b128 v247, v[164:167] offset:2048
	ds_write_b128 v247, v[168:171] offset:3072
	ds_read_b128 v[156:159], v248
	ds_read_b128 v[160:163], v249
	ds_read_b128 v[164:167], v250
	ds_read_b128 v[168:171], v251
	ds_write_b128 v112, v[172:175]
	ds_write_b128 v112, v[176:179] offset:1024
	ds_write_b128 v112, v[180:183] offset:2048
	ds_write_b128 v112, v[184:187] offset:3072
	v_exp_f32_e32 v36, v36
	v_exp_f32_e32 v37, v37
	v_exp_f32_e32 v38, v38
	v_exp_f32_e32 v39, v39
	s_waitcnt lgkmcnt(4)
	v_mfma_f32_32x32x16_bf16 v[188:203], v[156:159], v[48:51], v[188:203]
	v_exp_f32_e32 v40, v40
	v_exp_f32_e32 v41, v41
	v_mfma_f32_32x32x16_bf16 v[188:203], v[160:163], v[52:55], v[188:203]
	v_exp_f32_e32 v42, v42
	v_exp_f32_e32 v43, v43
	v_mfma_f32_32x32x16_bf16 v[188:203], v[164:167], v[56:59], v[188:203]
	v_exp_f32_e32 v44, v44
	v_exp_f32_e32 v45, v45
	v_mfma_f32_32x32x16_bf16 v[188:203], v[168:171], v[60:63], v[188:203]
	v_exp_f32_e32 v46, v46
	v_exp_f32_e32 v47, v47
	s_add_i32 s90, s67, 512
	v_add_u32_e32 v84, s90, v107
	v_add_u32_e32 v85, 0, v84
	v_add_u32_e32 v86, 1, v84
	v_add_u32_e32 v87, 2, v84
	v_add_u32_e32 v88, 3, v84
	v_cmp_gt_u32_e64 s[30:31], s98, v85
	v_cmp_gt_u32_e64 s[36:37], s98, v86
	v_cmp_gt_u32_e64 s[78:79], s98, v87
	v_cmp_gt_u32_e64 s[50:51], s98, v88
	v_cndmask_b32_e64 v32, 0, v32, s[30:31]
	v_add_u32_e32 v85, 8, v84
	v_cmp_gt_u32_e64 s[30:31], s98, v85
	v_cndmask_b32_e64 v33, 0, v33, s[36:37]
	v_add_u32_e32 v86, 9, v84
	v_cmp_gt_u32_e64 s[36:37], s98, v86
	v_cndmask_b32_e64 v34, 0, v34, s[78:79]
	v_add_u32_e32 v87, 10, v84
	v_cmp_gt_u32_e64 s[78:79], s98, v87
	v_cndmask_b32_e64 v35, 0, v35, s[50:51]
	v_add_u32_e32 v88, 11, v84
	v_cmp_gt_u32_e64 s[50:51], s98, v88
	v_cndmask_b32_e64 v36, 0, v36, s[30:31]
	v_add_u32_e32 v85, 16, v84
	v_cmp_gt_u32_e64 s[30:31], s98, v85
	v_cndmask_b32_e64 v37, 0, v37, s[36:37]
	v_add_u32_e32 v86, 17, v84
	v_cmp_gt_u32_e64 s[36:37], s98, v86
	v_cndmask_b32_e64 v38, 0, v38, s[78:79]
	v_add_u32_e32 v87, 18, v84
	v_cmp_gt_u32_e64 s[78:79], s98, v87
	v_cndmask_b32_e64 v39, 0, v39, s[50:51]
	v_add_u32_e32 v88, 19, v84
	v_cmp_gt_u32_e64 s[50:51], s98, v88
	v_cndmask_b32_e64 v40, 0, v40, s[30:31]
	v_add_u32_e32 v85, 24, v84
	v_cmp_gt_u32_e64 s[30:31], s98, v85
	v_cndmask_b32_e64 v41, 0, v41, s[36:37]
	v_add_u32_e32 v86, 25, v84
	v_cmp_gt_u32_e64 s[36:37], s98, v86
	v_cndmask_b32_e64 v42, 0, v42, s[78:79]
	v_add_u32_e32 v87, 26, v84
	v_cmp_gt_u32_e64 s[78:79], s98, v87
	v_cndmask_b32_e64 v43, 0, v43, s[50:51]
	v_add_u32_e32 v88, 27, v84
	v_cmp_gt_u32_e64 s[50:51], s98, v88
	v_nop
	v_cndmask_b32_e64 v44, 0, v44, s[30:31]
	v_cndmask_b32_e64 v45, 0, v45, s[36:37]
	v_cndmask_b32_e64 v46, 0, v46, s[78:79]
	v_cndmask_b32_e64 v47, 0, v47, s[50:51]
	v_cvt_pk_bf16_f32 v64, v32, v33
	v_cvt_pk_bf16_f32 v65, v34, v35
	v_cvt_pk_bf16_f32 v66, v36, v37
	v_cvt_pk_bf16_f32 v67, v38, v39
	v_cvt_pk_bf16_f32 v68, v40, v41
	v_cvt_pk_bf16_f32 v69, v42, v43
	v_cvt_pk_bf16_f32 v70, v44, v45
	v_cvt_pk_bf16_f32 v71, v46, v47
	v_pk_add_f32 v[232:233], v[232:233], v[32:33]
	v_pk_add_f32 v[232:233], v[232:233], v[34:35]
	v_pk_add_f32 v[232:233], v[232:233], v[36:37]
	v_pk_add_f32 v[232:233], v[232:233], v[38:39]
	v_pk_add_f32 v[232:233], v[232:233], v[40:41]
	v_pk_add_f32 v[232:233], v[232:233], v[42:43]
	v_pk_add_f32 v[232:233], v[232:233], v[44:45]
	v_pk_add_f32 v[232:233], v[232:233], v[46:47]
	v_mov_b32_e32 v115, v229
	ds_read2_b32 v[32:33], v115 offset0:0 offset1:1
	ds_read2_b32 v[34:35], v115 offset0:2 offset1:3
	ds_read2_b32 v[36:37], v115 offset0:8 offset1:9
	ds_read2_b32 v[38:39], v115 offset0:10 offset1:11
	ds_read2_b32 v[40:41], v115 offset0:16 offset1:17
	ds_read2_b32 v[42:43], v115 offset0:18 offset1:19
	ds_read2_b32 v[44:45], v115 offset0:24 offset1:25
	ds_read2_b32 v[46:47], v115 offset0:26 offset1:27
	v_mfma_f32_32x32x16_bf16 v[0:15], v[64:67], v[72:75], v[0:15]
	v_mfma_f32_32x32x16_bf16 v[16:31], v[64:67], v[76:79], v[16:31]
	v_mfma_f32_32x32x16_bf16 v[0:15], v[68:71], v[220:223], v[0:15]
	v_mfma_f32_32x32x16_bf16 v[16:31], v[68:71], v[224:227], v[16:31]
	s_add_i32 s90, s67, -128
	v_add_u32_e32 v80, s90, v239
	v_add_u32_e32 v83, s90, v240
	v_add_u32_e32 v99, s90, v241
	v_add_u32_e32 v253, s90, v242
	v_add_u32_e32 v254, s90, v101
	v_add_u32_e32 v255, s90, v150
	v_med3_i32 v80, v80, 0, s99
	v_med3_i32 v83, v83, 0, s99
	v_med3_i32 v99, v99, 0, s99
	v_med3_i32 v253, v253, 0, s99
	v_med3_i32 v254, v254, 0, s99
	v_med3_i32 v255, v255, 0, s99
	v_mad_u32_u24 v80, v80, s100, v252
	v_mad_u32_u24 v83, v83, s100, v252
	v_mad_u32_u24 v99, v99, s100, v252
	v_mad_u32_u24 v253, v253, s100, v252
	v_mad_u32_u24 v254, v254, s100, v153
	v_mad_u32_u24 v255, v255, s100, v153
	global_load_dwordx4 v[156:159], v80, s[82:83]
	global_load_dwordx4 v[160:163], v83, s[82:83]
	global_load_dwordx4 v[164:167], v99, s[82:83]
	global_load_dwordx4 v[168:171], v253, s[82:83]
	global_load_dwordx4 v[172:175], v254, s[82:83] offset:768
	global_load_dwordx4 v[176:179], v255, s[82:83] offset:768
	global_load_dwordx4 v[180:183], v254, s[82:83] offset:832
	global_load_dwordx4 v[184:187], v255, s[82:83] offset:832
	ds_read_b64_tr_b16 v[72:73], v231
	ds_read_b64_tr_b16 v[74:75], v231 offset:512
	ds_read_b64_tr_b16 v[76:77], v231 offset:2048
	ds_read_b64_tr_b16 v[78:79], v231 offset:2560
	ds_read_b64_tr_b16 v[220:221], v231 offset:1024
	ds_read_b64_tr_b16 v[222:223], v231 offset:1536
	ds_read_b64_tr_b16 v[224:225], v231 offset:3072
	ds_read_b64_tr_b16 v[226:227], v231 offset:3584
	v_exp_f32_e32 v188, v188
	v_exp_f32_e32 v189, v189
	v_exp_f32_e32 v190, v190
	v_exp_f32_e32 v191, v191
	s_waitcnt vmcnt(8)
	ds_write_b128 v247, v[116:119]
	ds_write_b128 v247, v[120:123] offset:1024
	ds_write_b128 v247, v[124:127] offset:2048
	ds_write_b128 v247, v[128:131] offset:3072
	ds_read_b128 v[116:119], v248
	ds_read_b128 v[120:123], v249
	ds_read_b128 v[124:127], v250
	ds_read_b128 v[128:131], v251
	ds_write_b128 v112, v[132:135]
	ds_write_b128 v112, v[136:139] offset:1024
	ds_write_b128 v112, v[140:143] offset:2048
	ds_write_b128 v112, v[144:147] offset:3072
	v_exp_f32_e32 v192, v192
	v_exp_f32_e32 v193, v193
	v_exp_f32_e32 v194, v194
	v_exp_f32_e32 v195, v195
	s_waitcnt lgkmcnt(4)
	v_mfma_f32_32x32x16_bf16 v[32:47], v[116:119], v[48:51], v[32:47]
	v_exp_f32_e32 v196, v196
	v_exp_f32_e32 v197, v197
	v_mfma_f32_32x32x16_bf16 v[32:47], v[120:123], v[52:55], v[32:47]
	v_exp_f32_e32 v198, v198
	v_exp_f32_e32 v199, v199
	v_mfma_f32_32x32x16_bf16 v[32:47], v[124:127], v[56:59], v[32:47]
	v_exp_f32_e32 v200, v200
	v_exp_f32_e32 v201, v201
	v_mfma_f32_32x32x16_bf16 v[32:47], v[128:131], v[60:63], v[32:47]
	v_exp_f32_e32 v202, v202
	v_exp_f32_e32 v203, v203
	s_add_i32 s90, s67, 544
	v_add_u32_e32 v84, s90, v107
	v_add_u32_e32 v85, 0, v84
	v_add_u32_e32 v86, 1, v84
	v_add_u32_e32 v87, 2, v84
	v_add_u32_e32 v88, 3, v84
	v_cmp_gt_u32_e64 s[30:31], s98, v85
	v_cmp_gt_u32_e64 s[36:37], s98, v86
	v_cmp_gt_u32_e64 s[78:79], s98, v87
	v_cmp_gt_u32_e64 s[50:51], s98, v88
	v_cndmask_b32_e64 v188, 0, v188, s[30:31]
	v_add_u32_e32 v85, 8, v84
	v_cmp_gt_u32_e64 s[30:31], s98, v85
	v_cndmask_b32_e64 v189, 0, v189, s[36:37]
	v_add_u32_e32 v86, 9, v84
	v_cmp_gt_u32_e64 s[36:37], s98, v86
	v_cndmask_b32_e64 v190, 0, v190, s[78:79]
	v_add_u32_e32 v87, 10, v84
	v_cmp_gt_u32_e64 s[78:79], s98, v87
	v_cndmask_b32_e64 v191, 0, v191, s[50:51]
	v_add_u32_e32 v88, 11, v84
	v_cmp_gt_u32_e64 s[50:51], s98, v88
	v_cndmask_b32_e64 v192, 0, v192, s[30:31]
	v_add_u32_e32 v85, 16, v84
	v_cmp_gt_u32_e64 s[30:31], s98, v85
	v_cndmask_b32_e64 v193, 0, v193, s[36:37]
	v_add_u32_e32 v86, 17, v84
	v_cmp_gt_u32_e64 s[36:37], s98, v86
	v_cndmask_b32_e64 v194, 0, v194, s[78:79]
	v_add_u32_e32 v87, 18, v84
	v_cmp_gt_u32_e64 s[78:79], s98, v87
	v_cndmask_b32_e64 v195, 0, v195, s[50:51]
	v_add_u32_e32 v88, 19, v84
	v_cmp_gt_u32_e64 s[50:51], s98, v88
	v_cndmask_b32_e64 v196, 0, v196, s[30:31]
	v_add_u32_e32 v85, 24, v84
	v_cmp_gt_u32_e64 s[30:31], s98, v85
	v_cndmask_b32_e64 v197, 0, v197, s[36:37]
	v_add_u32_e32 v86, 25, v84
	v_cmp_gt_u32_e64 s[36:37], s98, v86
	v_cndmask_b32_e64 v198, 0, v198, s[78:79]
	v_add_u32_e32 v87, 26, v84
	v_cmp_gt_u32_e64 s[78:79], s98, v87
	v_cndmask_b32_e64 v199, 0, v199, s[50:51]
	v_add_u32_e32 v88, 27, v84
	v_cmp_gt_u32_e64 s[50:51], s98, v88
	v_nop
	v_cndmask_b32_e64 v200, 0, v200, s[30:31]
	v_cndmask_b32_e64 v201, 0, v201, s[36:37]
	v_cndmask_b32_e64 v202, 0, v202, s[78:79]
	v_cndmask_b32_e64 v203, 0, v203, s[50:51]
	v_cvt_pk_bf16_f32 v64, v188, v189
	v_cvt_pk_bf16_f32 v65, v190, v191
	v_cvt_pk_bf16_f32 v66, v192, v193
	v_cvt_pk_bf16_f32 v67, v194, v195
	v_cvt_pk_bf16_f32 v68, v196, v197
	v_cvt_pk_bf16_f32 v69, v198, v199
	v_cvt_pk_bf16_f32 v70, v200, v201
	v_cvt_pk_bf16_f32 v71, v202, v203
	v_pk_add_f32 v[232:233], v[232:233], v[188:189]
	v_pk_add_f32 v[232:233], v[232:233], v[190:191]
	v_pk_add_f32 v[232:233], v[232:233], v[192:193]
	v_pk_add_f32 v[232:233], v[232:233], v[194:195]
	v_pk_add_f32 v[232:233], v[232:233], v[196:197]
	v_pk_add_f32 v[232:233], v[232:233], v[198:199]
	v_pk_add_f32 v[232:233], v[232:233], v[200:201]
	v_pk_add_f32 v[232:233], v[232:233], v[202:203]
	ds_read2_b32 v[188:189], v115 offset0:32 offset1:33
	ds_read2_b32 v[190:191], v115 offset0:34 offset1:35
	ds_read2_b32 v[192:193], v115 offset0:40 offset1:41
	ds_read2_b32 v[194:195], v115 offset0:42 offset1:43
	ds_read2_b32 v[196:197], v115 offset0:48 offset1:49
	ds_read2_b32 v[198:199], v115 offset0:50 offset1:51
	ds_read2_b32 v[200:201], v115 offset0:56 offset1:57
	ds_read2_b32 v[202:203], v115 offset0:58 offset1:59
	v_mfma_f32_32x32x16_bf16 v[0:15], v[64:67], v[72:75], v[0:15]
	v_mfma_f32_32x32x16_bf16 v[16:31], v[64:67], v[76:79], v[16:31]
	v_mfma_f32_32x32x16_bf16 v[0:15], v[68:71], v[220:223], v[0:15]
	v_mfma_f32_32x32x16_bf16 v[16:31], v[68:71], v[224:227], v[16:31]
	s_add_i32 s90, s67, 0
	v_add_u32_e32 v80, s90, v239
	v_add_u32_e32 v83, s90, v240
	v_add_u32_e32 v99, s90, v241
	v_add_u32_e32 v253, s90, v242
	v_add_u32_e32 v254, s90, v101
	v_add_u32_e32 v255, s90, v150
	v_med3_i32 v80, v80, 0, s99
	v_med3_i32 v83, v83, 0, s99
	v_med3_i32 v99, v99, 0, s99
	v_med3_i32 v253, v253, 0, s99
	v_med3_i32 v254, v254, 0, s99
	v_med3_i32 v255, v255, 0, s99
	v_mad_u32_u24 v80, v80, s100, v252
	v_mad_u32_u24 v83, v83, s100, v252
	v_mad_u32_u24 v99, v99, s100, v252
	v_mad_u32_u24 v253, v253, s100, v252
	v_mad_u32_u24 v254, v254, s100, v153
	v_mad_u32_u24 v255, v255, s100, v153
	global_load_dwordx4 v[116:119], v80, s[82:83]
	global_load_dwordx4 v[120:123], v83, s[82:83]
	global_load_dwordx4 v[124:127], v99, s[82:83]
	global_load_dwordx4 v[128:131], v253, s[82:83]
	global_load_dwordx4 v[132:135], v254, s[82:83] offset:768
	global_load_dwordx4 v[136:139], v255, s[82:83] offset:768
	global_load_dwordx4 v[140:143], v254, s[82:83] offset:832
	global_load_dwordx4 v[144:147], v255, s[82:83] offset:832
	ds_read_b64_tr_b16 v[72:73], v231
	ds_read_b64_tr_b16 v[74:75], v231 offset:512
	ds_read_b64_tr_b16 v[76:77], v231 offset:2048
	ds_read_b64_tr_b16 v[78:79], v231 offset:2560
	ds_read_b64_tr_b16 v[220:221], v231 offset:1024
	ds_read_b64_tr_b16 v[222:223], v231 offset:1536
	ds_read_b64_tr_b16 v[224:225], v231 offset:3072
	ds_read_b64_tr_b16 v[226:227], v231 offset:3584
	v_exp_f32_e32 v32, v32
	v_exp_f32_e32 v33, v33
	v_exp_f32_e32 v34, v34
	v_exp_f32_e32 v35, v35
	s_waitcnt vmcnt(8)
	ds_write_b128 v247, v[156:159]
	ds_write_b128 v247, v[160:163] offset:1024
	ds_write_b128 v247, v[164:167] offset:2048
	ds_write_b128 v247, v[168:171] offset:3072
	ds_read_b128 v[156:159], v248
	ds_read_b128 v[160:163], v249
	ds_read_b128 v[164:167], v250
	ds_read_b128 v[168:171], v251
	ds_write_b128 v112, v[172:175]
	ds_write_b128 v112, v[176:179] offset:1024
	ds_write_b128 v112, v[180:183] offset:2048
	ds_write_b128 v112, v[184:187] offset:3072
	v_exp_f32_e32 v36, v36
	v_exp_f32_e32 v37, v37
	v_exp_f32_e32 v38, v38
	v_exp_f32_e32 v39, v39
	s_waitcnt lgkmcnt(4)
	v_mfma_f32_32x32x16_bf16 v[188:203], v[156:159], v[48:51], v[188:203]
	v_exp_f32_e32 v40, v40
	v_exp_f32_e32 v41, v41
	v_mfma_f32_32x32x16_bf16 v[188:203], v[160:163], v[52:55], v[188:203]
	v_exp_f32_e32 v42, v42
	v_exp_f32_e32 v43, v43
	v_mfma_f32_32x32x16_bf16 v[188:203], v[164:167], v[56:59], v[188:203]
	v_exp_f32_e32 v44, v44
	v_exp_f32_e32 v45, v45
	v_mfma_f32_32x32x16_bf16 v[188:203], v[168:171], v[60:63], v[188:203]
	v_exp_f32_e32 v46, v46
	v_exp_f32_e32 v47, v47
	s_add_i32 s90, s67, -256
	v_lshlrev_b32_e32 v84, 2, v107
	v_add_u32_e32 v84, s90, v84
	v_add_u32_e32 v85, 0, v84
	v_add_u32_e32 v86, 4, v84
	v_add_u32_e32 v87, 8, v84
	v_add_u32_e32 v88, 12, v84
	v_cmp_gt_u32_e64 s[30:31], s98, v85
	v_cmp_gt_u32_e64 s[36:37], s98, v86
	v_cmp_gt_u32_e64 s[78:79], s98, v87
	v_cmp_gt_u32_e64 s[50:51], s98, v88
	v_cndmask_b32_e64 v32, 0, v32, s[30:31]
	v_add_u32_e32 v85, 32, v84
	v_cmp_gt_u32_e64 s[30:31], s98, v85
	v_cndmask_b32_e64 v33, 0, v33, s[36:37]
	v_add_u32_e32 v86, 36, v84
	v_cmp_gt_u32_e64 s[36:37], s98, v86
	v_cndmask_b32_e64 v34, 0, v34, s[78:79]
	v_add_u32_e32 v87, 40, v84
	v_cmp_gt_u32_e64 s[78:79], s98, v87
	v_cndmask_b32_e64 v35, 0, v35, s[50:51]
	v_add_u32_e32 v88, 44, v84
	v_cmp_gt_u32_e64 s[50:51], s98, v88
	v_cndmask_b32_e64 v36, 0, v36, s[30:31]
	v_add_u32_e32 v85, 64, v84
	v_cmp_gt_u32_e64 s[30:31], s98, v85
	v_cndmask_b32_e64 v37, 0, v37, s[36:37]
	v_add_u32_e32 v86, 68, v84
	v_cmp_gt_u32_e64 s[36:37], s98, v86
	v_cndmask_b32_e64 v38, 0, v38, s[78:79]
	v_add_u32_e32 v87, 72, v84
	v_cmp_gt_u32_e64 s[78:79], s98, v87
	v_cndmask_b32_e64 v39, 0, v39, s[50:51]
	v_add_u32_e32 v88, 76, v84
	v_cmp_gt_u32_e64 s[50:51], s98, v88
	v_cndmask_b32_e64 v40, 0, v40, s[30:31]
	v_add_u32_e32 v85, 96, v84
	v_cmp_gt_u32_e64 s[30:31], s98, v85
	v_cndmask_b32_e64 v41, 0, v41, s[36:37]
	v_add_u32_e32 v86, 100, v84
	v_cmp_gt_u32_e64 s[36:37], s98, v86
	v_cndmask_b32_e64 v42, 0, v42, s[78:79]
	v_add_u32_e32 v87, 104, v84
	v_cmp_gt_u32_e64 s[78:79], s98, v87
	v_cndmask_b32_e64 v43, 0, v43, s[50:51]
	v_add_u32_e32 v88, 108, v84
	v_cmp_gt_u32_e64 s[50:51], s98, v88
	v_nop
	v_cndmask_b32_e64 v44, 0, v44, s[30:31]
	v_cndmask_b32_e64 v45, 0, v45, s[36:37]
	v_cndmask_b32_e64 v46, 0, v46, s[78:79]
	v_cndmask_b32_e64 v47, 0, v47, s[50:51]
	v_cvt_pk_bf16_f32 v64, v32, v33
	v_cvt_pk_bf16_f32 v65, v34, v35
	v_cvt_pk_bf16_f32 v66, v36, v37
	v_cvt_pk_bf16_f32 v67, v38, v39
	v_cvt_pk_bf16_f32 v68, v40, v41
	v_cvt_pk_bf16_f32 v69, v42, v43
	v_cvt_pk_bf16_f32 v70, v44, v45
	v_cvt_pk_bf16_f32 v71, v46, v47
	v_pk_add_f32 v[232:233], v[232:233], v[32:33]
	v_pk_add_f32 v[232:233], v[232:233], v[34:35]
	v_pk_add_f32 v[232:233], v[232:233], v[36:37]
	v_pk_add_f32 v[232:233], v[232:233], v[38:39]
	v_pk_add_f32 v[232:233], v[232:233], v[40:41]
	v_pk_add_f32 v[232:233], v[232:233], v[42:43]
	v_pk_add_f32 v[232:233], v[232:233], v[44:45]
	v_pk_add_f32 v[232:233], v[232:233], v[46:47]
	ds_read2_b32 v[32:33], v115 offset0:64 offset1:65
	ds_read2_b32 v[34:35], v115 offset0:66 offset1:67
	ds_read2_b32 v[36:37], v115 offset0:72 offset1:73
	ds_read2_b32 v[38:39], v115 offset0:74 offset1:75
	ds_read2_b32 v[40:41], v115 offset0:80 offset1:81
	ds_read2_b32 v[42:43], v115 offset0:82 offset1:83
	ds_read2_b32 v[44:45], v115 offset0:88 offset1:89
	ds_read2_b32 v[46:47], v115 offset0:90 offset1:91
	v_mfma_f32_32x32x16_bf16 v[0:15], v[64:67], v[72:75], v[0:15]
	v_mfma_f32_32x32x16_bf16 v[16:31], v[64:67], v[76:79], v[16:31]
	v_mfma_f32_32x32x16_bf16 v[0:15], v[68:71], v[220:223], v[0:15]
	v_mfma_f32_32x32x16_bf16 v[16:31], v[68:71], v[224:227], v[16:31]
	s_add_i32 s90, s67, 128
	v_add_u32_e32 v80, s90, v239
	v_add_u32_e32 v83, s90, v240
	v_add_u32_e32 v99, s90, v241
	v_add_u32_e32 v253, s90, v242
	v_add_u32_e32 v254, s90, v101
	v_add_u32_e32 v255, s90, v150
	v_med3_i32 v80, v80, 0, s99
	v_med3_i32 v83, v83, 0, s99
	v_med3_i32 v99, v99, 0, s99
	v_med3_i32 v253, v253, 0, s99
	v_med3_i32 v254, v254, 0, s99
	v_med3_i32 v255, v255, 0, s99
	v_mad_u32_u24 v80, v80, s100, v252
	v_mad_u32_u24 v83, v83, s100, v252
	v_mad_u32_u24 v99, v99, s100, v252
	v_mad_u32_u24 v253, v253, s100, v252
	v_mad_u32_u24 v254, v254, s100, v153
	v_mad_u32_u24 v255, v255, s100, v153
	global_load_dwordx4 v[156:159], v80, s[82:83]
	global_load_dwordx4 v[160:163], v83, s[82:83]
	global_load_dwordx4 v[164:167], v99, s[82:83]
	global_load_dwordx4 v[168:171], v253, s[82:83]
	global_load_dwordx4 v[172:175], v254, s[82:83] offset:768
	global_load_dwordx4 v[176:179], v255, s[82:83] offset:768
	global_load_dwordx4 v[180:183], v254, s[82:83] offset:832
	global_load_dwordx4 v[184:187], v255, s[82:83] offset:832
	ds_read_b64_tr_b16 v[72:73], v231
	ds_read_b64_tr_b16 v[74:75], v231 offset:512
	ds_read_b64_tr_b16 v[76:77], v231 offset:2048
	ds_read_b64_tr_b16 v[78:79], v231 offset:2560
	ds_read_b64_tr_b16 v[220:221], v231 offset:1024
	ds_read_b64_tr_b16 v[222:223], v231 offset:1536
	ds_read_b64_tr_b16 v[224:225], v231 offset:3072
	ds_read_b64_tr_b16 v[226:227], v231 offset:3584
	v_exp_f32_e32 v188, v188
	v_exp_f32_e32 v189, v189
	v_exp_f32_e32 v190, v190
	v_exp_f32_e32 v191, v191
	s_waitcnt vmcnt(8)
	ds_write_b128 v247, v[116:119]
	ds_write_b128 v247, v[120:123] offset:1024
	ds_write_b128 v247, v[124:127] offset:2048
	ds_write_b128 v247, v[128:131] offset:3072
	ds_read_b128 v[116:119], v248
	ds_read_b128 v[120:123], v249
	ds_read_b128 v[124:127], v250
	ds_read_b128 v[128:131], v251
	ds_write_b128 v112, v[132:135]
	ds_write_b128 v112, v[136:139] offset:1024
	ds_write_b128 v112, v[140:143] offset:2048
	ds_write_b128 v112, v[144:147] offset:3072
	v_exp_f32_e32 v192, v192
	v_exp_f32_e32 v193, v193
	v_exp_f32_e32 v194, v194
	v_exp_f32_e32 v195, v195
	s_waitcnt lgkmcnt(4)
	v_mfma_f32_32x32x16_bf16 v[32:47], v[116:119], v[48:51], v[32:47]
	v_exp_f32_e32 v196, v196
	v_exp_f32_e32 v197, v197
	v_mfma_f32_32x32x16_bf16 v[32:47], v[120:123], v[52:55], v[32:47]
	v_exp_f32_e32 v198, v198
	v_exp_f32_e32 v199, v199
	v_mfma_f32_32x32x16_bf16 v[32:47], v[124:127], v[56:59], v[32:47]
	v_exp_f32_e32 v200, v200
	v_exp_f32_e32 v201, v201
	v_mfma_f32_32x32x16_bf16 v[32:47], v[128:131], v[60:63], v[32:47]
	v_exp_f32_e32 v202, v202
	v_exp_f32_e32 v203, v203
	s_add_i32 s90, s67, -128
	v_lshlrev_b32_e32 v84, 2, v107
	v_add_u32_e32 v84, s90, v84
	v_add_u32_e32 v85, 0, v84
	v_add_u32_e32 v86, 4, v84
	v_add_u32_e32 v87, 8, v84
	v_add_u32_e32 v88, 12, v84
	v_cmp_gt_u32_e64 s[30:31], s98, v85
	v_cmp_gt_u32_e64 s[36:37], s98, v86
	v_cmp_gt_u32_e64 s[78:79], s98, v87
	v_cmp_gt_u32_e64 s[50:51], s98, v88
	v_cndmask_b32_e64 v188, 0, v188, s[30:31]
	v_add_u32_e32 v85, 32, v84
	v_cmp_gt_u32_e64 s[30:31], s98, v85
	v_cndmask_b32_e64 v189, 0, v189, s[36:37]
	v_add_u32_e32 v86, 36, v84
	v_cmp_gt_u32_e64 s[36:37], s98, v86
	v_cndmask_b32_e64 v190, 0, v190, s[78:79]
	v_add_u32_e32 v87, 40, v84
	v_cmp_gt_u32_e64 s[78:79], s98, v87
	v_cndmask_b32_e64 v191, 0, v191, s[50:51]
	v_add_u32_e32 v88, 44, v84
	v_cmp_gt_u32_e64 s[50:51], s98, v88
	v_cndmask_b32_e64 v192, 0, v192, s[30:31]
	v_add_u32_e32 v85, 64, v84
	v_cmp_gt_u32_e64 s[30:31], s98, v85
	v_cndmask_b32_e64 v193, 0, v193, s[36:37]
	v_add_u32_e32 v86, 68, v84
	v_cmp_gt_u32_e64 s[36:37], s98, v86
	v_cndmask_b32_e64 v194, 0, v194, s[78:79]
	v_add_u32_e32 v87, 72, v84
	v_cmp_gt_u32_e64 s[78:79], s98, v87
	v_cndmask_b32_e64 v195, 0, v195, s[50:51]
	v_add_u32_e32 v88, 76, v84
	v_cmp_gt_u32_e64 s[50:51], s98, v88
	v_cndmask_b32_e64 v196, 0, v196, s[30:31]
	v_add_u32_e32 v85, 96, v84
	v_cmp_gt_u32_e64 s[30:31], s98, v85
	v_cndmask_b32_e64 v197, 0, v197, s[36:37]
	v_add_u32_e32 v86, 100, v84
	v_cmp_gt_u32_e64 s[36:37], s98, v86
	v_cndmask_b32_e64 v198, 0, v198, s[78:79]
	v_add_u32_e32 v87, 104, v84
	v_cmp_gt_u32_e64 s[78:79], s98, v87
	v_cndmask_b32_e64 v199, 0, v199, s[50:51]
	v_add_u32_e32 v88, 108, v84
	v_cmp_gt_u32_e64 s[50:51], s98, v88
	v_nop
	v_cndmask_b32_e64 v200, 0, v200, s[30:31]
	v_cndmask_b32_e64 v201, 0, v201, s[36:37]
	v_cndmask_b32_e64 v202, 0, v202, s[78:79]
	v_cndmask_b32_e64 v203, 0, v203, s[50:51]
	v_cvt_pk_bf16_f32 v64, v188, v189
	v_cvt_pk_bf16_f32 v65, v190, v191
	v_cvt_pk_bf16_f32 v66, v192, v193
	v_cvt_pk_bf16_f32 v67, v194, v195
	v_cvt_pk_bf16_f32 v68, v196, v197
	v_cvt_pk_bf16_f32 v69, v198, v199
	v_cvt_pk_bf16_f32 v70, v200, v201
	v_cvt_pk_bf16_f32 v71, v202, v203
	v_pk_add_f32 v[232:233], v[232:233], v[188:189]
	v_pk_add_f32 v[232:233], v[232:233], v[190:191]
	v_pk_add_f32 v[232:233], v[232:233], v[192:193]
	v_pk_add_f32 v[232:233], v[232:233], v[194:195]
	v_pk_add_f32 v[232:233], v[232:233], v[196:197]
	v_pk_add_f32 v[232:233], v[232:233], v[198:199]
	v_pk_add_f32 v[232:233], v[232:233], v[200:201]
	v_pk_add_f32 v[232:233], v[232:233], v[202:203]
	ds_read2_b32 v[188:189], v115 offset0:96 offset1:97
	ds_read2_b32 v[190:191], v115 offset0:98 offset1:99
	ds_read2_b32 v[192:193], v115 offset0:104 offset1:105
	ds_read2_b32 v[194:195], v115 offset0:106 offset1:107
	ds_read2_b32 v[196:197], v115 offset0:112 offset1:113
	ds_read2_b32 v[198:199], v115 offset0:114 offset1:115
	ds_read2_b32 v[200:201], v115 offset0:120 offset1:121
	ds_read2_b32 v[202:203], v115 offset0:122 offset1:123
	v_mfma_f32_32x32x16_bf16 v[0:15], v[64:67], v[72:75], v[0:15]
	v_mfma_f32_32x32x16_bf16 v[16:31], v[64:67], v[76:79], v[16:31]
	v_mfma_f32_32x32x16_bf16 v[0:15], v[68:71], v[220:223], v[0:15]
	v_mfma_f32_32x32x16_bf16 v[16:31], v[68:71], v[224:227], v[16:31]
	s_add_i32 s90, s67, 256
	v_add_u32_e32 v80, s90, v239
	v_add_u32_e32 v83, s90, v240
	v_add_u32_e32 v99, s90, v241
	v_add_u32_e32 v253, s90, v242
	v_add_u32_e32 v254, s90, v101
	v_add_u32_e32 v255, s90, v150
	v_med3_i32 v80, v80, 0, s99
	v_med3_i32 v83, v83, 0, s99
	v_med3_i32 v99, v99, 0, s99
	v_med3_i32 v253, v253, 0, s99
	v_med3_i32 v254, v254, 0, s99
	v_med3_i32 v255, v255, 0, s99
	v_mad_u32_u24 v80, v80, s100, v252
	v_mad_u32_u24 v83, v83, s100, v252
	v_mad_u32_u24 v99, v99, s100, v252
	v_mad_u32_u24 v253, v253, s100, v252
	v_mad_u32_u24 v254, v254, s100, v153
	v_mad_u32_u24 v255, v255, s100, v153
	global_load_dwordx4 v[116:119], v80, s[82:83]
	global_load_dwordx4 v[120:123], v83, s[82:83]
	global_load_dwordx4 v[124:127], v99, s[82:83]
	global_load_dwordx4 v[128:131], v253, s[82:83]
	global_load_dwordx4 v[132:135], v254, s[82:83] offset:768
	global_load_dwordx4 v[136:139], v255, s[82:83] offset:768
	global_load_dwordx4 v[140:143], v254, s[82:83] offset:832
	global_load_dwordx4 v[144:147], v255, s[82:83] offset:832
	ds_read_b64_tr_b16 v[72:73], v231
	ds_read_b64_tr_b16 v[74:75], v231 offset:512
	ds_read_b64_tr_b16 v[76:77], v231 offset:2048
	ds_read_b64_tr_b16 v[78:79], v231 offset:2560
	ds_read_b64_tr_b16 v[220:221], v231 offset:1024
	ds_read_b64_tr_b16 v[222:223], v231 offset:1536
	ds_read_b64_tr_b16 v[224:225], v231 offset:3072
	ds_read_b64_tr_b16 v[226:227], v231 offset:3584
	v_exp_f32_e32 v32, v32
	v_exp_f32_e32 v33, v33
	v_exp_f32_e32 v34, v34
	v_exp_f32_e32 v35, v35
	s_waitcnt vmcnt(8)
	ds_write_b128 v247, v[156:159]
	ds_write_b128 v247, v[160:163] offset:1024
	ds_write_b128 v247, v[164:167] offset:2048
	ds_write_b128 v247, v[168:171] offset:3072
	ds_read_b128 v[156:159], v248
	ds_read_b128 v[160:163], v249
	ds_read_b128 v[164:167], v250
	ds_read_b128 v[168:171], v251
	ds_write_b128 v112, v[172:175]
	ds_write_b128 v112, v[176:179] offset:1024
	ds_write_b128 v112, v[180:183] offset:2048
	ds_write_b128 v112, v[184:187] offset:3072
	v_exp_f32_e32 v36, v36
	v_exp_f32_e32 v37, v37
	v_exp_f32_e32 v38, v38
	v_exp_f32_e32 v39, v39
	s_waitcnt lgkmcnt(4)
	v_mfma_f32_32x32x16_bf16 v[188:203], v[156:159], v[48:51], v[188:203]
	v_exp_f32_e32 v40, v40
	v_exp_f32_e32 v41, v41
	v_mfma_f32_32x32x16_bf16 v[188:203], v[160:163], v[52:55], v[188:203]
	v_exp_f32_e32 v42, v42
	v_exp_f32_e32 v43, v43
	v_mfma_f32_32x32x16_bf16 v[188:203], v[164:167], v[56:59], v[188:203]
	v_exp_f32_e32 v44, v44
	v_exp_f32_e32 v45, v45
	v_mfma_f32_32x32x16_bf16 v[188:203], v[168:171], v[60:63], v[188:203]
	v_exp_f32_e32 v46, v46
	v_exp_f32_e32 v47, v47
	s_add_i32 s90, s67, 0
	v_lshlrev_b32_e32 v84, 2, v107
	v_add_u32_e32 v84, s90, v84
	v_add_u32_e32 v85, 0, v84
	v_add_u32_e32 v86, 4, v84
	v_add_u32_e32 v87, 8, v84
	v_add_u32_e32 v88, 12, v84
	v_cmp_gt_u32_e64 s[30:31], s98, v85
	v_cmp_gt_u32_e64 s[36:37], s98, v86
	v_cmp_gt_u32_e64 s[78:79], s98, v87
	v_cmp_gt_u32_e64 s[50:51], s98, v88
	v_cndmask_b32_e64 v32, 0, v32, s[30:31]
	v_add_u32_e32 v85, 32, v84
	v_cmp_gt_u32_e64 s[30:31], s98, v85
	v_cndmask_b32_e64 v33, 0, v33, s[36:37]
	v_add_u32_e32 v86, 36, v84
	v_cmp_gt_u32_e64 s[36:37], s98, v86
	v_cndmask_b32_e64 v34, 0, v34, s[78:79]
	v_add_u32_e32 v87, 40, v84
	v_cmp_gt_u32_e64 s[78:79], s98, v87
	v_cndmask_b32_e64 v35, 0, v35, s[50:51]
	v_add_u32_e32 v88, 44, v84
	v_cmp_gt_u32_e64 s[50:51], s98, v88
	v_cndmask_b32_e64 v36, 0, v36, s[30:31]
	v_add_u32_e32 v85, 64, v84
	v_cmp_gt_u32_e64 s[30:31], s98, v85
	v_cndmask_b32_e64 v37, 0, v37, s[36:37]
	v_add_u32_e32 v86, 68, v84
	v_cmp_gt_u32_e64 s[36:37], s98, v86
	v_cndmask_b32_e64 v38, 0, v38, s[78:79]
	v_add_u32_e32 v87, 72, v84
	v_cmp_gt_u32_e64 s[78:79], s98, v87
	v_cndmask_b32_e64 v39, 0, v39, s[50:51]
	v_add_u32_e32 v88, 76, v84
	v_cmp_gt_u32_e64 s[50:51], s98, v88
	v_cndmask_b32_e64 v40, 0, v40, s[30:31]
	v_add_u32_e32 v85, 96, v84
	v_cmp_gt_u32_e64 s[30:31], s98, v85
	v_cndmask_b32_e64 v41, 0, v41, s[36:37]
	v_add_u32_e32 v86, 100, v84
	v_cmp_gt_u32_e64 s[36:37], s98, v86
	v_cndmask_b32_e64 v42, 0, v42, s[78:79]
	v_add_u32_e32 v87, 104, v84
	v_cmp_gt_u32_e64 s[78:79], s98, v87
	v_cndmask_b32_e64 v43, 0, v43, s[50:51]
	v_add_u32_e32 v88, 108, v84
	v_cmp_gt_u32_e64 s[50:51], s98, v88
	v_nop
	v_cndmask_b32_e64 v44, 0, v44, s[30:31]
	v_cndmask_b32_e64 v45, 0, v45, s[36:37]
	v_cndmask_b32_e64 v46, 0, v46, s[78:79]
	v_cndmask_b32_e64 v47, 0, v47, s[50:51]
	v_cvt_pk_bf16_f32 v64, v32, v33
	v_cvt_pk_bf16_f32 v65, v34, v35
	v_cvt_pk_bf16_f32 v66, v36, v37
	v_cvt_pk_bf16_f32 v67, v38, v39
	v_cvt_pk_bf16_f32 v68, v40, v41
	v_cvt_pk_bf16_f32 v69, v42, v43
	v_cvt_pk_bf16_f32 v70, v44, v45
	v_cvt_pk_bf16_f32 v71, v46, v47
	v_pk_add_f32 v[232:233], v[232:233], v[32:33]
	v_pk_add_f32 v[232:233], v[232:233], v[34:35]
	v_pk_add_f32 v[232:233], v[232:233], v[36:37]
	v_pk_add_f32 v[232:233], v[232:233], v[38:39]
	v_pk_add_f32 v[232:233], v[232:233], v[40:41]
	v_pk_add_f32 v[232:233], v[232:233], v[42:43]
	v_pk_add_f32 v[232:233], v[232:233], v[44:45]
	v_pk_add_f32 v[232:233], v[232:233], v[46:47]
	ds_read2_b32 v[32:33], v115 offset0:128 offset1:129
	ds_read2_b32 v[34:35], v115 offset0:130 offset1:131
	ds_read2_b32 v[36:37], v115 offset0:136 offset1:137
	ds_read2_b32 v[38:39], v115 offset0:138 offset1:139
	ds_read2_b32 v[40:41], v115 offset0:144 offset1:145
	ds_read2_b32 v[42:43], v115 offset0:146 offset1:147
	ds_read2_b32 v[44:45], v115 offset0:152 offset1:153
	ds_read2_b32 v[46:47], v115 offset0:154 offset1:155
	v_mfma_f32_32x32x16_bf16 v[0:15], v[64:67], v[72:75], v[0:15]
	v_mfma_f32_32x32x16_bf16 v[16:31], v[64:67], v[76:79], v[16:31]
	v_mfma_f32_32x32x16_bf16 v[0:15], v[68:71], v[220:223], v[0:15]
	v_mfma_f32_32x32x16_bf16 v[16:31], v[68:71], v[224:227], v[16:31]
	s_add_i32 s90, s67, 384
	v_add_u32_e32 v80, s90, v239
	v_add_u32_e32 v83, s90, v240
	v_add_u32_e32 v99, s90, v241
	v_add_u32_e32 v253, s90, v242
	v_add_u32_e32 v254, s90, v101
	v_add_u32_e32 v255, s90, v150
	v_med3_i32 v80, v80, 0, s99
	v_med3_i32 v83, v83, 0, s99
	v_med3_i32 v99, v99, 0, s99
	v_med3_i32 v253, v253, 0, s99
	v_med3_i32 v254, v254, 0, s99
	v_med3_i32 v255, v255, 0, s99
	v_mad_u32_u24 v80, v80, s100, v252
	v_mad_u32_u24 v83, v83, s100, v252
	v_mad_u32_u24 v99, v99, s100, v252
	v_mad_u32_u24 v253, v253, s100, v252
	v_mad_u32_u24 v254, v254, s100, v153
	v_mad_u32_u24 v255, v255, s100, v153
	global_load_dwordx4 v[156:159], v80, s[82:83]
	global_load_dwordx4 v[160:163], v83, s[82:83]
	global_load_dwordx4 v[164:167], v99, s[82:83]
	global_load_dwordx4 v[168:171], v253, s[82:83]
	global_load_dwordx4 v[172:175], v254, s[82:83] offset:768
	global_load_dwordx4 v[176:179], v255, s[82:83] offset:768
	global_load_dwordx4 v[180:183], v254, s[82:83] offset:832
	global_load_dwordx4 v[184:187], v255, s[82:83] offset:832
	ds_read_b64_tr_b16 v[72:73], v231
	ds_read_b64_tr_b16 v[74:75], v231 offset:512
	ds_read_b64_tr_b16 v[76:77], v231 offset:2048
	ds_read_b64_tr_b16 v[78:79], v231 offset:2560
	ds_read_b64_tr_b16 v[220:221], v231 offset:1024
	ds_read_b64_tr_b16 v[222:223], v231 offset:1536
	ds_read_b64_tr_b16 v[224:225], v231 offset:3072
	ds_read_b64_tr_b16 v[226:227], v231 offset:3584
	v_exp_f32_e32 v188, v188
	v_exp_f32_e32 v189, v189
	v_exp_f32_e32 v190, v190
	v_exp_f32_e32 v191, v191
	s_waitcnt vmcnt(8)
	ds_write_b128 v247, v[116:119]
	ds_write_b128 v247, v[120:123] offset:1024
	ds_write_b128 v247, v[124:127] offset:2048
	ds_write_b128 v247, v[128:131] offset:3072
	ds_read_b128 v[116:119], v248
	ds_read_b128 v[120:123], v249
	ds_read_b128 v[124:127], v250
	ds_read_b128 v[128:131], v251
	ds_write_b128 v112, v[132:135]
	ds_write_b128 v112, v[136:139] offset:1024
	ds_write_b128 v112, v[140:143] offset:2048
	ds_write_b128 v112, v[144:147] offset:3072
	v_exp_f32_e32 v192, v192
	v_exp_f32_e32 v193, v193
	v_exp_f32_e32 v194, v194
	v_exp_f32_e32 v195, v195
	s_waitcnt lgkmcnt(4)
	v_mfma_f32_32x32x16_bf16 v[32:47], v[116:119], v[48:51], v[32:47]
	v_exp_f32_e32 v196, v196
	v_exp_f32_e32 v197, v197
	v_mfma_f32_32x32x16_bf16 v[32:47], v[120:123], v[52:55], v[32:47]
	v_exp_f32_e32 v198, v198
	v_exp_f32_e32 v199, v199
	v_mfma_f32_32x32x16_bf16 v[32:47], v[124:127], v[56:59], v[32:47]
	v_exp_f32_e32 v200, v200
	v_exp_f32_e32 v201, v201
	v_mfma_f32_32x32x16_bf16 v[32:47], v[128:131], v[60:63], v[32:47]
	v_exp_f32_e32 v202, v202
	v_exp_f32_e32 v203, v203
	s_add_i32 s90, s67, 128
	v_lshlrev_b32_e32 v84, 2, v107
	v_add_u32_e32 v84, s90, v84
	v_add_u32_e32 v85, 0, v84
	v_add_u32_e32 v86, 4, v84
	v_add_u32_e32 v87, 8, v84
	v_add_u32_e32 v88, 12, v84
	v_cmp_gt_u32_e64 s[30:31], s98, v85
	v_cmp_gt_u32_e64 s[36:37], s98, v86
	v_cmp_gt_u32_e64 s[78:79], s98, v87
	v_cmp_gt_u32_e64 s[50:51], s98, v88
	v_cndmask_b32_e64 v188, 0, v188, s[30:31]
	v_add_u32_e32 v85, 32, v84
	v_cmp_gt_u32_e64 s[30:31], s98, v85
	v_cndmask_b32_e64 v189, 0, v189, s[36:37]
	v_add_u32_e32 v86, 36, v84
	v_cmp_gt_u32_e64 s[36:37], s98, v86
	v_cndmask_b32_e64 v190, 0, v190, s[78:79]
	v_add_u32_e32 v87, 40, v84
	v_cmp_gt_u32_e64 s[78:79], s98, v87
	v_cndmask_b32_e64 v191, 0, v191, s[50:51]
	v_add_u32_e32 v88, 44, v84
	v_cmp_gt_u32_e64 s[50:51], s98, v88
	v_cndmask_b32_e64 v192, 0, v192, s[30:31]
	v_add_u32_e32 v85, 64, v84
	v_cmp_gt_u32_e64 s[30:31], s98, v85
	v_cndmask_b32_e64 v193, 0, v193, s[36:37]
	v_add_u32_e32 v86, 68, v84
	v_cmp_gt_u32_e64 s[36:37], s98, v86
	v_cndmask_b32_e64 v194, 0, v194, s[78:79]
	v_add_u32_e32 v87, 72, v84
	v_cmp_gt_u32_e64 s[78:79], s98, v87
	v_cndmask_b32_e64 v195, 0, v195, s[50:51]
	v_add_u32_e32 v88, 76, v84
	v_cmp_gt_u32_e64 s[50:51], s98, v88
	v_cndmask_b32_e64 v196, 0, v196, s[30:31]
	v_add_u32_e32 v85, 96, v84
	v_cmp_gt_u32_e64 s[30:31], s98, v85
	v_cndmask_b32_e64 v197, 0, v197, s[36:37]
	v_add_u32_e32 v86, 100, v84
	v_cmp_gt_u32_e64 s[36:37], s98, v86
	v_cndmask_b32_e64 v198, 0, v198, s[78:79]
	v_add_u32_e32 v87, 104, v84
	v_cmp_gt_u32_e64 s[78:79], s98, v87
	v_cndmask_b32_e64 v199, 0, v199, s[50:51]
	v_add_u32_e32 v88, 108, v84
	v_cmp_gt_u32_e64 s[50:51], s98, v88
	v_nop
	v_cndmask_b32_e64 v200, 0, v200, s[30:31]
	v_cndmask_b32_e64 v201, 0, v201, s[36:37]
	v_cndmask_b32_e64 v202, 0, v202, s[78:79]
	v_cndmask_b32_e64 v203, 0, v203, s[50:51]
	v_cvt_pk_bf16_f32 v64, v188, v189
	v_cvt_pk_bf16_f32 v65, v190, v191
	v_cvt_pk_bf16_f32 v66, v192, v193
	v_cvt_pk_bf16_f32 v67, v194, v195
	v_cvt_pk_bf16_f32 v68, v196, v197
	v_cvt_pk_bf16_f32 v69, v198, v199
	v_cvt_pk_bf16_f32 v70, v200, v201
	v_cvt_pk_bf16_f32 v71, v202, v203
	v_pk_add_f32 v[232:233], v[232:233], v[188:189]
	v_pk_add_f32 v[232:233], v[232:233], v[190:191]
	v_pk_add_f32 v[232:233], v[232:233], v[192:193]
	v_pk_add_f32 v[232:233], v[232:233], v[194:195]
	v_pk_add_f32 v[232:233], v[232:233], v[196:197]
	v_pk_add_f32 v[232:233], v[232:233], v[198:199]
	v_pk_add_f32 v[232:233], v[232:233], v[200:201]
	v_pk_add_f32 v[232:233], v[232:233], v[202:203]
	ds_read2_b32 v[188:189], v115 offset0:160 offset1:161
	ds_read2_b32 v[190:191], v115 offset0:162 offset1:163
	ds_read2_b32 v[192:193], v115 offset0:168 offset1:169
	ds_read2_b32 v[194:195], v115 offset0:170 offset1:171
	ds_read2_b32 v[196:197], v115 offset0:176 offset1:177
	ds_read2_b32 v[198:199], v115 offset0:178 offset1:179
	ds_read2_b32 v[200:201], v115 offset0:184 offset1:185
	ds_read2_b32 v[202:203], v115 offset0:186 offset1:187
	v_mfma_f32_32x32x16_bf16 v[0:15], v[64:67], v[72:75], v[0:15]
	v_mfma_f32_32x32x16_bf16 v[16:31], v[64:67], v[76:79], v[16:31]
	v_mfma_f32_32x32x16_bf16 v[0:15], v[68:71], v[220:223], v[0:15]
	v_mfma_f32_32x32x16_bf16 v[16:31], v[68:71], v[224:227], v[16:31]
	s_add_i32 s90, s67, 512
	v_add_u32_e32 v80, s90, v239
	v_add_u32_e32 v83, s90, v240
	v_add_u32_e32 v99, s90, v241
	v_add_u32_e32 v253, s90, v242
	v_add_u32_e32 v254, s90, v101
	v_add_u32_e32 v255, s90, v150
	v_med3_i32 v80, v80, 0, s99
	v_med3_i32 v83, v83, 0, s99
	v_med3_i32 v99, v99, 0, s99
	v_med3_i32 v253, v253, 0, s99
	v_med3_i32 v254, v254, 0, s99
	v_med3_i32 v255, v255, 0, s99
	v_mad_u32_u24 v80, v80, s100, v252
	v_mad_u32_u24 v83, v83, s100, v252
	v_mad_u32_u24 v99, v99, s100, v252
	v_mad_u32_u24 v253, v253, s100, v252
	v_mad_u32_u24 v254, v254, s100, v153
	v_mad_u32_u24 v255, v255, s100, v153
	global_load_dwordx4 v[116:119], v80, s[82:83]
	global_load_dwordx4 v[120:123], v83, s[82:83]
	global_load_dwordx4 v[124:127], v99, s[82:83]
	global_load_dwordx4 v[128:131], v253, s[82:83]
	global_load_dwordx4 v[132:135], v254, s[82:83] offset:768
	global_load_dwordx4 v[136:139], v255, s[82:83] offset:768
	global_load_dwordx4 v[140:143], v254, s[82:83] offset:832
	global_load_dwordx4 v[144:147], v255, s[82:83] offset:832
	ds_read_b64_tr_b16 v[72:73], v231
	ds_read_b64_tr_b16 v[74:75], v231 offset:512
	ds_read_b64_tr_b16 v[76:77], v231 offset:2048
	ds_read_b64_tr_b16 v[78:79], v231 offset:2560
	ds_read_b64_tr_b16 v[220:221], v231 offset:1024
	ds_read_b64_tr_b16 v[222:223], v231 offset:1536
	ds_read_b64_tr_b16 v[224:225], v231 offset:3072
	ds_read_b64_tr_b16 v[226:227], v231 offset:3584
	v_exp_f32_e32 v32, v32
	v_exp_f32_e32 v33, v33
	v_exp_f32_e32 v34, v34
	v_exp_f32_e32 v35, v35
	s_waitcnt vmcnt(8)
	ds_write_b128 v247, v[156:159]
	ds_write_b128 v247, v[160:163] offset:1024
	ds_write_b128 v247, v[164:167] offset:2048
	ds_write_b128 v247, v[168:171] offset:3072
	ds_read_b128 v[156:159], v248
	ds_read_b128 v[160:163], v249
	ds_read_b128 v[164:167], v250
	ds_read_b128 v[168:171], v251
	ds_write_b128 v112, v[172:175]
	ds_write_b128 v112, v[176:179] offset:1024
	ds_write_b128 v112, v[180:183] offset:2048
	ds_write_b128 v112, v[184:187] offset:3072
	v_exp_f32_e32 v36, v36
	v_exp_f32_e32 v37, v37
	v_exp_f32_e32 v38, v38
	v_exp_f32_e32 v39, v39
	s_waitcnt lgkmcnt(4)
	v_mfma_f32_32x32x16_bf16 v[188:203], v[156:159], v[48:51], v[188:203]
	v_exp_f32_e32 v40, v40
	v_exp_f32_e32 v41, v41
	v_mfma_f32_32x32x16_bf16 v[188:203], v[160:163], v[52:55], v[188:203]
	v_exp_f32_e32 v42, v42
	v_exp_f32_e32 v43, v43
	v_mfma_f32_32x32x16_bf16 v[188:203], v[164:167], v[56:59], v[188:203]
	v_exp_f32_e32 v44, v44
	v_exp_f32_e32 v45, v45
	v_mfma_f32_32x32x16_bf16 v[188:203], v[168:171], v[60:63], v[188:203]
	v_exp_f32_e32 v46, v46
	v_exp_f32_e32 v47, v47
	s_add_i32 s90, s67, 256
	v_lshlrev_b32_e32 v84, 2, v107
	v_add_u32_e32 v84, s90, v84
	v_add_u32_e32 v85, 0, v84
	v_add_u32_e32 v86, 4, v84
	v_add_u32_e32 v87, 8, v84
	v_add_u32_e32 v88, 12, v84
	v_cmp_gt_u32_e64 s[30:31], s98, v85
	v_cmp_gt_u32_e64 s[36:37], s98, v86
	v_cmp_gt_u32_e64 s[78:79], s98, v87
	v_cmp_gt_u32_e64 s[50:51], s98, v88
	v_cndmask_b32_e64 v32, 0, v32, s[30:31]
	v_add_u32_e32 v85, 32, v84
	v_cmp_gt_u32_e64 s[30:31], s98, v85
	v_cndmask_b32_e64 v33, 0, v33, s[36:37]
	v_add_u32_e32 v86, 36, v84
	v_cmp_gt_u32_e64 s[36:37], s98, v86
	v_cndmask_b32_e64 v34, 0, v34, s[78:79]
	v_add_u32_e32 v87, 40, v84
	v_cmp_gt_u32_e64 s[78:79], s98, v87
	v_cndmask_b32_e64 v35, 0, v35, s[50:51]
	v_add_u32_e32 v88, 44, v84
	v_cmp_gt_u32_e64 s[50:51], s98, v88
	v_cndmask_b32_e64 v36, 0, v36, s[30:31]
	v_add_u32_e32 v85, 64, v84
	v_cmp_gt_u32_e64 s[30:31], s98, v85
	v_cndmask_b32_e64 v37, 0, v37, s[36:37]
	v_add_u32_e32 v86, 68, v84
	v_cmp_gt_u32_e64 s[36:37], s98, v86
	v_cndmask_b32_e64 v38, 0, v38, s[78:79]
	v_add_u32_e32 v87, 72, v84
	v_cmp_gt_u32_e64 s[78:79], s98, v87
	v_cndmask_b32_e64 v39, 0, v39, s[50:51]
	v_add_u32_e32 v88, 76, v84
	v_cmp_gt_u32_e64 s[50:51], s98, v88
	v_cndmask_b32_e64 v40, 0, v40, s[30:31]
	v_add_u32_e32 v85, 96, v84
	v_cmp_gt_u32_e64 s[30:31], s98, v85
	v_cndmask_b32_e64 v41, 0, v41, s[36:37]
	v_add_u32_e32 v86, 100, v84
	v_cmp_gt_u32_e64 s[36:37], s98, v86
	v_cndmask_b32_e64 v42, 0, v42, s[78:79]
	v_add_u32_e32 v87, 104, v84
	v_cmp_gt_u32_e64 s[78:79], s98, v87
	v_cndmask_b32_e64 v43, 0, v43, s[50:51]
	v_add_u32_e32 v88, 108, v84
	v_cmp_gt_u32_e64 s[50:51], s98, v88
	v_nop
	v_cndmask_b32_e64 v44, 0, v44, s[30:31]
	v_cndmask_b32_e64 v45, 0, v45, s[36:37]
	v_cndmask_b32_e64 v46, 0, v46, s[78:79]
	v_cndmask_b32_e64 v47, 0, v47, s[50:51]
	v_cvt_pk_bf16_f32 v64, v32, v33
	v_cvt_pk_bf16_f32 v65, v34, v35
	v_cvt_pk_bf16_f32 v66, v36, v37
	v_cvt_pk_bf16_f32 v67, v38, v39
	v_cvt_pk_bf16_f32 v68, v40, v41
	v_cvt_pk_bf16_f32 v69, v42, v43
	v_cvt_pk_bf16_f32 v70, v44, v45
	v_cvt_pk_bf16_f32 v71, v46, v47
	v_pk_add_f32 v[232:233], v[232:233], v[32:33]
	v_pk_add_f32 v[232:233], v[232:233], v[34:35]
	v_pk_add_f32 v[232:233], v[232:233], v[36:37]
	v_pk_add_f32 v[232:233], v[232:233], v[38:39]
	v_pk_add_f32 v[232:233], v[232:233], v[40:41]
	v_pk_add_f32 v[232:233], v[232:233], v[42:43]
	v_pk_add_f32 v[232:233], v[232:233], v[44:45]
	v_pk_add_f32 v[232:233], v[232:233], v[46:47]
	ds_read2_b32 v[32:33], v115 offset0:192 offset1:193
	ds_read2_b32 v[34:35], v115 offset0:194 offset1:195
	ds_read2_b32 v[36:37], v115 offset0:200 offset1:201
	ds_read2_b32 v[38:39], v115 offset0:202 offset1:203
	ds_read2_b32 v[40:41], v115 offset0:208 offset1:209
	ds_read2_b32 v[42:43], v115 offset0:210 offset1:211
	ds_read2_b32 v[44:45], v115 offset0:216 offset1:217
	ds_read2_b32 v[46:47], v115 offset0:218 offset1:219
	v_mfma_f32_32x32x16_bf16 v[0:15], v[64:67], v[72:75], v[0:15]
	v_mfma_f32_32x32x16_bf16 v[16:31], v[64:67], v[76:79], v[16:31]
	v_mfma_f32_32x32x16_bf16 v[0:15], v[68:71], v[220:223], v[0:15]
	v_mfma_f32_32x32x16_bf16 v[16:31], v[68:71], v[224:227], v[16:31]
	s_add_i32 s90, s67, 640
	v_add_u32_e32 v80, s90, v239
	v_add_u32_e32 v83, s90, v240
	v_add_u32_e32 v99, s90, v241
	v_add_u32_e32 v253, s90, v242
	v_add_u32_e32 v254, s90, v101
	v_add_u32_e32 v255, s90, v150
	v_med3_i32 v80, v80, 0, s99
	v_med3_i32 v83, v83, 0, s99
	v_med3_i32 v99, v99, 0, s99
	v_med3_i32 v253, v253, 0, s99
	v_med3_i32 v254, v254, 0, s99
	v_med3_i32 v255, v255, 0, s99
	v_mad_u32_u24 v80, v80, s100, v252
	v_mad_u32_u24 v83, v83, s100, v252
	v_mad_u32_u24 v99, v99, s100, v252
	v_mad_u32_u24 v253, v253, s100, v252
	v_mad_u32_u24 v254, v254, s100, v153
	v_mad_u32_u24 v255, v255, s100, v153
	global_load_dwordx4 v[156:159], v80, s[82:83]
	global_load_dwordx4 v[160:163], v83, s[82:83]
	global_load_dwordx4 v[164:167], v99, s[82:83]
	global_load_dwordx4 v[168:171], v253, s[82:83]
	global_load_dwordx4 v[172:175], v254, s[82:83] offset:768
	global_load_dwordx4 v[176:179], v255, s[82:83] offset:768
	global_load_dwordx4 v[180:183], v254, s[82:83] offset:832
	global_load_dwordx4 v[184:187], v255, s[82:83] offset:832
	ds_read_b64_tr_b16 v[72:73], v231
	ds_read_b64_tr_b16 v[74:75], v231 offset:512
	ds_read_b64_tr_b16 v[76:77], v231 offset:2048
	ds_read_b64_tr_b16 v[78:79], v231 offset:2560
	ds_read_b64_tr_b16 v[220:221], v231 offset:1024
	ds_read_b64_tr_b16 v[222:223], v231 offset:1536
	ds_read_b64_tr_b16 v[224:225], v231 offset:3072
	ds_read_b64_tr_b16 v[226:227], v231 offset:3584
	v_exp_f32_e32 v188, v188
	v_exp_f32_e32 v189, v189
	v_exp_f32_e32 v190, v190
	v_exp_f32_e32 v191, v191
	s_waitcnt vmcnt(8)
	ds_write_b128 v247, v[116:119]
	ds_write_b128 v247, v[120:123] offset:1024
	ds_write_b128 v247, v[124:127] offset:2048
	ds_write_b128 v247, v[128:131] offset:3072
	ds_read_b128 v[116:119], v248
	ds_read_b128 v[120:123], v249
	ds_read_b128 v[124:127], v250
	ds_read_b128 v[128:131], v251
	ds_write_b128 v112, v[132:135]
	ds_write_b128 v112, v[136:139] offset:1024
	ds_write_b128 v112, v[140:143] offset:2048
	ds_write_b128 v112, v[144:147] offset:3072
	v_exp_f32_e32 v192, v192
	v_exp_f32_e32 v193, v193
	v_exp_f32_e32 v194, v194
	v_exp_f32_e32 v195, v195
	s_waitcnt lgkmcnt(4)
	v_mfma_f32_32x32x16_bf16 v[32:47], v[116:119], v[48:51], v[32:47]
	v_exp_f32_e32 v196, v196
	v_exp_f32_e32 v197, v197
	v_mfma_f32_32x32x16_bf16 v[32:47], v[120:123], v[52:55], v[32:47]
	v_exp_f32_e32 v198, v198
	v_exp_f32_e32 v199, v199
	v_mfma_f32_32x32x16_bf16 v[32:47], v[124:127], v[56:59], v[32:47]
	v_exp_f32_e32 v200, v200
	v_exp_f32_e32 v201, v201
	v_mfma_f32_32x32x16_bf16 v[32:47], v[128:131], v[60:63], v[32:47]
	v_exp_f32_e32 v202, v202
	v_exp_f32_e32 v203, v203
	s_add_i32 s90, s67, 384
	v_lshlrev_b32_e32 v84, 2, v107
	v_add_u32_e32 v84, s90, v84
	v_add_u32_e32 v85, 0, v84
	v_add_u32_e32 v86, 4, v84
	v_add_u32_e32 v87, 8, v84
	v_add_u32_e32 v88, 12, v84
	v_cmp_gt_u32_e64 s[30:31], s98, v85
	v_cmp_gt_u32_e64 s[36:37], s98, v86
	v_cmp_gt_u32_e64 s[78:79], s98, v87
	v_cmp_gt_u32_e64 s[50:51], s98, v88
	v_cndmask_b32_e64 v188, 0, v188, s[30:31]
	v_add_u32_e32 v85, 32, v84
	v_cmp_gt_u32_e64 s[30:31], s98, v85
	v_cndmask_b32_e64 v189, 0, v189, s[36:37]
	v_add_u32_e32 v86, 36, v84
	v_cmp_gt_u32_e64 s[36:37], s98, v86
	v_cndmask_b32_e64 v190, 0, v190, s[78:79]
	v_add_u32_e32 v87, 40, v84
	v_cmp_gt_u32_e64 s[78:79], s98, v87
	v_cndmask_b32_e64 v191, 0, v191, s[50:51]
	v_add_u32_e32 v88, 44, v84
	v_cmp_gt_u32_e64 s[50:51], s98, v88
	v_cndmask_b32_e64 v192, 0, v192, s[30:31]
	v_add_u32_e32 v85, 64, v84
	v_cmp_gt_u32_e64 s[30:31], s98, v85
	v_cndmask_b32_e64 v193, 0, v193, s[36:37]
	v_add_u32_e32 v86, 68, v84
	v_cmp_gt_u32_e64 s[36:37], s98, v86
	v_cndmask_b32_e64 v194, 0, v194, s[78:79]
	v_add_u32_e32 v87, 72, v84
	v_cmp_gt_u32_e64 s[78:79], s98, v87
	v_cndmask_b32_e64 v195, 0, v195, s[50:51]
	v_add_u32_e32 v88, 76, v84
	v_cmp_gt_u32_e64 s[50:51], s98, v88
	v_cndmask_b32_e64 v196, 0, v196, s[30:31]
	v_add_u32_e32 v85, 96, v84
	v_cmp_gt_u32_e64 s[30:31], s98, v85
	v_cndmask_b32_e64 v197, 0, v197, s[36:37]
	v_add_u32_e32 v86, 100, v84
	v_cmp_gt_u32_e64 s[36:37], s98, v86
	v_cndmask_b32_e64 v198, 0, v198, s[78:79]
	v_add_u32_e32 v87, 104, v84
	v_cmp_gt_u32_e64 s[78:79], s98, v87
	v_cndmask_b32_e64 v199, 0, v199, s[50:51]
	v_add_u32_e32 v88, 108, v84
	v_cmp_gt_u32_e64 s[50:51], s98, v88
	v_nop
	v_cndmask_b32_e64 v200, 0, v200, s[30:31]
	v_cndmask_b32_e64 v201, 0, v201, s[36:37]
	v_cndmask_b32_e64 v202, 0, v202, s[78:79]
	v_cndmask_b32_e64 v203, 0, v203, s[50:51]
	v_cvt_pk_bf16_f32 v64, v188, v189
	v_cvt_pk_bf16_f32 v65, v190, v191
	v_cvt_pk_bf16_f32 v66, v192, v193
	v_cvt_pk_bf16_f32 v67, v194, v195
	v_cvt_pk_bf16_f32 v68, v196, v197
	v_cvt_pk_bf16_f32 v69, v198, v199
	v_cvt_pk_bf16_f32 v70, v200, v201
	v_cvt_pk_bf16_f32 v71, v202, v203
	v_pk_add_f32 v[232:233], v[232:233], v[188:189]
	v_pk_add_f32 v[232:233], v[232:233], v[190:191]
	v_pk_add_f32 v[232:233], v[232:233], v[192:193]
	v_pk_add_f32 v[232:233], v[232:233], v[194:195]
	v_pk_add_f32 v[232:233], v[232:233], v[196:197]
	v_pk_add_f32 v[232:233], v[232:233], v[198:199]
	v_pk_add_f32 v[232:233], v[232:233], v[200:201]
	v_pk_add_f32 v[232:233], v[232:233], v[202:203]
	ds_read2_b32 v[188:189], v115 offset0:224 offset1:225
	ds_read2_b32 v[190:191], v115 offset0:226 offset1:227
	ds_read2_b32 v[192:193], v115 offset0:232 offset1:233
	ds_read2_b32 v[194:195], v115 offset0:234 offset1:235
	ds_read2_b32 v[196:197], v115 offset0:240 offset1:241
	ds_read2_b32 v[198:199], v115 offset0:242 offset1:243
	ds_read2_b32 v[200:201], v115 offset0:248 offset1:249
	ds_read2_b32 v[202:203], v115 offset0:250 offset1:251
	v_mfma_f32_32x32x16_bf16 v[0:15], v[64:67], v[72:75], v[0:15]
	v_mfma_f32_32x32x16_bf16 v[16:31], v[64:67], v[76:79], v[16:31]
	v_mfma_f32_32x32x16_bf16 v[0:15], v[68:71], v[220:223], v[0:15]
	v_mfma_f32_32x32x16_bf16 v[16:31], v[68:71], v[224:227], v[16:31]
	s_add_i32 s90, s67, -1024
	v_add_u32_e32 v80, s90, v243
	v_add_u32_e32 v83, s90, v244
	v_add_u32_e32 v99, s90, v245
	v_add_u32_e32 v253, s90, v246
	v_add_u32_e32 v254, s90, v148
	v_add_u32_e32 v255, s90, v151
	v_med3_i32 v80, v80, 0, s99
	v_med3_i32 v83, v83, 0, s99
	v_med3_i32 v99, v99, 0, s99
	v_med3_i32 v253, v253, 0, s99
	v_med3_i32 v254, v254, 0, s99
	v_med3_i32 v255, v255, 0, s99
	v_mad_u32_u24 v80, v80, s100, v252
	v_mad_u32_u24 v83, v83, s100, v252
	v_mad_u32_u24 v99, v99, s100, v252
	v_mad_u32_u24 v253, v253, s100, v252
	v_mad_u32_u24 v254, v254, s100, v153
	v_mad_u32_u24 v255, v255, s100, v153
	global_load_dwordx4 v[116:119], v80, s[82:83]
	global_load_dwordx4 v[120:123], v83, s[82:83]
	global_load_dwordx4 v[124:127], v99, s[82:83]
	global_load_dwordx4 v[128:131], v253, s[82:83]
	global_load_dwordx4 v[132:135], v254, s[82:83] offset:768
	global_load_dwordx4 v[136:139], v255, s[82:83] offset:768
	global_load_dwordx4 v[140:143], v254, s[82:83] offset:832
	global_load_dwordx4 v[144:147], v255, s[82:83] offset:832
	ds_read_b64_tr_b16 v[72:73], v231
	ds_read_b64_tr_b16 v[74:75], v231 offset:512
	ds_read_b64_tr_b16 v[76:77], v231 offset:2048
	ds_read_b64_tr_b16 v[78:79], v231 offset:2560
	ds_read_b64_tr_b16 v[220:221], v231 offset:1024
	ds_read_b64_tr_b16 v[222:223], v231 offset:1536
	ds_read_b64_tr_b16 v[224:225], v231 offset:3072
	ds_read_b64_tr_b16 v[226:227], v231 offset:3584
	v_exp_f32_e32 v32, v32
	v_exp_f32_e32 v33, v33
	v_exp_f32_e32 v34, v34
	v_exp_f32_e32 v35, v35
	s_waitcnt vmcnt(8)
	ds_write_b128 v247, v[156:159]
	ds_write_b128 v247, v[160:163] offset:1024
	ds_write_b128 v247, v[164:167] offset:2048
	ds_write_b128 v247, v[168:171] offset:3072
	ds_read_b128 v[156:159], v248
	ds_read_b128 v[160:163], v249
	ds_read_b128 v[164:167], v250
	ds_read_b128 v[168:171], v251
	ds_write_b128 v112, v[172:175]
	ds_write_b128 v112, v[176:179] offset:1024
	ds_write_b128 v112, v[180:183] offset:2048
	ds_write_b128 v112, v[184:187] offset:3072
	v_exp_f32_e32 v36, v36
	v_exp_f32_e32 v37, v37
	v_exp_f32_e32 v38, v38
	v_exp_f32_e32 v39, v39
	s_waitcnt lgkmcnt(4)
	v_mfma_f32_32x32x16_bf16 v[188:203], v[156:159], v[48:51], v[188:203]
	v_exp_f32_e32 v40, v40
	v_exp_f32_e32 v41, v41
	v_mfma_f32_32x32x16_bf16 v[188:203], v[160:163], v[52:55], v[188:203]
	v_exp_f32_e32 v42, v42
	v_exp_f32_e32 v43, v43
	v_mfma_f32_32x32x16_bf16 v[188:203], v[164:167], v[56:59], v[188:203]
	v_exp_f32_e32 v44, v44
	v_exp_f32_e32 v45, v45
	v_mfma_f32_32x32x16_bf16 v[188:203], v[168:171], v[60:63], v[188:203]
	v_exp_f32_e32 v46, v46
	v_exp_f32_e32 v47, v47
	s_add_i32 s90, s67, 512
	v_lshlrev_b32_e32 v84, 2, v107
	v_add_u32_e32 v84, s90, v84
	v_add_u32_e32 v85, 0, v84
	v_add_u32_e32 v86, 4, v84
	v_add_u32_e32 v87, 8, v84
	v_add_u32_e32 v88, 12, v84
	v_cmp_gt_u32_e64 s[30:31], s98, v85
	v_cmp_gt_u32_e64 s[36:37], s98, v86
	v_cmp_gt_u32_e64 s[78:79], s98, v87
	v_cmp_gt_u32_e64 s[50:51], s98, v88
	v_cndmask_b32_e64 v32, 0, v32, s[30:31]
	v_add_u32_e32 v85, 32, v84
	v_cmp_gt_u32_e64 s[30:31], s98, v85
	v_cndmask_b32_e64 v33, 0, v33, s[36:37]
	v_add_u32_e32 v86, 36, v84
	v_cmp_gt_u32_e64 s[36:37], s98, v86
	v_cndmask_b32_e64 v34, 0, v34, s[78:79]
	v_add_u32_e32 v87, 40, v84
	v_cmp_gt_u32_e64 s[78:79], s98, v87
	v_cndmask_b32_e64 v35, 0, v35, s[50:51]
	v_add_u32_e32 v88, 44, v84
	v_cmp_gt_u32_e64 s[50:51], s98, v88
	v_cndmask_b32_e64 v36, 0, v36, s[30:31]
	v_add_u32_e32 v85, 64, v84
	v_cmp_gt_u32_e64 s[30:31], s98, v85
	v_cndmask_b32_e64 v37, 0, v37, s[36:37]
	v_add_u32_e32 v86, 68, v84
	v_cmp_gt_u32_e64 s[36:37], s98, v86
	v_cndmask_b32_e64 v38, 0, v38, s[78:79]
	v_add_u32_e32 v87, 72, v84
	v_cmp_gt_u32_e64 s[78:79], s98, v87
	v_cndmask_b32_e64 v39, 0, v39, s[50:51]
	v_add_u32_e32 v88, 76, v84
	v_cmp_gt_u32_e64 s[50:51], s98, v88
	v_cndmask_b32_e64 v40, 0, v40, s[30:31]
	v_add_u32_e32 v85, 96, v84
	v_cmp_gt_u32_e64 s[30:31], s98, v85
	v_cndmask_b32_e64 v41, 0, v41, s[36:37]
	v_add_u32_e32 v86, 100, v84
	v_cmp_gt_u32_e64 s[36:37], s98, v86
	v_cndmask_b32_e64 v42, 0, v42, s[78:79]
	v_add_u32_e32 v87, 104, v84
	v_cmp_gt_u32_e64 s[78:79], s98, v87
	v_cndmask_b32_e64 v43, 0, v43, s[50:51]
	v_add_u32_e32 v88, 108, v84
	v_cmp_gt_u32_e64 s[50:51], s98, v88
	v_nop
	v_cndmask_b32_e64 v44, 0, v44, s[30:31]
	v_cndmask_b32_e64 v45, 0, v45, s[36:37]
	v_cndmask_b32_e64 v46, 0, v46, s[78:79]
	v_cndmask_b32_e64 v47, 0, v47, s[50:51]
	v_cvt_pk_bf16_f32 v64, v32, v33
	v_cvt_pk_bf16_f32 v65, v34, v35
	v_cvt_pk_bf16_f32 v66, v36, v37
	v_cvt_pk_bf16_f32 v67, v38, v39
	v_cvt_pk_bf16_f32 v68, v40, v41
	v_cvt_pk_bf16_f32 v69, v42, v43
	v_cvt_pk_bf16_f32 v70, v44, v45
	v_cvt_pk_bf16_f32 v71, v46, v47
	v_pk_add_f32 v[232:233], v[232:233], v[32:33]
	v_pk_add_f32 v[232:233], v[232:233], v[34:35]
	v_pk_add_f32 v[232:233], v[232:233], v[36:37]
	v_pk_add_f32 v[232:233], v[232:233], v[38:39]
	v_pk_add_f32 v[232:233], v[232:233], v[40:41]
	v_pk_add_f32 v[232:233], v[232:233], v[42:43]
	v_pk_add_f32 v[232:233], v[232:233], v[44:45]
	v_pk_add_f32 v[232:233], v[232:233], v[46:47]
	v_mov_b32_e32 v115, v230
	ds_read2_b32 v[32:33], v115 offset0:0 offset1:1
	ds_read2_b32 v[34:35], v115 offset0:2 offset1:3
	ds_read2_b32 v[36:37], v115 offset0:8 offset1:9
	ds_read2_b32 v[38:39], v115 offset0:10 offset1:11
	ds_read2_b32 v[40:41], v115 offset0:16 offset1:17
	ds_read2_b32 v[42:43], v115 offset0:18 offset1:19
	ds_read2_b32 v[44:45], v115 offset0:24 offset1:25
	ds_read2_b32 v[46:47], v115 offset0:26 offset1:27
	v_mfma_f32_32x32x16_bf16 v[0:15], v[64:67], v[72:75], v[0:15]
	v_mfma_f32_32x32x16_bf16 v[16:31], v[64:67], v[76:79], v[16:31]
	v_mfma_f32_32x32x16_bf16 v[0:15], v[68:71], v[220:223], v[0:15]
	v_mfma_f32_32x32x16_bf16 v[16:31], v[68:71], v[224:227], v[16:31]
	s_add_i32 s90, s67, -512
	v_add_u32_e32 v80, s90, v243
	v_add_u32_e32 v83, s90, v244
	v_add_u32_e32 v99, s90, v245
	v_add_u32_e32 v253, s90, v246
	v_add_u32_e32 v254, s90, v148
	v_add_u32_e32 v255, s90, v151
	v_med3_i32 v80, v80, 0, s99
	v_med3_i32 v83, v83, 0, s99
	v_med3_i32 v99, v99, 0, s99
	v_med3_i32 v253, v253, 0, s99
	v_med3_i32 v254, v254, 0, s99
	v_med3_i32 v255, v255, 0, s99
	v_mad_u32_u24 v80, v80, s100, v252
	v_mad_u32_u24 v83, v83, s100, v252
	v_mad_u32_u24 v99, v99, s100, v252
	v_mad_u32_u24 v253, v253, s100, v252
	v_mad_u32_u24 v254, v254, s100, v153
	v_mad_u32_u24 v255, v255, s100, v153
	global_load_dwordx4 v[156:159], v80, s[82:83]
	global_load_dwordx4 v[160:163], v83, s[82:83]
	global_load_dwordx4 v[164:167], v99, s[82:83]
	global_load_dwordx4 v[168:171], v253, s[82:83]
	global_load_dwordx4 v[172:175], v254, s[82:83] offset:768
	global_load_dwordx4 v[176:179], v255, s[82:83] offset:768
	global_load_dwordx4 v[180:183], v254, s[82:83] offset:832
	global_load_dwordx4 v[184:187], v255, s[82:83] offset:832
	ds_read_b64_tr_b16 v[72:73], v231
	ds_read_b64_tr_b16 v[74:75], v231 offset:512
	ds_read_b64_tr_b16 v[76:77], v231 offset:2048
	ds_read_b64_tr_b16 v[78:79], v231 offset:2560
	ds_read_b64_tr_b16 v[220:221], v231 offset:1024
	ds_read_b64_tr_b16 v[222:223], v231 offset:1536
	ds_read_b64_tr_b16 v[224:225], v231 offset:3072
	ds_read_b64_tr_b16 v[226:227], v231 offset:3584
	v_exp_f32_e32 v188, v188
	v_exp_f32_e32 v189, v189
	v_exp_f32_e32 v190, v190
	v_exp_f32_e32 v191, v191
	s_waitcnt vmcnt(8)
	ds_write_b128 v247, v[116:119]
	ds_write_b128 v247, v[120:123] offset:1024
	ds_write_b128 v247, v[124:127] offset:2048
	ds_write_b128 v247, v[128:131] offset:3072
	ds_read_b128 v[116:119], v248
	ds_read_b128 v[120:123], v249
	ds_read_b128 v[124:127], v250
	ds_read_b128 v[128:131], v251
	ds_write_b128 v112, v[132:135]
	ds_write_b128 v112, v[136:139] offset:1024
	ds_write_b128 v112, v[140:143] offset:2048
	ds_write_b128 v112, v[144:147] offset:3072
	v_exp_f32_e32 v192, v192
	v_exp_f32_e32 v193, v193
	v_exp_f32_e32 v194, v194
	v_exp_f32_e32 v195, v195
	s_waitcnt lgkmcnt(4)
	v_mfma_f32_32x32x16_bf16 v[32:47], v[116:119], v[48:51], v[32:47]
	v_exp_f32_e32 v196, v196
	v_exp_f32_e32 v197, v197
	v_mfma_f32_32x32x16_bf16 v[32:47], v[120:123], v[52:55], v[32:47]
	v_exp_f32_e32 v198, v198
	v_exp_f32_e32 v199, v199
	v_mfma_f32_32x32x16_bf16 v[32:47], v[124:127], v[56:59], v[32:47]
	v_exp_f32_e32 v200, v200
	v_exp_f32_e32 v201, v201
	v_mfma_f32_32x32x16_bf16 v[32:47], v[128:131], v[60:63], v[32:47]
	v_exp_f32_e32 v202, v202
	v_exp_f32_e32 v203, v203
	s_add_i32 s90, s67, 640
	v_lshlrev_b32_e32 v84, 2, v107
	v_add_u32_e32 v84, s90, v84
	v_add_u32_e32 v85, 0, v84
	v_add_u32_e32 v86, 4, v84
	v_add_u32_e32 v87, 8, v84
	v_add_u32_e32 v88, 12, v84
	v_cmp_gt_u32_e64 s[30:31], s98, v85
	v_cmp_gt_u32_e64 s[36:37], s98, v86
	v_cmp_gt_u32_e64 s[78:79], s98, v87
	v_cmp_gt_u32_e64 s[50:51], s98, v88
	v_cndmask_b32_e64 v188, 0, v188, s[30:31]
	v_add_u32_e32 v85, 32, v84
	v_cmp_gt_u32_e64 s[30:31], s98, v85
	v_cndmask_b32_e64 v189, 0, v189, s[36:37]
	v_add_u32_e32 v86, 36, v84
	v_cmp_gt_u32_e64 s[36:37], s98, v86
	v_cndmask_b32_e64 v190, 0, v190, s[78:79]
	v_add_u32_e32 v87, 40, v84
	v_cmp_gt_u32_e64 s[78:79], s98, v87
	v_cndmask_b32_e64 v191, 0, v191, s[50:51]
	v_add_u32_e32 v88, 44, v84
	v_cmp_gt_u32_e64 s[50:51], s98, v88
	v_cndmask_b32_e64 v192, 0, v192, s[30:31]
	v_add_u32_e32 v85, 64, v84
	v_cmp_gt_u32_e64 s[30:31], s98, v85
	v_cndmask_b32_e64 v193, 0, v193, s[36:37]
	v_add_u32_e32 v86, 68, v84
	v_cmp_gt_u32_e64 s[36:37], s98, v86
	v_cndmask_b32_e64 v194, 0, v194, s[78:79]
	v_add_u32_e32 v87, 72, v84
	v_cmp_gt_u32_e64 s[78:79], s98, v87
	v_cndmask_b32_e64 v195, 0, v195, s[50:51]
	v_add_u32_e32 v88, 76, v84
	v_cmp_gt_u32_e64 s[50:51], s98, v88
	v_cndmask_b32_e64 v196, 0, v196, s[30:31]
	v_add_u32_e32 v85, 96, v84
	v_cmp_gt_u32_e64 s[30:31], s98, v85
	v_cndmask_b32_e64 v197, 0, v197, s[36:37]
	v_add_u32_e32 v86, 100, v84
	v_cmp_gt_u32_e64 s[36:37], s98, v86
	v_cndmask_b32_e64 v198, 0, v198, s[78:79]
	v_add_u32_e32 v87, 104, v84
	v_cmp_gt_u32_e64 s[78:79], s98, v87
	v_cndmask_b32_e64 v199, 0, v199, s[50:51]
	v_add_u32_e32 v88, 108, v84
	v_cmp_gt_u32_e64 s[50:51], s98, v88
	v_nop
	v_cndmask_b32_e64 v200, 0, v200, s[30:31]
	v_cndmask_b32_e64 v201, 0, v201, s[36:37]
	v_cndmask_b32_e64 v202, 0, v202, s[78:79]
	v_cndmask_b32_e64 v203, 0, v203, s[50:51]
	v_cvt_pk_bf16_f32 v64, v188, v189
	v_cvt_pk_bf16_f32 v65, v190, v191
	v_cvt_pk_bf16_f32 v66, v192, v193
	v_cvt_pk_bf16_f32 v67, v194, v195
	v_cvt_pk_bf16_f32 v68, v196, v197
	v_cvt_pk_bf16_f32 v69, v198, v199
	v_cvt_pk_bf16_f32 v70, v200, v201
	v_cvt_pk_bf16_f32 v71, v202, v203
	v_pk_add_f32 v[232:233], v[232:233], v[188:189]
	v_pk_add_f32 v[232:233], v[232:233], v[190:191]
	v_pk_add_f32 v[232:233], v[232:233], v[192:193]
	v_pk_add_f32 v[232:233], v[232:233], v[194:195]
	v_pk_add_f32 v[232:233], v[232:233], v[196:197]
	v_pk_add_f32 v[232:233], v[232:233], v[198:199]
	v_pk_add_f32 v[232:233], v[232:233], v[200:201]
	v_pk_add_f32 v[232:233], v[232:233], v[202:203]
	ds_read2_b32 v[188:189], v115 offset0:32 offset1:33
	ds_read2_b32 v[190:191], v115 offset0:34 offset1:35
	ds_read2_b32 v[192:193], v115 offset0:40 offset1:41
	ds_read2_b32 v[194:195], v115 offset0:42 offset1:43
	ds_read2_b32 v[196:197], v115 offset0:48 offset1:49
	ds_read2_b32 v[198:199], v115 offset0:50 offset1:51
	ds_read2_b32 v[200:201], v115 offset0:56 offset1:57
	ds_read2_b32 v[202:203], v115 offset0:58 offset1:59
	v_mfma_f32_32x32x16_bf16 v[0:15], v[64:67], v[72:75], v[0:15]
	v_mfma_f32_32x32x16_bf16 v[16:31], v[64:67], v[76:79], v[16:31]
	v_mfma_f32_32x32x16_bf16 v[0:15], v[68:71], v[220:223], v[0:15]
	v_mfma_f32_32x32x16_bf16 v[16:31], v[68:71], v[224:227], v[16:31]
	s_add_i32 s90, s67, 0
	v_add_u32_e32 v80, s90, v243
	v_add_u32_e32 v83, s90, v244
	v_add_u32_e32 v99, s90, v245
	v_add_u32_e32 v253, s90, v246
	v_add_u32_e32 v254, s90, v148
	v_add_u32_e32 v255, s90, v151
	v_med3_i32 v80, v80, 0, s99
	v_med3_i32 v83, v83, 0, s99
	v_med3_i32 v99, v99, 0, s99
	v_med3_i32 v253, v253, 0, s99
	v_med3_i32 v254, v254, 0, s99
	v_med3_i32 v255, v255, 0, s99
	v_mad_u32_u24 v80, v80, s100, v252
	v_mad_u32_u24 v83, v83, s100, v252
	v_mad_u32_u24 v99, v99, s100, v252
	v_mad_u32_u24 v253, v253, s100, v252
	v_mad_u32_u24 v254, v254, s100, v153
	v_mad_u32_u24 v255, v255, s100, v153
	global_load_dwordx4 v[116:119], v80, s[82:83]
	global_load_dwordx4 v[120:123], v83, s[82:83]
	global_load_dwordx4 v[124:127], v99, s[82:83]
	global_load_dwordx4 v[128:131], v253, s[82:83]
	global_load_dwordx4 v[132:135], v254, s[82:83] offset:768
	global_load_dwordx4 v[136:139], v255, s[82:83] offset:768
	global_load_dwordx4 v[140:143], v254, s[82:83] offset:832
	global_load_dwordx4 v[144:147], v255, s[82:83] offset:832
	ds_read_b64_tr_b16 v[72:73], v231
	ds_read_b64_tr_b16 v[74:75], v231 offset:512
	ds_read_b64_tr_b16 v[76:77], v231 offset:2048
	ds_read_b64_tr_b16 v[78:79], v231 offset:2560
	ds_read_b64_tr_b16 v[220:221], v231 offset:1024
	ds_read_b64_tr_b16 v[222:223], v231 offset:1536
	ds_read_b64_tr_b16 v[224:225], v231 offset:3072
	ds_read_b64_tr_b16 v[226:227], v231 offset:3584
	v_exp_f32_e32 v32, v32
	v_exp_f32_e32 v33, v33
	v_exp_f32_e32 v34, v34
	v_exp_f32_e32 v35, v35
	s_waitcnt vmcnt(8)
	ds_write_b128 v247, v[156:159]
	ds_write_b128 v247, v[160:163] offset:1024
	ds_write_b128 v247, v[164:167] offset:2048
	ds_write_b128 v247, v[168:171] offset:3072
	ds_read_b128 v[156:159], v248
	ds_read_b128 v[160:163], v249
	ds_read_b128 v[164:167], v250
	ds_read_b128 v[168:171], v251
	ds_write_b128 v112, v[172:175]
	ds_write_b128 v112, v[176:179] offset:1024
	ds_write_b128 v112, v[180:183] offset:2048
	ds_write_b128 v112, v[184:187] offset:3072
	v_exp_f32_e32 v36, v36
	v_exp_f32_e32 v37, v37
	v_exp_f32_e32 v38, v38
	v_exp_f32_e32 v39, v39
	s_waitcnt lgkmcnt(4)
	v_mfma_f32_32x32x16_bf16 v[188:203], v[156:159], v[48:51], v[188:203]
	v_exp_f32_e32 v40, v40
	v_exp_f32_e32 v41, v41
	v_mfma_f32_32x32x16_bf16 v[188:203], v[160:163], v[52:55], v[188:203]
	v_exp_f32_e32 v42, v42
	v_exp_f32_e32 v43, v43
	v_mfma_f32_32x32x16_bf16 v[188:203], v[164:167], v[56:59], v[188:203]
	v_exp_f32_e32 v44, v44
	v_exp_f32_e32 v45, v45
	v_mfma_f32_32x32x16_bf16 v[188:203], v[168:171], v[60:63], v[188:203]
	v_exp_f32_e32 v46, v46
	v_exp_f32_e32 v47, v47
	s_add_i32 s90, s67, -1024
	v_lshlrev_b32_e32 v84, 4, v107
	v_add_u32_e32 v84, s90, v84
	v_add_u32_e32 v85, 0, v84
	v_add_u32_e32 v86, 16, v84
	v_add_u32_e32 v87, 32, v84
	v_add_u32_e32 v88, 48, v84
	v_cmp_gt_u32_e64 s[30:31], s98, v85
	v_cmp_gt_u32_e64 s[36:37], s98, v86
	v_cmp_gt_u32_e64 s[78:79], s98, v87
	v_cmp_gt_u32_e64 s[50:51], s98, v88
	v_cndmask_b32_e64 v32, 0, v32, s[30:31]
	v_add_u32_e32 v85, 128, v84
	v_cmp_gt_u32_e64 s[30:31], s98, v85
	v_cndmask_b32_e64 v33, 0, v33, s[36:37]
	v_add_u32_e32 v86, 144, v84
	v_cmp_gt_u32_e64 s[36:37], s98, v86
	v_cndmask_b32_e64 v34, 0, v34, s[78:79]
	v_add_u32_e32 v87, 160, v84
	v_cmp_gt_u32_e64 s[78:79], s98, v87
	v_cndmask_b32_e64 v35, 0, v35, s[50:51]
	v_add_u32_e32 v88, 176, v84
	v_cmp_gt_u32_e64 s[50:51], s98, v88
	v_cndmask_b32_e64 v36, 0, v36, s[30:31]
	v_add_u32_e32 v85, 256, v84
	v_cmp_gt_u32_e64 s[30:31], s98, v85
	v_cndmask_b32_e64 v37, 0, v37, s[36:37]
	v_add_u32_e32 v86, 272, v84
	v_cmp_gt_u32_e64 s[36:37], s98, v86
	v_cndmask_b32_e64 v38, 0, v38, s[78:79]
	v_add_u32_e32 v87, 288, v84
	v_cmp_gt_u32_e64 s[78:79], s98, v87
	v_cndmask_b32_e64 v39, 0, v39, s[50:51]
	v_add_u32_e32 v88, 304, v84
	v_cmp_gt_u32_e64 s[50:51], s98, v88
	v_cndmask_b32_e64 v40, 0, v40, s[30:31]
	v_add_u32_e32 v85, 384, v84
	v_cmp_gt_u32_e64 s[30:31], s98, v85
	v_cndmask_b32_e64 v41, 0, v41, s[36:37]
	v_add_u32_e32 v86, 400, v84
	v_cmp_gt_u32_e64 s[36:37], s98, v86
	v_cndmask_b32_e64 v42, 0, v42, s[78:79]
	v_add_u32_e32 v87, 416, v84
	v_cmp_gt_u32_e64 s[78:79], s98, v87
	v_cndmask_b32_e64 v43, 0, v43, s[50:51]
	v_add_u32_e32 v88, 432, v84
	v_cmp_gt_u32_e64 s[50:51], s98, v88
	v_nop
	v_cndmask_b32_e64 v44, 0, v44, s[30:31]
	v_cndmask_b32_e64 v45, 0, v45, s[36:37]
	v_cndmask_b32_e64 v46, 0, v46, s[78:79]
	v_cndmask_b32_e64 v47, 0, v47, s[50:51]
	v_cvt_pk_bf16_f32 v64, v32, v33
	v_cvt_pk_bf16_f32 v65, v34, v35
	v_cvt_pk_bf16_f32 v66, v36, v37
	v_cvt_pk_bf16_f32 v67, v38, v39
	v_cvt_pk_bf16_f32 v68, v40, v41
	v_cvt_pk_bf16_f32 v69, v42, v43
	v_cvt_pk_bf16_f32 v70, v44, v45
	v_cvt_pk_bf16_f32 v71, v46, v47
	v_pk_add_f32 v[232:233], v[232:233], v[32:33]
	v_pk_add_f32 v[232:233], v[232:233], v[34:35]
	v_pk_add_f32 v[232:233], v[232:233], v[36:37]
	v_pk_add_f32 v[232:233], v[232:233], v[38:39]
	v_pk_add_f32 v[232:233], v[232:233], v[40:41]
	v_pk_add_f32 v[232:233], v[232:233], v[42:43]
	v_pk_add_f32 v[232:233], v[232:233], v[44:45]
	v_pk_add_f32 v[232:233], v[232:233], v[46:47]
	ds_read2_b32 v[32:33], v115 offset0:64 offset1:65
	ds_read2_b32 v[34:35], v115 offset0:66 offset1:67
	ds_read2_b32 v[36:37], v115 offset0:72 offset1:73
	ds_read2_b32 v[38:39], v115 offset0:74 offset1:75
	ds_read2_b32 v[40:41], v115 offset0:80 offset1:81
	ds_read2_b32 v[42:43], v115 offset0:82 offset1:83
	ds_read2_b32 v[44:45], v115 offset0:88 offset1:89
	ds_read2_b32 v[46:47], v115 offset0:90 offset1:91
	v_mfma_f32_32x32x16_bf16 v[0:15], v[64:67], v[72:75], v[0:15]
	v_mfma_f32_32x32x16_bf16 v[16:31], v[64:67], v[76:79], v[16:31]
	v_mfma_f32_32x32x16_bf16 v[0:15], v[68:71], v[220:223], v[0:15]
	v_mfma_f32_32x32x16_bf16 v[16:31], v[68:71], v[224:227], v[16:31]
	s_add_i32 s90, s67, 512
	v_add_u32_e32 v80, s90, v243
	v_add_u32_e32 v83, s90, v244
	v_add_u32_e32 v99, s90, v245
	v_add_u32_e32 v253, s90, v246
	v_add_u32_e32 v254, s90, v148
	v_add_u32_e32 v255, s90, v151
	v_med3_i32 v80, v80, 0, s99
	v_med3_i32 v83, v83, 0, s99
	v_med3_i32 v99, v99, 0, s99
	v_med3_i32 v253, v253, 0, s99
	v_med3_i32 v254, v254, 0, s99
	v_med3_i32 v255, v255, 0, s99
	v_mad_u32_u24 v80, v80, s100, v252
	v_mad_u32_u24 v83, v83, s100, v252
	v_mad_u32_u24 v99, v99, s100, v252
	v_mad_u32_u24 v253, v253, s100, v252
	v_mad_u32_u24 v254, v254, s100, v153
	v_mad_u32_u24 v255, v255, s100, v153
	global_load_dwordx4 v[156:159], v80, s[82:83]
	global_load_dwordx4 v[160:163], v83, s[82:83]
	global_load_dwordx4 v[164:167], v99, s[82:83]
	global_load_dwordx4 v[168:171], v253, s[82:83]
	global_load_dwordx4 v[172:175], v254, s[82:83] offset:768
	global_load_dwordx4 v[176:179], v255, s[82:83] offset:768
	global_load_dwordx4 v[180:183], v254, s[82:83] offset:832
	global_load_dwordx4 v[184:187], v255, s[82:83] offset:832
	ds_read_b64_tr_b16 v[72:73], v231
	ds_read_b64_tr_b16 v[74:75], v231 offset:512
	ds_read_b64_tr_b16 v[76:77], v231 offset:2048
	ds_read_b64_tr_b16 v[78:79], v231 offset:2560
	ds_read_b64_tr_b16 v[220:221], v231 offset:1024
	ds_read_b64_tr_b16 v[222:223], v231 offset:1536
	ds_read_b64_tr_b16 v[224:225], v231 offset:3072
	ds_read_b64_tr_b16 v[226:227], v231 offset:3584
	v_exp_f32_e32 v188, v188
	v_exp_f32_e32 v189, v189
	v_exp_f32_e32 v190, v190
	v_exp_f32_e32 v191, v191
	s_waitcnt vmcnt(8)
	ds_write_b128 v247, v[116:119]
	ds_write_b128 v247, v[120:123] offset:1024
	ds_write_b128 v247, v[124:127] offset:2048
	ds_write_b128 v247, v[128:131] offset:3072
	ds_read_b128 v[116:119], v248
	ds_read_b128 v[120:123], v249
	ds_read_b128 v[124:127], v250
	ds_read_b128 v[128:131], v251
	ds_write_b128 v112, v[132:135]
	ds_write_b128 v112, v[136:139] offset:1024
	ds_write_b128 v112, v[140:143] offset:2048
	ds_write_b128 v112, v[144:147] offset:3072
	v_exp_f32_e32 v192, v192
	v_exp_f32_e32 v193, v193
	v_exp_f32_e32 v194, v194
	v_exp_f32_e32 v195, v195
	s_waitcnt lgkmcnt(4)
	v_mfma_f32_32x32x16_bf16 v[32:47], v[116:119], v[48:51], v[32:47]
	v_exp_f32_e32 v196, v196
	v_exp_f32_e32 v197, v197
	v_mfma_f32_32x32x16_bf16 v[32:47], v[120:123], v[52:55], v[32:47]
	v_exp_f32_e32 v198, v198
	v_exp_f32_e32 v199, v199
	v_mfma_f32_32x32x16_bf16 v[32:47], v[124:127], v[56:59], v[32:47]
	v_exp_f32_e32 v200, v200
	v_exp_f32_e32 v201, v201
	v_mfma_f32_32x32x16_bf16 v[32:47], v[128:131], v[60:63], v[32:47]
	v_exp_f32_e32 v202, v202
	v_exp_f32_e32 v203, v203
	s_add_i32 s90, s67, -512
	v_lshlrev_b32_e32 v84, 4, v107
	v_add_u32_e32 v84, s90, v84
	v_add_u32_e32 v85, 0, v84
	v_add_u32_e32 v86, 16, v84
	v_add_u32_e32 v87, 32, v84
	v_add_u32_e32 v88, 48, v84
	v_cmp_gt_u32_e64 s[30:31], s98, v85
	v_cmp_gt_u32_e64 s[36:37], s98, v86
	v_cmp_gt_u32_e64 s[78:79], s98, v87
	v_cmp_gt_u32_e64 s[50:51], s98, v88
	v_cndmask_b32_e64 v188, 0, v188, s[30:31]
	v_add_u32_e32 v85, 128, v84
	v_cmp_gt_u32_e64 s[30:31], s98, v85
	v_cndmask_b32_e64 v189, 0, v189, s[36:37]
	v_add_u32_e32 v86, 144, v84
	v_cmp_gt_u32_e64 s[36:37], s98, v86
	v_cndmask_b32_e64 v190, 0, v190, s[78:79]
	v_add_u32_e32 v87, 160, v84
	v_cmp_gt_u32_e64 s[78:79], s98, v87
	v_cndmask_b32_e64 v191, 0, v191, s[50:51]
	v_add_u32_e32 v88, 176, v84
	v_cmp_gt_u32_e64 s[50:51], s98, v88
	v_cndmask_b32_e64 v192, 0, v192, s[30:31]
	v_add_u32_e32 v85, 256, v84
	v_cmp_gt_u32_e64 s[30:31], s98, v85
	v_cndmask_b32_e64 v193, 0, v193, s[36:37]
	v_add_u32_e32 v86, 272, v84
	v_cmp_gt_u32_e64 s[36:37], s98, v86
	v_cndmask_b32_e64 v194, 0, v194, s[78:79]
	v_add_u32_e32 v87, 288, v84
	v_cmp_gt_u32_e64 s[78:79], s98, v87
	v_cndmask_b32_e64 v195, 0, v195, s[50:51]
	v_add_u32_e32 v88, 304, v84
	v_cmp_gt_u32_e64 s[50:51], s98, v88
	v_cndmask_b32_e64 v196, 0, v196, s[30:31]
	v_add_u32_e32 v85, 384, v84
	v_cmp_gt_u32_e64 s[30:31], s98, v85
	v_cndmask_b32_e64 v197, 0, v197, s[36:37]
	v_add_u32_e32 v86, 400, v84
	v_cmp_gt_u32_e64 s[36:37], s98, v86
	v_cndmask_b32_e64 v198, 0, v198, s[78:79]
	v_add_u32_e32 v87, 416, v84
	v_cmp_gt_u32_e64 s[78:79], s98, v87
	v_cndmask_b32_e64 v199, 0, v199, s[50:51]
	v_add_u32_e32 v88, 432, v84
	v_cmp_gt_u32_e64 s[50:51], s98, v88
	v_nop
	v_cndmask_b32_e64 v200, 0, v200, s[30:31]
	v_cndmask_b32_e64 v201, 0, v201, s[36:37]
	v_cndmask_b32_e64 v202, 0, v202, s[78:79]
	v_cndmask_b32_e64 v203, 0, v203, s[50:51]
	v_cvt_pk_bf16_f32 v64, v188, v189
	v_cvt_pk_bf16_f32 v65, v190, v191
	v_cvt_pk_bf16_f32 v66, v192, v193
	v_cvt_pk_bf16_f32 v67, v194, v195
	v_cvt_pk_bf16_f32 v68, v196, v197
	v_cvt_pk_bf16_f32 v69, v198, v199
	v_cvt_pk_bf16_f32 v70, v200, v201
	v_cvt_pk_bf16_f32 v71, v202, v203
	v_pk_add_f32 v[232:233], v[232:233], v[188:189]
	v_pk_add_f32 v[232:233], v[232:233], v[190:191]
	v_pk_add_f32 v[232:233], v[232:233], v[192:193]
	v_pk_add_f32 v[232:233], v[232:233], v[194:195]
	v_pk_add_f32 v[232:233], v[232:233], v[196:197]
	v_pk_add_f32 v[232:233], v[232:233], v[198:199]
	v_pk_add_f32 v[232:233], v[232:233], v[200:201]
	v_pk_add_f32 v[232:233], v[232:233], v[202:203]
	ds_read2_b32 v[188:189], v115 offset0:96 offset1:97
	ds_read2_b32 v[190:191], v115 offset0:98 offset1:99
	ds_read2_b32 v[192:193], v115 offset0:104 offset1:105
	ds_read2_b32 v[194:195], v115 offset0:106 offset1:107
	ds_read2_b32 v[196:197], v115 offset0:112 offset1:113
	ds_read2_b32 v[198:199], v115 offset0:114 offset1:115
	ds_read2_b32 v[200:201], v115 offset0:120 offset1:121
	ds_read2_b32 v[202:203], v115 offset0:122 offset1:123
	v_mfma_f32_32x32x16_bf16 v[0:15], v[64:67], v[72:75], v[0:15]
	v_mfma_f32_32x32x16_bf16 v[16:31], v[64:67], v[76:79], v[16:31]
	v_mfma_f32_32x32x16_bf16 v[0:15], v[68:71], v[220:223], v[0:15]
	v_mfma_f32_32x32x16_bf16 v[16:31], v[68:71], v[224:227], v[16:31]
	s_add_i32 s90, s67, 1024
	v_add_u32_e32 v80, s90, v243
	v_add_u32_e32 v83, s90, v244
	v_add_u32_e32 v99, s90, v245
	v_add_u32_e32 v253, s90, v246
	v_add_u32_e32 v254, s90, v148
	v_add_u32_e32 v255, s90, v151
	v_med3_i32 v80, v80, 0, s99
	v_med3_i32 v83, v83, 0, s99
	v_med3_i32 v99, v99, 0, s99
	v_med3_i32 v253, v253, 0, s99
	v_med3_i32 v254, v254, 0, s99
	v_med3_i32 v255, v255, 0, s99
	v_mad_u32_u24 v80, v80, s100, v252
	v_mad_u32_u24 v83, v83, s100, v252
	v_mad_u32_u24 v99, v99, s100, v252
	v_mad_u32_u24 v253, v253, s100, v252
	v_mad_u32_u24 v254, v254, s100, v153
	v_mad_u32_u24 v255, v255, s100, v153
	global_load_dwordx4 v[116:119], v80, s[82:83]
	global_load_dwordx4 v[120:123], v83, s[82:83]
	global_load_dwordx4 v[124:127], v99, s[82:83]
	global_load_dwordx4 v[128:131], v253, s[82:83]
	global_load_dwordx4 v[132:135], v254, s[82:83] offset:768
	global_load_dwordx4 v[136:139], v255, s[82:83] offset:768
	global_load_dwordx4 v[140:143], v254, s[82:83] offset:832
	global_load_dwordx4 v[144:147], v255, s[82:83] offset:832
	ds_read_b64_tr_b16 v[72:73], v231
	ds_read_b64_tr_b16 v[74:75], v231 offset:512
	ds_read_b64_tr_b16 v[76:77], v231 offset:2048
	ds_read_b64_tr_b16 v[78:79], v231 offset:2560
	ds_read_b64_tr_b16 v[220:221], v231 offset:1024
	ds_read_b64_tr_b16 v[222:223], v231 offset:1536
	ds_read_b64_tr_b16 v[224:225], v231 offset:3072
	ds_read_b64_tr_b16 v[226:227], v231 offset:3584
	v_exp_f32_e32 v32, v32
	v_exp_f32_e32 v33, v33
	v_exp_f32_e32 v34, v34
	v_exp_f32_e32 v35, v35
	s_waitcnt vmcnt(8)
	ds_write_b128 v247, v[156:159]
	ds_write_b128 v247, v[160:163] offset:1024
	ds_write_b128 v247, v[164:167] offset:2048
	ds_write_b128 v247, v[168:171] offset:3072
	ds_read_b128 v[156:159], v248
	ds_read_b128 v[160:163], v249
	ds_read_b128 v[164:167], v250
	ds_read_b128 v[168:171], v251
	ds_write_b128 v112, v[172:175]
	ds_write_b128 v112, v[176:179] offset:1024
	ds_write_b128 v112, v[180:183] offset:2048
	ds_write_b128 v112, v[184:187] offset:3072
	v_exp_f32_e32 v36, v36
	v_exp_f32_e32 v37, v37
	v_exp_f32_e32 v38, v38
	v_exp_f32_e32 v39, v39
	s_waitcnt lgkmcnt(4)
	v_mfma_f32_32x32x16_bf16 v[188:203], v[156:159], v[48:51], v[188:203]
	v_exp_f32_e32 v40, v40
	v_exp_f32_e32 v41, v41
	v_mfma_f32_32x32x16_bf16 v[188:203], v[160:163], v[52:55], v[188:203]
	v_exp_f32_e32 v42, v42
	v_exp_f32_e32 v43, v43
	v_mfma_f32_32x32x16_bf16 v[188:203], v[164:167], v[56:59], v[188:203]
	v_exp_f32_e32 v44, v44
	v_exp_f32_e32 v45, v45
	v_mfma_f32_32x32x16_bf16 v[188:203], v[168:171], v[60:63], v[188:203]
	v_exp_f32_e32 v46, v46
	v_exp_f32_e32 v47, v47
	s_add_i32 s90, s67, 0
	v_lshlrev_b32_e32 v84, 4, v107
	v_add_u32_e32 v84, s90, v84
	v_add_u32_e32 v85, 0, v84
	v_add_u32_e32 v86, 16, v84
	v_add_u32_e32 v87, 32, v84
	v_add_u32_e32 v88, 48, v84
	v_cmp_gt_u32_e64 s[30:31], s98, v85
	v_cmp_gt_u32_e64 s[36:37], s98, v86
	v_cmp_gt_u32_e64 s[78:79], s98, v87
	v_cmp_gt_u32_e64 s[50:51], s98, v88
	v_cndmask_b32_e64 v32, 0, v32, s[30:31]
	v_add_u32_e32 v85, 128, v84
	v_cmp_gt_u32_e64 s[30:31], s98, v85
	v_cndmask_b32_e64 v33, 0, v33, s[36:37]
	v_add_u32_e32 v86, 144, v84
	v_cmp_gt_u32_e64 s[36:37], s98, v86
	v_cndmask_b32_e64 v34, 0, v34, s[78:79]
	v_add_u32_e32 v87, 160, v84
	v_cmp_gt_u32_e64 s[78:79], s98, v87
	v_cndmask_b32_e64 v35, 0, v35, s[50:51]
	v_add_u32_e32 v88, 176, v84
	v_cmp_gt_u32_e64 s[50:51], s98, v88
	v_cndmask_b32_e64 v36, 0, v36, s[30:31]
	v_add_u32_e32 v85, 256, v84
	v_cmp_gt_u32_e64 s[30:31], s98, v85
	v_cndmask_b32_e64 v37, 0, v37, s[36:37]
	v_add_u32_e32 v86, 272, v84
	v_cmp_gt_u32_e64 s[36:37], s98, v86
	v_cndmask_b32_e64 v38, 0, v38, s[78:79]
	v_add_u32_e32 v87, 288, v84
	v_cmp_gt_u32_e64 s[78:79], s98, v87
	v_cndmask_b32_e64 v39, 0, v39, s[50:51]
	v_add_u32_e32 v88, 304, v84
	v_cmp_gt_u32_e64 s[50:51], s98, v88
	v_cndmask_b32_e64 v40, 0, v40, s[30:31]
	v_add_u32_e32 v85, 384, v84
	v_cmp_gt_u32_e64 s[30:31], s98, v85
	v_cndmask_b32_e64 v41, 0, v41, s[36:37]
	v_add_u32_e32 v86, 400, v84
	v_cmp_gt_u32_e64 s[36:37], s98, v86
	v_cndmask_b32_e64 v42, 0, v42, s[78:79]
	v_add_u32_e32 v87, 416, v84
	v_cmp_gt_u32_e64 s[78:79], s98, v87
	v_cndmask_b32_e64 v43, 0, v43, s[50:51]
	v_add_u32_e32 v88, 432, v84
	v_cmp_gt_u32_e64 s[50:51], s98, v88
	v_nop
	v_cndmask_b32_e64 v44, 0, v44, s[30:31]
	v_cndmask_b32_e64 v45, 0, v45, s[36:37]
	v_cndmask_b32_e64 v46, 0, v46, s[78:79]
	v_cndmask_b32_e64 v47, 0, v47, s[50:51]
	v_cvt_pk_bf16_f32 v64, v32, v33
	v_cvt_pk_bf16_f32 v65, v34, v35
	v_cvt_pk_bf16_f32 v66, v36, v37
	v_cvt_pk_bf16_f32 v67, v38, v39
	v_cvt_pk_bf16_f32 v68, v40, v41
	v_cvt_pk_bf16_f32 v69, v42, v43
	v_cvt_pk_bf16_f32 v70, v44, v45
	v_cvt_pk_bf16_f32 v71, v46, v47
	v_pk_add_f32 v[232:233], v[232:233], v[32:33]
	v_pk_add_f32 v[232:233], v[232:233], v[34:35]
	v_pk_add_f32 v[232:233], v[232:233], v[36:37]
	v_pk_add_f32 v[232:233], v[232:233], v[38:39]
	v_pk_add_f32 v[232:233], v[232:233], v[40:41]
	v_pk_add_f32 v[232:233], v[232:233], v[42:43]
	v_pk_add_f32 v[232:233], v[232:233], v[44:45]
	v_pk_add_f32 v[232:233], v[232:233], v[46:47]
	ds_read2_b32 v[32:33], v115 offset0:128 offset1:129
	ds_read2_b32 v[34:35], v115 offset0:130 offset1:131
	ds_read2_b32 v[36:37], v115 offset0:136 offset1:137
	ds_read2_b32 v[38:39], v115 offset0:138 offset1:139
	ds_read2_b32 v[40:41], v115 offset0:144 offset1:145
	ds_read2_b32 v[42:43], v115 offset0:146 offset1:147
	ds_read2_b32 v[44:45], v115 offset0:152 offset1:153
	ds_read2_b32 v[46:47], v115 offset0:154 offset1:155
	v_mfma_f32_32x32x16_bf16 v[0:15], v[64:67], v[72:75], v[0:15]
	v_mfma_f32_32x32x16_bf16 v[16:31], v[64:67], v[76:79], v[16:31]
	v_mfma_f32_32x32x16_bf16 v[0:15], v[68:71], v[220:223], v[0:15]
	v_mfma_f32_32x32x16_bf16 v[16:31], v[68:71], v[224:227], v[16:31]
	ds_read_b64_tr_b16 v[72:73], v231
	ds_read_b64_tr_b16 v[74:75], v231 offset:512
	ds_read_b64_tr_b16 v[76:77], v231 offset:2048
	ds_read_b64_tr_b16 v[78:79], v231 offset:2560
	ds_read_b64_tr_b16 v[220:221], v231 offset:1024
	ds_read_b64_tr_b16 v[222:223], v231 offset:1536
	ds_read_b64_tr_b16 v[224:225], v231 offset:3072
	ds_read_b64_tr_b16 v[226:227], v231 offset:3584
	v_exp_f32_e32 v188, v188
	v_exp_f32_e32 v189, v189
	v_exp_f32_e32 v190, v190
	v_exp_f32_e32 v191, v191
	s_waitcnt vmcnt(0)
	ds_write_b128 v247, v[116:119]
	ds_write_b128 v247, v[120:123] offset:1024
	ds_write_b128 v247, v[124:127] offset:2048
	ds_write_b128 v247, v[128:131] offset:3072
	ds_read_b128 v[116:119], v248
	ds_read_b128 v[120:123], v249
	ds_read_b128 v[124:127], v250
	ds_read_b128 v[128:131], v251
	ds_write_b128 v112, v[132:135]
	ds_write_b128 v112, v[136:139] offset:1024
	ds_write_b128 v112, v[140:143] offset:2048
	ds_write_b128 v112, v[144:147] offset:3072
	v_exp_f32_e32 v192, v192
	v_exp_f32_e32 v193, v193
	v_exp_f32_e32 v194, v194
	v_exp_f32_e32 v195, v195
	s_waitcnt lgkmcnt(4)
	v_mfma_f32_32x32x16_bf16 v[32:47], v[116:119], v[48:51], v[32:47]
	v_exp_f32_e32 v196, v196
	v_exp_f32_e32 v197, v197
	v_mfma_f32_32x32x16_bf16 v[32:47], v[120:123], v[52:55], v[32:47]
	v_exp_f32_e32 v198, v198
	v_exp_f32_e32 v199, v199
	v_mfma_f32_32x32x16_bf16 v[32:47], v[124:127], v[56:59], v[32:47]
	v_exp_f32_e32 v200, v200
	v_exp_f32_e32 v201, v201
	v_mfma_f32_32x32x16_bf16 v[32:47], v[128:131], v[60:63], v[32:47]
	v_exp_f32_e32 v202, v202
	v_exp_f32_e32 v203, v203
	s_add_i32 s90, s67, 512
	v_lshlrev_b32_e32 v84, 4, v107
	v_add_u32_e32 v84, s90, v84
	v_add_u32_e32 v85, 0, v84
	v_add_u32_e32 v86, 16, v84
	v_add_u32_e32 v87, 32, v84
	v_add_u32_e32 v88, 48, v84
	v_cmp_gt_u32_e64 s[30:31], s98, v85
	v_cmp_gt_u32_e64 s[36:37], s98, v86
	v_cmp_gt_u32_e64 s[78:79], s98, v87
	v_cmp_gt_u32_e64 s[50:51], s98, v88
	v_cndmask_b32_e64 v188, 0, v188, s[30:31]
	v_add_u32_e32 v85, 128, v84
	v_cmp_gt_u32_e64 s[30:31], s98, v85
	v_cndmask_b32_e64 v189, 0, v189, s[36:37]
	v_add_u32_e32 v86, 144, v84
	v_cmp_gt_u32_e64 s[36:37], s98, v86
	v_cndmask_b32_e64 v190, 0, v190, s[78:79]
	v_add_u32_e32 v87, 160, v84
	v_cmp_gt_u32_e64 s[78:79], s98, v87
	v_cndmask_b32_e64 v191, 0, v191, s[50:51]
	v_add_u32_e32 v88, 176, v84
	v_cmp_gt_u32_e64 s[50:51], s98, v88
	v_cndmask_b32_e64 v192, 0, v192, s[30:31]
	v_add_u32_e32 v85, 256, v84
	v_cmp_gt_u32_e64 s[30:31], s98, v85
	v_cndmask_b32_e64 v193, 0, v193, s[36:37]
	v_add_u32_e32 v86, 272, v84
	v_cmp_gt_u32_e64 s[36:37], s98, v86
	v_cndmask_b32_e64 v194, 0, v194, s[78:79]
	v_add_u32_e32 v87, 288, v84
	v_cmp_gt_u32_e64 s[78:79], s98, v87
	v_cndmask_b32_e64 v195, 0, v195, s[50:51]
	v_add_u32_e32 v88, 304, v84
	v_cmp_gt_u32_e64 s[50:51], s98, v88
	v_cndmask_b32_e64 v196, 0, v196, s[30:31]
	v_add_u32_e32 v85, 384, v84
	v_cmp_gt_u32_e64 s[30:31], s98, v85
	v_cndmask_b32_e64 v197, 0, v197, s[36:37]
	v_add_u32_e32 v86, 400, v84
	v_cmp_gt_u32_e64 s[36:37], s98, v86
	v_cndmask_b32_e64 v198, 0, v198, s[78:79]
	v_add_u32_e32 v87, 416, v84
	v_cmp_gt_u32_e64 s[78:79], s98, v87
	v_cndmask_b32_e64 v199, 0, v199, s[50:51]
	v_add_u32_e32 v88, 432, v84
	v_cmp_gt_u32_e64 s[50:51], s98, v88
	v_nop
	v_cndmask_b32_e64 v200, 0, v200, s[30:31]
	v_cndmask_b32_e64 v201, 0, v201, s[36:37]
	v_cndmask_b32_e64 v202, 0, v202, s[78:79]
	v_cndmask_b32_e64 v203, 0, v203, s[50:51]
	v_cvt_pk_bf16_f32 v64, v188, v189
	v_cvt_pk_bf16_f32 v65, v190, v191
	v_cvt_pk_bf16_f32 v66, v192, v193
	v_cvt_pk_bf16_f32 v67, v194, v195
	v_cvt_pk_bf16_f32 v68, v196, v197
	v_cvt_pk_bf16_f32 v69, v198, v199
	v_cvt_pk_bf16_f32 v70, v200, v201
	v_cvt_pk_bf16_f32 v71, v202, v203
	v_pk_add_f32 v[232:233], v[232:233], v[188:189]
	v_pk_add_f32 v[232:233], v[232:233], v[190:191]
	v_pk_add_f32 v[232:233], v[232:233], v[192:193]
	v_pk_add_f32 v[232:233], v[232:233], v[194:195]
	v_pk_add_f32 v[232:233], v[232:233], v[196:197]
	v_pk_add_f32 v[232:233], v[232:233], v[198:199]
	v_pk_add_f32 v[232:233], v[232:233], v[200:201]
	v_pk_add_f32 v[232:233], v[232:233], v[202:203]
	v_mfma_f32_32x32x16_bf16 v[0:15], v[64:67], v[72:75], v[0:15]
	v_mfma_f32_32x32x16_bf16 v[16:31], v[64:67], v[76:79], v[16:31]
	v_mfma_f32_32x32x16_bf16 v[0:15], v[68:71], v[220:223], v[0:15]
	v_mfma_f32_32x32x16_bf16 v[16:31], v[68:71], v[224:227], v[16:31]
	ds_read_b64_tr_b16 v[72:73], v231
	ds_read_b64_tr_b16 v[74:75], v231 offset:512
	ds_read_b64_tr_b16 v[76:77], v231 offset:2048
	ds_read_b64_tr_b16 v[78:79], v231 offset:2560
	ds_read_b64_tr_b16 v[220:221], v231 offset:1024
	ds_read_b64_tr_b16 v[222:223], v231 offset:1536
	ds_read_b64_tr_b16 v[224:225], v231 offset:3072
	ds_read_b64_tr_b16 v[226:227], v231 offset:3584
	s_waitcnt lgkmcnt(0)
	v_exp_f32_e32 v32, v32
	v_exp_f32_e32 v33, v33
	v_exp_f32_e32 v34, v34
	v_exp_f32_e32 v35, v35
	v_exp_f32_e32 v36, v36
	v_exp_f32_e32 v37, v37
	v_exp_f32_e32 v38, v38
	v_exp_f32_e32 v39, v39
	v_exp_f32_e32 v40, v40
	v_exp_f32_e32 v41, v41
	v_exp_f32_e32 v42, v42
	v_exp_f32_e32 v43, v43
	v_exp_f32_e32 v44, v44
	v_exp_f32_e32 v45, v45
	v_exp_f32_e32 v46, v46
	v_exp_f32_e32 v47, v47
	s_add_i32 s90, s67, 1024
	v_lshlrev_b32_e32 v84, 4, v107
	v_add_u32_e32 v84, s90, v84
	v_add_u32_e32 v85, 0, v84
	v_add_u32_e32 v86, 16, v84
	v_add_u32_e32 v87, 32, v84
	v_add_u32_e32 v88, 48, v84
	v_cmp_gt_u32_e64 s[30:31], s98, v85
	v_cmp_gt_u32_e64 s[36:37], s98, v86
	v_cmp_gt_u32_e64 s[78:79], s98, v87
	v_cmp_gt_u32_e64 s[50:51], s98, v88
	v_cndmask_b32_e64 v32, 0, v32, s[30:31]
	v_add_u32_e32 v85, 128, v84
	v_cmp_gt_u32_e64 s[30:31], s98, v85
	v_cndmask_b32_e64 v33, 0, v33, s[36:37]
	v_add_u32_e32 v86, 144, v84
	v_cmp_gt_u32_e64 s[36:37], s98, v86
	v_cndmask_b32_e64 v34, 0, v34, s[78:79]
	v_add_u32_e32 v87, 160, v84
	v_cmp_gt_u32_e64 s[78:79], s98, v87
	v_cndmask_b32_e64 v35, 0, v35, s[50:51]
	v_add_u32_e32 v88, 176, v84
	v_cmp_gt_u32_e64 s[50:51], s98, v88
	v_cndmask_b32_e64 v36, 0, v36, s[30:31]
	v_add_u32_e32 v85, 256, v84
	v_cmp_gt_u32_e64 s[30:31], s98, v85
	v_cndmask_b32_e64 v37, 0, v37, s[36:37]
	v_add_u32_e32 v86, 272, v84
	v_cmp_gt_u32_e64 s[36:37], s98, v86
	v_cndmask_b32_e64 v38, 0, v38, s[78:79]
	v_add_u32_e32 v87, 288, v84
	v_cmp_gt_u32_e64 s[78:79], s98, v87
	v_cndmask_b32_e64 v39, 0, v39, s[50:51]
	v_add_u32_e32 v88, 304, v84
	v_cmp_gt_u32_e64 s[50:51], s98, v88
	v_cndmask_b32_e64 v40, 0, v40, s[30:31]
	v_add_u32_e32 v85, 384, v84
	v_cmp_gt_u32_e64 s[30:31], s98, v85
	v_cndmask_b32_e64 v41, 0, v41, s[36:37]
	v_add_u32_e32 v86, 400, v84
	v_cmp_gt_u32_e64 s[36:37], s98, v86
	v_cndmask_b32_e64 v42, 0, v42, s[78:79]
	v_add_u32_e32 v87, 416, v84
	v_cmp_gt_u32_e64 s[78:79], s98, v87
	v_cndmask_b32_e64 v43, 0, v43, s[50:51]
	v_add_u32_e32 v88, 432, v84
	v_cmp_gt_u32_e64 s[50:51], s98, v88
	v_nop
	v_cndmask_b32_e64 v44, 0, v44, s[30:31]
	v_cndmask_b32_e64 v45, 0, v45, s[36:37]
	v_cndmask_b32_e64 v46, 0, v46, s[78:79]
	v_cndmask_b32_e64 v47, 0, v47, s[50:51]
	v_cvt_pk_bf16_f32 v64, v32, v33
	v_cvt_pk_bf16_f32 v65, v34, v35
	v_cvt_pk_bf16_f32 v66, v36, v37
	v_cvt_pk_bf16_f32 v67, v38, v39
	v_cvt_pk_bf16_f32 v68, v40, v41
	v_cvt_pk_bf16_f32 v69, v42, v43
	v_cvt_pk_bf16_f32 v70, v44, v45
	v_cvt_pk_bf16_f32 v71, v46, v47
	v_pk_add_f32 v[232:233], v[232:233], v[32:33]
	v_pk_add_f32 v[232:233], v[232:233], v[34:35]
	v_pk_add_f32 v[232:233], v[232:233], v[36:37]
	v_pk_add_f32 v[232:233], v[232:233], v[38:39]
	v_pk_add_f32 v[232:233], v[232:233], v[40:41]
	v_pk_add_f32 v[232:233], v[232:233], v[42:43]
	v_pk_add_f32 v[232:233], v[232:233], v[44:45]
	v_pk_add_f32 v[232:233], v[232:233], v[46:47]
	v_mfma_f32_32x32x16_bf16 v[0:15], v[64:67], v[72:75], v[0:15]
	v_mfma_f32_32x32x16_bf16 v[16:31], v[64:67], v[76:79], v[16:31]
	v_mfma_f32_32x32x16_bf16 v[0:15], v[68:71], v[220:223], v[0:15]
	v_mfma_f32_32x32x16_bf16 v[16:31], v[68:71], v[224:227], v[16:31]
	v_add_f32_e32 v113, v232, v233
	v_or_b32_e32 v114, 1, v107
	v_or_b32_e32 v97, 2, v107
	v_or_b32_e32 v96, 3, v107
	v_or_b32_e32 v95, 8, v107
	v_or_b32_e32 v94, 9, v107
	v_or_b32_e32 v93, 10, v107
	v_or_b32_e32 v92, 11, v107
	v_or_b32_e32 v91, 16, v107
	v_or_b32_e32 v90, 17, v107
	v_or_b32_e32 v89, 18, v107
	v_or_b32_e32 v88, 19, v107
	v_or_b32_e32 v87, 24, v107
	v_or_b32_e32 v86, 25, v107
	v_or_b32_e32 v85, 26, v107
	v_or_b32_e32 v84, 27, v107
	s_setprio 0
	s_nop 11
	s_branch .LBB0_1265
